# speedup vs baseline: 1.0157x; 1.0029x over previous
; DEVFI int lane_opaque() { unsigned m = ~0u; asm volatile("" : "+s"(m)); return (int)__builtin_amdgcn_mbcnt_hi(m, __builtin_amdgcn_mbcnt_lo(m, 0u)); }
; DEVFI float shx(float v, int mask, int lane) { return __int_as_float(__builtin_amdgcn_ds_bpermute((lane ^ mask) << 2, __float_as_int(v))); }
; DEVFI float red64(float v) {
;   const int ln = lane_opaque();
;   v += shx(v, 32, ln); v += shx(v, 16, ln); v += shx(v, 8, ln); v += shx(v, 4, ln); v += shx(v, 2, ln); v += shx(v, 1, ln); return v;
; }
; DEVFI void ln_rows4(const float* src, float* dst, bfraw* dstb, float* stats, const float* w, const float* b, int lane) {
;   float4 v[4][4];
; #pragma unroll
;   for (int r = 0; r < 4; ++r)
; #pragma unroll
;     for (int i = 0; i < 4; ++i) v[r][i] = ((const float4*)(src + r * 1024))[i * 64 + lane];
;   float4 ww[4], bb[4];
; #pragma unroll
;   for (int i = 0; i < 4; ++i) { ww[i] = ((const float4*)w)[i * 64 + lane]; bb[i] = ((const float4*)b)[i * 64 + lane]; }
; #pragma unroll
;   for (int r = 0; r < 4; ++r) {
;     float s = 0;
; #pragma unroll
;     for (int i = 0; i < 4; ++i) s += v[r][i].x + v[r][i].y + v[r][i].z + v[r][i].w;
;     const float mean = red64(s) * (1.f / 1024.f);
;     float q = 0;
; #pragma unroll
;     for (int i = 0; i < 4; ++i) { float a = v[r][i].x - mean, c1 = v[r][i].y - mean, c = v[r][i].z - mean, d = v[r][i].w - mean; q += a * a + c1 * c1 + c * c + d * d; }
;     const float rstd = 1.f / sqrtf(red64(q) * (1.f / 1024.f) + LN_EPS);
.LBB0_19:
	s_or_b64 exec, exec, s[6:7]
	s_mov_b64 s[6:7], s[0:1]
	s_load_dwordx2 s[8:9], s[6:7], 0xe8
	s_mov_b64 s[6:7], s[0:1]
	s_mov_b64 s[34:35], s[0:1]
	s_load_dwordx2 s[6:7], s[6:7], 0xe8
	s_mov_b64 s[36:37], s[0:1]
	v_lshl_add_u64 v[4:5], v[2:3], 0, v[110:111]
	s_load_dwordx2 s[34:35], s[34:35], 0x20
	global_load_dwordx4 v[94:97], v[4:5], off
	global_load_dwordx4 v[90:93], v[4:5], off offset:1024
	global_load_dwordx4 v[86:89], v[4:5], off offset:2048
	global_load_dwordx4 v[82:85], v[4:5], off offset:3072
	v_lshl_add_u64 v[4:5], v[2:3], 0, s[18:19]
	v_lshl_add_u64 v[6:7], v[2:3], 0, s[20:21]
	v_lshl_add_u64 v[2:3], v[2:3], 0, s[22:23]
	v_lshl_add_u64 v[8:9], v[4:5], 0, v[110:111]
	s_mov_b32 s38, -1
	v_lshl_add_u64 v[10:11], v[4:5], 0, v[112:113]
	v_lshl_add_u64 v[12:13], v[4:5], 0, v[114:115]
	v_lshl_add_u64 v[18:19], v[4:5], 0, v[116:117]
	v_lshl_add_u64 v[20:21], v[6:7], 0, v[110:111]
	v_lshl_add_u64 v[22:23], v[6:7], 0, v[112:113]
	v_lshl_add_u64 v[24:25], v[6:7], 0, v[114:115]
	v_lshl_add_u64 v[6:7], v[6:7], 0, v[116:117]
	v_lshl_add_u64 v[30:31], v[2:3], 0, v[110:111]
	v_lshl_add_u64 v[32:33], v[2:3], 0, v[112:113]
	v_lshl_add_u64 v[34:35], v[2:3], 0, v[114:115]
	v_lshl_add_u64 v[36:37], v[2:3], 0, v[116:117]
	global_load_dwordx4 v[78:81], v[8:9], off
	global_load_dwordx4 v[74:77], v[10:11], off
	global_load_dwordx4 v[70:73], v[12:13], off
	global_load_dwordx4 v[66:69], v[18:19], off
	global_load_dwordx4 v[62:65], v[20:21], off
	global_load_dwordx4 v[58:61], v[22:23], off
	global_load_dwordx4 v[54:57], v[24:25], off
	global_load_dwordx4 v[50:53], v[6:7], off
	global_load_dwordx4 v[38:41], v[30:31], off
	global_load_dwordx4 v[26:29], v[32:33], off
	global_load_dwordx4 v[14:17], v[34:35], off
	global_load_dwordx4 v[2:5], v[36:37], off
	s_load_dwordx2 s[36:37], s[36:37], 0x28
	s_waitcnt lgkmcnt(0)
	global_load_dwordx4 v[42:45], v110, s[34:35]
	global_load_dwordx4 v[30:33], v110, s[34:35] offset:1024
	global_load_dwordx4 v[18:21], v110, s[34:35] offset:2048
	global_load_dwordx4 v[6:9], v110, s[34:35] offset:3072
	global_load_dwordx4 v[46:49], v110, s[36:37]
	global_load_dwordx4 v[34:37], v110, s[36:37] offset:1024
	global_load_dwordx4 v[22:25], v110, s[36:37] offset:2048
	global_load_dwordx4 v[10:13], v110, s[36:37] offset:3072
	s_mov_b32 s34, -1
	v_mbcnt_lo_u32_b32 v107, s38, 0
	v_mbcnt_hi_u32_b32 v107, s38, v107
	v_lshlrev_b32_e32 v107, 2, v107
	v_xor_b32_e32 v120, 0x80, v107
	s_waitcnt vmcnt(23)
	v_add_f32_e32 v121, v94, v95
	s_waitcnt vmcnt(22)
	v_add_f32_e32 v122, v90, v91
	v_add_f32_e32 v121, v121, v96
	s_waitcnt vmcnt(21)
	v_add_f32_e32 v123, v86, v87
	v_add_f32_e32 v122, v122, v92
	v_add_f32_e32 v121, v121, v97
	s_waitcnt vmcnt(20)
	v_add_f32_e32 v124, v82, v83
	v_add_f32_e32 v123, v123, v88
	v_add_f32_e32 v122, v122, v93
	v_add_f32_e32 v121, 0, v121
	v_add_f32_e32 v124, v124, v84
	v_add_f32_e32 v123, v123, v89
	v_add_f32_e32 v121, v121, v122
	v_add_f32_e32 v124, v124, v85
	v_add_f32_e32 v121, v121, v123
	v_add_f32_e32 v121, v121, v124
	ds_bpermute_b32 v120, v120, v121
	v_xor_b32_e32 v122, 64, v107
	s_waitcnt lgkmcnt(0)
	v_add_f32_e32 v120, v121, v120
	ds_bpermute_b32 v121, v122, v120
	v_xor_b32_e32 v122, 32, v107
	s_waitcnt lgkmcnt(0)
	v_add_f32_e32 v120, v120, v121
	s_nop 1
	v_mov_b32_dpp v121, v120 row_ror:8 row_mask:0xf bank_mask:0xf
	v_xor_b32_e32 v122, 16, v107
	s_waitcnt lgkmcnt(0)
	v_add_f32_e32 v120, v120, v121
	s_nop 1
	v_mov_b32_dpp v121, v120 row_half_mirror row_mask:0xf bank_mask:0xf
	s_nop 1
	v_mov_b32_dpp v121, v121 quad_perm:[3,2,1,0] row_mask:0xf bank_mask:0xf
	v_xor_b32_e32 v122, 8, v107
	v_xor_b32_e32 v107, 4, v107
	s_waitcnt lgkmcnt(0)
	v_add_f32_e32 v120, v120, v121
	s_nop 1
	v_mov_b32_dpp v121, v120 quad_perm:[2,3,0,1] row_mask:0xf bank_mask:0xf
	s_waitcnt lgkmcnt(0)
	v_add_f32_e32 v120, v120, v121
	s_nop 1
	v_mov_b32_dpp v107, v120 quad_perm:[1,0,3,2] row_mask:0xf bank_mask:0xf
	v_mbcnt_lo_u32_b32 v121, s34, 0
	v_mbcnt_hi_u32_b32 v121, s34, v121
	v_lshlrev_b32_e32 v128, 2, v121
	v_xor_b32_e32 v129, 0x80, v128
	s_waitcnt lgkmcnt(0)
	v_add_f32_e32 v127, v120, v107
	v_fmamk_f32 v125, v127, 0xba800000, v95
	v_fmamk_f32 v122, v127, 0xba800000, v91
	v_fmamk_f32 v124, v127, 0xba800000, v94
	v_fmamk_f32 v121, v127, 0xba800000, v90
	v_fmamk_f32 v123, v127, 0xba800000, v92
	v_fmamk_f32 v107, v127, 0xba800000, v87
	v_fmamk_f32 v120, v127, 0xba800000, v88
	v_fmamk_f32 v88, v127, 0xba800000, v82
	v_fmamk_f32 v92, v127, 0xba800000, v83
	v_mul_f32_e32 v82, v125, v125
	v_mul_f32_e32 v83, v122, v122
	v_fmamk_f32 v126, v127, 0xba800000, v96
	v_fmamk_f32 v96, v127, 0xba800000, v86
	v_mul_f32_e32 v86, v107, v107
	v_fmac_f32_e32 v82, v124, v124
	v_fmac_f32_e32 v83, v121, v121
	v_fmac_f32_e32 v97, 0xba800000, v127
	v_fmac_f32_e32 v93, 0xba800000, v127
	v_mul_f32_e32 v87, v92, v92
	v_fmac_f32_e32 v86, v96, v96
	v_fmac_f32_e32 v82, v126, v126
	v_fmac_f32_e32 v83, v123, v123
	v_fmac_f32_e32 v89, 0xba800000, v127
	v_fmamk_f32 v84, v127, 0xba800000, v84
	v_fmac_f32_e32 v87, v88, v88
	v_fmac_f32_e32 v86, v120, v120
	v_fmac_f32_e32 v82, v97, v97
	v_fmac_f32_e32 v83, v93, v93
	v_fmac_f32_e32 v85, 0xba800000, v127
	v_fmac_f32_e32 v87, v84, v84
	v_fmac_f32_e32 v86, v89, v89
	v_add_f32_e32 v82, v82, v83
	v_fmac_f32_e32 v87, v85, v85
	v_add_f32_e32 v82, v86, v82
	v_add_f32_e32 v82, v87, v82
	ds_bpermute_b32 v83, v129, v82
	v_xor_b32_e32 v86, 64, v128
	s_waitcnt lgkmcnt(0)
	v_add_f32_e32 v82, v82, v83
	ds_bpermute_b32 v83, v86, v82
	v_xor_b32_e32 v86, 32, v128
	s_waitcnt lgkmcnt(0)
	v_add_f32_e32 v82, v82, v83
	s_nop 1
	v_mov_b32_dpp v83, v82 row_ror:8 row_mask:0xf bank_mask:0xf
	v_xor_b32_e32 v86, 16, v128
	s_waitcnt lgkmcnt(0)
; DEVFI void ln_rows4(const float* src, float* dst, bfraw* dstb, float* stats, const float* w, const float* b, int lane) {
;     ...
;   for (int r = 0; r < 4; ++r) {
;     float s = 0;
; #pragma unroll
;     for (int i = 0; i < 4; ++i) s += v[r][i].x + v[r][i].y + v[r][i].z + v[r][i].w;
;     const float mean = red64(s) * (1.f / 1024.f);
;     float q = 0;
; #pragma unroll
;     for (int i = 0; i < 4; ++i) { float a = v[r][i].x - mean, c1 = v[r][i].y - mean, c = v[r][i].z - mean, d = v[r][i].w - mean; q += a * a + c1 * c1 + c * c + d * d; }
;     const float rstd = 1.f / sqrtf(red64(q) * (1.f / 1024.f) + LN_EPS);
;     if (lane == 0) { stats[r * 2] = mean; stats[r * 2 + 1] = rstd; }
; #pragma unroll
;     for (int i = 0; i < 4; ++i) { const int c4 = i * 64 + lane;
;       float4 y; y.x = (v[r][i].x - mean) * rstd * ww[i].x + bb[i].x; y.y = (v[r][i].y - mean) * rstd * ww[i].y + bb[i].y;
;       y.z = (v[r][i].z - mean) * rstd * ww[i].z + bb[i].z; y.w = (v[r][i].w - mean) * rstd * ww[i].w + bb[i].w;
;       if (dst) ((float4*)(dst + r * 1024))[c4] = y;
;       u32x2 pk = {cvtpk(y.x, y.y), cvtpk(y.z, y.w)}; ((u32x2*)(dstb + r * 1024))[c4] = pk; }
	v_add_f32_e32 v82, v82, v83
	s_nop 1
	v_mov_b32_dpp v83, v82 row_half_mirror row_mask:0xf bank_mask:0xf
	s_nop 1
	v_mov_b32_dpp v83, v83 quad_perm:[3,2,1,0] row_mask:0xf bank_mask:0xf
	v_xor_b32_e32 v86, 8, v128
	s_waitcnt lgkmcnt(0)
	v_add_f32_e32 v82, v82, v83
	s_nop 1
	v_mov_b32_dpp v83, v82 quad_perm:[2,3,0,1] row_mask:0xf bank_mask:0xf
	v_xor_b32_e32 v86, 4, v128
	s_waitcnt lgkmcnt(0)
	v_add_f32_e32 v82, v82, v83
	s_nop 1
	v_mov_b32_dpp v83, v82 quad_perm:[1,0,3,2] row_mask:0xf bank_mask:0xf
	s_waitcnt lgkmcnt(0)
	v_add_f32_e32 v82, v82, v83
	v_fmamk_f32 v82, v82, 0x3a800000, v103
	v_mul_f32_e32 v83, 0x4f800000, v82
	v_cmp_gt_f32_e32 vcc, s30, v82
	s_nop 1
	v_cndmask_b32_e32 v86, v82, v83, vcc
	v_sqrt_f32_e32 v87, v86
	v_lshl_add_u64 v[82:83], v[118:119], 3, s[6:7]
	v_lshl_add_u64 v[82:83], v[82:83], 0, s[16:17]
	v_add_u32_e32 v90, -1, v87
	v_add_u32_e32 v91, 1, v87
	v_fma_f32 v94, -v90, v87, v86
	v_fma_f32 v95, -v91, v87, v86
	v_cmp_ge_f32_e64 s[6:7], 0, v94
	s_nop 1
	v_cndmask_b32_e64 v87, v87, v90, s[6:7]
	v_cmp_lt_f32_e64 s[6:7], 0, v95
	s_nop 1
	v_cndmask_b32_e64 v87, v87, v91, s[6:7]
	v_mul_f32_e32 v90, 0x37800000, v87
	v_cndmask_b32_e32 v87, v87, v90, vcc
	v_cmp_class_f32_e32 vcc, v86, v105
	s_nop 1
	v_cndmask_b32_e32 v86, v87, v86, vcc
	v_rcp_f32_e32 v90, v86
	s_nop 0
	v_fma_f32 v87, -v86, v90, 1.0
	v_fma_f32 v87, v87, v90, v90
	v_div_fixup_f32 v95, v87, v86, 1.0
	s_and_saveexec_b64 s[6:7], s[4:5]
	s_cbranch_execz .LBB0_21
	v_mul_f32_e32 v94, 0x3a800000, v127
	global_store_dwordx2 v[82:83], v[94:95], off
.LBB0_21:
	s_or_b64 exec, exec, s[6:7]
	v_lshlrev_b64 v[86:87], 11, v[118:119]
	v_lshl_add_u64 v[86:87], s[8:9], 0, v[86:87]
	v_mul_f32_e32 v90, v97, v95
	v_mul_f32_e32 v91, v126, v95
	v_lshl_add_u64 v[86:87], v[86:87], 0, s[24:25]
	s_waitcnt vmcnt(3)
	v_fma_f32 v90, v45, v90, v49
	v_fma_f32 v91, v44, v91, v48
	v_mul_f32_e32 v94, v125, v95
	v_mul_f32_e32 v97, v124, v95
	v_fma_f32 v94, v43, v94, v47
	v_fma_f32 v97, v42, v97, v46
	v_cvt_pk_bf16_f32 v118, v97, v94
	v_cvt_pk_bf16_f32 v119, v91, v90
	v_lshl_add_u64 v[90:91], v[86:87], 0, v[100:101]
	global_store_dwordx2 v[90:91], v[118:119], off
	v_mul_f32_e32 v93, v93, v95
	v_mul_f32_e32 v94, v123, v95
	v_mul_f32_e32 v118, v121, v95
	s_waitcnt vmcnt(3)
	v_fma_f32 v93, v33, v93, v37
	v_fma_f32 v94, v32, v94, v36
	v_mul_f32_e32 v97, v122, v95
	v_fma_f32 v118, v30, v118, v34
	v_mul_f32_e32 v89, v89, v95
	v_mul_f32_e32 v96, v96, v95
	v_fma_f32 v97, v31, v97, v35
	v_cvt_pk_bf16_f32 v118, v118, v97
	v_cvt_pk_bf16_f32 v119, v94, v93
	s_waitcnt vmcnt(2)
	v_fma_f32 v89, v21, v89, v25
	v_mul_f32_e32 v93, v120, v95
	v_mul_f32_e32 v94, v107, v95
	v_fma_f32 v96, v18, v96, v22
	v_mul_f32_e32 v84, v84, v95
	global_store_dwordx2 v[90:91], v[118:119], off offset:512
	v_fma_f32 v93, v20, v93, v24
	v_fma_f32 v94, v19, v94, v23
	v_cvt_pk_bf16_f32 v96, v96, v94
	v_cvt_pk_bf16_f32 v97, v93, v89
	s_waitcnt vmcnt(2)
	v_fma_f32 v89, v8, v84, v12
	v_mul_f32_e32 v84, v92, v95
	v_mul_f32_e32 v85, v85, v95
	v_fma_f32 v84, v7, v84, v11
	v_mul_f32_e32 v88, v88, v95
	global_store_dwordx2 v[90:91], v[96:97], off offset:1024
	v_fma_f32 v85, v9, v85, v13
	v_fma_f32 v88, v6, v88, v10
	v_cvt_pk_bf16_f32 v84, v88, v84
	v_cvt_pk_bf16_f32 v85, v89, v85
	global_store_dwordx2 v[90:91], v[84:85], off offset:1536
	v_add_f32_e32 v84, v78, v79
	v_add_f32_e32 v84, v84, v80
	v_add_f32_e32 v85, v74, v75
	v_add_f32_e32 v84, v84, v81
	v_add_f32_e32 v85, v85, v76
	v_add_f32_e32 v84, 0, v84
	v_add_f32_e32 v85, v85, v77
	v_add_f32_e32 v84, v84, v85
	v_add_f32_e32 v85, v70, v71
	v_add_f32_e32 v85, v85, v72
	v_add_f32_e32 v85, v85, v73
	v_add_f32_e32 v84, v84, v85
	v_add_f32_e32 v85, v66, v67
	v_add_f32_e32 v85, v85, v68
	v_add_f32_e32 v85, v85, v69
	s_mov_b32 s6, -1
	v_add_f32_e32 v84, v84, v85
	s_nop 0
	v_mbcnt_lo_u32_b32 v85, s6, 0
	v_mbcnt_hi_u32_b32 v85, s6, v85
	v_lshlrev_b32_e32 v85, 2, v85
	v_xor_b32_e32 v88, 0x80, v85
	ds_bpermute_b32 v88, v88, v84
	s_mov_b32 s6, -1
	s_waitcnt lgkmcnt(0)
	v_add_f32_e32 v84, v84, v88
	v_xor_b32_e32 v88, 64, v85
	ds_bpermute_b32 v88, v88, v84
	s_waitcnt lgkmcnt(0)
	v_add_f32_e32 v84, v84, v88
	v_xor_b32_e32 v88, 32, v85
	s_nop 1
	v_mov_b32_dpp v88, v84 row_ror:8 row_mask:0xf bank_mask:0xf
	s_waitcnt lgkmcnt(0)
	v_add_f32_e32 v84, v84, v88
	v_xor_b32_e32 v88, 16, v85
	s_nop 1
	v_mov_b32_dpp v88, v84 row_half_mirror row_mask:0xf bank_mask:0xf
	s_nop 1
	v_mov_b32_dpp v88, v88 quad_perm:[3,2,1,0] row_mask:0xf bank_mask:0xf
	s_waitcnt lgkmcnt(0)
	v_add_f32_e32 v84, v84, v88
	v_xor_b32_e32 v88, 8, v85
	s_nop 1
	v_mov_b32_dpp v88, v84 quad_perm:[2,3,0,1] row_mask:0xf bank_mask:0xf
	v_xor_b32_e32 v85, 4, v85
	s_waitcnt lgkmcnt(0)
	v_add_f32_e32 v84, v84, v88
	s_nop 1
	v_mov_b32_dpp v85, v84 quad_perm:[1,0,3,2] row_mask:0xf bank_mask:0xf
	s_waitcnt lgkmcnt(0)
	v_add_f32_e32 v88, v84, v85
	v_fmamk_f32 v79, v88, 0xba800000, v79
	v_fmamk_f32 v75, v88, 0xba800000, v75
	v_fmamk_f32 v78, v88, 0xba800000, v78
	v_fmamk_f32 v85, v88, 0xba800000, v80
	v_mul_f32_e32 v84, v79, v79
	v_fmamk_f32 v74, v88, 0xba800000, v74
	v_fmamk_f32 v80, v88, 0xba800000, v76
	v_mul_f32_e32 v76, v75, v75
	v_fmac_f32_e32 v84, v78, v78
	v_fmac_f32_e32 v76, v74, v74
	v_fmac_f32_e32 v81, 0xba800000, v88
	v_fmac_f32_e32 v84, v85, v85
	v_fmac_f32_e32 v77, 0xba800000, v88
	v_fmac_f32_e32 v76, v80, v80
	v_fmac_f32_e32 v84, v81, v81
	v_fmac_f32_e32 v76, v77, v77
	v_add_f32_e32 v89, v84, v76
	v_fmamk_f32 v76, v88, 0xba800000, v71
	v_fmamk_f32 v70, v88, 0xba800000, v70
	v_mul_f32_e32 v71, v76, v76
	v_fmamk_f32 v84, v88, 0xba800000, v72
	v_fmac_f32_e32 v71, v70, v70
	v_fmac_f32_e32 v73, 0xba800000, v88
	v_fmac_f32_e32 v71, v84, v84
	v_fmac_f32_e32 v71, v73, v73
	v_fmamk_f32 v72, v88, 0xba800000, v67
	v_add_f32_e32 v89, v71, v89
	v_fmamk_f32 v71, v88, 0xba800000, v66
	v_mul_f32_e32 v66, v72, v72
	v_fmamk_f32 v68, v88, 0xba800000, v68
	v_fmac_f32_e32 v66, v71, v71
	v_mbcnt_lo_u32_b32 v67, s6, 0
	v_fmac_f32_e32 v69, 0xba800000, v88
	v_fmac_f32_e32 v66, v68, v68
	v_mbcnt_hi_u32_b32 v67, s6, v67
	v_fmac_f32_e32 v66, v69, v69
	v_lshlrev_b32_e32 v67, 2, v67
	v_add_f32_e32 v66, v66, v89
	v_xor_b32_e32 v89, 0x80, v67
	ds_bpermute_b32 v89, v89, v66
	s_waitcnt lgkmcnt(0)
; DEVFI void ln_rows4(const float* src, float* dst, bfraw* dstb, float* stats, const float* w, const float* b, int lane) {
;     ...
;   for (int r = 0; r < 4; ++r) {
;     float s = 0;
; #pragma unroll
;     for (int i = 0; i < 4; ++i) s += v[r][i].x + v[r][i].y + v[r][i].z + v[r][i].w;
;     const float mean = red64(s) * (1.f / 1024.f);
;     float q = 0;
; #pragma unroll
;     for (int i = 0; i < 4; ++i) { float a = v[r][i].x - mean, c1 = v[r][i].y - mean, c = v[r][i].z - mean, d = v[r][i].w - mean; q += a * a + c1 * c1 + c * c + d * d; }
;     const float rstd = 1.f / sqrtf(red64(q) * (1.f / 1024.f) + LN_EPS);
;     if (lane == 0) { stats[r * 2] = mean; stats[r * 2 + 1] = rstd; }
; #pragma unroll
;     for (int i = 0; i < 4; ++i) { const int c4 = i * 64 + lane;
;       float4 y; y.x = (v[r][i].x - mean) * rstd * ww[i].x + bb[i].x; y.y = (v[r][i].y - mean) * rstd * ww[i].y + bb[i].y;
;       y.z = (v[r][i].z - mean) * rstd * ww[i].z + bb[i].z; y.w = (v[r][i].w - mean) * rstd * ww[i].w + bb[i].w;
;       if (dst) ((float4*)(dst + r * 1024))[c4] = y;
;       u32x2 pk = {cvtpk(y.x, y.y), cvtpk(y.z, y.w)}; ((u32x2*)(dstb + r * 1024))[c4] = pk; }
	v_add_f32_e32 v66, v66, v89
	v_xor_b32_e32 v89, 64, v67
	ds_bpermute_b32 v89, v89, v66
	s_waitcnt lgkmcnt(0)
	v_add_f32_e32 v66, v66, v89
	v_xor_b32_e32 v89, 32, v67
	s_nop 1
	v_mov_b32_dpp v89, v66 row_ror:8 row_mask:0xf bank_mask:0xf
	s_waitcnt lgkmcnt(0)
	v_add_f32_e32 v66, v66, v89
	v_xor_b32_e32 v89, 16, v67
	s_nop 1
	v_mov_b32_dpp v89, v66 row_half_mirror row_mask:0xf bank_mask:0xf
	s_nop 1
	v_mov_b32_dpp v89, v89 quad_perm:[3,2,1,0] row_mask:0xf bank_mask:0xf
	s_waitcnt lgkmcnt(0)
	v_add_f32_e32 v66, v66, v89
	v_xor_b32_e32 v89, 8, v67
	s_nop 1
	v_mov_b32_dpp v89, v66 quad_perm:[2,3,0,1] row_mask:0xf bank_mask:0xf
	v_xor_b32_e32 v67, 4, v67
	s_waitcnt lgkmcnt(0)
	v_add_f32_e32 v66, v66, v89
	s_nop 1
	v_mov_b32_dpp v67, v66 quad_perm:[1,0,3,2] row_mask:0xf bank_mask:0xf
	s_waitcnt lgkmcnt(0)
	v_add_f32_e32 v66, v66, v67
	v_fmamk_f32 v66, v66, 0x3a800000, v103
	v_mul_f32_e32 v67, 0x4f800000, v66
	v_cmp_gt_f32_e32 vcc, s30, v66
	s_nop 1
	v_cndmask_b32_e32 v66, v66, v67, vcc
	v_sqrt_f32_e32 v67, v66
	s_nop 0
	v_add_u32_e32 v89, -1, v67
	v_fma_f32 v92, -v89, v67, v66
	v_cmp_ge_f32_e64 s[6:7], 0, v92
	v_add_u32_e32 v92, 1, v67
	s_nop 0
	v_cndmask_b32_e64 v89, v67, v89, s[6:7]
	v_fma_f32 v67, -v92, v67, v66
	v_cmp_lt_f32_e64 s[6:7], 0, v67
	s_nop 1
	v_cndmask_b32_e64 v67, v89, v92, s[6:7]
	v_mul_f32_e32 v89, 0x37800000, v67
	v_cndmask_b32_e32 v67, v67, v89, vcc
	v_cmp_class_f32_e32 vcc, v66, v105
	s_nop 1
	v_cndmask_b32_e32 v66, v67, v66, vcc
	s_nop 0
	v_rcp_f32_e32 v89, v66
	s_nop 0
	v_fma_f32 v67, -v66, v89, 1.0
	v_fma_f32 v67, v67, v89, v89
	v_div_fixup_f32 v67, v67, v66, 1.0
	s_and_saveexec_b64 s[6:7], s[4:5]
	s_cbranch_execz .LBB0_23
	v_mul_f32_e32 v66, 0x3a800000, v88
	global_store_dwordx2 v[82:83], v[66:67], off offset:8
.LBB0_23:
	s_or_b64 exec, exec, s[6:7]
	v_mul_f32_e32 v66, v81, v67
	v_mul_f32_e32 v79, v79, v67
	v_mul_f32_e32 v78, v78, v67
	v_fma_f32 v66, v45, v66, v49
	v_mul_f32_e32 v81, v85, v67
	v_fma_f32 v79, v43, v79, v47
	v_fma_f32 v78, v42, v78, v46
	v_mul_f32_e32 v74, v74, v67
	v_fma_f32 v81, v44, v81, v48
	v_cvt_pk_bf16_f32 v78, v78, v79
	v_cvt_pk_bf16_f32 v79, v81, v66
	v_mul_f32_e32 v66, v77, v67
	v_mul_f32_e32 v75, v75, v67
	v_fma_f32 v74, v30, v74, v34
	global_store_dwordx2 v[90:91], v[78:79], off offset:2048
	v_fma_f32 v66, v33, v66, v37
	v_mul_f32_e32 v77, v80, v67
	v_fma_f32 v75, v31, v75, v35
	v_cvt_pk_bf16_f32 v74, v74, v75
	v_fma_f32 v77, v32, v77, v36
	v_cvt_pk_bf16_f32 v75, v77, v66
	global_store_dwordx2 v[90:91], v[74:75], off offset:2560
	v_mul_f32_e32 v66, v73, v67
	v_mul_f32_e32 v74, v76, v67
	v_fma_f32 v66, v21, v66, v25
	v_mul_f32_e32 v73, v84, v67
	v_fma_f32 v74, v19, v74, v23
	v_mul_f32_e32 v70, v70, v67
	v_fma_f32 v73, v20, v73, v24
	v_fma_f32 v70, v18, v70, v22
	v_cvt_pk_bf16_f32 v74, v70, v74
	v_cvt_pk_bf16_f32 v75, v73, v66
	v_mul_f32_e32 v66, v69, v67
	v_fma_f32 v69, v9, v66, v13
	v_mul_f32_e32 v66, v68, v67
	v_fma_f32 v68, v8, v66, v12
	v_mul_f32_e32 v66, v72, v67
	v_fma_f32 v66, v7, v66, v11
	v_mul_f32_e32 v67, v71, v67
	global_store_dwordx2 v[90:91], v[74:75], off offset:3072
	v_fma_f32 v67, v6, v67, v10
	v_cvt_pk_bf16_f32 v66, v67, v66
	v_cvt_pk_bf16_f32 v67, v68, v69
	global_store_dwordx2 v[90:91], v[66:67], off offset:3584
	v_add_f32_e32 v66, v62, v63
	v_add_f32_e32 v66, v66, v64
	v_add_f32_e32 v67, v58, v59
	v_add_f32_e32 v66, v66, v65
	v_add_f32_e32 v67, v67, v60
	v_add_f32_e32 v66, 0, v66
	v_add_f32_e32 v67, v67, v61
	v_add_f32_e32 v66, v66, v67
	v_add_f32_e32 v67, v54, v55
	v_add_f32_e32 v67, v67, v56
	v_add_f32_e32 v67, v67, v57
	v_add_f32_e32 v66, v66, v67
	v_add_f32_e32 v67, v50, v51
	v_add_f32_e32 v67, v67, v52
	v_add_f32_e32 v67, v67, v53
	s_mov_b32 s6, -1
	v_add_f32_e32 v66, v66, v67
	s_nop 0
	v_mbcnt_lo_u32_b32 v67, s6, 0
	v_mbcnt_hi_u32_b32 v67, s6, v67
	v_lshlrev_b32_e32 v67, 2, v67
	v_xor_b32_e32 v68, 0x80, v67
	ds_bpermute_b32 v68, v68, v66
	s_mov_b32 s6, -1
	s_waitcnt lgkmcnt(0)
	v_add_f32_e32 v66, v66, v68
	v_xor_b32_e32 v68, 64, v67
	ds_bpermute_b32 v68, v68, v66
	s_waitcnt lgkmcnt(0)
	v_add_f32_e32 v66, v66, v68
	v_xor_b32_e32 v68, 32, v67
	s_nop 1
	v_mov_b32_dpp v68, v66 row_ror:8 row_mask:0xf bank_mask:0xf
	s_waitcnt lgkmcnt(0)
	v_add_f32_e32 v66, v66, v68
	v_xor_b32_e32 v68, 16, v67
	s_nop 1
	v_mov_b32_dpp v68, v66 row_half_mirror row_mask:0xf bank_mask:0xf
	s_nop 1
	v_mov_b32_dpp v68, v68 quad_perm:[3,2,1,0] row_mask:0xf bank_mask:0xf
	s_waitcnt lgkmcnt(0)
	v_add_f32_e32 v66, v66, v68
	v_xor_b32_e32 v68, 8, v67
	s_nop 1
	v_mov_b32_dpp v68, v66 quad_perm:[2,3,0,1] row_mask:0xf bank_mask:0xf
	v_xor_b32_e32 v67, 4, v67
	s_waitcnt lgkmcnt(0)
	v_add_f32_e32 v66, v66, v68
	s_nop 1
	v_mov_b32_dpp v67, v66 quad_perm:[1,0,3,2] row_mask:0xf bank_mask:0xf
	s_waitcnt lgkmcnt(0)
	v_add_f32_e32 v70, v66, v67
	v_fmamk_f32 v68, v70, 0xba800000, v63
	v_fmamk_f32 v69, v70, 0xba800000, v64
	v_fmamk_f32 v64, v70, 0xba800000, v59
	v_fmamk_f32 v66, v70, 0xba800000, v62
	v_mul_f32_e32 v63, v68, v68
	v_fmamk_f32 v62, v70, 0xba800000, v58
	v_mul_f32_e32 v58, v64, v64
	v_fmac_f32_e32 v63, v66, v66
	v_fmamk_f32 v67, v70, 0xba800000, v60
	v_fmac_f32_e32 v58, v62, v62
	v_fmac_f32_e32 v65, 0xba800000, v70
	v_fmac_f32_e32 v63, v69, v69
	v_fmac_f32_e32 v61, 0xba800000, v70
	v_fmac_f32_e32 v58, v67, v67
	v_fmac_f32_e32 v63, v65, v65
	v_fmac_f32_e32 v58, v61, v61
	v_fmamk_f32 v55, v70, 0xba800000, v55
	v_add_f32_e32 v58, v63, v58
	v_fmamk_f32 v54, v70, 0xba800000, v54
	v_fmamk_f32 v63, v70, 0xba800000, v56
	v_mul_f32_e32 v56, v55, v55
	v_fmac_f32_e32 v56, v54, v54
	v_fmac_f32_e32 v57, 0xba800000, v70
	v_fmac_f32_e32 v56, v63, v63
	v_fmac_f32_e32 v56, v57, v57
	v_fmamk_f32 v60, v70, 0xba800000, v51
	v_add_f32_e32 v58, v56, v58
	v_fmamk_f32 v56, v70, 0xba800000, v50
	v_mul_f32_e32 v50, v60, v60
	v_fmamk_f32 v52, v70, 0xba800000, v52
	v_fmac_f32_e32 v50, v56, v56
	v_mbcnt_lo_u32_b32 v51, s6, 0
	v_fmac_f32_e32 v53, 0xba800000, v70
	v_fmac_f32_e32 v50, v52, v52
	v_mbcnt_hi_u32_b32 v51, s6, v51
	v_fmac_f32_e32 v50, v53, v53
	v_lshlrev_b32_e32 v51, 2, v51
	v_add_f32_e32 v50, v50, v58
	v_xor_b32_e32 v58, 0x80, v51
	ds_bpermute_b32 v58, v58, v50
	s_waitcnt lgkmcnt(0)
; DEVFI int lane_opaque() { unsigned m = ~0u; asm volatile("" : "+s"(m)); return (int)__builtin_amdgcn_mbcnt_hi(m, __builtin_amdgcn_mbcnt_lo(m, 0u)); }
; DEVFI float shx(float v, int mask, int lane) { return __int_as_float(__builtin_amdgcn_ds_bpermute((lane ^ mask) << 2, __float_as_int(v))); }
; DEVFI float red64(float v) {
;   const int ln = lane_opaque();
;   v += shx(v, 32, ln); v += shx(v, 16, ln); v += shx(v, 8, ln); v += shx(v, 4, ln); v += shx(v, 2, ln); v += shx(v, 1, ln); return v;
; }
; DEVFI void ln_rows4(const float* src, float* dst, bfraw* dstb, float* stats, const float* w, const float* b, int lane) {
;     ...
;     const float rstd = 1.f / sqrtf(red64(q) * (1.f / 1024.f) + LN_EPS);
;     if (lane == 0) { stats[r * 2] = mean; stats[r * 2 + 1] = rstd; }
	v_add_f32_e32 v50, v50, v58
	v_xor_b32_e32 v58, 64, v51
	ds_bpermute_b32 v58, v58, v50
	s_waitcnt lgkmcnt(0)
	v_add_f32_e32 v50, v50, v58
	v_xor_b32_e32 v58, 32, v51
	s_nop 1
	v_mov_b32_dpp v58, v50 row_ror:8 row_mask:0xf bank_mask:0xf
	s_waitcnt lgkmcnt(0)
	v_add_f32_e32 v50, v50, v58
	v_xor_b32_e32 v58, 16, v51
	s_nop 1
	v_mov_b32_dpp v58, v50 row_half_mirror row_mask:0xf bank_mask:0xf
	s_nop 1
	v_mov_b32_dpp v58, v58 quad_perm:[3,2,1,0] row_mask:0xf bank_mask:0xf
	s_waitcnt lgkmcnt(0)
	v_add_f32_e32 v50, v50, v58
	v_xor_b32_e32 v58, 8, v51
	s_nop 1
	v_mov_b32_dpp v58, v50 quad_perm:[2,3,0,1] row_mask:0xf bank_mask:0xf
	v_xor_b32_e32 v51, 4, v51
	s_waitcnt lgkmcnt(0)
	v_add_f32_e32 v50, v50, v58
	s_nop 1
	v_mov_b32_dpp v51, v50 quad_perm:[1,0,3,2] row_mask:0xf bank_mask:0xf
	s_waitcnt lgkmcnt(0)
	v_add_f32_e32 v50, v50, v51
	v_fmamk_f32 v50, v50, 0x3a800000, v103
	v_mul_f32_e32 v51, 0x4f800000, v50
	v_cmp_gt_f32_e32 vcc, s30, v50
	s_nop 1
	v_cndmask_b32_e32 v50, v50, v51, vcc
	v_sqrt_f32_e32 v51, v50
	s_nop 0
	v_add_u32_e32 v58, -1, v51
	v_fma_f32 v59, -v58, v51, v50
	v_cmp_ge_f32_e64 s[6:7], 0, v59
	v_add_u32_e32 v59, 1, v51
	s_nop 0
	v_cndmask_b32_e64 v58, v51, v58, s[6:7]
	v_fma_f32 v51, -v59, v51, v50
	v_cmp_lt_f32_e64 s[6:7], 0, v51
	s_nop 1
	v_cndmask_b32_e64 v51, v58, v59, s[6:7]
	v_mul_f32_e32 v58, 0x37800000, v51
	v_cndmask_b32_e32 v51, v51, v58, vcc
	v_cmp_class_f32_e32 vcc, v50, v105
	s_nop 1
	v_cndmask_b32_e32 v50, v51, v50, vcc
	s_nop 0
	v_rcp_f32_e32 v58, v50
	s_nop 0
	v_fma_f32 v51, -v50, v58, 1.0
	v_fma_f32 v51, v51, v58, v58
	v_div_fixup_f32 v59, v51, v50, 1.0
	s_and_saveexec_b64 s[6:7], s[4:5]
	s_cbranch_execz .LBB0_25
	v_mul_f32_e32 v58, 0x3a800000, v70
	global_store_dwordx2 v[82:83], v[58:59], off offset:16
; DEVFI void ln_rows4(const float* src, float* dst, bfraw* dstb, float* stats, const float* w, const float* b, int lane) {
;     ...
;   for (int r = 0; r < 4; ++r) {
;     float s = 0;
; #pragma unroll
;     for (int i = 0; i < 4; ++i) s += v[r][i].x + v[r][i].y + v[r][i].z + v[r][i].w;
;     const float mean = red64(s) * (1.f / 1024.f);
;     float q = 0;
; #pragma unroll
;     for (int i = 0; i < 4; ++i) { float a = v[r][i].x - mean, c1 = v[r][i].y - mean, c = v[r][i].z - mean, d = v[r][i].w - mean; q += a * a + c1 * c1 + c * c + d * d; }
;     const float rstd = 1.f / sqrtf(red64(q) * (1.f / 1024.f) + LN_EPS);
;     if (lane == 0) { stats[r * 2] = mean; stats[r * 2 + 1] = rstd; }
; #pragma unroll
;     for (int i = 0; i < 4; ++i) { const int c4 = i * 64 + lane;
;       float4 y; y.x = (v[r][i].x - mean) * rstd * ww[i].x + bb[i].x; y.y = (v[r][i].y - mean) * rstd * ww[i].y + bb[i].y;
;       y.z = (v[r][i].z - mean) * rstd * ww[i].z + bb[i].z; y.w = (v[r][i].w - mean) * rstd * ww[i].w + bb[i].w;
;       if (dst) ((float4*)(dst + r * 1024))[c4] = y;
;       u32x2 pk = {cvtpk(y.x, y.y), cvtpk(y.z, y.w)}; ((u32x2*)(dstb + r * 1024))[c4] = pk; }
.LBB0_25:
	s_or_b64 exec, exec, s[6:7]
	v_mul_f32_e32 v50, v65, v59
	v_fma_f32 v51, v45, v50, v49
	v_mul_f32_e32 v50, v69, v59
	v_fma_f32 v58, v44, v50, v48
	v_mul_f32_e32 v50, v68, v59
	v_lshl_add_u64 v[70:71], v[86:87], 0, s[18:19]
	v_fma_f32 v50, v43, v50, v47
	v_mul_f32_e32 v65, v66, v59
	v_fma_f32 v65, v42, v65, v46
	v_cvt_pk_bf16_f32 v50, v65, v50
	v_cvt_pk_bf16_f32 v51, v58, v51
	v_lshl_add_u64 v[68:69], v[70:71], 0, v[100:101]
	global_store_dwordx2 v[68:69], v[50:51], off
	v_mul_f32_e32 v50, v61, v59
	v_mul_f32_e32 v51, v67, v59
	v_fma_f32 v50, v33, v50, v37
	v_fma_f32 v51, v32, v51, v36
	v_mul_f32_e32 v58, v64, v59
	v_mul_f32_e32 v61, v62, v59
	v_fma_f32 v58, v31, v58, v35
	v_fma_f32 v61, v30, v61, v34
	v_cvt_pk_bf16_f32 v64, v61, v58
	v_cvt_pk_bf16_f32 v65, v51, v50
	v_lshlrev_b32_e32 v50, 3, v102
	v_mov_b32_e32 v51, v101
	v_mul_f32_e32 v57, v57, v59
	v_mul_f32_e32 v55, v55, v59
	v_mul_f32_e32 v54, v54, v59
	v_lshl_add_u64 v[66:67], v[70:71], 0, v[50:51]
	v_fma_f32 v57, v21, v57, v25
	v_mul_f32_e32 v58, v63, v59
	v_fma_f32 v55, v19, v55, v23
	v_fma_f32 v54, v18, v54, v22
	global_store_dwordx2 v[66:67], v[64:65], off
	v_fma_f32 v58, v20, v58, v24
	v_cvt_pk_bf16_f32 v62, v54, v55
	v_cvt_pk_bf16_f32 v63, v58, v57
	v_lshlrev_b32_e32 v54, 3, v104
	v_mov_b32_e32 v55, v101
	v_mul_f32_e32 v53, v53, v59
	v_mul_f32_e32 v52, v52, v59
	v_mul_f32_e32 v57, v60, v59
	v_mul_f32_e32 v56, v56, v59
	v_lshl_add_u64 v[64:65], v[70:71], 0, v[54:55]
	v_fma_f32 v53, v9, v53, v13
	v_fma_f32 v52, v8, v52, v12
	v_fma_f32 v57, v7, v57, v11
	v_fma_f32 v56, v6, v56, v10
	global_store_dwordx2 v[64:65], v[62:63], off
	v_cvt_pk_bf16_f32 v56, v56, v57
	v_cvt_pk_bf16_f32 v57, v52, v53
	v_lshlrev_b32_e32 v52, 3, v106
	v_mov_b32_e32 v53, v101
	v_lshl_add_u64 v[58:59], v[70:71], 0, v[52:53]
	global_store_dwordx2 v[58:59], v[56:57], off
	v_add_f32_e32 v56, v38, v39
	v_add_f32_e32 v56, v56, v40
	v_add_f32_e32 v57, v26, v27
	v_add_f32_e32 v56, v56, v41
	v_add_f32_e32 v57, v57, v28
	v_add_f32_e32 v56, 0, v56
	v_add_f32_e32 v57, v57, v29
	v_add_f32_e32 v56, v56, v57
	v_add_f32_e32 v57, v14, v15
	v_add_f32_e32 v57, v57, v16
	v_add_f32_e32 v57, v57, v17
	v_add_f32_e32 v56, v56, v57
	v_add_f32_e32 v57, v2, v3
	v_add_f32_e32 v57, v57, v4
	v_add_f32_e32 v57, v57, v5
	s_mov_b32 s6, -1
	v_add_f32_e32 v56, v56, v57
	s_nop 0
	v_mbcnt_lo_u32_b32 v57, s6, 0
	v_mbcnt_hi_u32_b32 v57, s6, v57
	v_lshlrev_b32_e32 v57, 2, v57
	v_xor_b32_e32 v58, 0x80, v57
	ds_bpermute_b32 v58, v58, v56
	s_mov_b32 s6, -1
	s_waitcnt lgkmcnt(0)
	v_add_f32_e32 v56, v56, v58
	v_xor_b32_e32 v58, 64, v57
	ds_bpermute_b32 v58, v58, v56
	s_waitcnt lgkmcnt(0)
	v_add_f32_e32 v56, v56, v58
	v_xor_b32_e32 v58, 32, v57
	s_nop 1
	v_mov_b32_dpp v58, v56 row_ror:8 row_mask:0xf bank_mask:0xf
	s_waitcnt lgkmcnt(0)
	v_add_f32_e32 v56, v56, v58
	v_xor_b32_e32 v58, 16, v57
	s_nop 1
	v_mov_b32_dpp v58, v56 row_half_mirror row_mask:0xf bank_mask:0xf
	s_nop 1
	v_mov_b32_dpp v58, v58 quad_perm:[3,2,1,0] row_mask:0xf bank_mask:0xf
	s_waitcnt lgkmcnt(0)
	v_add_f32_e32 v56, v56, v58
	v_xor_b32_e32 v58, 8, v57
	s_nop 1
	v_mov_b32_dpp v58, v56 quad_perm:[2,3,0,1] row_mask:0xf bank_mask:0xf
	v_xor_b32_e32 v57, 4, v57
	s_waitcnt lgkmcnt(0)
	v_add_f32_e32 v56, v56, v58
	s_nop 1
	v_mov_b32_dpp v57, v56 quad_perm:[1,0,3,2] row_mask:0xf bank_mask:0xf
	s_waitcnt lgkmcnt(0)
	v_add_f32_e32 v58, v56, v57
	v_fmamk_f32 v57, v58, 0xba800000, v39
	v_fmamk_f32 v39, v58, 0xba800000, v27
	v_fmamk_f32 v56, v58, 0xba800000, v38
	v_mul_f32_e32 v59, v57, v57
	v_fmamk_f32 v38, v58, 0xba800000, v26
	v_mul_f32_e32 v26, v39, v39
	v_fmamk_f32 v40, v58, 0xba800000, v40
	v_fmac_f32_e32 v59, v56, v56
	v_fmamk_f32 v28, v58, 0xba800000, v28
	v_fmac_f32_e32 v26, v38, v38
	v_fmac_f32_e32 v41, 0xba800000, v58
	v_fmac_f32_e32 v59, v40, v40
	v_fmac_f32_e32 v29, 0xba800000, v58
	v_fmac_f32_e32 v26, v28, v28
	v_fmac_f32_e32 v59, v41, v41
	v_fmac_f32_e32 v26, v29, v29
	v_fmamk_f32 v27, v58, 0xba800000, v15
	v_add_f32_e32 v59, v59, v26
	v_fmamk_f32 v26, v58, 0xba800000, v14
	v_mul_f32_e32 v14, v27, v27
	v_fmamk_f32 v16, v58, 0xba800000, v16
	v_fmac_f32_e32 v14, v26, v26
	v_fmac_f32_e32 v17, 0xba800000, v58
	v_fmac_f32_e32 v14, v16, v16
	v_fmac_f32_e32 v14, v17, v17
	v_fmamk_f32 v15, v58, 0xba800000, v3
	v_add_f32_e32 v59, v14, v59
	v_fmamk_f32 v14, v58, 0xba800000, v2
	v_mul_f32_e32 v2, v15, v15
	v_fmamk_f32 v4, v58, 0xba800000, v4
	v_fmac_f32_e32 v2, v14, v14
	v_mbcnt_lo_u32_b32 v3, s6, 0
	v_fmac_f32_e32 v5, 0xba800000, v58
	v_fmac_f32_e32 v2, v4, v4
	v_mbcnt_hi_u32_b32 v3, s6, v3
	v_fmac_f32_e32 v2, v5, v5
	v_lshlrev_b32_e32 v3, 2, v3
	v_add_f32_e32 v2, v2, v59
	v_xor_b32_e32 v59, 0x80, v3
	ds_bpermute_b32 v59, v59, v2
	s_waitcnt lgkmcnt(0)
	v_add_f32_e32 v2, v2, v59
	v_xor_b32_e32 v59, 64, v3
	ds_bpermute_b32 v59, v59, v2
	s_waitcnt lgkmcnt(0)
	v_add_f32_e32 v2, v2, v59
	v_xor_b32_e32 v59, 32, v3
	s_nop 1
	v_mov_b32_dpp v59, v2 row_ror:8 row_mask:0xf bank_mask:0xf
	s_waitcnt lgkmcnt(0)
	v_add_f32_e32 v2, v2, v59
	v_xor_b32_e32 v59, 16, v3
	s_nop 1
	v_mov_b32_dpp v59, v2 row_half_mirror row_mask:0xf bank_mask:0xf
	s_nop 1
	v_mov_b32_dpp v59, v59 quad_perm:[3,2,1,0] row_mask:0xf bank_mask:0xf
	s_waitcnt lgkmcnt(0)
	v_add_f32_e32 v2, v2, v59
	v_xor_b32_e32 v59, 8, v3
	s_nop 1
	v_mov_b32_dpp v59, v2 quad_perm:[2,3,0,1] row_mask:0xf bank_mask:0xf
	v_xor_b32_e32 v3, 4, v3
	s_waitcnt lgkmcnt(0)
	v_add_f32_e32 v2, v2, v59
	s_nop 1
	v_mov_b32_dpp v3, v2 quad_perm:[1,0,3,2] row_mask:0xf bank_mask:0xf
	s_waitcnt lgkmcnt(0)
	v_add_f32_e32 v2, v2, v3
	v_fmamk_f32 v2, v2, 0x3a800000, v103
	v_mul_f32_e32 v3, 0x4f800000, v2
	v_cmp_gt_f32_e32 vcc, s30, v2
	s_nop 1
	v_cndmask_b32_e32 v2, v2, v3, vcc
	v_sqrt_f32_e32 v3, v2
	s_nop 0
	v_add_u32_e32 v59, -1, v3
	v_fma_f32 v60, -v59, v3, v2
	v_cmp_ge_f32_e64 s[6:7], 0, v60
	v_add_u32_e32 v60, 1, v3
	s_nop 0
	v_cndmask_b32_e64 v59, v3, v59, s[6:7]
	v_fma_f32 v3, -v60, v3, v2
	v_cmp_lt_f32_e64 s[6:7], 0, v3
	s_nop 1
	v_cndmask_b32_e64 v3, v59, v60, s[6:7]
	v_mul_f32_e32 v59, 0x37800000, v3
	v_cndmask_b32_e32 v3, v3, v59, vcc
	v_cmp_class_f32_e32 vcc, v2, v105
	s_nop 1
	v_cndmask_b32_e32 v2, v3, v2, vcc
	s_nop 0
	v_rcp_f32_e32 v59, v2
	s_nop 0
	v_fma_f32 v3, -v2, v59, 1.0
	v_fma_f32 v3, v3, v59, v59
	v_div_fixup_f32 v3, v3, v2, 1.0
	s_and_saveexec_b64 s[6:7], s[4:5]
	s_cbranch_execz .LBB0_14
	v_mul_f32_e32 v2, 0x3a800000, v58
	global_store_dwordx2 v[82:83], v[2:3], off offset:24
	s_branch .LBB0_14

; DEVFI int lane_opaque() { unsigned m = ~0u; asm volatile("" : "+s"(m)); return (int)__builtin_amdgcn_mbcnt_hi(m, __builtin_amdgcn_mbcnt_lo(m, 0u)); }
; DEVFI float shx(float v, int mask, int lane) { return __int_as_float(__builtin_amdgcn_ds_bpermute((lane ^ mask) << 2, __float_as_int(v))); }
; #define ATTT ((float2*)(kargs()->ws + O_ATTT))
; DEVFI float red16(float v) {
;   const int ln = lane_opaque();
;   v += shx(v, 1, ln); v += shx(v, 2, ln); v += shx(v, 4, ln); v += shx(v, 8, ln); return v;
; }
; __global__ void __launch_bounds__(512) mega(Params p) {
;     ...
;                     const bool isk = c0 >= 7168; const float* nw = isk ? kn_w : qn_w; const float2* attt = ATTT;
; #pragma unroll
;                     for (int j = 0; j < 4; ++j) { const int pos = (r0 + j) & (seqlen - 1);
;                       float ss = 0;
; #pragma unroll
;                       for (int n = 0; n < 8; ++n) ss += a[n][j] * a[n][j];
;                       ss = red16(ss);
;                       const float rstd = 1.f / sqrtf(ss * (1.f / 128.f) + RMS_EPS);
; #pragma unroll
;                       for (int n = 0; n < 8; ++n) a[n][j] = a[n][j] * rstd * hv[n];
;                       const float4* tb = (const float4*)(attt + pos * 64 + fr * 4);
;                       const float4 t01 = tb[0], t23 = tb[1];
;                       const float2 csv[4] = {make_float2(t01.x, t01.y), make_float2(t01.z, t01.w), make_float2(t23.x, t23.y), make_float2(t23.z, t23.w)};
; #pragma unroll
;                       for (int hh = 0; hh < 2; ++hh)
; #pragma unroll
;                         for (int n = 0; n < 2; ++n) { const float2 cs = csv[hh * 2 + n];
;                           const float x1 = a[hh * 4 + n][j], x2 = a[hh * 4 + n + 2][j];
;                           a[hh * 4 + n][j] = x1 * cs.x - x2 * cs.y; a[hh * 4 + n + 2][j] = x1 * cs.y + x2 * cs.x; } }
.LBB0_763:
	s_mov_b64 s[2:3], s[0:1]
	s_load_dwordx2 s[2:3], s[2:3], 0xe8
	v_mul_f32_e32 v128, v120, v120
	v_fmac_f32_e32 v128, v124, v124
	v_fmac_f32_e32 v128, v108, v108
	v_fmac_f32_e32 v128, v104, v104
	s_waitcnt lgkmcnt(0)
	s_add_u32 s36, s2, 0x3da0000
	s_mov_b32 s2, -1
	v_fmac_f32_e32 v128, v116, v116
	v_fmac_f32_e32 v128, v112, v112
	v_mbcnt_lo_u32_b32 v129, s2, 0
	v_mbcnt_hi_u32_b32 v129, s2, v129
	v_fmac_f32_e32 v128, v100, v100
	v_lshlrev_b32_e32 v129, 2, v129
	v_fmac_f32_e32 v128, v96, v96
	v_xor_b32_e32 v130, 4, v129
	s_nop 1
	v_mov_b32_dpp v130, v128 quad_perm:[1,0,3,2] row_mask:0xf bank_mask:0xf
	v_mov_b32_e32 v170, 0x358637bd
	s_addc_u32 s37, s3, 0
	s_waitcnt lgkmcnt(0)
	v_add_f32_e32 v128, v128, v130
	v_xor_b32_e32 v130, 8, v129
	s_nop 1
	v_mov_b32_dpp v130, v128 quad_perm:[2,3,0,1] row_mask:0xf bank_mask:0xf
	s_waitcnt lgkmcnt(0)
	v_add_f32_e32 v128, v128, v130
	v_xor_b32_e32 v130, 16, v129
	s_nop 1
	v_mov_b32_dpp v130, v128 row_half_mirror row_mask:0xf bank_mask:0xf
	s_nop 1
	v_mov_b32_dpp v130, v130 quad_perm:[3,2,1,0] row_mask:0xf bank_mask:0xf
	v_xor_b32_e32 v129, 32, v129
	s_waitcnt lgkmcnt(0)
	v_add_f32_e32 v128, v128, v130
	s_nop 1
	v_mov_b32_dpp v129, v128 row_ror:8 row_mask:0xf bank_mask:0xf
	s_waitcnt lgkmcnt(0)
	v_add_f32_e32 v128, v128, v129
	v_fmamk_f32 v128, v128, 0x3c000000, v170
	v_cmp_gt_f32_e32 vcc, s30, v128
	v_mul_f32_e32 v129, 0x4f800000, v128
	s_nop 0
	v_cndmask_b32_e32 v128, v128, v129, vcc
	v_sqrt_f32_e32 v129, v128
	s_nop 0
	v_add_u32_e32 v130, -1, v129
	v_fma_f32 v131, -v130, v129, v128
	v_cmp_ge_f32_e64 s[6:7], 0, v131
	v_add_u32_e32 v131, 1, v129
	s_nop 0
	v_cndmask_b32_e64 v130, v129, v130, s[6:7]
	v_fma_f32 v129, -v131, v129, v128
	v_cmp_lt_f32_e64 s[6:7], 0, v129
	s_nop 1
	v_cndmask_b32_e64 v129, v130, v131, s[6:7]
	v_mul_f32_e32 v130, 0x37800000, v129
	v_cndmask_b32_e32 v129, v129, v130, vcc
	v_cmp_class_f32_e32 vcc, v128, v222
	s_nop 1
	v_cndmask_b32_e32 v128, v129, v128, vcc
	s_mov_b32 s2, -1
	v_rcp_f32_e32 v130, v128
	s_nop 0
	v_fma_f32 v129, -v128, v130, 1.0
	v_fma_f32 v129, v129, v130, v130
	v_div_fixup_f32 v128, v129, v128, 1.0
	v_mul_f32_e32 v129, v124, v128
	s_waitcnt vmcnt(0)
	v_mul_f32_e32 v133, v224, v129
	v_mul_f32_e32 v129, v120, v128
	v_mul_f32_e32 v134, v223, v129
	v_mul_f32_e32 v129, v108, v128
	v_mul_f32_e32 v135, v212, v129
	v_mul_f32_e32 v129, v104, v128
	v_mul_f32_e32 v136, v211, v129
	v_mul_f32_e32 v129, v116, v128
	v_mul_f32_e32 v141, v210, v129
	v_mul_f32_e32 v129, v112, v128
	v_mul_f32_e32 v150, v209, v129
	v_mul_f32_e32 v129, v100, v128
	v_mul_f32_e32 v128, v96, v128
	v_mul_f32_e32 v152, v207, v128
	v_and_b32_e32 v128, s14, v162
	v_mul_f32_e32 v151, v208, v129
	v_lshlrev_b32_e32 v128, 6, v128
	v_mov_b32_e32 v129, v177
	v_lshl_add_u64 v[130:131], v[128:129], 3, s[36:37]
	v_lshlrev_b32_e32 v128, 3, v132
	v_lshl_add_u64 v[130:131], v[130:131], 0, v[128:129]
	global_load_dwordx4 v[142:145], v[130:131], off offset:16
	global_load_dwordx4 v[146:149], v[130:131], off
	v_add_u32_e32 v131, 1, v162
	s_waitcnt vmcnt(0)
	v_mul_f32_e32 v130, v147, v135
	v_fma_f32 v139, v146, v133, -v130
	v_mul_f32_e32 v130, v149, v136
	v_fma_f32 v140, v148, v134, -v130
	v_mul_f32_e32 v130, v143, v151
	v_mul_f32_e32 v137, v146, v135
	v_fma_f32 v135, v142, v141, -v130
	v_mul_f32_e32 v130, v145, v152
	v_mul_f32_e32 v138, v148, v136
	v_fma_f32 v136, v144, v150, -v130
	v_mul_f32_e32 v130, v121, v121
	v_fmac_f32_e32 v130, v125, v125
	v_fmac_f32_e32 v130, v109, v109
	v_fmac_f32_e32 v137, v147, v133
	v_mul_f32_e32 v133, v142, v151
	v_fmac_f32_e32 v130, v105, v105
	v_fmac_f32_e32 v133, v143, v141
	v_fmac_f32_e32 v130, v117, v117
	v_mbcnt_lo_u32_b32 v141, s2, 0
	v_fmac_f32_e32 v130, v113, v113
	v_mbcnt_hi_u32_b32 v141, s2, v141
	v_fmac_f32_e32 v130, v101, v101
	v_lshlrev_b32_e32 v141, 2, v141
	v_fmac_f32_e32 v130, v97, v97
	v_xor_b32_e32 v142, 4, v141
	s_nop 1
	v_mov_b32_dpp v142, v130 quad_perm:[1,0,3,2] row_mask:0xf bank_mask:0xf
	v_fmac_f32_e32 v138, v149, v134
	v_mul_f32_e32 v134, v144, v152
	v_fmac_f32_e32 v134, v145, v150
	s_waitcnt lgkmcnt(0)
	v_add_f32_e32 v130, v130, v142
	v_xor_b32_e32 v142, 8, v141
	s_nop 1
	v_mov_b32_dpp v142, v130 quad_perm:[2,3,0,1] row_mask:0xf bank_mask:0xf
	s_waitcnt lgkmcnt(0)
	v_add_f32_e32 v130, v130, v142
	v_xor_b32_e32 v142, 16, v141
	s_nop 1
	v_mov_b32_dpp v142, v130 row_half_mirror row_mask:0xf bank_mask:0xf
	s_nop 1
	v_mov_b32_dpp v142, v142 quad_perm:[3,2,1,0] row_mask:0xf bank_mask:0xf
	v_xor_b32_e32 v141, 32, v141
	s_waitcnt lgkmcnt(0)
	v_add_f32_e32 v130, v130, v142
	s_nop 1
	v_mov_b32_dpp v141, v130 row_ror:8 row_mask:0xf bank_mask:0xf
	s_waitcnt lgkmcnt(0)
	v_add_f32_e32 v130, v130, v141
	v_fmamk_f32 v130, v130, 0x3c000000, v170
	v_cmp_gt_f32_e32 vcc, s30, v130
	v_mul_f32_e32 v141, 0x4f800000, v130
	s_nop 0
	v_cndmask_b32_e32 v130, v130, v141, vcc
	v_sqrt_f32_e32 v141, v130
	s_nop 0
	v_add_u32_e32 v142, -1, v141
	v_fma_f32 v143, -v142, v141, v130
	v_cmp_ge_f32_e64 s[6:7], 0, v143
	v_add_u32_e32 v143, 1, v141
	s_nop 0
	v_cndmask_b32_e64 v142, v141, v142, s[6:7]
	v_fma_f32 v141, -v143, v141, v130
	v_cmp_lt_f32_e64 s[6:7], 0, v141
	s_nop 1
	v_cndmask_b32_e64 v141, v142, v143, s[6:7]
	v_mul_f32_e32 v142, 0x37800000, v141
	v_cndmask_b32_e32 v141, v141, v142, vcc
	v_cmp_class_f32_e32 vcc, v130, v222
	s_nop 1
	v_cndmask_b32_e32 v130, v141, v130, vcc
	s_mov_b32 s2, -1
	v_rcp_f32_e32 v142, v130
	s_nop 0
	v_fma_f32 v141, -v130, v142, 1.0
	v_fma_f32 v141, v141, v142, v142
	v_div_fixup_f32 v130, v141, v130, 1.0
	v_mul_f32_e32 v145, v117, v130
	v_mul_f32_e32 v149, v210, v145
	v_mul_f32_e32 v145, v113, v130
	v_mul_f32_e32 v141, v125, v130
	v_mul_f32_e32 v142, v121, v130
	v_mul_f32_e32 v143, v109, v130
	v_mul_f32_e32 v144, v105, v130
	v_mul_f32_e32 v158, v209, v145
	v_mul_f32_e32 v145, v101, v130
	v_mul_f32_e32 v130, v97, v130
	v_mul_f32_e32 v160, v207, v130
	v_and_b32_e32 v130, s14, v131
	v_lshlrev_b32_e32 v130, 6, v130
	v_mov_b32_e32 v131, v177
	v_lshl_add_u64 v[130:131], v[130:131], 3, s[36:37]
	v_lshl_add_u64 v[130:131], v[130:131], 0, v[128:129]
	global_load_dwordx4 v[150:153], v[130:131], off offset:16
	global_load_dwordx4 v[154:157], v[130:131], off
	v_mul_f32_e32 v143, v212, v143
	v_mul_f32_e32 v141, v224, v141
	v_mul_f32_e32 v144, v211, v144
	v_mul_f32_e32 v142, v223, v142
	v_mul_f32_e32 v159, v208, v145
	v_add_u32_e32 v131, 2, v162
	s_waitcnt vmcnt(0)
; DEVFI int lane_opaque() { unsigned m = ~0u; asm volatile("" : "+s"(m)); return (int)__builtin_amdgcn_mbcnt_hi(m, __builtin_amdgcn_mbcnt_lo(m, 0u)); }
; DEVFI float shx(float v, int mask, int lane) { return __int_as_float(__builtin_amdgcn_ds_bpermute((lane ^ mask) << 2, __float_as_int(v))); }
; DEVFI float red16(float v) {
;   const int ln = lane_opaque();
;   v += shx(v, 1, ln); v += shx(v, 2, ln); v += shx(v, 4, ln); v += shx(v, 8, ln); return v;
; }
; __global__ void __launch_bounds__(512) mega(Params p) {
;     ...
;                     for (int j = 0; j < 4; ++j) { const int pos = (r0 + j) & (seqlen - 1);
;                       float ss = 0;
; #pragma unroll
;                       for (int n = 0; n < 8; ++n) ss += a[n][j] * a[n][j];
;                       ss = red16(ss);
;                       const float rstd = 1.f / sqrtf(ss * (1.f / 128.f) + RMS_EPS);
; #pragma unroll
;                       for (int n = 0; n < 8; ++n) a[n][j] = a[n][j] * rstd * hv[n];
;                       const float4* tb = (const float4*)(attt + pos * 64 + fr * 4);
;                       const float4 t01 = tb[0], t23 = tb[1];
;                       const float2 csv[4] = {make_float2(t01.x, t01.y), make_float2(t01.z, t01.w), make_float2(t23.x, t23.y), make_float2(t23.z, t23.w)};
; #pragma unroll
;                       for (int hh = 0; hh < 2; ++hh)
; #pragma unroll
;                         for (int n = 0; n < 2; ++n) { const float2 cs = csv[hh * 2 + n];
;                           const float x1 = a[hh * 4 + n][j], x2 = a[hh * 4 + n + 2][j];
;                           a[hh * 4 + n][j] = x1 * cs.x - x2 * cs.y; a[hh * 4 + n + 2][j] = x1 * cs.y + x2 * cs.x; } }
	v_mul_f32_e32 v130, v155, v143
	v_fma_f32 v147, v154, v141, -v130
	v_mul_f32_e32 v130, v157, v144
	v_fma_f32 v148, v156, v142, -v130
	v_mul_f32_e32 v130, v151, v159
	v_mul_f32_e32 v145, v154, v143
	v_fma_f32 v143, v150, v149, -v130
	v_mul_f32_e32 v130, v153, v160
	v_mul_f32_e32 v146, v156, v144
	v_fma_f32 v144, v152, v158, -v130
	v_mul_f32_e32 v130, v122, v122
	v_fmac_f32_e32 v130, v126, v126
	v_fmac_f32_e32 v130, v110, v110
	v_fmac_f32_e32 v145, v155, v141
	v_mul_f32_e32 v141, v150, v159
	v_fmac_f32_e32 v130, v106, v106
	v_fmac_f32_e32 v141, v151, v149
	v_fmac_f32_e32 v130, v118, v118
	v_mbcnt_lo_u32_b32 v149, s2, 0
	v_fmac_f32_e32 v130, v114, v114
	v_mbcnt_hi_u32_b32 v149, s2, v149
	v_fmac_f32_e32 v130, v102, v102
	v_lshlrev_b32_e32 v149, 2, v149
	v_fmac_f32_e32 v130, v98, v98
	v_xor_b32_e32 v150, 4, v149
	s_nop 1
	v_mov_b32_dpp v150, v130 quad_perm:[1,0,3,2] row_mask:0xf bank_mask:0xf
	v_fmac_f32_e32 v146, v157, v142
	v_mul_f32_e32 v142, v152, v160
	v_fmac_f32_e32 v142, v153, v158
	s_waitcnt lgkmcnt(0)
	v_add_f32_e32 v130, v130, v150
	v_xor_b32_e32 v150, 8, v149
	s_nop 1
	v_mov_b32_dpp v150, v130 quad_perm:[2,3,0,1] row_mask:0xf bank_mask:0xf
	s_waitcnt lgkmcnt(0)
	v_add_f32_e32 v130, v130, v150
	v_xor_b32_e32 v150, 16, v149
	s_nop 1
	v_mov_b32_dpp v150, v130 row_half_mirror row_mask:0xf bank_mask:0xf
	s_nop 1
	v_mov_b32_dpp v150, v150 quad_perm:[3,2,1,0] row_mask:0xf bank_mask:0xf
	v_xor_b32_e32 v149, 32, v149
	s_waitcnt lgkmcnt(0)
	v_add_f32_e32 v130, v130, v150
	s_nop 1
	v_mov_b32_dpp v149, v130 row_ror:8 row_mask:0xf bank_mask:0xf
	s_waitcnt lgkmcnt(0)
	v_add_f32_e32 v130, v130, v149
	v_fmamk_f32 v130, v130, 0x3c000000, v170
	v_cmp_gt_f32_e32 vcc, s30, v130
	v_mul_f32_e32 v149, 0x4f800000, v130
	s_nop 0
	v_cndmask_b32_e32 v130, v130, v149, vcc
	v_sqrt_f32_e32 v149, v130
	s_nop 0
	v_add_u32_e32 v150, -1, v149
	v_fma_f32 v151, -v150, v149, v130
	v_cmp_ge_f32_e64 s[6:7], 0, v151
	v_add_u32_e32 v151, 1, v149
	s_nop 0
	v_cndmask_b32_e64 v150, v149, v150, s[6:7]
	v_fma_f32 v149, -v151, v149, v130
	v_cmp_lt_f32_e64 s[6:7], 0, v149
	s_nop 1
	v_cndmask_b32_e64 v149, v150, v151, s[6:7]
	v_mul_f32_e32 v150, 0x37800000, v149
	v_cndmask_b32_e32 v149, v149, v150, vcc
	v_cmp_class_f32_e32 vcc, v130, v222
	s_nop 1
	v_cndmask_b32_e32 v130, v149, v130, vcc
	s_mov_b32 s2, -1
	v_rcp_f32_e32 v150, v130
	s_nop 0
	v_fma_f32 v149, -v130, v150, 1.0
	v_fma_f32 v149, v149, v150, v150
	v_div_fixup_f32 v130, v149, v130, 1.0
	v_mul_f32_e32 v153, v118, v130
	v_mul_f32_e32 v157, v210, v153
	v_mul_f32_e32 v153, v114, v130
	v_mul_f32_e32 v149, v126, v130
	v_mul_f32_e32 v150, v122, v130
	v_mul_f32_e32 v151, v110, v130
	v_mul_f32_e32 v152, v106, v130
	v_mul_f32_e32 v163, v209, v153
	v_mul_f32_e32 v153, v102, v130
	v_mul_f32_e32 v130, v98, v130
	v_mul_f32_e32 v169, v207, v130
	v_and_b32_e32 v130, s14, v131
	v_lshlrev_b32_e32 v130, 6, v130
	v_mov_b32_e32 v131, v177
	v_lshl_add_u64 v[130:131], v[130:131], 3, s[36:37]
	v_lshl_add_u64 v[130:131], v[130:131], 0, v[128:129]
	global_load_dwordx4 v[158:161], v[130:131], off offset:16
	global_load_dwordx4 v[164:167], v[130:131], off
	v_mul_f32_e32 v151, v212, v151
	v_mul_f32_e32 v149, v224, v149
	v_mul_f32_e32 v152, v211, v152
	v_mul_f32_e32 v150, v223, v150
	v_mul_f32_e32 v168, v208, v153
	v_add_u32_e32 v131, 3, v162
	s_waitcnt vmcnt(0)
	v_mul_f32_e32 v130, v165, v151
	v_fma_f32 v155, v164, v149, -v130
	v_mul_f32_e32 v130, v167, v152
	v_fma_f32 v156, v166, v150, -v130
	v_mul_f32_e32 v130, v159, v168
	v_mul_f32_e32 v153, v164, v151
	v_fma_f32 v151, v158, v157, -v130
	v_mul_f32_e32 v130, v161, v169
	v_mul_f32_e32 v154, v166, v152
	v_fma_f32 v152, v160, v163, -v130
	v_mul_f32_e32 v130, v123, v123
	v_fmac_f32_e32 v130, v127, v127
	v_fmac_f32_e32 v130, v111, v111
	v_fmac_f32_e32 v153, v165, v149
	v_mul_f32_e32 v149, v158, v168
	v_fmac_f32_e32 v130, v107, v107
	v_fmac_f32_e32 v149, v159, v157
	v_fmac_f32_e32 v130, v119, v119
	v_mbcnt_lo_u32_b32 v157, s2, 0
	v_fmac_f32_e32 v130, v115, v115
	v_mbcnt_hi_u32_b32 v157, s2, v157
	v_fmac_f32_e32 v130, v103, v103
	v_lshlrev_b32_e32 v157, 2, v157
	v_fmac_f32_e32 v130, v99, v99
	v_xor_b32_e32 v158, 4, v157
	s_nop 1
	v_mov_b32_dpp v158, v130 quad_perm:[1,0,3,2] row_mask:0xf bank_mask:0xf
	v_fmac_f32_e32 v154, v167, v150
	v_mul_f32_e32 v150, v160, v169
	v_fmac_f32_e32 v150, v161, v163
	s_waitcnt lgkmcnt(0)
; DEVFI float dpp_xor1(float x) { return __int_as_float(__builtin_amdgcn_update_dpp(0, __float_as_int(x), 0xB1, 0xF, 0xF, true)); }
; #define AQ ((bfraw*)(kargs()->ws + O_AQ))
; #define AK ((bfraw*)(kargs()->ws + O_AK))
; DEVFI void store_nat_m(bfraw* base, long ld, f32x4 (&a)[8], int fr) {
;   const bool odd = fr & 1;
;   bfraw* p0 = base + (odd ? 15 + fr : fr);
; #pragma unroll
;   for (int j = 0; j < 4; ++j)
; #pragma unroll
;     for (int n0 = 0; n0 < 8; n0 += 2) { const float own0 = a[n0][j], own1 = a[n0 + 1][j];
;       const float recv = dpp_xor1(odd ? own0 : own1);
;       const unsigned pk = odd ? cvtpk(recv, own1) : cvtpk(own0, recv);
;       *reinterpret_cast<unsigned*>(p0 + (long)j * ld + n0 * 16) = pk; }
; __global__ void __launch_bounds__(512) mega(Params p) {
;     ...
;                     for (int j = 0; j < 4; ++j) { const int pos = (r0 + j) & (seqlen - 1);
;                       float ss = 0;
; #pragma unroll
;                       for (int n = 0; n < 8; ++n) ss += a[n][j] * a[n][j];
;                       ss = red16(ss);
;                       const float rstd = 1.f / sqrtf(ss * (1.f / 128.f) + RMS_EPS);
; #pragma unroll
;                       for (int n = 0; n < 8; ++n) a[n][j] = a[n][j] * rstd * hv[n];
;                       const float4* tb = (const float4*)(attt + pos * 64 + fr * 4);
;                       const float4 t01 = tb[0], t23 = tb[1];
;                       const float2 csv[4] = {make_float2(t01.x, t01.y), make_float2(t01.z, t01.w), make_float2(t23.x, t23.y), make_float2(t23.z, t23.w)};
; #pragma unroll
;                       for (int hh = 0; hh < 2; ++hh)
; #pragma unroll
;                         for (int n = 0; n < 2; ++n) { const float2 cs = csv[hh * 2 + n];
;                           const float x1 = a[hh * 4 + n][j], x2 = a[hh * 4 + n + 2][j];
;                           a[hh * 4 + n][j] = x1 * cs.x - x2 * cs.y; a[hh * 4 + n + 2][j] = x1 * cs.y + x2 * cs.x; } }
;                     if (isk) store_nat_m(AK + (long)r0 * 256 + (c0 - 7168), 256, a, fr);
;                     else store_nat_m(AQ + (long)r0 * 1024 + (c0 - 6144), 1024, a, fr);
	v_add_f32_e32 v130, v130, v158
	v_xor_b32_e32 v158, 8, v157
	s_nop 1
	v_mov_b32_dpp v158, v130 quad_perm:[2,3,0,1] row_mask:0xf bank_mask:0xf
	s_waitcnt lgkmcnt(0)
	v_add_f32_e32 v130, v130, v158
	v_xor_b32_e32 v158, 16, v157
	s_nop 1
	v_mov_b32_dpp v158, v130 row_half_mirror row_mask:0xf bank_mask:0xf
	s_nop 1
	v_mov_b32_dpp v158, v158 quad_perm:[3,2,1,0] row_mask:0xf bank_mask:0xf
	v_xor_b32_e32 v157, 32, v157
	s_waitcnt lgkmcnt(0)
	v_add_f32_e32 v130, v130, v158
	s_nop 1
	v_mov_b32_dpp v157, v130 row_ror:8 row_mask:0xf bank_mask:0xf
	s_waitcnt lgkmcnt(0)
	v_add_f32_e32 v130, v130, v157
	v_fmamk_f32 v130, v130, 0x3c000000, v170
	v_cmp_gt_f32_e32 vcc, s30, v130
	v_mul_f32_e32 v157, 0x4f800000, v130
	s_nop 0
	v_cndmask_b32_e32 v130, v130, v157, vcc
	v_sqrt_f32_e32 v157, v130
	s_nop 0
	v_add_u32_e32 v158, -1, v157
	v_fma_f32 v159, -v158, v157, v130
	v_cmp_ge_f32_e64 s[6:7], 0, v159
	v_add_u32_e32 v159, 1, v157
	s_nop 0
	v_cndmask_b32_e64 v158, v157, v158, s[6:7]
	v_fma_f32 v157, -v159, v157, v130
	v_cmp_lt_f32_e64 s[6:7], 0, v157
	s_nop 1
	v_cndmask_b32_e64 v157, v158, v159, s[6:7]
	v_mul_f32_e32 v158, 0x37800000, v157
	v_cndmask_b32_e32 v157, v157, v158, vcc
	v_cmp_class_f32_e32 vcc, v130, v222
	s_nop 1
	v_cndmask_b32_e32 v130, v157, v130, vcc
	s_mov_b64 s[2:3], -1
	v_rcp_f32_e32 v158, v130
	s_nop 0
	v_fma_f32 v157, -v130, v158, 1.0
	v_fma_f32 v157, v157, v158, v158
	v_div_fixup_f32 v130, v157, v130, 1.0
	v_mul_f32_e32 v158, v123, v130
	v_mul_f32_e32 v163, v223, v158
	v_mul_f32_e32 v158, v111, v130
	v_mul_f32_e32 v160, v212, v158
	v_mul_f32_e32 v158, v107, v130
	v_mul_f32_e32 v161, v211, v158
	v_mul_f32_e32 v158, v119, v130
	v_mul_f32_e32 v170, v210, v158
	v_mul_f32_e32 v158, v115, v130
	v_mul_f32_e32 v157, v127, v130
	v_mul_f32_e32 v171, v209, v158
	v_mul_f32_e32 v158, v103, v130
	v_mul_f32_e32 v130, v99, v130
	v_mul_f32_e32 v173, v207, v130
	v_and_b32_e32 v130, s14, v131
	v_lshlrev_b32_e32 v130, 6, v130
	v_mov_b32_e32 v131, v177
	v_lshl_add_u64 v[130:131], v[130:131], 3, s[36:37]
	v_mul_f32_e32 v172, v208, v158
	v_lshl_add_u64 v[158:159], v[130:131], 0, v[128:129]
	global_load_dwordx4 v[128:131], v[158:159], off offset:16
	global_load_dwordx4 v[166:169], v[158:159], off
	v_mul_f32_e32 v157, v224, v157
	s_waitcnt vmcnt(0)
	v_mul_f32_e32 v158, v167, v160
	v_mul_f32_e32 v160, v166, v160
	v_fma_f32 v164, v166, v157, -v158
	v_fmac_f32_e32 v160, v167, v157
	v_mul_f32_e32 v157, v169, v161
	v_fma_f32 v165, v168, v163, -v157
	v_mul_f32_e32 v157, v129, v172
	v_fma_f32 v158, v128, v170, -v157
	v_mul_f32_e32 v157, v128, v172
	v_mul_f32_e32 v128, v131, v173
	v_fma_f32 v159, v130, v171, -v128
	v_and_b32_e32 v128, 1, v203
	v_mul_f32_e32 v161, v168, v161
	v_mul_f32_e32 v130, v130, v173
	v_cmp_eq_u32_e32 vcc, 0, v128
	v_cmp_eq_u32_e64 s[6:7], 1, v128
	v_add_u32_e32 v128, 15, v202
	v_fmac_f32_e32 v161, v169, v163
	v_fmac_f32_e32 v157, v129, v170
	v_fmac_f32_e32 v130, v131, v171
	v_ashrrev_i32_e32 v163, 31, v162
	v_cndmask_b32_e32 v131, v128, v202, vcc
	v_cndmask_b32_e32 v166, v139, v140, vcc
	s_and_b64 vcc, exec, s[8:9]
	s_cbranch_vccz .LBB0_829
	s_mov_b64 s[2:3], s[0:1]
	s_load_dwordx2 s[2:3], s[2:3], 0xe8
	v_mov_b32_dpp v128, v166 quad_perm:[1,0,3,2] row_mask:0xf bank_mask:0xf bound_ctrl:1
	s_and_saveexec_b64 s[8:9], s[6:7]
	s_xor_b64 s[8:9], exec, s[8:9]
	s_cbranch_execz .LBB0_766
	v_cvt_pk_bf16_f32 v167, v128, v140

; DEVFI float gelu_tanh(float x) {
;   float u = 0.7978845608028654f * (x + 0.044715f * x * x * x);
;   float t = __expf(2.f * u);
;   float th = 1.f - 2.f / (t + 1.f);
;   return 0.5f * x * (1.f + th);
; }
; __global__ void __launch_bounds__(512) mega(Params p) {
;     ...
; #pragma unroll
;                     for (int n = 0; n < 8; ++n)
; #pragma unroll
;                       for (int j = 0; j < 4; ++j) a[n][j] = gelu_tanh(a[n][j]);
.LBB0_896:
	s_andn2_b64 vcc, exec, s[2:3]
	s_cbranch_vccnz .LBB0_974
	v_mul_f32_e32 v129, 0x3d372713, v125
	v_mul_f32_e32 v129, v125, v129
	v_fma_f32 v129, v125, v129, v125
	v_mul_f32_e32 v129, 0x3f4c422a, v129
	v_add_f32_e32 v129, v129, v129
	v_mul_f32_e32 v129, 0x3fb8aa3b, v129
	v_exp_f32_e32 v130, v129
	v_mul_f32_e32 v129, 0x3d372713, v126
	v_mul_f32_e32 v129, v126, v129
	v_fma_f32 v129, v126, v129, v126
	v_mul_f32_e32 v129, 0x3f4c422a, v129
	v_add_f32_e32 v129, v129, v129
	v_mul_f32_e32 v129, 0x3fb8aa3b, v129
	v_mul_f32_e32 v128, 0x3d372713, v124
	v_exp_f32_e32 v134, v129
	v_mul_f32_e32 v129, 0x3d372713, v120
	v_mul_f32_e32 v128, v124, v128
	v_mul_f32_e32 v129, v120, v129
	v_fma_f32 v128, v124, v128, v124
	v_fma_f32 v129, v120, v129, v120
	v_mul_f32_e32 v128, 0x3f4c422a, v128
	v_mul_f32_e32 v129, 0x3f4c422a, v129
	v_add_f32_e32 v128, v128, v128
	v_add_f32_e32 v129, v129, v129
	v_mul_f32_e32 v128, 0x3fb8aa3b, v128
	v_mul_f32_e32 v129, 0x3fb8aa3b, v129
	v_exp_f32_e32 v128, v128
	v_exp_f32_e32 v129, v129
	v_mul_f32_e32 v131, 0x3d372713, v127
	v_mul_f32_e32 v131, v127, v131
	v_fma_f32 v131, v127, v131, v127
	v_pk_add_f32 v[128:129], v[128:129], 1.0 op_sel_hi:[1,0]
	v_mul_f32_e32 v131, 0x3f4c422a, v131
	v_add_f32_e32 v131, v131, v131
	v_mul_f32_e32 v131, 0x3fb8aa3b, v131
	v_exp_f32_e32 v136, v131
	v_rcp_f32_e32 v135, v129
	s_nop 0
	v_fma_f32 v131, -v129, v135, 1.0
	v_fma_f32 v135, v131, v135, v135
	v_add_f32_e32 v131, v135, v135
	v_div_fixup_f32 v129, v131, v129, 2.0
	v_mov_b32_e32 v139, v120
	v_rcp_f32_e32 v138, v128
	s_nop 0
	v_fma_f32 v131, -v128, v138, 1.0
	v_fma_f32 v138, v131, v138, v138
	v_add_f32_e32 v131, v138, v138
	v_div_fixup_f32 v128, v131, v128, 2.0
	v_mul_f32_e32 v131, 0x3d372713, v121
	v_mul_f32_e32 v131, v121, v131
	v_fma_f32 v131, v121, v131, v121
	v_mul_f32_e32 v131, 0x3f4c422a, v131
	v_add_f32_e32 v131, v131, v131
	v_mul_f32_e32 v131, 0x3fb8aa3b, v131
	v_exp_f32_e32 v131, v131
	v_pk_add_f32 v[128:129], v[128:129], 1.0 op_sel_hi:[1,0] neg_lo:[1,0] neg_hi:[1,0]
	v_mov_b32_e32 v138, v124
	v_pk_mul_f32 v[138:139], v[138:139], 0.5 op_sel_hi:[1,0]
	v_pk_add_f32 v[130:131], v[130:131], 1.0 op_sel_hi:[1,0]
	v_pk_add_f32 v[128:129], v[128:129], 1.0 op_sel_hi:[1,0]
	v_pk_mul_f32 v[144:145], v[138:139], v[128:129]
	s_cmpk_lt_u32 s26, 0x1400
	s_mov_b64 s[8:9], -1
	v_rcp_f32_e32 v135, v131
	s_nop 0
	v_fma_f32 v128, -v131, v135, 1.0
	v_fma_f32 v135, v128, v135, v135
	v_add_f32_e32 v128, v135, v135
	v_div_fixup_f32 v129, v128, v131, 2.0
	v_rcp_f32_e32 v137, v130
	s_nop 0
	v_fma_f32 v128, -v130, v137, 1.0
	v_fma_f32 v137, v128, v137, v137
	v_add_f32_e32 v128, v137, v137
	v_div_fixup_f32 v128, v128, v130, 2.0
	v_mul_f32_e32 v130, 0x3d372713, v122
	v_mul_f32_e32 v130, v122, v130
	v_fma_f32 v130, v122, v130, v122
	v_mul_f32_e32 v130, 0x3f4c422a, v130
	v_add_f32_e32 v130, v130, v130
	v_mul_f32_e32 v130, 0x3fb8aa3b, v130
	v_exp_f32_e32 v135, v130
	v_pk_add_f32 v[128:129], v[128:129], 1.0 op_sel_hi:[1,0] neg_lo:[1,0] neg_hi:[1,0]
	v_mov_b32_e32 v130, v125
	v_mov_b32_e32 v131, v121
	v_pk_add_f32 v[134:135], v[134:135], 1.0 op_sel_hi:[1,0]
	v_pk_mul_f32 v[130:131], v[130:131], 0.5 op_sel_hi:[1,0]
	v_pk_add_f32 v[128:129], v[128:129], 1.0 op_sel_hi:[1,0]
	s_nop 0
	v_pk_mul_f32 v[140:141], v[130:131], v[128:129]
	v_rcp_f32_e32 v137, v135
	s_nop 0
	v_fma_f32 v128, -v135, v137, 1.0
	v_fma_f32 v137, v128, v137, v137
	v_add_f32_e32 v128, v137, v137
	v_div_fixup_f32 v129, v128, v135, 2.0
	v_mul_f32_e32 v130, 0x3d372713, v123
	v_mul_f32_e32 v130, v123, v130
	v_fma_f32 v130, v123, v130, v123
	v_mul_f32_e32 v130, 0x3f4c422a, v130
	v_add_f32_e32 v130, v130, v130
	v_mul_f32_e32 v130, 0x3fb8aa3b, v130
	v_exp_f32_e32 v137, v130
	v_rcp_f32_e32 v131, v134
	s_nop 0
	v_fma_f32 v128, -v134, v131, 1.0
	v_fma_f32 v131, v128, v131, v131
	v_add_f32_e32 v128, v131, v131
	v_div_fixup_f32 v128, v128, v134, 2.0
	v_pk_add_f32 v[128:129], v[128:129], 1.0 op_sel_hi:[1,0] neg_lo:[1,0] neg_hi:[1,0]
	v_pk_add_f32 v[136:137], v[136:137], 1.0 op_sel_hi:[1,0]
	v_mov_b32_e32 v130, v126
	v_mov_b32_e32 v131, v122
	v_pk_mul_f32 v[130:131], v[130:131], 0.5 op_sel_hi:[1,0]
	v_pk_add_f32 v[128:129], v[128:129], 1.0 op_sel_hi:[1,0]
	s_nop 0
	v_pk_mul_f32 v[134:135], v[130:131], v[128:129]
	v_rcp_f32_e32 v138, v137
	s_nop 0
	v_fma_f32 v128, -v137, v138, 1.0
	v_fma_f32 v138, v128, v138, v138
	v_add_f32_e32 v128, v138, v138
	v_div_fixup_f32 v129, v128, v137, 2.0
	v_mul_f32_e32 v130, 0x3d372713, v108
	v_mul_f32_e32 v130, v108, v130
	v_fma_f32 v130, v108, v130, v108
	v_mul_f32_e32 v130, 0x3f4c422a, v130
	v_add_f32_e32 v130, v130, v130
	v_mul_f32_e32 v130, 0x3fb8aa3b, v130
	v_rcp_f32_e32 v131, v136
	s_nop 0
	v_fma_f32 v128, -v136, v131, 1.0
	v_fma_f32 v131, v128, v131, v131
	v_add_f32_e32 v128, v131, v131
	v_exp_f32_e32 v133, v130
	v_div_fixup_f32 v128, v128, v136, 2.0
	v_pk_add_f32 v[128:129], v[128:129], 1.0 op_sel_hi:[1,0] neg_lo:[1,0] neg_hi:[1,0]
	v_mov_b32_e32 v130, v127
	v_add_f32_e32 v133, 1.0, v133
	v_mov_b32_e32 v131, v123
	v_pk_mul_f32 v[130:131], v[130:131], 0.5 op_sel_hi:[1,0]
	v_pk_add_f32 v[128:129], v[128:129], 1.0 op_sel_hi:[1,0]
	s_nop 0
	v_pk_mul_f32 v[128:129], v[130:131], v[128:129]
	v_mul_f32_e32 v136, 0x3d372713, v109
	v_mul_f32_e32 v136, v109, v136
	v_fma_f32 v136, v109, v136, v109
	v_mul_f32_e32 v136, 0x3f4c422a, v136
	v_add_f32_e32 v136, v136, v136
	v_mul_f32_e32 v136, 0x3fb8aa3b, v136
	v_exp_f32_e32 v136, v136
	v_rcp_f32_e32 v137, v133
	s_nop 0
	v_fma_f32 v130, -v133, v137, 1.0
	v_fma_f32 v137, v130, v137, v137
	v_add_f32_e32 v130, v137, v137
	v_div_fixup_f32 v130, v130, v133, 2.0
	v_sub_f32_e32 v130, 1.0, v130
	v_add_f32_e32 v131, 1.0, v136
	v_mul_f32_e32 v137, 0.5, v108
; DEVFI float gelu_tanh(float x) {
;   float u = 0.7978845608028654f * (x + 0.044715f * x * x * x);
;   float t = __expf(2.f * u);
;   float th = 1.f - 2.f / (t + 1.f);
;   return 0.5f * x * (1.f + th);
; }
; __global__ void __launch_bounds__(512) mega(Params p) {
;     ...
;                     for (int n = 0; n < 8; ++n)
; #pragma unroll
;                       for (int j = 0; j < 4; ++j) a[n][j] = gelu_tanh(a[n][j]);
	v_add_f32_e32 v130, 1.0, v130
	v_mul_f32_e32 v156, v137, v130
	v_mul_f32_e32 v133, 0x3d372713, v110
	v_mul_f32_e32 v133, v110, v133
	v_fma_f32 v133, v110, v133, v110
	v_mul_f32_e32 v133, 0x3f4c422a, v133
	v_add_f32_e32 v133, v133, v133
	v_mul_f32_e32 v133, 0x3fb8aa3b, v133
	v_exp_f32_e32 v133, v133
	v_rcp_f32_e32 v136, v131
	s_nop 0
	v_fma_f32 v130, -v131, v136, 1.0
	v_fma_f32 v136, v130, v136, v136
	v_add_f32_e32 v130, v136, v136
	v_div_fixup_f32 v130, v130, v131, 2.0
	v_sub_f32_e32 v130, 1.0, v130
	v_add_f32_e32 v131, 1.0, v133
	v_mul_f32_e32 v137, 0.5, v109
	v_add_f32_e32 v130, 1.0, v130
	v_mul_f32_e32 v148, v137, v130
	v_mul_f32_e32 v133, 0x3d372713, v111
	v_mul_f32_e32 v133, v111, v133
	v_fma_f32 v133, v111, v133, v111
	v_mul_f32_e32 v133, 0x3f4c422a, v133
	v_add_f32_e32 v133, v133, v133
	v_mul_f32_e32 v133, 0x3fb8aa3b, v133
	v_exp_f32_e32 v133, v133
	v_rcp_f32_e32 v136, v131
	s_nop 0
	v_fma_f32 v130, -v131, v136, 1.0
	v_fma_f32 v136, v130, v136, v136
	v_add_f32_e32 v130, v136, v136
	v_div_fixup_f32 v130, v130, v131, 2.0
	v_sub_f32_e32 v130, 1.0, v130
	v_add_f32_e32 v131, 1.0, v133
	v_mul_f32_e32 v137, 0.5, v110
	v_add_f32_e32 v130, 1.0, v130
	v_mul_f32_e32 v138, v137, v130
	v_mul_f32_e32 v133, 0x3d372713, v104
	v_mul_f32_e32 v133, v104, v133
	v_fma_f32 v133, v104, v133, v104
	v_mul_f32_e32 v133, 0x3f4c422a, v133
	v_add_f32_e32 v133, v133, v133
	v_mul_f32_e32 v133, 0x3fb8aa3b, v133
	v_exp_f32_e32 v133, v133
	v_rcp_f32_e32 v136, v131
	s_nop 0
	v_fma_f32 v130, -v131, v136, 1.0
	v_fma_f32 v136, v130, v136, v136
	v_add_f32_e32 v130, v136, v136
	v_div_fixup_f32 v130, v130, v131, 2.0
	v_sub_f32_e32 v130, 1.0, v130
	v_add_f32_e32 v131, 1.0, v133
	v_mul_f32_e32 v137, 0.5, v111
	v_add_f32_e32 v130, 1.0, v130
	v_mul_f32_e32 v130, v137, v130
	v_mul_f32_e32 v137, 0x3d372713, v105
	v_mul_f32_e32 v137, v105, v137
	v_fma_f32 v137, v105, v137, v105
	v_mul_f32_e32 v137, 0x3f4c422a, v137
	v_add_f32_e32 v137, v137, v137
	v_mul_f32_e32 v137, 0x3fb8aa3b, v137
	v_exp_f32_e32 v137, v137
	v_rcp_f32_e32 v136, v131
	s_nop 0
	v_fma_f32 v133, -v131, v136, 1.0
	v_fma_f32 v136, v133, v136, v136
	v_add_f32_e32 v133, v136, v136
	v_div_fixup_f32 v131, v133, v131, 2.0
	v_sub_f32_e32 v131, 1.0, v131
	v_add_f32_e32 v133, 1.0, v137
	v_mul_f32_e32 v139, 0.5, v104
	v_add_f32_e32 v131, 1.0, v131
	v_mul_f32_e32 v170, v139, v131
	v_mul_f32_e32 v136, 0x3d372713, v106
	v_mul_f32_e32 v136, v106, v136
	v_fma_f32 v136, v106, v136, v106
	v_mul_f32_e32 v136, 0x3f4c422a, v136
	v_add_f32_e32 v136, v136, v136
	v_mul_f32_e32 v136, 0x3fb8aa3b, v136
	v_exp_f32_e32 v136, v136
	v_rcp_f32_e32 v137, v133
	s_nop 0
	v_fma_f32 v131, -v133, v137, 1.0
	v_fma_f32 v137, v131, v137, v137
	v_add_f32_e32 v131, v137, v137
	v_div_fixup_f32 v131, v131, v133, 2.0
	v_sub_f32_e32 v131, 1.0, v131
	v_add_f32_e32 v133, 1.0, v136
	v_mul_f32_e32 v139, 0.5, v105
	v_add_f32_e32 v131, 1.0, v131
	v_mul_f32_e32 v158, v139, v131
	v_mul_f32_e32 v136, 0x3d372713, v107
	v_mul_f32_e32 v136, v107, v136
	v_fma_f32 v136, v107, v136, v107
	v_mul_f32_e32 v136, 0x3f4c422a, v136
	v_add_f32_e32 v136, v136, v136
	v_mul_f32_e32 v136, 0x3fb8aa3b, v136
	v_exp_f32_e32 v136, v136
	v_rcp_f32_e32 v137, v133
	s_nop 0
	v_fma_f32 v131, -v133, v137, 1.0
	v_fma_f32 v137, v131, v137, v137
	v_add_f32_e32 v131, v137, v137
	v_div_fixup_f32 v131, v131, v133, 2.0
	v_sub_f32_e32 v131, 1.0, v131
	v_add_f32_e32 v133, 1.0, v136
	v_mul_f32_e32 v139, 0.5, v106
	v_add_f32_e32 v131, 1.0, v131
	v_mul_f32_e32 v146, v139, v131
	v_mul_f32_e32 v136, 0x3d372713, v116
	v_mul_f32_e32 v136, v116, v136
	v_fma_f32 v136, v116, v136, v116
	v_mul_f32_e32 v136, 0x3f4c422a, v136
	v_add_f32_e32 v136, v136, v136
	v_mul_f32_e32 v136, 0x3fb8aa3b, v136
	v_exp_f32_e32 v136, v136
	v_rcp_f32_e32 v137, v133
	s_nop 0
	v_fma_f32 v131, -v133, v137, 1.0
	v_fma_f32 v137, v131, v137, v137
	v_add_f32_e32 v131, v137, v137
	v_div_fixup_f32 v131, v131, v133, 2.0
	v_sub_f32_e32 v131, 1.0, v131
	v_add_f32_e32 v133, 1.0, v136
	v_mul_f32_e32 v136, 0.5, v107
	v_add_f32_e32 v131, 1.0, v131
	v_mul_f32_e32 v136, v136, v131
	v_mul_f32_e32 v137, 0x3d372713, v117
	v_mul_f32_e32 v137, v117, v137
	v_fma_f32 v137, v117, v137, v117
	v_mul_f32_e32 v137, 0x3f4c422a, v137
	v_add_f32_e32 v137, v137, v137
	v_mul_f32_e32 v137, 0x3fb8aa3b, v137
	v_exp_f32_e32 v137, v137
	v_rcp_f32_e32 v139, v133
	s_nop 0
	v_fma_f32 v131, -v133, v139, 1.0
	v_fma_f32 v139, v131, v139, v139
	v_add_f32_e32 v131, v139, v139
	v_div_fixup_f32 v131, v131, v133, 2.0
	v_sub_f32_e32 v131, 1.0, v131
	v_add_f32_e32 v133, 1.0, v137
	v_mul_f32_e32 v142, 0.5, v116
	v_add_f32_e32 v131, 1.0, v131
	v_mul_f32_e32 v172, v142, v131
	v_mul_f32_e32 v137, 0x3d372713, v118
	v_mul_f32_e32 v137, v118, v137
	v_fma_f32 v137, v118, v137, v118
	v_mul_f32_e32 v137, 0x3f4c422a, v137
	v_add_f32_e32 v137, v137, v137
	v_mul_f32_e32 v137, 0x3fb8aa3b, v137
	v_exp_f32_e32 v137, v137
	v_rcp_f32_e32 v139, v133
	s_nop 0
	v_fma_f32 v131, -v133, v139, 1.0
	v_fma_f32 v139, v131, v139, v139
	v_add_f32_e32 v131, v139, v139
	v_div_fixup_f32 v131, v131, v133, 2.0
	v_sub_f32_e32 v131, 1.0, v131
	v_add_f32_e32 v133, 1.0, v137
	v_mul_f32_e32 v142, 0.5, v117
	v_add_f32_e32 v131, 1.0, v131
	v_mul_f32_e32 v164, v142, v131
	v_mul_f32_e32 v137, 0x3d372713, v119
	v_mul_f32_e32 v137, v119, v137
	v_fma_f32 v137, v119, v137, v119
	v_mul_f32_e32 v137, 0x3f4c422a, v137
	v_add_f32_e32 v137, v137, v137
	v_mul_f32_e32 v137, 0x3fb8aa3b, v137
	v_exp_f32_e32 v137, v137
	v_rcp_f32_e32 v139, v133
	s_nop 0
	v_fma_f32 v131, -v133, v139, 1.0
	v_fma_f32 v139, v131, v139, v139
	v_add_f32_e32 v131, v139, v139
	v_div_fixup_f32 v131, v131, v133, 2.0
	v_sub_f32_e32 v131, 1.0, v131
	v_add_f32_e32 v133, 1.0, v137
; DEVFI float gelu_tanh(float x) {
;   float u = 0.7978845608028654f * (x + 0.044715f * x * x * x);
;   float t = __expf(2.f * u);
;   float th = 1.f - 2.f / (t + 1.f);
;   return 0.5f * x * (1.f + th);
; }
; __global__ void __launch_bounds__(512) mega(Params p) {
;     ...
;                     for (int n = 0; n < 8; ++n)
; #pragma unroll
;                       for (int j = 0; j < 4; ++j) a[n][j] = gelu_tanh(a[n][j]);
	v_mul_f32_e32 v142, 0.5, v118
	v_add_f32_e32 v131, 1.0, v131
	v_mul_f32_e32 v152, v142, v131
	v_mul_f32_e32 v137, 0x3d372713, v112
	v_mul_f32_e32 v137, v112, v137
	v_fma_f32 v137, v112, v137, v112
	v_mul_f32_e32 v137, 0x3f4c422a, v137
	v_add_f32_e32 v137, v137, v137
	v_mul_f32_e32 v137, 0x3fb8aa3b, v137
	v_exp_f32_e32 v137, v137
	v_rcp_f32_e32 v139, v133
	s_nop 0
	v_fma_f32 v131, -v133, v139, 1.0
	v_fma_f32 v139, v131, v139, v139
	v_add_f32_e32 v131, v139, v139
	v_div_fixup_f32 v131, v131, v133, 2.0
	v_sub_f32_e32 v131, 1.0, v131
	v_add_f32_e32 v133, 1.0, v137
	v_mul_f32_e32 v142, 0.5, v119
	v_add_f32_e32 v131, 1.0, v131
	v_mul_f32_e32 v142, v142, v131
	v_mul_f32_e32 v137, 0x3d372713, v113
	v_mul_f32_e32 v137, v113, v137
	v_fma_f32 v137, v113, v137, v113
	v_mul_f32_e32 v137, 0x3f4c422a, v137
	v_add_f32_e32 v137, v137, v137
	v_mul_f32_e32 v137, 0x3fb8aa3b, v137
	v_exp_f32_e32 v137, v137
	v_rcp_f32_e32 v139, v133
	s_nop 0
	v_fma_f32 v131, -v133, v139, 1.0
	v_fma_f32 v139, v131, v139, v139
	v_add_f32_e32 v131, v139, v139
	v_div_fixup_f32 v131, v131, v133, 2.0
	v_sub_f32_e32 v131, 1.0, v131
	v_add_f32_e32 v133, 1.0, v137
	v_mul_f32_e32 v143, 0.5, v112
	v_add_f32_e32 v131, 1.0, v131
	v_mul_f32_e32 v188, v143, v131
	v_mul_f32_e32 v137, 0x3d372713, v114
	v_mul_f32_e32 v137, v114, v137
	v_fma_f32 v137, v114, v137, v114
	v_mul_f32_e32 v137, 0x3f4c422a, v137
	v_add_f32_e32 v137, v137, v137
	v_mul_f32_e32 v137, 0x3fb8aa3b, v137
	v_exp_f32_e32 v137, v137
	v_rcp_f32_e32 v139, v133
	s_nop 0
	v_fma_f32 v131, -v133, v139, 1.0
	v_fma_f32 v139, v131, v139, v139
	v_add_f32_e32 v131, v139, v139
	v_div_fixup_f32 v131, v131, v133, 2.0
	v_sub_f32_e32 v131, 1.0, v131
	v_add_f32_e32 v133, 1.0, v137
	v_mul_f32_e32 v143, 0.5, v113
	v_add_f32_e32 v131, 1.0, v131
	v_mul_f32_e32 v174, v143, v131
	v_mul_f32_e32 v137, 0x3d372713, v115
	v_mul_f32_e32 v137, v115, v137
	v_fma_f32 v137, v115, v137, v115
	v_mul_f32_e32 v137, 0x3f4c422a, v137
	v_add_f32_e32 v137, v137, v137
	v_mul_f32_e32 v137, 0x3fb8aa3b, v137
	v_exp_f32_e32 v137, v137
	v_rcp_f32_e32 v139, v133
	s_nop 0
	v_fma_f32 v131, -v133, v139, 1.0
	v_fma_f32 v139, v131, v139, v139
	v_add_f32_e32 v131, v139, v139
	v_div_fixup_f32 v131, v131, v133, 2.0
	v_sub_f32_e32 v131, 1.0, v131
	v_add_f32_e32 v133, 1.0, v137
	v_mul_f32_e32 v143, 0.5, v114
	v_add_f32_e32 v131, 1.0, v131
	v_mul_f32_e32 v160, v143, v131
	v_mul_f32_e32 v137, 0x3d372713, v100
	v_mul_f32_e32 v137, v100, v137
	v_fma_f32 v137, v100, v137, v100
	v_mul_f32_e32 v137, 0x3f4c422a, v137
	v_add_f32_e32 v137, v137, v137
	v_mul_f32_e32 v137, 0x3fb8aa3b, v137
	v_exp_f32_e32 v137, v137
	v_rcp_f32_e32 v139, v133
	s_nop 0
	v_fma_f32 v131, -v133, v139, 1.0
	v_fma_f32 v139, v131, v139, v139
	v_add_f32_e32 v131, v139, v139
	v_div_fixup_f32 v131, v131, v133, 2.0
	v_sub_f32_e32 v131, 1.0, v131
	v_add_f32_e32 v133, 1.0, v137
	v_mul_f32_e32 v143, 0.5, v115
	v_add_f32_e32 v131, 1.0, v131
	v_mul_f32_e32 v150, v143, v131
	v_mul_f32_e32 v137, 0x3d372713, v101
	v_mul_f32_e32 v137, v101, v137
	v_fma_f32 v137, v101, v137, v101
	v_mul_f32_e32 v137, 0x3f4c422a, v137
	v_add_f32_e32 v137, v137, v137
	v_mul_f32_e32 v137, 0x3fb8aa3b, v137
	v_exp_f32_e32 v137, v137
	v_rcp_f32_e32 v139, v133
	s_nop 0
	v_fma_f32 v131, -v133, v139, 1.0
	v_fma_f32 v139, v131, v139, v139
	v_add_f32_e32 v131, v139, v139
	v_div_fixup_f32 v131, v131, v133, 2.0
	v_sub_f32_e32 v131, 1.0, v131
	v_add_f32_e32 v133, 1.0, v137
	v_mul_f32_e32 v143, 0.5, v100
	v_add_f32_e32 v131, 1.0, v131
	v_mul_f32_e32 v190, v143, v131
	v_mul_f32_e32 v137, 0x3d372713, v102
	v_mul_f32_e32 v137, v102, v137
	v_fma_f32 v137, v102, v137, v102
	v_mul_f32_e32 v137, 0x3f4c422a, v137
	v_add_f32_e32 v137, v137, v137
	v_mul_f32_e32 v137, 0x3fb8aa3b, v137
	v_exp_f32_e32 v137, v137
	v_rcp_f32_e32 v139, v133
	s_nop 0
	v_fma_f32 v131, -v133, v139, 1.0
	v_fma_f32 v139, v131, v139, v139
	v_add_f32_e32 v131, v139, v139
	v_div_fixup_f32 v131, v131, v133, 2.0
	v_sub_f32_e32 v131, 1.0, v131
	v_add_f32_e32 v133, 1.0, v137
	v_mul_f32_e32 v143, 0.5, v101
	v_add_f32_e32 v131, 1.0, v131
	v_mul_f32_e32 v186, v143, v131
	v_mul_f32_e32 v137, 0x3d372713, v103
	v_mul_f32_e32 v137, v103, v137
	v_fma_f32 v137, v103, v137, v103
	v_mul_f32_e32 v137, 0x3f4c422a, v137
	v_add_f32_e32 v137, v137, v137
	v_mul_f32_e32 v137, 0x3fb8aa3b, v137
	v_exp_f32_e32 v137, v137
	v_rcp_f32_e32 v139, v133
	s_nop 0
	v_fma_f32 v131, -v133, v139, 1.0
	v_fma_f32 v139, v131, v139, v139
	v_add_f32_e32 v131, v139, v139
	v_div_fixup_f32 v131, v131, v133, 2.0
	v_sub_f32_e32 v131, 1.0, v131
	v_add_f32_e32 v133, 1.0, v137
	v_mul_f32_e32 v143, 0.5, v102
	v_add_f32_e32 v131, 1.0, v131
	v_mul_f32_e32 v168, v143, v131
	v_mul_f32_e32 v137, 0x3d372713, v96
	v_mul_f32_e32 v137, v96, v137
	v_fma_f32 v137, v96, v137, v96
	v_mul_f32_e32 v137, 0x3f4c422a, v137
	v_add_f32_e32 v137, v137, v137
	v_mul_f32_e32 v137, 0x3fb8aa3b, v137
	v_exp_f32_e32 v137, v137
	v_rcp_f32_e32 v139, v133
	s_nop 0
	v_fma_f32 v131, -v133, v139, 1.0
	v_fma_f32 v139, v131, v139, v139
	v_add_f32_e32 v131, v139, v139
	v_div_fixup_f32 v131, v131, v133, 2.0
	v_sub_f32_e32 v131, 1.0, v131
	v_add_f32_e32 v133, 1.0, v137
	v_mul_f32_e32 v143, 0.5, v103
	v_add_f32_e32 v131, 1.0, v131
	v_mul_f32_e32 v154, v143, v131
	v_mul_f32_e32 v137, 0x3d372713, v97
	v_mul_f32_e32 v137, v97, v137
	v_fma_f32 v137, v97, v137, v97
	v_mul_f32_e32 v137, 0x3f4c422a, v137
	v_add_f32_e32 v137, v137, v137
	v_mul_f32_e32 v137, 0x3fb8aa3b, v137
	v_exp_f32_e32 v137, v137
	v_rcp_f32_e32 v139, v133
	s_nop 0
	v_fma_f32 v131, -v133, v139, 1.0
	v_fma_f32 v139, v131, v139, v139
	v_add_f32_e32 v131, v139, v139
	v_div_fixup_f32 v131, v131, v133, 2.0
	v_sub_f32_e32 v131, 1.0, v131
; DEVFI int lane_opaque() { unsigned m = ~0u; asm volatile("" : "+s"(m)); return (int)__builtin_amdgcn_mbcnt_hi(m, __builtin_amdgcn_mbcnt_lo(m, 0u)); }
; DEVFI float shx(float v, int mask, int lane) { return __int_as_float(__builtin_amdgcn_ds_bpermute((lane ^ mask) << 2, __float_as_int(v))); }
; #define SVSTAT ((float*)(kargs()->ws + O_SVSTAT))
; DEVFI float red16(float v) {
;   const int ln = lane_opaque();
;   v += shx(v, 1, ln); v += shx(v, 2, ln); v += shx(v, 4, ln); v += shx(v, 8, ln); return v;
; }
; __global__ void __launch_bounds__(512) mega(Params p) {
;     ...
;                     for (int n = 0; n < 8; ++n)
; #pragma unroll
;                       for (int j = 0; j < 4; ++j) a[n][j] = gelu_tanh(a[n][j]);
;                     if (c0 >= 5120) { float* stp = SVSTAT + (long)r0 * 16 + ((c0 - 5120) >> 7) * 2;
; #pragma unroll
;                       for (int j = 0; j < 4; ++j) { float s1 = 0, s2 = 0;
; #pragma unroll
;                         for (int n = 0; n < 8; ++n) { s1 += a[n][j]; s2 += a[n][j] * a[n][j]; }
;                         s1 = red16(s1); s2 = red16(s2);
;                         if (fr == 0) { stp[j * 16] = s1; stp[j * 16 + 1] = s2; } } }
	v_add_f32_e32 v133, 1.0, v137
	v_mul_f32_e32 v143, 0.5, v96
	v_add_f32_e32 v131, 1.0, v131
	v_mul_f32_e32 v194, v143, v131
	v_mul_f32_e32 v137, 0x3d372713, v98
	v_mul_f32_e32 v137, v98, v137
	v_fma_f32 v137, v98, v137, v98
	v_mul_f32_e32 v137, 0x3f4c422a, v137
	v_add_f32_e32 v137, v137, v137
	v_mul_f32_e32 v137, 0x3fb8aa3b, v137
	v_exp_f32_e32 v137, v137
	v_rcp_f32_e32 v139, v133
	s_nop 0
	v_fma_f32 v131, -v133, v139, 1.0
	v_fma_f32 v139, v131, v139, v139
	v_add_f32_e32 v131, v139, v139
	v_div_fixup_f32 v131, v131, v133, 2.0
	v_sub_f32_e32 v131, 1.0, v131
	v_add_f32_e32 v133, 1.0, v137
	v_mul_f32_e32 v143, 0.5, v97
	v_add_f32_e32 v131, 1.0, v131
	v_mul_f32_e32 v192, v143, v131
	v_mul_f32_e32 v137, 0x3d372713, v99
	v_mul_f32_e32 v137, v99, v137
	v_fma_f32 v137, v99, v137, v99
	v_mul_f32_e32 v137, 0x3f4c422a, v137
	v_add_f32_e32 v137, v137, v137
	v_mul_f32_e32 v137, 0x3fb8aa3b, v137
	v_exp_f32_e32 v137, v137
	v_rcp_f32_e32 v139, v133
	s_nop 0
	v_fma_f32 v131, -v133, v139, 1.0
	v_fma_f32 v139, v131, v139, v139
	v_add_f32_e32 v131, v139, v139
	v_div_fixup_f32 v131, v131, v133, 2.0
	v_sub_f32_e32 v131, 1.0, v131
	v_add_f32_e32 v133, 1.0, v137
	v_mul_f32_e32 v143, 0.5, v98
	v_add_f32_e32 v131, 1.0, v131
	v_mul_f32_e32 v184, v143, v131
	v_rcp_f32_e32 v139, v133
	s_nop 0
	v_fma_f32 v131, -v133, v139, 1.0
	v_fma_f32 v139, v131, v139, v139
	v_add_f32_e32 v131, v139, v139
	v_div_fixup_f32 v131, v131, v133, 2.0
	v_sub_f32_e32 v131, 1.0, v131
	v_mul_f32_e32 v133, 0.5, v99
	v_add_f32_e32 v131, 1.0, v131
	v_mul_f32_e32 v166, v133, v131
	s_cbranch_scc1 .LBB0_907
	s_mov_b64 s[2:3], s[0:1]
	s_load_dwordx2 s[2:3], s[2:3], 0xe8
	v_ashrrev_i32_e32 v163, 31, v162
	v_lshlrev_b64 v[178:179], 6, v[162:163]
	v_add_u32_e32 v131, 0xffffec00, v176
	v_lshrrev_b32_e32 v180, 4, v131
	s_waitcnt lgkmcnt(0)
	v_lshl_add_u64 v[178:179], s[2:3], 0, v[178:179]
	v_mov_b32_e32 v181, v177
	v_lshl_add_u64 v[178:179], v[178:179], 0, v[180:181]
	s_mov_b64 s[2:3], 0x3a720400
	v_lshl_add_u64 v[196:197], v[178:179], 0, s[2:3]
	v_mov_b32_e32 v178, v177
	v_mov_b32_e32 v179, v145
	v_pk_add_f32 v[178:179], v[144:145], v[178:179]
	v_pk_mul_f32 v[180:181], v[144:145], v[144:145]
	v_mul_f32_e32 v157, v156, v156
	v_mov_b32_e32 v179, v181
	v_pk_mov_b32 v[180:181], v[144:145], v[180:181] op_sel:[1,0]
	s_mov_b32 s2, -1
	v_pk_add_f32 v[178:179], v[178:179], v[180:181]
	v_mul_f32_e32 v171, v170, v170
	v_pk_add_f32 v[178:179], v[178:179], v[156:157]
	v_mbcnt_lo_u32_b32 v131, s2, 0
	v_mul_f32_e32 v173, v172, v172
	v_mbcnt_hi_u32_b32 v131, s2, v131
	s_mov_b32 s2, -1
	v_pk_add_f32 v[178:179], v[178:179], v[170:171]
	v_mul_f32_e32 v189, v188, v188
	v_pk_add_f32 v[178:179], v[178:179], v[172:173]
	v_mbcnt_lo_u32_b32 v143, s2, 0
	v_mul_f32_e32 v191, v190, v190
	v_mbcnt_hi_u32_b32 v143, s2, v143
	v_pk_add_f32 v[178:179], v[178:179], v[188:189]
	v_mul_f32_e32 v195, v194, v194
	v_lshlrev_b32_e32 v131, 2, v131
	v_lshlrev_b32_e32 v143, 2, v143
	v_pk_add_f32 v[178:179], v[178:179], v[190:191]
	v_xor_b32_e32 v133, 4, v131
	v_xor_b32_e32 v147, 4, v143
	v_pk_add_f32 v[178:179], v[178:179], v[194:195]
	s_nop 1
	v_mov_b32_dpp v180, v178 quad_perm:[1,0,3,2] row_mask:0xf bank_mask:0xf
	s_nop 0
	v_mov_b32_dpp v181, v179 quad_perm:[1,0,3,2] row_mask:0xf bank_mask:0xf
	v_xor_b32_e32 v137, 8, v131
	v_xor_b32_e32 v149, 8, v143
	v_xor_b32_e32 v139, 16, v131
	v_xor_b32_e32 v151, 16, v143
	s_waitcnt lgkmcnt(0)
	v_pk_add_f32 v[178:179], v[178:179], v[180:181]
	s_nop 1
	v_mov_b32_dpp v180, v178 quad_perm:[2,3,0,1] row_mask:0xf bank_mask:0xf
	s_nop 0
	v_mov_b32_dpp v181, v179 quad_perm:[2,3,0,1] row_mask:0xf bank_mask:0xf
	v_xor_b32_e32 v131, 32, v131
	v_cmp_eq_u32_e32 vcc, 0, v202
	s_waitcnt lgkmcnt(0)
	v_pk_add_f32 v[178:179], v[178:179], v[180:181]
	s_nop 1
	v_mov_b32_dpp v180, v178 row_half_mirror row_mask:0xf bank_mask:0xf
	s_nop 1
	v_mov_b32_dpp v180, v180 quad_perm:[3,2,1,0] row_mask:0xf bank_mask:0xf
	v_mov_b32_dpp v181, v179 row_half_mirror row_mask:0xf bank_mask:0xf
	s_nop 1
	v_mov_b32_dpp v181, v181 quad_perm:[3,2,1,0] row_mask:0xf bank_mask:0xf
	s_waitcnt lgkmcnt(0)
	v_pk_add_f32 v[198:199], v[178:179], v[180:181]
	s_nop 1
	v_mov_b32_dpp v200, v198 row_ror:8 row_mask:0xf bank_mask:0xf
	v_xor_b32_e32 v131, 32, v143
	v_mov_b32_dpp v201, v199 row_ror:8 row_mask:0xf bank_mask:0xf
	s_and_saveexec_b64 s[2:3], vcc
	s_cbranch_execz .LBB0_900
	s_waitcnt lgkmcnt(0)
	v_pk_add_f32 v[178:179], v[198:199], v[200:201]
	global_store_dwordx2 v[196:197], v[178:179], off
; DEVFI int lane_opaque() { unsigned m = ~0u; asm volatile("" : "+s"(m)); return (int)__builtin_amdgcn_mbcnt_hi(m, __builtin_amdgcn_mbcnt_lo(m, 0u)); }
; DEVFI float shx(float v, int mask, int lane) { return __int_as_float(__builtin_amdgcn_ds_bpermute((lane ^ mask) << 2, __float_as_int(v))); }
; #define SVSTAT ((float*)(kargs()->ws + O_SVSTAT))
; DEVFI float red16(float v) {
;   const int ln = lane_opaque();
;   v += shx(v, 1, ln); v += shx(v, 2, ln); v += shx(v, 4, ln); v += shx(v, 8, ln); return v;
; }
; __global__ void __launch_bounds__(512) mega(Params p) {
;     ...
;                     if (c0 >= 5120) { float* stp = SVSTAT + (long)r0 * 16 + ((c0 - 5120) >> 7) * 2;
; #pragma unroll
;                       for (int j = 0; j < 4; ++j) { float s1 = 0, s2 = 0;
; #pragma unroll
;                         for (int n = 0; n < 8; ++n) { s1 += a[n][j]; s2 += a[n][j] * a[n][j]; }
;                         s1 = red16(s1); s2 = red16(s2);
;                         if (fr == 0) { stp[j * 16] = s1; stp[j * 16 + 1] = s2; } } }
.LBB0_900:
	s_or_b64 exec, exec, s[2:3]
	v_mov_b32_e32 v178, v177
	v_mov_b32_e32 v179, v141
	v_pk_add_f32 v[178:179], v[140:141], v[178:179]
	v_pk_mul_f32 v[180:181], v[140:141], v[140:141]
	v_mul_f32_e32 v149, v148, v148
	v_mov_b32_e32 v179, v181
	v_pk_mov_b32 v[180:181], v[140:141], v[180:181] op_sel:[1,0]
	s_mov_b32 s2, -1
	v_pk_add_f32 v[178:179], v[178:179], v[180:181]
	v_mul_f32_e32 v159, v158, v158
	v_pk_add_f32 v[178:179], v[178:179], v[148:149]
	v_mbcnt_lo_u32_b32 v131, s2, 0
	v_mul_f32_e32 v165, v164, v164
	v_mbcnt_hi_u32_b32 v131, s2, v131
	s_mov_b32 s2, -1
	v_pk_add_f32 v[178:179], v[178:179], v[158:159]
	v_mul_f32_e32 v175, v174, v174
	v_pk_add_f32 v[178:179], v[178:179], v[164:165]
	v_mbcnt_lo_u32_b32 v137, s2, 0
	v_mul_f32_e32 v187, v186, v186
	v_mbcnt_hi_u32_b32 v137, s2, v137
	v_pk_add_f32 v[178:179], v[178:179], v[174:175]
	v_mul_f32_e32 v193, v192, v192
	v_lshlrev_b32_e32 v131, 2, v131
	v_lshlrev_b32_e32 v137, 2, v137
	v_pk_add_f32 v[178:179], v[178:179], v[186:187]
	v_xor_b32_e32 v133, 4, v131
	v_xor_b32_e32 v139, 4, v137
	v_pk_add_f32 v[178:179], v[178:179], v[192:193]
	s_nop 1
	v_mov_b32_dpp v180, v178 quad_perm:[1,0,3,2] row_mask:0xf bank_mask:0xf
	s_nop 0
	v_mov_b32_dpp v181, v179 quad_perm:[1,0,3,2] row_mask:0xf bank_mask:0xf
	v_xor_b32_e32 v133, 8, v131
	v_xor_b32_e32 v139, 8, v137
	s_waitcnt lgkmcnt(0)
	v_pk_add_f32 v[178:179], v[178:179], v[180:181]
	s_nop 1
	v_mov_b32_dpp v180, v178 quad_perm:[2,3,0,1] row_mask:0xf bank_mask:0xf
	s_nop 0
	v_mov_b32_dpp v181, v179 quad_perm:[2,3,0,1] row_mask:0xf bank_mask:0xf
	v_xor_b32_e32 v133, 16, v131
	v_xor_b32_e32 v139, 16, v137
	v_xor_b32_e32 v131, 32, v131
	s_waitcnt lgkmcnt(0)
	v_pk_add_f32 v[178:179], v[178:179], v[180:181]
	s_nop 1
	v_mov_b32_dpp v180, v178 row_half_mirror row_mask:0xf bank_mask:0xf
	s_nop 1
	v_mov_b32_dpp v180, v180 quad_perm:[3,2,1,0] row_mask:0xf bank_mask:0xf
	v_mov_b32_dpp v181, v179 row_half_mirror row_mask:0xf bank_mask:0xf
	s_nop 1
	v_mov_b32_dpp v181, v181 quad_perm:[3,2,1,0] row_mask:0xf bank_mask:0xf
	s_waitcnt lgkmcnt(0)
	v_pk_add_f32 v[198:199], v[178:179], v[180:181]
	s_nop 1
	v_mov_b32_dpp v200, v198 row_ror:8 row_mask:0xf bank_mask:0xf
	v_xor_b32_e32 v131, 32, v137
	v_mov_b32_dpp v201, v199 row_ror:8 row_mask:0xf bank_mask:0xf
	s_and_saveexec_b64 s[2:3], vcc
	s_cbranch_execz .LBB0_902
	s_waitcnt lgkmcnt(0)
	v_pk_add_f32 v[178:179], v[198:199], v[200:201]
	global_store_dwordx2 v[196:197], v[178:179], off offset:64
.LBB0_902:
	s_or_b64 exec, exec, s[2:3]
	v_mov_b32_e32 v178, v177
	v_mov_b32_e32 v179, v135
	v_pk_add_f32 v[178:179], v[134:135], v[178:179]
	v_pk_mul_f32 v[180:181], v[134:135], v[134:135]
	v_mul_f32_e32 v139, v138, v138
	v_mov_b32_e32 v179, v181
	v_pk_mov_b32 v[180:181], v[134:135], v[180:181] op_sel:[1,0]
	s_mov_b32 s2, -1
	v_pk_add_f32 v[178:179], v[178:179], v[180:181]
	v_mul_f32_e32 v147, v146, v146
	v_pk_add_f32 v[178:179], v[178:179], v[138:139]
	v_mbcnt_lo_u32_b32 v131, s2, 0
	v_mul_f32_e32 v153, v152, v152
	v_mbcnt_hi_u32_b32 v131, s2, v131
	s_mov_b32 s2, -1
	v_pk_add_f32 v[178:179], v[178:179], v[146:147]
	v_mul_f32_e32 v161, v160, v160
	v_pk_add_f32 v[178:179], v[178:179], v[152:153]
	v_mbcnt_lo_u32_b32 v137, s2, 0
	v_mul_f32_e32 v169, v168, v168
	v_mbcnt_hi_u32_b32 v137, s2, v137
	v_pk_add_f32 v[178:179], v[178:179], v[160:161]
	v_mul_f32_e32 v185, v184, v184
	v_lshlrev_b32_e32 v131, 2, v131
	v_lshlrev_b32_e32 v137, 2, v137
	v_pk_add_f32 v[178:179], v[178:179], v[168:169]
	v_xor_b32_e32 v133, 4, v131
	v_xor_b32_e32 v143, 4, v137
	v_pk_add_f32 v[178:179], v[178:179], v[184:185]
	s_nop 1
	v_mov_b32_dpp v180, v178 quad_perm:[1,0,3,2] row_mask:0xf bank_mask:0xf
	s_nop 0
	v_mov_b32_dpp v181, v179 quad_perm:[1,0,3,2] row_mask:0xf bank_mask:0xf
	v_xor_b32_e32 v133, 8, v131
	v_xor_b32_e32 v139, 8, v137
	s_waitcnt lgkmcnt(0)
	v_pk_add_f32 v[178:179], v[178:179], v[180:181]
	s_nop 1
	v_mov_b32_dpp v180, v178 quad_perm:[2,3,0,1] row_mask:0xf bank_mask:0xf
	s_nop 0
	v_mov_b32_dpp v181, v179 quad_perm:[2,3,0,1] row_mask:0xf bank_mask:0xf
	v_xor_b32_e32 v133, 16, v131
	v_xor_b32_e32 v139, 16, v137
	v_xor_b32_e32 v131, 32, v131
	s_waitcnt lgkmcnt(0)
	v_pk_add_f32 v[178:179], v[178:179], v[180:181]
	s_nop 1
	v_mov_b32_dpp v180, v178 row_half_mirror row_mask:0xf bank_mask:0xf
	s_nop 1
	v_mov_b32_dpp v180, v180 quad_perm:[3,2,1,0] row_mask:0xf bank_mask:0xf
	v_mov_b32_dpp v181, v179 row_half_mirror row_mask:0xf bank_mask:0xf
	s_nop 1
	v_mov_b32_dpp v181, v181 quad_perm:[3,2,1,0] row_mask:0xf bank_mask:0xf
	s_waitcnt lgkmcnt(0)
	v_pk_add_f32 v[198:199], v[178:179], v[180:181]
	s_nop 1
	v_mov_b32_dpp v200, v198 row_ror:8 row_mask:0xf bank_mask:0xf
	v_xor_b32_e32 v131, 32, v137
	v_mov_b32_dpp v201, v199 row_ror:8 row_mask:0xf bank_mask:0xf
	s_and_saveexec_b64 s[2:3], vcc
	s_cbranch_execz .LBB0_904
	s_waitcnt lgkmcnt(0)
	v_pk_add_f32 v[178:179], v[198:199], v[200:201]
	global_store_dwordx2 v[196:197], v[178:179], off offset:128
; DEVFI int lane_opaque() { unsigned m = ~0u; asm volatile("" : "+s"(m)); return (int)__builtin_amdgcn_mbcnt_hi(m, __builtin_amdgcn_mbcnt_lo(m, 0u)); }
; DEVFI float shx(float v, int mask, int lane) { return __int_as_float(__builtin_amdgcn_ds_bpermute((lane ^ mask) << 2, __float_as_int(v))); }
; #define SVSTAT ((float*)(kargs()->ws + O_SVSTAT))
; DEVFI float red16(float v) {
;   const int ln = lane_opaque();
;   v += shx(v, 1, ln); v += shx(v, 2, ln); v += shx(v, 4, ln); v += shx(v, 8, ln); return v;
; }
; __global__ void __launch_bounds__(512) mega(Params p) {
;     ...
;                     if (c0 >= 5120) { float* stp = SVSTAT + (long)r0 * 16 + ((c0 - 5120) >> 7) * 2;
; #pragma unroll
;                       for (int j = 0; j < 4; ++j) { float s1 = 0, s2 = 0;
; #pragma unroll
;                         for (int n = 0; n < 8; ++n) { s1 += a[n][j]; s2 += a[n][j] * a[n][j]; }
;                         s1 = red16(s1); s2 = red16(s2);
;                         if (fr == 0) { stp[j * 16] = s1; stp[j * 16 + 1] = s2; } } }
.LBB0_904:
	s_or_b64 exec, exec, s[2:3]
	v_mov_b32_e32 v178, v177
	v_mov_b32_e32 v179, v129
	v_pk_add_f32 v[178:179], v[128:129], v[178:179]
	v_pk_mul_f32 v[180:181], v[128:129], v[128:129]
	v_mul_f32_e32 v131, v130, v130
	v_mov_b32_e32 v179, v181
	v_pk_mov_b32 v[180:181], v[128:129], v[180:181] op_sel:[1,0]
	s_mov_b32 s2, -1
	v_pk_add_f32 v[178:179], v[178:179], v[180:181]
	v_mul_f32_e32 v137, v136, v136
	v_pk_add_f32 v[178:179], v[178:179], v[130:131]
	v_mbcnt_lo_u32_b32 v133, s2, 0
	v_mul_f32_e32 v143, v142, v142
	v_mbcnt_hi_u32_b32 v133, s2, v133
	s_mov_b32 s2, -1
	v_pk_add_f32 v[178:179], v[178:179], v[136:137]
	v_mul_f32_e32 v151, v150, v150
	v_pk_add_f32 v[178:179], v[178:179], v[142:143]
	v_mbcnt_lo_u32_b32 v147, s2, 0
	v_mul_f32_e32 v155, v154, v154
	v_mbcnt_hi_u32_b32 v147, s2, v147
	v_pk_add_f32 v[178:179], v[178:179], v[150:151]
	v_mul_f32_e32 v167, v166, v166
	v_lshlrev_b32_e32 v133, 2, v133
	v_lshlrev_b32_e32 v147, 2, v147
	v_pk_add_f32 v[178:179], v[178:179], v[154:155]
	v_xor_b32_e32 v139, 4, v133
	v_xor_b32_e32 v149, 4, v147
	v_pk_add_f32 v[178:179], v[178:179], v[166:167]
	s_nop 1
	v_mov_b32_dpp v180, v178 quad_perm:[1,0,3,2] row_mask:0xf bank_mask:0xf
	s_nop 0
	v_mov_b32_dpp v181, v179 quad_perm:[1,0,3,2] row_mask:0xf bank_mask:0xf
	v_xor_b32_e32 v131, 8, v133
	v_xor_b32_e32 v137, 8, v147
	s_waitcnt lgkmcnt(0)
	v_pk_add_f32 v[178:179], v[178:179], v[180:181]
	s_nop 1
	v_mov_b32_dpp v180, v178 quad_perm:[2,3,0,1] row_mask:0xf bank_mask:0xf
	s_nop 0
	v_mov_b32_dpp v181, v179 quad_perm:[2,3,0,1] row_mask:0xf bank_mask:0xf
	v_xor_b32_e32 v131, 16, v133
	v_xor_b32_e32 v137, 16, v147
	s_waitcnt lgkmcnt(0)
	v_pk_add_f32 v[178:179], v[178:179], v[180:181]
	s_nop 1
	v_mov_b32_dpp v180, v178 row_half_mirror row_mask:0xf bank_mask:0xf
	s_nop 1
	v_mov_b32_dpp v180, v180 quad_perm:[3,2,1,0] row_mask:0xf bank_mask:0xf
	v_mov_b32_dpp v181, v179 row_half_mirror row_mask:0xf bank_mask:0xf
	s_nop 1
	v_mov_b32_dpp v181, v181 quad_perm:[3,2,1,0] row_mask:0xf bank_mask:0xf
	v_xor_b32_e32 v131, 32, v133
	s_waitcnt lgkmcnt(0)
	v_pk_add_f32 v[198:199], v[178:179], v[180:181]
	s_nop 1
	v_mov_b32_dpp v200, v198 row_ror:8 row_mask:0xf bank_mask:0xf
	v_xor_b32_e32 v131, 32, v147
	v_mov_b32_dpp v201, v199 row_ror:8 row_mask:0xf bank_mask:0xf
	s_and_saveexec_b64 s[2:3], vcc
	s_cbranch_execz .LBB0_906
	s_waitcnt lgkmcnt(0)
	v_pk_add_f32 v[178:179], v[198:199], v[200:201]
	global_store_dwordx2 v[196:197], v[178:179], off offset:192

; DEVFI int lane_opaque() { unsigned m = ~0u; asm volatile("" : "+s"(m)); return (int)__builtin_amdgcn_mbcnt_hi(m, __builtin_amdgcn_mbcnt_lo(m, 0u)); }
; DEVFI float shx(float v, int mask, int lane) { return __int_as_float(__builtin_amdgcn_ds_bpermute((lane ^ mask) << 2, __float_as_int(v))); }
; #define ATTT ((float2*)(kargs()->ws + O_ATTT))
; DEVFI float red16(float v) {
;   const int ln = lane_opaque();
;   v += shx(v, 1, ln); v += shx(v, 2, ln); v += shx(v, 4, ln); v += shx(v, 8, ln); return v;
; }
; __global__ void __launch_bounds__(512) mega(Params p) {
;     ...
;                     const bool isk = c0 >= 7168; const float* nw = isk ? kn_w : qn_w; const float2* attt = ATTT;
; #pragma unroll
;                     for (int j = 0; j < 4; ++j) { const int pos = (r0 + j) & (seqlen - 1);
;                       float ss = 0;
; #pragma unroll
;                       for (int n = 0; n < 8; ++n) ss += a[n][j] * a[n][j];
;                       ss = red16(ss);
;                       const float rstd = 1.f / sqrtf(ss * (1.f / 128.f) + RMS_EPS);
; #pragma unroll
;                       for (int n = 0; n < 8; ++n) a[n][j] = a[n][j] * rstd * hv[n];
;                       const float4* tb = (const float4*)(attt + pos * 64 + fr * 4);
;                       const float4 t01 = tb[0], t23 = tb[1];
;                       const float2 csv[4] = {make_float2(t01.x, t01.y), make_float2(t01.z, t01.w), make_float2(t23.x, t23.y), make_float2(t23.z, t23.w)};
; #pragma unroll
;                       for (int hh = 0; hh < 2; ++hh)
; #pragma unroll
;                         for (int n = 0; n < 2; ++n) { const float2 cs = csv[hh * 2 + n];
;                           const float x1 = a[hh * 4 + n][j], x2 = a[hh * 4 + n + 2][j];
;                           a[hh * 4 + n][j] = x1 * cs.x - x2 * cs.y; a[hh * 4 + n + 2][j] = x1 * cs.y + x2 * cs.x; } }
.LBB0_1195:
	s_mov_b64 s[2:3], s[0:1]
	s_load_dwordx2 s[2:3], s[2:3], 0xe8
	v_mul_f32_e32 v96, v88, v88
	v_fmac_f32_e32 v96, v92, v92
	v_fmac_f32_e32 v96, v76, v76
	v_fmac_f32_e32 v96, v72, v72
	s_waitcnt lgkmcnt(0)
	s_add_u32 s36, s2, 0x3da0000
	s_mov_b32 s2, -1
	v_fmac_f32_e32 v96, v84, v84
	v_fmac_f32_e32 v96, v80, v80
	v_mbcnt_lo_u32_b32 v97, s2, 0
	v_mbcnt_hi_u32_b32 v97, s2, v97
	v_fmac_f32_e32 v96, v68, v68
	v_lshlrev_b32_e32 v97, 2, v97
	v_fmac_f32_e32 v96, v64, v64
	v_xor_b32_e32 v98, 4, v97
	s_nop 1
	v_mov_b32_dpp v98, v96 quad_perm:[1,0,3,2] row_mask:0xf bank_mask:0xf
	v_mov_b32_e32 v131, 0x358637bd
	s_addc_u32 s37, s3, 0
	v_mov_b32_e32 v161, v177
	s_waitcnt lgkmcnt(0)
	v_add_f32_e32 v96, v96, v98
	v_xor_b32_e32 v98, 8, v97
	s_nop 1
	v_mov_b32_dpp v98, v96 quad_perm:[2,3,0,1] row_mask:0xf bank_mask:0xf
	s_waitcnt lgkmcnt(0)
	v_add_f32_e32 v96, v96, v98
	v_xor_b32_e32 v98, 16, v97
	s_nop 1
	v_mov_b32_dpp v98, v96 row_half_mirror row_mask:0xf bank_mask:0xf
	s_nop 1
	v_mov_b32_dpp v98, v98 quad_perm:[3,2,1,0] row_mask:0xf bank_mask:0xf
	v_xor_b32_e32 v97, 32, v97
	s_waitcnt lgkmcnt(0)
	v_add_f32_e32 v96, v96, v98
	s_nop 1
	v_mov_b32_dpp v97, v96 row_ror:8 row_mask:0xf bank_mask:0xf
	s_waitcnt lgkmcnt(0)
	v_add_f32_e32 v96, v96, v97
	v_fmamk_f32 v96, v96, 0x3c000000, v131
	v_cmp_gt_f32_e32 vcc, s30, v96
	v_mul_f32_e32 v97, 0x4f800000, v96
	s_nop 0
	v_cndmask_b32_e32 v96, v96, v97, vcc
	v_sqrt_f32_e32 v97, v96
	s_nop 0
	v_add_u32_e32 v98, -1, v97
	v_fma_f32 v99, -v98, v97, v96
	v_cmp_ge_f32_e64 s[6:7], 0, v99
	v_add_u32_e32 v99, 1, v97
	s_nop 0
	v_cndmask_b32_e64 v98, v97, v98, s[6:7]
	v_fma_f32 v97, -v99, v97, v96
	v_cmp_lt_f32_e64 s[6:7], 0, v97
	s_nop 1
	v_cndmask_b32_e64 v97, v98, v99, s[6:7]
	v_mul_f32_e32 v98, 0x37800000, v97
	v_cndmask_b32_e32 v97, v97, v98, vcc
	v_cmp_class_f32_e32 vcc, v96, v222
	s_nop 1
	v_cndmask_b32_e32 v96, v97, v96, vcc
	s_mov_b32 s2, -1
	v_rcp_f32_e32 v98, v96
	s_nop 0
	v_fma_f32 v97, -v96, v98, 1.0
	v_fma_f32 v97, v97, v98, v98
	v_div_fixup_f32 v96, v97, v96, 1.0
	v_mul_f32_e32 v97, v92, v96
	s_waitcnt vmcnt(0)
	v_mul_f32_e32 v105, v224, v97
	v_mul_f32_e32 v97, v88, v96
	v_mul_f32_e32 v108, v223, v97
	v_mul_f32_e32 v97, v76, v96
	v_mul_f32_e32 v104, v212, v97
	v_mul_f32_e32 v97, v72, v96
	v_mul_f32_e32 v109, v211, v97
	v_mul_f32_e32 v97, v84, v96
	v_mul_f32_e32 v110, v210, v97
	v_mul_f32_e32 v97, v80, v96
	v_mul_f32_e32 v111, v209, v97
	v_mul_f32_e32 v97, v68, v96
	v_mul_f32_e32 v96, v64, v96
	v_mul_f32_e32 v113, v207, v96
	v_and_b32_e32 v96, s14, v128
	v_mul_f32_e32 v112, v208, v97
	v_lshlrev_b32_e32 v96, 6, v96
	v_mov_b32_e32 v97, v177
	v_lshl_add_u64 v[96:97], v[96:97], 3, s[36:37]
	v_lshl_add_u64 v[100:101], v[96:97], 0, v[160:161]
	global_load_dwordx4 v[96:99], v[100:101], off offset:16
	s_nop 0
	global_load_dwordx4 v[100:103], v[100:101], off
	s_waitcnt vmcnt(0)
	v_mul_f32_e32 v106, v101, v104
	v_fma_f32 v106, v100, v105, -v106
	v_mul_f32_e32 v104, v100, v104
	v_mul_f32_e32 v100, v103, v109
	v_fma_f32 v107, v102, v108, -v100
	v_mul_f32_e32 v100, v97, v112
	v_fmac_f32_e32 v104, v101, v105
	v_mul_f32_e32 v105, v102, v109
	v_fma_f32 v102, v96, v110, -v100
	v_mul_f32_e32 v100, v96, v112
	v_mul_f32_e32 v96, v99, v113
	v_fmac_f32_e32 v105, v103, v108
	v_fma_f32 v103, v98, v111, -v96
	v_mul_f32_e32 v96, v89, v89
	v_fmac_f32_e32 v96, v93, v93
	v_fmac_f32_e32 v96, v77, v77
	v_fmac_f32_e32 v96, v73, v73
	v_mul_f32_e32 v101, v98, v113
	v_fmac_f32_e32 v96, v85, v85
	v_mbcnt_lo_u32_b32 v98, s2, 0
	v_fmac_f32_e32 v96, v81, v81
	v_mbcnt_hi_u32_b32 v98, s2, v98
	v_fmac_f32_e32 v96, v69, v69
	v_lshlrev_b32_e32 v98, 2, v98
	v_fmac_f32_e32 v101, v99, v111
	v_fmac_f32_e32 v96, v65, v65
	v_xor_b32_e32 v99, 4, v98
	s_nop 1
	v_mov_b32_dpp v99, v96 quad_perm:[1,0,3,2] row_mask:0xf bank_mask:0xf
	v_fmac_f32_e32 v100, v97, v110
	v_add_u32_e32 v97, 1, v128
	s_waitcnt lgkmcnt(0)
	v_add_f32_e32 v96, v96, v99
	v_xor_b32_e32 v99, 8, v98
	s_nop 1
	v_mov_b32_dpp v99, v96 quad_perm:[2,3,0,1] row_mask:0xf bank_mask:0xf
	s_waitcnt lgkmcnt(0)
	v_add_f32_e32 v96, v96, v99
	v_xor_b32_e32 v99, 16, v98
	s_nop 1
	v_mov_b32_dpp v99, v96 row_half_mirror row_mask:0xf bank_mask:0xf
	s_nop 1
	v_mov_b32_dpp v99, v99 quad_perm:[3,2,1,0] row_mask:0xf bank_mask:0xf
	v_xor_b32_e32 v98, 32, v98
	s_waitcnt lgkmcnt(0)
	v_add_f32_e32 v96, v96, v99
	s_nop 1
	v_mov_b32_dpp v98, v96 row_ror:8 row_mask:0xf bank_mask:0xf
	s_waitcnt lgkmcnt(0)
	v_add_f32_e32 v96, v96, v98
	v_fmamk_f32 v96, v96, 0x3c000000, v131
	v_cmp_gt_f32_e32 vcc, s30, v96
	v_mul_f32_e32 v98, 0x4f800000, v96
	s_nop 0
	v_cndmask_b32_e32 v96, v96, v98, vcc
	v_sqrt_f32_e32 v98, v96
	s_nop 0
	v_add_u32_e32 v99, -1, v98
	v_fma_f32 v108, -v99, v98, v96
	v_cmp_ge_f32_e64 s[6:7], 0, v108
	v_add_u32_e32 v108, 1, v98
	s_nop 0
	v_cndmask_b32_e64 v99, v98, v99, s[6:7]
	v_fma_f32 v98, -v108, v98, v96
	v_cmp_lt_f32_e64 s[6:7], 0, v98
	s_nop 1
	v_cndmask_b32_e64 v98, v99, v108, s[6:7]
	v_mul_f32_e32 v99, 0x37800000, v98
	v_cndmask_b32_e32 v98, v98, v99, vcc
	v_cmp_class_f32_e32 vcc, v96, v222
	s_nop 1
	v_cndmask_b32_e32 v96, v98, v96, vcc
	s_mov_b32 s2, -1
	v_rcp_f32_e32 v99, v96
	s_nop 0
	v_fma_f32 v98, -v96, v99, 1.0
	v_fma_f32 v98, v98, v99, v99
	v_div_fixup_f32 v96, v98, v96, 1.0
	v_mul_f32_e32 v98, v93, v96
	v_mul_f32_e32 v113, v224, v98
	v_mul_f32_e32 v98, v89, v96
	v_mul_f32_e32 v116, v223, v98
	v_mul_f32_e32 v98, v77, v96
	v_mul_f32_e32 v112, v212, v98
	v_mul_f32_e32 v98, v73, v96
	v_mul_f32_e32 v117, v211, v98
	v_mul_f32_e32 v98, v85, v96
	v_mul_f32_e32 v118, v210, v98
	v_mul_f32_e32 v98, v81, v96
	v_mul_f32_e32 v119, v209, v98
	v_mul_f32_e32 v98, v69, v96
	v_mul_f32_e32 v96, v65, v96
	v_mul_f32_e32 v121, v207, v96
	v_and_b32_e32 v96, s14, v97
	v_lshlrev_b32_e32 v96, 6, v96
	v_mov_b32_e32 v97, v177
	v_lshl_add_u64 v[96:97], v[96:97], 3, s[36:37]
	v_lshl_add_u64 v[108:109], v[96:97], 0, v[160:161]
	v_mul_f32_e32 v120, v208, v98
	global_load_dwordx4 v[96:99], v[108:109], off offset:16
	s_nop 0
	global_load_dwordx4 v[108:111], v[108:109], off
	s_waitcnt vmcnt(0)
; DEVFI int lane_opaque() { unsigned m = ~0u; asm volatile("" : "+s"(m)); return (int)__builtin_amdgcn_mbcnt_hi(m, __builtin_amdgcn_mbcnt_lo(m, 0u)); }
; DEVFI float shx(float v, int mask, int lane) { return __int_as_float(__builtin_amdgcn_ds_bpermute((lane ^ mask) << 2, __float_as_int(v))); }
; DEVFI float red16(float v) {
;   const int ln = lane_opaque();
;   v += shx(v, 1, ln); v += shx(v, 2, ln); v += shx(v, 4, ln); v += shx(v, 8, ln); return v;
; }
; __global__ void __launch_bounds__(512) mega(Params p) {
;     ...
;                     for (int j = 0; j < 4; ++j) { const int pos = (r0 + j) & (seqlen - 1);
;                       float ss = 0;
; #pragma unroll
;                       for (int n = 0; n < 8; ++n) ss += a[n][j] * a[n][j];
;                       ss = red16(ss);
;                       const float rstd = 1.f / sqrtf(ss * (1.f / 128.f) + RMS_EPS);
; #pragma unroll
;                       for (int n = 0; n < 8; ++n) a[n][j] = a[n][j] * rstd * hv[n];
;                       const float4* tb = (const float4*)(attt + pos * 64 + fr * 4);
;                       const float4 t01 = tb[0], t23 = tb[1];
;                       const float2 csv[4] = {make_float2(t01.x, t01.y), make_float2(t01.z, t01.w), make_float2(t23.x, t23.y), make_float2(t23.z, t23.w)};
; #pragma unroll
;                       for (int hh = 0; hh < 2; ++hh)
; #pragma unroll
;                         for (int n = 0; n < 2; ++n) { const float2 cs = csv[hh * 2 + n];
;                           const float x1 = a[hh * 4 + n][j], x2 = a[hh * 4 + n + 2][j];
;                           a[hh * 4 + n][j] = x1 * cs.x - x2 * cs.y; a[hh * 4 + n + 2][j] = x1 * cs.y + x2 * cs.x; } }
	v_mul_f32_e32 v114, v109, v112
	v_fma_f32 v114, v108, v113, -v114
	v_mul_f32_e32 v112, v108, v112
	v_mul_f32_e32 v108, v111, v117
	v_fma_f32 v115, v110, v116, -v108
	v_mul_f32_e32 v108, v97, v120
	v_fmac_f32_e32 v112, v109, v113
	v_mul_f32_e32 v113, v110, v117
	v_fma_f32 v110, v96, v118, -v108
	v_mul_f32_e32 v108, v96, v120
	v_mul_f32_e32 v96, v99, v121
	v_fmac_f32_e32 v113, v111, v116
	v_fma_f32 v111, v98, v119, -v96
	v_mul_f32_e32 v96, v90, v90
	v_fmac_f32_e32 v96, v94, v94
	v_fmac_f32_e32 v96, v78, v78
	v_fmac_f32_e32 v96, v74, v74
	v_mul_f32_e32 v109, v98, v121
	v_fmac_f32_e32 v96, v86, v86
	v_mbcnt_lo_u32_b32 v98, s2, 0
	v_fmac_f32_e32 v96, v82, v82
	v_mbcnt_hi_u32_b32 v98, s2, v98
	v_fmac_f32_e32 v96, v70, v70
	v_lshlrev_b32_e32 v98, 2, v98
	v_fmac_f32_e32 v109, v99, v119
	v_fmac_f32_e32 v96, v66, v66
	v_xor_b32_e32 v99, 4, v98
	s_nop 1
	v_mov_b32_dpp v99, v96 quad_perm:[1,0,3,2] row_mask:0xf bank_mask:0xf
	v_fmac_f32_e32 v108, v97, v118
	v_add_u32_e32 v97, 2, v128
	s_waitcnt lgkmcnt(0)
	v_add_f32_e32 v96, v96, v99
	v_xor_b32_e32 v99, 8, v98
	s_nop 1
	v_mov_b32_dpp v99, v96 quad_perm:[2,3,0,1] row_mask:0xf bank_mask:0xf
	s_waitcnt lgkmcnt(0)
	v_add_f32_e32 v96, v96, v99
	v_xor_b32_e32 v99, 16, v98
	s_nop 1
	v_mov_b32_dpp v99, v96 row_half_mirror row_mask:0xf bank_mask:0xf
	s_nop 1
	v_mov_b32_dpp v99, v99 quad_perm:[3,2,1,0] row_mask:0xf bank_mask:0xf
	v_xor_b32_e32 v98, 32, v98
	s_waitcnt lgkmcnt(0)
	v_add_f32_e32 v96, v96, v99
	s_nop 1
	v_mov_b32_dpp v98, v96 row_ror:8 row_mask:0xf bank_mask:0xf
	s_waitcnt lgkmcnt(0)
	v_add_f32_e32 v96, v96, v98
	v_fmamk_f32 v96, v96, 0x3c000000, v131
	v_cmp_gt_f32_e32 vcc, s30, v96
	v_mul_f32_e32 v98, 0x4f800000, v96
	s_nop 0
	v_cndmask_b32_e32 v96, v96, v98, vcc
	v_sqrt_f32_e32 v98, v96
	s_nop 0
	v_add_u32_e32 v99, -1, v98
	v_fma_f32 v116, -v99, v98, v96
	v_cmp_ge_f32_e64 s[6:7], 0, v116
	v_add_u32_e32 v116, 1, v98
	s_nop 0
	v_cndmask_b32_e64 v99, v98, v99, s[6:7]
	v_fma_f32 v98, -v116, v98, v96
	v_cmp_lt_f32_e64 s[6:7], 0, v98
	s_nop 1
	v_cndmask_b32_e64 v98, v99, v116, s[6:7]
	v_mul_f32_e32 v99, 0x37800000, v98
	v_cndmask_b32_e32 v98, v98, v99, vcc
	v_cmp_class_f32_e32 vcc, v96, v222
	s_nop 1
	v_cndmask_b32_e32 v96, v98, v96, vcc
	s_mov_b32 s2, -1
	v_rcp_f32_e32 v99, v96
	s_nop 0
	v_fma_f32 v98, -v96, v99, 1.0
	v_fma_f32 v98, v98, v99, v99
	v_div_fixup_f32 v96, v98, v96, 1.0
	v_mul_f32_e32 v98, v94, v96
	v_mul_f32_e32 v121, v224, v98
	v_mul_f32_e32 v98, v90, v96
	v_mul_f32_e32 v124, v223, v98
	v_mul_f32_e32 v98, v78, v96
	v_mul_f32_e32 v120, v212, v98
	v_mul_f32_e32 v98, v74, v96
	v_mul_f32_e32 v125, v211, v98
	v_mul_f32_e32 v98, v86, v96
	v_mul_f32_e32 v126, v210, v98
	v_mul_f32_e32 v98, v82, v96
	v_mul_f32_e32 v127, v209, v98
	v_mul_f32_e32 v98, v70, v96
	v_mul_f32_e32 v96, v66, v96
	v_mul_f32_e32 v130, v207, v96
	v_and_b32_e32 v96, s14, v97
	v_lshlrev_b32_e32 v96, 6, v96
	v_mov_b32_e32 v97, v177
	v_lshl_add_u64 v[96:97], v[96:97], 3, s[36:37]
	v_lshl_add_u64 v[116:117], v[96:97], 0, v[160:161]
	v_mul_f32_e32 v129, v208, v98
	global_load_dwordx4 v[96:99], v[116:117], off offset:16
	s_nop 0
	global_load_dwordx4 v[116:119], v[116:117], off
	s_waitcnt vmcnt(0)
	v_mul_f32_e32 v122, v117, v120
	v_fma_f32 v122, v116, v121, -v122
	v_mul_f32_e32 v120, v116, v120
	v_mul_f32_e32 v116, v119, v125
	v_fma_f32 v123, v118, v124, -v116
	v_mul_f32_e32 v116, v97, v129
	v_fmac_f32_e32 v120, v117, v121
	v_mul_f32_e32 v121, v118, v125
	v_fma_f32 v118, v96, v126, -v116
	v_mul_f32_e32 v116, v96, v129
	v_mul_f32_e32 v96, v99, v130
	v_fmac_f32_e32 v121, v119, v124
	v_fma_f32 v119, v98, v127, -v96
	v_mul_f32_e32 v96, v91, v91
	v_fmac_f32_e32 v96, v95, v95
	v_fmac_f32_e32 v96, v79, v79
	v_fmac_f32_e32 v96, v75, v75
	v_mul_f32_e32 v117, v98, v130
	v_fmac_f32_e32 v96, v87, v87
	v_mbcnt_lo_u32_b32 v98, s2, 0
	v_fmac_f32_e32 v96, v83, v83
	v_mbcnt_hi_u32_b32 v98, s2, v98
	v_fmac_f32_e32 v96, v71, v71
	v_lshlrev_b32_e32 v98, 2, v98
	v_fmac_f32_e32 v117, v99, v127
	v_fmac_f32_e32 v96, v67, v67
	v_xor_b32_e32 v99, 4, v98
	s_nop 1
	v_mov_b32_dpp v99, v96 quad_perm:[1,0,3,2] row_mask:0xf bank_mask:0xf
	v_fmac_f32_e32 v116, v97, v126
	v_add_u32_e32 v97, 3, v128
	s_waitcnt lgkmcnt(0)
; DEVFI float dpp_xor1(float x) { return __int_as_float(__builtin_amdgcn_update_dpp(0, __float_as_int(x), 0xB1, 0xF, 0xF, true)); }
; #define AQ ((bfraw*)(kargs()->ws + O_AQ))
; #define AK ((bfraw*)(kargs()->ws + O_AK))
; DEVFI void store_nat_m(bfraw* base, long ld, f32x4 (&a)[8], int fr) {
;   const bool odd = fr & 1;
;   bfraw* p0 = base + (odd ? 15 + fr : fr);
; #pragma unroll
;   for (int j = 0; j < 4; ++j)
; #pragma unroll
;     for (int n0 = 0; n0 < 8; n0 += 2) { const float own0 = a[n0][j], own1 = a[n0 + 1][j];
;       const float recv = dpp_xor1(odd ? own0 : own1);
;       const unsigned pk = odd ? cvtpk(recv, own1) : cvtpk(own0, recv);
;       *reinterpret_cast<unsigned*>(p0 + (long)j * ld + n0 * 16) = pk; }
; __global__ void __launch_bounds__(512) mega(Params p) {
;     ...
;                     for (int j = 0; j < 4; ++j) { const int pos = (r0 + j) & (seqlen - 1);
;                       float ss = 0;
; #pragma unroll
;                       for (int n = 0; n < 8; ++n) ss += a[n][j] * a[n][j];
;                       ss = red16(ss);
;                       const float rstd = 1.f / sqrtf(ss * (1.f / 128.f) + RMS_EPS);
; #pragma unroll
;                       for (int n = 0; n < 8; ++n) a[n][j] = a[n][j] * rstd * hv[n];
;                       const float4* tb = (const float4*)(attt + pos * 64 + fr * 4);
;                       const float4 t01 = tb[0], t23 = tb[1];
;                       const float2 csv[4] = {make_float2(t01.x, t01.y), make_float2(t01.z, t01.w), make_float2(t23.x, t23.y), make_float2(t23.z, t23.w)};
; #pragma unroll
;                       for (int hh = 0; hh < 2; ++hh)
; #pragma unroll
;                         for (int n = 0; n < 2; ++n) { const float2 cs = csv[hh * 2 + n];
;                           const float x1 = a[hh * 4 + n][j], x2 = a[hh * 4 + n + 2][j];
;                           a[hh * 4 + n][j] = x1 * cs.x - x2 * cs.y; a[hh * 4 + n + 2][j] = x1 * cs.y + x2 * cs.x; } }
;                     if (isk) store_nat_m(AK + (long)r0 * 256 + (c0 - 7168), 256, a, fr);
;                     else store_nat_m(AQ + (long)r0 * 1024 + (c0 - 6144), 1024, a, fr);
	v_add_f32_e32 v96, v96, v99
	v_xor_b32_e32 v99, 8, v98
	s_nop 1
	v_mov_b32_dpp v99, v96 quad_perm:[2,3,0,1] row_mask:0xf bank_mask:0xf
	s_waitcnt lgkmcnt(0)
	v_add_f32_e32 v96, v96, v99
	v_xor_b32_e32 v99, 16, v98
	s_nop 1
	v_mov_b32_dpp v99, v96 row_half_mirror row_mask:0xf bank_mask:0xf
	s_nop 1
	v_mov_b32_dpp v99, v99 quad_perm:[3,2,1,0] row_mask:0xf bank_mask:0xf
	v_xor_b32_e32 v98, 32, v98
	s_waitcnt lgkmcnt(0)
	v_add_f32_e32 v96, v96, v99
	s_nop 1
	v_mov_b32_dpp v98, v96 row_ror:8 row_mask:0xf bank_mask:0xf
	s_waitcnt lgkmcnt(0)
	v_add_f32_e32 v96, v96, v98
	v_fmamk_f32 v96, v96, 0x3c000000, v131
	v_cmp_gt_f32_e32 vcc, s30, v96
	v_mul_f32_e32 v98, 0x4f800000, v96
	s_nop 0
	v_cndmask_b32_e32 v96, v96, v98, vcc
	v_sqrt_f32_e32 v98, v96
	s_nop 0
	v_add_u32_e32 v99, -1, v98
	v_fma_f32 v124, -v99, v98, v96
	v_cmp_ge_f32_e64 s[6:7], 0, v124
	v_add_u32_e32 v124, 1, v98
	s_nop 0
	v_cndmask_b32_e64 v99, v98, v99, s[6:7]
	v_fma_f32 v98, -v124, v98, v96
	v_cmp_lt_f32_e64 s[6:7], 0, v98
	s_nop 1
	v_cndmask_b32_e64 v98, v99, v124, s[6:7]
	v_mul_f32_e32 v99, 0x37800000, v98
	v_cndmask_b32_e32 v98, v98, v99, vcc
	v_cmp_class_f32_e32 vcc, v96, v222
	s_nop 1
	v_cndmask_b32_e32 v96, v98, v96, vcc
	s_mov_b64 s[2:3], -1
	v_rcp_f32_e32 v99, v96
	s_nop 0
	v_fma_f32 v98, -v96, v99, 1.0
	v_fma_f32 v98, v98, v99, v99
	v_div_fixup_f32 v96, v98, v96, 1.0
	v_mul_f32_e32 v98, v95, v96
	v_mul_f32_e32 v126, v224, v98
	v_mul_f32_e32 v98, v91, v96
	v_mul_f32_e32 v129, v223, v98
	v_mul_f32_e32 v98, v79, v96
	v_mul_f32_e32 v127, v212, v98
	v_mul_f32_e32 v98, v75, v96
	v_mul_f32_e32 v130, v211, v98
	v_mul_f32_e32 v98, v87, v96
	v_mul_f32_e32 v136, v210, v98
	v_mul_f32_e32 v98, v83, v96
	v_mul_f32_e32 v137, v209, v98
	v_mul_f32_e32 v98, v71, v96
	v_mul_f32_e32 v96, v67, v96
	v_mul_f32_e32 v139, v207, v96
	v_and_b32_e32 v96, s14, v97
	v_lshlrev_b32_e32 v96, 6, v96
	v_mov_b32_e32 v97, v177
	v_lshl_add_u64 v[96:97], v[96:97], 3, s[36:37]
	v_lshl_add_u64 v[124:125], v[96:97], 0, v[160:161]
	v_mul_f32_e32 v138, v208, v98
	global_load_dwordx4 v[96:99], v[124:125], off offset:16
	global_load_dwordx4 v[132:135], v[124:125], off
	s_waitcnt vmcnt(0)
	v_mul_f32_e32 v124, v133, v127
	v_fma_f32 v131, v132, v126, -v124
	v_mul_f32_e32 v124, v135, v130
	v_mul_f32_e32 v127, v132, v127
	v_fma_f32 v132, v134, v129, -v124
	v_mul_f32_e32 v124, v97, v138
	v_fma_f32 v125, v96, v136, -v124
	v_mul_f32_e32 v124, v96, v138
	v_mul_f32_e32 v96, v99, v139
	v_fmac_f32_e32 v127, v133, v126
	v_fma_f32 v126, v98, v137, -v96
	v_and_b32_e32 v96, 1, v203
	v_mul_f32_e32 v130, v134, v130
	v_mul_f32_e32 v98, v98, v139
	v_cmp_eq_u32_e32 vcc, 0, v96
	v_cmp_eq_u32_e64 s[6:7], 1, v96
	v_add_u32_e32 v96, 15, v202
	v_fmac_f32_e32 v130, v135, v129
	v_fmac_f32_e32 v124, v97, v136
	v_fmac_f32_e32 v98, v99, v137
	v_ashrrev_i32_e32 v129, 31, v128
	v_cndmask_b32_e32 v99, v96, v202, vcc
	v_cndmask_b32_e32 v133, v106, v107, vcc
	s_and_b64 vcc, exec, s[8:9]
	s_cbranch_vccz .LBB0_1261
	s_mov_b64 s[2:3], s[0:1]
	s_load_dwordx2 s[2:3], s[2:3], 0xe8
	v_mov_b32_dpp v96, v133 quad_perm:[1,0,3,2] row_mask:0xf bank_mask:0xf bound_ctrl:1
	s_and_saveexec_b64 s[8:9], s[6:7]
	s_xor_b64 s[8:9], exec, s[8:9]
	s_cbranch_execz .LBB0_1198
	v_cvt_pk_bf16_f32 v134, v96, v107

; DEVFI float gelu_tanh(float x) {
;   float u = 0.7978845608028654f * (x + 0.044715f * x * x * x);
;   float t = __expf(2.f * u);
;   float th = 1.f - 2.f / (t + 1.f);
;   return 0.5f * x * (1.f + th);
; }
; __global__ void __launch_bounds__(512) mega(Params p) {
;     ...
; #pragma unroll
;                     for (int n = 0; n < 8; ++n)
; #pragma unroll
;                       for (int j = 0; j < 4; ++j) a[n][j] = gelu_tanh(a[n][j]);
.LBB0_1328:
	s_andn2_b64 vcc, exec, s[2:3]
	s_cbranch_vccnz .LBB0_1406
	v_mul_f32_e32 v97, 0x3d372713, v93
	v_mul_f32_e32 v97, v93, v97
	v_fma_f32 v97, v93, v97, v93
	v_mul_f32_e32 v97, 0x3f4c422a, v97
	v_add_f32_e32 v97, v97, v97
	v_mul_f32_e32 v97, 0x3fb8aa3b, v97
	v_exp_f32_e32 v98, v97
	v_mul_f32_e32 v97, 0x3d372713, v94
	v_mul_f32_e32 v97, v94, v97
	v_fma_f32 v97, v94, v97, v94
	v_mul_f32_e32 v97, 0x3f4c422a, v97
	v_add_f32_e32 v97, v97, v97
	v_mul_f32_e32 v97, 0x3fb8aa3b, v97
	v_mul_f32_e32 v96, 0x3d372713, v92
	v_exp_f32_e32 v100, v97
	v_mul_f32_e32 v97, 0x3d372713, v88
	v_mul_f32_e32 v96, v92, v96
	v_mul_f32_e32 v97, v88, v97
	v_fma_f32 v96, v92, v96, v92
	v_fma_f32 v97, v88, v97, v88
	v_mul_f32_e32 v96, 0x3f4c422a, v96
	v_mul_f32_e32 v97, 0x3f4c422a, v97
	v_add_f32_e32 v96, v96, v96
	v_add_f32_e32 v97, v97, v97
	v_mul_f32_e32 v96, 0x3fb8aa3b, v96
	v_mul_f32_e32 v97, 0x3fb8aa3b, v97
	v_exp_f32_e32 v96, v96
	v_exp_f32_e32 v97, v97
	v_mul_f32_e32 v99, 0x3d372713, v95
	v_mul_f32_e32 v99, v95, v99
	v_fma_f32 v99, v95, v99, v95
	v_pk_add_f32 v[96:97], v[96:97], 1.0 op_sel_hi:[1,0]
	v_mul_f32_e32 v99, 0x3f4c422a, v99
	v_add_f32_e32 v99, v99, v99
	v_mul_f32_e32 v99, 0x3fb8aa3b, v99
	v_exp_f32_e32 v102, v99
	v_rcp_f32_e32 v103, v97
	s_nop 0
	v_fma_f32 v99, -v97, v103, 1.0
	v_fma_f32 v103, v99, v103, v103
	v_add_f32_e32 v99, v103, v103
	v_div_fixup_f32 v97, v99, v97, 2.0
	s_cmpk_lt_u32 s26, 0x1400
	v_rcp_f32_e32 v105, v96
	s_nop 0
	v_fma_f32 v99, -v96, v105, 1.0
	v_fma_f32 v105, v99, v105, v105
	v_add_f32_e32 v99, v105, v105
	v_div_fixup_f32 v96, v99, v96, 2.0
	v_mul_f32_e32 v99, 0x3d372713, v89
	v_mul_f32_e32 v99, v89, v99
	v_fma_f32 v99, v89, v99, v89
	v_mul_f32_e32 v99, 0x3f4c422a, v99
	v_add_f32_e32 v99, v99, v99
	v_mul_f32_e32 v99, 0x3fb8aa3b, v99
	v_exp_f32_e32 v99, v99
	v_pk_add_f32 v[96:97], v[96:97], 1.0 op_sel_hi:[1,0] neg_lo:[1,0] neg_hi:[1,0]
	v_mov_b32_e32 v104, v92
	v_mov_b32_e32 v105, v88
	v_pk_add_f32 v[98:99], v[98:99], 1.0 op_sel_hi:[1,0]
	v_pk_mul_f32 v[104:105], v[104:105], 0.5 op_sel_hi:[1,0]
	v_pk_add_f32 v[96:97], v[96:97], 1.0 op_sel_hi:[1,0]
	s_mov_b64 s[8:9], -1
	v_pk_mul_f32 v[110:111], v[104:105], v[96:97]
	v_rcp_f32_e32 v103, v99
	s_nop 0
	v_fma_f32 v96, -v99, v103, 1.0
	v_fma_f32 v103, v96, v103, v103
	v_add_f32_e32 v96, v103, v103
	v_div_fixup_f32 v97, v96, v99, 2.0
	v_rcp_f32_e32 v104, v98
	s_nop 0
	v_fma_f32 v96, -v98, v104, 1.0
	v_fma_f32 v104, v96, v104, v104
	v_add_f32_e32 v96, v104, v104
	v_div_fixup_f32 v96, v96, v98, 2.0
	v_mul_f32_e32 v98, 0x3d372713, v90
	v_mul_f32_e32 v98, v90, v98
	v_fma_f32 v98, v90, v98, v90
	v_mul_f32_e32 v98, 0x3f4c422a, v98
	v_add_f32_e32 v98, v98, v98
	v_mul_f32_e32 v98, 0x3fb8aa3b, v98
	v_exp_f32_e32 v101, v98
	v_pk_add_f32 v[96:97], v[96:97], 1.0 op_sel_hi:[1,0] neg_lo:[1,0] neg_hi:[1,0]
	v_mov_b32_e32 v98, v93
	v_mov_b32_e32 v99, v89
	v_pk_add_f32 v[100:101], v[100:101], 1.0 op_sel_hi:[1,0]
	v_pk_mul_f32 v[98:99], v[98:99], 0.5 op_sel_hi:[1,0]
	v_pk_add_f32 v[96:97], v[96:97], 1.0 op_sel_hi:[1,0]
	s_nop 0
	v_pk_mul_f32 v[106:107], v[98:99], v[96:97]
	v_rcp_f32_e32 v104, v101
	s_nop 0
	v_fma_f32 v96, -v101, v104, 1.0
	v_fma_f32 v104, v96, v104, v104
	v_add_f32_e32 v96, v104, v104
	v_div_fixup_f32 v97, v96, v101, 2.0
	v_mul_f32_e32 v98, 0x3d372713, v91
	v_mul_f32_e32 v98, v91, v98
	v_fma_f32 v98, v91, v98, v91
	v_mul_f32_e32 v98, 0x3f4c422a, v98
	v_add_f32_e32 v98, v98, v98
	v_mul_f32_e32 v98, 0x3fb8aa3b, v98
	v_exp_f32_e32 v103, v98
	v_rcp_f32_e32 v99, v100
	s_nop 0
	v_fma_f32 v96, -v100, v99, 1.0
	v_fma_f32 v99, v96, v99, v99
	v_add_f32_e32 v96, v99, v99
	v_div_fixup_f32 v96, v96, v100, 2.0
	v_pk_add_f32 v[96:97], v[96:97], 1.0 op_sel_hi:[1,0] neg_lo:[1,0] neg_hi:[1,0]
	v_pk_add_f32 v[102:103], v[102:103], 1.0 op_sel_hi:[1,0]
	v_mov_b32_e32 v98, v94
	v_mov_b32_e32 v99, v90
	v_pk_mul_f32 v[98:99], v[98:99], 0.5 op_sel_hi:[1,0]
	v_pk_add_f32 v[96:97], v[96:97], 1.0 op_sel_hi:[1,0]
	s_nop 0
	v_pk_mul_f32 v[100:101], v[98:99], v[96:97]
	v_rcp_f32_e32 v105, v103
	s_nop 0
	v_fma_f32 v96, -v103, v105, 1.0
	v_fma_f32 v105, v96, v105, v105
	v_add_f32_e32 v96, v105, v105
	v_div_fixup_f32 v97, v96, v103, 2.0
	v_mul_f32_e32 v98, 0x3d372713, v76
	v_mul_f32_e32 v98, v76, v98
	v_fma_f32 v98, v76, v98, v76
	v_mul_f32_e32 v98, 0x3f4c422a, v98
	v_add_f32_e32 v98, v98, v98
	v_rcp_f32_e32 v99, v102
	s_nop 0
	v_fma_f32 v96, -v102, v99, 1.0
	v_fma_f32 v99, v96, v99, v99
	v_add_f32_e32 v96, v99, v99
	v_mul_f32_e32 v98, 0x3fb8aa3b, v98
	v_div_fixup_f32 v96, v96, v102, 2.0
	v_exp_f32_e32 v102, v98
	v_pk_add_f32 v[96:97], v[96:97], 1.0 op_sel_hi:[1,0] neg_lo:[1,0] neg_hi:[1,0]
	v_mov_b32_e32 v98, v95
	v_mov_b32_e32 v99, v91
	v_add_f32_e32 v102, 1.0, v102
	v_pk_mul_f32 v[98:99], v[98:99], 0.5 op_sel_hi:[1,0]
	v_pk_add_f32 v[96:97], v[96:97], 1.0 op_sel_hi:[1,0]
	s_nop 0
	v_pk_mul_f32 v[96:97], v[98:99], v[96:97]
	v_mul_f32_e32 v103, 0x3d372713, v77
	v_mul_f32_e32 v103, v77, v103
	v_fma_f32 v103, v77, v103, v77
	v_mul_f32_e32 v103, 0x3f4c422a, v103
	v_add_f32_e32 v103, v103, v103
	v_mul_f32_e32 v103, 0x3fb8aa3b, v103
	v_exp_f32_e32 v103, v103
	v_rcp_f32_e32 v104, v102
	s_nop 0
	v_fma_f32 v98, -v102, v104, 1.0
	v_fma_f32 v104, v98, v104, v104
	v_add_f32_e32 v98, v104, v104
	v_div_fixup_f32 v98, v98, v102, 2.0
	v_sub_f32_e32 v98, 1.0, v98
	v_add_f32_e32 v99, 1.0, v103
	v_mul_f32_e32 v104, 0.5, v76
	v_add_f32_e32 v98, 1.0, v98
	v_mul_f32_e32 v122, v104, v98
	v_mul_f32_e32 v102, 0x3d372713, v78
	v_mul_f32_e32 v102, v78, v102
	v_fma_f32 v102, v78, v102, v78
	v_mul_f32_e32 v102, 0x3f4c422a, v102
	v_add_f32_e32 v102, v102, v102
	v_mul_f32_e32 v102, 0x3fb8aa3b, v102
	v_exp_f32_e32 v102, v102
; DEVFI float gelu_tanh(float x) {
;   float u = 0.7978845608028654f * (x + 0.044715f * x * x * x);
;   float t = __expf(2.f * u);
;   float th = 1.f - 2.f / (t + 1.f);
;   return 0.5f * x * (1.f + th);
; }
; __global__ void __launch_bounds__(512) mega(Params p) {
;     ...
;                     for (int n = 0; n < 8; ++n)
; #pragma unroll
;                       for (int j = 0; j < 4; ++j) a[n][j] = gelu_tanh(a[n][j]);
	v_rcp_f32_e32 v103, v99
	s_nop 0
	v_fma_f32 v98, -v99, v103, 1.0
	v_fma_f32 v103, v98, v103, v103
	v_add_f32_e32 v98, v103, v103
	v_div_fixup_f32 v98, v98, v99, 2.0
	v_sub_f32_e32 v98, 1.0, v98
	v_add_f32_e32 v99, 1.0, v102
	v_mul_f32_e32 v104, 0.5, v77
	v_add_f32_e32 v98, 1.0, v98
	v_mul_f32_e32 v114, v104, v98
	v_mul_f32_e32 v102, 0x3d372713, v79
	v_mul_f32_e32 v102, v79, v102
	v_fma_f32 v102, v79, v102, v79
	v_mul_f32_e32 v102, 0x3f4c422a, v102
	v_add_f32_e32 v102, v102, v102
	v_mul_f32_e32 v102, 0x3fb8aa3b, v102
	v_exp_f32_e32 v102, v102
	v_rcp_f32_e32 v103, v99
	s_nop 0
	v_fma_f32 v98, -v99, v103, 1.0
	v_fma_f32 v103, v98, v103, v103
	v_add_f32_e32 v98, v103, v103
	v_div_fixup_f32 v98, v98, v99, 2.0
	v_sub_f32_e32 v98, 1.0, v98
	v_add_f32_e32 v99, 1.0, v102
	v_mul_f32_e32 v104, 0.5, v78
	v_add_f32_e32 v98, 1.0, v98
	v_mul_f32_e32 v104, v104, v98
	v_mul_f32_e32 v102, 0x3d372713, v72
	v_mul_f32_e32 v102, v72, v102
	v_fma_f32 v102, v72, v102, v72
	v_mul_f32_e32 v102, 0x3f4c422a, v102
	v_add_f32_e32 v102, v102, v102
	v_mul_f32_e32 v102, 0x3fb8aa3b, v102
	v_exp_f32_e32 v102, v102
	v_rcp_f32_e32 v103, v99
	s_nop 0
	v_fma_f32 v98, -v99, v103, 1.0
	v_fma_f32 v103, v98, v103, v103
	v_add_f32_e32 v98, v103, v103
	v_div_fixup_f32 v98, v98, v99, 2.0
	v_sub_f32_e32 v98, 1.0, v98
	v_add_f32_e32 v99, 1.0, v102
	v_mul_f32_e32 v105, 0.5, v79
	v_add_f32_e32 v98, 1.0, v98
	v_mul_f32_e32 v98, v105, v98
	v_mul_f32_e32 v105, 0x3d372713, v73
	v_mul_f32_e32 v105, v73, v105
	v_fma_f32 v105, v73, v105, v73
	v_mul_f32_e32 v105, 0x3f4c422a, v105
	v_add_f32_e32 v105, v105, v105
	v_mul_f32_e32 v105, 0x3fb8aa3b, v105
	v_exp_f32_e32 v105, v105
	v_rcp_f32_e32 v103, v99
	s_nop 0
	v_fma_f32 v102, -v99, v103, 1.0
	v_fma_f32 v103, v102, v103, v103
	v_add_f32_e32 v102, v103, v103
	v_div_fixup_f32 v99, v102, v99, 2.0
	v_sub_f32_e32 v99, 1.0, v99
	v_add_f32_e32 v102, 1.0, v105
	v_mul_f32_e32 v108, 0.5, v72
	v_add_f32_e32 v99, 1.0, v99
	v_mul_f32_e32 v136, v108, v99
	v_mul_f32_e32 v103, 0x3d372713, v74
	v_mul_f32_e32 v103, v74, v103
	v_fma_f32 v103, v74, v103, v74
	v_mul_f32_e32 v103, 0x3f4c422a, v103
	v_add_f32_e32 v103, v103, v103
	v_mul_f32_e32 v103, 0x3fb8aa3b, v103
	v_exp_f32_e32 v103, v103
	v_rcp_f32_e32 v105, v102
	s_nop 0
	v_fma_f32 v99, -v102, v105, 1.0
	v_fma_f32 v105, v99, v105, v105
	v_add_f32_e32 v99, v105, v105
	v_div_fixup_f32 v99, v99, v102, 2.0
	v_sub_f32_e32 v99, 1.0, v99
	v_add_f32_e32 v102, 1.0, v103
	v_mul_f32_e32 v108, 0.5, v73
	v_add_f32_e32 v99, 1.0, v99
	v_mul_f32_e32 v124, v108, v99
	v_mul_f32_e32 v103, 0x3d372713, v75
	v_mul_f32_e32 v103, v75, v103
	v_fma_f32 v103, v75, v103, v75
	v_mul_f32_e32 v103, 0x3f4c422a, v103
	v_add_f32_e32 v103, v103, v103
	v_mul_f32_e32 v103, 0x3fb8aa3b, v103
	v_exp_f32_e32 v103, v103
	v_rcp_f32_e32 v105, v102
	s_nop 0
	v_fma_f32 v99, -v102, v105, 1.0
	v_fma_f32 v105, v99, v105, v105
	v_add_f32_e32 v99, v105, v105
	v_div_fixup_f32 v99, v99, v102, 2.0
	v_sub_f32_e32 v99, 1.0, v99
	v_add_f32_e32 v102, 1.0, v103
	v_mul_f32_e32 v108, 0.5, v74
	v_add_f32_e32 v99, 1.0, v99
	v_mul_f32_e32 v112, v108, v99
	v_mul_f32_e32 v103, 0x3d372713, v84
	v_mul_f32_e32 v103, v84, v103
	v_fma_f32 v103, v84, v103, v84
	v_mul_f32_e32 v103, 0x3f4c422a, v103
	v_add_f32_e32 v103, v103, v103
	v_mul_f32_e32 v103, 0x3fb8aa3b, v103
	v_exp_f32_e32 v103, v103
	v_rcp_f32_e32 v105, v102
	s_nop 0
	v_fma_f32 v99, -v102, v105, 1.0
	v_fma_f32 v105, v99, v105, v105
	v_add_f32_e32 v99, v105, v105
	v_div_fixup_f32 v99, v99, v102, 2.0
	v_sub_f32_e32 v99, 1.0, v99
	v_add_f32_e32 v103, 1.0, v103
	v_mul_f32_e32 v102, 0.5, v75
	v_add_f32_e32 v99, 1.0, v99
	v_mul_f32_e32 v102, v102, v99
	v_mul_f32_e32 v105, 0x3d372713, v85
	v_mul_f32_e32 v105, v85, v105
	v_fma_f32 v105, v85, v105, v85
	v_mul_f32_e32 v105, 0x3f4c422a, v105
	v_add_f32_e32 v105, v105, v105
	v_mul_f32_e32 v105, 0x3fb8aa3b, v105
	v_exp_f32_e32 v105, v105
	v_rcp_f32_e32 v108, v103
	s_nop 0
	v_fma_f32 v99, -v103, v108, 1.0
	v_fma_f32 v108, v99, v108, v108
	v_add_f32_e32 v99, v108, v108
	v_div_fixup_f32 v99, v99, v103, 2.0
	v_sub_f32_e32 v99, 1.0, v99
	v_add_f32_e32 v103, 1.0, v105
	v_mul_f32_e32 v109, 0.5, v84
	v_add_f32_e32 v99, 1.0, v99
	v_mul_f32_e32 v138, v109, v99
	v_mul_f32_e32 v105, 0x3d372713, v86
	v_mul_f32_e32 v105, v86, v105
	v_fma_f32 v105, v86, v105, v86
	v_mul_f32_e32 v105, 0x3f4c422a, v105
	v_add_f32_e32 v105, v105, v105
	v_mul_f32_e32 v105, 0x3fb8aa3b, v105
	v_exp_f32_e32 v105, v105
	v_rcp_f32_e32 v108, v103
	s_nop 0
	v_fma_f32 v99, -v103, v108, 1.0
	v_fma_f32 v108, v99, v108, v108
	v_add_f32_e32 v99, v108, v108
	v_div_fixup_f32 v99, v99, v103, 2.0
	v_sub_f32_e32 v99, 1.0, v99
	v_add_f32_e32 v103, 1.0, v105
	v_mul_f32_e32 v109, 0.5, v85
	v_add_f32_e32 v99, 1.0, v99
	v_mul_f32_e32 v130, v109, v99
	v_mul_f32_e32 v105, 0x3d372713, v87
	v_mul_f32_e32 v105, v87, v105
	v_fma_f32 v105, v87, v105, v87
	v_mul_f32_e32 v105, 0x3f4c422a, v105
	v_add_f32_e32 v105, v105, v105
	v_mul_f32_e32 v105, 0x3fb8aa3b, v105
	v_exp_f32_e32 v105, v105
	v_rcp_f32_e32 v108, v103
	s_nop 0
	v_fma_f32 v99, -v103, v108, 1.0
	v_fma_f32 v108, v99, v108, v108
	v_add_f32_e32 v99, v108, v108
	v_div_fixup_f32 v99, v99, v103, 2.0
	v_sub_f32_e32 v99, 1.0, v99
	v_add_f32_e32 v103, 1.0, v105
	v_mul_f32_e32 v109, 0.5, v86
	v_add_f32_e32 v99, 1.0, v99
	v_mul_f32_e32 v118, v109, v99
	v_mul_f32_e32 v105, 0x3d372713, v80
	v_mul_f32_e32 v105, v80, v105
	v_fma_f32 v105, v80, v105, v80
	v_mul_f32_e32 v105, 0x3f4c422a, v105
	v_add_f32_e32 v105, v105, v105
	v_mul_f32_e32 v105, 0x3fb8aa3b, v105
	v_exp_f32_e32 v105, v105
	v_rcp_f32_e32 v108, v103
	s_nop 0
	v_fma_f32 v99, -v103, v108, 1.0
	v_fma_f32 v108, v99, v108, v108
	v_add_f32_e32 v99, v108, v108
; #define SVSTAT ((float*)(kargs()->ws + O_SVSTAT))
; DEVFI float gelu_tanh(float x) {
;   float u = 0.7978845608028654f * (x + 0.044715f * x * x * x);
;   float t = __expf(2.f * u);
;   float th = 1.f - 2.f / (t + 1.f);
;   return 0.5f * x * (1.f + th);
; }
; __global__ void __launch_bounds__(512) mega(Params p) {
;     ...
;                     for (int n = 0; n < 8; ++n)
; #pragma unroll
;                       for (int j = 0; j < 4; ++j) a[n][j] = gelu_tanh(a[n][j]);
;                     if (c0 >= 5120) { float* stp = SVSTAT + (long)r0 * 16 + ((c0 - 5120) >> 7) * 2;
	v_div_fixup_f32 v99, v99, v103, 2.0
	v_sub_f32_e32 v99, 1.0, v99
	v_add_f32_e32 v103, 1.0, v105
	v_mul_f32_e32 v108, 0.5, v87
	v_add_f32_e32 v99, 1.0, v99
	v_mul_f32_e32 v108, v108, v99
	v_mul_f32_e32 v105, 0x3d372713, v81
	v_mul_f32_e32 v105, v81, v105
	v_fma_f32 v105, v81, v105, v81
	v_mul_f32_e32 v105, 0x3f4c422a, v105
	v_add_f32_e32 v105, v105, v105
	v_mul_f32_e32 v105, 0x3fb8aa3b, v105
	v_exp_f32_e32 v105, v105
	v_rcp_f32_e32 v109, v103
	s_nop 0
	v_fma_f32 v99, -v103, v109, 1.0
	v_fma_f32 v109, v99, v109, v109
	v_add_f32_e32 v99, v109, v109
	v_div_fixup_f32 v99, v99, v103, 2.0
	v_sub_f32_e32 v99, 1.0, v99
	v_add_f32_e32 v103, 1.0, v105
	v_mul_f32_e32 v113, 0.5, v80
	v_add_f32_e32 v99, 1.0, v99
	v_mul_f32_e32 v146, v113, v99
	v_mul_f32_e32 v105, 0x3d372713, v82
	v_mul_f32_e32 v105, v82, v105
	v_fma_f32 v105, v82, v105, v82
	v_mul_f32_e32 v105, 0x3f4c422a, v105
	v_add_f32_e32 v105, v105, v105
	v_mul_f32_e32 v105, 0x3fb8aa3b, v105
	v_exp_f32_e32 v105, v105
	v_rcp_f32_e32 v109, v103
	s_nop 0
	v_fma_f32 v99, -v103, v109, 1.0
	v_fma_f32 v109, v99, v109, v109
	v_add_f32_e32 v99, v109, v109
	v_div_fixup_f32 v99, v99, v103, 2.0
	v_sub_f32_e32 v99, 1.0, v99
	v_add_f32_e32 v103, 1.0, v105
	v_mul_f32_e32 v113, 0.5, v81
	v_add_f32_e32 v99, 1.0, v99
	v_mul_f32_e32 v140, v113, v99
	v_mul_f32_e32 v105, 0x3d372713, v83
	v_mul_f32_e32 v105, v83, v105
	v_fma_f32 v105, v83, v105, v83
	v_mul_f32_e32 v105, 0x3f4c422a, v105
	v_add_f32_e32 v105, v105, v105
	v_mul_f32_e32 v105, 0x3fb8aa3b, v105
	v_exp_f32_e32 v105, v105
	v_rcp_f32_e32 v109, v103
	s_nop 0
	v_fma_f32 v99, -v103, v109, 1.0
	v_fma_f32 v109, v99, v109, v109
	v_add_f32_e32 v99, v109, v109
	v_div_fixup_f32 v99, v99, v103, 2.0
	v_sub_f32_e32 v99, 1.0, v99
	v_add_f32_e32 v103, 1.0, v105
	v_mul_f32_e32 v113, 0.5, v82
	v_add_f32_e32 v99, 1.0, v99
	v_mul_f32_e32 v126, v113, v99
	v_mul_f32_e32 v105, 0x3d372713, v68
	v_mul_f32_e32 v105, v68, v105
	v_fma_f32 v105, v68, v105, v68
	v_mul_f32_e32 v105, 0x3f4c422a, v105
	v_add_f32_e32 v105, v105, v105
	v_mul_f32_e32 v105, 0x3fb8aa3b, v105
	v_exp_f32_e32 v105, v105
	v_rcp_f32_e32 v109, v103
	s_nop 0
	v_fma_f32 v99, -v103, v109, 1.0
	v_fma_f32 v109, v99, v109, v109
	v_add_f32_e32 v99, v109, v109
	v_div_fixup_f32 v99, v99, v103, 2.0
	v_sub_f32_e32 v99, 1.0, v99
	v_add_f32_e32 v103, 1.0, v105
	v_mul_f32_e32 v113, 0.5, v83
	v_add_f32_e32 v99, 1.0, v99
	v_mul_f32_e32 v116, v113, v99
	v_mul_f32_e32 v105, 0x3d372713, v69
	v_mul_f32_e32 v105, v69, v105
	v_fma_f32 v105, v69, v105, v69
	v_mul_f32_e32 v105, 0x3f4c422a, v105
	v_add_f32_e32 v105, v105, v105
	v_mul_f32_e32 v105, 0x3fb8aa3b, v105
	v_exp_f32_e32 v105, v105
	v_rcp_f32_e32 v109, v103
	s_nop 0
	v_fma_f32 v99, -v103, v109, 1.0
	v_fma_f32 v109, v99, v109, v109
	v_add_f32_e32 v99, v109, v109
	v_div_fixup_f32 v99, v99, v103, 2.0
	v_sub_f32_e32 v99, 1.0, v99
	v_add_f32_e32 v103, 1.0, v105
	v_mul_f32_e32 v113, 0.5, v68
	v_add_f32_e32 v99, 1.0, v99
	v_mul_f32_e32 v148, v113, v99
	v_mul_f32_e32 v105, 0x3d372713, v70
	v_mul_f32_e32 v105, v70, v105
	v_fma_f32 v105, v70, v105, v70
	v_mul_f32_e32 v105, 0x3f4c422a, v105
	v_add_f32_e32 v105, v105, v105
	v_mul_f32_e32 v105, 0x3fb8aa3b, v105
	v_exp_f32_e32 v105, v105
	v_rcp_f32_e32 v109, v103
	s_nop 0
	v_fma_f32 v99, -v103, v109, 1.0
	v_fma_f32 v109, v99, v109, v109
	v_add_f32_e32 v99, v109, v109
	v_div_fixup_f32 v99, v99, v103, 2.0
	v_sub_f32_e32 v99, 1.0, v99
	v_add_f32_e32 v103, 1.0, v105
	v_mul_f32_e32 v113, 0.5, v69
	v_add_f32_e32 v99, 1.0, v99
	v_mul_f32_e32 v144, v113, v99
	v_mul_f32_e32 v105, 0x3d372713, v71
	v_mul_f32_e32 v105, v71, v105
	v_fma_f32 v105, v71, v105, v71
	v_mul_f32_e32 v105, 0x3f4c422a, v105
	v_add_f32_e32 v105, v105, v105
	v_mul_f32_e32 v105, 0x3fb8aa3b, v105
	v_exp_f32_e32 v105, v105
	v_rcp_f32_e32 v109, v103
	s_nop 0
	v_fma_f32 v99, -v103, v109, 1.0
	v_fma_f32 v109, v99, v109, v109
	v_add_f32_e32 v99, v109, v109
	v_div_fixup_f32 v99, v99, v103, 2.0
	v_sub_f32_e32 v99, 1.0, v99
	v_add_f32_e32 v103, 1.0, v105
	v_mul_f32_e32 v113, 0.5, v70
	v_add_f32_e32 v99, 1.0, v99
	v_mul_f32_e32 v134, v113, v99
	v_mul_f32_e32 v105, 0x3d372713, v64
	v_mul_f32_e32 v105, v64, v105
	v_fma_f32 v105, v64, v105, v64
	v_mul_f32_e32 v105, 0x3f4c422a, v105
	v_add_f32_e32 v105, v105, v105
	v_mul_f32_e32 v105, 0x3fb8aa3b, v105
	v_exp_f32_e32 v105, v105
	v_rcp_f32_e32 v109, v103
	s_nop 0
	v_fma_f32 v99, -v103, v109, 1.0
	v_fma_f32 v109, v99, v109, v109
	v_add_f32_e32 v99, v109, v109
	v_div_fixup_f32 v99, v99, v103, 2.0
	v_sub_f32_e32 v99, 1.0, v99
	v_add_f32_e32 v103, 1.0, v105
	v_mul_f32_e32 v113, 0.5, v71
	v_add_f32_e32 v99, 1.0, v99
	v_mul_f32_e32 v120, v113, v99
	v_mul_f32_e32 v105, 0x3d372713, v65
	v_mul_f32_e32 v105, v65, v105
	v_fma_f32 v105, v65, v105, v65
	v_mul_f32_e32 v105, 0x3f4c422a, v105
	v_add_f32_e32 v105, v105, v105
	v_mul_f32_e32 v105, 0x3fb8aa3b, v105
	v_exp_f32_e32 v105, v105
	v_rcp_f32_e32 v109, v103
	s_nop 0
	v_fma_f32 v99, -v103, v109, 1.0
	v_fma_f32 v109, v99, v109, v109
	v_add_f32_e32 v99, v109, v109
	v_div_fixup_f32 v99, v99, v103, 2.0
	v_sub_f32_e32 v99, 1.0, v99
	v_add_f32_e32 v103, 1.0, v105
	v_mul_f32_e32 v113, 0.5, v64
	v_add_f32_e32 v99, 1.0, v99
	v_mul_f32_e32 v152, v113, v99
	v_mul_f32_e32 v105, 0x3d372713, v66
	v_mul_f32_e32 v105, v66, v105
	v_fma_f32 v105, v66, v105, v66
	v_mul_f32_e32 v105, 0x3f4c422a, v105
	v_add_f32_e32 v105, v105, v105
	v_mul_f32_e32 v105, 0x3fb8aa3b, v105
	v_exp_f32_e32 v105, v105
	v_rcp_f32_e32 v109, v103
	s_nop 0
	v_fma_f32 v99, -v103, v109, 1.0
	v_fma_f32 v109, v99, v109, v109
	v_add_f32_e32 v99, v109, v109
	v_div_fixup_f32 v99, v99, v103, 2.0
	v_sub_f32_e32 v99, 1.0, v99
	v_add_f32_e32 v103, 1.0, v105
	v_mul_f32_e32 v113, 0.5, v65
	v_add_f32_e32 v99, 1.0, v99
	v_mul_f32_e32 v150, v113, v99
	v_mul_f32_e32 v105, 0x3d372713, v67
	v_mul_f32_e32 v105, v67, v105
	v_fma_f32 v105, v67, v105, v67
	v_mul_f32_e32 v105, 0x3f4c422a, v105
	v_add_f32_e32 v105, v105, v105
	v_mul_f32_e32 v105, 0x3fb8aa3b, v105
	v_exp_f32_e32 v105, v105
	v_rcp_f32_e32 v109, v103
	s_nop 0
	v_fma_f32 v99, -v103, v109, 1.0
	v_fma_f32 v109, v99, v109, v109
	v_add_f32_e32 v99, v109, v109
	v_div_fixup_f32 v99, v99, v103, 2.0
	v_sub_f32_e32 v99, 1.0, v99
	v_add_f32_e32 v103, 1.0, v105
	v_mul_f32_e32 v113, 0.5, v66
	v_add_f32_e32 v99, 1.0, v99
	v_mul_f32_e32 v142, v113, v99
	v_rcp_f32_e32 v109, v103
	s_nop 0
	v_fma_f32 v99, -v103, v109, 1.0
	v_fma_f32 v109, v99, v109, v109
	v_add_f32_e32 v99, v109, v109
	v_div_fixup_f32 v99, v99, v103, 2.0
	v_sub_f32_e32 v99, 1.0, v99
	v_mul_f32_e32 v103, 0.5, v67
	v_add_f32_e32 v99, 1.0, v99
	v_mul_f32_e32 v132, v103, v99
	s_cbranch_scc1 .LBB0_1339
; DEVFI int lane_opaque() { unsigned m = ~0u; asm volatile("" : "+s"(m)); return (int)__builtin_amdgcn_mbcnt_hi(m, __builtin_amdgcn_mbcnt_lo(m, 0u)); }
; DEVFI float shx(float v, int mask, int lane) { return __int_as_float(__builtin_amdgcn_ds_bpermute((lane ^ mask) << 2, __float_as_int(v))); }
; #define SVSTAT ((float*)(kargs()->ws + O_SVSTAT))
; DEVFI float red16(float v) {
;   const int ln = lane_opaque();
;   v += shx(v, 1, ln); v += shx(v, 2, ln); v += shx(v, 4, ln); v += shx(v, 8, ln); return v;
; }
; __global__ void __launch_bounds__(512) mega(Params p) {
;     ...
;                     if (c0 >= 5120) { float* stp = SVSTAT + (long)r0 * 16 + ((c0 - 5120) >> 7) * 2;
; #pragma unroll
;                       for (int j = 0; j < 4; ++j) { float s1 = 0, s2 = 0;
; #pragma unroll
;                         for (int n = 0; n < 8; ++n) { s1 += a[n][j]; s2 += a[n][j] * a[n][j]; }
;                         s1 = red16(s1); s2 = red16(s2);
;                         if (fr == 0) { stp[j * 16] = s1; stp[j * 16 + 1] = s2; } } }
	s_mov_b64 s[2:3], s[0:1]
	s_load_dwordx2 s[2:3], s[2:3], 0xe8
	v_ashrrev_i32_e32 v129, 31, v128
	v_lshlrev_b64 v[154:155], 6, v[128:129]
	v_add_u32_e32 v99, 0xffffec00, v176
	v_lshrrev_b32_e32 v156, 4, v99
	s_waitcnt lgkmcnt(0)
	v_lshl_add_u64 v[154:155], s[2:3], 0, v[154:155]
	v_mov_b32_e32 v157, v177
	v_lshl_add_u64 v[154:155], v[154:155], 0, v[156:157]
	v_mov_b32_e32 v156, v177
	v_mov_b32_e32 v157, v111
	v_pk_add_f32 v[156:157], v[110:111], v[156:157]
	v_pk_mul_f32 v[158:159], v[110:111], v[110:111]
	s_mov_b64 s[2:3], 0x3a720400
	v_mov_b32_e32 v157, v159
	v_pk_mov_b32 v[158:159], v[110:111], v[158:159] op_sel:[1,0]
	v_lshl_add_u64 v[154:155], v[154:155], 0, s[2:3]
	v_mul_f32_e32 v123, v122, v122
	s_mov_b32 s2, -1
	v_pk_add_f32 v[156:157], v[156:157], v[158:159]
	v_mul_f32_e32 v137, v136, v136
	v_pk_add_f32 v[156:157], v[156:157], v[122:123]
	v_mbcnt_lo_u32_b32 v99, s2, 0
	v_mul_f32_e32 v139, v138, v138
	v_mbcnt_hi_u32_b32 v99, s2, v99
	s_mov_b32 s2, -1
	v_pk_add_f32 v[156:157], v[156:157], v[136:137]
	v_mul_f32_e32 v147, v146, v146
	v_pk_add_f32 v[156:157], v[156:157], v[138:139]
	v_mbcnt_lo_u32_b32 v113, s2, 0
	v_mul_f32_e32 v149, v148, v148
	v_mbcnt_hi_u32_b32 v113, s2, v113
	v_pk_add_f32 v[156:157], v[156:157], v[146:147]
	v_mul_f32_e32 v153, v152, v152
	v_lshlrev_b32_e32 v99, 2, v99
	v_lshlrev_b32_e32 v113, 2, v113
	v_pk_add_f32 v[156:157], v[156:157], v[148:149]
	v_xor_b32_e32 v103, 4, v99
	v_xor_b32_e32 v115, 4, v113
	v_pk_add_f32 v[156:157], v[156:157], v[152:153]
	s_nop 1
	v_mov_b32_dpp v158, v156 quad_perm:[1,0,3,2] row_mask:0xf bank_mask:0xf
	s_nop 0
	v_mov_b32_dpp v159, v157 quad_perm:[1,0,3,2] row_mask:0xf bank_mask:0xf
	v_xor_b32_e32 v105, 8, v99
	v_xor_b32_e32 v117, 8, v113
	v_xor_b32_e32 v109, 16, v99
	v_xor_b32_e32 v119, 16, v113
	s_waitcnt lgkmcnt(0)
	v_pk_add_f32 v[156:157], v[156:157], v[158:159]
	s_nop 1
	v_mov_b32_dpp v158, v156 quad_perm:[2,3,0,1] row_mask:0xf bank_mask:0xf
	s_nop 0
	v_mov_b32_dpp v159, v157 quad_perm:[2,3,0,1] row_mask:0xf bank_mask:0xf
	v_xor_b32_e32 v99, 32, v99
	v_cmp_eq_u32_e32 vcc, 0, v202
	s_waitcnt lgkmcnt(0)
	v_pk_add_f32 v[156:157], v[156:157], v[158:159]
	s_nop 1
	v_mov_b32_dpp v158, v156 row_half_mirror row_mask:0xf bank_mask:0xf
	s_nop 1
	v_mov_b32_dpp v158, v158 quad_perm:[3,2,1,0] row_mask:0xf bank_mask:0xf
	v_mov_b32_dpp v159, v157 row_half_mirror row_mask:0xf bank_mask:0xf
	s_nop 1
	v_mov_b32_dpp v159, v159 quad_perm:[3,2,1,0] row_mask:0xf bank_mask:0xf
	s_waitcnt lgkmcnt(0)
	v_pk_add_f32 v[156:157], v[156:157], v[158:159]
	s_nop 1
	v_mov_b32_dpp v158, v156 row_ror:8 row_mask:0xf bank_mask:0xf
	v_xor_b32_e32 v99, 32, v113
	v_mov_b32_dpp v159, v157 row_ror:8 row_mask:0xf bank_mask:0xf
	s_and_saveexec_b64 s[2:3], vcc
	s_cbranch_execz .LBB0_1332
	s_waitcnt lgkmcnt(0)
	v_pk_add_f32 v[156:157], v[156:157], v[158:159]
	global_store_dwordx2 v[154:155], v[156:157], off
.LBB0_1332:
	s_or_b64 exec, exec, s[2:3]
	v_mov_b32_e32 v156, v177
	v_mov_b32_e32 v157, v107
	v_pk_add_f32 v[156:157], v[106:107], v[156:157]
	s_waitcnt lgkmcnt(0)
	v_pk_mul_f32 v[158:159], v[106:107], v[106:107]
	v_mul_f32_e32 v115, v114, v114
	v_mov_b32_e32 v157, v159
	v_pk_mov_b32 v[158:159], v[106:107], v[158:159] op_sel:[1,0]
	s_mov_b32 s2, -1
	v_pk_add_f32 v[156:157], v[156:157], v[158:159]
	v_mul_f32_e32 v125, v124, v124
	v_pk_add_f32 v[156:157], v[156:157], v[114:115]
	v_mbcnt_lo_u32_b32 v99, s2, 0
	v_mul_f32_e32 v131, v130, v130
	v_mbcnt_hi_u32_b32 v99, s2, v99
	s_mov_b32 s2, -1
	v_pk_add_f32 v[156:157], v[156:157], v[124:125]
	v_mul_f32_e32 v141, v140, v140
	v_pk_add_f32 v[156:157], v[156:157], v[130:131]
	v_mbcnt_lo_u32_b32 v105, s2, 0
	v_mul_f32_e32 v145, v144, v144
	v_mbcnt_hi_u32_b32 v105, s2, v105
	v_pk_add_f32 v[156:157], v[156:157], v[140:141]
	v_mul_f32_e32 v151, v150, v150
	v_lshlrev_b32_e32 v99, 2, v99
	v_lshlrev_b32_e32 v105, 2, v105
	v_pk_add_f32 v[156:157], v[156:157], v[144:145]
	v_xor_b32_e32 v103, 4, v99
	v_xor_b32_e32 v109, 4, v105
	v_pk_add_f32 v[156:157], v[156:157], v[150:151]
	s_nop 1
	v_mov_b32_dpp v158, v156 quad_perm:[1,0,3,2] row_mask:0xf bank_mask:0xf
	s_nop 0
	v_mov_b32_dpp v159, v157 quad_perm:[1,0,3,2] row_mask:0xf bank_mask:0xf
	v_xor_b32_e32 v103, 8, v99
	v_xor_b32_e32 v109, 8, v105
	s_waitcnt lgkmcnt(0)
	v_pk_add_f32 v[156:157], v[156:157], v[158:159]
	s_nop 1
	v_mov_b32_dpp v158, v156 quad_perm:[2,3,0,1] row_mask:0xf bank_mask:0xf
	s_nop 0
	v_mov_b32_dpp v159, v157 quad_perm:[2,3,0,1] row_mask:0xf bank_mask:0xf
	v_xor_b32_e32 v103, 16, v99
	v_xor_b32_e32 v109, 16, v105
	v_xor_b32_e32 v99, 32, v99
	s_waitcnt lgkmcnt(0)
	v_pk_add_f32 v[156:157], v[156:157], v[158:159]
	s_nop 1
	v_mov_b32_dpp v158, v156 row_half_mirror row_mask:0xf bank_mask:0xf
	s_nop 1
	v_mov_b32_dpp v158, v158 quad_perm:[3,2,1,0] row_mask:0xf bank_mask:0xf
	v_mov_b32_dpp v159, v157 row_half_mirror row_mask:0xf bank_mask:0xf
	s_nop 1
	v_mov_b32_dpp v159, v159 quad_perm:[3,2,1,0] row_mask:0xf bank_mask:0xf
	s_waitcnt lgkmcnt(0)
	v_pk_add_f32 v[156:157], v[156:157], v[158:159]
	s_nop 1
	v_mov_b32_dpp v158, v156 row_ror:8 row_mask:0xf bank_mask:0xf
	v_xor_b32_e32 v99, 32, v105
	v_mov_b32_dpp v159, v157 row_ror:8 row_mask:0xf bank_mask:0xf
	s_and_saveexec_b64 s[2:3], vcc
	s_cbranch_execz .LBB0_1334
	s_waitcnt lgkmcnt(0)
	v_pk_add_f32 v[156:157], v[156:157], v[158:159]
	global_store_dwordx2 v[154:155], v[156:157], off offset:64
; DEVFI int lane_opaque() { unsigned m = ~0u; asm volatile("" : "+s"(m)); return (int)__builtin_amdgcn_mbcnt_hi(m, __builtin_amdgcn_mbcnt_lo(m, 0u)); }
; DEVFI float shx(float v, int mask, int lane) { return __int_as_float(__builtin_amdgcn_ds_bpermute((lane ^ mask) << 2, __float_as_int(v))); }
; #define SVSTAT ((float*)(kargs()->ws + O_SVSTAT))
; DEVFI float red16(float v) {
;   const int ln = lane_opaque();
;   v += shx(v, 1, ln); v += shx(v, 2, ln); v += shx(v, 4, ln); v += shx(v, 8, ln); return v;
; }
; __global__ void __launch_bounds__(512) mega(Params p) {
;     ...
;                     if (c0 >= 5120) { float* stp = SVSTAT + (long)r0 * 16 + ((c0 - 5120) >> 7) * 2;
; #pragma unroll
;                       for (int j = 0; j < 4; ++j) { float s1 = 0, s2 = 0;
; #pragma unroll
;                         for (int n = 0; n < 8; ++n) { s1 += a[n][j]; s2 += a[n][j] * a[n][j]; }
;                         s1 = red16(s1); s2 = red16(s2);
;                         if (fr == 0) { stp[j * 16] = s1; stp[j * 16 + 1] = s2; } } }
.LBB0_1334:
	s_or_b64 exec, exec, s[2:3]
	v_mov_b32_e32 v156, v177
	v_mov_b32_e32 v157, v101
	v_pk_add_f32 v[156:157], v[100:101], v[156:157]
	s_waitcnt lgkmcnt(0)
	v_pk_mul_f32 v[158:159], v[100:101], v[100:101]
	v_mul_f32_e32 v105, v104, v104
	v_mov_b32_e32 v157, v159
	v_pk_mov_b32 v[158:159], v[100:101], v[158:159] op_sel:[1,0]
	s_mov_b32 s2, -1
	v_pk_add_f32 v[156:157], v[156:157], v[158:159]
	v_mul_f32_e32 v113, v112, v112
	v_pk_add_f32 v[156:157], v[156:157], v[104:105]
	v_mbcnt_lo_u32_b32 v99, s2, 0
	v_mul_f32_e32 v119, v118, v118
	v_mbcnt_hi_u32_b32 v99, s2, v99
	s_mov_b32 s2, -1
	v_pk_add_f32 v[156:157], v[156:157], v[112:113]
	v_mul_f32_e32 v127, v126, v126
	v_pk_add_f32 v[156:157], v[156:157], v[118:119]
	v_mbcnt_lo_u32_b32 v109, s2, 0
	v_mul_f32_e32 v135, v134, v134
	v_mbcnt_hi_u32_b32 v109, s2, v109
	v_pk_add_f32 v[156:157], v[156:157], v[126:127]
	v_mul_f32_e32 v143, v142, v142
	v_lshlrev_b32_e32 v99, 2, v99
	v_lshlrev_b32_e32 v109, 2, v109
	v_pk_add_f32 v[156:157], v[156:157], v[134:135]
	v_xor_b32_e32 v103, 4, v99
	v_xor_b32_e32 v115, 4, v109
	v_pk_add_f32 v[156:157], v[156:157], v[142:143]
	s_nop 1
	v_mov_b32_dpp v158, v156 quad_perm:[1,0,3,2] row_mask:0xf bank_mask:0xf
	s_nop 0
	v_mov_b32_dpp v159, v157 quad_perm:[1,0,3,2] row_mask:0xf bank_mask:0xf
	v_xor_b32_e32 v103, 8, v99
	v_xor_b32_e32 v105, 8, v109
	s_waitcnt lgkmcnt(0)
	v_pk_add_f32 v[156:157], v[156:157], v[158:159]
	s_nop 1
	v_mov_b32_dpp v158, v156 quad_perm:[2,3,0,1] row_mask:0xf bank_mask:0xf
	s_nop 0
	v_mov_b32_dpp v159, v157 quad_perm:[2,3,0,1] row_mask:0xf bank_mask:0xf
	v_xor_b32_e32 v103, 16, v99
	v_xor_b32_e32 v105, 16, v109
	v_xor_b32_e32 v99, 32, v99
	s_waitcnt lgkmcnt(0)
	v_pk_add_f32 v[156:157], v[156:157], v[158:159]
	s_nop 1
	v_mov_b32_dpp v158, v156 row_half_mirror row_mask:0xf bank_mask:0xf
	s_nop 1
	v_mov_b32_dpp v158, v158 quad_perm:[3,2,1,0] row_mask:0xf bank_mask:0xf
	v_mov_b32_dpp v159, v157 row_half_mirror row_mask:0xf bank_mask:0xf
	s_nop 1
	v_mov_b32_dpp v159, v159 quad_perm:[3,2,1,0] row_mask:0xf bank_mask:0xf
	s_waitcnt lgkmcnt(0)
	v_pk_add_f32 v[156:157], v[156:157], v[158:159]
	s_nop 1
	v_mov_b32_dpp v158, v156 row_ror:8 row_mask:0xf bank_mask:0xf
	v_xor_b32_e32 v99, 32, v109
	v_mov_b32_dpp v159, v157 row_ror:8 row_mask:0xf bank_mask:0xf
	s_and_saveexec_b64 s[2:3], vcc
	s_cbranch_execz .LBB0_1336
	s_waitcnt lgkmcnt(0)
	v_pk_add_f32 v[156:157], v[156:157], v[158:159]
	global_store_dwordx2 v[154:155], v[156:157], off offset:128
.LBB0_1336:
	s_or_b64 exec, exec, s[2:3]
	v_mov_b32_e32 v156, v177
	v_mov_b32_e32 v157, v97
	v_pk_add_f32 v[156:157], v[96:97], v[156:157]
	s_waitcnt lgkmcnt(0)
	v_pk_mul_f32 v[158:159], v[96:97], v[96:97]
	v_mul_f32_e32 v99, v98, v98
	v_mov_b32_e32 v157, v159
	v_pk_mov_b32 v[158:159], v[96:97], v[158:159] op_sel:[1,0]
	s_mov_b32 s2, -1
	v_pk_add_f32 v[156:157], v[156:157], v[158:159]
	v_mul_f32_e32 v103, v102, v102
	v_pk_add_f32 v[156:157], v[156:157], v[98:99]
	v_mbcnt_lo_u32_b32 v105, s2, 0
	v_mul_f32_e32 v109, v108, v108
	v_mbcnt_hi_u32_b32 v105, s2, v105
	s_mov_b32 s2, -1
	v_pk_add_f32 v[156:157], v[156:157], v[102:103]
	v_mul_f32_e32 v117, v116, v116
	v_pk_add_f32 v[156:157], v[156:157], v[108:109]
	v_mbcnt_lo_u32_b32 v115, s2, 0
	v_mul_f32_e32 v121, v120, v120
	v_mbcnt_hi_u32_b32 v115, s2, v115
	v_pk_add_f32 v[156:157], v[156:157], v[116:117]
	v_mul_f32_e32 v133, v132, v132
	v_lshlrev_b32_e32 v105, 2, v105
	v_lshlrev_b32_e32 v115, 2, v115
	v_pk_add_f32 v[156:157], v[156:157], v[120:121]
	v_xor_b32_e32 v113, 4, v105
	v_xor_b32_e32 v119, 4, v115
	v_pk_add_f32 v[156:157], v[156:157], v[132:133]
	s_nop 1
	v_mov_b32_dpp v158, v156 quad_perm:[1,0,3,2] row_mask:0xf bank_mask:0xf
	s_nop 0
	v_mov_b32_dpp v159, v157 quad_perm:[1,0,3,2] row_mask:0xf bank_mask:0xf
	v_xor_b32_e32 v99, 8, v105
	v_xor_b32_e32 v103, 8, v115
	s_waitcnt lgkmcnt(0)
	v_pk_add_f32 v[156:157], v[156:157], v[158:159]
	s_nop 1
	v_mov_b32_dpp v158, v156 quad_perm:[2,3,0,1] row_mask:0xf bank_mask:0xf
	s_nop 0
	v_mov_b32_dpp v159, v157 quad_perm:[2,3,0,1] row_mask:0xf bank_mask:0xf
	v_xor_b32_e32 v99, 16, v105
	v_xor_b32_e32 v103, 16, v115
	s_waitcnt lgkmcnt(0)
	v_pk_add_f32 v[156:157], v[156:157], v[158:159]
	s_nop 1
	v_mov_b32_dpp v158, v156 row_half_mirror row_mask:0xf bank_mask:0xf
	s_nop 1
	v_mov_b32_dpp v158, v158 quad_perm:[3,2,1,0] row_mask:0xf bank_mask:0xf
	v_mov_b32_dpp v159, v157 row_half_mirror row_mask:0xf bank_mask:0xf
	s_nop 1
	v_mov_b32_dpp v159, v159 quad_perm:[3,2,1,0] row_mask:0xf bank_mask:0xf
	v_xor_b32_e32 v99, 32, v105
	s_waitcnt lgkmcnt(0)
	v_pk_add_f32 v[156:157], v[156:157], v[158:159]
	s_nop 1
	v_mov_b32_dpp v158, v156 row_ror:8 row_mask:0xf bank_mask:0xf
	v_xor_b32_e32 v99, 32, v115
	v_mov_b32_dpp v159, v157 row_ror:8 row_mask:0xf bank_mask:0xf
	s_and_saveexec_b64 s[2:3], vcc
	s_cbranch_execz .LBB0_1338
	s_waitcnt lgkmcnt(0)
	v_pk_add_f32 v[156:157], v[156:157], v[158:159]
	global_store_dwordx2 v[154:155], v[156:157], off offset:192

; DEVFI int lane_opaque() { unsigned m = ~0u; asm volatile("" : "+s"(m)); return (int)__builtin_amdgcn_mbcnt_hi(m, __builtin_amdgcn_mbcnt_lo(m, 0u)); }
; DEVFI float shx(float v, int mask, int lane) { return __int_as_float(__builtin_amdgcn_ds_bpermute((lane ^ mask) << 2, __float_as_int(v))); }
; #define ATTT ((float2*)(kargs()->ws + O_ATTT))
; DEVFI float red16(float v) {
;   const int ln = lane_opaque();
;   v += shx(v, 1, ln); v += shx(v, 2, ln); v += shx(v, 4, ln); v += shx(v, 8, ln); return v;
; }
; __global__ void __launch_bounds__(512) mega(Params p) {
;     ...
;                     const bool isk = c0 >= 7168; const float* nw = isk ? kn_w : qn_w; const float2* attt = ATTT;
; #pragma unroll
;                     for (int j = 0; j < 4; ++j) { const int pos = (r0 + j) & (seqlen - 1);
;                       float ss = 0;
; #pragma unroll
;                       for (int n = 0; n < 8; ++n) ss += a[n][j] * a[n][j];
;                       ss = red16(ss);
;                       const float rstd = 1.f / sqrtf(ss * (1.f / 128.f) + RMS_EPS);
; #pragma unroll
;                       for (int n = 0; n < 8; ++n) a[n][j] = a[n][j] * rstd * hv[n];
;                       const float4* tb = (const float4*)(attt + pos * 64 + fr * 4);
;                       const float4 t01 = tb[0], t23 = tb[1];
;                       const float2 csv[4] = {make_float2(t01.x, t01.y), make_float2(t01.z, t01.w), make_float2(t23.x, t23.y), make_float2(t23.z, t23.w)};
; #pragma unroll
;                       for (int hh = 0; hh < 2; ++hh)
; #pragma unroll
;                         for (int n = 0; n < 2; ++n) { const float2 cs = csv[hh * 2 + n];
;                           const float x1 = a[hh * 4 + n][j], x2 = a[hh * 4 + n + 2][j];
;                           a[hh * 4 + n][j] = x1 * cs.x - x2 * cs.y; a[hh * 4 + n + 2][j] = x1 * cs.y + x2 * cs.x; } }
.LBB0_1627:
	s_mov_b64 s[2:3], s[0:1]
	s_load_dwordx2 s[2:3], s[2:3], 0xe8
	v_mul_f32_e32 v64, v56, v56
	v_fmac_f32_e32 v64, v60, v60
	v_fmac_f32_e32 v64, v44, v44
	v_fmac_f32_e32 v64, v40, v40
	s_waitcnt lgkmcnt(0)
	s_add_u32 s36, s2, 0x3da0000
	s_mov_b32 s2, -1
	v_fmac_f32_e32 v64, v52, v52
	v_fmac_f32_e32 v64, v48, v48
	v_mbcnt_lo_u32_b32 v65, s2, 0
	v_mbcnt_hi_u32_b32 v65, s2, v65
	v_fmac_f32_e32 v64, v36, v36
	v_lshlrev_b32_e32 v65, 2, v65
	v_fmac_f32_e32 v64, v32, v32
	v_xor_b32_e32 v66, 4, v65
	s_nop 1
	v_mov_b32_dpp v66, v64 quad_perm:[1,0,3,2] row_mask:0xf bank_mask:0xf
	v_mov_b32_e32 v99, 0x358637bd
	s_addc_u32 s37, s3, 0
	v_mov_b32_e32 v161, v177
	s_waitcnt lgkmcnt(0)
	v_add_f32_e32 v64, v64, v66
	v_xor_b32_e32 v66, 8, v65
	s_nop 1
	v_mov_b32_dpp v66, v64 quad_perm:[2,3,0,1] row_mask:0xf bank_mask:0xf
	s_waitcnt lgkmcnt(0)
	v_add_f32_e32 v64, v64, v66
	v_xor_b32_e32 v66, 16, v65
	s_nop 1
	v_mov_b32_dpp v66, v64 row_half_mirror row_mask:0xf bank_mask:0xf
	s_nop 1
	v_mov_b32_dpp v66, v66 quad_perm:[3,2,1,0] row_mask:0xf bank_mask:0xf
	v_xor_b32_e32 v65, 32, v65
	s_waitcnt lgkmcnt(0)
	v_add_f32_e32 v64, v64, v66
	s_nop 1
	v_mov_b32_dpp v65, v64 row_ror:8 row_mask:0xf bank_mask:0xf
	s_waitcnt lgkmcnt(0)
	v_add_f32_e32 v64, v64, v65
	v_fmamk_f32 v64, v64, 0x3c000000, v99
	v_cmp_gt_f32_e32 vcc, s30, v64
	v_mul_f32_e32 v65, 0x4f800000, v64
	s_nop 0
	v_cndmask_b32_e32 v64, v64, v65, vcc
	v_sqrt_f32_e32 v65, v64
	s_nop 0
	v_add_u32_e32 v66, -1, v65
	v_fma_f32 v67, -v66, v65, v64
	v_cmp_ge_f32_e64 s[6:7], 0, v67
	v_add_u32_e32 v67, 1, v65
	s_nop 0
	v_cndmask_b32_e64 v66, v65, v66, s[6:7]
	v_fma_f32 v65, -v67, v65, v64
	v_cmp_lt_f32_e64 s[6:7], 0, v65
	s_nop 1
	v_cndmask_b32_e64 v65, v66, v67, s[6:7]
	v_mul_f32_e32 v66, 0x37800000, v65
	v_cndmask_b32_e32 v65, v65, v66, vcc
	v_cmp_class_f32_e32 vcc, v64, v222
	s_nop 1
	v_cndmask_b32_e32 v64, v65, v64, vcc
	s_mov_b32 s2, -1
	v_rcp_f32_e32 v66, v64
	s_nop 0
	v_fma_f32 v65, -v64, v66, 1.0
	v_fma_f32 v65, v65, v66, v66
	v_div_fixup_f32 v64, v65, v64, 1.0
	v_mul_f32_e32 v65, v60, v64
	s_waitcnt vmcnt(0)
	v_mul_f32_e32 v73, v224, v65
	v_mul_f32_e32 v65, v56, v64
	v_mul_f32_e32 v76, v223, v65
	v_mul_f32_e32 v65, v44, v64
	v_mul_f32_e32 v72, v212, v65
	v_mul_f32_e32 v65, v40, v64
	v_mul_f32_e32 v77, v211, v65
	v_mul_f32_e32 v65, v52, v64
	v_mul_f32_e32 v78, v210, v65
	v_mul_f32_e32 v65, v48, v64
	v_mul_f32_e32 v79, v209, v65
	v_mul_f32_e32 v65, v36, v64
	v_mul_f32_e32 v64, v32, v64
	v_mul_f32_e32 v81, v207, v64
	v_and_b32_e32 v64, s14, v96
	v_mul_f32_e32 v80, v208, v65
	v_lshlrev_b32_e32 v64, 6, v64
	v_mov_b32_e32 v65, v177
	v_lshl_add_u64 v[64:65], v[64:65], 3, s[36:37]
	v_lshl_add_u64 v[68:69], v[64:65], 0, v[160:161]
	global_load_dwordx4 v[64:67], v[68:69], off offset:16
	s_nop 0
	global_load_dwordx4 v[68:71], v[68:69], off
	s_waitcnt vmcnt(0)
	v_mul_f32_e32 v74, v69, v72
	v_fma_f32 v74, v68, v73, -v74
	v_mul_f32_e32 v72, v68, v72
	v_mul_f32_e32 v68, v71, v77
	v_fma_f32 v75, v70, v76, -v68
	v_mul_f32_e32 v68, v65, v80
	v_fmac_f32_e32 v72, v69, v73
	v_mul_f32_e32 v73, v70, v77
	v_fma_f32 v70, v64, v78, -v68
	v_mul_f32_e32 v68, v64, v80
	v_mul_f32_e32 v64, v67, v81
	v_fmac_f32_e32 v73, v71, v76
	v_fma_f32 v71, v66, v79, -v64
	v_mul_f32_e32 v64, v57, v57
	v_fmac_f32_e32 v64, v61, v61
	v_fmac_f32_e32 v64, v45, v45
	v_fmac_f32_e32 v64, v41, v41
	v_mul_f32_e32 v69, v66, v81
	v_fmac_f32_e32 v64, v53, v53
	v_mbcnt_lo_u32_b32 v66, s2, 0
	v_fmac_f32_e32 v64, v49, v49
	v_mbcnt_hi_u32_b32 v66, s2, v66
	v_fmac_f32_e32 v64, v37, v37
	v_lshlrev_b32_e32 v66, 2, v66
	v_fmac_f32_e32 v69, v67, v79
	v_fmac_f32_e32 v64, v33, v33
	v_xor_b32_e32 v67, 4, v66
	s_nop 1
	v_mov_b32_dpp v67, v64 quad_perm:[1,0,3,2] row_mask:0xf bank_mask:0xf
	v_fmac_f32_e32 v68, v65, v78
	v_add_u32_e32 v65, 1, v96
	s_waitcnt lgkmcnt(0)
	v_add_f32_e32 v64, v64, v67
	v_xor_b32_e32 v67, 8, v66
	s_nop 1
	v_mov_b32_dpp v67, v64 quad_perm:[2,3,0,1] row_mask:0xf bank_mask:0xf
	s_waitcnt lgkmcnt(0)
	v_add_f32_e32 v64, v64, v67
	v_xor_b32_e32 v67, 16, v66
	s_nop 1
	v_mov_b32_dpp v67, v64 row_half_mirror row_mask:0xf bank_mask:0xf
	s_nop 1
	v_mov_b32_dpp v67, v67 quad_perm:[3,2,1,0] row_mask:0xf bank_mask:0xf
	v_xor_b32_e32 v66, 32, v66
	s_waitcnt lgkmcnt(0)
	v_add_f32_e32 v64, v64, v67
	s_nop 1
	v_mov_b32_dpp v66, v64 row_ror:8 row_mask:0xf bank_mask:0xf
	s_waitcnt lgkmcnt(0)
	v_add_f32_e32 v64, v64, v66
	v_fmamk_f32 v64, v64, 0x3c000000, v99
	v_cmp_gt_f32_e32 vcc, s30, v64
	v_mul_f32_e32 v66, 0x4f800000, v64
	s_nop 0
	v_cndmask_b32_e32 v64, v64, v66, vcc
	v_sqrt_f32_e32 v66, v64
	s_nop 0
	v_add_u32_e32 v67, -1, v66
	v_fma_f32 v76, -v67, v66, v64
	v_cmp_ge_f32_e64 s[6:7], 0, v76
	v_add_u32_e32 v76, 1, v66
	s_nop 0
	v_cndmask_b32_e64 v67, v66, v67, s[6:7]
	v_fma_f32 v66, -v76, v66, v64
	v_cmp_lt_f32_e64 s[6:7], 0, v66
	s_nop 1
	v_cndmask_b32_e64 v66, v67, v76, s[6:7]
	v_mul_f32_e32 v67, 0x37800000, v66
	v_cndmask_b32_e32 v66, v66, v67, vcc
	v_cmp_class_f32_e32 vcc, v64, v222
	s_nop 1
	v_cndmask_b32_e32 v64, v66, v64, vcc
	s_mov_b32 s2, -1
	v_rcp_f32_e32 v67, v64
	s_nop 0
	v_fma_f32 v66, -v64, v67, 1.0
	v_fma_f32 v66, v66, v67, v67
	v_div_fixup_f32 v64, v66, v64, 1.0
	v_mul_f32_e32 v66, v61, v64
	v_mul_f32_e32 v81, v224, v66
	v_mul_f32_e32 v66, v57, v64
	v_mul_f32_e32 v84, v223, v66
	v_mul_f32_e32 v66, v45, v64
	v_mul_f32_e32 v80, v212, v66
	v_mul_f32_e32 v66, v41, v64
	v_mul_f32_e32 v85, v211, v66
	v_mul_f32_e32 v66, v53, v64
	v_mul_f32_e32 v86, v210, v66
	v_mul_f32_e32 v66, v49, v64
	v_mul_f32_e32 v87, v209, v66
	v_mul_f32_e32 v66, v37, v64
	v_mul_f32_e32 v64, v33, v64
	v_mul_f32_e32 v89, v207, v64
	v_and_b32_e32 v64, s14, v65
	v_lshlrev_b32_e32 v64, 6, v64
	v_mov_b32_e32 v65, v177
	v_lshl_add_u64 v[64:65], v[64:65], 3, s[36:37]
	v_lshl_add_u64 v[76:77], v[64:65], 0, v[160:161]
	v_mul_f32_e32 v88, v208, v66
	global_load_dwordx4 v[64:67], v[76:77], off offset:16
	s_nop 0
	global_load_dwordx4 v[76:79], v[76:77], off
	s_waitcnt vmcnt(0)
; DEVFI int lane_opaque() { unsigned m = ~0u; asm volatile("" : "+s"(m)); return (int)__builtin_amdgcn_mbcnt_hi(m, __builtin_amdgcn_mbcnt_lo(m, 0u)); }
; DEVFI float shx(float v, int mask, int lane) { return __int_as_float(__builtin_amdgcn_ds_bpermute((lane ^ mask) << 2, __float_as_int(v))); }
; #define AQ ((bfraw*)(kargs()->ws + O_AQ))
; #define AK ((bfraw*)(kargs()->ws + O_AK))
; DEVFI float red16(float v) {
;   const int ln = lane_opaque();
;   v += shx(v, 1, ln); v += shx(v, 2, ln); v += shx(v, 4, ln); v += shx(v, 8, ln); return v;
; }
; __global__ void __launch_bounds__(512) mega(Params p) {
;     ...
;                     for (int j = 0; j < 4; ++j) { const int pos = (r0 + j) & (seqlen - 1);
;                       float ss = 0;
; #pragma unroll
;                       for (int n = 0; n < 8; ++n) ss += a[n][j] * a[n][j];
;                       ss = red16(ss);
;                       const float rstd = 1.f / sqrtf(ss * (1.f / 128.f) + RMS_EPS);
; #pragma unroll
;                       for (int n = 0; n < 8; ++n) a[n][j] = a[n][j] * rstd * hv[n];
;                       const float4* tb = (const float4*)(attt + pos * 64 + fr * 4);
;                       const float4 t01 = tb[0], t23 = tb[1];
;                       const float2 csv[4] = {make_float2(t01.x, t01.y), make_float2(t01.z, t01.w), make_float2(t23.x, t23.y), make_float2(t23.z, t23.w)};
; #pragma unroll
;                       for (int hh = 0; hh < 2; ++hh)
; #pragma unroll
;                         for (int n = 0; n < 2; ++n) { const float2 cs = csv[hh * 2 + n];
;                           const float x1 = a[hh * 4 + n][j], x2 = a[hh * 4 + n + 2][j];
;                           a[hh * 4 + n][j] = x1 * cs.x - x2 * cs.y; a[hh * 4 + n + 2][j] = x1 * cs.y + x2 * cs.x; } }
;                     if (isk) store_nat_m(AK + (long)r0 * 256 + (c0 - 7168), 256, a, fr);
;                     else store_nat_m(AQ + (long)r0 * 1024 + (c0 - 6144), 1024, a, fr);
	v_mul_f32_e32 v82, v77, v80
	v_fma_f32 v82, v76, v81, -v82
	v_mul_f32_e32 v80, v76, v80
	v_mul_f32_e32 v76, v79, v85
	v_fma_f32 v83, v78, v84, -v76
	v_mul_f32_e32 v76, v65, v88
	v_fmac_f32_e32 v80, v77, v81
	v_mul_f32_e32 v81, v78, v85
	v_fma_f32 v78, v64, v86, -v76
	v_mul_f32_e32 v76, v64, v88
	v_mul_f32_e32 v64, v67, v89
	v_fmac_f32_e32 v81, v79, v84
	v_fma_f32 v79, v66, v87, -v64
	v_mul_f32_e32 v64, v58, v58
	v_fmac_f32_e32 v64, v62, v62
	v_fmac_f32_e32 v64, v46, v46
	v_fmac_f32_e32 v64, v42, v42
	v_mul_f32_e32 v77, v66, v89
	v_fmac_f32_e32 v64, v54, v54
	v_mbcnt_lo_u32_b32 v66, s2, 0
	v_fmac_f32_e32 v64, v50, v50
	v_mbcnt_hi_u32_b32 v66, s2, v66
	v_fmac_f32_e32 v64, v38, v38
	v_lshlrev_b32_e32 v66, 2, v66
	v_fmac_f32_e32 v77, v67, v87
	v_fmac_f32_e32 v64, v34, v34
	v_xor_b32_e32 v67, 4, v66
	s_nop 1
	v_mov_b32_dpp v67, v64 quad_perm:[1,0,3,2] row_mask:0xf bank_mask:0xf
	v_fmac_f32_e32 v76, v65, v86
	v_add_u32_e32 v65, 2, v96
	s_waitcnt lgkmcnt(0)
	v_add_f32_e32 v64, v64, v67
	v_xor_b32_e32 v67, 8, v66
	s_nop 1
	v_mov_b32_dpp v67, v64 quad_perm:[2,3,0,1] row_mask:0xf bank_mask:0xf
	s_waitcnt lgkmcnt(0)
	v_add_f32_e32 v64, v64, v67
	v_xor_b32_e32 v67, 16, v66
	s_nop 1
	v_mov_b32_dpp v67, v64 row_half_mirror row_mask:0xf bank_mask:0xf
	s_nop 1
	v_mov_b32_dpp v67, v67 quad_perm:[3,2,1,0] row_mask:0xf bank_mask:0xf
	v_xor_b32_e32 v66, 32, v66
	s_waitcnt lgkmcnt(0)
	v_add_f32_e32 v64, v64, v67
	s_nop 1
	v_mov_b32_dpp v66, v64 row_ror:8 row_mask:0xf bank_mask:0xf
	s_waitcnt lgkmcnt(0)
	v_add_f32_e32 v64, v64, v66
	v_fmamk_f32 v64, v64, 0x3c000000, v99
	v_cmp_gt_f32_e32 vcc, s30, v64
	v_mul_f32_e32 v66, 0x4f800000, v64
	s_nop 0
	v_cndmask_b32_e32 v64, v64, v66, vcc
	v_sqrt_f32_e32 v66, v64
	s_nop 0
	v_add_u32_e32 v67, -1, v66
	v_fma_f32 v84, -v67, v66, v64
	v_cmp_ge_f32_e64 s[6:7], 0, v84
	v_add_u32_e32 v84, 1, v66
	s_nop 0
	v_cndmask_b32_e64 v67, v66, v67, s[6:7]
	v_fma_f32 v66, -v84, v66, v64
	v_cmp_lt_f32_e64 s[6:7], 0, v66
	s_nop 1
	v_cndmask_b32_e64 v66, v67, v84, s[6:7]
	v_mul_f32_e32 v67, 0x37800000, v66
	v_cndmask_b32_e32 v66, v66, v67, vcc
	v_cmp_class_f32_e32 vcc, v64, v222
	s_nop 1
	v_cndmask_b32_e32 v64, v66, v64, vcc
	s_mov_b32 s2, -1
	v_rcp_f32_e32 v67, v64
	s_nop 0
	v_fma_f32 v66, -v64, v67, 1.0
	v_fma_f32 v66, v66, v67, v67
	v_div_fixup_f32 v64, v66, v64, 1.0
	v_mul_f32_e32 v66, v62, v64
	v_mul_f32_e32 v89, v224, v66
	v_mul_f32_e32 v66, v58, v64
	v_mul_f32_e32 v92, v223, v66
	v_mul_f32_e32 v66, v46, v64
	v_mul_f32_e32 v88, v212, v66
	v_mul_f32_e32 v66, v42, v64
	v_mul_f32_e32 v93, v211, v66
	v_mul_f32_e32 v66, v54, v64
	v_mul_f32_e32 v94, v210, v66
	v_mul_f32_e32 v66, v50, v64
	v_mul_f32_e32 v95, v209, v66
	v_mul_f32_e32 v66, v38, v64
	v_mul_f32_e32 v64, v34, v64
	v_mul_f32_e32 v98, v207, v64
	v_and_b32_e32 v64, s14, v65
	v_lshlrev_b32_e32 v64, 6, v64
	v_mov_b32_e32 v65, v177
	v_lshl_add_u64 v[64:65], v[64:65], 3, s[36:37]
	v_lshl_add_u64 v[84:85], v[64:65], 0, v[160:161]
	v_mul_f32_e32 v97, v208, v66
	global_load_dwordx4 v[64:67], v[84:85], off offset:16
	s_nop 0
	global_load_dwordx4 v[84:87], v[84:85], off
	s_waitcnt vmcnt(0)
	v_mul_f32_e32 v90, v85, v88
	v_fma_f32 v90, v84, v89, -v90
	v_mul_f32_e32 v88, v84, v88
	v_mul_f32_e32 v84, v87, v93
	v_fma_f32 v91, v86, v92, -v84
	v_mul_f32_e32 v84, v65, v97
	v_fmac_f32_e32 v88, v85, v89
	v_mul_f32_e32 v89, v86, v93
	v_fma_f32 v86, v64, v94, -v84
	v_mul_f32_e32 v84, v64, v97
	v_mul_f32_e32 v64, v67, v98
	v_fmac_f32_e32 v89, v87, v92
	v_fma_f32 v87, v66, v95, -v64
	v_mul_f32_e32 v64, v59, v59
	v_fmac_f32_e32 v64, v63, v63
	v_fmac_f32_e32 v64, v47, v47
	v_fmac_f32_e32 v64, v43, v43
	v_mul_f32_e32 v85, v66, v98
	v_fmac_f32_e32 v64, v55, v55
	v_mbcnt_lo_u32_b32 v66, s2, 0
	v_fmac_f32_e32 v64, v51, v51
	v_mbcnt_hi_u32_b32 v66, s2, v66
	v_fmac_f32_e32 v64, v39, v39
	v_lshlrev_b32_e32 v66, 2, v66
	v_fmac_f32_e32 v85, v67, v95
	v_fmac_f32_e32 v64, v35, v35
	v_xor_b32_e32 v67, 4, v66
	s_nop 1
	v_mov_b32_dpp v67, v64 quad_perm:[1,0,3,2] row_mask:0xf bank_mask:0xf
	v_fmac_f32_e32 v84, v65, v94
	v_add_u32_e32 v65, 3, v96
	s_waitcnt lgkmcnt(0)
	v_add_f32_e32 v64, v64, v67
	v_xor_b32_e32 v67, 8, v66
	s_nop 1
	v_mov_b32_dpp v67, v64 quad_perm:[2,3,0,1] row_mask:0xf bank_mask:0xf
	s_waitcnt lgkmcnt(0)
	v_add_f32_e32 v64, v64, v67
	v_xor_b32_e32 v67, 16, v66
	s_nop 1
	v_mov_b32_dpp v67, v64 row_half_mirror row_mask:0xf bank_mask:0xf
	s_nop 1
	v_mov_b32_dpp v67, v67 quad_perm:[3,2,1,0] row_mask:0xf bank_mask:0xf
	v_xor_b32_e32 v66, 32, v66
	s_waitcnt lgkmcnt(0)
	v_add_f32_e32 v64, v64, v67
	s_nop 1
	v_mov_b32_dpp v66, v64 row_ror:8 row_mask:0xf bank_mask:0xf
	s_waitcnt lgkmcnt(0)
	v_add_f32_e32 v64, v64, v66
	v_fmamk_f32 v64, v64, 0x3c000000, v99
	v_cmp_gt_f32_e32 vcc, s30, v64
	v_mul_f32_e32 v66, 0x4f800000, v64
	s_nop 0
	v_cndmask_b32_e32 v64, v64, v66, vcc
	v_sqrt_f32_e32 v66, v64
	s_nop 0
	v_add_u32_e32 v67, -1, v66
	v_fma_f32 v92, -v67, v66, v64
	v_cmp_ge_f32_e64 s[6:7], 0, v92
	v_add_u32_e32 v92, 1, v66
	s_nop 0
	v_cndmask_b32_e64 v67, v66, v67, s[6:7]
	v_fma_f32 v66, -v92, v66, v64
	v_cmp_lt_f32_e64 s[6:7], 0, v66
	s_nop 1
	v_cndmask_b32_e64 v66, v67, v92, s[6:7]
	v_mul_f32_e32 v67, 0x37800000, v66
	v_cndmask_b32_e32 v66, v66, v67, vcc
	v_cmp_class_f32_e32 vcc, v64, v222
	s_nop 1
	v_cndmask_b32_e32 v64, v66, v64, vcc
	s_mov_b64 s[2:3], -1
	v_rcp_f32_e32 v67, v64
	s_nop 0
	v_fma_f32 v66, -v64, v67, 1.0
	v_fma_f32 v66, v66, v67, v67
	v_div_fixup_f32 v64, v66, v64, 1.0
	v_mul_f32_e32 v66, v63, v64
	v_mul_f32_e32 v94, v224, v66
	v_mul_f32_e32 v66, v59, v64
	v_mul_f32_e32 v97, v223, v66
	v_mul_f32_e32 v66, v47, v64
	v_mul_f32_e32 v95, v212, v66
	v_mul_f32_e32 v66, v43, v64
	v_mul_f32_e32 v98, v211, v66
	v_mul_f32_e32 v66, v55, v64
	v_mul_f32_e32 v104, v210, v66
	v_mul_f32_e32 v66, v51, v64
	v_mul_f32_e32 v105, v209, v66
	v_mul_f32_e32 v66, v39, v64
	v_mul_f32_e32 v64, v35, v64
	v_mul_f32_e32 v107, v207, v64
	v_and_b32_e32 v64, s14, v65
	v_lshlrev_b32_e32 v64, 6, v64
	v_mov_b32_e32 v65, v177
	v_lshl_add_u64 v[64:65], v[64:65], 3, s[36:37]
	v_lshl_add_u64 v[92:93], v[64:65], 0, v[160:161]
	v_mul_f32_e32 v106, v208, v66
	global_load_dwordx4 v[64:67], v[92:93], off offset:16
	global_load_dwordx4 v[100:103], v[92:93], off
	s_waitcnt vmcnt(0)
	v_mul_f32_e32 v92, v101, v95
	v_fma_f32 v99, v100, v94, -v92
	v_mul_f32_e32 v92, v103, v98
	v_mul_f32_e32 v95, v100, v95
	v_fma_f32 v100, v102, v97, -v92
	v_mul_f32_e32 v92, v65, v106
	v_fma_f32 v93, v64, v104, -v92
	v_mul_f32_e32 v92, v64, v106
	v_mul_f32_e32 v64, v67, v107
	v_fmac_f32_e32 v95, v101, v94
	v_fma_f32 v94, v66, v105, -v64
	v_and_b32_e32 v64, 1, v203
	v_mul_f32_e32 v98, v102, v98
	v_mul_f32_e32 v66, v66, v107
	v_cmp_eq_u32_e32 vcc, 0, v64
	v_cmp_eq_u32_e64 s[6:7], 1, v64
	v_add_u32_e32 v64, 15, v202
	v_fmac_f32_e32 v98, v103, v97
	v_fmac_f32_e32 v92, v65, v104
	v_fmac_f32_e32 v66, v67, v105
	v_ashrrev_i32_e32 v97, 31, v96
	v_cndmask_b32_e32 v67, v64, v202, vcc
	v_cndmask_b32_e32 v101, v74, v75, vcc
	s_and_b64 vcc, exec, s[8:9]
	s_cbranch_vccz .LBB0_1693
; DEVFI float dpp_xor1(float x) { return __int_as_float(__builtin_amdgcn_update_dpp(0, __float_as_int(x), 0xB1, 0xF, 0xF, true)); }
; #define AQ ((bfraw*)(kargs()->ws + O_AQ))
; #define AK ((bfraw*)(kargs()->ws + O_AK))
; DEVFI void store_nat_m(bfraw* base, long ld, f32x4 (&a)[8], int fr) {
;   const bool odd = fr & 1;
;   bfraw* p0 = base + (odd ? 15 + fr : fr);
; #pragma unroll
;   for (int j = 0; j < 4; ++j)
; #pragma unroll
;     for (int n0 = 0; n0 < 8; n0 += 2) { const float own0 = a[n0][j], own1 = a[n0 + 1][j];
;       const float recv = dpp_xor1(odd ? own0 : own1);
;       const unsigned pk = odd ? cvtpk(recv, own1) : cvtpk(own0, recv);
;       *reinterpret_cast<unsigned*>(p0 + (long)j * ld + n0 * 16) = pk; }
; __global__ void __launch_bounds__(512) mega(Params p) {
;     ...
;                     if (isk) store_nat_m(AK + (long)r0 * 256 + (c0 - 7168), 256, a, fr);
;                     else store_nat_m(AQ + (long)r0 * 1024 + (c0 - 6144), 1024, a, fr);
	s_mov_b64 s[2:3], s[0:1]
	s_load_dwordx2 s[2:3], s[2:3], 0xe8
	v_mov_b32_dpp v64, v101 quad_perm:[1,0,3,2] row_mask:0xf bank_mask:0xf bound_ctrl:1
	s_and_saveexec_b64 s[8:9], s[6:7]
	s_xor_b64 s[8:9], exec, s[8:9]
	s_cbranch_execz .LBB0_1630
	v_cvt_pk_bf16_f32 v102, v64, v75

; DEVFI float gelu_tanh(float x) {
;   float u = 0.7978845608028654f * (x + 0.044715f * x * x * x);
;   float t = __expf(2.f * u);
;   float th = 1.f - 2.f / (t + 1.f);
;   return 0.5f * x * (1.f + th);
; }
; __global__ void __launch_bounds__(512) mega(Params p) {
;     ...
; #pragma unroll
;                     for (int n = 0; n < 8; ++n)
; #pragma unroll
;                       for (int j = 0; j < 4; ++j) a[n][j] = gelu_tanh(a[n][j]);
.LBB0_1760:
	s_andn2_b64 vcc, exec, s[2:3]
	s_cbranch_vccnz .LBB0_1838
	v_mul_f32_e32 v65, 0x3d372713, v61
	v_mul_f32_e32 v65, v61, v65
	v_fma_f32 v65, v61, v65, v61
	v_mul_f32_e32 v65, 0x3f4c422a, v65
	v_add_f32_e32 v65, v65, v65
	v_mul_f32_e32 v65, 0x3fb8aa3b, v65
	v_exp_f32_e32 v66, v65
	v_mul_f32_e32 v65, 0x3d372713, v62
	v_mul_f32_e32 v65, v62, v65
	v_fma_f32 v65, v62, v65, v62
	v_mul_f32_e32 v65, 0x3f4c422a, v65
	v_add_f32_e32 v65, v65, v65
	v_mul_f32_e32 v65, 0x3fb8aa3b, v65
	v_mul_f32_e32 v64, 0x3d372713, v60
	v_exp_f32_e32 v68, v65
	v_mul_f32_e32 v65, 0x3d372713, v56
	v_mul_f32_e32 v64, v60, v64
	v_mul_f32_e32 v65, v56, v65
	v_fma_f32 v64, v60, v64, v60
	v_fma_f32 v65, v56, v65, v56
	v_mul_f32_e32 v64, 0x3f4c422a, v64
	v_mul_f32_e32 v65, 0x3f4c422a, v65
	v_add_f32_e32 v64, v64, v64
	v_add_f32_e32 v65, v65, v65
	v_mul_f32_e32 v64, 0x3fb8aa3b, v64
	v_mul_f32_e32 v65, 0x3fb8aa3b, v65
	v_exp_f32_e32 v64, v64
	v_exp_f32_e32 v65, v65
	v_mul_f32_e32 v67, 0x3d372713, v63
	v_mul_f32_e32 v67, v63, v67
	v_fma_f32 v67, v63, v67, v63
	v_pk_add_f32 v[64:65], v[64:65], 1.0 op_sel_hi:[1,0]
	v_mul_f32_e32 v67, 0x3f4c422a, v67
	v_add_f32_e32 v67, v67, v67
	v_mul_f32_e32 v67, 0x3fb8aa3b, v67
	v_exp_f32_e32 v70, v67
	v_rcp_f32_e32 v71, v65
	s_nop 0
	v_fma_f32 v67, -v65, v71, 1.0
	v_fma_f32 v71, v67, v71, v71
	v_add_f32_e32 v67, v71, v71
	v_div_fixup_f32 v65, v67, v65, 2.0
	s_cmpk_lt_u32 s26, 0x1400
	v_rcp_f32_e32 v73, v64
	s_nop 0
	v_fma_f32 v67, -v64, v73, 1.0
	v_fma_f32 v73, v67, v73, v73
	v_add_f32_e32 v67, v73, v73
	v_div_fixup_f32 v64, v67, v64, 2.0
	v_mul_f32_e32 v67, 0x3d372713, v57
	v_mul_f32_e32 v67, v57, v67
	v_fma_f32 v67, v57, v67, v57
	v_mul_f32_e32 v67, 0x3f4c422a, v67
	v_add_f32_e32 v67, v67, v67
	v_mul_f32_e32 v67, 0x3fb8aa3b, v67
	v_exp_f32_e32 v67, v67
	v_pk_add_f32 v[64:65], v[64:65], 1.0 op_sel_hi:[1,0] neg_lo:[1,0] neg_hi:[1,0]
	v_mov_b32_e32 v72, v60
	v_mov_b32_e32 v73, v56
	v_pk_add_f32 v[66:67], v[66:67], 1.0 op_sel_hi:[1,0]
	v_pk_mul_f32 v[72:73], v[72:73], 0.5 op_sel_hi:[1,0]
	v_pk_add_f32 v[64:65], v[64:65], 1.0 op_sel_hi:[1,0]
	s_mov_b64 s[8:9], -1
	v_pk_mul_f32 v[78:79], v[72:73], v[64:65]
	v_rcp_f32_e32 v71, v67
	s_nop 0
	v_fma_f32 v64, -v67, v71, 1.0
	v_fma_f32 v71, v64, v71, v71
	v_add_f32_e32 v64, v71, v71
	v_div_fixup_f32 v65, v64, v67, 2.0
	v_rcp_f32_e32 v72, v66
	s_nop 0
	v_fma_f32 v64, -v66, v72, 1.0
	v_fma_f32 v72, v64, v72, v72
	v_add_f32_e32 v64, v72, v72
	v_div_fixup_f32 v64, v64, v66, 2.0
	v_mul_f32_e32 v66, 0x3d372713, v58
	v_mul_f32_e32 v66, v58, v66
	v_fma_f32 v66, v58, v66, v58
	v_mul_f32_e32 v66, 0x3f4c422a, v66
	v_add_f32_e32 v66, v66, v66
	v_mul_f32_e32 v66, 0x3fb8aa3b, v66
	v_exp_f32_e32 v69, v66
	v_pk_add_f32 v[64:65], v[64:65], 1.0 op_sel_hi:[1,0] neg_lo:[1,0] neg_hi:[1,0]
	v_mov_b32_e32 v66, v61
	v_mov_b32_e32 v67, v57
	v_pk_add_f32 v[68:69], v[68:69], 1.0 op_sel_hi:[1,0]
	v_pk_mul_f32 v[66:67], v[66:67], 0.5 op_sel_hi:[1,0]
	v_pk_add_f32 v[64:65], v[64:65], 1.0 op_sel_hi:[1,0]
	s_nop 0
	v_pk_mul_f32 v[74:75], v[66:67], v[64:65]
	v_rcp_f32_e32 v72, v69
	s_nop 0
	v_fma_f32 v64, -v69, v72, 1.0
	v_fma_f32 v72, v64, v72, v72
	v_add_f32_e32 v64, v72, v72
	v_div_fixup_f32 v65, v64, v69, 2.0
	v_mul_f32_e32 v66, 0x3d372713, v59
	v_mul_f32_e32 v66, v59, v66
	v_fma_f32 v66, v59, v66, v59
	v_mul_f32_e32 v66, 0x3f4c422a, v66
	v_add_f32_e32 v66, v66, v66
	v_mul_f32_e32 v66, 0x3fb8aa3b, v66
	v_exp_f32_e32 v71, v66
	v_rcp_f32_e32 v67, v68
	s_nop 0
	v_fma_f32 v64, -v68, v67, 1.0
	v_fma_f32 v67, v64, v67, v67
	v_add_f32_e32 v64, v67, v67
	v_div_fixup_f32 v64, v64, v68, 2.0
	v_pk_add_f32 v[64:65], v[64:65], 1.0 op_sel_hi:[1,0] neg_lo:[1,0] neg_hi:[1,0]
	v_pk_add_f32 v[70:71], v[70:71], 1.0 op_sel_hi:[1,0]
	v_mov_b32_e32 v66, v62
	v_mov_b32_e32 v67, v58
	v_pk_mul_f32 v[66:67], v[66:67], 0.5 op_sel_hi:[1,0]
	v_pk_add_f32 v[64:65], v[64:65], 1.0 op_sel_hi:[1,0]
	s_nop 0
	v_pk_mul_f32 v[68:69], v[66:67], v[64:65]
	v_rcp_f32_e32 v73, v71
	s_nop 0
	v_fma_f32 v64, -v71, v73, 1.0
	v_fma_f32 v73, v64, v73, v73
	v_add_f32_e32 v64, v73, v73
	v_div_fixup_f32 v65, v64, v71, 2.0
	v_mul_f32_e32 v66, 0x3d372713, v44
	v_mul_f32_e32 v66, v44, v66
	v_fma_f32 v66, v44, v66, v44
	v_mul_f32_e32 v66, 0x3f4c422a, v66
	v_add_f32_e32 v66, v66, v66
	v_rcp_f32_e32 v67, v70
	s_nop 0
	v_fma_f32 v64, -v70, v67, 1.0
	v_fma_f32 v67, v64, v67, v67
	v_add_f32_e32 v64, v67, v67
	v_mul_f32_e32 v66, 0x3fb8aa3b, v66
	v_div_fixup_f32 v64, v64, v70, 2.0
	v_exp_f32_e32 v70, v66
	v_pk_add_f32 v[64:65], v[64:65], 1.0 op_sel_hi:[1,0] neg_lo:[1,0] neg_hi:[1,0]
	v_mov_b32_e32 v66, v63
	v_mov_b32_e32 v67, v59
	v_add_f32_e32 v70, 1.0, v70
	v_pk_mul_f32 v[66:67], v[66:67], 0.5 op_sel_hi:[1,0]
	v_pk_add_f32 v[64:65], v[64:65], 1.0 op_sel_hi:[1,0]
	s_nop 0
	v_pk_mul_f32 v[64:65], v[66:67], v[64:65]
	v_mul_f32_e32 v71, 0x3d372713, v45
	v_mul_f32_e32 v71, v45, v71
	v_fma_f32 v71, v45, v71, v45
	v_mul_f32_e32 v71, 0x3f4c422a, v71
	v_add_f32_e32 v71, v71, v71
	v_mul_f32_e32 v71, 0x3fb8aa3b, v71
	v_exp_f32_e32 v71, v71
	v_rcp_f32_e32 v72, v70
	s_nop 0
	v_fma_f32 v66, -v70, v72, 1.0
	v_fma_f32 v72, v66, v72, v72
	v_add_f32_e32 v66, v72, v72
	v_div_fixup_f32 v66, v66, v70, 2.0
	v_sub_f32_e32 v66, 1.0, v66
	v_add_f32_e32 v67, 1.0, v71
	v_mul_f32_e32 v72, 0.5, v44
	v_add_f32_e32 v66, 1.0, v66
	v_mul_f32_e32 v90, v72, v66
	v_mul_f32_e32 v70, 0x3d372713, v46
	v_mul_f32_e32 v70, v46, v70
	v_fma_f32 v70, v46, v70, v46
	v_mul_f32_e32 v70, 0x3f4c422a, v70
	v_add_f32_e32 v70, v70, v70
	v_mul_f32_e32 v70, 0x3fb8aa3b, v70
	v_exp_f32_e32 v70, v70
	v_rcp_f32_e32 v71, v67
	s_nop 0
	v_fma_f32 v66, -v67, v71, 1.0
	v_fma_f32 v71, v66, v71, v71
	v_add_f32_e32 v66, v71, v71
; DEVFI float gelu_tanh(float x) {
;   float u = 0.7978845608028654f * (x + 0.044715f * x * x * x);
;   float t = __expf(2.f * u);
;   float th = 1.f - 2.f / (t + 1.f);
;   return 0.5f * x * (1.f + th);
; }
; __global__ void __launch_bounds__(512) mega(Params p) {
;     ...
;                     for (int n = 0; n < 8; ++n)
; #pragma unroll
;                       for (int j = 0; j < 4; ++j) a[n][j] = gelu_tanh(a[n][j]);
	v_div_fixup_f32 v66, v66, v67, 2.0
	v_sub_f32_e32 v66, 1.0, v66
	v_add_f32_e32 v67, 1.0, v70
	v_mul_f32_e32 v72, 0.5, v45
	v_add_f32_e32 v66, 1.0, v66
	v_mul_f32_e32 v82, v72, v66
	v_mul_f32_e32 v70, 0x3d372713, v47
	v_mul_f32_e32 v70, v47, v70
	v_fma_f32 v70, v47, v70, v47
	v_mul_f32_e32 v70, 0x3f4c422a, v70
	v_add_f32_e32 v70, v70, v70
	v_mul_f32_e32 v70, 0x3fb8aa3b, v70
	v_exp_f32_e32 v70, v70
	v_rcp_f32_e32 v71, v67
	s_nop 0
	v_fma_f32 v66, -v67, v71, 1.0
	v_fma_f32 v71, v66, v71, v71
	v_add_f32_e32 v66, v71, v71
	v_div_fixup_f32 v66, v66, v67, 2.0
	v_sub_f32_e32 v66, 1.0, v66
	v_add_f32_e32 v67, 1.0, v70
	v_mul_f32_e32 v72, 0.5, v46
	v_add_f32_e32 v66, 1.0, v66
	v_mul_f32_e32 v72, v72, v66
	v_mul_f32_e32 v70, 0x3d372713, v40
	v_mul_f32_e32 v70, v40, v70
	v_fma_f32 v70, v40, v70, v40
	v_mul_f32_e32 v70, 0x3f4c422a, v70
	v_add_f32_e32 v70, v70, v70
	v_mul_f32_e32 v70, 0x3fb8aa3b, v70
	v_exp_f32_e32 v70, v70
	v_rcp_f32_e32 v71, v67
	s_nop 0
	v_fma_f32 v66, -v67, v71, 1.0
	v_fma_f32 v71, v66, v71, v71
	v_add_f32_e32 v66, v71, v71
	v_div_fixup_f32 v66, v66, v67, 2.0
	v_sub_f32_e32 v66, 1.0, v66
	v_add_f32_e32 v67, 1.0, v70
	v_mul_f32_e32 v73, 0.5, v47
	v_add_f32_e32 v66, 1.0, v66
	v_mul_f32_e32 v66, v73, v66
	v_mul_f32_e32 v73, 0x3d372713, v41
	v_mul_f32_e32 v73, v41, v73
	v_fma_f32 v73, v41, v73, v41
	v_mul_f32_e32 v73, 0x3f4c422a, v73
	v_add_f32_e32 v73, v73, v73
	v_mul_f32_e32 v73, 0x3fb8aa3b, v73
	v_exp_f32_e32 v73, v73
	v_rcp_f32_e32 v71, v67
	s_nop 0
	v_fma_f32 v70, -v67, v71, 1.0
	v_fma_f32 v71, v70, v71, v71
	v_add_f32_e32 v70, v71, v71
	v_div_fixup_f32 v67, v70, v67, 2.0
	v_sub_f32_e32 v67, 1.0, v67
	v_add_f32_e32 v70, 1.0, v73
	v_mul_f32_e32 v76, 0.5, v40
	v_add_f32_e32 v67, 1.0, v67
	v_mul_f32_e32 v104, v76, v67
	v_mul_f32_e32 v71, 0x3d372713, v42
	v_mul_f32_e32 v71, v42, v71
	v_fma_f32 v71, v42, v71, v42
	v_mul_f32_e32 v71, 0x3f4c422a, v71
	v_add_f32_e32 v71, v71, v71
	v_mul_f32_e32 v71, 0x3fb8aa3b, v71
	v_exp_f32_e32 v71, v71
	v_rcp_f32_e32 v73, v70
	s_nop 0
	v_fma_f32 v67, -v70, v73, 1.0
	v_fma_f32 v73, v67, v73, v73
	v_add_f32_e32 v67, v73, v73
	v_div_fixup_f32 v67, v67, v70, 2.0
	v_sub_f32_e32 v67, 1.0, v67
	v_add_f32_e32 v70, 1.0, v71
	v_mul_f32_e32 v76, 0.5, v41
	v_add_f32_e32 v67, 1.0, v67
	v_mul_f32_e32 v92, v76, v67
	v_mul_f32_e32 v71, 0x3d372713, v43
	v_mul_f32_e32 v71, v43, v71
	v_fma_f32 v71, v43, v71, v43
	v_mul_f32_e32 v71, 0x3f4c422a, v71
	v_add_f32_e32 v71, v71, v71
	v_mul_f32_e32 v71, 0x3fb8aa3b, v71
	v_exp_f32_e32 v71, v71
	v_rcp_f32_e32 v73, v70
	s_nop 0
	v_fma_f32 v67, -v70, v73, 1.0
	v_fma_f32 v73, v67, v73, v73
	v_add_f32_e32 v67, v73, v73
	v_div_fixup_f32 v67, v67, v70, 2.0
	v_sub_f32_e32 v67, 1.0, v67
	v_add_f32_e32 v70, 1.0, v71
	v_mul_f32_e32 v76, 0.5, v42
	v_add_f32_e32 v67, 1.0, v67
	v_mul_f32_e32 v80, v76, v67
	v_mul_f32_e32 v71, 0x3d372713, v52
	v_mul_f32_e32 v71, v52, v71
	v_fma_f32 v71, v52, v71, v52
	v_mul_f32_e32 v71, 0x3f4c422a, v71
	v_add_f32_e32 v71, v71, v71
	v_mul_f32_e32 v71, 0x3fb8aa3b, v71
	v_exp_f32_e32 v71, v71
	v_rcp_f32_e32 v73, v70
	s_nop 0
	v_fma_f32 v67, -v70, v73, 1.0
	v_fma_f32 v73, v67, v73, v73
	v_add_f32_e32 v67, v73, v73
	v_div_fixup_f32 v67, v67, v70, 2.0
	v_sub_f32_e32 v67, 1.0, v67
	v_add_f32_e32 v71, 1.0, v71
	v_mul_f32_e32 v70, 0.5, v43
	v_add_f32_e32 v67, 1.0, v67
	v_mul_f32_e32 v70, v70, v67
	v_mul_f32_e32 v73, 0x3d372713, v53
	v_mul_f32_e32 v73, v53, v73
	v_fma_f32 v73, v53, v73, v53
	v_mul_f32_e32 v73, 0x3f4c422a, v73
	v_add_f32_e32 v73, v73, v73
	v_mul_f32_e32 v73, 0x3fb8aa3b, v73
	v_exp_f32_e32 v73, v73
	v_rcp_f32_e32 v76, v71
	s_nop 0
	v_fma_f32 v67, -v71, v76, 1.0
	v_fma_f32 v76, v67, v76, v76
	v_add_f32_e32 v67, v76, v76
	v_div_fixup_f32 v67, v67, v71, 2.0
	v_sub_f32_e32 v67, 1.0, v67
	v_add_f32_e32 v71, 1.0, v73
	v_mul_f32_e32 v77, 0.5, v52
	v_add_f32_e32 v67, 1.0, v67
	v_mul_f32_e32 v106, v77, v67
	v_mul_f32_e32 v73, 0x3d372713, v54
	v_mul_f32_e32 v73, v54, v73
	v_fma_f32 v73, v54, v73, v54
	v_mul_f32_e32 v73, 0x3f4c422a, v73
	v_add_f32_e32 v73, v73, v73
	v_mul_f32_e32 v73, 0x3fb8aa3b, v73
	v_exp_f32_e32 v73, v73
	v_rcp_f32_e32 v76, v71
	s_nop 0
	v_fma_f32 v67, -v71, v76, 1.0
	v_fma_f32 v76, v67, v76, v76
	v_add_f32_e32 v67, v76, v76
	v_div_fixup_f32 v67, v67, v71, 2.0
	v_sub_f32_e32 v67, 1.0, v67
	v_add_f32_e32 v71, 1.0, v73
	v_mul_f32_e32 v77, 0.5, v53
	v_add_f32_e32 v67, 1.0, v67
	v_mul_f32_e32 v98, v77, v67
	v_mul_f32_e32 v73, 0x3d372713, v55
	v_mul_f32_e32 v73, v55, v73
	v_fma_f32 v73, v55, v73, v55
	v_mul_f32_e32 v73, 0x3f4c422a, v73
	v_add_f32_e32 v73, v73, v73
	v_mul_f32_e32 v73, 0x3fb8aa3b, v73
	v_exp_f32_e32 v73, v73
	v_rcp_f32_e32 v76, v71
	s_nop 0
	v_fma_f32 v67, -v71, v76, 1.0
	v_fma_f32 v76, v67, v76, v76
	v_add_f32_e32 v67, v76, v76
	v_div_fixup_f32 v67, v67, v71, 2.0
	v_sub_f32_e32 v67, 1.0, v67
	v_add_f32_e32 v71, 1.0, v73
	v_mul_f32_e32 v77, 0.5, v54
	v_add_f32_e32 v67, 1.0, v67
	v_mul_f32_e32 v86, v77, v67
	v_mul_f32_e32 v73, 0x3d372713, v48
	v_mul_f32_e32 v73, v48, v73
	v_fma_f32 v73, v48, v73, v48
	v_mul_f32_e32 v73, 0x3f4c422a, v73
	v_add_f32_e32 v73, v73, v73
	v_mul_f32_e32 v73, 0x3fb8aa3b, v73
	v_exp_f32_e32 v73, v73
	v_rcp_f32_e32 v76, v71
	s_nop 0
	v_fma_f32 v67, -v71, v76, 1.0
	v_fma_f32 v76, v67, v76, v76
	v_add_f32_e32 v67, v76, v76
	v_div_fixup_f32 v67, v67, v71, 2.0
	v_sub_f32_e32 v67, 1.0, v67
	v_add_f32_e32 v71, 1.0, v73
	v_mul_f32_e32 v76, 0.5, v55
	v_add_f32_e32 v67, 1.0, v67
	v_mul_f32_e32 v76, v76, v67
	v_mul_f32_e32 v73, 0x3d372713, v49
	v_mul_f32_e32 v73, v49, v73
	v_fma_f32 v73, v49, v73, v49
	v_mul_f32_e32 v73, 0x3f4c422a, v73
	v_add_f32_e32 v73, v73, v73
	v_mul_f32_e32 v73, 0x3fb8aa3b, v73
	v_exp_f32_e32 v73, v73
; #define SVSTAT ((float*)(kargs()->ws + O_SVSTAT))
; DEVFI float gelu_tanh(float x) {
;   float u = 0.7978845608028654f * (x + 0.044715f * x * x * x);
;   float t = __expf(2.f * u);
;   float th = 1.f - 2.f / (t + 1.f);
;   return 0.5f * x * (1.f + th);
; }
; __global__ void __launch_bounds__(512) mega(Params p) {
;     ...
;                     for (int n = 0; n < 8; ++n)
; #pragma unroll
;                       for (int j = 0; j < 4; ++j) a[n][j] = gelu_tanh(a[n][j]);
;                     if (c0 >= 5120) { float* stp = SVSTAT + (long)r0 * 16 + ((c0 - 5120) >> 7) * 2;
	v_rcp_f32_e32 v77, v71
	s_nop 0
	v_fma_f32 v67, -v71, v77, 1.0
	v_fma_f32 v77, v67, v77, v77
	v_add_f32_e32 v67, v77, v77
	v_div_fixup_f32 v67, v67, v71, 2.0
	v_sub_f32_e32 v67, 1.0, v67
	v_add_f32_e32 v71, 1.0, v73
	v_mul_f32_e32 v81, 0.5, v48
	v_add_f32_e32 v67, 1.0, v67
	v_mul_f32_e32 v114, v81, v67
	v_mul_f32_e32 v73, 0x3d372713, v50
	v_mul_f32_e32 v73, v50, v73
	v_fma_f32 v73, v50, v73, v50
	v_mul_f32_e32 v73, 0x3f4c422a, v73
	v_add_f32_e32 v73, v73, v73
	v_mul_f32_e32 v73, 0x3fb8aa3b, v73
	v_exp_f32_e32 v73, v73
	v_rcp_f32_e32 v77, v71
	s_nop 0
	v_fma_f32 v67, -v71, v77, 1.0
	v_fma_f32 v77, v67, v77, v77
	v_add_f32_e32 v67, v77, v77
	v_div_fixup_f32 v67, v67, v71, 2.0
	v_sub_f32_e32 v67, 1.0, v67
	v_add_f32_e32 v71, 1.0, v73
	v_mul_f32_e32 v81, 0.5, v49
	v_add_f32_e32 v67, 1.0, v67
	v_mul_f32_e32 v108, v81, v67
	v_mul_f32_e32 v73, 0x3d372713, v51
	v_mul_f32_e32 v73, v51, v73
	v_fma_f32 v73, v51, v73, v51
	v_mul_f32_e32 v73, 0x3f4c422a, v73
	v_add_f32_e32 v73, v73, v73
	v_mul_f32_e32 v73, 0x3fb8aa3b, v73
	v_exp_f32_e32 v73, v73
	v_rcp_f32_e32 v77, v71
	s_nop 0
	v_fma_f32 v67, -v71, v77, 1.0
	v_fma_f32 v77, v67, v77, v77
	v_add_f32_e32 v67, v77, v77
	v_div_fixup_f32 v67, v67, v71, 2.0
	v_sub_f32_e32 v67, 1.0, v67
	v_add_f32_e32 v71, 1.0, v73
	v_mul_f32_e32 v81, 0.5, v50
	v_add_f32_e32 v67, 1.0, v67
	v_mul_f32_e32 v94, v81, v67
	v_mul_f32_e32 v73, 0x3d372713, v36
	v_mul_f32_e32 v73, v36, v73
	v_fma_f32 v73, v36, v73, v36
	v_mul_f32_e32 v73, 0x3f4c422a, v73
	v_add_f32_e32 v73, v73, v73
	v_mul_f32_e32 v73, 0x3fb8aa3b, v73
	v_exp_f32_e32 v73, v73
	v_rcp_f32_e32 v77, v71
	s_nop 0
	v_fma_f32 v67, -v71, v77, 1.0
	v_fma_f32 v77, v67, v77, v77
	v_add_f32_e32 v67, v77, v77
	v_div_fixup_f32 v67, v67, v71, 2.0
	v_sub_f32_e32 v67, 1.0, v67
	v_add_f32_e32 v71, 1.0, v73
	v_mul_f32_e32 v81, 0.5, v51
	v_add_f32_e32 v67, 1.0, v67
	v_mul_f32_e32 v84, v81, v67
	v_mul_f32_e32 v73, 0x3d372713, v37
	v_mul_f32_e32 v73, v37, v73
	v_fma_f32 v73, v37, v73, v37
	v_mul_f32_e32 v73, 0x3f4c422a, v73
	v_add_f32_e32 v73, v73, v73
	v_mul_f32_e32 v73, 0x3fb8aa3b, v73
	v_exp_f32_e32 v73, v73
	v_rcp_f32_e32 v77, v71
	s_nop 0
	v_fma_f32 v67, -v71, v77, 1.0
	v_fma_f32 v77, v67, v77, v77
	v_add_f32_e32 v67, v77, v77
	v_div_fixup_f32 v67, v67, v71, 2.0
	v_sub_f32_e32 v67, 1.0, v67
	v_add_f32_e32 v71, 1.0, v73
	v_mul_f32_e32 v81, 0.5, v36
	v_add_f32_e32 v67, 1.0, v67
	v_mul_f32_e32 v116, v81, v67
	v_mul_f32_e32 v73, 0x3d372713, v38
	v_mul_f32_e32 v73, v38, v73
	v_fma_f32 v73, v38, v73, v38
	v_mul_f32_e32 v73, 0x3f4c422a, v73
	v_add_f32_e32 v73, v73, v73
	v_mul_f32_e32 v73, 0x3fb8aa3b, v73
	v_exp_f32_e32 v73, v73
	v_rcp_f32_e32 v77, v71
	s_nop 0
	v_fma_f32 v67, -v71, v77, 1.0
	v_fma_f32 v77, v67, v77, v77
	v_add_f32_e32 v67, v77, v77
	v_div_fixup_f32 v67, v67, v71, 2.0
	v_sub_f32_e32 v67, 1.0, v67
	v_add_f32_e32 v71, 1.0, v73
	v_mul_f32_e32 v81, 0.5, v37
	v_add_f32_e32 v67, 1.0, v67
	v_mul_f32_e32 v112, v81, v67
	v_mul_f32_e32 v73, 0x3d372713, v39
	v_mul_f32_e32 v73, v39, v73
	v_fma_f32 v73, v39, v73, v39
	v_mul_f32_e32 v73, 0x3f4c422a, v73
	v_add_f32_e32 v73, v73, v73
	v_mul_f32_e32 v73, 0x3fb8aa3b, v73
	v_exp_f32_e32 v73, v73
	v_rcp_f32_e32 v77, v71
	s_nop 0
	v_fma_f32 v67, -v71, v77, 1.0
	v_fma_f32 v77, v67, v77, v77
	v_add_f32_e32 v67, v77, v77
	v_div_fixup_f32 v67, v67, v71, 2.0
	v_sub_f32_e32 v67, 1.0, v67
	v_add_f32_e32 v71, 1.0, v73
	v_mul_f32_e32 v81, 0.5, v38
	v_add_f32_e32 v67, 1.0, v67
	v_mul_f32_e32 v102, v81, v67
	v_mul_f32_e32 v73, 0x3d372713, v32
	v_mul_f32_e32 v73, v32, v73
	v_fma_f32 v73, v32, v73, v32
	v_mul_f32_e32 v73, 0x3f4c422a, v73
	v_add_f32_e32 v73, v73, v73
	v_mul_f32_e32 v73, 0x3fb8aa3b, v73
	v_exp_f32_e32 v73, v73
	v_rcp_f32_e32 v77, v71
	s_nop 0
	v_fma_f32 v67, -v71, v77, 1.0
	v_fma_f32 v77, v67, v77, v77
	v_add_f32_e32 v67, v77, v77
	v_div_fixup_f32 v67, v67, v71, 2.0
	v_sub_f32_e32 v67, 1.0, v67
	v_add_f32_e32 v71, 1.0, v73
	v_mul_f32_e32 v81, 0.5, v39
	v_add_f32_e32 v67, 1.0, v67
	v_mul_f32_e32 v88, v81, v67
	v_mul_f32_e32 v73, 0x3d372713, v33
	v_mul_f32_e32 v73, v33, v73
	v_fma_f32 v73, v33, v73, v33
	v_mul_f32_e32 v73, 0x3f4c422a, v73
	v_add_f32_e32 v73, v73, v73
	v_mul_f32_e32 v73, 0x3fb8aa3b, v73
	v_exp_f32_e32 v73, v73
	v_rcp_f32_e32 v77, v71
	s_nop 0
	v_fma_f32 v67, -v71, v77, 1.0
	v_fma_f32 v77, v67, v77, v77
	v_add_f32_e32 v67, v77, v77
	v_div_fixup_f32 v67, v67, v71, 2.0
	v_sub_f32_e32 v67, 1.0, v67
	v_add_f32_e32 v71, 1.0, v73
	v_mul_f32_e32 v81, 0.5, v32
	v_add_f32_e32 v67, 1.0, v67
	v_mul_f32_e32 v120, v81, v67
	v_mul_f32_e32 v73, 0x3d372713, v34
	v_mul_f32_e32 v73, v34, v73
	v_fma_f32 v73, v34, v73, v34
	v_mul_f32_e32 v73, 0x3f4c422a, v73
	v_add_f32_e32 v73, v73, v73
	v_mul_f32_e32 v73, 0x3fb8aa3b, v73
	v_exp_f32_e32 v73, v73
	v_rcp_f32_e32 v77, v71
	s_nop 0
	v_fma_f32 v67, -v71, v77, 1.0
	v_fma_f32 v77, v67, v77, v77
	v_add_f32_e32 v67, v77, v77
	v_div_fixup_f32 v67, v67, v71, 2.0
	v_sub_f32_e32 v67, 1.0, v67
	v_add_f32_e32 v71, 1.0, v73
	v_mul_f32_e32 v81, 0.5, v33
	v_add_f32_e32 v67, 1.0, v67
	v_mul_f32_e32 v118, v81, v67
	v_mul_f32_e32 v73, 0x3d372713, v35
	v_mul_f32_e32 v73, v35, v73
	v_fma_f32 v73, v35, v73, v35
	v_mul_f32_e32 v73, 0x3f4c422a, v73
	v_add_f32_e32 v73, v73, v73
	v_mul_f32_e32 v73, 0x3fb8aa3b, v73
	v_exp_f32_e32 v73, v73
	v_rcp_f32_e32 v77, v71
	s_nop 0
	v_fma_f32 v67, -v71, v77, 1.0
	v_fma_f32 v77, v67, v77, v77
	v_add_f32_e32 v67, v77, v77
	v_div_fixup_f32 v67, v67, v71, 2.0
	v_sub_f32_e32 v67, 1.0, v67
	v_add_f32_e32 v71, 1.0, v73
	v_mul_f32_e32 v81, 0.5, v34
	v_add_f32_e32 v67, 1.0, v67
	v_mul_f32_e32 v110, v81, v67
	v_rcp_f32_e32 v77, v71
	s_nop 0
	v_fma_f32 v67, -v71, v77, 1.0
	v_fma_f32 v77, v67, v77, v77
	v_add_f32_e32 v67, v77, v77
	v_div_fixup_f32 v67, v67, v71, 2.0
	v_sub_f32_e32 v67, 1.0, v67
	v_mul_f32_e32 v71, 0.5, v35
	v_add_f32_e32 v67, 1.0, v67
	v_mul_f32_e32 v100, v71, v67
	s_cbranch_scc1 .LBB0_1771
; DEVFI int lane_opaque() { unsigned m = ~0u; asm volatile("" : "+s"(m)); return (int)__builtin_amdgcn_mbcnt_hi(m, __builtin_amdgcn_mbcnt_lo(m, 0u)); }
; DEVFI float shx(float v, int mask, int lane) { return __int_as_float(__builtin_amdgcn_ds_bpermute((lane ^ mask) << 2, __float_as_int(v))); }
; #define SVSTAT ((float*)(kargs()->ws + O_SVSTAT))
; DEVFI float red16(float v) {
;   const int ln = lane_opaque();
;   v += shx(v, 1, ln); v += shx(v, 2, ln); v += shx(v, 4, ln); v += shx(v, 8, ln); return v;
; }
; __global__ void __launch_bounds__(512) mega(Params p) {
;     ...
;                     if (c0 >= 5120) { float* stp = SVSTAT + (long)r0 * 16 + ((c0 - 5120) >> 7) * 2;
; #pragma unroll
;                       for (int j = 0; j < 4; ++j) { float s1 = 0, s2 = 0;
; #pragma unroll
;                         for (int n = 0; n < 8; ++n) { s1 += a[n][j]; s2 += a[n][j] * a[n][j]; }
;                         s1 = red16(s1); s2 = red16(s2);
;                         if (fr == 0) { stp[j * 16] = s1; stp[j * 16 + 1] = s2; } } }
	s_mov_b64 s[2:3], s[0:1]
	s_load_dwordx2 s[2:3], s[2:3], 0xe8
	v_ashrrev_i32_e32 v97, 31, v96
	v_lshlrev_b64 v[122:123], 6, v[96:97]
	v_add_u32_e32 v67, 0xffffec00, v176
	v_lshrrev_b32_e32 v124, 4, v67
	s_waitcnt lgkmcnt(0)
	v_lshl_add_u64 v[122:123], s[2:3], 0, v[122:123]
	v_mov_b32_e32 v125, v177
	v_lshl_add_u64 v[122:123], v[122:123], 0, v[124:125]
	v_mov_b32_e32 v124, v177
	v_mov_b32_e32 v125, v79
	v_pk_add_f32 v[124:125], v[78:79], v[124:125]
	v_pk_mul_f32 v[126:127], v[78:79], v[78:79]
	s_mov_b64 s[2:3], 0x3a720400
	v_mov_b32_e32 v125, v127
	v_pk_mov_b32 v[126:127], v[78:79], v[126:127] op_sel:[1,0]
	v_lshl_add_u64 v[122:123], v[122:123], 0, s[2:3]
	v_mul_f32_e32 v91, v90, v90
	s_mov_b32 s2, -1
	v_pk_add_f32 v[124:125], v[124:125], v[126:127]
	v_mul_f32_e32 v105, v104, v104
	v_pk_add_f32 v[124:125], v[124:125], v[90:91]
	v_mbcnt_lo_u32_b32 v67, s2, 0
	v_mul_f32_e32 v107, v106, v106
	v_mbcnt_hi_u32_b32 v67, s2, v67
	s_mov_b32 s2, -1
	v_pk_add_f32 v[124:125], v[124:125], v[104:105]
	v_mul_f32_e32 v115, v114, v114
	v_pk_add_f32 v[124:125], v[124:125], v[106:107]
	v_mbcnt_lo_u32_b32 v81, s2, 0
	v_mul_f32_e32 v117, v116, v116
	v_mbcnt_hi_u32_b32 v81, s2, v81
	v_pk_add_f32 v[124:125], v[124:125], v[114:115]
	v_mul_f32_e32 v121, v120, v120
	v_lshlrev_b32_e32 v67, 2, v67
	v_lshlrev_b32_e32 v81, 2, v81
	v_pk_add_f32 v[124:125], v[124:125], v[116:117]
	v_xor_b32_e32 v71, 4, v67
	v_xor_b32_e32 v83, 4, v81
	v_pk_add_f32 v[124:125], v[124:125], v[120:121]
	s_nop 1
	v_mov_b32_dpp v126, v124 quad_perm:[1,0,3,2] row_mask:0xf bank_mask:0xf
	s_nop 0
	v_mov_b32_dpp v127, v125 quad_perm:[1,0,3,2] row_mask:0xf bank_mask:0xf
	v_xor_b32_e32 v73, 8, v67
	v_xor_b32_e32 v85, 8, v81
	v_xor_b32_e32 v77, 16, v67
	v_xor_b32_e32 v87, 16, v81
	s_waitcnt lgkmcnt(0)
	v_pk_add_f32 v[124:125], v[124:125], v[126:127]
	s_nop 1
	v_mov_b32_dpp v126, v124 quad_perm:[2,3,0,1] row_mask:0xf bank_mask:0xf
	s_nop 0
	v_mov_b32_dpp v127, v125 quad_perm:[2,3,0,1] row_mask:0xf bank_mask:0xf
	v_xor_b32_e32 v67, 32, v67
	v_cmp_eq_u32_e32 vcc, 0, v202
	s_waitcnt lgkmcnt(0)
	v_pk_add_f32 v[124:125], v[124:125], v[126:127]
	s_nop 1
	v_mov_b32_dpp v126, v124 row_half_mirror row_mask:0xf bank_mask:0xf
	s_nop 1
	v_mov_b32_dpp v126, v126 quad_perm:[3,2,1,0] row_mask:0xf bank_mask:0xf
	v_mov_b32_dpp v127, v125 row_half_mirror row_mask:0xf bank_mask:0xf
	s_nop 1
	v_mov_b32_dpp v127, v127 quad_perm:[3,2,1,0] row_mask:0xf bank_mask:0xf
	s_waitcnt lgkmcnt(0)
	v_pk_add_f32 v[124:125], v[124:125], v[126:127]
	s_nop 1
	v_mov_b32_dpp v126, v124 row_ror:8 row_mask:0xf bank_mask:0xf
	v_xor_b32_e32 v67, 32, v81
	v_mov_b32_dpp v127, v125 row_ror:8 row_mask:0xf bank_mask:0xf
	s_and_saveexec_b64 s[2:3], vcc
	s_cbranch_execz .LBB0_1764
	s_waitcnt lgkmcnt(0)
	v_pk_add_f32 v[124:125], v[124:125], v[126:127]
	global_store_dwordx2 v[122:123], v[124:125], off
.LBB0_1764:
	s_or_b64 exec, exec, s[2:3]
	v_mov_b32_e32 v124, v177
	v_mov_b32_e32 v125, v75
	v_pk_add_f32 v[124:125], v[74:75], v[124:125]
	s_waitcnt lgkmcnt(0)
	v_pk_mul_f32 v[126:127], v[74:75], v[74:75]
	v_mul_f32_e32 v83, v82, v82
	v_mov_b32_e32 v125, v127
	v_pk_mov_b32 v[126:127], v[74:75], v[126:127] op_sel:[1,0]
	s_mov_b32 s2, -1
	v_pk_add_f32 v[124:125], v[124:125], v[126:127]
	v_mul_f32_e32 v93, v92, v92
	v_pk_add_f32 v[124:125], v[124:125], v[82:83]
	v_mbcnt_lo_u32_b32 v67, s2, 0
	v_mul_f32_e32 v99, v98, v98
	v_mbcnt_hi_u32_b32 v67, s2, v67
	s_mov_b32 s2, -1
	v_pk_add_f32 v[124:125], v[124:125], v[92:93]
	v_mul_f32_e32 v109, v108, v108
	v_pk_add_f32 v[124:125], v[124:125], v[98:99]
	v_mbcnt_lo_u32_b32 v73, s2, 0
	v_mul_f32_e32 v113, v112, v112
	v_mbcnt_hi_u32_b32 v73, s2, v73
	v_pk_add_f32 v[124:125], v[124:125], v[108:109]
	v_mul_f32_e32 v119, v118, v118
	v_lshlrev_b32_e32 v67, 2, v67
	v_lshlrev_b32_e32 v73, 2, v73
	v_pk_add_f32 v[124:125], v[124:125], v[112:113]
	v_xor_b32_e32 v71, 4, v67
	v_xor_b32_e32 v77, 4, v73
	v_pk_add_f32 v[124:125], v[124:125], v[118:119]
	s_nop 1
	v_mov_b32_dpp v126, v124 quad_perm:[1,0,3,2] row_mask:0xf bank_mask:0xf
	s_nop 0
	v_mov_b32_dpp v127, v125 quad_perm:[1,0,3,2] row_mask:0xf bank_mask:0xf
	v_xor_b32_e32 v71, 8, v67
	v_xor_b32_e32 v77, 8, v73
	s_waitcnt lgkmcnt(0)
	v_pk_add_f32 v[124:125], v[124:125], v[126:127]
	s_nop 1
	v_mov_b32_dpp v126, v124 quad_perm:[2,3,0,1] row_mask:0xf bank_mask:0xf
	s_nop 0
	v_mov_b32_dpp v127, v125 quad_perm:[2,3,0,1] row_mask:0xf bank_mask:0xf
	v_xor_b32_e32 v71, 16, v67
	v_xor_b32_e32 v77, 16, v73
	v_xor_b32_e32 v67, 32, v67
	s_waitcnt lgkmcnt(0)
	v_pk_add_f32 v[124:125], v[124:125], v[126:127]
	s_nop 1
	v_mov_b32_dpp v126, v124 row_half_mirror row_mask:0xf bank_mask:0xf
	s_nop 1
	v_mov_b32_dpp v126, v126 quad_perm:[3,2,1,0] row_mask:0xf bank_mask:0xf
	v_mov_b32_dpp v127, v125 row_half_mirror row_mask:0xf bank_mask:0xf
	s_nop 1
	v_mov_b32_dpp v127, v127 quad_perm:[3,2,1,0] row_mask:0xf bank_mask:0xf
	s_waitcnt lgkmcnt(0)
	v_pk_add_f32 v[124:125], v[124:125], v[126:127]
	s_nop 1
	v_mov_b32_dpp v126, v124 row_ror:8 row_mask:0xf bank_mask:0xf
	v_xor_b32_e32 v67, 32, v73
	v_mov_b32_dpp v127, v125 row_ror:8 row_mask:0xf bank_mask:0xf
	s_and_saveexec_b64 s[2:3], vcc
	s_cbranch_execz .LBB0_1766
	s_waitcnt lgkmcnt(0)
	v_pk_add_f32 v[124:125], v[124:125], v[126:127]
	global_store_dwordx2 v[122:123], v[124:125], off offset:64
; DEVFI int lane_opaque() { unsigned m = ~0u; asm volatile("" : "+s"(m)); return (int)__builtin_amdgcn_mbcnt_hi(m, __builtin_amdgcn_mbcnt_lo(m, 0u)); }
; DEVFI float shx(float v, int mask, int lane) { return __int_as_float(__builtin_amdgcn_ds_bpermute((lane ^ mask) << 2, __float_as_int(v))); }
; #define SVSTAT ((float*)(kargs()->ws + O_SVSTAT))
; DEVFI float red16(float v) {
;   const int ln = lane_opaque();
;   v += shx(v, 1, ln); v += shx(v, 2, ln); v += shx(v, 4, ln); v += shx(v, 8, ln); return v;
; }
; __global__ void __launch_bounds__(512) mega(Params p) {
;     ...
;                     if (c0 >= 5120) { float* stp = SVSTAT + (long)r0 * 16 + ((c0 - 5120) >> 7) * 2;
; #pragma unroll
;                       for (int j = 0; j < 4; ++j) { float s1 = 0, s2 = 0;
; #pragma unroll
;                         for (int n = 0; n < 8; ++n) { s1 += a[n][j]; s2 += a[n][j] * a[n][j]; }
;                         s1 = red16(s1); s2 = red16(s2);
;                         if (fr == 0) { stp[j * 16] = s1; stp[j * 16 + 1] = s2; } } }
.LBB0_1766:
	s_or_b64 exec, exec, s[2:3]
	v_mov_b32_e32 v124, v177
	v_mov_b32_e32 v125, v69
	v_pk_add_f32 v[124:125], v[68:69], v[124:125]
	s_waitcnt lgkmcnt(0)
	v_pk_mul_f32 v[126:127], v[68:69], v[68:69]
	v_mul_f32_e32 v73, v72, v72
	v_mov_b32_e32 v125, v127
	v_pk_mov_b32 v[126:127], v[68:69], v[126:127] op_sel:[1,0]
	s_mov_b32 s2, -1
	v_pk_add_f32 v[124:125], v[124:125], v[126:127]
	v_mul_f32_e32 v81, v80, v80
	v_pk_add_f32 v[124:125], v[124:125], v[72:73]
	v_mbcnt_lo_u32_b32 v67, s2, 0
	v_mul_f32_e32 v87, v86, v86
	v_mbcnt_hi_u32_b32 v67, s2, v67
	s_mov_b32 s2, -1
	v_pk_add_f32 v[124:125], v[124:125], v[80:81]
	v_mul_f32_e32 v95, v94, v94
	v_pk_add_f32 v[124:125], v[124:125], v[86:87]
	v_mbcnt_lo_u32_b32 v77, s2, 0
	v_mul_f32_e32 v103, v102, v102
	v_mbcnt_hi_u32_b32 v77, s2, v77
	v_pk_add_f32 v[124:125], v[124:125], v[94:95]
	v_mul_f32_e32 v111, v110, v110
	v_lshlrev_b32_e32 v67, 2, v67
	v_lshlrev_b32_e32 v77, 2, v77
	v_pk_add_f32 v[124:125], v[124:125], v[102:103]
	v_xor_b32_e32 v71, 4, v67
	v_xor_b32_e32 v83, 4, v77
	v_pk_add_f32 v[124:125], v[124:125], v[110:111]
	s_nop 1
	v_mov_b32_dpp v126, v124 quad_perm:[1,0,3,2] row_mask:0xf bank_mask:0xf
	s_nop 0
	v_mov_b32_dpp v127, v125 quad_perm:[1,0,3,2] row_mask:0xf bank_mask:0xf
	v_xor_b32_e32 v71, 8, v67
	v_xor_b32_e32 v73, 8, v77
	s_waitcnt lgkmcnt(0)
	v_pk_add_f32 v[124:125], v[124:125], v[126:127]
	s_nop 1
	v_mov_b32_dpp v126, v124 quad_perm:[2,3,0,1] row_mask:0xf bank_mask:0xf
	s_nop 0
	v_mov_b32_dpp v127, v125 quad_perm:[2,3,0,1] row_mask:0xf bank_mask:0xf
	v_xor_b32_e32 v71, 16, v67
	v_xor_b32_e32 v73, 16, v77
	v_xor_b32_e32 v67, 32, v67
	s_waitcnt lgkmcnt(0)
	v_pk_add_f32 v[124:125], v[124:125], v[126:127]
	s_nop 1
	v_mov_b32_dpp v126, v124 row_half_mirror row_mask:0xf bank_mask:0xf
	s_nop 1
	v_mov_b32_dpp v126, v126 quad_perm:[3,2,1,0] row_mask:0xf bank_mask:0xf
	v_mov_b32_dpp v127, v125 row_half_mirror row_mask:0xf bank_mask:0xf
	s_nop 1
	v_mov_b32_dpp v127, v127 quad_perm:[3,2,1,0] row_mask:0xf bank_mask:0xf
	s_waitcnt lgkmcnt(0)
	v_pk_add_f32 v[124:125], v[124:125], v[126:127]
	s_nop 1
	v_mov_b32_dpp v126, v124 row_ror:8 row_mask:0xf bank_mask:0xf
	v_xor_b32_e32 v67, 32, v77
	v_mov_b32_dpp v127, v125 row_ror:8 row_mask:0xf bank_mask:0xf
	s_and_saveexec_b64 s[2:3], vcc
	s_cbranch_execz .LBB0_1768
	s_waitcnt lgkmcnt(0)
	v_pk_add_f32 v[124:125], v[124:125], v[126:127]
	global_store_dwordx2 v[122:123], v[124:125], off offset:128
.LBB0_1768:
	s_or_b64 exec, exec, s[2:3]
	v_mov_b32_e32 v124, v177
	v_mov_b32_e32 v125, v65
	v_pk_add_f32 v[124:125], v[64:65], v[124:125]
	s_waitcnt lgkmcnt(0)
	v_pk_mul_f32 v[126:127], v[64:65], v[64:65]
	v_mul_f32_e32 v67, v66, v66
	v_mov_b32_e32 v125, v127
	v_pk_mov_b32 v[126:127], v[64:65], v[126:127] op_sel:[1,0]
	s_mov_b32 s2, -1
	v_pk_add_f32 v[124:125], v[124:125], v[126:127]
	v_mul_f32_e32 v71, v70, v70
	v_pk_add_f32 v[124:125], v[124:125], v[66:67]
	v_mbcnt_lo_u32_b32 v73, s2, 0
	v_mul_f32_e32 v77, v76, v76
	v_mbcnt_hi_u32_b32 v73, s2, v73
	s_mov_b32 s2, -1
	v_pk_add_f32 v[124:125], v[124:125], v[70:71]
	v_mul_f32_e32 v85, v84, v84
	v_pk_add_f32 v[124:125], v[124:125], v[76:77]
	v_mbcnt_lo_u32_b32 v83, s2, 0
	v_mul_f32_e32 v89, v88, v88
	v_mbcnt_hi_u32_b32 v83, s2, v83
	v_pk_add_f32 v[124:125], v[124:125], v[84:85]
	v_mul_f32_e32 v101, v100, v100
	v_lshlrev_b32_e32 v73, 2, v73
	v_lshlrev_b32_e32 v83, 2, v83
	v_pk_add_f32 v[124:125], v[124:125], v[88:89]
	v_xor_b32_e32 v81, 4, v73
	v_xor_b32_e32 v87, 4, v83
	v_pk_add_f32 v[124:125], v[124:125], v[100:101]
	s_nop 1
	v_mov_b32_dpp v126, v124 quad_perm:[1,0,3,2] row_mask:0xf bank_mask:0xf
	s_nop 0
	v_mov_b32_dpp v127, v125 quad_perm:[1,0,3,2] row_mask:0xf bank_mask:0xf
	v_xor_b32_e32 v67, 8, v73
	v_xor_b32_e32 v71, 8, v83
	s_waitcnt lgkmcnt(0)
	v_pk_add_f32 v[124:125], v[124:125], v[126:127]
	s_nop 1
	v_mov_b32_dpp v126, v124 quad_perm:[2,3,0,1] row_mask:0xf bank_mask:0xf
	s_nop 0
	v_mov_b32_dpp v127, v125 quad_perm:[2,3,0,1] row_mask:0xf bank_mask:0xf
	v_xor_b32_e32 v67, 16, v73
	v_xor_b32_e32 v71, 16, v83
	s_waitcnt lgkmcnt(0)
	v_pk_add_f32 v[124:125], v[124:125], v[126:127]
	s_nop 1
	v_mov_b32_dpp v126, v124 row_half_mirror row_mask:0xf bank_mask:0xf
	s_nop 1
	v_mov_b32_dpp v126, v126 quad_perm:[3,2,1,0] row_mask:0xf bank_mask:0xf
	v_mov_b32_dpp v127, v125 row_half_mirror row_mask:0xf bank_mask:0xf
	s_nop 1
	v_mov_b32_dpp v127, v127 quad_perm:[3,2,1,0] row_mask:0xf bank_mask:0xf
	v_xor_b32_e32 v67, 32, v73
	s_waitcnt lgkmcnt(0)
	v_pk_add_f32 v[124:125], v[124:125], v[126:127]
	s_nop 1
	v_mov_b32_dpp v126, v124 row_ror:8 row_mask:0xf bank_mask:0xf
	v_xor_b32_e32 v67, 32, v83
	v_mov_b32_dpp v127, v125 row_ror:8 row_mask:0xf bank_mask:0xf
	s_and_saveexec_b64 s[2:3], vcc
	s_cbranch_execz .LBB0_1770
	s_waitcnt lgkmcnt(0)
	v_pk_add_f32 v[124:125], v[124:125], v[126:127]
	global_store_dwordx2 v[122:123], v[124:125], off offset:192

; #define ATTT ((float2*)(kargs()->ws + O_ATTT))
; __global__ void __launch_bounds__(512) mega(Params p) {
;     ...
;                     const bool isk = c0 >= 7168; const float* nw = isk ? kn_w : qn_w; const float2* attt = ATTT;
; #pragma unroll
;                     for (int j = 0; j < 4; ++j) { const int pos = (r0 + j) & (seqlen - 1);
;                       float ss = 0;
; #pragma unroll
;                       for (int n = 0; n < 8; ++n) ss += a[n][j] * a[n][j];
;                       ss = red16(ss);
;                       const float rstd = 1.f / sqrtf(ss * (1.f / 128.f) + RMS_EPS);
; #pragma unroll
;                       for (int n = 0; n < 8; ++n) a[n][j] = a[n][j] * rstd * hv[n];
;                       const float4* tb = (const float4*)(attt + pos * 64 + fr * 4);
;                       const float4 t01 = tb[0], t23 = tb[1];
;                       const float2 csv[4] = {make_float2(t01.x, t01.y), make_float2(t01.z, t01.w), make_float2(t23.x, t23.y), make_float2(t23.z, t23.w)};
; #pragma unroll
;                       for (int hh = 0; hh < 2; ++hh)
; #pragma unroll
;                         for (int n = 0; n < 2; ++n) { const float2 cs = csv[hh * 2 + n];
;                           const float x1 = a[hh * 4 + n][j], x2 = a[hh * 4 + n + 2][j];
;                           a[hh * 4 + n][j] = x1 * cs.x - x2 * cs.y; a[hh * 4 + n + 2][j] = x1 * cs.y + x2 * cs.x; } }
.LBB0_2059:
	s_mov_b64 s[2:3], s[0:1]
	s_load_dwordx2 s[2:3], s[2:3], 0xe8
	v_mul_f32_e32 v32, v24, v24
	v_fmac_f32_e32 v32, v28, v28
	v_fmac_f32_e32 v32, v12, v12
	v_fmac_f32_e32 v32, v8, v8
	s_waitcnt lgkmcnt(0)
	s_add_u32 s36, s2, 0x3da0000
	s_mov_b32 s2, -1
	v_fmac_f32_e32 v32, v20, v20
	v_fmac_f32_e32 v32, v16, v16
	v_mbcnt_lo_u32_b32 v33, s2, 0
	v_mbcnt_hi_u32_b32 v33, s2, v33
	v_fmac_f32_e32 v32, v4, v4
	v_lshlrev_b32_e32 v33, 2, v33
	v_fmac_f32_e32 v32, v0, v0
	v_xor_b32_e32 v34, 4, v33
	s_nop 1
	v_mov_b32_dpp v34, v32 quad_perm:[1,0,3,2] row_mask:0xf bank_mask:0xf
	v_mov_b32_e32 v67, 0x358637bd
	s_addc_u32 s37, s3, 0
	v_mov_b32_e32 v161, v177
	s_waitcnt lgkmcnt(0)
	v_add_f32_e32 v32, v32, v34
	v_xor_b32_e32 v34, 8, v33
	s_nop 1
	v_mov_b32_dpp v34, v32 quad_perm:[2,3,0,1] row_mask:0xf bank_mask:0xf
	s_waitcnt lgkmcnt(0)
	v_add_f32_e32 v32, v32, v34
	v_xor_b32_e32 v34, 16, v33
	s_nop 1
	v_mov_b32_dpp v34, v32 row_half_mirror row_mask:0xf bank_mask:0xf
	s_nop 1
	v_mov_b32_dpp v34, v34 quad_perm:[3,2,1,0] row_mask:0xf bank_mask:0xf
	v_xor_b32_e32 v33, 32, v33
	s_waitcnt lgkmcnt(0)
	v_add_f32_e32 v32, v32, v34
	s_nop 1
	v_mov_b32_dpp v33, v32 row_ror:8 row_mask:0xf bank_mask:0xf
	s_waitcnt lgkmcnt(0)
	v_add_f32_e32 v32, v32, v33
	v_fmamk_f32 v32, v32, 0x3c000000, v67
	v_cmp_gt_f32_e32 vcc, s30, v32
	v_mul_f32_e32 v33, 0x4f800000, v32
	s_nop 0
	v_cndmask_b32_e32 v32, v32, v33, vcc
	v_sqrt_f32_e32 v33, v32
	s_nop 0
	v_add_u32_e32 v34, -1, v33
	v_fma_f32 v35, -v34, v33, v32
	v_cmp_ge_f32_e64 s[4:5], 0, v35
	v_add_u32_e32 v35, 1, v33
	s_nop 0
	v_cndmask_b32_e64 v34, v33, v34, s[4:5]
	v_fma_f32 v33, -v35, v33, v32
	v_cmp_lt_f32_e64 s[4:5], 0, v33
	s_nop 1
	v_cndmask_b32_e64 v33, v34, v35, s[4:5]
	v_mul_f32_e32 v34, 0x37800000, v33
	v_cndmask_b32_e32 v33, v33, v34, vcc
	v_cmp_class_f32_e32 vcc, v32, v222
	s_nop 1
	v_cndmask_b32_e32 v32, v33, v32, vcc
	s_mov_b32 s2, -1
	v_rcp_f32_e32 v34, v32
	s_nop 0
	v_fma_f32 v33, -v32, v34, 1.0
	v_fma_f32 v33, v33, v34, v34
	v_div_fixup_f32 v32, v33, v32, 1.0
	v_mul_f32_e32 v33, v28, v32
	s_waitcnt vmcnt(0)
	v_mul_f32_e32 v41, v224, v33
	v_mul_f32_e32 v33, v24, v32
	v_mul_f32_e32 v44, v223, v33
	v_mul_f32_e32 v33, v12, v32
	v_mul_f32_e32 v40, v212, v33
	v_mul_f32_e32 v33, v8, v32
	v_mul_f32_e32 v45, v211, v33
	v_mul_f32_e32 v33, v20, v32
	v_mul_f32_e32 v46, v210, v33
	v_mul_f32_e32 v33, v16, v32
	v_mul_f32_e32 v47, v209, v33
	v_mul_f32_e32 v33, v4, v32
	v_mul_f32_e32 v32, v0, v32
	v_mul_f32_e32 v49, v207, v32
	v_and_b32_e32 v32, s14, v64
	v_mul_f32_e32 v48, v208, v33
	v_lshlrev_b32_e32 v32, 6, v32
	v_mov_b32_e32 v33, v177
	v_lshl_add_u64 v[32:33], v[32:33], 3, s[36:37]
	v_lshl_add_u64 v[36:37], v[32:33], 0, v[160:161]
	global_load_dwordx4 v[32:35], v[36:37], off offset:16
	s_nop 0
	global_load_dwordx4 v[36:39], v[36:37], off
	s_waitcnt vmcnt(0)
	v_mul_f32_e32 v42, v37, v40
	v_fma_f32 v42, v36, v41, -v42
	v_mul_f32_e32 v40, v36, v40
	v_mul_f32_e32 v36, v39, v45
	v_fma_f32 v43, v38, v44, -v36
	v_mul_f32_e32 v36, v33, v48
	v_fmac_f32_e32 v40, v37, v41
	v_mul_f32_e32 v41, v38, v45
	v_fma_f32 v38, v32, v46, -v36
	v_mul_f32_e32 v36, v32, v48
	v_mul_f32_e32 v32, v35, v49
	v_fmac_f32_e32 v41, v39, v44
	v_fma_f32 v39, v34, v47, -v32
	v_mul_f32_e32 v32, v25, v25
	v_fmac_f32_e32 v32, v29, v29
	v_fmac_f32_e32 v32, v13, v13
	v_fmac_f32_e32 v32, v9, v9
	v_mul_f32_e32 v37, v34, v49
	v_fmac_f32_e32 v32, v21, v21
	v_mbcnt_lo_u32_b32 v34, s2, 0
	v_fmac_f32_e32 v32, v17, v17
	v_mbcnt_hi_u32_b32 v34, s2, v34
	v_fmac_f32_e32 v32, v5, v5
	v_lshlrev_b32_e32 v34, 2, v34
	v_fmac_f32_e32 v37, v35, v47
	v_fmac_f32_e32 v32, v1, v1
	v_xor_b32_e32 v35, 4, v34
	s_nop 1
	v_mov_b32_dpp v35, v32 quad_perm:[1,0,3,2] row_mask:0xf bank_mask:0xf
	v_fmac_f32_e32 v36, v33, v46
	v_add_u32_e32 v33, 1, v64
	s_waitcnt lgkmcnt(0)
	v_add_f32_e32 v32, v32, v35
	v_xor_b32_e32 v35, 8, v34
	s_nop 1
	v_mov_b32_dpp v35, v32 quad_perm:[2,3,0,1] row_mask:0xf bank_mask:0xf
	s_waitcnt lgkmcnt(0)
	v_add_f32_e32 v32, v32, v35
	v_xor_b32_e32 v35, 16, v34
	s_nop 1
	v_mov_b32_dpp v35, v32 row_half_mirror row_mask:0xf bank_mask:0xf
	s_nop 1
	v_mov_b32_dpp v35, v35 quad_perm:[3,2,1,0] row_mask:0xf bank_mask:0xf
	v_xor_b32_e32 v34, 32, v34
	s_waitcnt lgkmcnt(0)
	v_add_f32_e32 v32, v32, v35
	s_nop 1
	v_mov_b32_dpp v34, v32 row_ror:8 row_mask:0xf bank_mask:0xf
	s_waitcnt lgkmcnt(0)
	v_add_f32_e32 v32, v32, v34
	v_fmamk_f32 v32, v32, 0x3c000000, v67
	v_cmp_gt_f32_e32 vcc, s30, v32
	v_mul_f32_e32 v34, 0x4f800000, v32
	s_nop 0
	v_cndmask_b32_e32 v32, v32, v34, vcc
	v_sqrt_f32_e32 v34, v32
	s_nop 0
	v_add_u32_e32 v35, -1, v34
	v_fma_f32 v44, -v35, v34, v32
	v_cmp_ge_f32_e64 s[4:5], 0, v44
	v_add_u32_e32 v44, 1, v34
	s_nop 0
	v_cndmask_b32_e64 v35, v34, v35, s[4:5]
	v_fma_f32 v34, -v44, v34, v32
	v_cmp_lt_f32_e64 s[4:5], 0, v34
	s_nop 1
	v_cndmask_b32_e64 v34, v35, v44, s[4:5]
	v_mul_f32_e32 v35, 0x37800000, v34
	v_cndmask_b32_e32 v34, v34, v35, vcc
	v_cmp_class_f32_e32 vcc, v32, v222
	s_nop 1
	v_cndmask_b32_e32 v32, v34, v32, vcc
	s_mov_b32 s2, -1
	v_rcp_f32_e32 v35, v32
	s_nop 0
	v_fma_f32 v34, -v32, v35, 1.0
	v_fma_f32 v34, v34, v35, v35
	v_div_fixup_f32 v32, v34, v32, 1.0
	v_mul_f32_e32 v34, v29, v32
	v_mul_f32_e32 v49, v224, v34
	v_mul_f32_e32 v34, v25, v32
	v_mul_f32_e32 v52, v223, v34
	v_mul_f32_e32 v34, v13, v32
	v_mul_f32_e32 v48, v212, v34
	v_mul_f32_e32 v34, v9, v32
	v_mul_f32_e32 v53, v211, v34
	v_mul_f32_e32 v34, v21, v32
	v_mul_f32_e32 v54, v210, v34
	v_mul_f32_e32 v34, v17, v32
	v_mul_f32_e32 v55, v209, v34
	v_mul_f32_e32 v34, v5, v32
	v_mul_f32_e32 v32, v1, v32
	v_mul_f32_e32 v57, v207, v32
	v_and_b32_e32 v32, s14, v33
	v_lshlrev_b32_e32 v32, 6, v32
	v_mov_b32_e32 v33, v177
	v_lshl_add_u64 v[32:33], v[32:33], 3, s[36:37]
	v_lshl_add_u64 v[44:45], v[32:33], 0, v[160:161]
	v_mul_f32_e32 v56, v208, v34
	global_load_dwordx4 v[32:35], v[44:45], off offset:16
	s_nop 0
	global_load_dwordx4 v[44:47], v[44:45], off
	s_waitcnt vmcnt(0)
; #define ATTT ((float2*)(kargs()->ws + O_ATTT))
; #define AQ ((bfraw*)(kargs()->ws + O_AQ))
; #define AK ((bfraw*)(kargs()->ws + O_AK))
; __global__ void __launch_bounds__(512) mega(Params p) {
;     ...
;                     const bool isk = c0 >= 7168; const float* nw = isk ? kn_w : qn_w; const float2* attt = ATTT;
; #pragma unroll
;                     for (int j = 0; j < 4; ++j) { const int pos = (r0 + j) & (seqlen - 1);
;                       float ss = 0;
; #pragma unroll
;                       for (int n = 0; n < 8; ++n) ss += a[n][j] * a[n][j];
;                       ss = red16(ss);
;                       const float rstd = 1.f / sqrtf(ss * (1.f / 128.f) + RMS_EPS);
; #pragma unroll
;                       for (int n = 0; n < 8; ++n) a[n][j] = a[n][j] * rstd * hv[n];
;                       const float4* tb = (const float4*)(attt + pos * 64 + fr * 4);
;                       const float4 t01 = tb[0], t23 = tb[1];
;                       const float2 csv[4] = {make_float2(t01.x, t01.y), make_float2(t01.z, t01.w), make_float2(t23.x, t23.y), make_float2(t23.z, t23.w)};
; #pragma unroll
;                       for (int hh = 0; hh < 2; ++hh)
; #pragma unroll
;                         for (int n = 0; n < 2; ++n) { const float2 cs = csv[hh * 2 + n];
;                           const float x1 = a[hh * 4 + n][j], x2 = a[hh * 4 + n + 2][j];
;                           a[hh * 4 + n][j] = x1 * cs.x - x2 * cs.y; a[hh * 4 + n + 2][j] = x1 * cs.y + x2 * cs.x; } }
;                     if (isk) store_nat_m(AK + (long)r0 * 256 + (c0 - 7168), 256, a, fr);
;                     else store_nat_m(AQ + (long)r0 * 1024 + (c0 - 6144), 1024, a, fr);
	v_mul_f32_e32 v50, v45, v48
	v_fma_f32 v50, v44, v49, -v50
	v_mul_f32_e32 v48, v44, v48
	v_mul_f32_e32 v44, v47, v53
	v_fma_f32 v51, v46, v52, -v44
	v_mul_f32_e32 v44, v33, v56
	v_fmac_f32_e32 v48, v45, v49
	v_mul_f32_e32 v49, v46, v53
	v_fma_f32 v46, v32, v54, -v44
	v_mul_f32_e32 v44, v32, v56
	v_mul_f32_e32 v32, v35, v57
	v_fmac_f32_e32 v49, v47, v52
	v_fma_f32 v47, v34, v55, -v32
	v_mul_f32_e32 v32, v26, v26
	v_fmac_f32_e32 v32, v30, v30
	v_fmac_f32_e32 v32, v14, v14
	v_fmac_f32_e32 v32, v10, v10
	v_mul_f32_e32 v45, v34, v57
	v_fmac_f32_e32 v32, v22, v22
	v_mbcnt_lo_u32_b32 v34, s2, 0
	v_fmac_f32_e32 v32, v18, v18
	v_mbcnt_hi_u32_b32 v34, s2, v34
	v_fmac_f32_e32 v32, v6, v6
	v_lshlrev_b32_e32 v34, 2, v34
	v_fmac_f32_e32 v45, v35, v55
	v_fmac_f32_e32 v32, v2, v2
	v_xor_b32_e32 v35, 4, v34
	s_nop 1
	v_mov_b32_dpp v35, v32 quad_perm:[1,0,3,2] row_mask:0xf bank_mask:0xf
	v_fmac_f32_e32 v44, v33, v54
	v_add_u32_e32 v33, 2, v64
	s_waitcnt lgkmcnt(0)
	v_add_f32_e32 v32, v32, v35
	v_xor_b32_e32 v35, 8, v34
	s_nop 1
	v_mov_b32_dpp v35, v32 quad_perm:[2,3,0,1] row_mask:0xf bank_mask:0xf
	s_waitcnt lgkmcnt(0)
	v_add_f32_e32 v32, v32, v35
	v_xor_b32_e32 v35, 16, v34
	s_nop 1
	v_mov_b32_dpp v35, v32 row_half_mirror row_mask:0xf bank_mask:0xf
	s_nop 1
	v_mov_b32_dpp v35, v35 quad_perm:[3,2,1,0] row_mask:0xf bank_mask:0xf
	v_xor_b32_e32 v34, 32, v34
	s_waitcnt lgkmcnt(0)
	v_add_f32_e32 v32, v32, v35
	s_nop 1
	v_mov_b32_dpp v34, v32 row_ror:8 row_mask:0xf bank_mask:0xf
	s_waitcnt lgkmcnt(0)
	v_add_f32_e32 v32, v32, v34
	v_fmamk_f32 v32, v32, 0x3c000000, v67
	v_cmp_gt_f32_e32 vcc, s30, v32
	v_mul_f32_e32 v34, 0x4f800000, v32
	s_nop 0
	v_cndmask_b32_e32 v32, v32, v34, vcc
	v_sqrt_f32_e32 v34, v32
	s_nop 0
	v_add_u32_e32 v35, -1, v34
	v_fma_f32 v52, -v35, v34, v32
	v_cmp_ge_f32_e64 s[4:5], 0, v52
	v_add_u32_e32 v52, 1, v34
	s_nop 0
	v_cndmask_b32_e64 v35, v34, v35, s[4:5]
	v_fma_f32 v34, -v52, v34, v32
	v_cmp_lt_f32_e64 s[4:5], 0, v34
	s_nop 1
	v_cndmask_b32_e64 v34, v35, v52, s[4:5]
	v_mul_f32_e32 v35, 0x37800000, v34
	v_cndmask_b32_e32 v34, v34, v35, vcc
	v_cmp_class_f32_e32 vcc, v32, v222
	s_nop 1
	v_cndmask_b32_e32 v32, v34, v32, vcc
	s_mov_b32 s2, -1
	v_rcp_f32_e32 v35, v32
	s_nop 0
	v_fma_f32 v34, -v32, v35, 1.0
	v_fma_f32 v34, v34, v35, v35
	v_div_fixup_f32 v32, v34, v32, 1.0
	v_mul_f32_e32 v34, v30, v32
	v_mul_f32_e32 v57, v224, v34
	v_mul_f32_e32 v34, v26, v32
	v_mul_f32_e32 v60, v223, v34
	v_mul_f32_e32 v34, v14, v32
	v_mul_f32_e32 v56, v212, v34
	v_mul_f32_e32 v34, v10, v32
	v_mul_f32_e32 v61, v211, v34
	v_mul_f32_e32 v34, v22, v32
	v_mul_f32_e32 v62, v210, v34
	v_mul_f32_e32 v34, v18, v32
	v_mul_f32_e32 v63, v209, v34
	v_mul_f32_e32 v34, v6, v32
	v_mul_f32_e32 v32, v2, v32
	v_mul_f32_e32 v66, v207, v32
	v_and_b32_e32 v32, s14, v33
	v_lshlrev_b32_e32 v32, 6, v32
	v_mov_b32_e32 v33, v177
	v_lshl_add_u64 v[32:33], v[32:33], 3, s[36:37]
	v_lshl_add_u64 v[52:53], v[32:33], 0, v[160:161]
	v_mul_f32_e32 v65, v208, v34
	global_load_dwordx4 v[32:35], v[52:53], off offset:16
	s_nop 0
	global_load_dwordx4 v[52:55], v[52:53], off
	s_waitcnt vmcnt(0)
	v_mul_f32_e32 v58, v53, v56
	v_fma_f32 v58, v52, v57, -v58
	v_mul_f32_e32 v56, v52, v56
	v_mul_f32_e32 v52, v55, v61
	v_fma_f32 v59, v54, v60, -v52
	v_mul_f32_e32 v52, v33, v65
	v_fmac_f32_e32 v56, v53, v57
	v_mul_f32_e32 v57, v54, v61
	v_fma_f32 v54, v32, v62, -v52
	v_mul_f32_e32 v52, v32, v65
	v_mul_f32_e32 v32, v35, v66
	v_fmac_f32_e32 v57, v55, v60
	v_fma_f32 v55, v34, v63, -v32
	v_mul_f32_e32 v32, v27, v27
	v_fmac_f32_e32 v32, v31, v31
	v_fmac_f32_e32 v32, v15, v15
	v_fmac_f32_e32 v32, v11, v11
	v_mul_f32_e32 v53, v34, v66
	v_fmac_f32_e32 v32, v23, v23
	v_mbcnt_lo_u32_b32 v34, s2, 0
	v_fmac_f32_e32 v32, v19, v19
	v_mbcnt_hi_u32_b32 v34, s2, v34
	v_fmac_f32_e32 v32, v7, v7
	v_lshlrev_b32_e32 v34, 2, v34
	v_fmac_f32_e32 v53, v35, v63
	v_fmac_f32_e32 v32, v3, v3
	v_xor_b32_e32 v35, 4, v34
	s_nop 1
	v_mov_b32_dpp v35, v32 quad_perm:[1,0,3,2] row_mask:0xf bank_mask:0xf
	v_fmac_f32_e32 v52, v33, v62
	v_add_u32_e32 v33, 3, v64
	s_waitcnt lgkmcnt(0)
	v_add_f32_e32 v32, v32, v35
	v_xor_b32_e32 v35, 8, v34
	s_nop 1
	v_mov_b32_dpp v35, v32 quad_perm:[2,3,0,1] row_mask:0xf bank_mask:0xf
	s_waitcnt lgkmcnt(0)
	v_add_f32_e32 v32, v32, v35
	v_xor_b32_e32 v35, 16, v34
	s_nop 1
	v_mov_b32_dpp v35, v32 row_half_mirror row_mask:0xf bank_mask:0xf
	s_nop 1
	v_mov_b32_dpp v35, v35 quad_perm:[3,2,1,0] row_mask:0xf bank_mask:0xf
	v_xor_b32_e32 v34, 32, v34
	s_waitcnt lgkmcnt(0)
	v_add_f32_e32 v32, v32, v35
	s_nop 1
	v_mov_b32_dpp v34, v32 row_ror:8 row_mask:0xf bank_mask:0xf
	s_waitcnt lgkmcnt(0)
	v_add_f32_e32 v32, v32, v34
	v_fmamk_f32 v32, v32, 0x3c000000, v67
	v_cmp_gt_f32_e32 vcc, s30, v32
	v_mul_f32_e32 v34, 0x4f800000, v32
	s_nop 0
	v_cndmask_b32_e32 v32, v32, v34, vcc
	v_sqrt_f32_e32 v34, v32
	s_nop 0
	v_add_u32_e32 v35, -1, v34
	v_fma_f32 v60, -v35, v34, v32
	v_cmp_ge_f32_e64 s[4:5], 0, v60
	v_add_u32_e32 v60, 1, v34
	s_nop 0
	v_cndmask_b32_e64 v35, v34, v35, s[4:5]
	v_fma_f32 v34, -v60, v34, v32
	v_cmp_lt_f32_e64 s[4:5], 0, v34
	s_nop 1
	v_cndmask_b32_e64 v34, v35, v60, s[4:5]
	v_mul_f32_e32 v35, 0x37800000, v34
	v_cndmask_b32_e32 v34, v34, v35, vcc
	v_cmp_class_f32_e32 vcc, v32, v222
	s_nop 1
	v_cndmask_b32_e32 v32, v34, v32, vcc
	s_mov_b64 s[2:3], -1
	v_rcp_f32_e32 v35, v32
	s_nop 0
	v_fma_f32 v34, -v32, v35, 1.0
	v_fma_f32 v34, v34, v35, v35
	v_div_fixup_f32 v32, v34, v32, 1.0
	v_mul_f32_e32 v34, v31, v32
	v_mul_f32_e32 v62, v224, v34
	v_mul_f32_e32 v34, v27, v32
	v_mul_f32_e32 v65, v223, v34
	v_mul_f32_e32 v34, v15, v32
	v_mul_f32_e32 v63, v212, v34
	v_mul_f32_e32 v34, v11, v32
	v_mul_f32_e32 v66, v211, v34
	v_mul_f32_e32 v34, v23, v32
	v_mul_f32_e32 v72, v210, v34
	v_mul_f32_e32 v34, v19, v32
	v_mul_f32_e32 v73, v209, v34
	v_mul_f32_e32 v34, v7, v32
	v_mul_f32_e32 v32, v3, v32
	v_mul_f32_e32 v75, v207, v32
	v_and_b32_e32 v32, s14, v33
	v_lshlrev_b32_e32 v32, 6, v32
	v_mov_b32_e32 v33, v177
	v_lshl_add_u64 v[32:33], v[32:33], 3, s[36:37]
	v_lshl_add_u64 v[60:61], v[32:33], 0, v[160:161]
	v_mul_f32_e32 v74, v208, v34
	global_load_dwordx4 v[32:35], v[60:61], off offset:16
	global_load_dwordx4 v[68:71], v[60:61], off
	s_waitcnt vmcnt(0)
	v_mul_f32_e32 v60, v69, v63
	v_fma_f32 v67, v68, v62, -v60
	v_mul_f32_e32 v60, v71, v66
	v_mul_f32_e32 v63, v68, v63
	v_fma_f32 v68, v70, v65, -v60
	v_mul_f32_e32 v60, v33, v74
	v_fma_f32 v61, v32, v72, -v60
	v_mul_f32_e32 v60, v32, v74
	v_mul_f32_e32 v32, v35, v75
	v_fmac_f32_e32 v63, v69, v62
	v_fma_f32 v62, v34, v73, -v32
	v_and_b32_e32 v32, 1, v203
	v_mul_f32_e32 v66, v70, v66
	v_mul_f32_e32 v34, v34, v75
	v_cmp_eq_u32_e32 vcc, 0, v32
	v_cmp_eq_u32_e64 s[4:5], 1, v32
	v_add_u32_e32 v32, 15, v202
	v_fmac_f32_e32 v66, v71, v65
	v_fmac_f32_e32 v60, v33, v72
	v_fmac_f32_e32 v34, v35, v73
	v_ashrrev_i32_e32 v65, 31, v64
	v_cndmask_b32_e32 v35, v32, v202, vcc
	v_cndmask_b32_e32 v69, v42, v43, vcc
	s_and_b64 vcc, exec, s[6:7]
	s_cbranch_vccz .LBB0_2125
; DEVFI float dpp_xor1(float x) { return __int_as_float(__builtin_amdgcn_update_dpp(0, __float_as_int(x), 0xB1, 0xF, 0xF, true)); }
; DEVFI void store_nat_m(bfraw* base, long ld, f32x4 (&a)[8], int fr) {
;   const bool odd = fr & 1;
;   bfraw* p0 = base + (odd ? 15 + fr : fr);
; #pragma unroll
;   for (int j = 0; j < 4; ++j)
; #pragma unroll
;     for (int n0 = 0; n0 < 8; n0 += 2) { const float own0 = a[n0][j], own1 = a[n0 + 1][j];
;       const float recv = dpp_xor1(odd ? own0 : own1);
;       const unsigned pk = odd ? cvtpk(recv, own1) : cvtpk(own0, recv);
;       *reinterpret_cast<unsigned*>(p0 + (long)j * ld + n0 * 16) = pk; }
	s_mov_b64 s[2:3], s[0:1]
	s_load_dwordx2 s[2:3], s[2:3], 0xe8
	v_mov_b32_dpp v32, v69 quad_perm:[1,0,3,2] row_mask:0xf bank_mask:0xf bound_ctrl:1
	s_and_saveexec_b64 s[6:7], s[4:5]
	s_xor_b64 s[6:7], exec, s[6:7]
	s_cbranch_execz .LBB0_2062
	v_cvt_pk_bf16_f32 v70, v32, v43

; DEVFI float gelu_tanh(float x) {
;   float u = 0.7978845608028654f * (x + 0.044715f * x * x * x);
;   float t = __expf(2.f * u);
;   float th = 1.f - 2.f / (t + 1.f);
;   return 0.5f * x * (1.f + th);
; }
; __global__ void __launch_bounds__(512) mega(Params p) {
;     ...
;                   } else if (c0 < 6144) {
; #pragma unroll
;                     for (int n = 0; n < 8; ++n)
; #pragma unroll
;                       for (int j = 0; j < 4; ++j) a[n][j] = gelu_tanh(a[n][j]);
.LBB0_2192:
	s_andn2_b64 vcc, exec, s[2:3]
	s_cbranch_vccnz .LBB0_2270
	v_mul_f32_e32 v32, 0x3d372713, v28
	v_mul_f32_e32 v33, 0x3d372713, v24
	v_mul_f32_e32 v32, v28, v32
	v_mul_f32_e32 v33, v24, v33
	v_fma_f32 v32, v28, v32, v28
	v_fma_f32 v33, v24, v33, v24
	v_mul_f32_e32 v32, 0x3f4c422a, v32
	v_mul_f32_e32 v33, 0x3f4c422a, v33
	v_add_f32_e32 v32, v32, v32
	v_add_f32_e32 v33, v33, v33
	v_mul_f32_e32 v32, 0x3fb8aa3b, v32
	v_mul_f32_e32 v33, 0x3fb8aa3b, v33
	v_exp_f32_e32 v34, v32
	v_exp_f32_e32 v35, v33
	v_mul_f32_e32 v32, 0x3d372713, v29
	v_mul_f32_e32 v32, v29, v32
	v_fma_f32 v32, v29, v32, v29
	v_pk_add_f32 v[34:35], v[34:35], 1.0 op_sel_hi:[1,0]
	v_mul_f32_e32 v32, 0x3f4c422a, v32
	v_add_f32_e32 v32, v32, v32
	v_mul_f32_e32 v32, 0x3fb8aa3b, v32
	v_exp_f32_e32 v36, v32
	v_rcp_f32_e32 v37, v35
	s_nop 0
	v_fma_f32 v33, -v35, v37, 1.0
	v_fma_f32 v37, v33, v37, v37
	v_add_f32_e32 v33, v37, v37
	v_div_fixup_f32 v35, v33, v35, 2.0
	v_mul_f32_e32 v32, 0x3d372713, v30
	v_mul_f32_e32 v32, v30, v32
	v_fma_f32 v32, v30, v32, v30
	v_rcp_f32_e32 v37, v34
	s_nop 0
	v_fma_f32 v33, -v34, v37, 1.0
	v_fma_f32 v37, v33, v37, v37
	v_add_f32_e32 v33, v37, v37
	v_div_fixup_f32 v34, v33, v34, 2.0
	v_mul_f32_e32 v33, 0x3d372713, v25
	v_mul_f32_e32 v33, v25, v33
	v_fma_f32 v33, v25, v33, v25
	v_mul_f32_e32 v33, 0x3f4c422a, v33
	v_add_f32_e32 v33, v33, v33
	v_mul_f32_e32 v33, 0x3fb8aa3b, v33
	v_exp_f32_e32 v37, v33
	v_pk_add_f32 v[34:35], v[34:35], 1.0 op_sel_hi:[1,0] neg_lo:[1,0] neg_hi:[1,0]
	v_mov_b32_e32 v40, v28
	v_mov_b32_e32 v41, v24
	v_pk_mul_f32 v[40:41], v[40:41], 0.5 op_sel_hi:[1,0]
	v_pk_add_f32 v[34:35], v[34:35], 1.0 op_sel_hi:[1,0]
	v_mul_f32_e32 v32, 0x3f4c422a, v32
	v_pk_mul_f32 v[40:41], v[40:41], v[34:35]
	v_pk_add_f32 v[34:35], v[36:37], 1.0 op_sel_hi:[1,0]
	v_add_f32_e32 v32, v32, v32
	v_mul_f32_e32 v32, 0x3fb8aa3b, v32
	v_exp_f32_e32 v38, v32
	v_mul_f32_e32 v32, 0x3d372713, v31
	v_rcp_f32_e32 v36, v35
	s_nop 0
	v_fma_f32 v33, -v35, v36, 1.0
	v_fma_f32 v36, v33, v36, v36
	v_add_f32_e32 v33, v36, v36
	v_div_fixup_f32 v35, v33, v35, 2.0
	v_mul_f32_e32 v32, v31, v32
	v_fma_f32 v32, v31, v32, v31
	v_mul_f32_e32 v32, 0x3f4c422a, v32
	v_rcp_f32_e32 v36, v34
	s_nop 0
	v_fma_f32 v33, -v34, v36, 1.0
	v_fma_f32 v36, v33, v36, v36
	v_add_f32_e32 v33, v36, v36
	v_div_fixup_f32 v34, v33, v34, 2.0
	v_mul_f32_e32 v33, 0x3d372713, v26
	v_mul_f32_e32 v33, v26, v33
	v_fma_f32 v33, v26, v33, v26
	v_mul_f32_e32 v33, 0x3f4c422a, v33
	v_add_f32_e32 v33, v33, v33
	v_mul_f32_e32 v33, 0x3fb8aa3b, v33
	v_exp_f32_e32 v39, v33
	v_pk_add_f32 v[34:35], v[34:35], 1.0 op_sel_hi:[1,0] neg_lo:[1,0] neg_hi:[1,0]
	v_mov_b32_e32 v36, v29
	v_mov_b32_e32 v37, v25
	v_pk_mul_f32 v[36:37], v[36:37], 0.5 op_sel_hi:[1,0]
	v_pk_add_f32 v[34:35], v[34:35], 1.0 op_sel_hi:[1,0]
	v_add_f32_e32 v32, v32, v32
	v_pk_mul_f32 v[36:37], v[36:37], v[34:35]
	v_pk_add_f32 v[34:35], v[38:39], 1.0 op_sel_hi:[1,0]
	v_mul_f32_e32 v32, 0x3fb8aa3b, v32
	v_exp_f32_e32 v32, v32
	s_mov_b64 s[6:7], -1
	s_cmpk_lt_u32 s26, 0x1400
	v_rcp_f32_e32 v38, v35
	s_nop 0
	v_fma_f32 v33, -v35, v38, 1.0
	v_fma_f32 v38, v33, v38, v38
	v_add_f32_e32 v33, v38, v38
	v_div_fixup_f32 v35, v33, v35, 2.0
	s_nop 0
	v_rcp_f32_e32 v38, v34
	s_nop 0
	v_fma_f32 v33, -v34, v38, 1.0
	v_fma_f32 v38, v33, v38, v38
	v_add_f32_e32 v33, v38, v38
	v_div_fixup_f32 v34, v33, v34, 2.0
	v_mul_f32_e32 v33, 0x3d372713, v27
	v_mul_f32_e32 v33, v27, v33
	v_fma_f32 v33, v27, v33, v27
	v_mul_f32_e32 v33, 0x3f4c422a, v33
	v_add_f32_e32 v33, v33, v33
	v_mul_f32_e32 v33, 0x3fb8aa3b, v33
	v_exp_f32_e32 v33, v33
	v_pk_add_f32 v[34:35], v[34:35], 1.0 op_sel_hi:[1,0] neg_lo:[1,0] neg_hi:[1,0]
	v_mov_b32_e32 v38, v30
	v_mov_b32_e32 v39, v26
	v_pk_mul_f32 v[38:39], v[38:39], 0.5 op_sel_hi:[1,0]
	v_pk_add_f32 v[34:35], v[34:35], 1.0 op_sel_hi:[1,0]
	v_pk_add_f32 v[32:33], v[32:33], 1.0 op_sel_hi:[1,0]
	v_pk_mul_f32 v[34:35], v[38:39], v[34:35]
	s_nop 0
	v_rcp_f32_e32 v39, v33
	s_nop 0
	v_fma_f32 v38, -v33, v39, 1.0
	v_fma_f32 v39, v38, v39, v39
	v_add_f32_e32 v38, v39, v39
	v_div_fixup_f32 v33, v38, v33, 2.0
	s_nop 0
	v_rcp_f32_e32 v39, v32
	s_nop 0
	v_fma_f32 v38, -v32, v39, 1.0
	v_fma_f32 v39, v38, v39, v39
	v_add_f32_e32 v38, v39, v39
	v_div_fixup_f32 v32, v38, v32, 2.0
	v_pk_add_f32 v[32:33], v[32:33], 1.0 op_sel_hi:[1,0] neg_lo:[1,0] neg_hi:[1,0]
	v_mov_b32_e32 v38, v31
	v_mov_b32_e32 v39, v27
	v_pk_mul_f32 v[38:39], v[38:39], 0.5 op_sel_hi:[1,0]
	v_pk_add_f32 v[32:33], v[32:33], 1.0 op_sel_hi:[1,0]
	s_nop 0
	v_pk_mul_f32 v[32:33], v[38:39], v[32:33]
	v_mul_f32_e32 v38, 0x3d372713, v12
	v_mul_f32_e32 v38, v12, v38
	v_fma_f32 v38, v12, v38, v12
	v_mul_f32_e32 v38, 0x3f4c422a, v38
	v_add_f32_e32 v38, v38, v38
	v_mul_f32_e32 v38, 0x3fb8aa3b, v38
	v_exp_f32_e32 v38, v38
	s_nop 0
	v_add_f32_e32 v38, 1.0, v38
	s_nop 0
	v_rcp_f32_e32 v42, v38
	s_nop 0
	v_fma_f32 v39, -v38, v42, 1.0
	v_fma_f32 v42, v39, v42, v42
	v_add_f32_e32 v39, v42, v42
	v_div_fixup_f32 v38, v39, v38, 2.0
	v_sub_f32_e32 v38, 1.0, v38
	v_mul_f32_e32 v39, 0.5, v12
	v_add_f32_e32 v38, 1.0, v38
	v_mul_f32_e32 v48, v39, v38
	v_mul_f32_e32 v38, 0x3d372713, v13
	v_mul_f32_e32 v38, v13, v38
	v_fma_f32 v38, v13, v38, v13
	v_mul_f32_e32 v38, 0x3f4c422a, v38
	v_add_f32_e32 v38, v38, v38
	v_mul_f32_e32 v38, 0x3fb8aa3b, v38
	v_exp_f32_e32 v38, v38
	s_nop 0
	v_add_f32_e32 v38, 1.0, v38
	s_nop 0
	v_rcp_f32_e32 v42, v38
	s_nop 0
	v_fma_f32 v39, -v38, v42, 1.0
	v_fma_f32 v42, v39, v42, v42
	v_add_f32_e32 v39, v42, v42
	v_div_fixup_f32 v38, v39, v38, 2.0
	v_sub_f32_e32 v38, 1.0, v38
	v_mul_f32_e32 v39, 0.5, v13
	v_add_f32_e32 v38, 1.0, v38
	v_mul_f32_e32 v44, v39, v38
	v_mul_f32_e32 v38, 0x3d372713, v14
; DEVFI float gelu_tanh(float x) {
;   float u = 0.7978845608028654f * (x + 0.044715f * x * x * x);
;   float t = __expf(2.f * u);
;   float th = 1.f - 2.f / (t + 1.f);
;   return 0.5f * x * (1.f + th);
; }
; __global__ void __launch_bounds__(512) mega(Params p) {
;     ...
;                       for (int j = 0; j < 4; ++j) a[n][j] = gelu_tanh(a[n][j]);
	v_mul_f32_e32 v38, v14, v38
	v_fma_f32 v38, v14, v38, v14
	v_mul_f32_e32 v38, 0x3f4c422a, v38
	v_add_f32_e32 v38, v38, v38
	v_mul_f32_e32 v38, 0x3fb8aa3b, v38
	v_exp_f32_e32 v38, v38
	s_nop 0
	v_add_f32_e32 v38, 1.0, v38
	s_nop 0
	v_rcp_f32_e32 v42, v38
	s_nop 0
	v_fma_f32 v39, -v38, v42, 1.0
	v_fma_f32 v42, v39, v42, v42
	v_add_f32_e32 v39, v42, v42
	v_div_fixup_f32 v38, v39, v38, 2.0
	v_sub_f32_e32 v38, 1.0, v38
	v_mul_f32_e32 v39, 0.5, v14
	v_add_f32_e32 v38, 1.0, v38
	v_mul_f32_e32 v42, v39, v38
	v_mul_f32_e32 v38, 0x3d372713, v15
	v_mul_f32_e32 v38, v15, v38
	v_fma_f32 v38, v15, v38, v15
	v_mul_f32_e32 v38, 0x3f4c422a, v38
	v_add_f32_e32 v38, v38, v38
	v_mul_f32_e32 v38, 0x3fb8aa3b, v38
	v_exp_f32_e32 v38, v38
	s_nop 0
	v_add_f32_e32 v38, 1.0, v38
	s_nop 0
	v_rcp_f32_e32 v43, v38
	s_nop 0
	v_fma_f32 v39, -v38, v43, 1.0
	v_fma_f32 v43, v39, v43, v43
	v_add_f32_e32 v39, v43, v43
	v_div_fixup_f32 v38, v39, v38, 2.0
	v_sub_f32_e32 v38, 1.0, v38
	v_mul_f32_e32 v39, 0.5, v15
	v_add_f32_e32 v38, 1.0, v38
	v_mul_f32_e32 v38, v39, v38
	v_mul_f32_e32 v39, 0x3d372713, v8
	v_mul_f32_e32 v39, v8, v39
	v_fma_f32 v39, v8, v39, v8
	v_mul_f32_e32 v39, 0x3f4c422a, v39
	v_add_f32_e32 v39, v39, v39
	v_mul_f32_e32 v39, 0x3fb8aa3b, v39
	v_exp_f32_e32 v39, v39
	s_nop 0
	v_add_f32_e32 v39, 1.0, v39
	s_nop 0
	v_rcp_f32_e32 v45, v39
	s_nop 0
	v_fma_f32 v43, -v39, v45, 1.0
	v_fma_f32 v45, v43, v45, v45
	v_add_f32_e32 v43, v45, v45
	v_div_fixup_f32 v39, v43, v39, 2.0
	v_sub_f32_e32 v39, 1.0, v39
	v_mul_f32_e32 v43, 0.5, v8
	v_add_f32_e32 v39, 1.0, v39
	v_mul_f32_e32 v58, v43, v39
	v_mul_f32_e32 v39, 0x3d372713, v9
	v_mul_f32_e32 v39, v9, v39
	v_fma_f32 v39, v9, v39, v9
	v_mul_f32_e32 v39, 0x3f4c422a, v39
	v_add_f32_e32 v39, v39, v39
	v_mul_f32_e32 v39, 0x3fb8aa3b, v39
	v_exp_f32_e32 v39, v39
	s_nop 0
	v_add_f32_e32 v39, 1.0, v39
	s_nop 0
	v_rcp_f32_e32 v45, v39
	s_nop 0
	v_fma_f32 v43, -v39, v45, 1.0
	v_fma_f32 v45, v43, v45, v45
	v_add_f32_e32 v43, v45, v45
	v_div_fixup_f32 v39, v43, v39, 2.0
	v_sub_f32_e32 v39, 1.0, v39
	v_mul_f32_e32 v43, 0.5, v9
	v_add_f32_e32 v39, 1.0, v39
	v_mul_f32_e32 v54, v43, v39
	v_mul_f32_e32 v39, 0x3d372713, v10
	v_mul_f32_e32 v39, v10, v39
	v_fma_f32 v39, v10, v39, v10
	v_mul_f32_e32 v39, 0x3f4c422a, v39
	v_add_f32_e32 v39, v39, v39
	v_mul_f32_e32 v39, 0x3fb8aa3b, v39
	v_exp_f32_e32 v39, v39
	s_nop 0
	v_add_f32_e32 v39, 1.0, v39
	s_nop 0
	v_rcp_f32_e32 v45, v39
	s_nop 0
	v_fma_f32 v43, -v39, v45, 1.0
	v_fma_f32 v45, v43, v45, v45
	v_add_f32_e32 v43, v45, v45
	v_div_fixup_f32 v39, v43, v39, 2.0
	v_sub_f32_e32 v39, 1.0, v39
	v_mul_f32_e32 v43, 0.5, v10
	v_add_f32_e32 v39, 1.0, v39
	v_mul_f32_e32 v50, v43, v39
	v_mul_f32_e32 v39, 0x3d372713, v11
	v_mul_f32_e32 v39, v11, v39
	v_fma_f32 v39, v11, v39, v11
	v_mul_f32_e32 v39, 0x3f4c422a, v39
	v_add_f32_e32 v39, v39, v39
	v_mul_f32_e32 v39, 0x3fb8aa3b, v39
	v_exp_f32_e32 v39, v39
	s_nop 0
	v_add_f32_e32 v39, 1.0, v39
	s_nop 0
	v_rcp_f32_e32 v45, v39
	s_nop 0
	v_fma_f32 v43, -v39, v45, 1.0
	v_fma_f32 v45, v43, v45, v45
	v_add_f32_e32 v43, v45, v45
	v_div_fixup_f32 v39, v43, v39, 2.0
	v_sub_f32_e32 v39, 1.0, v39
	v_mul_f32_e32 v43, 0.5, v11
	v_add_f32_e32 v39, 1.0, v39
	v_mul_f32_e32 v46, v43, v39
	v_mul_f32_e32 v39, 0x3d372713, v20
	v_mul_f32_e32 v39, v20, v39
	v_fma_f32 v39, v20, v39, v20
	v_mul_f32_e32 v39, 0x3f4c422a, v39
	v_add_f32_e32 v39, v39, v39
	v_mul_f32_e32 v39, 0x3fb8aa3b, v39
	v_exp_f32_e32 v39, v39
	s_nop 0
	v_add_f32_e32 v39, 1.0, v39
	s_nop 0
	v_rcp_f32_e32 v45, v39
	s_nop 0
	v_fma_f32 v43, -v39, v45, 1.0
	v_fma_f32 v45, v43, v45, v45
	v_add_f32_e32 v43, v45, v45
	v_div_fixup_f32 v39, v43, v39, 2.0
	v_sub_f32_e32 v39, 1.0, v39
	v_mul_f32_e32 v43, 0.5, v20
	v_add_f32_e32 v39, 1.0, v39
	v_mul_f32_e32 v66, v43, v39
	v_mul_f32_e32 v39, 0x3d372713, v21
	v_mul_f32_e32 v39, v21, v39
	v_fma_f32 v39, v21, v39, v21
	v_mul_f32_e32 v39, 0x3f4c422a, v39
	v_add_f32_e32 v39, v39, v39
	v_mul_f32_e32 v39, 0x3fb8aa3b, v39
	v_exp_f32_e32 v39, v39
	s_nop 0
	v_add_f32_e32 v39, 1.0, v39
	s_nop 0
	v_rcp_f32_e32 v45, v39
	s_nop 0
	v_fma_f32 v43, -v39, v45, 1.0
	v_fma_f32 v45, v43, v45, v45
	v_add_f32_e32 v43, v45, v45
	v_div_fixup_f32 v39, v43, v39, 2.0
	v_sub_f32_e32 v39, 1.0, v39
	v_mul_f32_e32 v43, 0.5, v21
	v_add_f32_e32 v39, 1.0, v39
	v_mul_f32_e32 v60, v43, v39
	v_mul_f32_e32 v39, 0x3d372713, v22
	v_mul_f32_e32 v39, v22, v39
	v_fma_f32 v39, v22, v39, v22
	v_mul_f32_e32 v39, 0x3f4c422a, v39
	v_add_f32_e32 v39, v39, v39
	v_mul_f32_e32 v39, 0x3fb8aa3b, v39
	v_exp_f32_e32 v39, v39
	s_nop 0
	v_add_f32_e32 v39, 1.0, v39
	s_nop 0
	v_rcp_f32_e32 v45, v39
	s_nop 0
	v_fma_f32 v43, -v39, v45, 1.0
	v_fma_f32 v45, v43, v45, v45
	v_add_f32_e32 v43, v45, v45
	v_div_fixup_f32 v39, v43, v39, 2.0
	v_sub_f32_e32 v39, 1.0, v39
	v_mul_f32_e32 v43, 0.5, v22
	v_add_f32_e32 v39, 1.0, v39
	v_mul_f32_e32 v56, v43, v39
	v_mul_f32_e32 v39, 0x3d372713, v23
	v_mul_f32_e32 v39, v23, v39
	v_fma_f32 v39, v23, v39, v23
	v_mul_f32_e32 v39, 0x3f4c422a, v39
	v_add_f32_e32 v39, v39, v39
	v_mul_f32_e32 v39, 0x3fb8aa3b, v39
	v_exp_f32_e32 v39, v39
	s_nop 0
	v_add_f32_e32 v39, 1.0, v39
	s_nop 0
	v_rcp_f32_e32 v45, v39
	s_nop 0
	v_fma_f32 v43, -v39, v45, 1.0
	v_fma_f32 v45, v43, v45, v45
	v_add_f32_e32 v43, v45, v45
	v_div_fixup_f32 v39, v43, v39, 2.0
	v_sub_f32_e32 v39, 1.0, v39
	v_mul_f32_e32 v43, 0.5, v23
	v_add_f32_e32 v39, 1.0, v39
	v_mul_f32_e32 v52, v43, v39
	v_mul_f32_e32 v39, 0x3d372713, v16
	v_mul_f32_e32 v39, v16, v39
	v_fma_f32 v39, v16, v39, v16
	v_mul_f32_e32 v39, 0x3f4c422a, v39
	v_add_f32_e32 v39, v39, v39
	v_mul_f32_e32 v39, 0x3fb8aa3b, v39
	v_exp_f32_e32 v39, v39
	s_nop 0
	v_add_f32_e32 v39, 1.0, v39
	s_nop 0
; DEVFI float gelu_tanh(float x) {
;   float u = 0.7978845608028654f * (x + 0.044715f * x * x * x);
;   float t = __expf(2.f * u);
;   float th = 1.f - 2.f / (t + 1.f);
;   return 0.5f * x * (1.f + th);
; }
; __global__ void __launch_bounds__(512) mega(Params p) {
;     ...
;                       for (int j = 0; j < 4; ++j) a[n][j] = gelu_tanh(a[n][j]);
	v_rcp_f32_e32 v45, v39
	s_nop 0
	v_fma_f32 v43, -v39, v45, 1.0
	v_fma_f32 v45, v43, v45, v45
	v_add_f32_e32 v43, v45, v45
	v_div_fixup_f32 v39, v43, v39, 2.0
	v_sub_f32_e32 v39, 1.0, v39
	v_mul_f32_e32 v43, 0.5, v16
	v_add_f32_e32 v39, 1.0, v39
	v_mul_f32_e32 v76, v43, v39
	v_mul_f32_e32 v39, 0x3d372713, v17
	v_mul_f32_e32 v39, v17, v39
	v_fma_f32 v39, v17, v39, v17
	v_mul_f32_e32 v39, 0x3f4c422a, v39
	v_add_f32_e32 v39, v39, v39
	v_mul_f32_e32 v39, 0x3fb8aa3b, v39
	v_exp_f32_e32 v39, v39
	s_nop 0
	v_add_f32_e32 v39, 1.0, v39
	s_nop 0
	v_rcp_f32_e32 v45, v39
	s_nop 0
	v_fma_f32 v43, -v39, v45, 1.0
	v_fma_f32 v45, v43, v45, v45
	v_add_f32_e32 v43, v45, v45
	v_div_fixup_f32 v39, v43, v39, 2.0
	v_sub_f32_e32 v39, 1.0, v39
	v_mul_f32_e32 v43, 0.5, v17
	v_add_f32_e32 v39, 1.0, v39
	v_mul_f32_e32 v72, v43, v39
	v_mul_f32_e32 v39, 0x3d372713, v18
	v_mul_f32_e32 v39, v18, v39
	v_fma_f32 v39, v18, v39, v18
	v_mul_f32_e32 v39, 0x3f4c422a, v39
	v_add_f32_e32 v39, v39, v39
	v_mul_f32_e32 v39, 0x3fb8aa3b, v39
	v_exp_f32_e32 v39, v39
	s_nop 0
	v_add_f32_e32 v39, 1.0, v39
	s_nop 0
	v_rcp_f32_e32 v45, v39
	s_nop 0
	v_fma_f32 v43, -v39, v45, 1.0
	v_fma_f32 v45, v43, v45, v45
	v_add_f32_e32 v43, v45, v45
	v_div_fixup_f32 v39, v43, v39, 2.0
	v_sub_f32_e32 v39, 1.0, v39
	v_mul_f32_e32 v43, 0.5, v18
	v_add_f32_e32 v39, 1.0, v39
	v_mul_f32_e32 v68, v43, v39
	v_mul_f32_e32 v39, 0x3d372713, v19
	v_mul_f32_e32 v39, v19, v39
	v_fma_f32 v39, v19, v39, v19
	v_mul_f32_e32 v39, 0x3f4c422a, v39
	v_add_f32_e32 v39, v39, v39
	v_mul_f32_e32 v39, 0x3fb8aa3b, v39
	v_exp_f32_e32 v39, v39
	s_nop 0
	v_add_f32_e32 v39, 1.0, v39
	s_nop 0
	v_rcp_f32_e32 v45, v39
	s_nop 0
	v_fma_f32 v43, -v39, v45, 1.0
	v_fma_f32 v45, v43, v45, v45
	v_add_f32_e32 v43, v45, v45
	v_div_fixup_f32 v39, v43, v39, 2.0
	v_sub_f32_e32 v39, 1.0, v39
	v_mul_f32_e32 v43, 0.5, v19
	v_add_f32_e32 v39, 1.0, v39
	v_mul_f32_e32 v62, v43, v39
	v_mul_f32_e32 v39, 0x3d372713, v4
	v_mul_f32_e32 v39, v4, v39
	v_fma_f32 v39, v4, v39, v4
	v_mul_f32_e32 v39, 0x3f4c422a, v39
	v_add_f32_e32 v39, v39, v39
	v_mul_f32_e32 v39, 0x3fb8aa3b, v39
	v_exp_f32_e32 v39, v39
	s_nop 0
	v_add_f32_e32 v39, 1.0, v39
	s_nop 0
	v_rcp_f32_e32 v45, v39
	s_nop 0
	v_fma_f32 v43, -v39, v45, 1.0
	v_fma_f32 v45, v43, v45, v45
	v_add_f32_e32 v43, v45, v45
	v_div_fixup_f32 v39, v43, v39, 2.0
	v_sub_f32_e32 v39, 1.0, v39
	v_mul_f32_e32 v43, 0.5, v4
	v_add_f32_e32 v39, 1.0, v39
	v_mul_f32_e32 v82, v43, v39
	v_mul_f32_e32 v39, 0x3d372713, v5
	v_mul_f32_e32 v39, v5, v39
	v_fma_f32 v39, v5, v39, v5
	v_mul_f32_e32 v39, 0x3f4c422a, v39
	v_add_f32_e32 v39, v39, v39
	v_mul_f32_e32 v39, 0x3fb8aa3b, v39
	v_exp_f32_e32 v39, v39
	s_nop 0
	v_add_f32_e32 v39, 1.0, v39
	s_nop 0
	v_rcp_f32_e32 v45, v39
	s_nop 0
	v_fma_f32 v43, -v39, v45, 1.0
	v_fma_f32 v45, v43, v45, v45
	v_add_f32_e32 v43, v45, v45
	v_div_fixup_f32 v39, v43, v39, 2.0
	v_sub_f32_e32 v39, 1.0, v39
	v_mul_f32_e32 v43, 0.5, v5
	v_add_f32_e32 v39, 1.0, v39
	v_mul_f32_e32 v78, v43, v39
	v_mul_f32_e32 v39, 0x3d372713, v6
	v_mul_f32_e32 v39, v6, v39
	v_fma_f32 v39, v6, v39, v6
	v_mul_f32_e32 v39, 0x3f4c422a, v39
	v_add_f32_e32 v39, v39, v39
	v_mul_f32_e32 v39, 0x3fb8aa3b, v39
	v_exp_f32_e32 v39, v39
	s_nop 0
	v_add_f32_e32 v39, 1.0, v39
	s_nop 0
	v_rcp_f32_e32 v45, v39
	s_nop 0
	v_fma_f32 v43, -v39, v45, 1.0
	v_fma_f32 v45, v43, v45, v45
	v_add_f32_e32 v43, v45, v45
	v_div_fixup_f32 v39, v43, v39, 2.0
	v_sub_f32_e32 v39, 1.0, v39
	v_mul_f32_e32 v43, 0.5, v6
	v_add_f32_e32 v39, 1.0, v39
	v_mul_f32_e32 v74, v43, v39
	v_mul_f32_e32 v39, 0x3d372713, v7
	v_mul_f32_e32 v39, v7, v39
	v_fma_f32 v39, v7, v39, v7
	v_mul_f32_e32 v39, 0x3f4c422a, v39
	v_add_f32_e32 v39, v39, v39
	v_mul_f32_e32 v39, 0x3fb8aa3b, v39
	v_exp_f32_e32 v39, v39
	s_nop 0
	v_add_f32_e32 v39, 1.0, v39
	s_nop 0
	v_rcp_f32_e32 v45, v39
	s_nop 0
	v_fma_f32 v43, -v39, v45, 1.0
	v_fma_f32 v45, v43, v45, v45
	v_add_f32_e32 v43, v45, v45
	v_div_fixup_f32 v39, v43, v39, 2.0
	v_sub_f32_e32 v39, 1.0, v39
	v_mul_f32_e32 v43, 0.5, v7
	v_add_f32_e32 v39, 1.0, v39
	v_mul_f32_e32 v70, v43, v39
	v_mul_f32_e32 v39, 0x3d372713, v0
	v_mul_f32_e32 v39, v0, v39
	v_fma_f32 v39, v0, v39, v0
	v_mul_f32_e32 v39, 0x3f4c422a, v39
	v_add_f32_e32 v39, v39, v39
	v_mul_f32_e32 v39, 0x3fb8aa3b, v39
	v_exp_f32_e32 v39, v39
	s_nop 0
	v_add_f32_e32 v39, 1.0, v39
	s_nop 0
	v_rcp_f32_e32 v45, v39
	s_nop 0
	v_fma_f32 v43, -v39, v45, 1.0
	v_fma_f32 v45, v43, v45, v45
	v_add_f32_e32 v43, v45, v45
	v_div_fixup_f32 v39, v43, v39, 2.0
	v_sub_f32_e32 v39, 1.0, v39
	v_mul_f32_e32 v43, 0.5, v0
	v_add_f32_e32 v39, 1.0, v39
	v_mul_f32_e32 v88, v43, v39
	v_mul_f32_e32 v39, 0x3d372713, v1
	v_mul_f32_e32 v39, v1, v39
	v_fma_f32 v39, v1, v39, v1
	v_mul_f32_e32 v39, 0x3f4c422a, v39
	v_add_f32_e32 v39, v39, v39
	v_mul_f32_e32 v39, 0x3fb8aa3b, v39
	v_exp_f32_e32 v39, v39
	s_nop 0
	v_add_f32_e32 v39, 1.0, v39
	s_nop 0
	v_rcp_f32_e32 v45, v39
	s_nop 0
	v_fma_f32 v43, -v39, v45, 1.0
	v_fma_f32 v45, v43, v45, v45
	v_add_f32_e32 v43, v45, v45
	v_div_fixup_f32 v39, v43, v39, 2.0
	v_sub_f32_e32 v39, 1.0, v39
	v_mul_f32_e32 v43, 0.5, v1
	v_add_f32_e32 v39, 1.0, v39
	v_mul_f32_e32 v86, v43, v39
	v_mul_f32_e32 v39, 0x3d372713, v2
	v_mul_f32_e32 v39, v2, v39
	v_fma_f32 v39, v2, v39, v2
	v_mul_f32_e32 v39, 0x3f4c422a, v39
	v_add_f32_e32 v39, v39, v39
	v_mul_f32_e32 v39, 0x3fb8aa3b, v39
	v_exp_f32_e32 v39, v39
	s_nop 0
	v_add_f32_e32 v39, 1.0, v39
	s_nop 0
	v_rcp_f32_e32 v45, v39
	s_nop 0
	v_fma_f32 v43, -v39, v45, 1.0
	v_fma_f32 v45, v43, v45, v45
	v_add_f32_e32 v43, v45, v45
	v_div_fixup_f32 v39, v43, v39, 2.0
	v_sub_f32_e32 v39, 1.0, v39
	v_mul_f32_e32 v43, 0.5, v2
	v_add_f32_e32 v39, 1.0, v39
	v_mul_f32_e32 v84, v43, v39
	v_mul_f32_e32 v39, 0x3d372713, v3
	v_mul_f32_e32 v39, v3, v39
	v_fma_f32 v39, v3, v39, v3
	v_mul_f32_e32 v39, 0x3f4c422a, v39
	v_add_f32_e32 v39, v39, v39
	v_mul_f32_e32 v39, 0x3fb8aa3b, v39
	v_exp_f32_e32 v39, v39
	s_nop 0
	v_add_f32_e32 v39, 1.0, v39
	s_nop 0
	v_rcp_f32_e32 v45, v39
	s_nop 0
	v_fma_f32 v43, -v39, v45, 1.0
	v_fma_f32 v45, v43, v45, v45
	v_add_f32_e32 v43, v45, v45
	v_div_fixup_f32 v39, v43, v39, 2.0
	v_sub_f32_e32 v39, 1.0, v39
	v_mul_f32_e32 v43, 0.5, v3
	v_add_f32_e32 v39, 1.0, v39
	v_mul_f32_e32 v80, v43, v39
	s_cbranch_scc1 .LBB0_2203
; #define SVSTAT ((float*)(kargs()->ws + O_SVSTAT))
; __global__ void __launch_bounds__(512) mega(Params p) {
;     ...
;                     if (c0 >= 5120) { float* stp = SVSTAT + (long)r0 * 16 + ((c0 - 5120) >> 7) * 2;
; #pragma unroll
;                       for (int j = 0; j < 4; ++j) { float s1 = 0, s2 = 0;
; #pragma unroll
;                         for (int n = 0; n < 8; ++n) { s1 += a[n][j]; s2 += a[n][j] * a[n][j]; }
;                         s1 = red16(s1); s2 = red16(s2);
;                         if (fr == 0) { stp[j * 16] = s1; stp[j * 16 + 1] = s2; } } }
	s_mov_b64 s[2:3], s[0:1]
	s_load_dwordx2 s[2:3], s[2:3], 0xe8
	v_ashrrev_i32_e32 v65, 31, v64
	v_lshlrev_b64 v[90:91], 6, v[64:65]
	v_add_u32_e32 v39, 0xffffec00, v176
	v_lshrrev_b32_e32 v92, 4, v39
	s_waitcnt lgkmcnt(0)
	v_lshl_add_u64 v[90:91], s[2:3], 0, v[90:91]
	v_mov_b32_e32 v93, v177
	v_lshl_add_u64 v[90:91], v[90:91], 0, v[92:93]
	v_mov_b32_e32 v92, v177
	v_mov_b32_e32 v93, v41
	v_pk_add_f32 v[92:93], v[40:41], v[92:93]
	v_pk_mul_f32 v[94:95], v[40:41], v[40:41]
	s_mov_b64 s[2:3], 0x3a720400
	v_mov_b32_e32 v93, v95
	v_pk_mov_b32 v[94:95], v[40:41], v[94:95] op_sel:[1,0]
	v_lshl_add_u64 v[90:91], v[90:91], 0, s[2:3]
	v_mul_f32_e32 v49, v48, v48
	s_mov_b32 s2, -1
	v_pk_add_f32 v[92:93], v[92:93], v[94:95]
	v_mul_f32_e32 v59, v58, v58
	v_pk_add_f32 v[92:93], v[92:93], v[48:49]
	v_mbcnt_lo_u32_b32 v39, s2, 0
	v_mul_f32_e32 v67, v66, v66
	v_mbcnt_hi_u32_b32 v39, s2, v39
	s_mov_b32 s2, -1
	v_pk_add_f32 v[92:93], v[92:93], v[58:59]
	v_mul_f32_e32 v77, v76, v76
	v_pk_add_f32 v[92:93], v[92:93], v[66:67]
	v_mbcnt_lo_u32_b32 v51, s2, 0
	v_mul_f32_e32 v83, v82, v82
	v_mbcnt_hi_u32_b32 v51, s2, v51
	v_pk_add_f32 v[92:93], v[92:93], v[76:77]
	v_mul_f32_e32 v89, v88, v88
	v_lshlrev_b32_e32 v39, 2, v39
	v_lshlrev_b32_e32 v51, 2, v51
	v_pk_add_f32 v[92:93], v[92:93], v[82:83]
	v_xor_b32_e32 v43, 4, v39
	v_xor_b32_e32 v53, 4, v51
	v_pk_add_f32 v[92:93], v[92:93], v[88:89]
	s_nop 1
	v_mov_b32_dpp v94, v92 quad_perm:[1,0,3,2] row_mask:0xf bank_mask:0xf
	s_nop 0
	v_mov_b32_dpp v95, v93 quad_perm:[1,0,3,2] row_mask:0xf bank_mask:0xf
	v_xor_b32_e32 v45, 8, v39
	v_xor_b32_e32 v55, 8, v51
	v_xor_b32_e32 v47, 16, v39
	v_xor_b32_e32 v57, 16, v51
	s_waitcnt lgkmcnt(0)
	v_pk_add_f32 v[92:93], v[92:93], v[94:95]
	s_nop 1
	v_mov_b32_dpp v94, v92 quad_perm:[2,3,0,1] row_mask:0xf bank_mask:0xf
	s_nop 0
	v_mov_b32_dpp v95, v93 quad_perm:[2,3,0,1] row_mask:0xf bank_mask:0xf
	v_xor_b32_e32 v39, 32, v39
	v_cmp_eq_u32_e32 vcc, 0, v202
	s_waitcnt lgkmcnt(0)
	v_pk_add_f32 v[92:93], v[92:93], v[94:95]
	s_nop 1
	v_mov_b32_dpp v94, v92 row_half_mirror row_mask:0xf bank_mask:0xf
	s_nop 1
	v_mov_b32_dpp v94, v94 quad_perm:[3,2,1,0] row_mask:0xf bank_mask:0xf
	v_mov_b32_dpp v95, v93 row_half_mirror row_mask:0xf bank_mask:0xf
	s_nop 1
	v_mov_b32_dpp v95, v95 quad_perm:[3,2,1,0] row_mask:0xf bank_mask:0xf
	s_waitcnt lgkmcnt(0)
	v_pk_add_f32 v[92:93], v[92:93], v[94:95]
	s_nop 1
	v_mov_b32_dpp v94, v92 row_ror:8 row_mask:0xf bank_mask:0xf
	v_xor_b32_e32 v39, 32, v51
	v_mov_b32_dpp v95, v93 row_ror:8 row_mask:0xf bank_mask:0xf
	s_and_saveexec_b64 s[2:3], vcc
	s_cbranch_execz .LBB0_2196
	s_waitcnt lgkmcnt(0)
	v_pk_add_f32 v[92:93], v[92:93], v[94:95]
	global_store_dwordx2 v[90:91], v[92:93], off
.LBB0_2196:
	s_or_b64 exec, exec, s[2:3]
	v_mov_b32_e32 v92, v177
	v_mov_b32_e32 v93, v37
	v_pk_add_f32 v[92:93], v[36:37], v[92:93]
	s_waitcnt lgkmcnt(0)
	v_pk_mul_f32 v[94:95], v[36:37], v[36:37]
	v_mul_f32_e32 v45, v44, v44
	v_mov_b32_e32 v93, v95
	v_pk_mov_b32 v[94:95], v[36:37], v[94:95] op_sel:[1,0]
	s_mov_b32 s2, -1
	v_pk_add_f32 v[92:93], v[92:93], v[94:95]
	v_mul_f32_e32 v55, v54, v54
	v_pk_add_f32 v[92:93], v[92:93], v[44:45]
	v_mbcnt_lo_u32_b32 v39, s2, 0
	v_mul_f32_e32 v61, v60, v60
	v_mbcnt_hi_u32_b32 v39, s2, v39
	s_mov_b32 s2, -1
	v_pk_add_f32 v[92:93], v[92:93], v[54:55]
	v_mul_f32_e32 v73, v72, v72
	v_pk_add_f32 v[92:93], v[92:93], v[60:61]
	v_mbcnt_lo_u32_b32 v47, s2, 0
	v_mul_f32_e32 v79, v78, v78
	v_mbcnt_hi_u32_b32 v47, s2, v47
	v_pk_add_f32 v[92:93], v[92:93], v[72:73]
	v_mul_f32_e32 v87, v86, v86
	v_lshlrev_b32_e32 v39, 2, v39
	v_lshlrev_b32_e32 v47, 2, v47
	v_pk_add_f32 v[92:93], v[92:93], v[78:79]
	v_xor_b32_e32 v43, 4, v39
	v_xor_b32_e32 v49, 4, v47
	v_pk_add_f32 v[92:93], v[92:93], v[86:87]
	s_nop 1
	v_mov_b32_dpp v94, v92 quad_perm:[1,0,3,2] row_mask:0xf bank_mask:0xf
	s_nop 0
	v_mov_b32_dpp v95, v93 quad_perm:[1,0,3,2] row_mask:0xf bank_mask:0xf
	v_xor_b32_e32 v43, 8, v39
	v_xor_b32_e32 v45, 8, v47
	s_waitcnt lgkmcnt(0)
	v_pk_add_f32 v[92:93], v[92:93], v[94:95]
	s_nop 1
	v_mov_b32_dpp v94, v92 quad_perm:[2,3,0,1] row_mask:0xf bank_mask:0xf
	s_nop 0
	v_mov_b32_dpp v95, v93 quad_perm:[2,3,0,1] row_mask:0xf bank_mask:0xf
	v_xor_b32_e32 v43, 16, v39
	v_xor_b32_e32 v45, 16, v47
	v_xor_b32_e32 v39, 32, v39
	s_waitcnt lgkmcnt(0)
	v_pk_add_f32 v[92:93], v[92:93], v[94:95]
	s_nop 1
	v_mov_b32_dpp v94, v92 row_half_mirror row_mask:0xf bank_mask:0xf
	s_nop 1
	v_mov_b32_dpp v94, v94 quad_perm:[3,2,1,0] row_mask:0xf bank_mask:0xf
	v_mov_b32_dpp v95, v93 row_half_mirror row_mask:0xf bank_mask:0xf
	s_nop 1
	v_mov_b32_dpp v95, v95 quad_perm:[3,2,1,0] row_mask:0xf bank_mask:0xf
	s_waitcnt lgkmcnt(0)
	v_pk_add_f32 v[92:93], v[92:93], v[94:95]
	s_nop 1
	v_mov_b32_dpp v94, v92 row_ror:8 row_mask:0xf bank_mask:0xf
	v_xor_b32_e32 v39, 32, v47
	v_mov_b32_dpp v95, v93 row_ror:8 row_mask:0xf bank_mask:0xf
	s_and_saveexec_b64 s[2:3], vcc
	s_cbranch_execz .LBB0_2198
	s_waitcnt lgkmcnt(0)
	v_pk_add_f32 v[92:93], v[92:93], v[94:95]
	global_store_dwordx2 v[90:91], v[92:93], off offset:64
; #define SVSTAT ((float*)(kargs()->ws + O_SVSTAT))
; __global__ void __launch_bounds__(512) mega(Params p) {
;     ...
;                     if (c0 >= 5120) { float* stp = SVSTAT + (long)r0 * 16 + ((c0 - 5120) >> 7) * 2;
; #pragma unroll
;                       for (int j = 0; j < 4; ++j) { float s1 = 0, s2 = 0;
; #pragma unroll
;                         for (int n = 0; n < 8; ++n) { s1 += a[n][j]; s2 += a[n][j] * a[n][j]; }
;                         s1 = red16(s1); s2 = red16(s2);
;                         if (fr == 0) { stp[j * 16] = s1; stp[j * 16 + 1] = s2; } } }
.LBB0_2198:
	s_or_b64 exec, exec, s[2:3]
	v_mov_b32_e32 v92, v177
	v_mov_b32_e32 v93, v35
	v_pk_add_f32 v[92:93], v[34:35], v[92:93]
	s_waitcnt lgkmcnt(0)
	v_pk_mul_f32 v[94:95], v[34:35], v[34:35]
	v_mul_f32_e32 v43, v42, v42
	v_mov_b32_e32 v93, v95
	v_pk_mov_b32 v[94:95], v[34:35], v[94:95] op_sel:[1,0]
	s_mov_b32 s2, -1
	v_pk_add_f32 v[92:93], v[92:93], v[94:95]
	v_mul_f32_e32 v51, v50, v50
	v_pk_add_f32 v[92:93], v[92:93], v[42:43]
	v_mbcnt_lo_u32_b32 v39, s2, 0
	v_mul_f32_e32 v57, v56, v56
	v_mbcnt_hi_u32_b32 v39, s2, v39
	s_mov_b32 s2, -1
	v_pk_add_f32 v[92:93], v[92:93], v[50:51]
	v_mul_f32_e32 v69, v68, v68
	v_pk_add_f32 v[92:93], v[92:93], v[56:57]
	v_mbcnt_lo_u32_b32 v47, s2, 0
	v_mul_f32_e32 v75, v74, v74
	v_mbcnt_hi_u32_b32 v47, s2, v47
	v_pk_add_f32 v[92:93], v[92:93], v[68:69]
	v_mul_f32_e32 v85, v84, v84
	v_lshlrev_b32_e32 v39, 2, v39
	v_lshlrev_b32_e32 v47, 2, v47
	v_pk_add_f32 v[92:93], v[92:93], v[74:75]
	v_xor_b32_e32 v45, 4, v39
	v_xor_b32_e32 v49, 4, v47
	v_pk_add_f32 v[92:93], v[92:93], v[84:85]
	s_nop 1
	v_mov_b32_dpp v94, v92 quad_perm:[1,0,3,2] row_mask:0xf bank_mask:0xf
	s_nop 0
	v_mov_b32_dpp v95, v93 quad_perm:[1,0,3,2] row_mask:0xf bank_mask:0xf
	v_xor_b32_e32 v43, 8, v39
	v_xor_b32_e32 v45, 8, v47
	s_waitcnt lgkmcnt(0)
	v_pk_add_f32 v[92:93], v[92:93], v[94:95]
	s_nop 1
	v_mov_b32_dpp v94, v92 quad_perm:[2,3,0,1] row_mask:0xf bank_mask:0xf
	s_nop 0
	v_mov_b32_dpp v95, v93 quad_perm:[2,3,0,1] row_mask:0xf bank_mask:0xf
	v_xor_b32_e32 v43, 16, v39
	v_xor_b32_e32 v45, 16, v47
	v_xor_b32_e32 v39, 32, v39
	s_waitcnt lgkmcnt(0)
	v_pk_add_f32 v[92:93], v[92:93], v[94:95]
	s_nop 1
	v_mov_b32_dpp v94, v92 row_half_mirror row_mask:0xf bank_mask:0xf
	s_nop 1
	v_mov_b32_dpp v94, v94 quad_perm:[3,2,1,0] row_mask:0xf bank_mask:0xf
	v_mov_b32_dpp v95, v93 row_half_mirror row_mask:0xf bank_mask:0xf
	s_nop 1
	v_mov_b32_dpp v95, v95 quad_perm:[3,2,1,0] row_mask:0xf bank_mask:0xf
	s_waitcnt lgkmcnt(0)
	v_pk_add_f32 v[92:93], v[92:93], v[94:95]
	s_nop 1
	v_mov_b32_dpp v94, v92 row_ror:8 row_mask:0xf bank_mask:0xf
	v_xor_b32_e32 v39, 32, v47
	v_mov_b32_dpp v95, v93 row_ror:8 row_mask:0xf bank_mask:0xf
	s_and_saveexec_b64 s[2:3], vcc
	s_cbranch_execz .LBB0_2200
	s_waitcnt lgkmcnt(0)
	v_pk_add_f32 v[92:93], v[92:93], v[94:95]
	global_store_dwordx2 v[90:91], v[92:93], off offset:128
.LBB0_2200:
	s_or_b64 exec, exec, s[2:3]
	v_mov_b32_e32 v92, v177
	v_mov_b32_e32 v93, v33
	v_pk_add_f32 v[92:93], v[32:33], v[92:93]
	s_waitcnt lgkmcnt(0)
	v_pk_mul_f32 v[94:95], v[32:33], v[32:33]
	v_mul_f32_e32 v39, v38, v38
	v_mov_b32_e32 v93, v95
	v_pk_mov_b32 v[94:95], v[32:33], v[94:95] op_sel:[1,0]
	s_mov_b32 s2, -1
	v_pk_add_f32 v[92:93], v[92:93], v[94:95]
	v_mul_f32_e32 v47, v46, v46
	v_pk_add_f32 v[92:93], v[92:93], v[38:39]
	v_mbcnt_lo_u32_b32 v43, s2, 0
	v_mul_f32_e32 v53, v52, v52
	v_mbcnt_hi_u32_b32 v43, s2, v43
	s_mov_b32 s2, -1
	v_pk_add_f32 v[92:93], v[92:93], v[46:47]
	v_mul_f32_e32 v63, v62, v62
	v_pk_add_f32 v[92:93], v[92:93], v[52:53]
	v_mbcnt_lo_u32_b32 v49, s2, 0
	v_mul_f32_e32 v71, v70, v70
	v_mbcnt_hi_u32_b32 v49, s2, v49
	v_pk_add_f32 v[92:93], v[92:93], v[62:63]
	v_mul_f32_e32 v81, v80, v80
	v_lshlrev_b32_e32 v43, 2, v43
	v_lshlrev_b32_e32 v49, 2, v49
	v_pk_add_f32 v[92:93], v[92:93], v[70:71]
	v_xor_b32_e32 v45, 4, v43
	v_xor_b32_e32 v51, 4, v49
	v_pk_add_f32 v[92:93], v[92:93], v[80:81]
	s_nop 1
	v_mov_b32_dpp v94, v92 quad_perm:[1,0,3,2] row_mask:0xf bank_mask:0xf
	s_nop 0
	v_mov_b32_dpp v95, v93 quad_perm:[1,0,3,2] row_mask:0xf bank_mask:0xf
	v_xor_b32_e32 v39, 8, v43
	v_xor_b32_e32 v45, 8, v49
	s_waitcnt lgkmcnt(0)
	v_pk_add_f32 v[92:93], v[92:93], v[94:95]
	s_nop 1
	v_mov_b32_dpp v94, v92 quad_perm:[2,3,0,1] row_mask:0xf bank_mask:0xf
	s_nop 0
	v_mov_b32_dpp v95, v93 quad_perm:[2,3,0,1] row_mask:0xf bank_mask:0xf
	v_xor_b32_e32 v39, 16, v43
	v_xor_b32_e32 v45, 16, v49
	s_waitcnt lgkmcnt(0)
	v_pk_add_f32 v[92:93], v[92:93], v[94:95]
	s_nop 1
	v_mov_b32_dpp v94, v92 row_half_mirror row_mask:0xf bank_mask:0xf
	s_nop 1
	v_mov_b32_dpp v94, v94 quad_perm:[3,2,1,0] row_mask:0xf bank_mask:0xf
	v_mov_b32_dpp v95, v93 row_half_mirror row_mask:0xf bank_mask:0xf
	s_nop 1
	v_mov_b32_dpp v95, v95 quad_perm:[3,2,1,0] row_mask:0xf bank_mask:0xf
	v_xor_b32_e32 v39, 32, v43
	s_waitcnt lgkmcnt(0)
	v_pk_add_f32 v[92:93], v[92:93], v[94:95]
	s_nop 1
	v_mov_b32_dpp v94, v92 row_ror:8 row_mask:0xf bank_mask:0xf
	v_xor_b32_e32 v39, 32, v49
	v_mov_b32_dpp v95, v93 row_ror:8 row_mask:0xf bank_mask:0xf
	s_and_saveexec_b64 s[2:3], vcc
	s_cbranch_execz .LBB0_2202
	s_waitcnt lgkmcnt(0)
	v_pk_add_f32 v[92:93], v[92:93], v[94:95]
	global_store_dwordx2 v[90:91], v[92:93], off offset:192

; #define RK ((bfraw*)(kargs()->ws + O_RK))
; #define RVT ((bfraw*)(kargs()->ws + O_RVT))
; #define ST ((bfraw*)(kargs()->ws + O_ST))
; #define LGT ((float*)(kargs()->ws + O_LGT))
; __global__ void __launch_bounds__(512) mega(Params p) {
;     ...
;         for (int bi = bid; bi < 128 * 8; bi += nb) {
;           int tz = tid; asm volatile("" : "+v"(tz));
;           const int w = __builtin_amdgcn_readfirstlane(tz >> 6), lz = tz & 63, fr = tz & 15, fq = (tz >> 4) & 3;
;           const int head = bi & 7, chunk = bi >> 3;
;           const float lgf = LGT[l * 16 + head], lgb = LGT[l * 16 + 8 + head];
;           const long tok0 = (long)chunk * 128;
;           __syncthreads();
;           { const bfraw* kb = RK + tok0 * 1024 + head * 128; const bfraw* vb = RVT + ((long)(chunk * 8 + head) * 128) * 128;
;             const bfraw* sfb = ST + ((long)((chunk * 8 + head) * 2)) * 16384;
;             const int wz = w;
; #pragma unroll
;             for (int g = 0; g < 16; ++g) { const int blk = g * 8 + wz, row = (blk & 31) * 4 + (lz >> 4), c = (lz ^ row) & 15;
;               const bfraw* sp = (g < 4) ? kb + (long)row * 1024 + c * 8 : (g < 8) ? vb + row * 128 + c * 8 : sfb + (g < 12 ? 0 : 16384) + row * 128 + c * 8;
;               __builtin_amdgcn_global_load_lds((const unsigned*)sp, (unsigned*)(shm + blk * 1024), 16, 0, 0); } }
.LBB0_2481:
	v_mov_b32_e32 v116, v114
	s_and_b32 s17, s16, 7
	v_readfirstlane_b32 s2, v116
	s_ashr_i32 s18, s2, 6
	s_mov_b64 s[2:3], s[0:1]
	s_load_dwordx2 s[4:5], s[2:3], 0xe8
	s_or_b32 s12, s17, s10
	s_ashr_i32 s2, s16, 3
	s_lshl_b64 s[14:15], s[12:13], 2
	v_bfe_u32 v68, v116, 4, 2
	s_waitcnt lgkmcnt(0)
	s_add_u32 s4, s4, s14
	s_addc_u32 s5, s5, s15
	global_load_dword v117, v252, s[4:5]
	s_mov_b64 s[4:5], s[0:1]
	s_load_dwordx2 s[4:5], s[4:5], 0xe8
	v_and_b32_e32 v115, 15, v116
	v_lshrrev_b32_e32 v119, 4, v116
	v_lshlrev_b32_e32 v120, 8, v115
	v_bitop3_b32 v8, v68, v115, 4 bitop3:0x36
	s_waitcnt lgkmcnt(0)
	s_add_u32 s4, s4, s14
	s_addc_u32 s5, s5, s15
	global_load_dword v118, v252, s[4:5] offset:32
	s_mov_b64 s[4:5], s[0:1]
	s_waitcnt vmcnt(63) expcnt(7) lgkmcnt(15)
	s_barrier
	s_load_dwordx2 s[4:5], s[4:5], 0xe8
	s_ashr_i32 s3, s2, 31
	s_lshl_b64 s[14:15], s[2:3], 18
	v_bitop3_b32 v16, v68, v115, 8 bitop3:0x36
	v_bitop3_b32 v26, v68, v115, 12 bitop3:0x36
	s_waitcnt lgkmcnt(0)
	s_add_u32 s4, s4, s14
	s_addc_u32 s5, s5, s15
	s_lshl_b32 s12, s17, 8
	s_add_u32 s7, s4, s12
	s_addc_u32 s19, s5, 0
	s_mov_b64 s[4:5], s[0:1]
	s_load_dwordx2 s[14:15], s[4:5], 0xe8
	s_mov_b64 s[4:5], s[0:1]
	s_load_dwordx2 s[4:5], s[4:5], 0xe8
	s_add_u32 s20, s7, 0x13720000
	s_addc_u32 s21, s19, 0
	s_ashr_i32 s7, s6, 31
	s_lshl_b64 s[22:23], s[6:7], 15
	s_waitcnt lgkmcnt(0)
	s_add_u32 s7, s4, s22
	s_addc_u32 s19, s5, s23
	s_add_u32 s4, s7, 0x30720000
	s_addc_u32 s5, s19, 0
	s_lshl_b32 s22, s18, 2
	s_and_b32 s22, s22, 0x7c
	v_or_b32_e32 v0, s22, v68
	v_bitop3_b32 v2, s22, v116, v68 bitop3:0x36
	v_lshlrev_b32_e32 v176, 11, v0
	v_lshlrev_b32_e32 v2, 4, v2
	s_add_i32 s22, s18, 8
	v_lshl_add_u64 v[0:1], s[20:21], 0, v[176:177]
	v_and_b32_e32 v176, 0xf0, v2
	s_lshl_b32 s23, s22, 2
	v_lshl_add_u64 v[0:1], v[0:1], 0, v[176:177]
	s_lshl_b32 m0, s18, 10
	s_and_b32 s23, s23, 0x7c
	global_load_lds_dwordx4 v[0:1], off
	v_or_b32_e32 v0, s23, v68
	v_bitop3_b32 v2, s23, v116, v68 bitop3:0x36
	v_lshlrev_b32_e32 v176, 11, v0
	v_lshlrev_b32_e32 v2, 4, v2
	s_lshl_b32 m0, s22, 10
	s_add_i32 s22, s18, 16
	v_lshl_add_u64 v[0:1], s[20:21], 0, v[176:177]
	v_and_b32_e32 v176, 0xf0, v2
	s_lshl_b32 s23, s22, 2
	v_lshl_add_u64 v[0:1], v[0:1], 0, v[176:177]
	s_and_b32 s23, s23, 0x7c
	global_load_lds_dwordx4 v[0:1], off
	v_or_b32_e32 v0, s23, v68
	v_bitop3_b32 v2, s23, v116, v68 bitop3:0x36
	v_lshlrev_b32_e32 v176, 11, v0
	v_lshlrev_b32_e32 v2, 4, v2
	s_lshl_b32 m0, s22, 10
	s_add_i32 s22, s18, 24
	v_lshl_add_u64 v[0:1], s[20:21], 0, v[176:177]
	v_and_b32_e32 v176, 0xf0, v2
	s_lshl_b32 s23, s22, 2
	v_lshl_add_u64 v[0:1], v[0:1], 0, v[176:177]
	s_and_b32 s23, s23, 0x7c
	global_load_lds_dwordx4 v[0:1], off
	v_or_b32_e32 v0, s23, v68
	v_bitop3_b32 v2, s23, v116, v68 bitop3:0x36
	v_lshlrev_b32_e32 v176, 11, v0
	v_lshlrev_b32_e32 v2, 4, v2
	v_lshl_add_u64 v[0:1], s[20:21], 0, v[176:177]
	v_and_b32_e32 v176, 0xf0, v2
	v_lshl_add_u64 v[0:1], v[0:1], 0, v[176:177]
	s_lshl_b32 m0, s22, 10
	s_add_i32 s20, s18, 32
	global_load_lds_dwordx4 v[0:1], off
	v_lshl_or_b32 v0, s20, 2, v68
	s_and_b32 s21, s20, 31
	v_lshlrev_b32_e32 v2, 8, v68
	v_bitop3_b32 v0, v0, 15, v116 bitop3:0x48
	v_lshl_or_b32 v1, s21, 10, v2
	v_lshl_or_b32 v176, v0, 4, v1
	v_lshl_add_u64 v[0:1], s[14:15], 0, v[176:177]
	v_lshl_add_u64 v[0:1], v[0:1], 0, s[8:9]
	s_lshl_b32 m0, s20, 10
	s_add_i32 s20, s18, 40
	global_load_lds_dwordx4 v[0:1], off
	v_lshl_or_b32 v0, s20, 2, v68
	s_and_b32 s21, s20, 31
	v_bitop3_b32 v0, v0, 15, v116 bitop3:0x48
	v_lshl_or_b32 v1, s21, 10, v2
	v_lshl_or_b32 v176, v0, 4, v1
	v_lshl_add_u64 v[0:1], s[14:15], 0, v[176:177]
	v_lshl_add_u64 v[0:1], v[0:1], 0, s[8:9]
	s_lshl_b32 m0, s20, 10
	s_add_i32 s20, s18, 48
	global_load_lds_dwordx4 v[0:1], off
	v_lshl_or_b32 v0, s20, 2, v68
	s_and_b32 s21, s20, 31
	v_bitop3_b32 v0, v0, 15, v116 bitop3:0x48
	v_lshl_or_b32 v1, s21, 10, v2
	v_lshl_or_b32 v176, v0, 4, v1
	v_lshl_add_u64 v[0:1], s[14:15], 0, v[176:177]
	v_lshl_add_u64 v[0:1], v[0:1], 0, s[8:9]
	s_lshl_b32 m0, s20, 10
	s_add_i32 s20, s18, 56
	global_load_lds_dwordx4 v[0:1], off
	v_lshl_or_b32 v0, s20, 2, v68
	s_and_b32 s21, s20, 31
	v_bitop3_b32 v0, v0, 15, v116 bitop3:0x48
	v_lshl_or_b32 v1, s21, 10, v2
	v_lshl_or_b32 v176, v0, 4, v1
	v_lshl_add_u64 v[0:1], s[14:15], 0, v[176:177]
	s_add_i32 s14, s18, 64
	s_lshl_b32 s15, s14, 2
	v_lshl_add_u64 v[0:1], v[0:1], 0, s[8:9]
	s_lshl_b32 m0, s20, 10
	s_and_b32 s15, s15, 0x7c
	global_load_lds_dwordx4 v[0:1], off
	v_or_b32_e32 v0, s15, v68
	v_bitop3_b32 v2, s15, v116, v68 bitop3:0x36
	v_lshlrev_b32_e32 v176, 8, v0
	v_lshlrev_b32_e32 v2, 4, v2
	s_lshl_b32 m0, s14, 10
	s_add_i32 s14, s18, 0x48
	v_lshl_add_u64 v[0:1], s[4:5], 0, v[176:177]
	v_and_b32_e32 v176, 0xf0, v2
	s_lshl_b32 s15, s14, 2
	v_lshl_add_u64 v[0:1], v[0:1], 0, v[176:177]
	s_and_b32 s15, s15, 0x7c
	global_load_lds_dwordx4 v[0:1], off
	v_or_b32_e32 v0, s15, v68
	v_bitop3_b32 v2, s15, v116, v68 bitop3:0x36
	v_lshlrev_b32_e32 v176, 8, v0
	v_lshlrev_b32_e32 v2, 4, v2
	s_lshl_b32 m0, s14, 10
	s_add_i32 s14, s18, 0x50
	v_lshl_add_u64 v[0:1], s[4:5], 0, v[176:177]
	v_and_b32_e32 v176, 0xf0, v2
	s_lshl_b32 s15, s14, 2
	v_lshl_add_u64 v[0:1], v[0:1], 0, v[176:177]
	s_and_b32 s15, s15, 0x7c
	global_load_lds_dwordx4 v[0:1], off
	v_or_b32_e32 v0, s15, v68
	v_bitop3_b32 v2, s15, v116, v68 bitop3:0x36
	v_lshlrev_b32_e32 v176, 8, v0
	v_lshlrev_b32_e32 v2, 4, v2
	s_lshl_b32 m0, s14, 10
	s_add_i32 s14, s18, 0x58
	v_lshl_add_u64 v[0:1], s[4:5], 0, v[176:177]
	v_and_b32_e32 v176, 0xf0, v2
	s_lshl_b32 s15, s14, 2
	v_lshl_add_u64 v[0:1], v[0:1], 0, v[176:177]
	s_and_b32 s15, s15, 0x7c
	global_load_lds_dwordx4 v[0:1], off
; #define SBAR() __builtin_amdgcn_sched_barrier(0)
; #define WAIT_V0() asm volatile("s_waitcnt vmcnt(0)" ::: "memory")
; #define RQ ((bfraw*)(kargs()->ws + O_RQ))
; #define RK ((bfraw*)(kargs()->ws + O_RK))
; #define RVT ((bfraw*)(kargs()->ws + O_RVT))
; #define ST ((bfraw*)(kargs()->ws + O_ST))
; __global__ void __launch_bounds__(512) mega(Params p) {
;     ...
;           { const bfraw* kb = RK + tok0 * 1024 + head * 128; const bfraw* vb = RVT + ((long)(chunk * 8 + head) * 128) * 128;
;             const bfraw* sfb = ST + ((long)((chunk * 8 + head) * 2)) * 16384;
;             const int wz = w;
; #pragma unroll
;             for (int g = 0; g < 16; ++g) { const int blk = g * 8 + wz, row = (blk & 31) * 4 + (lz >> 4), c = (lz ^ row) & 15;
;               const bfraw* sp = (g < 4) ? kb + (long)row * 1024 + c * 8 : (g < 8) ? vb + row * 128 + c * 8 : sfb + (g < 12 ? 0 : 16384) + row * 128 + c * 8;
;               __builtin_amdgcn_global_load_lds((const unsigned*)sp, (unsigned*)(shm + blk * 1024), 16, 0, 0); } }
;           bf16x8 qf[4];
;           { const bfraw* qp = RQ + (tok0 + w * 16 + fr) * 1024 + head * 128 + fq * 8;
; #pragma unroll
;             for (int sx = 0; sx < 4; ++sx) qf[sx] = *(const bf16x8*)(qp + sx * 32); }
;           WAIT_V0(); __syncthreads();
;           f32x4 o[8];
;           { f32x4 af[8] = {}, ab[8] = {};
; #pragma unroll
;             for (int ne = 0; ne < 8; ++ne) { bf16x8 Bf[4], Bb[4];
; #pragma unroll
;               for (int sx = 0; sx < 4; ++sx) { Bf[sx] = RLD16(2, ne * 16 + fr, sx * 4 + fq); Bb[sx] = RLD16(3, ne * 16 + fr, sx * 4 + fq); }
;               SBAR();
; #pragma unroll
;               for (int sx = 0; sx < 4; ++sx) { af[ne] = __builtin_amdgcn_mfma_f32_16x16x32_bf16(qf[sx], Bf[sx], af[ne], 0, 0, 0);
;                 ab[ne] = __builtin_amdgcn_mfma_f32_16x16x32_bf16(qf[sx], Bb[sx], ab[ne], 0, 0, 0); }
;               SBAR(); }
	v_or_b32_e32 v0, s15, v68
	v_bitop3_b32 v2, s15, v116, v68 bitop3:0x36
	v_lshlrev_b32_e32 v176, 8, v0
	v_lshlrev_b32_e32 v2, 4, v2
	s_lshl_b32 m0, s14, 10
	s_add_i32 s14, s18, 0x60
	v_lshl_add_u64 v[0:1], s[4:5], 0, v[176:177]
	v_and_b32_e32 v176, 0xf0, v2
	s_lshl_b32 s4, s14, 2
	v_lshl_add_u64 v[0:1], v[0:1], 0, v[176:177]
	s_and_b32 s4, s4, 0x7c
	global_load_lds_dwordx4 v[0:1], off
	v_or_b32_e32 v0, s4, v68
	v_bitop3_b32 v2, s4, v116, v68 bitop3:0x36
	s_add_u32 s4, s7, 0x30728000
	s_addc_u32 s5, s19, 0
	v_lshlrev_b32_e32 v176, 8, v0
	v_lshlrev_b32_e32 v2, 4, v2
	s_add_i32 s7, s18, 0x68
	v_lshl_add_u64 v[0:1], s[4:5], 0, v[176:177]
	v_and_b32_e32 v176, 0xf0, v2
	s_lshl_b32 m0, s14, 10
	s_lshl_b32 s14, s7, 2
	v_lshl_add_u64 v[0:1], v[0:1], 0, v[176:177]
	s_and_b32 s14, s14, 0x7c
	global_load_lds_dwordx4 v[0:1], off
	v_or_b32_e32 v0, s14, v68
	v_bitop3_b32 v2, s14, v116, v68 bitop3:0x36
	v_lshlrev_b32_e32 v176, 8, v0
	v_lshlrev_b32_e32 v2, 4, v2
	s_lshl_b32 m0, s7, 10
	s_add_i32 s7, s18, 0x70
	v_lshl_add_u64 v[0:1], s[4:5], 0, v[176:177]
	v_and_b32_e32 v176, 0xf0, v2
	s_lshl_b32 s14, s7, 2
	v_lshl_add_u64 v[0:1], v[0:1], 0, v[176:177]
	s_and_b32 s14, s14, 0x7c
	global_load_lds_dwordx4 v[0:1], off
	v_or_b32_e32 v0, s14, v68
	v_bitop3_b32 v2, s14, v116, v68 bitop3:0x36
	v_lshlrev_b32_e32 v176, 8, v0
	v_lshlrev_b32_e32 v2, 4, v2
	s_lshl_b32 m0, s7, 10
	s_add_i32 s7, s18, 0x78
	v_lshl_add_u64 v[0:1], s[4:5], 0, v[176:177]
	v_and_b32_e32 v176, 0xf0, v2
	s_lshl_b32 s14, s7, 2
	v_lshl_add_u64 v[0:1], v[0:1], 0, v[176:177]
	s_and_b32 s14, s14, 0x7c
	global_load_lds_dwordx4 v[0:1], off
	v_or_b32_e32 v0, s14, v68
	v_bitop3_b32 v2, s14, v116, v68 bitop3:0x36
	v_lshlrev_b32_e32 v176, 8, v0
	v_lshlrev_b32_e32 v2, 4, v2
	v_lshl_add_u64 v[0:1], s[4:5], 0, v[176:177]
	v_and_b32_e32 v176, 0xf0, v2
	v_lshl_add_u64 v[0:1], v[0:1], 0, v[176:177]
	s_lshl_b32 m0, s7, 10
	s_lshl_b64 s[4:5], s[2:3], 7
	s_mov_b64 s[2:3], s[0:1]
	global_load_lds_dwordx4 v[0:1], off
	s_load_dwordx2 s[14:15], s[2:3], 0xe8
	s_lshl_b32 s2, s18, 4
	s_ashr_i32 s3, s2, 31
	s_add_u32 s7, s4, s2
	s_addc_u32 s3, s5, s3
	v_or_b32_e32 v104, s7, v115
	v_mov_b32_e32 v105, s3
	v_lshlrev_b64 v[0:1], 11, v[104:105]
	s_waitcnt lgkmcnt(0)
	v_lshl_add_u64 v[0:1], s[14:15], 0, v[0:1]
	v_lshl_add_u64 v[0:1], v[0:1], 0, s[12:13]
	v_lshlrev_b32_e32 v176, 4, v68
	v_lshl_add_u64 v[0:1], v[0:1], 0, v[176:177]
	v_lshl_add_u64 v[2:3], v[0:1], 0, s[24:25]
	v_add_co_u32_e32 v0, vcc, s84, v0
	v_or_b32_e32 v24, 0x10000, v120
	s_nop 0
	v_addc_co_u32_e32 v1, vcc, 0, v1, vcc
	global_load_dwordx4 v[64:67], v[2:3], off offset:64
	global_load_dwordx4 v[84:87], v[2:3], off offset:128
	global_load_dwordx4 v[92:95], v[0:1], off
	global_load_dwordx4 v[88:91], v[2:3], off offset:192
	v_bitop3_b32 v0, v119, v115, 3 bitop3:0x6c
	v_or_b32_e32 v25, 0x18000, v120
	v_lshlrev_b32_e32 v69, 4, v0
	v_lshlrev_b32_e32 v82, 4, v8
	v_lshlrev_b32_e32 v83, 4, v16
	v_lshlrev_b32_e32 v121, 4, v26
	v_or_b32_e32 v0, v24, v69
	v_or_b32_e32 v4, v25, v69
	v_or_b32_e32 v8, v24, v82
	v_or_b32_e32 v12, v25, v82
	v_or_b32_e32 v16, v24, v83
	v_or_b32_e32 v20, v25, v83
	v_or_b32_e32 v24, v24, v121
	s_waitcnt vmcnt(0)
	s_waitcnt vmcnt(0)
	s_barrier
	ds_read_b128 v[0:3], v0
	ds_read_b128 v[4:7], v4
	ds_read_b128 v[8:11], v8
	ds_read_b128 v[12:15], v12
	ds_read_b128 v[16:19], v16
	ds_read_b128 v[20:23], v20
	v_or_b32_e32 v28, v25, v121
	ds_read_b128 v[24:27], v24
	ds_read_b128 v[32:35], v28
	s_waitcnt lgkmcnt(7)
	v_mfma_f32_16x16x32_bf16 v[0:3], v[92:95], v[0:3], 0
	s_waitcnt lgkmcnt(6)
	v_mfma_f32_16x16x32_bf16 v[4:7], v[92:95], v[4:7], 0
	s_waitcnt lgkmcnt(5)
	v_mfma_f32_16x16x32_bf16 v[0:3], v[64:67], v[8:11], v[0:3]
	s_waitcnt lgkmcnt(4)
	v_mfma_f32_16x16x32_bf16 v[4:7], v[64:67], v[12:15], v[4:7]
	s_waitcnt lgkmcnt(3)
	v_mfma_f32_16x16x32_bf16 v[0:3], v[84:87], v[16:19], v[0:3]
	s_waitcnt lgkmcnt(2)
	v_mfma_f32_16x16x32_bf16 v[4:7], v[84:87], v[20:23], v[4:7]
	s_waitcnt lgkmcnt(1)
	v_mfma_f32_16x16x32_bf16 v[28:31], v[88:91], v[24:27], v[0:3]
	s_waitcnt lgkmcnt(0)
	v_mfma_f32_16x16x32_bf16 v[60:63], v[88:91], v[32:35], v[4:7]
	v_or_b32_e32 v24, 0x1000, v120
	v_or_b32_e32 v100, 0x10000, v69
	v_or_b32_e32 v101, 0x18000, v69
	v_or_b32_e32 v102, 0x10000, v82
	v_or_b32_e32 v103, 0x18000, v82
	v_or_b32_e32 v104, 0x10000, v83
	v_or_b32_e32 v106, 0x18000, v83
	v_or_b32_e32 v107, 0x10000, v121
	v_or_b32_e32 v108, 0x18000, v121
	v_or_b32_e32 v0, v100, v24
	v_or_b32_e32 v4, v101, v24
	v_or_b32_e32 v8, v102, v24
	v_or_b32_e32 v12, v103, v24
	v_or_b32_e32 v16, v104, v24
	v_or_b32_e32 v20, v106, v24
	v_or_b32_e32 v25, v107, v24
	v_or_b32_e32 v32, v108, v24
	ds_read_b128 v[0:3], v0
	ds_read_b128 v[4:7], v4
	ds_read_b128 v[8:11], v8
	ds_read_b128 v[12:15], v12
	ds_read_b128 v[16:19], v16
	ds_read_b128 v[20:23], v20
	ds_read_b128 v[24:27], v25
	ds_read_b128 v[32:35], v32
	s_waitcnt lgkmcnt(7)
	v_mfma_f32_16x16x32_bf16 v[0:3], v[92:95], v[0:3], 0
	s_waitcnt lgkmcnt(6)
	v_mfma_f32_16x16x32_bf16 v[4:7], v[92:95], v[4:7], 0
	s_waitcnt lgkmcnt(5)
	v_mfma_f32_16x16x32_bf16 v[0:3], v[64:67], v[8:11], v[0:3]
	s_waitcnt lgkmcnt(4)
	v_mfma_f32_16x16x32_bf16 v[4:7], v[64:67], v[12:15], v[4:7]
	s_waitcnt lgkmcnt(3)
	v_mfma_f32_16x16x32_bf16 v[0:3], v[84:87], v[16:19], v[0:3]
	s_waitcnt lgkmcnt(2)
	v_mfma_f32_16x16x32_bf16 v[4:7], v[84:87], v[20:23], v[4:7]
	s_waitcnt lgkmcnt(1)
	v_mfma_f32_16x16x32_bf16 v[0:3], v[88:91], v[24:27], v[0:3]
	s_waitcnt lgkmcnt(0)
; #define SBAR() __builtin_amdgcn_sched_barrier(0)
; __global__ void __launch_bounds__(512) mega(Params p) {
;     ...
;           { f32x4 af[8] = {}, ab[8] = {};
; #pragma unroll
;             for (int ne = 0; ne < 8; ++ne) { bf16x8 Bf[4], Bb[4];
; #pragma unroll
;               for (int sx = 0; sx < 4; ++sx) { Bf[sx] = RLD16(2, ne * 16 + fr, sx * 4 + fq); Bb[sx] = RLD16(3, ne * 16 + fr, sx * 4 + fq); }
;               SBAR();
; #pragma unroll
;               for (int sx = 0; sx < 4; ++sx) { af[ne] = __builtin_amdgcn_mfma_f32_16x16x32_bf16(qf[sx], Bf[sx], af[ne], 0, 0, 0);
;                 ab[ne] = __builtin_amdgcn_mfma_f32_16x16x32_bf16(qf[sx], Bb[sx], ab[ne], 0, 0, 0); }
;               SBAR(); }
	v_mfma_f32_16x16x32_bf16 v[56:59], v[88:91], v[32:35], v[4:7]
	v_or_b32_e32 v32, 0x2000, v120
	s_nop 2
	v_or_b32_e32 v4, v100, v32
	v_or_b32_e32 v8, v101, v32
	v_or_b32_e32 v12, v102, v32
	v_or_b32_e32 v16, v103, v32
	v_or_b32_e32 v20, v104, v32
	v_or_b32_e32 v24, v106, v32
	v_or_b32_e32 v33, v107, v32
	v_or_b32_e32 v36, v108, v32
	ds_read_b128 v[4:7], v4
	ds_read_b128 v[8:11], v8
	ds_read_b128 v[12:15], v12
	ds_read_b128 v[16:19], v16
	ds_read_b128 v[20:23], v20
	ds_read_b128 v[24:27], v24
	ds_read_b128 v[32:35], v33
	ds_read_b128 v[36:39], v36
	s_waitcnt lgkmcnt(7)
	v_mfma_f32_16x16x32_bf16 v[4:7], v[92:95], v[4:7], 0
	s_waitcnt lgkmcnt(6)
	v_mfma_f32_16x16x32_bf16 v[8:11], v[92:95], v[8:11], 0
	s_waitcnt lgkmcnt(5)
	v_mfma_f32_16x16x32_bf16 v[4:7], v[64:67], v[12:15], v[4:7]
	s_waitcnt lgkmcnt(4)
	v_mfma_f32_16x16x32_bf16 v[8:11], v[64:67], v[16:19], v[8:11]
	s_waitcnt lgkmcnt(3)
	v_mfma_f32_16x16x32_bf16 v[4:7], v[84:87], v[20:23], v[4:7]
	s_waitcnt lgkmcnt(2)
	v_mfma_f32_16x16x32_bf16 v[8:11], v[84:87], v[24:27], v[8:11]
	s_waitcnt lgkmcnt(1)
	v_mfma_f32_16x16x32_bf16 v[4:7], v[88:91], v[32:35], v[4:7]
	s_waitcnt lgkmcnt(0)
	v_mfma_f32_16x16x32_bf16 v[52:55], v[88:91], v[36:39], v[8:11]
	v_or_b32_e32 v36, 0x3000, v120
	s_nop 2
	v_or_b32_e32 v8, v100, v36
	v_or_b32_e32 v12, v101, v36
	v_or_b32_e32 v16, v102, v36
	v_or_b32_e32 v20, v103, v36
	v_or_b32_e32 v24, v104, v36
	v_or_b32_e32 v32, v106, v36
	v_or_b32_e32 v37, v107, v36
	v_or_b32_e32 v40, v108, v36
	ds_read_b128 v[8:11], v8
	ds_read_b128 v[12:15], v12
	ds_read_b128 v[16:19], v16
	ds_read_b128 v[20:23], v20
	ds_read_b128 v[24:27], v24
	ds_read_b128 v[32:35], v32
	ds_read_b128 v[36:39], v37
	ds_read_b128 v[40:43], v40
	s_waitcnt lgkmcnt(7)
	v_mfma_f32_16x16x32_bf16 v[8:11], v[92:95], v[8:11], 0
	s_waitcnt lgkmcnt(6)
	v_mfma_f32_16x16x32_bf16 v[12:15], v[92:95], v[12:15], 0
	s_waitcnt lgkmcnt(5)
	v_mfma_f32_16x16x32_bf16 v[8:11], v[64:67], v[16:19], v[8:11]
	s_waitcnt lgkmcnt(4)
	v_mfma_f32_16x16x32_bf16 v[12:15], v[64:67], v[20:23], v[12:15]
	s_waitcnt lgkmcnt(3)
	v_mfma_f32_16x16x32_bf16 v[8:11], v[84:87], v[24:27], v[8:11]
	s_waitcnt lgkmcnt(2)
	v_mfma_f32_16x16x32_bf16 v[12:15], v[84:87], v[32:35], v[12:15]
	s_waitcnt lgkmcnt(1)
	v_mfma_f32_16x16x32_bf16 v[8:11], v[88:91], v[36:39], v[8:11]
	s_waitcnt lgkmcnt(0)
	v_mfma_f32_16x16x32_bf16 v[48:51], v[88:91], v[40:43], v[12:15]
	v_or_b32_e32 v40, 0x4000, v120
	s_nop 2
	v_or_b32_e32 v12, v100, v40
	v_or_b32_e32 v16, v101, v40
	v_or_b32_e32 v20, v102, v40
	v_or_b32_e32 v24, v103, v40
	v_or_b32_e32 v32, v104, v40
	v_or_b32_e32 v36, v106, v40
	v_or_b32_e32 v41, v107, v40
	v_or_b32_e32 v44, v108, v40
	ds_read_b128 v[12:15], v12
	ds_read_b128 v[16:19], v16
	ds_read_b128 v[20:23], v20
	ds_read_b128 v[24:27], v24
	ds_read_b128 v[32:35], v32
	ds_read_b128 v[36:39], v36
	ds_read_b128 v[40:43], v41
	ds_read_b128 v[44:47], v44
	s_waitcnt lgkmcnt(7)
	v_mfma_f32_16x16x32_bf16 v[12:15], v[92:95], v[12:15], 0
	s_waitcnt lgkmcnt(6)
	v_mfma_f32_16x16x32_bf16 v[16:19], v[92:95], v[16:19], 0
	s_waitcnt lgkmcnt(5)
	v_mfma_f32_16x16x32_bf16 v[12:15], v[64:67], v[20:23], v[12:15]
	s_waitcnt lgkmcnt(4)
	v_mfma_f32_16x16x32_bf16 v[16:19], v[64:67], v[24:27], v[16:19]
	s_waitcnt lgkmcnt(3)
	v_mfma_f32_16x16x32_bf16 v[12:15], v[84:87], v[32:35], v[12:15]
	s_waitcnt lgkmcnt(2)
	v_mfma_f32_16x16x32_bf16 v[16:19], v[84:87], v[36:39], v[16:19]
	s_waitcnt lgkmcnt(1)
	v_mfma_f32_16x16x32_bf16 v[12:15], v[88:91], v[40:43], v[12:15]
	s_waitcnt lgkmcnt(0)
	v_mfma_f32_16x16x32_bf16 v[44:47], v[88:91], v[44:47], v[16:19]
	v_or_b32_e32 v70, 0x5000, v120
	s_nop 2
	v_or_b32_e32 v16, v100, v70
	v_or_b32_e32 v20, v101, v70
	v_or_b32_e32 v24, v102, v70
	v_or_b32_e32 v32, v103, v70
	v_or_b32_e32 v36, v104, v70
	v_or_b32_e32 v40, v106, v70
	v_or_b32_e32 v71, v107, v70
	v_or_b32_e32 v74, v108, v70
	ds_read_b128 v[16:19], v16
	ds_read_b128 v[20:23], v20
	ds_read_b128 v[24:27], v24
	ds_read_b128 v[32:35], v32
	ds_read_b128 v[36:39], v36
	ds_read_b128 v[40:43], v40
	ds_read_b128 v[70:73], v71
	ds_read_b128 v[74:77], v74
	s_waitcnt lgkmcnt(7)
	v_mfma_f32_16x16x32_bf16 v[16:19], v[92:95], v[16:19], 0
	s_waitcnt lgkmcnt(6)
	v_mfma_f32_16x16x32_bf16 v[20:23], v[92:95], v[20:23], 0
	s_waitcnt lgkmcnt(5)
	v_mfma_f32_16x16x32_bf16 v[16:19], v[64:67], v[24:27], v[16:19]
	s_waitcnt lgkmcnt(4)
	v_mfma_f32_16x16x32_bf16 v[20:23], v[64:67], v[32:35], v[20:23]
	s_waitcnt lgkmcnt(3)
	v_mfma_f32_16x16x32_bf16 v[16:19], v[84:87], v[36:39], v[16:19]
	s_waitcnt lgkmcnt(2)
	v_mfma_f32_16x16x32_bf16 v[20:23], v[84:87], v[40:43], v[20:23]
	s_waitcnt lgkmcnt(1)
	v_mfma_f32_16x16x32_bf16 v[16:19], v[88:91], v[70:73], v[16:19]
	s_waitcnt lgkmcnt(0)
	v_mfma_f32_16x16x32_bf16 v[40:43], v[88:91], v[74:77], v[20:23]
	v_or_b32_e32 v78, 0x6000, v120
	s_nop 2
	v_or_b32_e32 v20, v100, v78
	v_or_b32_e32 v24, v101, v78
	v_or_b32_e32 v32, v102, v78
	v_or_b32_e32 v36, v103, v78
	v_or_b32_e32 v70, v104, v78
	v_or_b32_e32 v74, v106, v78
	v_or_b32_e32 v79, v107, v78
	v_or_b32_e32 v96, v108, v78
	ds_read_b128 v[20:23], v20
	ds_read_b128 v[24:27], v24
	ds_read_b128 v[32:35], v32
	ds_read_b128 v[36:39], v36
	ds_read_b128 v[70:73], v70
	ds_read_b128 v[74:77], v74
	ds_read_b128 v[78:81], v79
	ds_read_b128 v[96:99], v96
	s_waitcnt lgkmcnt(7)
	v_mfma_f32_16x16x32_bf16 v[20:23], v[92:95], v[20:23], 0
	s_waitcnt lgkmcnt(6)
	v_mfma_f32_16x16x32_bf16 v[24:27], v[92:95], v[24:27], 0
	s_waitcnt lgkmcnt(5)
	v_mfma_f32_16x16x32_bf16 v[20:23], v[64:67], v[32:35], v[20:23]
	s_waitcnt lgkmcnt(4)
	v_mfma_f32_16x16x32_bf16 v[24:27], v[64:67], v[36:39], v[24:27]
	s_waitcnt lgkmcnt(3)
	v_mfma_f32_16x16x32_bf16 v[20:23], v[84:87], v[70:73], v[20:23]
	s_waitcnt lgkmcnt(2)
; #define SBAR() __builtin_amdgcn_sched_barrier(0)
; __global__ void __launch_bounds__(512) mega(Params p) {
;     ...
;             for (int ne = 0; ne < 8; ++ne) { bf16x8 Bf[4], Bb[4];
; #pragma unroll
;               for (int sx = 0; sx < 4; ++sx) { Bf[sx] = RLD16(2, ne * 16 + fr, sx * 4 + fq); Bb[sx] = RLD16(3, ne * 16 + fr, sx * 4 + fq); }
;               SBAR();
; #pragma unroll
;               for (int sx = 0; sx < 4; ++sx) { af[ne] = __builtin_amdgcn_mfma_f32_16x16x32_bf16(qf[sx], Bf[sx], af[ne], 0, 0, 0);
;                 ab[ne] = __builtin_amdgcn_mfma_f32_16x16x32_bf16(qf[sx], Bb[sx], ab[ne], 0, 0, 0); }
;               SBAR(); }
; #pragma unroll
;             for (int j = 0; j < 4; ++j) { const int c = w * 16 + fq * 4 + j; const float xf = __expf(lgf * (float)(c + 1)), xb = __expf(lgb * (float)(128 - c));
; #pragma unroll
;               for (int ne = 0; ne < 8; ++ne) o[ne][j] = xf * af[ne][j] + xb * ab[ne][j]; } }
;           bf16x8 pf[4];
;           { f32x4 sc[8] = {};
; #pragma unroll
;             for (int n2 = 0; n2 < 4; ++n2) { bf16x8 A[2][4];
; #pragma unroll
;               for (int q2 = 0; q2 < 2; ++q2)
; #pragma unroll
;                 for (int sx = 0; sx < 4; ++sx) A[q2][sx] = RLD16(0, (n2 * 2 + q2) * 16 + fr, sx * 4 + fq);
;               SBAR();
; #pragma unroll
;               for (int q2 = 0; q2 < 2; ++q2)
; #pragma unroll
;                 for (int sx = 0; sx < 4; ++sx) sc[n2 * 2 + q2] = __builtin_amdgcn_mfma_f32_16x16x32_bf16(A[q2][sx], qf[sx], sc[n2 * 2 + q2], 0, 0, 0);
;               SBAR(); }
	v_mfma_f32_16x16x32_bf16 v[24:27], v[84:87], v[74:77], v[24:27]
	s_waitcnt lgkmcnt(1)
	v_mfma_f32_16x16x32_bf16 v[20:23], v[88:91], v[78:81], v[20:23]
	s_waitcnt lgkmcnt(0)
	v_mfma_f32_16x16x32_bf16 v[36:39], v[88:91], v[96:99], v[24:27]
	v_or_b32_e32 v109, 0x7000, v120
	s_nop 2
	v_or_b32_e32 v24, v100, v109
	v_or_b32_e32 v32, v101, v109
	v_or_b32_e32 v70, v102, v109
	v_or_b32_e32 v74, v103, v109
	v_or_b32_e32 v78, v104, v109
	v_or_b32_e32 v96, v106, v109
	v_or_b32_e32 v100, v107, v109
	ds_read_b128 v[24:27], v24
	ds_read_b128 v[32:35], v32
	ds_read_b128 v[70:73], v70
	ds_read_b128 v[74:77], v74
	ds_read_b128 v[78:81], v78
	ds_read_b128 v[96:99], v96
	v_or_b32_e32 v104, v108, v109
	ds_read_b128 v[100:103], v100
	ds_read_b128 v[106:109], v104
	s_waitcnt lgkmcnt(7)
	v_mfma_f32_16x16x32_bf16 v[24:27], v[92:95], v[24:27], 0
	s_waitcnt lgkmcnt(6)
	v_mfma_f32_16x16x32_bf16 v[32:35], v[92:95], v[32:35], 0
	s_waitcnt lgkmcnt(5)
	v_mfma_f32_16x16x32_bf16 v[24:27], v[64:67], v[70:73], v[24:27]
	s_waitcnt lgkmcnt(4)
	v_mfma_f32_16x16x32_bf16 v[32:35], v[64:67], v[74:77], v[32:35]
	s_waitcnt lgkmcnt(3)
	v_mfma_f32_16x16x32_bf16 v[24:27], v[84:87], v[78:81], v[24:27]
	s_waitcnt lgkmcnt(2)
	v_mfma_f32_16x16x32_bf16 v[32:35], v[84:87], v[96:99], v[32:35]
	s_waitcnt lgkmcnt(1)
	v_mfma_f32_16x16x32_bf16 v[24:27], v[88:91], v[100:103], v[24:27]
	s_waitcnt lgkmcnt(0)
	v_mfma_f32_16x16x32_bf16 v[32:35], v[88:91], v[106:109], v[32:35]
	v_lshlrev_b32_e32 v104, 2, v68
	v_or_b32_e32 v68, s2, v104
	v_or_b32_e32 v70, 1, v68
	v_cvt_f32_i32_e32 v71, v70
	v_sub_u32_e32 v70, 0x80, v70
	v_cvt_f32_i32_e32 v70, v70
	v_or_b32_e32 v146, v120, v69
	v_mul_f32_e32 v71, v117, v71
	v_mul_f32_e32 v71, 0x3fb8aa3b, v71
	v_exp_f32_e32 v106, v71
	v_sub_u32_e32 v71, 0x80, v68
	v_cvt_f32_i32_e32 v71, v71
	v_mul_f32_e32 v70, v118, v70
	v_mul_f32_e32 v70, 0x3fb8aa3b, v70
	v_exp_f32_e32 v109, v70
	v_mul_f32_e32 v71, v118, v71
	v_mul_f32_e32 v71, 0x3fb8aa3b, v71
	v_exp_f32_e32 v108, v71
	v_or_b32_e32 v71, 2, v68
	v_or_b32_e32 v70, 3, v68
	v_add_u32_e32 v68, 4, v68
	v_cvt_f32_i32_e32 v68, v68
	v_cvt_f32_i32_e32 v72, v71
	v_sub_u32_e32 v71, 0x80, v71
	v_cvt_f32_i32_e32 v71, v71
	v_mul_f32_e32 v68, v117, v68
	v_mul_f32_e32 v72, v117, v72
	v_mul_f32_e32 v68, 0x3fb8aa3b, v68
	v_mul_f32_e32 v72, 0x3fb8aa3b, v72
	v_exp_f32_e32 v111, v68
	v_sub_u32_e32 v68, 0x80, v70
	v_exp_f32_e32 v107, v72
	v_cvt_f32_i32_e32 v72, v70
	v_cvt_f32_i32_e32 v68, v68
	v_mul_f32_e32 v71, v118, v71
	v_mul_f32_e32 v71, 0x3fb8aa3b, v71
	v_mul_f32_e32 v72, v117, v72
	v_mul_f32_e32 v68, v118, v68
	v_mul_f32_e32 v72, 0x3fb8aa3b, v72
	v_mul_f32_e32 v68, 0x3fb8aa3b, v68
	v_or_b32_e32 v147, v120, v82
	v_or_b32_e32 v148, v120, v83
	v_or_b32_e32 v121, v120, v121
	v_exp_f32_e32 v110, v72
	v_exp_f32_e32 v112, v71
	v_exp_f32_e32 v113, v68
	ds_read_b128 v[68:71], v146
	ds_read_b128 v[72:75], v147
	ds_read_b128 v[76:79], v148
	ds_read_b128 v[80:83], v121
	ds_read_b128 v[96:99], v146 offset:4096
	ds_read_b128 v[100:103], v147 offset:4096
	ds_read_b128 v[122:125], v148 offset:4096
	ds_read_b128 v[126:129], v121 offset:4096
	s_waitcnt lgkmcnt(7)
	v_mfma_f32_16x16x32_bf16 v[68:71], v[68:71], v[92:95], 0
	s_waitcnt lgkmcnt(6)
	v_mfma_f32_16x16x32_bf16 v[68:71], v[72:75], v[64:67], v[68:71]
	s_waitcnt lgkmcnt(5)
	v_mfma_f32_16x16x32_bf16 v[68:71], v[76:79], v[84:87], v[68:71]
	s_waitcnt lgkmcnt(4)
	v_mfma_f32_16x16x32_bf16 v[130:133], v[80:83], v[88:91], v[68:71]
	s_waitcnt lgkmcnt(3)
	v_mfma_f32_16x16x32_bf16 v[68:71], v[96:99], v[92:95], 0
	s_waitcnt lgkmcnt(2)
	v_mfma_f32_16x16x32_bf16 v[68:71], v[100:103], v[64:67], v[68:71]
	s_waitcnt lgkmcnt(1)
	v_mfma_f32_16x16x32_bf16 v[68:71], v[122:125], v[84:87], v[68:71]
	s_waitcnt lgkmcnt(0)
	v_mfma_f32_16x16x32_bf16 v[100:103], v[126:129], v[88:91], v[68:71]
	s_nop 5
	ds_read_b128 v[68:71], v146 offset:8192
	ds_read_b128 v[72:75], v146 offset:12288
	ds_read_b128 v[76:79], v147 offset:8192
	ds_read_b128 v[80:83], v147 offset:12288
	ds_read_b128 v[96:99], v148 offset:8192
	ds_read_b128 v[122:125], v148 offset:12288
	ds_read_b128 v[126:129], v121 offset:8192
	ds_read_b128 v[134:137], v121 offset:12288
	s_waitcnt lgkmcnt(7)
	v_mfma_f32_16x16x32_bf16 v[68:71], v[68:71], v[92:95], 0
	s_waitcnt lgkmcnt(5)
	v_mfma_f32_16x16x32_bf16 v[68:71], v[76:79], v[64:67], v[68:71]
	s_waitcnt lgkmcnt(3)
	v_mfma_f32_16x16x32_bf16 v[68:71], v[96:99], v[84:87], v[68:71]
	s_waitcnt lgkmcnt(1)
	v_mfma_f32_16x16x32_bf16 v[96:99], v[126:129], v[88:91], v[68:71]
	v_mfma_f32_16x16x32_bf16 v[68:71], v[72:75], v[92:95], 0
	v_mfma_f32_16x16x32_bf16 v[68:71], v[80:83], v[64:67], v[68:71]
	v_mfma_f32_16x16x32_bf16 v[68:71], v[122:125], v[84:87], v[68:71]
	s_waitcnt lgkmcnt(0)
	v_mfma_f32_16x16x32_bf16 v[80:83], v[134:137], v[88:91], v[68:71]
	s_nop 5
	ds_read_b128 v[68:71], v146 offset:16384
	ds_read_b128 v[72:75], v146 offset:20480
	ds_read_b128 v[76:79], v147 offset:16384
	ds_read_b128 v[122:125], v147 offset:20480
	ds_read_b128 v[126:129], v148 offset:16384
	ds_read_b128 v[134:137], v148 offset:20480
	ds_read_b128 v[138:141], v121 offset:16384
	ds_read_b128 v[142:145], v121 offset:20480
	s_waitcnt lgkmcnt(7)
	v_mfma_f32_16x16x32_bf16 v[68:71], v[68:71], v[92:95], 0
	s_waitcnt lgkmcnt(5)
	v_mfma_f32_16x16x32_bf16 v[68:71], v[76:79], v[64:67], v[68:71]
	s_waitcnt lgkmcnt(3)
	v_mfma_f32_16x16x32_bf16 v[68:71], v[126:129], v[84:87], v[68:71]
	s_waitcnt lgkmcnt(1)
	v_mfma_f32_16x16x32_bf16 v[76:79], v[138:141], v[88:91], v[68:71]
	v_mfma_f32_16x16x32_bf16 v[68:71], v[72:75], v[92:95], 0
	v_mfma_f32_16x16x32_bf16 v[68:71], v[122:125], v[64:67], v[68:71]
	v_mfma_f32_16x16x32_bf16 v[68:71], v[134:137], v[84:87], v[68:71]
	s_waitcnt lgkmcnt(0)
; DEVFI bfraw f2bf(float x) { unsigned u = __float_as_uint(x); u += 0x7fffu + ((u >> 16) & 1u); return (bfraw)(u >> 16); }
; #define SBAR() __builtin_amdgcn_sched_barrier(0)
; __global__ void __launch_bounds__(512) mega(Params p) {
;     ...
;             for (int n2 = 0; n2 < 4; ++n2) { bf16x8 A[2][4];
; #pragma unroll
;               for (int q2 = 0; q2 < 2; ++q2)
; #pragma unroll
;                 for (int sx = 0; sx < 4; ++sx) A[q2][sx] = RLD16(0, (n2 * 2 + q2) * 16 + fr, sx * 4 + fq);
;               SBAR();
; #pragma unroll
;               for (int q2 = 0; q2 < 2; ++q2)
; #pragma unroll
;                 for (int sx = 0; sx < 4; ++sx) sc[n2 * 2 + q2] = __builtin_amdgcn_mfma_f32_16x16x32_bf16(A[q2][sx], qf[sx], sc[n2 * 2 + q2], 0, 0, 0);
;               SBAR(); }
;             const int cc = w * 16 + fr;
; #pragma unroll
;             for (int sx = 0; sx < 4; ++sx)
; #pragma unroll
;               for (int hf = 0; hf < 2; ++hf)
; #pragma unroll
;                 for (int j = 0; j < 4; ++j) { const int n = 2 * sx + hf, mm = n * 16 + fq * 4 + j, diff = cc - mm;
;                   const float Dm = (diff >= 0) ? __expf(lgf * (float)diff) : __expf(lgb * (float)(-diff));
;                   pf[sx][hf * 4 + j] = (short)f2bf(sc[n][j] * Dm); } }
	v_mfma_f32_16x16x32_bf16 v[72:75], v[142:145], v[88:91], v[68:71]
	s_nop 5
	ds_read_b128 v[68:71], v146 offset:24576
	ds_read_b128 v[122:125], v146 offset:28672
	ds_read_b128 v[126:129], v147 offset:24576
	ds_read_b128 v[134:137], v147 offset:28672
	ds_read_b128 v[138:141], v148 offset:24576
	ds_read_b128 v[142:145], v148 offset:28672
	ds_read_b128 v[146:149], v121 offset:24576
	ds_read_b128 v[150:153], v121 offset:28672
	s_waitcnt lgkmcnt(7)
	v_mfma_f32_16x16x32_bf16 v[68:71], v[68:71], v[92:95], 0
	s_waitcnt lgkmcnt(6)
	v_mfma_f32_16x16x32_bf16 v[92:95], v[122:125], v[92:95], 0
	s_waitcnt lgkmcnt(5)
	v_mfma_f32_16x16x32_bf16 v[68:71], v[126:129], v[64:67], v[68:71]
	s_waitcnt lgkmcnt(4)
	v_mfma_f32_16x16x32_bf16 v[64:67], v[134:137], v[64:67], v[92:95]
	s_waitcnt lgkmcnt(3)
	v_mfma_f32_16x16x32_bf16 v[68:71], v[138:141], v[84:87], v[68:71]
	s_waitcnt lgkmcnt(2)
	v_mfma_f32_16x16x32_bf16 v[64:67], v[142:145], v[84:87], v[64:67]
	s_waitcnt lgkmcnt(1)
	v_mfma_f32_16x16x32_bf16 v[68:71], v[146:149], v[88:91], v[68:71]
	s_waitcnt lgkmcnt(0)
	v_mfma_f32_16x16x32_bf16 v[64:67], v[150:153], v[88:91], v[64:67]
	v_or_b32_e32 v87, s2, v115
	v_sub_u32_e32 v84, v87, v104
	v_sub_u32_e32 v85, 0, v84
	v_max_i32_e32 v85, v84, v85
	v_cvt_f32_u32_e32 v85, v85
	v_cmp_gt_i32_e32 vcc, 0, v84
	v_or_b32_e32 v86, 1, v104
	s_nop 0
	v_cndmask_b32_e32 v84, v117, v118, vcc
	v_mul_f32_e32 v84, v84, v85
	v_sub_u32_e32 v85, v87, v86
	v_sub_u32_e32 v88, 0, v85
	v_max_i32_e32 v88, v85, v88
	v_cvt_f32_u32_e32 v88, v88
	v_cmp_gt_i32_e32 vcc, 0, v85
	v_mul_f32_e32 v84, 0x3fb8aa3b, v84
	v_exp_f32_e32 v84, v84
	v_cndmask_b32_e32 v85, v117, v118, vcc
	v_mul_f32_e32 v85, v85, v88
	v_mul_f32_e32 v85, 0x3fb8aa3b, v85
	v_exp_f32_e32 v85, v85
	s_nop 0
	v_pk_mul_f32 v[94:95], v[84:85], v[130:131]
	v_or_b32_e32 v85, 2, v104
	v_sub_u32_e32 v84, v87, v85
	v_sub_u32_e32 v88, 0, v84
	v_max_i32_e32 v88, v84, v88
	v_cvt_f32_u32_e32 v88, v88
	v_cmp_gt_i32_e32 vcc, 0, v84
	v_bfe_u32 v124, v94, 16, 1
	v_bfe_u32 v123, v95, 16, 1
	v_cndmask_b32_e32 v84, v117, v118, vcc
	v_mul_f32_e32 v84, v84, v88
	v_mul_f32_e32 v84, 0x3fb8aa3b, v84
	v_exp_f32_e32 v88, v84
	v_or_b32_e32 v84, 3, v104
	v_sub_u32_e32 v89, v87, v84
	v_sub_u32_e32 v90, 0, v89
	v_max_i32_e32 v90, v89, v90
	v_cvt_f32_u32_e32 v90, v90
	v_cmp_gt_i32_e32 vcc, 0, v89
	s_nop 1
	v_cndmask_b32_e32 v89, v117, v118, vcc
	v_mul_f32_e32 v89, v89, v90
	v_or_b32_e32 v90, 16, v104
	v_sub_u32_e32 v90, v87, v90
	v_sub_u32_e32 v91, 0, v90
	v_max_i32_e32 v91, v90, v91
	v_cvt_f32_u32_e32 v91, v91
	v_cmp_gt_i32_e32 vcc, 0, v90
	v_mul_f32_e32 v89, 0x3fb8aa3b, v89
	v_exp_f32_e32 v89, v89
	v_cndmask_b32_e32 v90, v117, v118, vcc
	v_mul_f32_e32 v90, v90, v91
	v_or_b32_e32 v91, 17, v104
	v_sub_u32_e32 v91, v87, v91
	v_sub_u32_e32 v92, 0, v91
	v_max_i32_e32 v92, v91, v92
	v_cvt_f32_u32_e32 v92, v92
	v_cmp_gt_i32_e32 vcc, 0, v91
	v_mul_f32_e32 v90, 0x3fb8aa3b, v90
	v_exp_f32_e32 v90, v90
	v_cndmask_b32_e32 v91, v117, v118, vcc
	v_mul_f32_e32 v91, v91, v92
	v_mul_f32_e32 v91, 0x3fb8aa3b, v91
	v_exp_f32_e32 v91, v91
	v_pk_mul_f32 v[88:89], v[88:89], v[132:133]
	v_pk_mul_f32 v[100:101], v[90:91], v[100:101]
	v_or_b32_e32 v90, 18, v104
	v_sub_u32_e32 v90, v87, v90
	v_sub_u32_e32 v91, 0, v90
	v_max_i32_e32 v91, v90, v91
	v_cvt_f32_u32_e32 v91, v91
	v_cmp_gt_i32_e32 vcc, 0, v90
	v_bfe_u32 v122, v100, 16, 1
	v_bfe_u32 v121, v101, 16, 1
	v_cndmask_b32_e32 v90, v117, v118, vcc
	v_mul_f32_e32 v90, v90, v91
	v_or_b32_e32 v91, 19, v104
	v_sub_u32_e32 v91, v87, v91
	v_sub_u32_e32 v92, 0, v91
	v_max_i32_e32 v92, v91, v92
	v_cvt_f32_u32_e32 v92, v92
	v_cmp_gt_i32_e32 vcc, 0, v91
	v_mul_f32_e32 v90, 0x3fb8aa3b, v90
	v_exp_f32_e32 v90, v90
	v_cndmask_b32_e32 v91, v117, v118, vcc
	v_mul_f32_e32 v91, v91, v92
	v_mul_f32_e32 v91, 0x3fb8aa3b, v91
	v_exp_f32_e32 v91, v91
	s_nop 0
	v_pk_mul_f32 v[92:93], v[90:91], v[102:103]
	s_nop 0
	v_bfe_u32 v90, v93, 16, 1
	v_add3_u32 v93, v93, v90, s82
	v_add3_u32 v90, v94, v124, s82
	v_add3_u32 v94, v100, v122, s82
	v_or_b32_e32 v100, 32, v104
	v_bfe_u32 v91, v92, 16, 1
	v_sub_u32_e32 v100, v87, v100
	v_add3_u32 v91, v92, v91, s82
	v_add3_u32 v92, v95, v123, s82
	v_add3_u32 v95, v101, v121, s82
	v_sub_u32_e32 v101, 0, v100
	v_max_i32_e32 v101, v100, v101
	v_cvt_f32_u32_e32 v101, v101
	v_cmp_gt_i32_e32 vcc, 0, v100
	v_bfe_u32 v102, v89, 16, 1
	v_add3_u32 v89, v89, v102, s82
	v_cndmask_b32_e32 v100, v117, v118, vcc
	v_mul_f32_e32 v100, v100, v101
	v_or_b32_e32 v101, 33, v104
	v_sub_u32_e32 v101, v87, v101
	v_sub_u32_e32 v102, 0, v101
	v_max_i32_e32 v102, v101, v102
	v_cvt_f32_u32_e32 v102, v102
	v_cmp_gt_i32_e32 vcc, 0, v101
	v_mul_f32_e32 v100, 0x3fb8aa3b, v100
	v_exp_f32_e32 v100, v100
	v_cndmask_b32_e32 v101, v117, v118, vcc
	v_mul_f32_e32 v101, v101, v102
	v_mul_f32_e32 v101, 0x3fb8aa3b, v101
	v_exp_f32_e32 v101, v101
	v_bfe_u32 v103, v88, 16, 1
	v_add3_u32 v88, v88, v103, s82
	v_pk_mul_f32 v[100:101], v[100:101], v[96:97]
	v_or_b32_e32 v96, 34, v104
	v_sub_u32_e32 v96, v87, v96
	v_sub_u32_e32 v97, 0, v96
	v_max_i32_e32 v97, v96, v97
	v_cvt_f32_u32_e32 v97, v97
	v_cmp_gt_i32_e32 vcc, 0, v96
	v_bfe_u32 v124, v100, 16, 1
	v_bfe_u32 v123, v101, 16, 1
	v_cndmask_b32_e32 v96, v117, v118, vcc
	v_mul_f32_e32 v96, v96, v97
	v_or_b32_e32 v97, 35, v104
	v_sub_u32_e32 v97, v87, v97
	v_sub_u32_e32 v102, 0, v97
	v_max_i32_e32 v102, v97, v102
	v_cvt_f32_u32_e32 v102, v102
	v_cmp_gt_i32_e32 vcc, 0, v97
	v_mul_f32_e32 v96, 0x3fb8aa3b, v96
	v_exp_f32_e32 v96, v96
	v_cndmask_b32_e32 v97, v117, v118, vcc
	v_mul_f32_e32 v97, v97, v102
	v_mul_f32_e32 v97, 0x3fb8aa3b, v97
	v_exp_f32_e32 v97, v97
	s_nop 0
	v_pk_mul_f32 v[96:97], v[96:97], v[98:99]
; DEVFI bfraw f2bf(float x) { unsigned u = __float_as_uint(x); u += 0x7fffu + ((u >> 16) & 1u); return (bfraw)(u >> 16); }
; __global__ void __launch_bounds__(512) mega(Params p) {
;     ...
;             const int cc = w * 16 + fr;
; #pragma unroll
;             for (int sx = 0; sx < 4; ++sx)
; #pragma unroll
;               for (int hf = 0; hf < 2; ++hf)
; #pragma unroll
;                 for (int j = 0; j < 4; ++j) { const int n = 2 * sx + hf, mm = n * 16 + fq * 4 + j, diff = cc - mm;
;                   const float Dm = (diff >= 0) ? __expf(lgf * (float)diff) : __expf(lgb * (float)(-diff));
;                   pf[sx][hf * 4 + j] = (short)f2bf(sc[n][j] * Dm); } }
	v_or_b32_e32 v98, 48, v104
	v_sub_u32_e32 v98, v87, v98
	v_sub_u32_e32 v99, 0, v98
	v_max_i32_e32 v99, v98, v99
	v_cvt_f32_u32_e32 v99, v99
	v_cmp_gt_i32_e32 vcc, 0, v98
	s_nop 1
	v_cndmask_b32_e32 v98, v117, v118, vcc
	v_mul_f32_e32 v98, v98, v99
	v_or_b32_e32 v99, 49, v104
	v_sub_u32_e32 v99, v87, v99
	v_sub_u32_e32 v102, 0, v99
	v_max_i32_e32 v102, v99, v102
	v_cvt_f32_u32_e32 v102, v102
	v_cmp_gt_i32_e32 vcc, 0, v99
	v_mul_f32_e32 v98, 0x3fb8aa3b, v98
	v_exp_f32_e32 v98, v98
	v_cndmask_b32_e32 v99, v117, v118, vcc
	v_mul_f32_e32 v99, v99, v102
	v_mul_f32_e32 v99, 0x3fb8aa3b, v99
	v_exp_f32_e32 v99, v99
	s_nop 0
	v_pk_mul_f32 v[98:99], v[98:99], v[80:81]
	v_or_b32_e32 v80, 50, v104
	v_sub_u32_e32 v80, v87, v80
	v_sub_u32_e32 v81, 0, v80
	v_max_i32_e32 v81, v80, v81
	v_cvt_f32_u32_e32 v81, v81
	v_cmp_gt_i32_e32 vcc, 0, v80
	v_bfe_u32 v122, v98, 16, 1
	v_add3_u32 v98, v98, v122, s82
	v_cndmask_b32_e32 v80, v117, v118, vcc
	v_mul_f32_e32 v80, v80, v81
	v_or_b32_e32 v81, 51, v104
	v_sub_u32_e32 v81, v87, v81
	v_sub_u32_e32 v102, 0, v81
	v_max_i32_e32 v102, v81, v102
	v_cvt_f32_u32_e32 v102, v102
	v_cmp_gt_i32_e32 vcc, 0, v81
	v_mul_f32_e32 v80, 0x3fb8aa3b, v80
	v_exp_f32_e32 v80, v80
	v_cndmask_b32_e32 v81, v117, v118, vcc
	v_mul_f32_e32 v81, v81, v102
	v_mul_f32_e32 v81, 0x3fb8aa3b, v81
	v_exp_f32_e32 v81, v81
	v_bfe_u32 v121, v99, 16, 1
	v_add3_u32 v99, v99, v121, s82
	v_pk_mul_f32 v[102:103], v[80:81], v[82:83]
	s_nop 0
	v_bfe_u32 v82, v103, 16, 1
	v_bfe_u32 v81, v97, 16, 1
	v_add3_u32 v81, v97, v81, s82
	v_add3_u32 v97, v103, v82, s82
	v_add3_u32 v82, v100, v124, s82
	v_or_b32_e32 v100, 64, v104
	v_bfe_u32 v80, v96, 16, 1
	v_sub_u32_e32 v100, v87, v100
	v_add3_u32 v80, v96, v80, s82
	v_add3_u32 v96, v101, v123, s82
	v_sub_u32_e32 v101, 0, v100
	v_max_i32_e32 v101, v100, v101
	v_cvt_f32_u32_e32 v101, v101
	v_cmp_gt_i32_e32 vcc, 0, v100
	v_bfe_u32 v83, v102, 16, 1
	v_add3_u32 v83, v102, v83, s82
	v_cndmask_b32_e32 v100, v117, v118, vcc
	v_mul_f32_e32 v100, v100, v101
	v_or_b32_e32 v101, 0x41, v104
	v_sub_u32_e32 v101, v87, v101
	v_sub_u32_e32 v102, 0, v101
	v_max_i32_e32 v102, v101, v102
	v_cvt_f32_u32_e32 v102, v102
	v_cmp_gt_i32_e32 vcc, 0, v101
	v_mul_f32_e32 v100, 0x3fb8aa3b, v100
	v_exp_f32_e32 v100, v100
	v_cndmask_b32_e32 v101, v117, v118, vcc
	v_mul_f32_e32 v101, v101, v102
	v_mul_f32_e32 v101, 0x3fb8aa3b, v101
	v_exp_f32_e32 v101, v101
	s_nop 0
	v_pk_mul_f32 v[76:77], v[100:101], v[76:77]
	v_or_b32_e32 v100, 0x42, v104
	v_sub_u32_e32 v100, v87, v100
	v_sub_u32_e32 v101, 0, v100
	v_max_i32_e32 v101, v100, v101
	v_cvt_f32_u32_e32 v101, v101
	v_cmp_gt_i32_e32 vcc, 0, v100
	v_bfe_u32 v123, v77, 16, 1
	v_bfe_u32 v124, v76, 16, 1
	v_cndmask_b32_e32 v100, v117, v118, vcc
	v_mul_f32_e32 v100, v100, v101
	v_or_b32_e32 v101, 0x43, v104
	v_sub_u32_e32 v101, v87, v101
	v_sub_u32_e32 v102, 0, v101
	v_max_i32_e32 v102, v101, v102
	v_cvt_f32_u32_e32 v102, v102
	v_cmp_gt_i32_e32 vcc, 0, v101
	v_mul_f32_e32 v100, 0x3fb8aa3b, v100
	v_exp_f32_e32 v100, v100
	v_cndmask_b32_e32 v101, v117, v118, vcc
	v_mul_f32_e32 v101, v101, v102
	v_mul_f32_e32 v101, 0x3fb8aa3b, v101
	v_exp_f32_e32 v101, v101
	v_add3_u32 v142, v76, v124, s82
	v_add3_u32 v143, v77, v123, s82
	v_pk_mul_f32 v[78:79], v[100:101], v[78:79]
	v_or_b32_e32 v100, 0x50, v104
	v_sub_u32_e32 v100, v87, v100
	v_sub_u32_e32 v101, 0, v100
	v_max_i32_e32 v101, v100, v101
	v_cvt_f32_u32_e32 v101, v101
	v_cmp_gt_i32_e32 vcc, 0, v100
	v_bfe_u32 v103, v78, 16, 1
	v_add3_u32 v78, v78, v103, s82
	v_cndmask_b32_e32 v100, v117, v118, vcc
	v_mul_f32_e32 v100, v100, v101
	v_or_b32_e32 v101, 0x51, v104
	v_sub_u32_e32 v101, v87, v101
	v_sub_u32_e32 v102, 0, v101
	v_max_i32_e32 v102, v101, v102
	v_cvt_f32_u32_e32 v102, v102
	v_cmp_gt_i32_e32 vcc, 0, v101
	v_mul_f32_e32 v100, 0x3fb8aa3b, v100
	v_exp_f32_e32 v100, v100
	v_cndmask_b32_e32 v101, v117, v118, vcc
	v_mul_f32_e32 v101, v101, v102
	v_mul_f32_e32 v101, 0x3fb8aa3b, v101
	v_exp_f32_e32 v101, v101
	s_nop 0
	v_pk_mul_f32 v[72:73], v[100:101], v[72:73]
	v_or_b32_e32 v100, 0x52, v104
	v_sub_u32_e32 v100, v87, v100
	v_sub_u32_e32 v101, 0, v100
	v_max_i32_e32 v101, v100, v101
	v_cvt_f32_u32_e32 v101, v101
	v_cmp_gt_i32_e32 vcc, 0, v100
	v_bfe_u32 v122, v72, 16, 1
	v_add3_u32 v144, v72, v122, s82
	v_cndmask_b32_e32 v100, v117, v118, vcc
	v_mul_f32_e32 v100, v100, v101
	v_or_b32_e32 v101, 0x53, v104
	v_sub_u32_e32 v101, v87, v101
	v_sub_u32_e32 v102, 0, v101
	v_max_i32_e32 v102, v101, v102
	v_cvt_f32_u32_e32 v102, v102
	v_cmp_gt_i32_e32 vcc, 0, v101
	v_or_b32_e32 v72, 0x60, v104
	v_bfe_u32 v121, v73, 16, 1
	v_cndmask_b32_e32 v101, v117, v118, vcc
	v_sub_u32_e32 v72, v87, v72
	v_mul_f32_e32 v101, v101, v102
	v_add3_u32 v145, v73, v121, s82
	v_sub_u32_e32 v73, 0, v72
	v_mul_f32_e32 v100, 0x3fb8aa3b, v100
	v_mul_f32_e32 v101, 0x3fb8aa3b, v101
	v_max_i32_e32 v73, v72, v73
	v_exp_f32_e32 v100, v100
	v_exp_f32_e32 v101, v101
	v_cvt_f32_u32_e32 v73, v73
	v_cmp_gt_i32_e32 vcc, 0, v72
	v_bfe_u32 v102, v79, 16, 1
	v_pk_mul_f32 v[74:75], v[100:101], v[74:75]
	v_cndmask_b32_e32 v72, v117, v118, vcc
	v_mul_f32_e32 v72, v72, v73
	v_or_b32_e32 v73, 0x61, v104
	v_bfe_u32 v101, v74, 16, 1
	v_sub_u32_e32 v73, v87, v73
	v_add3_u32 v140, v74, v101, s82
	v_sub_u32_e32 v74, 0, v73
	v_max_i32_e32 v74, v73, v74
	v_cvt_f32_u32_e32 v74, v74
	v_cmp_gt_i32_e32 vcc, 0, v73
	v_mul_f32_e32 v72, 0x3fb8aa3b, v72
	v_exp_f32_e32 v72, v72
	v_cndmask_b32_e32 v73, v117, v118, vcc
	v_mul_f32_e32 v73, v73, v74
	v_mul_f32_e32 v73, 0x3fb8aa3b, v73
	v_exp_f32_e32 v73, v73
	v_bfe_u32 v100, v75, 16, 1
	v_add3_u32 v141, v75, v100, s82
	v_add3_u32 v79, v79, v102, s82
	v_pk_mul_f32 v[68:69], v[72:73], v[68:69]
; DEVFI bfraw f2bf(float x) { unsigned u = __float_as_uint(x); u += 0x7fffu + ((u >> 16) & 1u); return (bfraw)(u >> 16); }
; #define SBAR() __builtin_amdgcn_sched_barrier(0)
; __global__ void __launch_bounds__(512) mega(Params p) {
;     ...
;             for (int j = 0; j < 4; ++j) { const int c = w * 16 + fq * 4 + j; const float xf = __expf(lgf * (float)(c + 1)), xb = __expf(lgb * (float)(128 - c));
; #pragma unroll
;               for (int ne = 0; ne < 8; ++ne) o[ne][j] = xf * af[ne][j] + xb * ab[ne][j]; } }
;     ...
;             const int cc = w * 16 + fr;
; #pragma unroll
;             for (int sx = 0; sx < 4; ++sx)
; #pragma unroll
;               for (int hf = 0; hf < 2; ++hf)
; #pragma unroll
;                 for (int j = 0; j < 4; ++j) { const int n = 2 * sx + hf, mm = n * 16 + fq * 4 + j, diff = cc - mm;
;                   const float Dm = (diff >= 0) ? __expf(lgf * (float)diff) : __expf(lgb * (float)(-diff));
;                   pf[sx][hf * 4 + j] = (short)f2bf(sc[n][j] * Dm); } }
;           { const char* vl = shm + 32768 + fr * 256 + (fq & 1) * 8;
; #pragma unroll
;             for (int n2 = 0; n2 < 4; ++n2) { s16x4 lo[2][4], hi[2][4];
; #pragma unroll
;               for (int q2 = 0; q2 < 2; ++q2)
; #pragma unroll
;                 for (int sx = 0; sx < 4; ++sx) { lo[q2][sx] = *(const s16x4*)(vl + (n2 * 2 + q2) * 4096 + ((((sx * 4 + (fq >> 1)) ^ fr) & 15) << 4));
;                   hi[q2][sx] = *(const s16x4*)(vl + (n2 * 2 + q2) * 4096 + ((((sx * 4 + 2 + (fq >> 1)) ^ fr) & 15) << 4)); }
;               SBAR();
; #pragma unroll
;               for (int q2 = 0; q2 < 2; ++q2)
; #pragma unroll
;                 for (int sx = 0; sx < 4; ++sx) { const bf16x8 B = {lo[q2][sx][0], lo[q2][sx][1], lo[q2][sx][2], lo[q2][sx][3], hi[q2][sx][0], hi[q2][sx][1], hi[q2][sx][2], hi[q2][sx][3]};
;                   o[n2 * 2 + q2] = __builtin_amdgcn_mfma_f32_16x16x32_bf16(pf[sx], B, o[n2 * 2 + q2], 0, 0, 0); }
;               SBAR(); } }
	v_or_b32_e32 v72, 0x62, v104
	v_sub_u32_e32 v72, v87, v72
	v_sub_u32_e32 v73, 0, v72
	v_max_i32_e32 v73, v72, v73
	v_cvt_f32_u32_e32 v73, v73
	v_cmp_gt_i32_e32 vcc, 0, v72
	v_bfe_u32 v100, v68, 16, 1
	v_add3_u32 v150, v68, v100, s82
	v_cndmask_b32_e32 v72, v117, v118, vcc
	v_mul_f32_e32 v72, v72, v73
	v_or_b32_e32 v73, 0x63, v104
	v_sub_u32_e32 v73, v87, v73
	v_sub_u32_e32 v74, 0, v73
	v_max_i32_e32 v74, v73, v74
	v_cvt_f32_u32_e32 v74, v74
	v_cmp_gt_i32_e32 vcc, 0, v73
	v_mul_f32_e32 v72, 0x3fb8aa3b, v72
	v_exp_f32_e32 v72, v72
	v_cndmask_b32_e32 v73, v117, v118, vcc
	v_mul_f32_e32 v73, v73, v74
	v_mul_f32_e32 v73, 0x3fb8aa3b, v73
	v_exp_f32_e32 v73, v73
	s_nop 0
	v_pk_mul_f32 v[70:71], v[72:73], v[70:71]
	v_or_b32_e32 v72, 0x70, v104
	v_sub_u32_e32 v72, v87, v72
	v_sub_u32_e32 v73, 0, v72
	v_max_i32_e32 v73, v72, v73
	v_cvt_f32_u32_e32 v73, v73
	v_cmp_gt_i32_e32 vcc, 0, v72
	v_bfe_u32 v75, v70, 16, 1
	v_add3_u32 v146, v70, v75, s82
	v_cndmask_b32_e32 v72, v117, v118, vcc
	v_mul_f32_e32 v72, v72, v73
	v_or_b32_e32 v73, 0x71, v104
	v_sub_u32_e32 v73, v87, v73
	v_sub_u32_e32 v74, 0, v73
	v_max_i32_e32 v74, v73, v74
	v_cvt_f32_u32_e32 v74, v74
	v_cmp_gt_i32_e32 vcc, 0, v73
	v_mul_f32_e32 v72, 0x3fb8aa3b, v72
	v_exp_f32_e32 v72, v72
	v_cndmask_b32_e32 v73, v117, v118, vcc
	v_mul_f32_e32 v73, v73, v74
	v_mul_f32_e32 v73, 0x3fb8aa3b, v73
	v_exp_f32_e32 v73, v73
	s_nop 0
	v_pk_mul_f32 v[64:65], v[72:73], v[64:65]
	v_or_b32_e32 v72, 0x72, v104
	v_sub_u32_e32 v72, v87, v72
	v_sub_u32_e32 v73, 0, v72
	v_max_i32_e32 v73, v72, v73
	v_cvt_f32_u32_e32 v73, v73
	v_cmp_gt_i32_e32 vcc, 0, v72
	v_bfe_u32 v76, v65, 16, 1
	v_bfe_u32 v77, v64, 16, 1
	v_cndmask_b32_e32 v72, v117, v118, vcc
	v_mul_f32_e32 v72, v72, v73
	v_or_b32_e32 v73, 0x73, v104
	v_sub_u32_e32 v73, v87, v73
	v_sub_u32_e32 v74, 0, v73
	v_max_i32_e32 v74, v73, v74
	v_cvt_f32_u32_e32 v74, v74
	v_cmp_gt_i32_e32 vcc, 0, v73
	v_mul_f32_e32 v72, 0x3fb8aa3b, v72
	v_exp_f32_e32 v72, v72
	v_cndmask_b32_e32 v73, v117, v118, vcc
	v_mul_f32_e32 v73, v73, v74
	v_mul_f32_e32 v73, 0x3fb8aa3b, v73
	v_exp_f32_e32 v73, v73
	v_add3_u32 v151, v64, v77, s82
	v_add3_u32 v152, v65, v76, s82
	v_lshrrev_b32_e32 v64, 1, v116
	v_pk_mul_f32 v[66:67], v[72:73], v[66:67]
	v_bfe_u32 v65, v119, 1, 1
	v_bfe_u32 v73, v66, 16, 1
	v_add3_u32 v148, v66, v73, s82
	v_and_or_b32 v64, v64, 8, v120
	v_bitop3_b32 v66, v65, v116, 15 bitop3:0x78
	v_lshl_or_b32 v153, v66, 4, v64
	v_bitop3_b32 v66, v65, v115, 2 bitop3:0x36
	v_lshl_or_b32 v154, v66, 4, v64
	v_bitop3_b32 v66, v65, v115, 4 bitop3:0x36
	v_lshl_or_b32 v155, v66, 4, v64
	v_bitop3_b32 v66, v65, v115, 6 bitop3:0x36
	v_lshl_or_b32 v156, v66, 4, v64
	v_bitop3_b32 v66, v65, v115, 8 bitop3:0x36
	v_lshl_or_b32 v157, v66, 4, v64
	v_bitop3_b32 v66, v65, v115, 10 bitop3:0x36
	v_lshl_or_b32 v158, v66, 4, v64
	v_bitop3_b32 v66, v65, v115, 12 bitop3:0x36
	v_bitop3_b32 v65, v65, v115, 14 bitop3:0x36
	v_bfe_u32 v74, v71, 16, 1
	v_lshl_or_b32 v159, v66, 4, v64
	v_lshl_or_b32 v160, v65, 4, v64
	v_add3_u32 v147, v71, v74, s82
	ds_read2st64_b64 v[74:77], v153 offset0:64 offset1:72
	ds_read2st64_b64 v[100:103], v154 offset0:64 offset1:72
	ds_read2st64_b64 v[116:119], v155 offset0:64 offset1:72
	ds_read2st64_b64 v[120:123], v156 offset0:64 offset1:72
	ds_read2st64_b64 v[124:127], v157 offset0:64 offset1:72
	ds_read2st64_b64 v[128:131], v158 offset0:64 offset1:72
	ds_read2st64_b64 v[132:135], v159 offset0:64 offset1:72
	ds_read2st64_b64 v[136:139], v160 offset0:64 offset1:72
	v_bfe_u32 v72, v67, 16, 1
	v_bfe_u32 v87, v69, 16, 1
	v_add3_u32 v149, v67, v72, s82
	v_add3_u32 v87, v69, v87, s82
	v_perm_b32 v67, v93, v91, s58
	v_perm_b32 v65, v89, v88, s58
	v_perm_b32 v66, v95, v94, s58
	v_perm_b32 v64, v92, v90, s58
	v_pk_mul_f32 v[62:63], v[112:113], v[62:63]
	v_pk_mul_f32 v[60:61], v[108:109], v[60:61]
	s_waitcnt lgkmcnt(7)
	v_mov_b32_e32 v68, v74
	v_mov_b32_e32 v69, v75
	s_waitcnt lgkmcnt(6)
	v_mov_b32_e32 v70, v100
	v_mov_b32_e32 v71, v101
	v_pk_fma_f32 v[30:31], v[110:111], v[30:31], v[62:63]
	v_pk_fma_f32 v[28:29], v[106:107], v[28:29], v[60:61]
	v_perm_b32 v63, v97, v83, s58
	v_perm_b32 v61, v81, v80, s58
	v_perm_b32 v62, v99, v98, s58
	v_perm_b32 v60, v96, v82, s58
	v_mfma_f32_16x16x32_bf16 v[28:31], v[64:67], v[68:71], v[28:31]
	v_mul_f32_e64 v58, v112, v58
	v_mul_f32_e64 v59, v113, v59
	v_pk_mul_f32 v[56:57], v[108:109], v[56:57]
	v_mov_b32_e32 v100, v76
	v_mov_b32_e32 v101, v77
	v_pk_fma_f32 v[2:3], v[110:111], v[2:3], v[58:59]
	v_pk_fma_f32 v[0:1], v[106:107], v[0:1], v[56:57]
	s_waitcnt lgkmcnt(5)
	v_mov_b32_e32 v68, v116
	v_mov_b32_e32 v69, v117
	v_mfma_f32_16x16x32_bf16 v[0:3], v[64:67], v[100:103], v[0:3]
	s_waitcnt lgkmcnt(4)
	v_mov_b32_e32 v70, v120
	v_mov_b32_e32 v71, v121
	v_mov_b32_e32 v120, v118
	v_mov_b32_e32 v121, v119
	v_mfma_f32_16x16x32_bf16 v[28:31], v[60:63], v[68:71], v[28:31]
	v_perm_b32 v71, v141, v140, s58
	v_perm_b32 v69, v79, v78, s58
	v_perm_b32 v70, v145, v144, s58
	v_perm_b32 v68, v143, v142, s58
	v_mfma_f32_16x16x32_bf16 v[0:3], v[60:63], v[120:123], v[0:3]
	s_waitcnt lgkmcnt(3)
	v_mov_b32_e32 v72, v124
	v_mov_b32_e32 v73, v125
	s_waitcnt lgkmcnt(2)
	v_mov_b32_e32 v74, v128
	v_mov_b32_e32 v75, v129
	v_mov_b32_e32 v128, v126
	v_mov_b32_e32 v129, v127
	v_mfma_f32_16x16x32_bf16 v[28:31], v[68:71], v[72:75], v[28:31]
	v_perm_b32 v75, v149, v148, s58
	v_perm_b32 v73, v147, v146, s58
	v_perm_b32 v74, v152, v151, s58
	v_perm_b32 v72, v87, v150, s58
	v_mfma_f32_16x16x32_bf16 v[0:3], v[68:71], v[128:131], v[0:3]
	s_waitcnt lgkmcnt(1)
	v_mov_b32_e32 v78, v132
	v_mov_b32_e32 v79, v133
	s_waitcnt lgkmcnt(0)
; #define SBAR() __builtin_amdgcn_sched_barrier(0)
; __global__ void __launch_bounds__(512) mega(Params p) {
;     ...
;             for (int j = 0; j < 4; ++j) { const int c = w * 16 + fq * 4 + j; const float xf = __expf(lgf * (float)(c + 1)), xb = __expf(lgb * (float)(128 - c));
; #pragma unroll
;               for (int ne = 0; ne < 8; ++ne) o[ne][j] = xf * af[ne][j] + xb * ab[ne][j]; } }
;     ...
;           { const char* vl = shm + 32768 + fr * 256 + (fq & 1) * 8;
; #pragma unroll
;             for (int n2 = 0; n2 < 4; ++n2) { s16x4 lo[2][4], hi[2][4];
; #pragma unroll
;               for (int q2 = 0; q2 < 2; ++q2)
; #pragma unroll
;                 for (int sx = 0; sx < 4; ++sx) { lo[q2][sx] = *(const s16x4*)(vl + (n2 * 2 + q2) * 4096 + ((((sx * 4 + (fq >> 1)) ^ fr) & 15) << 4));
;                   hi[q2][sx] = *(const s16x4*)(vl + (n2 * 2 + q2) * 4096 + ((((sx * 4 + 2 + (fq >> 1)) ^ fr) & 15) << 4)); }
;               SBAR();
; #pragma unroll
;               for (int q2 = 0; q2 < 2; ++q2)
; #pragma unroll
;                 for (int sx = 0; sx < 4; ++sx) { const bf16x8 B = {lo[q2][sx][0], lo[q2][sx][1], lo[q2][sx][2], lo[q2][sx][3], hi[q2][sx][0], hi[q2][sx][1], hi[q2][sx][2], hi[q2][sx][3]};
;                   o[n2 * 2 + q2] = __builtin_amdgcn_mfma_f32_16x16x32_bf16(pf[sx], B, o[n2 * 2 + q2], 0, 0, 0); }
;               SBAR(); } }
	v_mov_b32_e32 v80, v136
	v_mov_b32_e32 v81, v137
	v_mov_b32_e32 v136, v134
	v_mov_b32_e32 v137, v135
	v_mfma_f32_16x16x32_bf16 v[28:31], v[72:75], v[78:81], v[28:31]
	s_nop 0
	v_mfma_f32_16x16x32_bf16 v[0:3], v[72:75], v[136:139], v[0:3]
	ds_read2st64_b64 v[56:59], v153 offset0:80 offset1:88
	ds_read2st64_b64 v[76:79], v154 offset0:80 offset1:88
	ds_read2st64_b64 v[80:83], v155 offset0:80 offset1:88
	ds_read2st64_b64 v[88:91], v156 offset0:80 offset1:88
	ds_read2st64_b64 v[92:95], v157 offset0:80 offset1:88
	ds_read2st64_b64 v[96:99], v158 offset0:80 offset1:88
	ds_read2st64_b64 v[100:103], v159 offset0:80 offset1:88
	ds_read2st64_b64 v[116:119], v160 offset0:80 offset1:88
	v_pk_mul_f32 v[54:55], v[112:113], v[54:55]
	v_pk_mul_f32 v[52:53], v[108:109], v[52:53]
	v_pk_mul_f32 v[50:51], v[112:113], v[50:51]
	v_pk_mul_f32 v[48:49], v[108:109], v[48:49]
	s_waitcnt lgkmcnt(7)
	v_mov_b32_e32 v120, v56
	v_mov_b32_e32 v121, v57
	s_waitcnt lgkmcnt(6)
	v_mov_b32_e32 v122, v76
	v_mov_b32_e32 v123, v77
	v_pk_fma_f32 v[6:7], v[110:111], v[6:7], v[54:55]
	v_pk_fma_f32 v[4:5], v[106:107], v[4:5], v[52:53]
	v_mov_b32_e32 v76, v58
	v_mov_b32_e32 v77, v59
	v_pk_fma_f32 v[10:11], v[110:111], v[10:11], v[50:51]
	v_pk_fma_f32 v[8:9], v[106:107], v[8:9], v[48:49]
	v_mfma_f32_16x16x32_bf16 v[4:7], v[64:67], v[120:123], v[4:7]
	s_waitcnt lgkmcnt(5)
	v_mov_b32_e32 v52, v80
	v_mov_b32_e32 v53, v81
	s_waitcnt lgkmcnt(4)
	v_mov_b32_e32 v54, v88
	v_mfma_f32_16x16x32_bf16 v[8:11], v[64:67], v[76:79], v[8:11]
	v_mov_b32_e32 v55, v89
	v_mov_b32_e32 v88, v82
	v_mov_b32_e32 v89, v83
	v_mfma_f32_16x16x32_bf16 v[4:7], v[60:63], v[52:55], v[4:7]
	s_waitcnt lgkmcnt(3)
	v_mov_b32_e32 v52, v92
	v_mov_b32_e32 v53, v93
	s_waitcnt lgkmcnt(2)
	v_mov_b32_e32 v54, v96
	v_mfma_f32_16x16x32_bf16 v[8:11], v[60:63], v[88:91], v[8:11]
	v_mov_b32_e32 v55, v97
	v_mov_b32_e32 v96, v94
	v_mov_b32_e32 v97, v95
	v_mfma_f32_16x16x32_bf16 v[4:7], v[68:71], v[52:55], v[4:7]
	s_waitcnt lgkmcnt(1)
	v_mov_b32_e32 v52, v100
	v_mov_b32_e32 v53, v101
	s_waitcnt lgkmcnt(0)
	v_mov_b32_e32 v54, v116
	v_mfma_f32_16x16x32_bf16 v[8:11], v[68:71], v[96:99], v[8:11]
	v_mov_b32_e32 v55, v117
	v_mov_b32_e32 v116, v102
	v_mov_b32_e32 v117, v103
	v_mfma_f32_16x16x32_bf16 v[4:7], v[72:75], v[52:55], v[4:7]
	s_nop 0
	v_mfma_f32_16x16x32_bf16 v[8:11], v[72:75], v[116:119], v[8:11]
	ds_read2st64_b64 v[48:51], v153 offset0:96 offset1:104
	ds_read2st64_b64 v[52:55], v154 offset0:96 offset1:104
	ds_read2st64_b64 v[56:59], v155 offset0:96 offset1:104
	ds_read2st64_b64 v[76:79], v156 offset0:96 offset1:104
	ds_read2st64_b64 v[80:83], v157 offset0:96 offset1:104
	ds_read2st64_b64 v[88:91], v158 offset0:96 offset1:104
	ds_read2st64_b64 v[92:95], v159 offset0:96 offset1:104
	ds_read2st64_b64 v[96:99], v160 offset0:96 offset1:104
	v_pk_mul_f32 v[46:47], v[112:113], v[46:47]
	v_pk_mul_f32 v[44:45], v[108:109], v[44:45]
	v_pk_mul_f32 v[42:43], v[112:113], v[42:43]
	v_pk_mul_f32 v[40:41], v[108:109], v[40:41]
	s_waitcnt lgkmcnt(7)
	v_mov_b32_e32 v100, v48
	v_mov_b32_e32 v101, v49
	s_waitcnt lgkmcnt(6)
	v_mov_b32_e32 v102, v52
	v_mov_b32_e32 v103, v53
	v_pk_fma_f32 v[14:15], v[110:111], v[14:15], v[46:47]
	v_pk_fma_f32 v[12:13], v[106:107], v[12:13], v[44:45]
	v_mov_b32_e32 v52, v50
	v_mov_b32_e32 v53, v51
	v_pk_fma_f32 v[18:19], v[110:111], v[18:19], v[42:43]
	v_pk_fma_f32 v[16:17], v[106:107], v[16:17], v[40:41]
	v_mfma_f32_16x16x32_bf16 v[12:15], v[64:67], v[100:103], v[12:15]
	s_waitcnt lgkmcnt(5)
	v_mov_b32_e32 v44, v56
	v_mov_b32_e32 v45, v57
	s_waitcnt lgkmcnt(4)
	v_mov_b32_e32 v46, v76
	v_mfma_f32_16x16x32_bf16 v[16:19], v[64:67], v[52:55], v[16:19]
	v_mov_b32_e32 v47, v77
	v_mov_b32_e32 v76, v58
	v_mov_b32_e32 v77, v59
	v_mfma_f32_16x16x32_bf16 v[12:15], v[60:63], v[44:47], v[12:15]
	s_waitcnt lgkmcnt(3)
	v_mov_b32_e32 v44, v80
	v_mov_b32_e32 v45, v81
	s_waitcnt lgkmcnt(2)
	v_mov_b32_e32 v46, v88
	v_mfma_f32_16x16x32_bf16 v[16:19], v[60:63], v[76:79], v[16:19]
	v_mov_b32_e32 v47, v89
	v_mov_b32_e32 v88, v82
	v_mov_b32_e32 v89, v83
	v_mfma_f32_16x16x32_bf16 v[12:15], v[68:71], v[44:47], v[12:15]
	s_waitcnt lgkmcnt(1)
	v_mov_b32_e32 v44, v92
	v_mov_b32_e32 v45, v93
	s_waitcnt lgkmcnt(0)
	v_mov_b32_e32 v46, v96
	v_mfma_f32_16x16x32_bf16 v[16:19], v[68:71], v[88:91], v[16:19]
	v_mov_b32_e32 v47, v97
	v_mov_b32_e32 v96, v94
	v_mov_b32_e32 v97, v95
	v_mfma_f32_16x16x32_bf16 v[12:15], v[72:75], v[44:47], v[12:15]
	s_nop 0
	v_mfma_f32_16x16x32_bf16 v[16:19], v[72:75], v[96:99], v[16:19]
	ds_read2st64_b64 v[40:43], v153 offset0:112 offset1:120
	ds_read2st64_b64 v[44:47], v154 offset0:112 offset1:120
	ds_read2st64_b64 v[48:51], v155 offset0:112 offset1:120
	ds_read2st64_b64 v[52:55], v156 offset0:112 offset1:120
	ds_read2st64_b64 v[56:59], v157 offset0:112 offset1:120
	ds_read2st64_b64 v[76:79], v158 offset0:112 offset1:120
	ds_read2st64_b64 v[80:83], v159 offset0:112 offset1:120
	ds_read2st64_b64 v[88:91], v160 offset0:112 offset1:120
	v_pk_mul_f32 v[38:39], v[112:113], v[38:39]
	v_pk_mul_f32 v[36:37], v[108:109], v[36:37]
	v_pk_mul_f32 v[34:35], v[112:113], v[34:35]
	v_pk_mul_f32 v[32:33], v[108:109], v[32:33]
	s_waitcnt lgkmcnt(7)
	v_mov_b32_e32 v92, v40
	v_mov_b32_e32 v93, v41
	s_waitcnt lgkmcnt(6)
	v_mov_b32_e32 v94, v44
	v_mov_b32_e32 v95, v45
	v_pk_fma_f32 v[22:23], v[110:111], v[22:23], v[38:39]
	v_pk_fma_f32 v[20:21], v[106:107], v[20:21], v[36:37]
	v_mov_b32_e32 v44, v42
	v_mov_b32_e32 v45, v43
	v_pk_fma_f32 v[26:27], v[110:111], v[26:27], v[34:35]
	v_pk_fma_f32 v[24:25], v[106:107], v[24:25], v[32:33]
	v_mfma_f32_16x16x32_bf16 v[20:23], v[64:67], v[92:95], v[20:23]
	s_waitcnt lgkmcnt(5)
; DEVFI float bf2f(bfraw h) { return __uint_as_float(((unsigned)h) << 16); }
; DEVFI bfraw f2bf(float x) { unsigned u = __float_as_uint(x); u += 0x7fffu + ((u >> 16) & 1u); return (bfraw)(u >> 16); }
; #define RG ((bfraw*)(kargs()->ws + O_RG))
; #define RO ((bfraw*)(kargs()->ws + O_RO))
; __global__ void __launch_bounds__(512) mega(Params p) {
;     ...
;           float gw[8];
; #pragma unroll
;           for (int ne = 0; ne < 8; ++ne) gw[ne] = gn_w[head * 128 + ne * 16 + fr];
; #pragma unroll
;           for (int j = 0; j < 4; ++j) { float s1 = 0;
; #pragma unroll
;             for (int ne = 0; ne < 8; ++ne) s1 += o[ne][j];
;             const float mean = red16(s1) * (1.f / 128.f); float s2 = 0;
; #pragma unroll
;             for (int ne = 0; ne < 8; ++ne) { const float dd = o[ne][j] - mean; s2 += dd * dd; }
;             const float rstd = 1.f / sqrtf(red16(s2) * (1.f / 128.f) + LN_EPS);
;             const long tok = tok0 + w * 16 + fq * 4 + j;
;             const bfraw* gp = RG + tok * 1024 + head * 128 + fr; bfraw* op = RO + tok * 1024 + head * 128 + fr;
; #pragma unroll
;             for (int ne = 0; ne < 8; ++ne) op[ne * 16] = f2bf((o[ne][j] - mean) * rstd * gw[ne] * bf2f(gp[ne * 16])); }
	v_mov_b32_e32 v36, v48
	v_mov_b32_e32 v37, v49
	s_waitcnt lgkmcnt(4)
	v_mov_b32_e32 v38, v52
	v_mfma_f32_16x16x32_bf16 v[24:27], v[64:67], v[44:47], v[24:27]
	v_mov_b32_e32 v39, v53
	v_mov_b32_e32 v52, v50
	v_mov_b32_e32 v53, v51
	v_mfma_f32_16x16x32_bf16 v[20:23], v[60:63], v[36:39], v[20:23]
	s_waitcnt lgkmcnt(3)
	v_mov_b32_e32 v36, v56
	v_mov_b32_e32 v37, v57
	s_waitcnt lgkmcnt(2)
	v_mov_b32_e32 v38, v76
	v_mfma_f32_16x16x32_bf16 v[24:27], v[60:63], v[52:55], v[24:27]
	v_mov_b32_e32 v39, v77
	v_mov_b32_e32 v76, v58
	v_mov_b32_e32 v77, v59
	v_mfma_f32_16x16x32_bf16 v[20:23], v[68:71], v[36:39], v[20:23]
	s_waitcnt lgkmcnt(1)
	v_mov_b32_e32 v36, v80
	v_mov_b32_e32 v37, v81
	s_waitcnt lgkmcnt(0)
	v_mov_b32_e32 v38, v88
	v_mfma_f32_16x16x32_bf16 v[24:27], v[68:71], v[76:79], v[24:27]
	v_mov_b32_e32 v39, v89
	v_mov_b32_e32 v88, v82
	v_mov_b32_e32 v89, v83
	v_mfma_f32_16x16x32_bf16 v[20:23], v[72:75], v[36:39], v[20:23]
	s_nop 0
	v_mfma_f32_16x16x32_bf16 v[24:27], v[72:75], v[88:91], v[24:27]
	s_mov_b64 s[2:3], s[0:1]
	s_load_dwordx2 s[4:5], s[2:3], 0x50
	s_lshl_b64 s[2:3], s[54:55], 2
	v_lshlrev_b32_e32 v32, 2, v115
	v_lshl_or_b32 v32, s17, 9, v32
	v_or_b32_e32 v104, s7, v104
	s_waitcnt lgkmcnt(0)
	s_add_u32 s4, s4, s2
	s_addc_u32 s5, s5, s3
	global_load_dword v43, v32, s[4:5]
	s_mov_b64 s[4:5], s[0:1]
	s_load_dwordx2 s[4:5], s[4:5], 0x50
	v_lshlrev_b32_e32 v176, 1, v115
	s_waitcnt lgkmcnt(0)
	s_add_u32 s4, s4, s2
	s_addc_u32 s5, s5, s3
	global_load_dword v36, v32, s[4:5] offset:64
	s_mov_b64 s[4:5], s[0:1]
	s_load_dwordx2 s[4:5], s[4:5], 0x50
	s_waitcnt lgkmcnt(0)
	s_add_u32 s4, s4, s2
	s_addc_u32 s5, s5, s3
	global_load_dword v37, v32, s[4:5] offset:128
	s_mov_b64 s[4:5], s[0:1]
	s_load_dwordx2 s[4:5], s[4:5], 0x50
	s_waitcnt lgkmcnt(0)
	s_add_u32 s4, s4, s2
	s_addc_u32 s5, s5, s3
	global_load_dword v38, v32, s[4:5] offset:192
	s_mov_b64 s[4:5], s[0:1]
	s_load_dwordx2 s[4:5], s[4:5], 0x50
	s_waitcnt lgkmcnt(0)
	s_add_u32 s4, s4, s2
	s_addc_u32 s5, s5, s3
	global_load_dword v39, v32, s[4:5] offset:256
	s_mov_b64 s[4:5], s[0:1]
	s_load_dwordx2 s[4:5], s[4:5], 0x50
	s_waitcnt lgkmcnt(0)
	s_add_u32 s4, s4, s2
	s_addc_u32 s5, s5, s3
	global_load_dword v41, v32, s[4:5] offset:320
	s_mov_b64 s[4:5], s[0:1]
	s_load_dwordx2 s[4:5], s[4:5], 0x50
	s_waitcnt lgkmcnt(0)
	s_add_u32 s4, s4, s2
	s_addc_u32 s5, s5, s3
	global_load_dword v40, v32, s[4:5] offset:384
	s_mov_b64 s[4:5], s[0:1]
	s_load_dwordx2 s[4:5], s[4:5], 0x50
	s_waitcnt lgkmcnt(0)
	s_add_u32 s2, s4, s2
	s_addc_u32 s3, s5, s3
	global_load_dword v42, v32, s[2:3] offset:448
	v_add_f32_e32 v32, 0, v28
	v_add_f32_e32 v32, v32, v0
	v_add_f32_e32 v32, v32, v4
	v_add_f32_e32 v32, v32, v8
	s_mov_b32 s2, -1
	v_add_f32_e32 v32, v32, v12
	v_add_f32_e32 v32, v32, v16
	v_mbcnt_lo_u32_b32 v33, s2, 0
	v_mbcnt_hi_u32_b32 v33, s2, v33
	v_add_f32_e32 v32, v32, v20
	v_lshlrev_b32_e32 v33, 2, v33
	v_add_f32_e32 v32, v32, v24
	v_xor_b32_e32 v34, 4, v33
	s_nop 1
	v_mov_b32_dpp v34, v32 quad_perm:[1,0,3,2] row_mask:0xf bank_mask:0xf
	s_mov_b32 s2, -1
	s_add_i32 s16, s16, s28
	s_add_u32 s8, s8, s72
	s_waitcnt lgkmcnt(0)
	v_add_f32_e32 v32, v32, v34
	v_xor_b32_e32 v34, 8, v33
	s_nop 1
	v_mov_b32_dpp v34, v32 quad_perm:[2,3,0,1] row_mask:0xf bank_mask:0xf
	s_addc_u32 s9, s9, s73
	s_add_i32 s6, s6, s59
	s_cmpk_gt_i32 s16, 0x3ff
	s_waitcnt lgkmcnt(0)
	v_add_f32_e32 v32, v32, v34
	v_xor_b32_e32 v34, 16, v33
	s_nop 1
	v_mov_b32_dpp v34, v32 row_half_mirror row_mask:0xf bank_mask:0xf
	s_nop 1
	v_mov_b32_dpp v34, v34 quad_perm:[3,2,1,0] row_mask:0xf bank_mask:0xf
	v_xor_b32_e32 v33, 32, v33
	s_waitcnt lgkmcnt(0)
	v_add_f32_e32 v32, v32, v34
	s_nop 1
	v_mov_b32_dpp v33, v32 row_ror:8 row_mask:0xf bank_mask:0xf
	s_waitcnt lgkmcnt(0)
	v_add_f32_e32 v32, v32, v33
	v_fmamk_f32 v45, v32, 0xbc000000, v0
	v_fmamk_f32 v50, v32, 0xbc000000, v28
	v_mul_f32_e32 v33, v45, v45
	v_fmac_f32_e32 v33, v50, v50
	v_fmamk_f32 v44, v32, 0xbc000000, v4
	v_fmac_f32_e32 v33, v44, v44
	v_fmamk_f32 v28, v32, 0xbc000000, v8
	v_fmac_f32_e32 v33, v28, v28
	v_fmamk_f32 v12, v32, 0xbc000000, v12
	v_fmac_f32_e32 v33, v12, v12
	v_fmamk_f32 v8, v32, 0xbc000000, v16
	v_mbcnt_lo_u32_b32 v16, s2, 0
	v_fmac_f32_e32 v33, v8, v8
	v_fmamk_f32 v4, v32, 0xbc000000, v20
	v_mbcnt_hi_u32_b32 v16, s2, v16
	v_fmac_f32_e32 v33, v4, v4
	v_fmamk_f32 v0, v32, 0xbc000000, v24
	v_lshlrev_b32_e32 v16, 2, v16
	v_fmac_f32_e32 v33, v0, v0
	v_xor_b32_e32 v20, 4, v16
	s_nop 1
	v_mov_b32_dpp v20, v33 quad_perm:[1,0,3,2] row_mask:0xf bank_mask:0xf
	v_xor_b32_e32 v24, 8, v16
	s_waitcnt lgkmcnt(0)
	v_add_f32_e32 v20, v33, v20
	s_nop 1
	v_mov_b32_dpp v24, v20 quad_perm:[2,3,0,1] row_mask:0xf bank_mask:0xf
	s_waitcnt lgkmcnt(0)
	v_add_f32_e32 v20, v20, v24
	v_xor_b32_e32 v24, 16, v16
	s_nop 1
	v_mov_b32_dpp v24, v20 row_half_mirror row_mask:0xf bank_mask:0xf
	s_nop 1
	v_mov_b32_dpp v24, v24 quad_perm:[3,2,1,0] row_mask:0xf bank_mask:0xf
	v_xor_b32_e32 v16, 32, v16
	s_waitcnt lgkmcnt(0)
	v_add_f32_e32 v20, v20, v24
	s_nop 1
	v_mov_b32_dpp v16, v20 row_ror:8 row_mask:0xf bank_mask:0xf
	s_waitcnt lgkmcnt(0)
	v_add_f32_e32 v16, v20, v16
	v_fmamk_f32 v16, v16, 0x3c000000, v183
	v_cmp_gt_f32_e32 vcc, s30, v16
	v_mul_f32_e32 v20, 0x4f800000, v16
	s_nop 0
	v_cndmask_b32_e32 v16, v16, v20, vcc
	v_sqrt_f32_e32 v20, v16
	s_nop 0
	v_add_u32_e32 v24, -1, v20
	v_fma_f32 v32, -v24, v20, v16
	v_cmp_ge_f32_e64 s[4:5], 0, v32
	v_add_u32_e32 v32, 1, v20
	s_nop 0
	v_cndmask_b32_e64 v24, v20, v24, s[4:5]
	v_fma_f32 v20, -v32, v20, v16
	v_cmp_lt_f32_e64 s[4:5], 0, v20
	s_nop 1
	v_cndmask_b32_e64 v20, v24, v32, s[4:5]
	v_mul_f32_e32 v24, 0x37800000, v20
	v_cndmask_b32_e32 v20, v20, v24, vcc
	v_cmp_class_f32_e32 vcc, v16, v222
	s_nop 1
	v_cndmask_b32_e32 v16, v20, v16, vcc
	s_mov_b64 s[2:3], s[0:1]
	s_load_dwordx2 s[2:3], s[2:3], 0xe8
	v_lshlrev_b64 v[34:35], 11, v[104:105]
	v_rcp_f32_e32 v24, v16
	s_nop 0
	v_fma_f32 v20, -v16, v24, 1.0
	v_fma_f32 v20, v20, v24, v24
	s_waitcnt lgkmcnt(0)
; DEVFI float bf2f(bfraw h) { return __uint_as_float(((unsigned)h) << 16); }
; DEVFI bfraw f2bf(float x) { unsigned u = __float_as_uint(x); u += 0x7fffu + ((u >> 16) & 1u); return (bfraw)(u >> 16); }
; #define RG ((bfraw*)(kargs()->ws + O_RG))
; #define RO ((bfraw*)(kargs()->ws + O_RO))
; __global__ void __launch_bounds__(512) mega(Params p) {
;     ...
;           for (int j = 0; j < 4; ++j) { float s1 = 0;
; #pragma unroll
;             for (int ne = 0; ne < 8; ++ne) s1 += o[ne][j];
;             const float mean = red16(s1) * (1.f / 128.f); float s2 = 0;
; #pragma unroll
;             for (int ne = 0; ne < 8; ++ne) { const float dd = o[ne][j] - mean; s2 += dd * dd; }
;             const float rstd = 1.f / sqrtf(red16(s2) * (1.f / 128.f) + LN_EPS);
;             const long tok = tok0 + w * 16 + fq * 4 + j;
;             const bfraw* gp = RG + tok * 1024 + head * 128 + fr; bfraw* op = RO + tok * 1024 + head * 128 + fr;
; #pragma unroll
;             for (int ne = 0; ne < 8; ++ne) op[ne * 16] = f2bf((o[ne][j] - mean) * rstd * gw[ne] * bf2f(gp[ne * 16])); }
	v_lshl_add_u64 v[32:33], s[2:3], 0, v[34:35]
	v_lshl_add_u64 v[32:33], v[32:33], 0, s[12:13]
	v_lshl_add_u64 v[46:47], v[32:33], 0, v[176:177]
	v_lshl_add_u64 v[32:33], v[46:47], 0, s[42:43]
	v_add_co_u32_e32 v46, vcc, s68, v46
	s_mov_b64 s[2:3], s[0:1]
	s_nop 0
	v_addc_co_u32_e32 v47, vcc, 0, v47, vcc
	global_load_ushort v24, v[46:47], off
	global_load_ushort v184, v[32:33], off offset:32
	global_load_ushort v185, v[32:33], off offset:64
	global_load_ushort v186, v[32:33], off offset:96
	global_load_ushort v187, v[32:33], off offset:128
	global_load_ushort v188, v[32:33], off offset:160
	global_load_ushort v189, v[32:33], off offset:192
	global_load_ushort v190, v[32:33], off offset:224
	s_load_dwordx2 s[2:3], s[2:3], 0xe8
	v_div_fixup_f32 v16, v20, v16, 1.0
	v_mul_f32_e32 v20, v16, v50
	s_waitcnt vmcnt(8)
	v_mul_f32_e32 v20, v20, v43
	v_mul_f32_e32 v12, v16, v12
	s_waitcnt lgkmcnt(0)
	v_lshl_add_u64 v[34:35], s[2:3], 0, v[34:35]
	v_lshl_add_u64 v[34:35], v[34:35], 0, s[12:13]
	v_lshl_add_u64 v[48:49], v[34:35], 0, v[176:177]
	v_add_co_u32_e32 v46, vcc, s69, v48
	v_lshl_add_u64 v[34:35], v[48:49], 0, s[50:51]
	s_nop 0
	v_addc_co_u32_e32 v47, vcc, 0, v49, vcc
	s_waitcnt vmcnt(4)
	v_mul_f32_e32 v12, v12, v39
	v_mul_f32_e32 v8, v16, v8
	s_waitcnt vmcnt(3)
	v_mul_f32_e32 v8, v8, v41
	v_mul_f32_e32 v4, v16, v4
	s_waitcnt vmcnt(2)
	v_mul_f32_e32 v4, v4, v40
	v_mul_f32_e32 v0, v16, v0
	s_waitcnt vmcnt(1)
	v_mul_f32_e32 v0, v0, v42
	s_mov_b32 s2, -1
	v_or_b32_e32 v104, s7, v86
	s_waitcnt vmcnt(0)
	v_lshlrev_b32_e32 v24, 16, v24
	v_mul_f32_e32 v20, v20, v24
	v_bfe_u32 v24, v20, 16, 1
	v_add3_u32 v20, v20, v24, s82
	global_store_short_d16_hi v[46:47], v20, off
	v_mul_f32_e32 v20, v16, v45
	v_mul_f32_e32 v20, v20, v36
	v_lshlrev_b32_e32 v24, 16, v184
	v_mul_f32_e32 v20, v20, v24
	v_bfe_u32 v24, v20, 16, 1
	v_add3_u32 v20, v20, v24, s82
	global_store_short_d16_hi v[34:35], v20, off offset:32
	v_mul_f32_e32 v20, v16, v44
	v_mul_f32_e32 v20, v20, v37
	v_lshlrev_b32_e32 v24, 16, v185
	v_mul_f32_e32 v20, v20, v24
	v_bfe_u32 v24, v20, 16, 1
	v_add3_u32 v20, v20, v24, s82
	global_store_short_d16_hi v[34:35], v20, off offset:64
	v_mul_f32_e32 v20, v16, v28
	v_mul_f32_e32 v20, v20, v38
	v_lshlrev_b32_e32 v24, 16, v186
	v_mul_f32_e32 v20, v20, v24
	v_bfe_u32 v24, v20, 16, 1
	v_add3_u32 v20, v20, v24, s82
	global_store_short_d16_hi v[34:35], v20, off offset:96
	v_lshlrev_b32_e32 v20, 16, v187
	v_mul_f32_e32 v12, v12, v20
	v_bfe_u32 v20, v12, 16, 1
	v_add3_u32 v12, v12, v20, s82
	global_store_short_d16_hi v[34:35], v12, off offset:128
	v_lshlrev_b32_e32 v12, 16, v188
	v_mul_f32_e32 v8, v8, v12
	v_bfe_u32 v12, v8, 16, 1
	v_add3_u32 v8, v8, v12, s82
	global_store_short_d16_hi v[34:35], v8, off offset:160
	v_lshlrev_b32_e32 v8, 16, v189
	v_mul_f32_e32 v4, v4, v8
	v_bfe_u32 v8, v4, 16, 1
	v_add3_u32 v4, v4, v8, s82
	global_store_short_d16_hi v[34:35], v4, off offset:192
	v_lshlrev_b32_e32 v4, 16, v190
	v_mul_f32_e32 v0, v0, v4
	v_bfe_u32 v4, v0, 16, 1
	v_add3_u32 v0, v0, v4, s82
	global_store_short_d16_hi v[34:35], v0, off offset:224
	v_add_f32_e32 v0, 0, v29
	v_add_f32_e32 v0, v0, v1
	v_add_f32_e32 v0, v0, v5
	v_add_f32_e32 v0, v0, v9
	v_add_f32_e32 v0, v0, v13
	v_add_f32_e32 v0, v0, v17
	v_mbcnt_lo_u32_b32 v4, s2, 0
	v_mbcnt_hi_u32_b32 v4, s2, v4
	v_add_f32_e32 v0, v0, v21
	v_lshlrev_b32_e32 v4, 2, v4
	v_add_f32_e32 v0, v0, v25
	v_xor_b32_e32 v8, 4, v4
	s_nop 1
	v_mov_b32_dpp v8, v0 quad_perm:[1,0,3,2] row_mask:0xf bank_mask:0xf
	s_mov_b32 s2, -1
	s_waitcnt lgkmcnt(0)
	v_add_f32_e32 v0, v0, v8
	v_xor_b32_e32 v8, 8, v4
	s_nop 1
	v_mov_b32_dpp v8, v0 quad_perm:[2,3,0,1] row_mask:0xf bank_mask:0xf
	s_waitcnt lgkmcnt(0)
	v_add_f32_e32 v0, v0, v8
	v_xor_b32_e32 v8, 16, v4
	s_nop 1
	v_mov_b32_dpp v8, v0 row_half_mirror row_mask:0xf bank_mask:0xf
	s_nop 1
	v_mov_b32_dpp v8, v8 quad_perm:[3,2,1,0] row_mask:0xf bank_mask:0xf
	v_xor_b32_e32 v4, 32, v4
	s_waitcnt lgkmcnt(0)
	v_add_f32_e32 v0, v0, v8
	s_nop 1
	v_mov_b32_dpp v4, v0 row_ror:8 row_mask:0xf bank_mask:0xf
	s_waitcnt lgkmcnt(0)
	v_add_f32_e32 v0, v0, v4
	v_fmamk_f32 v24, v0, 0xbc000000, v1
	v_fmamk_f32 v34, v0, 0xbc000000, v29
	v_mul_f32_e32 v1, v24, v24
	v_fmac_f32_e32 v1, v34, v34
	v_fmamk_f32 v20, v0, 0xbc000000, v5
	v_fmac_f32_e32 v1, v20, v20
	v_fmamk_f32 v16, v0, 0xbc000000, v9
	v_fmac_f32_e32 v1, v16, v16
	v_fmamk_f32 v13, v0, 0xbc000000, v13
	v_fmac_f32_e32 v1, v13, v13
	v_fmamk_f32 v12, v0, 0xbc000000, v17
	v_fmamk_f32 v9, v0, 0xbc000000, v21
	v_fmamk_f32 v8, v0, 0xbc000000, v25
	v_mbcnt_lo_u32_b32 v0, s2, 0
	v_fmac_f32_e32 v1, v12, v12
	v_mbcnt_hi_u32_b32 v0, s2, v0
	v_fmac_f32_e32 v1, v9, v9
	v_lshlrev_b32_e32 v0, 2, v0
	v_fmac_f32_e32 v1, v8, v8
	v_xor_b32_e32 v4, 4, v0
	s_nop 1
	v_mov_b32_dpp v4, v1 quad_perm:[1,0,3,2] row_mask:0xf bank_mask:0xf
	s_waitcnt lgkmcnt(0)
	v_add_f32_e32 v1, v1, v4
	v_xor_b32_e32 v4, 8, v0
	s_nop 1
	v_mov_b32_dpp v4, v1 quad_perm:[2,3,0,1] row_mask:0xf bank_mask:0xf
	s_waitcnt lgkmcnt(0)
	v_add_f32_e32 v1, v1, v4
	v_xor_b32_e32 v4, 16, v0
	s_nop 1
	v_mov_b32_dpp v4, v1 row_half_mirror row_mask:0xf bank_mask:0xf
	s_nop 1
	v_mov_b32_dpp v4, v4 quad_perm:[3,2,1,0] row_mask:0xf bank_mask:0xf
	v_xor_b32_e32 v0, 32, v0
	s_waitcnt lgkmcnt(0)
	v_add_f32_e32 v1, v1, v4
	s_nop 1
	v_mov_b32_dpp v0, v1 row_ror:8 row_mask:0xf bank_mask:0xf
	s_waitcnt lgkmcnt(0)
; DEVFI float bf2f(bfraw h) { return __uint_as_float(((unsigned)h) << 16); }
; DEVFI bfraw f2bf(float x) { unsigned u = __float_as_uint(x); u += 0x7fffu + ((u >> 16) & 1u); return (bfraw)(u >> 16); }
; #define RG ((bfraw*)(kargs()->ws + O_RG))
; #define RO ((bfraw*)(kargs()->ws + O_RO))
; __global__ void __launch_bounds__(512) mega(Params p) {
;     ...
;           for (int j = 0; j < 4; ++j) { float s1 = 0;
; #pragma unroll
;             for (int ne = 0; ne < 8; ++ne) s1 += o[ne][j];
;             const float mean = red16(s1) * (1.f / 128.f); float s2 = 0;
; #pragma unroll
;             for (int ne = 0; ne < 8; ++ne) { const float dd = o[ne][j] - mean; s2 += dd * dd; }
;             const float rstd = 1.f / sqrtf(red16(s2) * (1.f / 128.f) + LN_EPS);
;             const long tok = tok0 + w * 16 + fq * 4 + j;
;             const bfraw* gp = RG + tok * 1024 + head * 128 + fr; bfraw* op = RO + tok * 1024 + head * 128 + fr;
; #pragma unroll
;             for (int ne = 0; ne < 8; ++ne) op[ne * 16] = f2bf((o[ne][j] - mean) * rstd * gw[ne] * bf2f(gp[ne * 16])); }
	v_add_f32_e32 v0, v1, v0
	v_fmamk_f32 v0, v0, 0x3c000000, v183
	v_cmp_gt_f32_e32 vcc, s30, v0
	v_mul_f32_e32 v1, 0x4f800000, v0
	s_nop 0
	v_cndmask_b32_e32 v0, v0, v1, vcc
	v_sqrt_f32_e32 v1, v0
	s_nop 0
	v_add_u32_e32 v4, -1, v1
	v_fma_f32 v5, -v4, v1, v0
	v_cmp_ge_f32_e64 s[4:5], 0, v5
	v_add_u32_e32 v5, 1, v1
	s_nop 0
	v_cndmask_b32_e64 v4, v1, v4, s[4:5]
	v_fma_f32 v1, -v5, v1, v0
	v_cmp_lt_f32_e64 s[4:5], 0, v1
	s_nop 1
	v_cndmask_b32_e64 v1, v4, v5, s[4:5]
	v_mul_f32_e32 v4, 0x37800000, v1
	v_cndmask_b32_e32 v1, v1, v4, vcc
	v_cmp_class_f32_e32 vcc, v0, v222
	s_nop 1
	v_cndmask_b32_e32 v0, v1, v0, vcc
	s_mov_b64 s[2:3], s[0:1]
	s_load_dwordx2 s[2:3], s[2:3], 0xe8
	v_rcp_f32_e32 v4, v0
	s_nop 0
	v_fma_f32 v1, -v0, v4, 1.0
	v_fma_f32 v1, v1, v4, v4
	v_lshlrev_b64 v[4:5], 11, v[104:105]
	v_div_fixup_f32 v17, v1, v0, 1.0
	s_waitcnt lgkmcnt(0)
	v_lshl_add_u64 v[0:1], s[2:3], 0, v[4:5]
	v_lshl_add_u64 v[0:1], v[0:1], 0, s[12:13]
	v_lshl_add_u64 v[28:29], v[0:1], 0, v[176:177]
	v_lshl_add_u64 v[0:1], v[28:29], 0, s[42:43]
	v_add_co_u32_e32 v28, vcc, s68, v28
	s_mov_b64 s[2:3], s[0:1]
	s_nop 0
	v_addc_co_u32_e32 v29, vcc, 0, v29, vcc
	global_load_ushort v25, v[28:29], off
	global_load_ushort v184, v[0:1], off offset:32
	global_load_ushort v185, v[0:1], off offset:64
	global_load_ushort v186, v[0:1], off offset:96
	global_load_ushort v187, v[0:1], off offset:128
	global_load_ushort v188, v[0:1], off offset:160
	global_load_ushort v189, v[0:1], off offset:192
	global_load_ushort v190, v[0:1], off offset:224
	s_load_dwordx2 s[2:3], s[2:3], 0xe8
	v_mul_f32_e32 v21, v17, v34
	v_mul_f32_e32 v21, v21, v43
	v_mul_f32_e32 v20, v17, v20
	v_mul_f32_e32 v20, v20, v37
	s_waitcnt lgkmcnt(0)
	v_lshl_add_u64 v[4:5], s[2:3], 0, v[4:5]
	v_lshl_add_u64 v[4:5], v[4:5], 0, s[12:13]
	v_lshl_add_u64 v[32:33], v[4:5], 0, v[176:177]
	v_add_co_u32_e32 v28, vcc, s69, v32
	v_lshl_add_u64 v[4:5], v[32:33], 0, s[50:51]
	s_nop 0
	v_addc_co_u32_e32 v29, vcc, 0, v33, vcc
	v_mul_f32_e32 v16, v17, v16
	v_mul_f32_e32 v16, v16, v38
	v_mul_f32_e32 v13, v17, v13
	v_mul_f32_e32 v13, v13, v39
	v_mul_f32_e32 v12, v17, v12
	v_mul_f32_e32 v12, v12, v41
	v_mul_f32_e32 v9, v17, v9
	v_mul_f32_e32 v9, v9, v40
	v_mul_f32_e32 v8, v17, v8
	v_mul_f32_e32 v8, v8, v42
	s_mov_b32 s2, -1
	v_or_b32_e32 v104, s7, v85
	s_waitcnt vmcnt(0)
	v_lshlrev_b32_e32 v25, 16, v25
	v_mul_f32_e32 v21, v21, v25
	v_bfe_u32 v25, v21, 16, 1
	v_add3_u32 v21, v21, v25, s82
	global_store_short_d16_hi v[28:29], v21, off
	v_mul_f32_e32 v21, v17, v24
	v_mul_f32_e32 v21, v21, v36
	v_lshlrev_b32_e32 v24, 16, v184
	v_mul_f32_e32 v21, v21, v24
	v_bfe_u32 v24, v21, 16, 1
	v_add3_u32 v21, v21, v24, s82
	global_store_short_d16_hi v[4:5], v21, off offset:32
	v_lshlrev_b32_e32 v21, 16, v185
	v_mul_f32_e32 v20, v20, v21
	v_bfe_u32 v21, v20, 16, 1
	v_add3_u32 v20, v20, v21, s82
	global_store_short_d16_hi v[4:5], v20, off offset:64
	v_lshlrev_b32_e32 v20, 16, v186
	v_mul_f32_e32 v16, v16, v20
	v_bfe_u32 v20, v16, 16, 1
	v_add3_u32 v16, v16, v20, s82
	global_store_short_d16_hi v[4:5], v16, off offset:96
	v_lshlrev_b32_e32 v16, 16, v187
	v_mul_f32_e32 v13, v13, v16
	v_bfe_u32 v16, v13, 16, 1
	v_add3_u32 v13, v13, v16, s82
	global_store_short_d16_hi v[4:5], v13, off offset:128
	v_lshlrev_b32_e32 v13, 16, v188
	v_mul_f32_e32 v12, v12, v13
	v_bfe_u32 v13, v12, 16, 1
	v_add3_u32 v12, v12, v13, s82
	global_store_short_d16_hi v[4:5], v12, off offset:160
	v_lshlrev_b32_e32 v12, 16, v189
	v_mul_f32_e32 v9, v9, v12
	v_bfe_u32 v12, v9, 16, 1
	v_add3_u32 v9, v9, v12, s82
	global_store_short_d16_hi v[4:5], v9, off offset:192
	v_lshlrev_b32_e32 v0, 16, v190
	v_mul_f32_e32 v0, v8, v0
	v_bfe_u32 v1, v0, 16, 1
	v_add3_u32 v0, v0, v1, s82
	global_store_short_d16_hi v[4:5], v0, off offset:224
	v_add_f32_e32 v0, 0, v30
	v_add_f32_e32 v0, v0, v2
	v_add_f32_e32 v0, v0, v6
	v_add_f32_e32 v0, v0, v10
	v_add_f32_e32 v0, v0, v14
	v_add_f32_e32 v0, v0, v18
	v_mbcnt_lo_u32_b32 v1, s2, 0
	v_mbcnt_hi_u32_b32 v1, s2, v1
	v_add_f32_e32 v0, v0, v22
	v_lshlrev_b32_e32 v1, 2, v1
	v_add_f32_e32 v0, v0, v26
	v_xor_b32_e32 v4, 4, v1
	s_nop 1
	v_mov_b32_dpp v4, v0 quad_perm:[1,0,3,2] row_mask:0xf bank_mask:0xf
	s_mov_b32 s2, -1
	s_waitcnt lgkmcnt(0)
	v_add_f32_e32 v0, v0, v4
	v_xor_b32_e32 v4, 8, v1
	s_nop 1
	v_mov_b32_dpp v4, v0 quad_perm:[2,3,0,1] row_mask:0xf bank_mask:0xf
	s_waitcnt lgkmcnt(0)
	v_add_f32_e32 v0, v0, v4
	v_xor_b32_e32 v4, 16, v1
	s_nop 1
	v_mov_b32_dpp v4, v0 row_half_mirror row_mask:0xf bank_mask:0xf
	s_nop 1
	v_mov_b32_dpp v4, v4 quad_perm:[3,2,1,0] row_mask:0xf bank_mask:0xf
	v_xor_b32_e32 v1, 32, v1
	s_waitcnt lgkmcnt(0)
	v_add_f32_e32 v0, v0, v4
	s_nop 1
	v_mov_b32_dpp v1, v0 row_ror:8 row_mask:0xf bank_mask:0xf
	s_waitcnt lgkmcnt(0)
	v_add_f32_e32 v0, v0, v1
	v_fmamk_f32 v13, v0, 0xbc000000, v2
	v_fmamk_f32 v24, v0, 0xbc000000, v30
	v_mul_f32_e32 v1, v13, v13
	v_fmac_f32_e32 v1, v24, v24
	v_fmamk_f32 v12, v0, 0xbc000000, v6
	v_fmac_f32_e32 v1, v12, v12
	v_fmamk_f32 v10, v0, 0xbc000000, v10
	v_fmac_f32_e32 v1, v10, v10
	v_fmamk_f32 v9, v0, 0xbc000000, v14
	v_fmac_f32_e32 v1, v9, v9
	v_fmamk_f32 v8, v0, 0xbc000000, v18
	v_fmamk_f32 v6, v0, 0xbc000000, v22
	v_fmamk_f32 v2, v0, 0xbc000000, v26
	v_mbcnt_lo_u32_b32 v0, s2, 0
	v_fmac_f32_e32 v1, v8, v8
	v_mbcnt_hi_u32_b32 v0, s2, v0
	v_fmac_f32_e32 v1, v6, v6
	v_lshlrev_b32_e32 v0, 2, v0
	v_fmac_f32_e32 v1, v2, v2
	v_xor_b32_e32 v4, 4, v0
	s_nop 1
	v_mov_b32_dpp v4, v1 quad_perm:[1,0,3,2] row_mask:0xf bank_mask:0xf
	s_waitcnt lgkmcnt(0)
	v_add_f32_e32 v1, v1, v4
	v_xor_b32_e32 v4, 8, v0
	s_nop 1
	v_mov_b32_dpp v4, v1 quad_perm:[2,3,0,1] row_mask:0xf bank_mask:0xf
	s_waitcnt lgkmcnt(0)
; DEVFI float bf2f(bfraw h) { return __uint_as_float(((unsigned)h) << 16); }
; DEVFI bfraw f2bf(float x) { unsigned u = __float_as_uint(x); u += 0x7fffu + ((u >> 16) & 1u); return (bfraw)(u >> 16); }
; #define RG ((bfraw*)(kargs()->ws + O_RG))
; #define RO ((bfraw*)(kargs()->ws + O_RO))
; __global__ void __launch_bounds__(512) mega(Params p) {
;     ...
;           for (int j = 0; j < 4; ++j) { float s1 = 0;
; #pragma unroll
;             for (int ne = 0; ne < 8; ++ne) s1 += o[ne][j];
;             const float mean = red16(s1) * (1.f / 128.f); float s2 = 0;
; #pragma unroll
;             for (int ne = 0; ne < 8; ++ne) { const float dd = o[ne][j] - mean; s2 += dd * dd; }
;             const float rstd = 1.f / sqrtf(red16(s2) * (1.f / 128.f) + LN_EPS);
;             const long tok = tok0 + w * 16 + fq * 4 + j;
;             const bfraw* gp = RG + tok * 1024 + head * 128 + fr; bfraw* op = RO + tok * 1024 + head * 128 + fr;
; #pragma unroll
;             for (int ne = 0; ne < 8; ++ne) op[ne * 16] = f2bf((o[ne][j] - mean) * rstd * gw[ne] * bf2f(gp[ne * 16])); }
	v_add_f32_e32 v1, v1, v4
	v_xor_b32_e32 v4, 16, v0
	s_nop 1
	v_mov_b32_dpp v4, v1 row_half_mirror row_mask:0xf bank_mask:0xf
	s_nop 1
	v_mov_b32_dpp v4, v4 quad_perm:[3,2,1,0] row_mask:0xf bank_mask:0xf
	v_xor_b32_e32 v0, 32, v0
	s_waitcnt lgkmcnt(0)
	v_add_f32_e32 v1, v1, v4
	s_nop 1
	v_mov_b32_dpp v0, v1 row_ror:8 row_mask:0xf bank_mask:0xf
	s_waitcnt lgkmcnt(0)
	v_add_f32_e32 v0, v1, v0
	v_fmamk_f32 v0, v0, 0x3c000000, v183
	v_cmp_gt_f32_e32 vcc, s30, v0
	v_mul_f32_e32 v1, 0x4f800000, v0
	s_nop 0
	v_cndmask_b32_e32 v0, v0, v1, vcc
	v_sqrt_f32_e32 v1, v0
	s_nop 0
	v_add_u32_e32 v4, -1, v1
	v_fma_f32 v5, -v4, v1, v0
	v_cmp_ge_f32_e64 s[4:5], 0, v5
	v_add_u32_e32 v5, 1, v1
	s_nop 0
	v_cndmask_b32_e64 v4, v1, v4, s[4:5]
	v_fma_f32 v1, -v5, v1, v0
	v_cmp_lt_f32_e64 s[4:5], 0, v1
	s_nop 1
	v_cndmask_b32_e64 v1, v4, v5, s[4:5]
	v_mul_f32_e32 v4, 0x37800000, v1
	v_cndmask_b32_e32 v1, v1, v4, vcc
	v_cmp_class_f32_e32 vcc, v0, v222
	s_nop 1
	v_cndmask_b32_e32 v0, v1, v0, vcc
	s_mov_b64 s[2:3], s[0:1]
	s_load_dwordx2 s[2:3], s[2:3], 0xe8
	v_rcp_f32_e32 v4, v0
	s_nop 0
	v_fma_f32 v1, -v0, v4, 1.0
	v_fma_f32 v1, v1, v4, v4
	v_lshlrev_b64 v[4:5], 11, v[104:105]
	v_div_fixup_f32 v14, v1, v0, 1.0
	s_waitcnt lgkmcnt(0)
	v_lshl_add_u64 v[0:1], s[2:3], 0, v[4:5]
	v_lshl_add_u64 v[0:1], v[0:1], 0, s[12:13]
	v_lshl_add_u64 v[16:17], v[0:1], 0, v[176:177]
	v_lshl_add_u64 v[0:1], v[16:17], 0, s[42:43]
	v_add_co_u32_e32 v16, vcc, s68, v16
	s_mov_b64 s[2:3], s[0:1]
	s_nop 0
	v_addc_co_u32_e32 v17, vcc, 0, v17, vcc
	global_load_ushort v16, v[16:17], off
	global_load_ushort v184, v[0:1], off offset:32
	global_load_ushort v185, v[0:1], off offset:64
	global_load_ushort v186, v[0:1], off offset:96
	global_load_ushort v187, v[0:1], off offset:128
	global_load_ushort v188, v[0:1], off offset:160
	global_load_ushort v189, v[0:1], off offset:192
	global_load_ushort v190, v[0:1], off offset:224
	s_load_dwordx2 s[2:3], s[2:3], 0xe8
	v_mul_f32_e32 v18, v14, v24
	v_mul_f32_e32 v18, v18, v43
	v_mul_f32_e32 v13, v14, v13
	v_mul_f32_e32 v13, v13, v36
	s_waitcnt lgkmcnt(0)
	v_lshl_add_u64 v[4:5], s[2:3], 0, v[4:5]
	v_lshl_add_u64 v[4:5], v[4:5], 0, s[12:13]
	v_lshl_add_u64 v[20:21], v[4:5], 0, v[176:177]
	v_lshl_add_u64 v[4:5], v[20:21], 0, s[50:51]
	v_mul_f32_e32 v12, v14, v12
	v_mul_f32_e32 v12, v12, v37
	v_mul_f32_e32 v10, v14, v10
	v_mul_f32_e32 v10, v10, v38
	v_mul_f32_e32 v9, v14, v9
	v_mul_f32_e32 v9, v9, v39
	v_mul_f32_e32 v8, v14, v8
	v_mul_f32_e32 v8, v8, v41
	v_mul_f32_e32 v6, v14, v6
	v_mul_f32_e32 v6, v6, v40
	v_mul_f32_e32 v2, v14, v2
	v_mul_f32_e32 v2, v2, v42
	s_mov_b32 s2, -1
	v_or_b32_e32 v104, s7, v84
	s_waitcnt vmcnt(0)
	v_lshlrev_b32_e32 v16, 16, v16
	v_mul_f32_e32 v16, v18, v16
	v_bfe_u32 v17, v16, 16, 1
	v_add3_u32 v18, v16, v17, s82
	v_add_co_u32_e32 v16, vcc, s69, v20
	s_nop 1
	v_addc_co_u32_e32 v17, vcc, 0, v21, vcc
	global_store_short_d16_hi v[16:17], v18, off
	v_lshlrev_b32_e32 v16, 16, v184
	v_mul_f32_e32 v13, v13, v16
	v_bfe_u32 v16, v13, 16, 1
	v_add3_u32 v13, v13, v16, s82
	global_store_short_d16_hi v[4:5], v13, off offset:32
	v_lshlrev_b32_e32 v13, 16, v185
	v_mul_f32_e32 v12, v12, v13
	v_bfe_u32 v13, v12, 16, 1
	v_add3_u32 v12, v12, v13, s82
	global_store_short_d16_hi v[4:5], v12, off offset:64
	v_lshlrev_b32_e32 v12, 16, v186
	v_mul_f32_e32 v10, v10, v12
	v_bfe_u32 v12, v10, 16, 1
	v_add3_u32 v10, v10, v12, s82
	global_store_short_d16_hi v[4:5], v10, off offset:96
	v_lshlrev_b32_e32 v10, 16, v187
	v_mul_f32_e32 v9, v9, v10
	v_bfe_u32 v10, v9, 16, 1
	v_add3_u32 v9, v9, v10, s82
	global_store_short_d16_hi v[4:5], v9, off offset:128
	v_lshlrev_b32_e32 v9, 16, v188
	v_mul_f32_e32 v8, v8, v9
	v_bfe_u32 v9, v8, 16, 1
	v_add3_u32 v8, v8, v9, s82
	global_store_short_d16_hi v[4:5], v8, off offset:160
	v_lshlrev_b32_e32 v8, 16, v189
	v_mul_f32_e32 v6, v6, v8
	v_bfe_u32 v8, v6, 16, 1
	v_add3_u32 v6, v6, v8, s82
	global_store_short_d16_hi v[4:5], v6, off offset:192
	v_lshlrev_b32_e32 v0, 16, v190
	v_mul_f32_e32 v0, v2, v0
	v_bfe_u32 v1, v0, 16, 1
	v_add3_u32 v0, v0, v1, s82
	global_store_short_d16_hi v[4:5], v0, off offset:224
	v_add_f32_e32 v0, 0, v31
	v_add_f32_e32 v0, v0, v3
	v_add_f32_e32 v0, v0, v7
	v_add_f32_e32 v0, v0, v11
	v_add_f32_e32 v0, v0, v15
	v_add_f32_e32 v0, v0, v19
	v_mbcnt_lo_u32_b32 v1, s2, 0
	v_mbcnt_hi_u32_b32 v1, s2, v1
	v_add_f32_e32 v0, v0, v23
	v_lshlrev_b32_e32 v1, 2, v1
	v_add_f32_e32 v0, v0, v27
	v_xor_b32_e32 v2, 4, v1
	s_nop 1
	v_mov_b32_dpp v2, v0 quad_perm:[1,0,3,2] row_mask:0xf bank_mask:0xf
	s_mov_b32 s2, -1
	s_waitcnt lgkmcnt(0)
	v_add_f32_e32 v0, v0, v2
	v_xor_b32_e32 v2, 8, v1
	s_nop 1
	v_mov_b32_dpp v2, v0 quad_perm:[2,3,0,1] row_mask:0xf bank_mask:0xf
	s_waitcnt lgkmcnt(0)
	v_add_f32_e32 v0, v0, v2
	v_xor_b32_e32 v2, 16, v1
	s_nop 1
	v_mov_b32_dpp v2, v0 row_half_mirror row_mask:0xf bank_mask:0xf
	s_nop 1
	v_mov_b32_dpp v2, v2 quad_perm:[3,2,1,0] row_mask:0xf bank_mask:0xf
	v_xor_b32_e32 v1, 32, v1
	s_waitcnt lgkmcnt(0)
; DEVFI float bf2f(bfraw h) { return __uint_as_float(((unsigned)h) << 16); }
; DEVFI bfraw f2bf(float x) { unsigned u = __float_as_uint(x); u += 0x7fffu + ((u >> 16) & 1u); return (bfraw)(u >> 16); }
; #define RG ((bfraw*)(kargs()->ws + O_RG))
; #define RO ((bfraw*)(kargs()->ws + O_RO))
; __global__ void __launch_bounds__(512) mega(Params p) {
;     ...
;           for (int j = 0; j < 4; ++j) { float s1 = 0;
; #pragma unroll
;             for (int ne = 0; ne < 8; ++ne) s1 += o[ne][j];
;             const float mean = red16(s1) * (1.f / 128.f); float s2 = 0;
; #pragma unroll
;             for (int ne = 0; ne < 8; ++ne) { const float dd = o[ne][j] - mean; s2 += dd * dd; }
;             const float rstd = 1.f / sqrtf(red16(s2) * (1.f / 128.f) + LN_EPS);
;             const long tok = tok0 + w * 16 + fq * 4 + j;
;             const bfraw* gp = RG + tok * 1024 + head * 128 + fr; bfraw* op = RO + tok * 1024 + head * 128 + fr;
; #pragma unroll
;             for (int ne = 0; ne < 8; ++ne) op[ne * 16] = f2bf((o[ne][j] - mean) * rstd * gw[ne] * bf2f(gp[ne * 16])); }
	v_add_f32_e32 v0, v0, v2
	s_nop 1
	v_mov_b32_dpp v1, v0 row_ror:8 row_mask:0xf bank_mask:0xf
	s_waitcnt lgkmcnt(0)
	v_add_f32_e32 v0, v0, v1
	v_fmac_f32_e32 v3, 0xbc000000, v0
	v_fmac_f32_e32 v31, 0xbc000000, v0
	v_mul_f32_e32 v1, v3, v3
	v_fmac_f32_e32 v1, v31, v31
	v_fmac_f32_e32 v7, 0xbc000000, v0
	v_fmac_f32_e32 v1, v7, v7
	v_fmac_f32_e32 v11, 0xbc000000, v0
	v_fmac_f32_e32 v1, v11, v11
	v_fmac_f32_e32 v15, 0xbc000000, v0
	v_fmac_f32_e32 v1, v15, v15
	v_fmac_f32_e32 v19, 0xbc000000, v0
	v_fmac_f32_e32 v23, 0xbc000000, v0
	v_fmac_f32_e32 v27, 0xbc000000, v0
	v_mbcnt_lo_u32_b32 v0, s2, 0
	v_fmac_f32_e32 v1, v19, v19
	v_mbcnt_hi_u32_b32 v0, s2, v0
	v_fmac_f32_e32 v1, v23, v23
	v_lshlrev_b32_e32 v0, 2, v0
	v_fmac_f32_e32 v1, v27, v27
	v_xor_b32_e32 v2, 4, v0
	s_nop 1
	v_mov_b32_dpp v2, v1 quad_perm:[1,0,3,2] row_mask:0xf bank_mask:0xf
	s_waitcnt lgkmcnt(0)
	v_add_f32_e32 v1, v1, v2
	v_xor_b32_e32 v2, 8, v0
	s_nop 1
	v_mov_b32_dpp v2, v1 quad_perm:[2,3,0,1] row_mask:0xf bank_mask:0xf
	s_waitcnt lgkmcnt(0)
	v_add_f32_e32 v1, v1, v2
	v_xor_b32_e32 v2, 16, v0
	s_nop 1
	v_mov_b32_dpp v2, v1 row_half_mirror row_mask:0xf bank_mask:0xf
	s_nop 1
	v_mov_b32_dpp v2, v2 quad_perm:[3,2,1,0] row_mask:0xf bank_mask:0xf
	v_xor_b32_e32 v0, 32, v0
	s_waitcnt lgkmcnt(0)
	v_add_f32_e32 v1, v1, v2
	s_nop 1
	v_mov_b32_dpp v0, v1 row_ror:8 row_mask:0xf bank_mask:0xf
	s_waitcnt lgkmcnt(0)
	v_add_f32_e32 v0, v1, v0
	v_fmamk_f32 v0, v0, 0x3c000000, v183
	v_cmp_gt_f32_e32 vcc, s30, v0
	v_mul_f32_e32 v1, 0x4f800000, v0
	s_nop 0
	v_cndmask_b32_e32 v0, v0, v1, vcc
	v_sqrt_f32_e32 v1, v0
	s_nop 0
	v_add_u32_e32 v2, -1, v1
	v_fma_f32 v4, -v2, v1, v0
	v_cmp_ge_f32_e64 s[4:5], 0, v4
	v_add_u32_e32 v4, 1, v1
	s_nop 0
	v_cndmask_b32_e64 v2, v1, v2, s[4:5]
	v_fma_f32 v1, -v4, v1, v0
	v_cmp_lt_f32_e64 s[4:5], 0, v1
	s_nop 1
	v_cndmask_b32_e64 v1, v2, v4, s[4:5]
	v_mul_f32_e32 v2, 0x37800000, v1
	v_cndmask_b32_e32 v1, v1, v2, vcc
	v_cmp_class_f32_e32 vcc, v0, v222
	s_nop 1
	v_cndmask_b32_e32 v0, v1, v0, vcc
	s_mov_b64 s[2:3], s[0:1]
	s_load_dwordx2 s[2:3], s[2:3], 0xe8
	v_rcp_f32_e32 v2, v0
	s_nop 0
	v_fma_f32 v1, -v0, v2, 1.0
	v_fma_f32 v1, v1, v2, v2
	v_lshlrev_b64 v[4:5], 11, v[104:105]
	v_div_fixup_f32 v2, v1, v0, 1.0
	s_waitcnt lgkmcnt(0)
	v_lshl_add_u64 v[0:1], s[2:3], 0, v[4:5]
	v_lshl_add_u64 v[0:1], v[0:1], 0, s[12:13]
	v_lshl_add_u64 v[8:9], v[0:1], 0, v[176:177]
	v_lshl_add_u64 v[0:1], v[8:9], 0, s[42:43]
	v_add_co_u32_e32 v8, vcc, s68, v8
	s_mov_b64 s[2:3], s[0:1]
	s_nop 0
	v_addc_co_u32_e32 v9, vcc, 0, v9, vcc
	global_load_ushort v8, v[8:9], off
	global_load_ushort v184, v[0:1], off offset:32
	global_load_ushort v185, v[0:1], off offset:64
	global_load_ushort v186, v[0:1], off offset:96
	global_load_ushort v187, v[0:1], off offset:128
	global_load_ushort v188, v[0:1], off offset:160
	global_load_ushort v189, v[0:1], off offset:192
	global_load_ushort v190, v[0:1], off offset:224
	s_load_dwordx2 s[2:3], s[2:3], 0xe8
	v_mul_f32_e32 v6, v2, v31
	v_mul_f32_e32 v6, v6, v43
	v_mul_f32_e32 v3, v2, v3
	v_mul_f32_e32 v3, v3, v36
	s_waitcnt lgkmcnt(0)
	v_lshl_add_u64 v[4:5], s[2:3], 0, v[4:5]
	v_lshl_add_u64 v[4:5], v[4:5], 0, s[12:13]
	v_lshl_add_u64 v[12:13], v[4:5], 0, v[176:177]
	v_lshl_add_u64 v[4:5], v[12:13], 0, s[50:51]
	s_waitcnt vmcnt(0)
	v_lshlrev_b32_e32 v8, 16, v8
	v_mul_f32_e32 v6, v6, v8
	v_bfe_u32 v8, v6, 16, 1
	v_add3_u32 v6, v6, v8, s82
	v_add_co_u32_e32 v8, vcc, s69, v12
	s_nop 1
	v_addc_co_u32_e32 v9, vcc, 0, v13, vcc
	global_store_short_d16_hi v[8:9], v6, off
	v_lshlrev_b32_e32 v6, 16, v184
	v_mul_f32_e32 v3, v3, v6
	v_bfe_u32 v6, v3, 16, 1
	v_add3_u32 v3, v3, v6, s82
	global_store_short_d16_hi v[4:5], v3, off offset:32
	v_mul_f32_e32 v3, v2, v7
	v_mul_f32_e32 v3, v3, v37
	v_lshlrev_b32_e32 v6, 16, v185
	v_mul_f32_e32 v3, v3, v6
	v_bfe_u32 v6, v3, 16, 1
	v_add3_u32 v3, v3, v6, s82
	global_store_short_d16_hi v[4:5], v3, off offset:64
	v_mul_f32_e32 v3, v2, v11
	v_mul_f32_e32 v3, v3, v38
	v_lshlrev_b32_e32 v6, 16, v186
	v_mul_f32_e32 v3, v3, v6
	v_bfe_u32 v6, v3, 16, 1
	v_add3_u32 v3, v3, v6, s82
	global_store_short_d16_hi v[4:5], v3, off offset:96
	v_mul_f32_e32 v3, v2, v15
	v_mul_f32_e32 v3, v3, v39
	v_lshlrev_b32_e32 v6, 16, v187
	v_mul_f32_e32 v3, v3, v6
	v_bfe_u32 v6, v3, 16, 1
	v_add3_u32 v3, v3, v6, s82
	global_store_short_d16_hi v[4:5], v3, off offset:128
	v_mul_f32_e32 v3, v2, v19
	v_mul_f32_e32 v3, v3, v41
	v_lshlrev_b32_e32 v6, 16, v188
	v_mul_f32_e32 v3, v3, v6
	v_bfe_u32 v6, v3, 16, 1
	v_add3_u32 v3, v3, v6, s82
	global_store_short_d16_hi v[4:5], v3, off offset:160
	v_mul_f32_e32 v3, v2, v23
	v_mul_f32_e32 v3, v3, v40
	v_mul_f32_e32 v2, v2, v27
	v_mul_f32_e32 v2, v2, v42
	v_lshlrev_b32_e32 v6, 16, v189
	v_mul_f32_e32 v3, v3, v6
	v_bfe_u32 v6, v3, 16, 1
	v_add3_u32 v3, v3, v6, s82
	global_store_short_d16_hi v[4:5], v3, off offset:192
	v_lshlrev_b32_e32 v0, 16, v190
	v_mul_f32_e32 v0, v2, v0
	v_bfe_u32 v1, v0, 16, 1
	v_add3_u32 v0, v0, v1, s82
	global_store_short_d16_hi v[4:5], v0, off offset:224
	s_cbranch_scc0 .LBB0_2481

; DEVFI void ln_resid4(const float* ysrc, float* ydst, bfraw* fb, float* stats, const float* pw, const float* pb,
;                      const float* w, const float* b, int lane, bool fin) {
;   f32x4 v[4][4];
; #pragma unroll
;   for (int r = 0; r < 4; ++r)
; #pragma unroll
;     for (int i = 0; i < 4; ++i) v[r][i] = __builtin_nontemporal_load((const f32x4*)(ysrc + r * 1024) + i * 64 + lane);
;   u32x2 fv[4][4];
; #pragma unroll
;   for (int r = 0; r < 4; ++r)
; #pragma unroll
;     for (int i = 0; i < 4; ++i) fv[r][i] = __builtin_nontemporal_load((const u32x2*)(fb + r * 1024) + i * 64 + lane);
;   f32x4 pwv[4], pbv[4], ww[4], bb[4];
; #pragma unroll
;   for (int i = 0; i < 4; ++i) { pwv[i] = ((const f32x4*)pw)[i * 64 + lane]; pbv[i] = ((const f32x4*)pb)[i * 64 + lane];
;     ww[i] = ((const f32x4*)w)[i * 64 + lane]; bb[i] = ((const f32x4*)b)[i * 64 + lane]; }
; #pragma unroll
;   for (int r = 0; r < 4; ++r) {
;     const float pmu = stats[r * 2], prs = stats[r * 2 + 1];
;     f32x4 y[4];
; #pragma unroll
;     for (int i = 0; i < 4; ++i) { const unsigned f0 = fv[r][i][0], f1 = fv[r][i][1];
;       const f32x4 f4 = {__uint_as_float(f0 << 16), __uint_as_float(f0 & 0xffff0000u), __uint_as_float(f1 << 16), __uint_as_float(f1 & 0xffff0000u)};
;       y[i] = ALPHA * ((v[r][i] - pmu) * prs * pwv[i] + pbv[i]) + f4; }
.LBB0_3162:
	v_lshlrev_b32_e32 v176, 4, v130
	v_lshl_add_u64 v[64:65], v[0:1], 0, v[176:177]
	v_lshlrev_b64 v[2:3], 11, v[168:169]
	v_lshl_add_u64 v[156:157], v[168:169], 3, s[18:19]
	global_load_dwordx4 v[112:115], v[64:65], off nt
	global_load_dwordx2 v[178:179], v[156:157], off
	v_lshl_add_u64 v[154:155], s[16:17], 0, v[2:3]
	v_lshlrev_b32_e32 v158, 3, v130
	v_mov_b32_e32 v159, v177
	v_lshl_add_u64 v[172:173], v[154:155], 0, v[158:159]
	global_load_dwordx2 v[180:181], v[172:173], off nt
	global_load_dwordx4 v[40:43], v[132:133], off
	global_load_dwordx4 v[44:47], v[134:135], off
	global_load_dwordx2 v[196:197], v[172:173], off offset:512 nt
	global_load_dwordx4 v[116:119], v[64:65], off offset:1024 nt
	global_load_dwordx4 v[48:51], v[132:133], off offset:1024
	global_load_dwordx4 v[52:55], v[134:135], off offset:1024
	global_load_dwordx4 v[24:27], v[136:137], off
	global_load_dwordx4 v[16:19], v[136:137], off offset:1024
	global_load_dwordx4 v[28:31], v[138:139], off
	global_load_dwordx4 v[20:23], v[138:139], off offset:1024
	global_load_dwordx4 v[56:59], v[132:133], off offset:2048
	global_load_dwordx4 v[32:35], v[132:133], off offset:3072
	global_load_dwordx2 v[198:199], v[172:173], off offset:1024 nt
	global_load_dwordx4 v[60:63], v[134:135], off offset:2048
	global_load_dwordx4 v[36:39], v[134:135], off offset:3072
	global_load_dwordx4 v[8:11], v[136:137], off offset:2048
	global_load_dwordx4 v[0:3], v[136:137], off offset:3072
	global_load_dwordx4 v[120:123], v[64:65], off offset:2048 nt
	global_load_dwordx4 v[12:15], v[138:139], off offset:2048
	global_load_dwordx4 v[4:7], v[138:139], off offset:3072
	global_load_dwordx4 v[124:127], v[64:65], off offset:3072 nt
	global_load_dwordx2 v[200:201], v[172:173], off offset:1536 nt
	v_add_co_u32_e32 v66, vcc, 0x1000, v64
	s_movk_i32 s2, 0x3000
	s_nop 0
	v_addc_co_u32_e32 v67, vcc, 0, v65, vcc
	v_add_co_u32_e32 v68, vcc, s53, v64
	v_add_co_u32_e64 v70, s[6:7], s56, v172
	s_nop 0
	v_addc_co_u32_e32 v69, vcc, 0, v65, vcc
	v_add_co_u32_e32 v64, vcc, s2, v64
	v_addc_co_u32_e64 v71, s[6:7], 0, v173, s[6:7]
	s_nop 0
	v_addc_co_u32_e32 v65, vcc, 0, v65, vcc
	s_mov_b32 s2, -1
	global_load_dwordx2 v[194:195], v[172:173], off offset:2048 nt
	global_load_dwordx2 v[192:193], v[172:173], off offset:2560 nt
	global_load_dwordx2 v[190:191], v[172:173], off offset:3072 nt
	global_load_dwordx2 v[188:189], v[172:173], off offset:3584 nt
	global_load_dwordx4 v[108:111], v[66:67], off nt
	global_load_dwordx4 v[104:107], v[66:67], off offset:1024 nt
	global_load_dwordx4 v[100:103], v[66:67], off offset:2048 nt
	global_load_dwordx4 v[96:99], v[66:67], off offset:3072 nt
	global_load_dwordx2 v[186:187], v[70:71], off nt
	global_load_dwordx2 v[184:185], v[70:71], off offset:512 nt
	global_load_dwordx2 v[174:175], v[70:71], off offset:1024 nt
	global_load_dwordx2 v[170:171], v[70:71], off offset:1536 nt
	global_load_dwordx2 v[166:167], v[70:71], off offset:2048 nt
	global_load_dwordx2 v[164:165], v[70:71], off offset:2560 nt
	global_load_dwordx2 v[162:163], v[70:71], off offset:3072 nt
	global_load_dwordx2 v[160:161], v[70:71], off offset:3584 nt
	global_load_dwordx4 v[88:91], v[68:69], off offset:1024 nt
	global_load_dwordx4 v[84:87], v[68:69], off offset:2048 nt
	global_load_dwordx4 v[80:83], v[68:69], off offset:3072 nt
	global_load_dwordx4 v[92:95], v[64:65], off offset:-4096 nt
	global_load_dwordx4 v[76:79], v[64:65], off nt
	global_load_dwordx4 v[72:75], v[64:65], off offset:1024 nt
	s_nop 0
	global_load_dwordx4 v[68:71], v[64:65], off offset:2048 nt
	s_nop 0
	global_load_dwordx4 v[64:67], v[64:65], off offset:3072 nt
	s_waitcnt vmcnt(46)
	v_lshlrev_b32_e32 v202, 16, v180
	v_and_b32_e32 v203, 0xffff0000, v180
	v_lshlrev_b32_e32 v180, 16, v181
	v_and_b32_e32 v181, 0xffff0000, v181
	v_mbcnt_lo_u32_b32 v141, s2, 0
	v_mbcnt_hi_u32_b32 v141, s2, v141
	v_lshlrev_b32_e32 v141, 2, v141
	v_xor_b32_e32 v143, 0x80, v141
	s_mov_b32 s2, -1
	v_sub_f32_e32 v115, v115, v178
	v_sub_f32_e32 v114, v114, v178
	v_pk_mul_f32 v[114:115], v[178:179], v[114:115] op_sel:[1,0]
	s_waitcnt vmcnt(42)
	v_sub_f32_e32 v117, v117, v178
	v_sub_f32_e32 v116, v116, v178
	v_sub_f32_e32 v113, v113, v178
	v_sub_f32_e32 v112, v112, v178
	v_pk_fma_f32 v[114:115], v[42:43], v[114:115], v[46:47]
	v_pk_mul_f32 v[116:117], v[178:179], v[116:117] op_sel:[1,0]
	s_waitcnt vmcnt(28)
	v_sub_f32_e32 v121, v121, v178
	v_sub_f32_e32 v120, v120, v178
	v_pk_mul_f32 v[112:113], v[178:179], v[112:113] op_sel:[1,0]
	v_pk_fma_f32 v[114:115], v[114:115], s[52:53], v[180:181] op_sel_hi:[1,0,1]
	v_lshlrev_b32_e32 v180, 16, v196
	v_and_b32_e32 v181, 0xffff0000, v196
	v_sub_f32_e32 v119, v119, v178
	v_sub_f32_e32 v118, v118, v178
	v_pk_fma_f32 v[116:117], v[48:49], v[116:117], v[52:53]
	v_pk_mul_f32 v[120:121], v[178:179], v[120:121] op_sel:[1,0]
	s_waitcnt vmcnt(25)
	v_sub_f32_e32 v125, v125, v178
	v_sub_f32_e32 v124, v124, v178
	v_pk_fma_f32 v[112:113], v[40:41], v[112:113], v[44:45]
	v_pk_mul_f32 v[118:119], v[178:179], v[118:119] op_sel:[1,0]
	v_pk_fma_f32 v[116:117], v[116:117], s[52:53], v[180:181] op_sel_hi:[1,0,1]
	v_lshlrev_b32_e32 v180, 16, v198
	v_and_b32_e32 v181, 0xffff0000, v198
	v_pk_fma_f32 v[120:121], v[56:57], v[120:121], v[60:61]
	v_pk_mul_f32 v[124:125], v[178:179], v[124:125] op_sel:[1,0]
	v_pk_fma_f32 v[112:113], v[112:113], s[52:53], v[202:203] op_sel_hi:[1,0,1]
	v_lshlrev_b32_e32 v196, 16, v197
	v_and_b32_e32 v197, 0xffff0000, v197
	v_pk_fma_f32 v[118:119], v[50:51], v[118:119], v[54:55]
	v_sub_f32_e32 v123, v123, v178
	v_sub_f32_e32 v122, v122, v178
	v_pk_fma_f32 v[120:121], v[120:121], s[52:53], v[180:181] op_sel_hi:[1,0,1]
	s_waitcnt vmcnt(24)
; DEVFI int lane_opaque() { unsigned m = ~0u; asm volatile("" : "+s"(m)); return (int)__builtin_amdgcn_mbcnt_hi(m, __builtin_amdgcn_mbcnt_lo(m, 0u)); }
; DEVFI float shx(float v, int mask, int lane) { return __int_as_float(__builtin_amdgcn_ds_bpermute((lane ^ mask) << 2, __float_as_int(v))); }
; DEVFI float red64(float v) {
;   const int ln = lane_opaque();
;   v += shx(v, 32, ln); v += shx(v, 16, ln); v += shx(v, 8, ln); v += shx(v, 4, ln); v += shx(v, 2, ln); v += shx(v, 1, ln); return v;
; }
; DEVFI void ln_resid4(const float* ysrc, float* ydst, bfraw* fb, float* stats, const float* pw, const float* pb,
;                      const float* w, const float* b, int lane, bool fin) {
;     ...
;     for (int i = 0; i < 4; ++i) { const unsigned f0 = fv[r][i][0], f1 = fv[r][i][1];
;       const f32x4 f4 = {__uint_as_float(f0 << 16), __uint_as_float(f0 & 0xffff0000u), __uint_as_float(f1 << 16), __uint_as_float(f1 & 0xffff0000u)};
;       y[i] = ALPHA * ((v[r][i] - pmu) * prs * pwv[i] + pbv[i]) + f4; }
;     float s = 0;
; #pragma unroll
;     for (int i = 0; i < 4; ++i) s += y[i][0] + y[i][1] + y[i][2] + y[i][3];
;     const float mean = red64(s) * (1.f / 1024.f);
;     float q = 0;
; #pragma unroll
;     for (int i = 0; i < 4; ++i) { const f32x4 d = y[i] - mean; q += d[0] * d[0] + d[1] * d[1] + d[2] * d[2] + d[3] * d[3]; }
;     const float rstd = 1.f / sqrtf(red64(q) * (1.f / 1024.f) + LN_EPS);
;     if (lane == 0) { stats[r * 2] = mean; stats[r * 2 + 1] = rstd; }
	v_lshlrev_b32_e32 v180, 16, v200
	v_and_b32_e32 v181, 0xffff0000, v200
	v_sub_f32_e32 v127, v127, v178
	v_sub_f32_e32 v126, v126, v178
	v_pk_fma_f32 v[124:125], v[32:33], v[124:125], v[36:37]
	v_pk_fma_f32 v[118:119], v[118:119], s[52:53], v[196:197] op_sel_hi:[1,0,1]
	v_pk_mul_f32 v[122:123], v[178:179], v[122:123] op_sel:[1,0]
	v_pk_mul_f32 v[126:127], v[178:179], v[126:127] op_sel:[1,0]
	v_pk_fma_f32 v[124:125], v[124:125], s[52:53], v[180:181] op_sel_hi:[1,0,1]
	v_mov_b32_e32 v178, v116
	v_mov_b32_e32 v179, v112
	v_mov_b32_e32 v180, v117
	v_mov_b32_e32 v181, v113
	v_pk_add_f32 v[178:179], v[178:179], v[180:181]
	v_mov_b32_e32 v180, v118
	v_mov_b32_e32 v181, v114
	v_pk_add_f32 v[178:179], v[180:181], v[178:179]
	v_mov_b32_e32 v180, v119
	v_mov_b32_e32 v181, v115
	v_lshlrev_b32_e32 v196, 16, v199
	v_and_b32_e32 v197, 0xffff0000, v199
	v_pk_fma_f32 v[122:123], v[58:59], v[122:123], v[62:63]
	v_pk_add_f32 v[178:179], v[180:181], v[178:179]
	v_pk_fma_f32 v[122:123], v[122:123], s[52:53], v[196:197] op_sel_hi:[1,0,1]
	v_lshlrev_b32_e32 v196, 16, v201
	v_and_b32_e32 v197, 0xffff0000, v201
	v_pk_fma_f32 v[126:127], v[34:35], v[126:127], v[38:39]
	v_add_f32_e32 v131, 0, v179
	v_pk_fma_f32 v[126:127], v[126:127], s[52:53], v[196:197] op_sel_hi:[1,0,1]
	v_add_f32_e32 v131, v178, v131
	v_mov_b32_e32 v178, v124
	v_mov_b32_e32 v179, v120
	v_mov_b32_e32 v180, v125
	v_mov_b32_e32 v181, v121
	v_pk_add_f32 v[178:179], v[178:179], v[180:181]
	v_mov_b32_e32 v180, v126
	v_mov_b32_e32 v181, v122
	v_pk_add_f32 v[178:179], v[180:181], v[178:179]
	v_mov_b32_e32 v180, v127
	v_mov_b32_e32 v181, v123
	v_pk_add_f32 v[178:179], v[180:181], v[178:179]
	s_nop 0
	v_add_f32_e32 v131, v179, v131
	v_add_f32_e32 v131, v178, v131
	ds_bpermute_b32 v143, v143, v131
	s_waitcnt lgkmcnt(0)
	v_add_f32_e32 v131, v131, v143
	v_xor_b32_e32 v143, 64, v141
	ds_bpermute_b32 v143, v143, v131
	s_waitcnt lgkmcnt(0)
	v_add_f32_e32 v131, v131, v143
	v_xor_b32_e32 v143, 32, v141
	ds_bpermute_b32 v143, v143, v131
	s_waitcnt lgkmcnt(0)
	v_add_f32_e32 v131, v131, v143
	v_xor_b32_e32 v143, 16, v141
	ds_bpermute_b32 v143, v143, v131
	s_waitcnt lgkmcnt(0)
	v_add_f32_e32 v131, v131, v143
	v_xor_b32_e32 v143, 8, v141
	ds_bpermute_b32 v143, v143, v131
	v_xor_b32_e32 v141, 4, v141
	s_waitcnt lgkmcnt(0)
	v_add_f32_e32 v131, v131, v143
	ds_bpermute_b32 v141, v141, v131
	s_waitcnt lgkmcnt(0)
	v_add_f32_e32 v131, v131, v141
	v_fmamk_f32 v211, v131, 0xba800000, v113
	v_fmamk_f32 v207, v131, 0xba800000, v117
	v_fmamk_f32 v210, v131, 0xba800000, v112
	v_mul_f32_e32 v141, v211, v211
	v_fmamk_f32 v206, v131, 0xba800000, v116
	v_mul_f32_e32 v143, v207, v207
	v_fmamk_f32 v208, v131, 0xba800000, v114
	v_fmac_f32_e32 v141, v210, v210
	v_fmamk_f32 v204, v131, 0xba800000, v118
	v_fmac_f32_e32 v143, v206, v206
	v_fmamk_f32 v209, v131, 0xba800000, v115
	v_fmac_f32_e32 v141, v208, v208
	v_fmamk_f32 v205, v131, 0xba800000, v119
	v_fmac_f32_e32 v143, v204, v204
	v_fmac_f32_e32 v141, v209, v209
	v_fmac_f32_e32 v143, v205, v205
	v_fmamk_f32 v203, v131, 0xba800000, v121
	v_add_f32_e32 v141, v141, v143
	v_fmamk_f32 v202, v131, 0xba800000, v120
	v_mul_f32_e32 v143, v203, v203
	v_fmamk_f32 v200, v131, 0xba800000, v122
	v_fmac_f32_e32 v143, v202, v202
	v_fmamk_f32 v201, v131, 0xba800000, v123
	v_fmac_f32_e32 v143, v200, v200
	v_fmac_f32_e32 v143, v201, v201
	v_fmamk_f32 v199, v131, 0xba800000, v125
	v_add_f32_e32 v141, v143, v141
	v_fmamk_f32 v198, v131, 0xba800000, v124
	v_mul_f32_e32 v143, v199, v199
	v_fmamk_f32 v196, v131, 0xba800000, v126
	v_fmac_f32_e32 v143, v198, v198
	v_fmamk_f32 v197, v131, 0xba800000, v127
	v_fmac_f32_e32 v143, v196, v196
	v_fmac_f32_e32 v143, v197, v197
	v_add_f32_e32 v141, v143, v141
	v_mbcnt_lo_u32_b32 v143, s2, 0
	v_mbcnt_hi_u32_b32 v143, s2, v143
	v_lshlrev_b32_e32 v143, 2, v143
	v_xor_b32_e32 v145, 0x80, v143
	ds_bpermute_b32 v145, v145, v141
	s_waitcnt lgkmcnt(0)
	v_add_f32_e32 v141, v141, v145
	v_xor_b32_e32 v145, 64, v143
	ds_bpermute_b32 v145, v145, v141
	s_waitcnt lgkmcnt(0)
	v_add_f32_e32 v141, v141, v145
	v_xor_b32_e32 v145, 32, v143
	s_nop 1
	v_mov_b32_dpp v145, v141 row_ror:8 row_mask:0xf bank_mask:0xf
	s_waitcnt lgkmcnt(0)
	v_add_f32_e32 v141, v141, v145
	v_xor_b32_e32 v145, 16, v143
	s_nop 1
	v_mov_b32_dpp v145, v141 row_half_mirror row_mask:0xf bank_mask:0xf
	s_nop 1
	v_mov_b32_dpp v145, v145 quad_perm:[3,2,1,0] row_mask:0xf bank_mask:0xf
	s_waitcnt lgkmcnt(0)
	v_add_f32_e32 v141, v141, v145
	v_xor_b32_e32 v145, 8, v143
	s_nop 1
	v_mov_b32_dpp v145, v141 quad_perm:[2,3,0,1] row_mask:0xf bank_mask:0xf
	v_xor_b32_e32 v143, 4, v143
	s_waitcnt lgkmcnt(0)
	v_add_f32_e32 v141, v141, v145
	s_nop 1
	v_mov_b32_dpp v143, v141 quad_perm:[1,0,3,2] row_mask:0xf bank_mask:0xf
	s_waitcnt lgkmcnt(0)
	v_add_f32_e32 v141, v141, v143
	v_fmamk_f32 v141, v141, 0x3a800000, v183
	v_mul_f32_e32 v143, 0x4f800000, v141
	v_cmp_gt_f32_e32 vcc, s30, v141
	s_nop 1
	v_cndmask_b32_e32 v141, v141, v143, vcc
	v_sqrt_f32_e32 v143, v141
	s_nop 0
	v_add_u32_e32 v145, -1, v143
	v_fma_f32 v149, -v145, v143, v141
	v_cmp_ge_f32_e64 s[6:7], 0, v149
	v_add_u32_e32 v149, 1, v143
	s_nop 0
	v_cndmask_b32_e64 v145, v143, v145, s[6:7]
	v_fma_f32 v143, -v149, v143, v141
	v_cmp_lt_f32_e64 s[6:7], 0, v143
	s_nop 1
	v_cndmask_b32_e64 v143, v145, v149, s[6:7]
	v_mul_f32_e32 v145, 0x37800000, v143
	v_cndmask_b32_e32 v143, v143, v145, vcc
	v_cmp_class_f32_e32 vcc, v141, v222
	s_nop 1
	v_cndmask_b32_e32 v141, v143, v141, vcc
	s_nop 0
	v_rcp_f32_e32 v145, v141
	s_nop 0
	v_fma_f32 v143, -v141, v145, 1.0
	v_fma_f32 v143, v143, v145, v145
	v_div_fixup_f32 v212, v143, v141, 1.0
	s_and_saveexec_b64 s[2:3], s[4:5]
	s_cbranch_execz .LBB0_3164
	v_mul_f32_e32 v178, 0x3a800000, v131
	v_mov_b32_e32 v179, v212
	global_store_dwordx2 v[156:157], v[178:179], off
; DEVFI void ln_resid4(const float* ysrc, float* ydst, bfraw* fb, float* stats, const float* pw, const float* pb,
;                      const float* w, const float* b, int lane, bool fin) {
;     ...
;   for (int r = 0; r < 4; ++r) {
;     const float pmu = stats[r * 2], prs = stats[r * 2 + 1];
;     f32x4 y[4];
; #pragma unroll
;     for (int i = 0; i < 4; ++i) { const unsigned f0 = fv[r][i][0], f1 = fv[r][i][1];
;       const f32x4 f4 = {__uint_as_float(f0 << 16), __uint_as_float(f0 & 0xffff0000u), __uint_as_float(f1 << 16), __uint_as_float(f1 & 0xffff0000u)};
;       y[i] = ALPHA * ((v[r][i] - pmu) * prs * pwv[i] + pbv[i]) + f4; }
;     float s = 0;
; #pragma unroll
;     for (int i = 0; i < 4; ++i) s += y[i][0] + y[i][1] + y[i][2] + y[i][3];
;     const float mean = red64(s) * (1.f / 1024.f);
;     float q = 0;
; #pragma unroll
;     for (int i = 0; i < 4; ++i) { const f32x4 d = y[i] - mean; q += d[0] * d[0] + d[1] * d[1] + d[2] * d[2] + d[3] * d[3]; }
;     const float rstd = 1.f / sqrtf(red64(q) * (1.f / 1024.f) + LN_EPS);
;     if (lane == 0) { stats[r * 2] = mean; stats[r * 2 + 1] = rstd; }
; #pragma unroll
;     for (int i = 0; i < 4; ++i) { const int c4 = i * 64 + lane;
;       const f32x4 z = (y[i] - mean) * rstd * ww[i] + bb[i];
;       __builtin_nontemporal_store(fin ? z : y[i], (f32x4*)(ydst + r * 1024) + c4);
;       u32x2 pk = {cvtpk(z[0], z[1]), cvtpk(z[2], z[3])}; ((u32x2*)(fb + r * 1024))[c4] = pk; }
.LBB0_3164:
	s_or_b64 exec, exec, s[2:3]
	v_lshlrev_b64 v[168:169], 10, v[168:169]
	v_lshl_add_u64 v[168:169], v[168:169], 2, s[14:15]
	v_pk_mul_f32 v[178:179], v[208:209], v[212:213] op_sel_hi:[1,0]
	v_pk_mul_f32 v[180:181], v[210:211], v[212:213] op_sel_hi:[1,0]
	v_lshl_add_u64 v[208:209], v[168:169], 0, v[176:177]
	v_pk_fma_f32 v[178:179], v[26:27], v[178:179], v[30:31]
	v_pk_fma_f32 v[180:181], v[24:25], v[180:181], v[28:29]
	global_store_dwordx4 v[208:209], v[112:115], off nt
	s_mov_b32 s2, -1
	s_nop 0
	v_cvt_pk_bf16_f32 v112, v180, v181
	v_cvt_pk_bf16_f32 v113, v178, v179
	v_pk_mul_f32 v[114:115], v[206:207], v[212:213] op_sel_hi:[1,0]
	global_store_dwordx2 v[172:173], v[112:113], off
	v_pk_mul_f32 v[112:113], v[204:205], v[212:213] op_sel_hi:[1,0]
	v_pk_fma_f32 v[114:115], v[16:17], v[114:115], v[20:21]
	v_pk_fma_f32 v[112:113], v[18:19], v[112:113], v[22:23]
	global_store_dwordx4 v[208:209], v[116:119], off offset:1024 nt
	v_cvt_pk_bf16_f32 v114, v114, v115
	v_cvt_pk_bf16_f32 v115, v112, v113
	global_store_dwordx2 v[172:173], v[114:115], off offset:512
	v_pk_mul_f32 v[114:115], v[202:203], v[212:213] op_sel_hi:[1,0]
	v_pk_mul_f32 v[112:113], v[200:201], v[212:213] op_sel_hi:[1,0]
	v_pk_fma_f32 v[114:115], v[8:9], v[114:115], v[12:13]
	v_pk_fma_f32 v[112:113], v[10:11], v[112:113], v[14:15]
	global_store_dwordx4 v[208:209], v[120:123], off offset:2048 nt
	v_cvt_pk_bf16_f32 v114, v114, v115
	v_cvt_pk_bf16_f32 v115, v112, v113
	global_store_dwordx2 v[172:173], v[114:115], off offset:1024
	v_pk_mul_f32 v[114:115], v[198:199], v[212:213] op_sel_hi:[1,0]
	v_pk_mul_f32 v[112:113], v[196:197], v[212:213] op_sel_hi:[1,0]
	v_pk_fma_f32 v[114:115], v[0:1], v[114:115], v[4:5]
	v_pk_fma_f32 v[112:113], v[2:3], v[112:113], v[6:7]
	global_store_dwordx4 v[208:209], v[124:127], off offset:3072 nt
	v_cvt_pk_bf16_f32 v114, v114, v115
	v_cvt_pk_bf16_f32 v115, v112, v113
	global_store_dwordx2 v[172:173], v[114:115], off offset:1536
	global_load_dwordx2 v[112:113], v[156:157], off offset:8
	s_waitcnt vmcnt(32)
	v_lshlrev_b32_e32 v114, 16, v194
	v_and_b32_e32 v115, 0xffff0000, v194
	s_waitcnt vmcnt(31)
	v_lshlrev_b32_e32 v118, 16, v192
	v_and_b32_e32 v119, 0xffff0000, v192
	v_lshlrev_b32_e32 v116, 16, v195
	v_and_b32_e32 v117, 0xffff0000, v195
	v_lshlrev_b32_e32 v120, 16, v193
	v_and_b32_e32 v121, 0xffff0000, v193
	s_waitcnt vmcnt(30)
	v_lshlrev_b32_e32 v122, 16, v190
	v_and_b32_e32 v123, 0xffff0000, v190
	s_waitcnt vmcnt(29)
	v_lshlrev_b32_e32 v126, 16, v188
	v_and_b32_e32 v127, 0xffff0000, v188
	v_lshlrev_b32_e32 v124, 16, v191
	v_and_b32_e32 v125, 0xffff0000, v191
	v_lshlrev_b32_e32 v178, 16, v189
	v_and_b32_e32 v179, 0xffff0000, v189
	s_waitcnt vmcnt(0)
	v_sub_f32_e32 v109, v109, v112
	v_sub_f32_e32 v108, v108, v112
	v_sub_f32_e32 v105, v105, v112
	v_sub_f32_e32 v104, v104, v112
	v_sub_f32_e32 v111, v111, v112
	v_sub_f32_e32 v110, v110, v112
	v_sub_f32_e32 v107, v107, v112
	v_sub_f32_e32 v106, v106, v112
	v_pk_mul_f32 v[108:109], v[112:113], v[108:109] op_sel:[1,0]
	v_pk_mul_f32 v[104:105], v[112:113], v[104:105] op_sel:[1,0]
	v_pk_mul_f32 v[110:111], v[112:113], v[110:111] op_sel:[1,0]
	v_pk_mul_f32 v[106:107], v[112:113], v[106:107] op_sel:[1,0]
	v_pk_fma_f32 v[108:109], v[40:41], v[108:109], v[44:45]
	v_pk_fma_f32 v[104:105], v[48:49], v[104:105], v[52:53]
	v_sub_f32_e32 v101, v101, v112
	v_sub_f32_e32 v100, v100, v112
	v_sub_f32_e32 v103, v103, v112
	v_sub_f32_e32 v102, v102, v112
	v_sub_f32_e32 v97, v97, v112
	v_sub_f32_e32 v96, v96, v112
	v_sub_f32_e32 v99, v99, v112
	v_sub_f32_e32 v98, v98, v112
	v_pk_fma_f32 v[110:111], v[42:43], v[110:111], v[46:47]
	v_pk_fma_f32 v[106:107], v[50:51], v[106:107], v[54:55]
	v_pk_fma_f32 v[108:109], v[108:109], s[52:53], v[114:115] op_sel_hi:[1,0,1]
	v_pk_fma_f32 v[104:105], v[104:105], s[52:53], v[118:119] op_sel_hi:[1,0,1]
	v_pk_mul_f32 v[102:103], v[112:113], v[102:103] op_sel:[1,0]
	v_pk_mul_f32 v[100:101], v[112:113], v[100:101] op_sel:[1,0]
	v_pk_mul_f32 v[98:99], v[112:113], v[98:99] op_sel:[1,0]
	v_pk_mul_f32 v[96:97], v[112:113], v[96:97] op_sel:[1,0]
	v_pk_fma_f32 v[110:111], v[110:111], s[52:53], v[116:117] op_sel_hi:[1,0,1]
	v_pk_fma_f32 v[106:107], v[106:107], s[52:53], v[120:121] op_sel_hi:[1,0,1]
	v_mov_b32_e32 v112, v104
	v_mov_b32_e32 v113, v108
	v_mov_b32_e32 v114, v105
	v_mov_b32_e32 v115, v109
	v_pk_add_f32 v[112:113], v[112:113], v[114:115]
	v_mov_b32_e32 v114, v106
	v_mov_b32_e32 v115, v110
	v_pk_add_f32 v[112:113], v[114:115], v[112:113]
	v_mov_b32_e32 v114, v107
	v_mov_b32_e32 v115, v111
	v_pk_fma_f32 v[100:101], v[56:57], v[100:101], v[60:61]
	v_pk_fma_f32 v[96:97], v[32:33], v[96:97], v[36:37]
	v_pk_add_f32 v[112:113], v[114:115], v[112:113]
	v_pk_fma_f32 v[102:103], v[58:59], v[102:103], v[62:63]
	v_pk_fma_f32 v[98:99], v[34:35], v[98:99], v[38:39]
	v_pk_fma_f32 v[100:101], v[100:101], s[52:53], v[122:123] op_sel_hi:[1,0,1]
	v_pk_fma_f32 v[96:97], v[96:97], s[52:53], v[126:127] op_sel_hi:[1,0,1]
	v_add_f32_e32 v113, 0, v113
	v_pk_fma_f32 v[102:103], v[102:103], s[52:53], v[124:125] op_sel_hi:[1,0,1]
	v_pk_fma_f32 v[98:99], v[98:99], s[52:53], v[178:179] op_sel_hi:[1,0,1]
	v_add_f32_e32 v116, v112, v113
	v_mov_b32_e32 v112, v96
	v_mov_b32_e32 v113, v100
	v_mov_b32_e32 v114, v97
	v_mov_b32_e32 v115, v101
	v_pk_add_f32 v[112:113], v[112:113], v[114:115]
	v_mov_b32_e32 v114, v98
	v_mov_b32_e32 v115, v102
	v_pk_add_f32 v[112:113], v[114:115], v[112:113]
	v_mov_b32_e32 v114, v99
	v_mov_b32_e32 v115, v103
	v_pk_add_f32 v[112:113], v[114:115], v[112:113]
	s_nop 0
	v_add_f32_e32 v113, v113, v116
	v_add_f32_e32 v112, v112, v113
	v_mbcnt_lo_u32_b32 v113, s2, 0
	v_mbcnt_hi_u32_b32 v113, s2, v113
	v_lshlrev_b32_e32 v113, 2, v113
	v_xor_b32_e32 v114, 0x80, v113
	ds_bpermute_b32 v114, v114, v112
	s_mov_b32 s2, -1
	s_waitcnt lgkmcnt(0)
; DEVFI int lane_opaque() { unsigned m = ~0u; asm volatile("" : "+s"(m)); return (int)__builtin_amdgcn_mbcnt_hi(m, __builtin_amdgcn_mbcnt_lo(m, 0u)); }
; DEVFI float shx(float v, int mask, int lane) { return __int_as_float(__builtin_amdgcn_ds_bpermute((lane ^ mask) << 2, __float_as_int(v))); }
; DEVFI float red64(float v) {
;   const int ln = lane_opaque();
;   v += shx(v, 32, ln); v += shx(v, 16, ln); v += shx(v, 8, ln); v += shx(v, 4, ln); v += shx(v, 2, ln); v += shx(v, 1, ln); return v;
; }
; DEVFI void ln_resid4(const float* ysrc, float* ydst, bfraw* fb, float* stats, const float* pw, const float* pb,
;                      const float* w, const float* b, int lane, bool fin) {
;     ...
;     const float mean = red64(s) * (1.f / 1024.f);
;     float q = 0;
; #pragma unroll
;     for (int i = 0; i < 4; ++i) { const f32x4 d = y[i] - mean; q += d[0] * d[0] + d[1] * d[1] + d[2] * d[2] + d[3] * d[3]; }
;     const float rstd = 1.f / sqrtf(red64(q) * (1.f / 1024.f) + LN_EPS);
;     if (lane == 0) { stats[r * 2] = mean; stats[r * 2 + 1] = rstd; }
	v_add_f32_e32 v112, v112, v114
	v_xor_b32_e32 v114, 64, v113
	ds_bpermute_b32 v114, v114, v112
	s_waitcnt lgkmcnt(0)
	v_add_f32_e32 v112, v112, v114
	v_xor_b32_e32 v114, 32, v113
	s_nop 1
	v_mov_b32_dpp v114, v112 row_ror:8 row_mask:0xf bank_mask:0xf
	s_waitcnt lgkmcnt(0)
	v_add_f32_e32 v112, v112, v114
	v_xor_b32_e32 v114, 16, v113
	s_nop 1
	v_mov_b32_dpp v114, v112 row_half_mirror row_mask:0xf bank_mask:0xf
	s_nop 1
	v_mov_b32_dpp v114, v114 quad_perm:[3,2,1,0] row_mask:0xf bank_mask:0xf
	s_waitcnt lgkmcnt(0)
	v_add_f32_e32 v112, v112, v114
	v_xor_b32_e32 v114, 8, v113
	s_nop 1
	v_mov_b32_dpp v114, v112 quad_perm:[2,3,0,1] row_mask:0xf bank_mask:0xf
	v_xor_b32_e32 v113, 4, v113
	s_waitcnt lgkmcnt(0)
	v_add_f32_e32 v112, v112, v114
	s_nop 1
	v_mov_b32_dpp v113, v112 quad_perm:[1,0,3,2] row_mask:0xf bank_mask:0xf
	s_waitcnt lgkmcnt(0)
	v_add_f32_e32 v131, v112, v113
	v_fmamk_f32 v127, v131, 0xba800000, v109
	v_fmamk_f32 v123, v131, 0xba800000, v105
	v_fmamk_f32 v126, v131, 0xba800000, v108
	v_mul_f32_e32 v112, v127, v127
	v_fmamk_f32 v122, v131, 0xba800000, v104
	v_mul_f32_e32 v113, v123, v123
	v_fmamk_f32 v124, v131, 0xba800000, v110
	v_fmac_f32_e32 v112, v126, v126
	v_fmamk_f32 v120, v131, 0xba800000, v106
	v_fmac_f32_e32 v113, v122, v122
	v_fmamk_f32 v125, v131, 0xba800000, v111
	v_fmac_f32_e32 v112, v124, v124
	v_fmamk_f32 v121, v131, 0xba800000, v107
	v_fmac_f32_e32 v113, v120, v120
	v_fmac_f32_e32 v112, v125, v125
	v_fmac_f32_e32 v113, v121, v121
	v_fmamk_f32 v119, v131, 0xba800000, v101
	v_add_f32_e32 v112, v112, v113
	v_fmamk_f32 v118, v131, 0xba800000, v100
	v_mul_f32_e32 v113, v119, v119
	v_fmamk_f32 v116, v131, 0xba800000, v102
	v_fmac_f32_e32 v113, v118, v118
	v_fmamk_f32 v117, v131, 0xba800000, v103
	v_fmac_f32_e32 v113, v116, v116
	v_fmamk_f32 v115, v131, 0xba800000, v97
	v_fmac_f32_e32 v113, v117, v117
	v_fmamk_f32 v114, v131, 0xba800000, v96
	v_mul_f32_e32 v143, v115, v115
	v_add_f32_e32 v141, v113, v112
	v_fmamk_f32 v112, v131, 0xba800000, v98
	v_fmac_f32_e32 v143, v114, v114
	v_fmamk_f32 v113, v131, 0xba800000, v99
	v_fmac_f32_e32 v143, v112, v112
	v_fmac_f32_e32 v143, v113, v113
	v_add_f32_e32 v141, v143, v141
	v_mbcnt_lo_u32_b32 v143, s2, 0
	v_mbcnt_hi_u32_b32 v143, s2, v143
	v_lshlrev_b32_e32 v143, 2, v143
	v_xor_b32_e32 v145, 0x80, v143
	ds_bpermute_b32 v145, v145, v141
	s_waitcnt lgkmcnt(0)
	v_add_f32_e32 v141, v141, v145
	v_xor_b32_e32 v145, 64, v143
	ds_bpermute_b32 v145, v145, v141
	s_waitcnt lgkmcnt(0)
	v_add_f32_e32 v141, v141, v145
	v_xor_b32_e32 v145, 32, v143
	s_nop 1
	v_mov_b32_dpp v145, v141 row_ror:8 row_mask:0xf bank_mask:0xf
	s_waitcnt lgkmcnt(0)
	v_add_f32_e32 v141, v141, v145
	v_xor_b32_e32 v145, 16, v143
	s_nop 1
	v_mov_b32_dpp v145, v141 row_half_mirror row_mask:0xf bank_mask:0xf
	s_nop 1
	v_mov_b32_dpp v145, v145 quad_perm:[3,2,1,0] row_mask:0xf bank_mask:0xf
	s_waitcnt lgkmcnt(0)
	v_add_f32_e32 v141, v141, v145
	v_xor_b32_e32 v145, 8, v143
	s_nop 1
	v_mov_b32_dpp v145, v141 quad_perm:[2,3,0,1] row_mask:0xf bank_mask:0xf
	v_xor_b32_e32 v143, 4, v143
	s_waitcnt lgkmcnt(0)
	v_add_f32_e32 v141, v141, v145
	s_nop 1
	v_mov_b32_dpp v143, v141 quad_perm:[1,0,3,2] row_mask:0xf bank_mask:0xf
	s_waitcnt lgkmcnt(0)
	v_add_f32_e32 v141, v141, v143
	v_fmamk_f32 v141, v141, 0x3a800000, v183
	v_mul_f32_e32 v143, 0x4f800000, v141
	v_cmp_gt_f32_e32 vcc, s30, v141
	s_nop 1
	v_cndmask_b32_e32 v141, v141, v143, vcc
	v_sqrt_f32_e32 v143, v141
	s_nop 0
	v_add_u32_e32 v145, -1, v143
	v_fma_f32 v149, -v145, v143, v141
	v_cmp_ge_f32_e64 s[6:7], 0, v149
	v_add_u32_e32 v149, 1, v143
	s_nop 0
	v_cndmask_b32_e64 v145, v143, v145, s[6:7]
	v_fma_f32 v143, -v149, v143, v141
	v_cmp_lt_f32_e64 s[6:7], 0, v143
	s_nop 1
	v_cndmask_b32_e64 v143, v145, v149, s[6:7]
	v_mul_f32_e32 v145, 0x37800000, v143
	v_cndmask_b32_e32 v143, v143, v145, vcc
	v_cmp_class_f32_e32 vcc, v141, v222
	s_nop 1
	v_cndmask_b32_e32 v141, v143, v141, vcc
	s_nop 0
	v_rcp_f32_e32 v145, v141
	s_nop 0
	v_fma_f32 v143, -v141, v145, 1.0
	v_fma_f32 v143, v143, v145, v145
	v_div_fixup_f32 v188, v143, v141, 1.0
	s_and_saveexec_b64 s[2:3], s[4:5]
	s_cbranch_execz .LBB0_3166
	v_mul_f32_e32 v178, 0x3a800000, v131
	v_mov_b32_e32 v179, v188
	global_store_dwordx2 v[156:157], v[178:179], off offset:8
; DEVFI void ln_resid4(const float* ysrc, float* ydst, bfraw* fb, float* stats, const float* pw, const float* pb,
;                      const float* w, const float* b, int lane, bool fin) {
;     ...
;   for (int r = 0; r < 4; ++r) {
;     const float pmu = stats[r * 2], prs = stats[r * 2 + 1];
;     f32x4 y[4];
; #pragma unroll
;     for (int i = 0; i < 4; ++i) { const unsigned f0 = fv[r][i][0], f1 = fv[r][i][1];
;       const f32x4 f4 = {__uint_as_float(f0 << 16), __uint_as_float(f0 & 0xffff0000u), __uint_as_float(f1 << 16), __uint_as_float(f1 & 0xffff0000u)};
;       y[i] = ALPHA * ((v[r][i] - pmu) * prs * pwv[i] + pbv[i]) + f4; }
;     float s = 0;
; #pragma unroll
;     for (int i = 0; i < 4; ++i) s += y[i][0] + y[i][1] + y[i][2] + y[i][3];
;     const float mean = red64(s) * (1.f / 1024.f);
;     float q = 0;
; #pragma unroll
;     for (int i = 0; i < 4; ++i) { const f32x4 d = y[i] - mean; q += d[0] * d[0] + d[1] * d[1] + d[2] * d[2] + d[3] * d[3]; }
;     const float rstd = 1.f / sqrtf(red64(q) * (1.f / 1024.f) + LN_EPS);
;     if (lane == 0) { stats[r * 2] = mean; stats[r * 2 + 1] = rstd; }
; #pragma unroll
;     for (int i = 0; i < 4; ++i) { const int c4 = i * 64 + lane;
;       const f32x4 z = (y[i] - mean) * rstd * ww[i] + bb[i];
;       __builtin_nontemporal_store(fin ? z : y[i], (f32x4*)(ydst + r * 1024) + c4);
;       u32x2 pk = {cvtpk(z[0], z[1]), cvtpk(z[2], z[3])}; ((u32x2*)(fb + r * 1024))[c4] = pk; }
.LBB0_3166:
	s_or_b64 exec, exec, s[2:3]
	s_mov_b64 s[2:3], 0x1000
	v_lshl_add_u64 v[178:179], v[168:169], 0, s[2:3]
	v_pk_mul_f32 v[124:125], v[124:125], v[188:189] op_sel_hi:[1,0]
	v_pk_mul_f32 v[126:127], v[126:127], v[188:189] op_sel_hi:[1,0]
	v_lshl_add_u64 v[180:181], v[178:179], 0, v[176:177]
	v_pk_fma_f32 v[124:125], v[26:27], v[124:125], v[30:31]
	v_pk_fma_f32 v[126:127], v[24:25], v[126:127], v[28:29]
	global_store_dwordx4 v[180:181], v[108:111], off nt
	v_mov_b32_e32 v149, v177
	v_mov_b32_e32 v151, v177
	v_cvt_pk_bf16_f32 v108, v126, v127
	v_cvt_pk_bf16_f32 v109, v124, v125
	global_store_dwordx2 v[172:173], v[108:109], off offset:2048
	v_pk_mul_f32 v[108:109], v[120:121], v[188:189] op_sel_hi:[1,0]
	v_pk_mul_f32 v[110:111], v[122:123], v[188:189] op_sel_hi:[1,0]
	v_lshl_add_u64 v[120:121], v[178:179], 0, v[148:149]
	v_pk_fma_f32 v[108:109], v[18:19], v[108:109], v[22:23]
	v_pk_fma_f32 v[110:111], v[16:17], v[110:111], v[20:21]
	global_store_dwordx4 v[120:121], v[104:107], off nt
	v_mov_b32_e32 v153, v177
	s_mov_b32 s2, -1
	v_cvt_pk_bf16_f32 v104, v110, v111
	v_cvt_pk_bf16_f32 v105, v108, v109
	global_store_dwordx2 v[172:173], v[104:105], off offset:2560
	v_pk_mul_f32 v[104:105], v[116:117], v[188:189] op_sel_hi:[1,0]
	v_pk_mul_f32 v[106:107], v[118:119], v[188:189] op_sel_hi:[1,0]
	v_lshl_add_u64 v[108:109], v[178:179], 0, v[150:151]
	v_pk_fma_f32 v[104:105], v[10:11], v[104:105], v[14:15]
	v_pk_fma_f32 v[106:107], v[8:9], v[106:107], v[12:13]
	global_store_dwordx4 v[108:109], v[100:103], off nt
	v_lshlrev_b32_e32 v110, 16, v170
	v_and_b32_e32 v111, 0xffff0000, v170
	v_cvt_pk_bf16_f32 v100, v106, v107
	v_cvt_pk_bf16_f32 v101, v104, v105
	global_store_dwordx2 v[172:173], v[100:101], off offset:3072
	v_pk_mul_f32 v[100:101], v[112:113], v[188:189] op_sel_hi:[1,0]
	v_pk_mul_f32 v[102:103], v[114:115], v[188:189] op_sel_hi:[1,0]
	v_lshl_add_u64 v[104:105], v[178:179], 0, v[152:153]
	v_pk_fma_f32 v[100:101], v[2:3], v[100:101], v[6:7]
	v_pk_fma_f32 v[102:103], v[0:1], v[102:103], v[4:5]
	global_store_dwordx4 v[104:105], v[96:99], off nt
	v_lshlrev_b32_e32 v104, 16, v185
	v_and_b32_e32 v105, 0xffff0000, v185
	v_cvt_pk_bf16_f32 v96, v102, v103
	v_cvt_pk_bf16_f32 v97, v100, v101
	global_store_dwordx2 v[172:173], v[96:97], off offset:3584
	global_load_dwordx2 v[96:97], v[156:157], off offset:16
	v_lshlrev_b32_e32 v98, 16, v186
	v_and_b32_e32 v99, 0xffff0000, v186
	v_lshlrev_b32_e32 v102, 16, v184
	v_and_b32_e32 v103, 0xffff0000, v184
	v_lshlrev_b32_e32 v100, 16, v187
	v_and_b32_e32 v101, 0xffff0000, v187
	v_lshlrev_b32_e32 v106, 16, v174
	v_and_b32_e32 v107, 0xffff0000, v174
	v_lshlrev_b32_e32 v108, 16, v175
	v_and_b32_e32 v109, 0xffff0000, v175
	v_lshlrev_b32_e32 v112, 16, v171
	v_and_b32_e32 v113, 0xffff0000, v171
	s_waitcnt vmcnt(0)
	v_sub_f32_e32 v93, v93, v96
	v_sub_f32_e32 v92, v92, v96
	v_sub_f32_e32 v89, v89, v96
	v_sub_f32_e32 v88, v88, v96
	v_sub_f32_e32 v95, v95, v96
	v_sub_f32_e32 v94, v94, v96
	v_sub_f32_e32 v91, v91, v96
	v_sub_f32_e32 v90, v90, v96
	v_pk_mul_f32 v[92:93], v[96:97], v[92:93] op_sel:[1,0]
	v_pk_mul_f32 v[88:89], v[96:97], v[88:89] op_sel:[1,0]
	v_pk_mul_f32 v[94:95], v[96:97], v[94:95] op_sel:[1,0]
	v_pk_mul_f32 v[90:91], v[96:97], v[90:91] op_sel:[1,0]
	v_pk_fma_f32 v[92:93], v[40:41], v[92:93], v[44:45]
	v_pk_fma_f32 v[88:89], v[48:49], v[88:89], v[52:53]
	v_sub_f32_e32 v85, v85, v96
	v_sub_f32_e32 v84, v84, v96
	v_sub_f32_e32 v87, v87, v96
	v_sub_f32_e32 v86, v86, v96
	v_sub_f32_e32 v81, v81, v96
	v_sub_f32_e32 v80, v80, v96
	v_sub_f32_e32 v83, v83, v96
	v_sub_f32_e32 v82, v82, v96
	v_pk_fma_f32 v[94:95], v[42:43], v[94:95], v[46:47]
	v_pk_fma_f32 v[90:91], v[50:51], v[90:91], v[54:55]
	v_pk_fma_f32 v[92:93], v[92:93], s[52:53], v[98:99] op_sel_hi:[1,0,1]
	v_pk_fma_f32 v[88:89], v[88:89], s[52:53], v[102:103] op_sel_hi:[1,0,1]
	v_pk_mul_f32 v[86:87], v[96:97], v[86:87] op_sel:[1,0]
	v_pk_mul_f32 v[84:85], v[96:97], v[84:85] op_sel:[1,0]
	v_pk_fma_f32 v[94:95], v[94:95], s[52:53], v[100:101] op_sel_hi:[1,0,1]
	v_pk_fma_f32 v[90:91], v[90:91], s[52:53], v[104:105] op_sel_hi:[1,0,1]
	v_pk_mul_f32 v[82:83], v[96:97], v[82:83] op_sel:[1,0]
	v_pk_mul_f32 v[80:81], v[96:97], v[80:81] op_sel:[1,0]
	v_mov_b32_e32 v96, v88
	v_mov_b32_e32 v97, v92
	v_mov_b32_e32 v98, v89
	v_mov_b32_e32 v99, v93
	v_pk_add_f32 v[96:97], v[96:97], v[98:99]
	v_mov_b32_e32 v98, v90
	v_mov_b32_e32 v99, v94
	v_pk_add_f32 v[96:97], v[98:99], v[96:97]
	v_mov_b32_e32 v98, v91
	v_mov_b32_e32 v99, v95
	v_pk_fma_f32 v[84:85], v[56:57], v[84:85], v[60:61]
	v_pk_fma_f32 v[80:81], v[32:33], v[80:81], v[36:37]
	v_pk_add_f32 v[96:97], v[98:99], v[96:97]
	v_pk_fma_f32 v[86:87], v[58:59], v[86:87], v[62:63]
	v_pk_fma_f32 v[84:85], v[84:85], s[52:53], v[106:107] op_sel_hi:[1,0,1]
	v_pk_fma_f32 v[82:83], v[34:35], v[82:83], v[38:39]
	v_pk_fma_f32 v[80:81], v[80:81], s[52:53], v[110:111] op_sel_hi:[1,0,1]
	v_add_f32_e32 v97, 0, v97
	v_pk_fma_f32 v[86:87], v[86:87], s[52:53], v[108:109] op_sel_hi:[1,0,1]
	v_pk_fma_f32 v[82:83], v[82:83], s[52:53], v[112:113] op_sel_hi:[1,0,1]
	v_add_f32_e32 v100, v96, v97
	v_mov_b32_e32 v96, v80
	v_mov_b32_e32 v97, v84
	v_mov_b32_e32 v98, v81
	v_mov_b32_e32 v99, v85
	v_pk_add_f32 v[96:97], v[96:97], v[98:99]
	v_mov_b32_e32 v98, v82
	v_mov_b32_e32 v99, v86
	v_pk_add_f32 v[96:97], v[98:99], v[96:97]
	v_mov_b32_e32 v98, v83
	v_mov_b32_e32 v99, v87
	v_pk_add_f32 v[96:97], v[98:99], v[96:97]
	s_nop 0
	v_add_f32_e32 v97, v97, v100
	v_add_f32_e32 v96, v96, v97
	v_mbcnt_lo_u32_b32 v97, s2, 0
	v_mbcnt_hi_u32_b32 v97, s2, v97
	v_lshlrev_b32_e32 v97, 2, v97
	v_xor_b32_e32 v98, 0x80, v97
	ds_bpermute_b32 v98, v98, v96
	s_mov_b32 s2, -1
	s_waitcnt lgkmcnt(0)
; DEVFI int lane_opaque() { unsigned m = ~0u; asm volatile("" : "+s"(m)); return (int)__builtin_amdgcn_mbcnt_hi(m, __builtin_amdgcn_mbcnt_lo(m, 0u)); }
; DEVFI float shx(float v, int mask, int lane) { return __int_as_float(__builtin_amdgcn_ds_bpermute((lane ^ mask) << 2, __float_as_int(v))); }
; DEVFI float red64(float v) {
;   const int ln = lane_opaque();
;   v += shx(v, 32, ln); v += shx(v, 16, ln); v += shx(v, 8, ln); v += shx(v, 4, ln); v += shx(v, 2, ln); v += shx(v, 1, ln); return v;
; }
; DEVFI void ln_resid4(const float* ysrc, float* ydst, bfraw* fb, float* stats, const float* pw, const float* pb,
;                      const float* w, const float* b, int lane, bool fin) {
;     ...
;     const float mean = red64(s) * (1.f / 1024.f);
;     float q = 0;
; #pragma unroll
;     for (int i = 0; i < 4; ++i) { const f32x4 d = y[i] - mean; q += d[0] * d[0] + d[1] * d[1] + d[2] * d[2] + d[3] * d[3]; }
;     const float rstd = 1.f / sqrtf(red64(q) * (1.f / 1024.f) + LN_EPS);
;     if (lane == 0) { stats[r * 2] = mean; stats[r * 2 + 1] = rstd; }
	v_add_f32_e32 v96, v96, v98
	v_xor_b32_e32 v98, 64, v97
	ds_bpermute_b32 v98, v98, v96
	s_waitcnt lgkmcnt(0)
	v_add_f32_e32 v96, v96, v98
	v_xor_b32_e32 v98, 32, v97
	s_nop 1
	v_mov_b32_dpp v98, v96 row_ror:8 row_mask:0xf bank_mask:0xf
	s_waitcnt lgkmcnt(0)
	v_add_f32_e32 v96, v96, v98
	v_xor_b32_e32 v98, 16, v97
	s_nop 1
	v_mov_b32_dpp v98, v96 row_half_mirror row_mask:0xf bank_mask:0xf
	s_nop 1
	v_mov_b32_dpp v98, v98 quad_perm:[3,2,1,0] row_mask:0xf bank_mask:0xf
	s_waitcnt lgkmcnt(0)
	v_add_f32_e32 v96, v96, v98
	v_xor_b32_e32 v98, 8, v97
	s_nop 1
	v_mov_b32_dpp v98, v96 quad_perm:[2,3,0,1] row_mask:0xf bank_mask:0xf
	v_xor_b32_e32 v97, 4, v97
	s_waitcnt lgkmcnt(0)
	v_add_f32_e32 v96, v96, v98
	s_nop 1
	v_mov_b32_dpp v97, v96 quad_perm:[1,0,3,2] row_mask:0xf bank_mask:0xf
	s_waitcnt lgkmcnt(0)
	v_add_f32_e32 v113, v96, v97
	v_fmamk_f32 v111, v113, 0xba800000, v93
	v_fmamk_f32 v107, v113, 0xba800000, v89
	v_fmamk_f32 v110, v113, 0xba800000, v92
	v_mul_f32_e32 v96, v111, v111
	v_fmamk_f32 v106, v113, 0xba800000, v88
	v_mul_f32_e32 v97, v107, v107
	v_fmamk_f32 v108, v113, 0xba800000, v94
	v_fmac_f32_e32 v96, v110, v110
	v_fmamk_f32 v104, v113, 0xba800000, v90
	v_fmac_f32_e32 v97, v106, v106
	v_fmamk_f32 v109, v113, 0xba800000, v95
	v_fmac_f32_e32 v96, v108, v108
	v_fmamk_f32 v105, v113, 0xba800000, v91
	v_fmac_f32_e32 v97, v104, v104
	v_fmac_f32_e32 v96, v109, v109
	v_fmac_f32_e32 v97, v105, v105
	v_fmamk_f32 v103, v113, 0xba800000, v85
	v_add_f32_e32 v96, v96, v97
	v_fmamk_f32 v102, v113, 0xba800000, v84
	v_mul_f32_e32 v97, v103, v103
	v_fmamk_f32 v100, v113, 0xba800000, v86
	v_fmac_f32_e32 v97, v102, v102
	v_fmamk_f32 v101, v113, 0xba800000, v87
	v_fmac_f32_e32 v97, v100, v100
	v_fmamk_f32 v99, v113, 0xba800000, v81
	v_fmac_f32_e32 v97, v101, v101
	v_fmamk_f32 v98, v113, 0xba800000, v80
	v_mul_f32_e32 v114, v99, v99
	v_add_f32_e32 v112, v97, v96
	v_fmamk_f32 v96, v113, 0xba800000, v82
	v_fmac_f32_e32 v114, v98, v98
	v_fmamk_f32 v97, v113, 0xba800000, v83
	v_fmac_f32_e32 v114, v96, v96
	v_fmac_f32_e32 v114, v97, v97
	v_add_f32_e32 v112, v114, v112
	v_mbcnt_lo_u32_b32 v114, s2, 0
	v_mbcnt_hi_u32_b32 v114, s2, v114
	v_lshlrev_b32_e32 v114, 2, v114
	v_xor_b32_e32 v115, 0x80, v114
	ds_bpermute_b32 v115, v115, v112
	s_waitcnt lgkmcnt(0)
	v_add_f32_e32 v112, v112, v115
	v_xor_b32_e32 v115, 64, v114
	ds_bpermute_b32 v115, v115, v112
	s_waitcnt lgkmcnt(0)
	v_add_f32_e32 v112, v112, v115
	v_xor_b32_e32 v115, 32, v114
	s_nop 1
	v_mov_b32_dpp v115, v112 row_ror:8 row_mask:0xf bank_mask:0xf
	s_waitcnt lgkmcnt(0)
	v_add_f32_e32 v112, v112, v115
	v_xor_b32_e32 v115, 16, v114
	s_nop 1
	v_mov_b32_dpp v115, v112 row_half_mirror row_mask:0xf bank_mask:0xf
	s_nop 1
	v_mov_b32_dpp v115, v115 quad_perm:[3,2,1,0] row_mask:0xf bank_mask:0xf
	s_waitcnt lgkmcnt(0)
	v_add_f32_e32 v112, v112, v115
	v_xor_b32_e32 v115, 8, v114
	s_nop 1
	v_mov_b32_dpp v115, v112 quad_perm:[2,3,0,1] row_mask:0xf bank_mask:0xf
	v_xor_b32_e32 v114, 4, v114
	s_waitcnt lgkmcnt(0)
	v_add_f32_e32 v112, v112, v115
	s_nop 1
	v_mov_b32_dpp v114, v112 quad_perm:[1,0,3,2] row_mask:0xf bank_mask:0xf
	s_waitcnt lgkmcnt(0)
	v_add_f32_e32 v112, v112, v114
	v_fmamk_f32 v112, v112, 0x3a800000, v183
	v_mul_f32_e32 v114, 0x4f800000, v112
	v_cmp_gt_f32_e32 vcc, s30, v112
	s_nop 1
	v_cndmask_b32_e32 v112, v112, v114, vcc
	v_sqrt_f32_e32 v114, v112
	s_nop 0
	v_add_u32_e32 v115, -1, v114
	v_fma_f32 v116, -v115, v114, v112
	v_cmp_ge_f32_e64 s[6:7], 0, v116
	v_add_u32_e32 v116, 1, v114
	s_nop 0
	v_cndmask_b32_e64 v115, v114, v115, s[6:7]
	v_fma_f32 v114, -v116, v114, v112
	v_cmp_lt_f32_e64 s[6:7], 0, v114
	s_nop 1
	v_cndmask_b32_e64 v114, v115, v116, s[6:7]
	v_mul_f32_e32 v115, 0x37800000, v114
	v_cndmask_b32_e32 v114, v114, v115, vcc
	v_cmp_class_f32_e32 vcc, v112, v222
	s_nop 1
	v_cndmask_b32_e32 v112, v114, v112, vcc
	s_nop 0
	v_rcp_f32_e32 v115, v112
	s_nop 0
	v_fma_f32 v114, -v112, v115, 1.0
	v_fma_f32 v114, v114, v115, v115
	v_div_fixup_f32 v112, v114, v112, 1.0
	s_and_saveexec_b64 s[2:3], s[4:5]
	s_cbranch_execz .LBB0_3168
	v_mul_f32_e32 v114, 0x3a800000, v113
	v_mov_b32_e32 v115, v112
	global_store_dwordx2 v[156:157], v[114:115], off offset:16
.LBB0_3168:
	s_or_b64 exec, exec, s[2:3]
	s_mov_b64 s[2:3], 0x2000
	v_lshl_add_u64 v[114:115], v[168:169], 0, s[2:3]
	s_mov_b64 s[2:3], 0x1000
	v_lshl_add_u64 v[116:117], v[154:155], 0, s[2:3]
	v_pk_mul_f32 v[108:109], v[108:109], v[112:113] op_sel_hi:[1,0]
	v_pk_mul_f32 v[110:111], v[110:111], v[112:113] op_sel_hi:[1,0]
	v_lshl_add_u64 v[118:119], v[114:115], 0, v[176:177]
	v_mov_b32_e32 v159, v177
	v_pk_fma_f32 v[108:109], v[26:27], v[108:109], v[30:31]
	v_pk_fma_f32 v[110:111], v[24:25], v[110:111], v[28:29]
	global_store_dwordx4 v[118:119], v[92:95], off nt
	s_mov_b32 s2, -1
	s_nop 0
	v_cvt_pk_bf16_f32 v92, v110, v111
	v_cvt_pk_bf16_f32 v93, v108, v109
	v_lshl_add_u64 v[94:95], v[116:117], 0, v[158:159]
	global_store_dwordx2 v[94:95], v[92:93], off
	v_pk_mul_f32 v[92:93], v[104:105], v[112:113] op_sel_hi:[1,0]
	v_lshl_add_u64 v[104:105], v[114:115], 0, v[148:149]
	v_pk_mul_f32 v[94:95], v[106:107], v[112:113] op_sel_hi:[1,0]
	v_pk_fma_f32 v[92:93], v[18:19], v[92:93], v[22:23]
	global_store_dwordx4 v[104:105], v[88:91], off nt
	v_pk_fma_f32 v[94:95], v[16:17], v[94:95], v[20:21]
	s_nop 0
	v_lshlrev_b32_e32 v88, 3, v140
	v_mov_b32_e32 v89, v177
	v_cvt_pk_bf16_f32 v90, v94, v95
	v_cvt_pk_bf16_f32 v91, v92, v93
	v_lshl_add_u64 v[92:93], v[116:117], 0, v[88:89]
	global_store_dwordx2 v[92:93], v[90:91], off
	v_pk_mul_f32 v[90:91], v[100:101], v[112:113] op_sel_hi:[1,0]
	v_lshl_add_u64 v[94:95], v[114:115], 0, v[150:151]
	v_pk_mul_f32 v[92:93], v[102:103], v[112:113] op_sel_hi:[1,0]
; DEVFI void ln_resid4(const float* ysrc, float* ydst, bfraw* fb, float* stats, const float* pw, const float* pb,
;                      const float* w, const float* b, int lane, bool fin) {
;     ...
;   for (int r = 0; r < 4; ++r) {
;     const float pmu = stats[r * 2], prs = stats[r * 2 + 1];
;     f32x4 y[4];
; #pragma unroll
;     for (int i = 0; i < 4; ++i) { const unsigned f0 = fv[r][i][0], f1 = fv[r][i][1];
;       const f32x4 f4 = {__uint_as_float(f0 << 16), __uint_as_float(f0 & 0xffff0000u), __uint_as_float(f1 << 16), __uint_as_float(f1 & 0xffff0000u)};
;       y[i] = ALPHA * ((v[r][i] - pmu) * prs * pwv[i] + pbv[i]) + f4; }
;     float s = 0;
; #pragma unroll
;     for (int i = 0; i < 4; ++i) s += y[i][0] + y[i][1] + y[i][2] + y[i][3];
;     const float mean = red64(s) * (1.f / 1024.f);
;     float q = 0;
; #pragma unroll
;     for (int i = 0; i < 4; ++i) { const f32x4 d = y[i] - mean; q += d[0] * d[0] + d[1] * d[1] + d[2] * d[2] + d[3] * d[3]; }
;     const float rstd = 1.f / sqrtf(red64(q) * (1.f / 1024.f) + LN_EPS);
;     if (lane == 0) { stats[r * 2] = mean; stats[r * 2 + 1] = rstd; }
; #pragma unroll
;     for (int i = 0; i < 4; ++i) { const int c4 = i * 64 + lane;
;       const f32x4 z = (y[i] - mean) * rstd * ww[i] + bb[i];
;       __builtin_nontemporal_store(fin ? z : y[i], (f32x4*)(ydst + r * 1024) + c4);
;       u32x2 pk = {cvtpk(z[0], z[1]), cvtpk(z[2], z[3])}; ((u32x2*)(fb + r * 1024))[c4] = pk; }
	v_pk_fma_f32 v[90:91], v[10:11], v[90:91], v[14:15]
	global_store_dwordx4 v[94:95], v[84:87], off nt
	v_pk_fma_f32 v[92:93], v[8:9], v[92:93], v[12:13]
	v_lshlrev_b32_e32 v94, 16, v165
	v_lshlrev_b32_e32 v84, 3, v142
	v_mov_b32_e32 v85, v177
	v_cvt_pk_bf16_f32 v86, v92, v93
	v_cvt_pk_bf16_f32 v87, v90, v91
	v_lshl_add_u64 v[90:91], v[116:117], 0, v[84:85]
	global_store_dwordx2 v[90:91], v[86:87], off
	v_pk_mul_f32 v[86:87], v[96:97], v[112:113] op_sel_hi:[1,0]
	v_lshl_add_u64 v[92:93], v[114:115], 0, v[152:153]
	v_pk_mul_f32 v[90:91], v[98:99], v[112:113] op_sel_hi:[1,0]
	v_pk_fma_f32 v[86:87], v[2:3], v[86:87], v[6:7]
	global_store_dwordx4 v[92:93], v[80:83], off nt
	v_pk_fma_f32 v[90:91], v[0:1], v[90:91], v[4:5]
	v_lshlrev_b32_e32 v92, 16, v164
	v_lshlrev_b32_e32 v80, 3, v144
	v_mov_b32_e32 v81, v177
	v_cvt_pk_bf16_f32 v82, v90, v91
	v_cvt_pk_bf16_f32 v83, v86, v87
	v_lshl_add_u64 v[86:87], v[116:117], 0, v[80:81]
	global_store_dwordx2 v[86:87], v[82:83], off
	global_load_dwordx2 v[82:83], v[156:157], off offset:24
	v_lshlrev_b32_e32 v86, 16, v166
	v_and_b32_e32 v87, 0xffff0000, v166
	v_and_b32_e32 v93, 0xffff0000, v164
	v_lshlrev_b32_e32 v90, 16, v167
	v_and_b32_e32 v91, 0xffff0000, v167
	v_and_b32_e32 v95, 0xffff0000, v165
	v_lshlrev_b32_e32 v96, 16, v162
	v_and_b32_e32 v97, 0xffff0000, v162
	v_lshlrev_b32_e32 v98, 16, v163
	v_and_b32_e32 v99, 0xffff0000, v163
	s_waitcnt vmcnt(0)
	v_sub_f32_e32 v77, v77, v82
	v_sub_f32_e32 v76, v76, v82
	v_sub_f32_e32 v79, v79, v82
	v_sub_f32_e32 v78, v78, v82
	v_sub_f32_e32 v73, v73, v82
	v_sub_f32_e32 v72, v72, v82
	v_sub_f32_e32 v75, v75, v82
	v_sub_f32_e32 v74, v74, v82
	v_sub_f32_e32 v69, v69, v82
	v_sub_f32_e32 v68, v68, v82
	v_sub_f32_e32 v71, v71, v82
	v_sub_f32_e32 v70, v70, v82
	v_pk_mul_f32 v[78:79], v[82:83], v[78:79] op_sel:[1,0]
	v_pk_mul_f32 v[76:77], v[82:83], v[76:77] op_sel:[1,0]
	v_pk_mul_f32 v[74:75], v[82:83], v[74:75] op_sel:[1,0]
	v_pk_mul_f32 v[72:73], v[82:83], v[72:73] op_sel:[1,0]
	v_pk_mul_f32 v[70:71], v[82:83], v[70:71] op_sel:[1,0]
	v_pk_mul_f32 v[68:69], v[82:83], v[68:69] op_sel:[1,0]
	v_pk_fma_f32 v[40:41], v[40:41], v[76:77], v[44:45]
	v_pk_fma_f32 v[42:43], v[42:43], v[78:79], v[46:47]
	v_pk_fma_f32 v[44:45], v[48:49], v[72:73], v[52:53]
	v_pk_fma_f32 v[46:47], v[50:51], v[74:75], v[54:55]
	v_pk_fma_f32 v[52:53], v[56:57], v[68:69], v[60:61]
	v_pk_fma_f32 v[54:55], v[58:59], v[70:71], v[62:63]
	v_sub_f32_e32 v57, v65, v82
	v_sub_f32_e32 v56, v64, v82
	v_sub_f32_e32 v59, v67, v82
	v_sub_f32_e32 v58, v66, v82
	v_pk_fma_f32 v[48:49], v[40:41], s[52:53], v[86:87] op_sel_hi:[1,0,1]
	v_pk_fma_f32 v[44:45], v[44:45], s[52:53], v[92:93] op_sel_hi:[1,0,1]
	v_pk_mul_f32 v[58:59], v[82:83], v[58:59] op_sel:[1,0]
	v_pk_mul_f32 v[56:57], v[82:83], v[56:57] op_sel:[1,0]
	v_pk_fma_f32 v[50:51], v[42:43], s[52:53], v[90:91] op_sel_hi:[1,0,1]
	v_pk_fma_f32 v[46:47], v[46:47], s[52:53], v[94:95] op_sel_hi:[1,0,1]
	v_pk_fma_f32 v[32:33], v[32:33], v[56:57], v[36:37]
	v_pk_fma_f32 v[34:35], v[34:35], v[58:59], v[38:39]
	v_mov_b32_e32 v36, v44
	v_mov_b32_e32 v37, v48
	v_mov_b32_e32 v38, v45
	v_mov_b32_e32 v39, v49
	v_pk_add_f32 v[36:37], v[36:37], v[38:39]
	v_mov_b32_e32 v38, v46
	v_mov_b32_e32 v39, v50
	v_pk_add_f32 v[36:37], v[38:39], v[36:37]
	v_mov_b32_e32 v38, v47
	v_mov_b32_e32 v39, v51
	v_pk_fma_f32 v[40:41], v[52:53], s[52:53], v[96:97] op_sel_hi:[1,0,1]
	v_lshlrev_b32_e32 v52, 16, v160
	v_and_b32_e32 v53, 0xffff0000, v160
	v_pk_add_f32 v[36:37], v[38:39], v[36:37]
	v_pk_fma_f32 v[42:43], v[54:55], s[52:53], v[98:99] op_sel_hi:[1,0,1]
	v_lshlrev_b32_e32 v54, 16, v161
	v_and_b32_e32 v55, 0xffff0000, v161
	v_pk_fma_f32 v[32:33], v[32:33], s[52:53], v[52:53] op_sel_hi:[1,0,1]
	v_add_f32_e32 v37, 0, v37
	v_pk_fma_f32 v[34:35], v[34:35], s[52:53], v[54:55] op_sel_hi:[1,0,1]
	v_add_f32_e32 v52, v36, v37
	v_mov_b32_e32 v36, v32
	v_mov_b32_e32 v37, v40
	v_mov_b32_e32 v38, v33
	v_mov_b32_e32 v39, v41
	v_pk_add_f32 v[36:37], v[36:37], v[38:39]
	v_mov_b32_e32 v38, v34
	v_mov_b32_e32 v39, v42
	v_pk_add_f32 v[36:37], v[38:39], v[36:37]
	v_mov_b32_e32 v38, v35
	v_mov_b32_e32 v39, v43
	v_pk_add_f32 v[36:37], v[38:39], v[36:37]
	s_nop 0
	v_add_f32_e32 v37, v37, v52
	v_add_f32_e32 v36, v36, v37
	v_mbcnt_lo_u32_b32 v37, s2, 0
	v_mbcnt_hi_u32_b32 v37, s2, v37
	v_lshlrev_b32_e32 v37, 2, v37
	v_xor_b32_e32 v38, 0x80, v37
	ds_bpermute_b32 v38, v38, v36
	s_mov_b32 s2, -1
	s_waitcnt lgkmcnt(0)
; DEVFI int lane_opaque() { unsigned m = ~0u; asm volatile("" : "+s"(m)); return (int)__builtin_amdgcn_mbcnt_hi(m, __builtin_amdgcn_mbcnt_lo(m, 0u)); }
; DEVFI float shx(float v, int mask, int lane) { return __int_as_float(__builtin_amdgcn_ds_bpermute((lane ^ mask) << 2, __float_as_int(v))); }
; DEVFI float red64(float v) {
;   const int ln = lane_opaque();
;   v += shx(v, 32, ln); v += shx(v, 16, ln); v += shx(v, 8, ln); v += shx(v, 4, ln); v += shx(v, 2, ln); v += shx(v, 1, ln); return v;
; }
; DEVFI void ln_resid4(const float* ysrc, float* ydst, bfraw* fb, float* stats, const float* pw, const float* pb,
;                      const float* w, const float* b, int lane, bool fin) {
;     ...
;     const float mean = red64(s) * (1.f / 1024.f);
;     float q = 0;
; #pragma unroll
;     for (int i = 0; i < 4; ++i) { const f32x4 d = y[i] - mean; q += d[0] * d[0] + d[1] * d[1] + d[2] * d[2] + d[3] * d[3]; }
;     const float rstd = 1.f / sqrtf(red64(q) * (1.f / 1024.f) + LN_EPS);
;     if (lane == 0) { stats[r * 2] = mean; stats[r * 2 + 1] = rstd; }
	v_add_f32_e32 v36, v36, v38
	v_xor_b32_e32 v38, 64, v37
	ds_bpermute_b32 v38, v38, v36
	s_waitcnt lgkmcnt(0)
	v_add_f32_e32 v36, v36, v38
	v_xor_b32_e32 v38, 32, v37
	s_nop 1
	v_mov_b32_dpp v38, v36 row_ror:8 row_mask:0xf bank_mask:0xf
	s_waitcnt lgkmcnt(0)
	v_add_f32_e32 v36, v36, v38
	v_xor_b32_e32 v38, 16, v37
	s_nop 1
	v_mov_b32_dpp v38, v36 row_half_mirror row_mask:0xf bank_mask:0xf
	s_nop 1
	v_mov_b32_dpp v38, v38 quad_perm:[3,2,1,0] row_mask:0xf bank_mask:0xf
	s_waitcnt lgkmcnt(0)
	v_add_f32_e32 v36, v36, v38
	v_xor_b32_e32 v38, 8, v37
	s_nop 1
	v_mov_b32_dpp v38, v36 quad_perm:[2,3,0,1] row_mask:0xf bank_mask:0xf
	v_xor_b32_e32 v37, 4, v37
	s_waitcnt lgkmcnt(0)
	v_add_f32_e32 v36, v36, v38
	s_nop 1
	v_mov_b32_dpp v37, v36 quad_perm:[1,0,3,2] row_mask:0xf bank_mask:0xf
	s_waitcnt lgkmcnt(0)
	v_add_f32_e32 v65, v36, v37
	v_fmamk_f32 v63, v65, 0xba800000, v49
	v_fmamk_f32 v59, v65, 0xba800000, v45
	v_fmamk_f32 v62, v65, 0xba800000, v48
	v_mul_f32_e32 v36, v63, v63
	v_fmamk_f32 v58, v65, 0xba800000, v44
	v_mul_f32_e32 v37, v59, v59
	v_fmamk_f32 v60, v65, 0xba800000, v50
	v_fmac_f32_e32 v36, v62, v62
	v_fmamk_f32 v56, v65, 0xba800000, v46
	v_fmac_f32_e32 v37, v58, v58
	v_fmamk_f32 v61, v65, 0xba800000, v51
	v_fmac_f32_e32 v36, v60, v60
	v_fmamk_f32 v57, v65, 0xba800000, v47
	v_fmac_f32_e32 v37, v56, v56
	v_fmac_f32_e32 v36, v61, v61
	v_fmac_f32_e32 v37, v57, v57
	v_fmamk_f32 v55, v65, 0xba800000, v41
	v_add_f32_e32 v36, v36, v37
	v_fmamk_f32 v54, v65, 0xba800000, v40
	v_mul_f32_e32 v37, v55, v55
	v_fmamk_f32 v52, v65, 0xba800000, v42
	v_fmac_f32_e32 v37, v54, v54
	v_fmamk_f32 v53, v65, 0xba800000, v43
	v_fmac_f32_e32 v37, v52, v52
	v_fmamk_f32 v39, v65, 0xba800000, v33
	v_fmac_f32_e32 v37, v53, v53
	v_fmamk_f32 v38, v65, 0xba800000, v32
	v_mul_f32_e32 v66, v39, v39
	v_add_f32_e32 v64, v37, v36
	v_fmamk_f32 v36, v65, 0xba800000, v34
	v_fmac_f32_e32 v66, v38, v38
	v_fmamk_f32 v37, v65, 0xba800000, v35
	v_fmac_f32_e32 v66, v36, v36
	v_fmac_f32_e32 v66, v37, v37
	v_add_f32_e32 v64, v66, v64
	v_mbcnt_lo_u32_b32 v66, s2, 0
	v_mbcnt_hi_u32_b32 v66, s2, v66
	v_lshlrev_b32_e32 v66, 2, v66
	v_xor_b32_e32 v67, 0x80, v66
	ds_bpermute_b32 v67, v67, v64
	s_waitcnt lgkmcnt(0)
	v_add_f32_e32 v64, v64, v67
	v_xor_b32_e32 v67, 64, v66
	ds_bpermute_b32 v67, v67, v64
	s_waitcnt lgkmcnt(0)
	v_add_f32_e32 v64, v64, v67
	v_xor_b32_e32 v67, 32, v66
	s_nop 1
	v_mov_b32_dpp v67, v64 row_ror:8 row_mask:0xf bank_mask:0xf
	s_waitcnt lgkmcnt(0)
	v_add_f32_e32 v64, v64, v67
	v_xor_b32_e32 v67, 16, v66
	s_nop 1
	v_mov_b32_dpp v67, v64 row_half_mirror row_mask:0xf bank_mask:0xf
	s_nop 1
	v_mov_b32_dpp v67, v67 quad_perm:[3,2,1,0] row_mask:0xf bank_mask:0xf
	s_waitcnt lgkmcnt(0)
	v_add_f32_e32 v64, v64, v67
	v_xor_b32_e32 v67, 8, v66
	s_nop 1
	v_mov_b32_dpp v67, v64 quad_perm:[2,3,0,1] row_mask:0xf bank_mask:0xf
	v_xor_b32_e32 v66, 4, v66
	s_waitcnt lgkmcnt(0)
	v_add_f32_e32 v64, v64, v67
	s_nop 1
	v_mov_b32_dpp v66, v64 quad_perm:[1,0,3,2] row_mask:0xf bank_mask:0xf
	s_waitcnt lgkmcnt(0)
	v_add_f32_e32 v64, v64, v66
	v_fmamk_f32 v64, v64, 0x3a800000, v183
	v_mul_f32_e32 v66, 0x4f800000, v64
	v_cmp_gt_f32_e32 vcc, s30, v64
	s_nop 1
	v_cndmask_b32_e32 v64, v64, v66, vcc
	v_sqrt_f32_e32 v66, v64
	s_nop 0
	v_add_u32_e32 v67, -1, v66
	v_fma_f32 v68, -v67, v66, v64
	v_cmp_ge_f32_e64 s[6:7], 0, v68
	v_add_u32_e32 v68, 1, v66
	s_nop 0
	v_cndmask_b32_e64 v67, v66, v67, s[6:7]
	v_fma_f32 v66, -v68, v66, v64
	v_cmp_lt_f32_e64 s[6:7], 0, v66
	s_nop 1
	v_cndmask_b32_e64 v66, v67, v68, s[6:7]
	v_mul_f32_e32 v67, 0x37800000, v66
	v_cndmask_b32_e32 v66, v66, v67, vcc
	v_cmp_class_f32_e32 vcc, v64, v222
	s_nop 1
	v_cndmask_b32_e32 v64, v66, v64, vcc
	s_nop 0
	v_rcp_f32_e32 v67, v64
	s_nop 0
	v_fma_f32 v66, -v64, v67, 1.0
	v_fma_f32 v66, v66, v67, v67
	v_div_fixup_f32 v64, v66, v64, 1.0
	s_and_saveexec_b64 s[2:3], s[4:5]
	s_cbranch_execz .LBB0_3153
	v_mul_f32_e32 v66, 0x3a800000, v65
	v_mov_b32_e32 v67, v64
	global_store_dwordx2 v[156:157], v[66:67], off offset:24
	s_branch .LBB0_3153

; DEVFI int lane_opaque() { unsigned m = ~0u; asm volatile("" : "+s"(m)); return (int)__builtin_amdgcn_mbcnt_hi(m, __builtin_amdgcn_mbcnt_lo(m, 0u)); }
; DEVFI float shx(float v, int mask, int lane) { return __int_as_float(__builtin_amdgcn_ds_bpermute((lane ^ mask) << 2, __float_as_int(v))); }
; #define SBAR() __builtin_amdgcn_sched_barrier(0)
; DEVFI float red16max(float v) {
;   const int ln = lane_opaque();
;   v = fmaxf(v, shx(v, 1, ln)); v = fmaxf(v, shx(v, 2, ln)); v = fmaxf(v, shx(v, 4, ln)); v = fmaxf(v, shx(v, 8, ln)); return v;
; }
; __global__ void __launch_bounds__(512) mega(Params p) {
;     ...
;             auto smax = [&](f32x4 (&a)[8], const int m) {
; #pragma unroll
;               for (int j = 0; j < 4; ++j) { float mx = a[0][j];
; #pragma unroll
;                 for (int n = 1; n < 8; ++n) mx = fmaxf(mx, a[n][j]);
;                 mx = red16max(mx);
;                 if (fr == 0) red[wcI * 256 + rb + m * 16 + j] = mx; }
;               SBAR(); };
;             smax(acc[0], 0); smax(acc[1], 1); smax(acc[2], 2); smax(acc[3], 3);
.LBB0_3460:
	v_max_f32_e32 v128, v120, v120
	v_max_f32_e32 v129, v124, v124
	s_mov_b32 s2, -1
	v_max_f32_e32 v128, v129, v128
	v_max3_f32 v128, v128, v116, v112
	v_mbcnt_lo_u32_b32 v129, s2, 0
	v_mbcnt_hi_u32_b32 v129, s2, v129
	v_max3_f32 v128, v128, v108, v104
	v_lshlrev_b32_e32 v133, 2, v129
	v_max3_f32 v128, v128, v100, v96
	v_xor_b32_e32 v129, 4, v133
	s_nop 1
	v_mov_b32_dpp v129, v128 quad_perm:[1,0,3,2] row_mask:0xf bank_mask:0xf
	v_xor_b32_e32 v134, 16, v133
	v_cmp_eq_u32_e32 vcc, 0, v131
	s_waitcnt lgkmcnt(0)
	v_max_f32_e32 v129, v129, v129
	v_max_f32_e32 v128, v128, v129
	v_xor_b32_e32 v129, 8, v133
	s_nop 1
	v_mov_b32_dpp v129, v128 quad_perm:[2,3,0,1] row_mask:0xf bank_mask:0xf
	s_waitcnt lgkmcnt(0)
	v_max_f32_e32 v129, v129, v129
	v_max_f32_e32 v128, v128, v129
	s_nop 1
	v_mov_b32_dpp v129, v128 row_half_mirror row_mask:0xf bank_mask:0xf
	s_nop 1
	v_mov_b32_dpp v129, v129 quad_perm:[3,2,1,0] row_mask:0xf bank_mask:0xf
	v_lshrrev_b32_e32 v134, 2, v132
	v_and_b32_e32 v134, 12, v134
	s_waitcnt lgkmcnt(0)
	v_max_f32_e32 v129, v129, v129
	v_max_f32_e32 v129, v128, v129
	v_xor_b32_e32 v128, 32, v133
	s_nop 0
	v_mov_b32_dpp v135, v129 row_ror:8 row_mask:0xf bank_mask:0xf
	v_lshl_or_b32 v128, s12, 6, v134
	v_lshlrev_b32_e32 v133, 2, v128
	v_lshlrev_b32_e32 v134, 10, v130
	s_mov_b64 s[2:3], exec
	s_and_b64 s[8:9], s[2:3], vcc
	v_mov_b32_e32 v182, v252
	s_mov_b64 exec, s[8:9]
	s_cbranch_execz .LBB0_3462
	s_waitcnt lgkmcnt(0)
	v_max_f32_e32 v135, v135, v135
	v_max_f32_e32 v129, v129, v129
	v_add3_u32 v136, v133, v134, s55
	v_max_f32_e32 v129, v129, v135
	ds_write_b32 v136, v129
.LBB0_3462:
	s_or_b64 exec, exec, s[2:3]
	v_max_f32_e32 v129, v121, v121
	s_waitcnt lgkmcnt(0)
	v_max_f32_e32 v135, v125, v125
	s_mov_b32 s2, -1
	v_max_f32_e32 v129, v135, v129
	v_max3_f32 v129, v129, v117, v113
	v_mbcnt_lo_u32_b32 v135, s2, 0
	v_mbcnt_hi_u32_b32 v135, s2, v135
	v_max3_f32 v129, v129, v109, v105
	v_lshlrev_b32_e32 v135, 2, v135
	v_max3_f32 v129, v129, v101, v97
	v_xor_b32_e32 v136, 4, v135
	s_nop 1
	v_mov_b32_dpp v136, v129 quad_perm:[1,0,3,2] row_mask:0xf bank_mask:0xf
	s_waitcnt lgkmcnt(0)
	v_max_f32_e32 v136, v136, v136
	v_max_f32_e32 v129, v129, v136
	v_xor_b32_e32 v136, 8, v135
	s_nop 1
	v_mov_b32_dpp v136, v129 quad_perm:[2,3,0,1] row_mask:0xf bank_mask:0xf
	s_waitcnt lgkmcnt(0)
	v_max_f32_e32 v136, v136, v136
	v_max_f32_e32 v129, v129, v136
	v_xor_b32_e32 v136, 16, v135
	s_nop 1
	v_mov_b32_dpp v136, v129 row_half_mirror row_mask:0xf bank_mask:0xf
	s_nop 1
	v_mov_b32_dpp v136, v136 quad_perm:[3,2,1,0] row_mask:0xf bank_mask:0xf
	v_xor_b32_e32 v135, 32, v135
	s_waitcnt lgkmcnt(0)
	v_max_f32_e32 v136, v136, v136
	v_max_f32_e32 v129, v129, v136
	s_nop 1
	v_mov_b32_dpp v135, v129 row_ror:8 row_mask:0xf bank_mask:0xf
	s_mov_b64 s[2:3], exec
	s_and_b64 s[8:9], s[2:3], vcc
	v_mov_b32_e32 v183, v216
	v_mov_b32_e32 v253, v217
	v_mov_b32_e32 v252, 0x3a720000
	s_mov_b64 exec, s[8:9]
	s_cbranch_execz .LBB0_3464
	s_waitcnt lgkmcnt(0)
	v_max_f32_e32 v135, v135, v135
	v_max_f32_e32 v129, v129, v129
	s_mov_b32 s8, 0x10004
	v_max_f32_e32 v129, v129, v135
	v_add3_u32 v135, v133, v134, s8
	ds_write_b32 v135, v129
.LBB0_3464:
	s_or_b64 exec, exec, s[2:3]
	v_max_f32_e32 v129, v122, v122
	s_waitcnt lgkmcnt(0)
	v_max_f32_e32 v135, v126, v126
	s_mov_b32 s2, -1
	v_max_f32_e32 v129, v135, v129
	v_max3_f32 v129, v129, v118, v114
	v_mbcnt_lo_u32_b32 v135, s2, 0
	v_mbcnt_hi_u32_b32 v135, s2, v135
	v_max3_f32 v129, v129, v110, v106
	v_lshlrev_b32_e32 v135, 2, v135
	v_max3_f32 v129, v129, v102, v98
	v_xor_b32_e32 v136, 4, v135
	s_nop 1
	v_mov_b32_dpp v136, v129 quad_perm:[1,0,3,2] row_mask:0xf bank_mask:0xf
	s_waitcnt lgkmcnt(0)
	v_max_f32_e32 v136, v136, v136
	v_max_f32_e32 v129, v129, v136
	v_xor_b32_e32 v136, 8, v135
	s_nop 1
	v_mov_b32_dpp v136, v129 quad_perm:[2,3,0,1] row_mask:0xf bank_mask:0xf
	s_waitcnt lgkmcnt(0)
	v_max_f32_e32 v136, v136, v136
	v_max_f32_e32 v129, v129, v136
	v_xor_b32_e32 v136, 16, v135
	s_nop 1
	v_mov_b32_dpp v136, v129 row_half_mirror row_mask:0xf bank_mask:0xf
	s_nop 1
	v_mov_b32_dpp v136, v136 quad_perm:[3,2,1,0] row_mask:0xf bank_mask:0xf
	v_xor_b32_e32 v135, 32, v135
	s_waitcnt lgkmcnt(0)
	v_max_f32_e32 v136, v136, v136
	v_max_f32_e32 v129, v129, v136
	s_nop 1
	v_mov_b32_dpp v135, v129 row_ror:8 row_mask:0xf bank_mask:0xf
	s_and_saveexec_b64 s[2:3], vcc
	s_cbranch_execz .LBB0_3466
	s_waitcnt lgkmcnt(0)
	v_max_f32_e32 v135, v135, v135
	v_max_f32_e32 v129, v129, v129
	s_mov_b32 s8, 0x10008
	v_max_f32_e32 v129, v129, v135
	v_add3_u32 v135, v133, v134, s8
	ds_write_b32 v135, v129
.LBB0_3466:
	s_or_b64 exec, exec, s[2:3]
	v_max_f32_e32 v129, v123, v123
	s_waitcnt lgkmcnt(0)
	v_max_f32_e32 v135, v127, v127
	s_mov_b32 s2, -1
	v_max_f32_e32 v129, v135, v129
	v_max3_f32 v129, v129, v119, v115
	v_mbcnt_lo_u32_b32 v135, s2, 0
	v_mbcnt_hi_u32_b32 v135, s2, v135
	v_max3_f32 v129, v129, v111, v107
	v_lshlrev_b32_e32 v135, 2, v135
	v_max3_f32 v129, v129, v103, v99
	v_xor_b32_e32 v136, 4, v135
	s_nop 1
	v_mov_b32_dpp v136, v129 quad_perm:[1,0,3,2] row_mask:0xf bank_mask:0xf
	s_waitcnt lgkmcnt(0)
	v_max_f32_e32 v136, v136, v136
	v_max_f32_e32 v129, v129, v136
	v_xor_b32_e32 v136, 8, v135
	s_nop 1
	v_mov_b32_dpp v136, v129 quad_perm:[2,3,0,1] row_mask:0xf bank_mask:0xf
	s_waitcnt lgkmcnt(0)
	v_max_f32_e32 v136, v136, v136
	v_max_f32_e32 v129, v129, v136
	v_xor_b32_e32 v136, 16, v135
	s_nop 1
	v_mov_b32_dpp v136, v129 row_half_mirror row_mask:0xf bank_mask:0xf
	s_nop 1
	v_mov_b32_dpp v136, v136 quad_perm:[3,2,1,0] row_mask:0xf bank_mask:0xf
	v_xor_b32_e32 v135, 32, v135
	s_waitcnt lgkmcnt(0)
	v_max_f32_e32 v136, v136, v136
	v_max_f32_e32 v129, v129, v136
	s_nop 1
	v_mov_b32_dpp v135, v129 row_ror:8 row_mask:0xf bank_mask:0xf
	s_and_saveexec_b64 s[2:3], vcc
	s_cbranch_execz .LBB0_3468
	s_waitcnt lgkmcnt(0)
	v_max_f32_e32 v135, v135, v135
	v_max_f32_e32 v129, v129, v129
	s_mov_b32 s8, 0x1000c
	v_max_f32_e32 v129, v129, v135
	v_add3_u32 v135, v133, v134, s8
	ds_write_b32 v135, v129
; DEVFI int lane_opaque() { unsigned m = ~0u; asm volatile("" : "+s"(m)); return (int)__builtin_amdgcn_mbcnt_hi(m, __builtin_amdgcn_mbcnt_lo(m, 0u)); }
; DEVFI float shx(float v, int mask, int lane) { return __int_as_float(__builtin_amdgcn_ds_bpermute((lane ^ mask) << 2, __float_as_int(v))); }
; #define SBAR() __builtin_amdgcn_sched_barrier(0)
; DEVFI float red16max(float v) {
;   const int ln = lane_opaque();
;   v = fmaxf(v, shx(v, 1, ln)); v = fmaxf(v, shx(v, 2, ln)); v = fmaxf(v, shx(v, 4, ln)); v = fmaxf(v, shx(v, 8, ln)); return v;
; }
; __global__ void __launch_bounds__(512) mega(Params p) {
;     ...
;             auto smax = [&](f32x4 (&a)[8], const int m) {
; #pragma unroll
;               for (int j = 0; j < 4; ++j) { float mx = a[0][j];
; #pragma unroll
;                 for (int n = 1; n < 8; ++n) mx = fmaxf(mx, a[n][j]);
;                 mx = red16max(mx);
;                 if (fr == 0) red[wcI * 256 + rb + m * 16 + j] = mx; }
;               SBAR(); };
;             smax(acc[0], 0); smax(acc[1], 1); smax(acc[2], 2); smax(acc[3], 3);
.LBB0_3468:
	s_or_b64 exec, exec, s[2:3]
	v_max_f32_e32 v129, v88, v88
	s_waitcnt lgkmcnt(0)
	v_max_f32_e32 v135, v92, v92
	s_mov_b32 s2, -1
	v_max_f32_e32 v129, v135, v129
	v_max3_f32 v129, v129, v84, v80
	v_mbcnt_lo_u32_b32 v135, s2, 0
	v_mbcnt_hi_u32_b32 v135, s2, v135
	v_max3_f32 v129, v129, v76, v72
	v_lshlrev_b32_e32 v135, 2, v135
	v_max3_f32 v129, v129, v68, v64
	v_xor_b32_e32 v136, 4, v135
	s_nop 1
	v_mov_b32_dpp v136, v129 quad_perm:[1,0,3,2] row_mask:0xf bank_mask:0xf
	s_waitcnt lgkmcnt(0)
	v_max_f32_e32 v136, v136, v136
	v_max_f32_e32 v129, v129, v136
	v_xor_b32_e32 v136, 8, v135
	s_nop 1
	v_mov_b32_dpp v136, v129 quad_perm:[2,3,0,1] row_mask:0xf bank_mask:0xf
	s_waitcnt lgkmcnt(0)
	v_max_f32_e32 v136, v136, v136
	v_max_f32_e32 v129, v129, v136
	v_xor_b32_e32 v136, 16, v135
	s_nop 1
	v_mov_b32_dpp v136, v129 row_half_mirror row_mask:0xf bank_mask:0xf
	s_nop 1
	v_mov_b32_dpp v136, v136 quad_perm:[3,2,1,0] row_mask:0xf bank_mask:0xf
	v_xor_b32_e32 v135, 32, v135
	s_waitcnt lgkmcnt(0)
	v_max_f32_e32 v136, v136, v136
	v_max_f32_e32 v129, v129, v136
	s_nop 1
	v_mov_b32_dpp v135, v129 row_ror:8 row_mask:0xf bank_mask:0xf
	s_and_saveexec_b64 s[2:3], vcc
	s_cbranch_execz .LBB0_3470
	s_waitcnt lgkmcnt(0)
	v_max_f32_e32 v135, v135, v135
	v_max_f32_e32 v129, v129, v129
	s_mov_b32 s8, 0x10040
	v_max_f32_e32 v129, v129, v135
	v_add3_u32 v135, v133, v134, s8
	ds_write_b32 v135, v129
.LBB0_3470:
	s_or_b64 exec, exec, s[2:3]
	v_max_f32_e32 v129, v89, v89
	s_waitcnt lgkmcnt(0)
	v_max_f32_e32 v135, v93, v93
	s_mov_b32 s2, -1
	v_max_f32_e32 v129, v135, v129
	v_max3_f32 v129, v129, v85, v81
	v_mbcnt_lo_u32_b32 v135, s2, 0
	v_mbcnt_hi_u32_b32 v135, s2, v135
	v_max3_f32 v129, v129, v77, v73
	v_lshlrev_b32_e32 v135, 2, v135
	v_max3_f32 v129, v129, v69, v65
	v_xor_b32_e32 v136, 4, v135
	s_nop 1
	v_mov_b32_dpp v136, v129 quad_perm:[1,0,3,2] row_mask:0xf bank_mask:0xf
	s_waitcnt lgkmcnt(0)
	v_max_f32_e32 v136, v136, v136
	v_max_f32_e32 v129, v129, v136
	v_xor_b32_e32 v136, 8, v135
	s_nop 1
	v_mov_b32_dpp v136, v129 quad_perm:[2,3,0,1] row_mask:0xf bank_mask:0xf
	s_waitcnt lgkmcnt(0)
	v_max_f32_e32 v136, v136, v136
	v_max_f32_e32 v129, v129, v136
	v_xor_b32_e32 v136, 16, v135
	s_nop 1
	v_mov_b32_dpp v136, v129 row_half_mirror row_mask:0xf bank_mask:0xf
	s_nop 1
	v_mov_b32_dpp v136, v136 quad_perm:[3,2,1,0] row_mask:0xf bank_mask:0xf
	v_xor_b32_e32 v135, 32, v135
	s_waitcnt lgkmcnt(0)
	v_max_f32_e32 v136, v136, v136
	v_max_f32_e32 v129, v129, v136
	s_nop 1
	v_mov_b32_dpp v135, v129 row_ror:8 row_mask:0xf bank_mask:0xf
	s_and_saveexec_b64 s[2:3], vcc
	s_cbranch_execz .LBB0_3472
	s_waitcnt lgkmcnt(0)
	v_max_f32_e32 v135, v135, v135
	v_max_f32_e32 v129, v129, v129
	s_mov_b32 s8, 0x10044
	v_max_f32_e32 v129, v129, v135
	v_add3_u32 v135, v133, v134, s8
	ds_write_b32 v135, v129
.LBB0_3472:
	s_or_b64 exec, exec, s[2:3]
	v_max_f32_e32 v129, v90, v90
	s_waitcnt lgkmcnt(0)
	v_max_f32_e32 v135, v94, v94
	s_mov_b32 s2, -1
	v_max_f32_e32 v129, v135, v129
	v_max3_f32 v129, v129, v86, v82
	v_mbcnt_lo_u32_b32 v135, s2, 0
	v_mbcnt_hi_u32_b32 v135, s2, v135
	v_max3_f32 v129, v129, v78, v74
	v_lshlrev_b32_e32 v135, 2, v135
	v_max3_f32 v129, v129, v70, v66
	v_xor_b32_e32 v136, 4, v135
	s_nop 1
	v_mov_b32_dpp v136, v129 quad_perm:[1,0,3,2] row_mask:0xf bank_mask:0xf
	s_waitcnt lgkmcnt(0)
	v_max_f32_e32 v136, v136, v136
	v_max_f32_e32 v129, v129, v136
	v_xor_b32_e32 v136, 8, v135
	s_nop 1
	v_mov_b32_dpp v136, v129 quad_perm:[2,3,0,1] row_mask:0xf bank_mask:0xf
	s_waitcnt lgkmcnt(0)
	v_max_f32_e32 v136, v136, v136
	v_max_f32_e32 v129, v129, v136
	v_xor_b32_e32 v136, 16, v135
	s_nop 1
	v_mov_b32_dpp v136, v129 row_half_mirror row_mask:0xf bank_mask:0xf
	s_nop 1
	v_mov_b32_dpp v136, v136 quad_perm:[3,2,1,0] row_mask:0xf bank_mask:0xf
	v_xor_b32_e32 v135, 32, v135
	s_waitcnt lgkmcnt(0)
	v_max_f32_e32 v136, v136, v136
	v_max_f32_e32 v129, v129, v136
	s_nop 1
	v_mov_b32_dpp v135, v129 row_ror:8 row_mask:0xf bank_mask:0xf
	s_and_saveexec_b64 s[2:3], vcc
	s_cbranch_execz .LBB0_3474
	s_waitcnt lgkmcnt(0)
	v_max_f32_e32 v135, v135, v135
	v_max_f32_e32 v129, v129, v129
	s_mov_b32 s8, 0x10048
	v_max_f32_e32 v129, v129, v135
	v_add3_u32 v135, v133, v134, s8
	ds_write_b32 v135, v129
.LBB0_3474:
	s_or_b64 exec, exec, s[2:3]
	v_max_f32_e32 v129, v91, v91
	s_waitcnt lgkmcnt(0)
	v_max_f32_e32 v135, v95, v95
	s_mov_b32 s2, -1
	v_max_f32_e32 v129, v135, v129
	v_max3_f32 v129, v129, v87, v83
	v_mbcnt_lo_u32_b32 v135, s2, 0
	v_mbcnt_hi_u32_b32 v135, s2, v135
	v_max3_f32 v129, v129, v79, v75
	v_lshlrev_b32_e32 v135, 2, v135
	v_max3_f32 v129, v129, v71, v67
	v_xor_b32_e32 v136, 4, v135
	s_nop 1
	v_mov_b32_dpp v136, v129 quad_perm:[1,0,3,2] row_mask:0xf bank_mask:0xf
	s_waitcnt lgkmcnt(0)
	v_max_f32_e32 v136, v136, v136
	v_max_f32_e32 v129, v129, v136
	v_xor_b32_e32 v136, 8, v135
	s_nop 1
	v_mov_b32_dpp v136, v129 quad_perm:[2,3,0,1] row_mask:0xf bank_mask:0xf
	s_waitcnt lgkmcnt(0)
	v_max_f32_e32 v136, v136, v136
	v_max_f32_e32 v129, v129, v136
	v_xor_b32_e32 v136, 16, v135
	s_nop 1
	v_mov_b32_dpp v136, v129 row_half_mirror row_mask:0xf bank_mask:0xf
	s_nop 1
	v_mov_b32_dpp v136, v136 quad_perm:[3,2,1,0] row_mask:0xf bank_mask:0xf
	v_xor_b32_e32 v135, 32, v135
	s_waitcnt lgkmcnt(0)
	v_max_f32_e32 v136, v136, v136
	v_max_f32_e32 v129, v129, v136
	s_nop 1
	v_mov_b32_dpp v135, v129 row_ror:8 row_mask:0xf bank_mask:0xf
	s_and_saveexec_b64 s[2:3], vcc
	s_cbranch_execz .LBB0_3476
	s_waitcnt lgkmcnt(0)
	v_max_f32_e32 v135, v135, v135
	v_max_f32_e32 v129, v129, v129
	s_mov_b32 s8, 0x1004c
	v_max_f32_e32 v129, v129, v135
	v_add3_u32 v135, v133, v134, s8
	ds_write_b32 v135, v129
; DEVFI int lane_opaque() { unsigned m = ~0u; asm volatile("" : "+s"(m)); return (int)__builtin_amdgcn_mbcnt_hi(m, __builtin_amdgcn_mbcnt_lo(m, 0u)); }
; DEVFI float shx(float v, int mask, int lane) { return __int_as_float(__builtin_amdgcn_ds_bpermute((lane ^ mask) << 2, __float_as_int(v))); }
; #define SBAR() __builtin_amdgcn_sched_barrier(0)
; DEVFI float red16max(float v) {
;   const int ln = lane_opaque();
;   v = fmaxf(v, shx(v, 1, ln)); v = fmaxf(v, shx(v, 2, ln)); v = fmaxf(v, shx(v, 4, ln)); v = fmaxf(v, shx(v, 8, ln)); return v;
; }
; __global__ void __launch_bounds__(512) mega(Params p) {
;     ...
;             auto smax = [&](f32x4 (&a)[8], const int m) {
; #pragma unroll
;               for (int j = 0; j < 4; ++j) { float mx = a[0][j];
; #pragma unroll
;                 for (int n = 1; n < 8; ++n) mx = fmaxf(mx, a[n][j]);
;                 mx = red16max(mx);
;                 if (fr == 0) red[wcI * 256 + rb + m * 16 + j] = mx; }
;               SBAR(); };
;             smax(acc[0], 0); smax(acc[1], 1); smax(acc[2], 2); smax(acc[3], 3);
.LBB0_3476:
	s_or_b64 exec, exec, s[2:3]
	v_max_f32_e32 v129, v56, v56
	s_waitcnt lgkmcnt(0)
	v_max_f32_e32 v135, v60, v60
	s_mov_b32 s2, -1
	v_max_f32_e32 v129, v135, v129
	v_max3_f32 v129, v129, v52, v48
	v_mbcnt_lo_u32_b32 v135, s2, 0
	v_mbcnt_hi_u32_b32 v135, s2, v135
	v_max3_f32 v129, v129, v44, v40
	v_lshlrev_b32_e32 v135, 2, v135
	v_max3_f32 v129, v129, v36, v32
	v_xor_b32_e32 v136, 4, v135
	s_nop 1
	v_mov_b32_dpp v136, v129 quad_perm:[1,0,3,2] row_mask:0xf bank_mask:0xf
	s_waitcnt lgkmcnt(0)
	v_max_f32_e32 v136, v136, v136
	v_max_f32_e32 v129, v129, v136
	v_xor_b32_e32 v136, 8, v135
	s_nop 1
	v_mov_b32_dpp v136, v129 quad_perm:[2,3,0,1] row_mask:0xf bank_mask:0xf
	s_waitcnt lgkmcnt(0)
	v_max_f32_e32 v136, v136, v136
	v_max_f32_e32 v129, v129, v136
	v_xor_b32_e32 v136, 16, v135
	s_nop 1
	v_mov_b32_dpp v136, v129 row_half_mirror row_mask:0xf bank_mask:0xf
	s_nop 1
	v_mov_b32_dpp v136, v136 quad_perm:[3,2,1,0] row_mask:0xf bank_mask:0xf
	v_xor_b32_e32 v135, 32, v135
	s_waitcnt lgkmcnt(0)
	v_max_f32_e32 v136, v136, v136
	v_max_f32_e32 v129, v129, v136
	s_nop 1
	v_mov_b32_dpp v135, v129 row_ror:8 row_mask:0xf bank_mask:0xf
	s_and_saveexec_b64 s[2:3], vcc
	s_cbranch_execz .LBB0_3478
	s_waitcnt lgkmcnt(0)
	v_max_f32_e32 v135, v135, v135
	v_max_f32_e32 v129, v129, v129
	s_mov_b32 s8, 0x10080
	v_max_f32_e32 v129, v129, v135
	v_add3_u32 v135, v133, v134, s8
	ds_write_b32 v135, v129
.LBB0_3478:
	s_or_b64 exec, exec, s[2:3]
	v_max_f32_e32 v129, v57, v57
	s_waitcnt lgkmcnt(0)
	v_max_f32_e32 v135, v61, v61
	s_mov_b32 s2, -1
	v_max_f32_e32 v129, v135, v129
	v_max3_f32 v129, v129, v53, v49
	v_mbcnt_lo_u32_b32 v135, s2, 0
	v_mbcnt_hi_u32_b32 v135, s2, v135
	v_max3_f32 v129, v129, v45, v41
	v_lshlrev_b32_e32 v135, 2, v135
	v_max3_f32 v129, v129, v37, v33
	v_xor_b32_e32 v136, 4, v135
	s_nop 1
	v_mov_b32_dpp v136, v129 quad_perm:[1,0,3,2] row_mask:0xf bank_mask:0xf
	s_waitcnt lgkmcnt(0)
	v_max_f32_e32 v136, v136, v136
	v_max_f32_e32 v129, v129, v136
	v_xor_b32_e32 v136, 8, v135
	s_nop 1
	v_mov_b32_dpp v136, v129 quad_perm:[2,3,0,1] row_mask:0xf bank_mask:0xf
	s_waitcnt lgkmcnt(0)
	v_max_f32_e32 v136, v136, v136
	v_max_f32_e32 v129, v129, v136
	v_xor_b32_e32 v136, 16, v135
	s_nop 1
	v_mov_b32_dpp v136, v129 row_half_mirror row_mask:0xf bank_mask:0xf
	s_nop 1
	v_mov_b32_dpp v136, v136 quad_perm:[3,2,1,0] row_mask:0xf bank_mask:0xf
	v_xor_b32_e32 v135, 32, v135
	s_waitcnt lgkmcnt(0)
	v_max_f32_e32 v136, v136, v136
	v_max_f32_e32 v129, v129, v136
	s_nop 1
	v_mov_b32_dpp v135, v129 row_ror:8 row_mask:0xf bank_mask:0xf
	s_and_saveexec_b64 s[2:3], vcc
	s_cbranch_execz .LBB0_3480
	s_waitcnt lgkmcnt(0)
	v_max_f32_e32 v135, v135, v135
	v_max_f32_e32 v129, v129, v129
	s_mov_b32 s8, 0x10084
	v_max_f32_e32 v129, v129, v135
	v_add3_u32 v135, v133, v134, s8
	ds_write_b32 v135, v129
.LBB0_3480:
	s_or_b64 exec, exec, s[2:3]
	v_max_f32_e32 v129, v58, v58
	s_waitcnt lgkmcnt(0)
	v_max_f32_e32 v135, v62, v62
	s_mov_b32 s2, -1
	v_max_f32_e32 v129, v135, v129
	v_max3_f32 v129, v129, v54, v50
	v_mbcnt_lo_u32_b32 v135, s2, 0
	v_mbcnt_hi_u32_b32 v135, s2, v135
	v_max3_f32 v129, v129, v46, v42
	v_lshlrev_b32_e32 v135, 2, v135
	v_max3_f32 v129, v129, v38, v34
	v_xor_b32_e32 v136, 4, v135
	s_nop 1
	v_mov_b32_dpp v136, v129 quad_perm:[1,0,3,2] row_mask:0xf bank_mask:0xf
	s_waitcnt lgkmcnt(0)
	v_max_f32_e32 v136, v136, v136
	v_max_f32_e32 v129, v129, v136
	v_xor_b32_e32 v136, 8, v135
	s_nop 1
	v_mov_b32_dpp v136, v129 quad_perm:[2,3,0,1] row_mask:0xf bank_mask:0xf
	s_waitcnt lgkmcnt(0)
	v_max_f32_e32 v136, v136, v136
	v_max_f32_e32 v129, v129, v136
	v_xor_b32_e32 v136, 16, v135
	s_nop 1
	v_mov_b32_dpp v136, v129 row_half_mirror row_mask:0xf bank_mask:0xf
	s_nop 1
	v_mov_b32_dpp v136, v136 quad_perm:[3,2,1,0] row_mask:0xf bank_mask:0xf
	v_xor_b32_e32 v135, 32, v135
	s_waitcnt lgkmcnt(0)
	v_max_f32_e32 v136, v136, v136
	v_max_f32_e32 v129, v129, v136
	s_nop 1
	v_mov_b32_dpp v135, v129 row_ror:8 row_mask:0xf bank_mask:0xf
	s_and_saveexec_b64 s[2:3], vcc
	s_cbranch_execz .LBB0_3482
	s_waitcnt lgkmcnt(0)
	v_max_f32_e32 v135, v135, v135
	v_max_f32_e32 v129, v129, v129
	s_mov_b32 s8, 0x10088
	v_max_f32_e32 v129, v129, v135
	v_add3_u32 v135, v133, v134, s8
	ds_write_b32 v135, v129
.LBB0_3482:
	s_or_b64 exec, exec, s[2:3]
	v_max_f32_e32 v129, v59, v59
	s_waitcnt lgkmcnt(0)
	v_max_f32_e32 v135, v63, v63
	s_mov_b32 s2, -1
	v_max_f32_e32 v129, v135, v129
	v_max3_f32 v129, v129, v55, v51
	v_mbcnt_lo_u32_b32 v135, s2, 0
	v_mbcnt_hi_u32_b32 v135, s2, v135
	v_max3_f32 v129, v129, v47, v43
	v_lshlrev_b32_e32 v135, 2, v135
	v_max3_f32 v129, v129, v39, v35
	v_xor_b32_e32 v136, 4, v135
	s_nop 1
	v_mov_b32_dpp v136, v129 quad_perm:[1,0,3,2] row_mask:0xf bank_mask:0xf
	s_waitcnt lgkmcnt(0)
	v_max_f32_e32 v136, v136, v136
	v_max_f32_e32 v129, v129, v136
	v_xor_b32_e32 v136, 8, v135
	s_nop 1
	v_mov_b32_dpp v136, v129 quad_perm:[2,3,0,1] row_mask:0xf bank_mask:0xf
	s_waitcnt lgkmcnt(0)
	v_max_f32_e32 v136, v136, v136
	v_max_f32_e32 v129, v129, v136
	v_xor_b32_e32 v136, 16, v135
	s_nop 1
	v_mov_b32_dpp v136, v129 row_half_mirror row_mask:0xf bank_mask:0xf
	s_nop 1
	v_mov_b32_dpp v136, v136 quad_perm:[3,2,1,0] row_mask:0xf bank_mask:0xf
	v_xor_b32_e32 v135, 32, v135
	s_waitcnt lgkmcnt(0)
	v_max_f32_e32 v136, v136, v136
	v_max_f32_e32 v129, v129, v136
	s_nop 1
	v_mov_b32_dpp v135, v129 row_ror:8 row_mask:0xf bank_mask:0xf
	s_and_saveexec_b64 s[2:3], vcc
	s_cbranch_execz .LBB0_3484
	s_waitcnt lgkmcnt(0)
	v_max_f32_e32 v135, v135, v135
	v_max_f32_e32 v129, v129, v129
	s_mov_b32 s8, 0x1008c
	v_max_f32_e32 v129, v129, v135
	v_add3_u32 v135, v133, v134, s8
	ds_write_b32 v135, v129
; DEVFI int lane_opaque() { unsigned m = ~0u; asm volatile("" : "+s"(m)); return (int)__builtin_amdgcn_mbcnt_hi(m, __builtin_amdgcn_mbcnt_lo(m, 0u)); }
; DEVFI float shx(float v, int mask, int lane) { return __int_as_float(__builtin_amdgcn_ds_bpermute((lane ^ mask) << 2, __float_as_int(v))); }
; #define SBAR() __builtin_amdgcn_sched_barrier(0)
; DEVFI float red16max(float v) {
;   const int ln = lane_opaque();
;   v = fmaxf(v, shx(v, 1, ln)); v = fmaxf(v, shx(v, 2, ln)); v = fmaxf(v, shx(v, 4, ln)); v = fmaxf(v, shx(v, 8, ln)); return v;
; }
; __global__ void __launch_bounds__(512) mega(Params p) {
;     ...
;             auto smax = [&](f32x4 (&a)[8], const int m) {
; #pragma unroll
;               for (int j = 0; j < 4; ++j) { float mx = a[0][j];
; #pragma unroll
;                 for (int n = 1; n < 8; ++n) mx = fmaxf(mx, a[n][j]);
;                 mx = red16max(mx);
;                 if (fr == 0) red[wcI * 256 + rb + m * 16 + j] = mx; }
;               SBAR(); };
;             smax(acc[0], 0); smax(acc[1], 1); smax(acc[2], 2); smax(acc[3], 3);
.LBB0_3484:
	s_or_b64 exec, exec, s[2:3]
	v_max_f32_e32 v129, v24, v24
	s_waitcnt lgkmcnt(0)
	v_max_f32_e32 v135, v28, v28
	s_mov_b32 s2, -1
	v_max_f32_e32 v129, v135, v129
	v_max3_f32 v129, v129, v20, v16
	v_mbcnt_lo_u32_b32 v135, s2, 0
	v_mbcnt_hi_u32_b32 v135, s2, v135
	v_max3_f32 v129, v129, v12, v8
	v_lshlrev_b32_e32 v135, 2, v135
	v_max3_f32 v129, v129, v4, v0
	v_xor_b32_e32 v136, 4, v135
	s_nop 1
	v_mov_b32_dpp v136, v129 quad_perm:[1,0,3,2] row_mask:0xf bank_mask:0xf
	s_waitcnt lgkmcnt(0)
	v_max_f32_e32 v136, v136, v136
	v_max_f32_e32 v129, v129, v136
	v_xor_b32_e32 v136, 8, v135
	s_nop 1
	v_mov_b32_dpp v136, v129 quad_perm:[2,3,0,1] row_mask:0xf bank_mask:0xf
	s_waitcnt lgkmcnt(0)
	v_max_f32_e32 v136, v136, v136
	v_max_f32_e32 v129, v129, v136
	v_xor_b32_e32 v136, 16, v135
	s_nop 1
	v_mov_b32_dpp v136, v129 row_half_mirror row_mask:0xf bank_mask:0xf
	s_nop 1
	v_mov_b32_dpp v136, v136 quad_perm:[3,2,1,0] row_mask:0xf bank_mask:0xf
	v_xor_b32_e32 v135, 32, v135
	s_waitcnt lgkmcnt(0)
	v_max_f32_e32 v136, v136, v136
	v_max_f32_e32 v129, v129, v136
	s_nop 1
	v_mov_b32_dpp v135, v129 row_ror:8 row_mask:0xf bank_mask:0xf
	s_and_saveexec_b64 s[2:3], vcc
	s_cbranch_execz .LBB0_3486
	s_waitcnt lgkmcnt(0)
	v_max_f32_e32 v135, v135, v135
	v_max_f32_e32 v129, v129, v129
	s_mov_b32 s8, 0x100c0
	v_max_f32_e32 v129, v129, v135
	v_add3_u32 v135, v133, v134, s8
	ds_write_b32 v135, v129
.LBB0_3486:
	s_or_b64 exec, exec, s[2:3]
	v_max_f32_e32 v129, v25, v25
	s_waitcnt lgkmcnt(0)
	v_max_f32_e32 v135, v29, v29
	s_mov_b32 s2, -1
	v_max_f32_e32 v129, v135, v129
	v_max3_f32 v129, v129, v21, v17
	v_mbcnt_lo_u32_b32 v135, s2, 0
	v_mbcnt_hi_u32_b32 v135, s2, v135
	v_max3_f32 v129, v129, v13, v9
	v_lshlrev_b32_e32 v135, 2, v135
	v_max3_f32 v129, v129, v5, v1
	v_xor_b32_e32 v136, 4, v135
	s_nop 1
	v_mov_b32_dpp v136, v129 quad_perm:[1,0,3,2] row_mask:0xf bank_mask:0xf
	s_waitcnt lgkmcnt(0)
	v_max_f32_e32 v136, v136, v136
	v_max_f32_e32 v129, v129, v136
	v_xor_b32_e32 v136, 8, v135
	s_nop 1
	v_mov_b32_dpp v136, v129 quad_perm:[2,3,0,1] row_mask:0xf bank_mask:0xf
	s_waitcnt lgkmcnt(0)
	v_max_f32_e32 v136, v136, v136
	v_max_f32_e32 v129, v129, v136
	v_xor_b32_e32 v136, 16, v135
	s_nop 1
	v_mov_b32_dpp v136, v129 row_half_mirror row_mask:0xf bank_mask:0xf
	s_nop 1
	v_mov_b32_dpp v136, v136 quad_perm:[3,2,1,0] row_mask:0xf bank_mask:0xf
	v_xor_b32_e32 v135, 32, v135
	s_waitcnt lgkmcnt(0)
	v_max_f32_e32 v136, v136, v136
	v_max_f32_e32 v129, v129, v136
	s_nop 1
	v_mov_b32_dpp v135, v129 row_ror:8 row_mask:0xf bank_mask:0xf
	s_and_saveexec_b64 s[2:3], vcc
	s_cbranch_execz .LBB0_3488
	s_waitcnt lgkmcnt(0)
	v_max_f32_e32 v135, v135, v135
	v_max_f32_e32 v129, v129, v129
	s_mov_b32 s8, 0x100c4
	v_max_f32_e32 v129, v129, v135
	v_add3_u32 v135, v133, v134, s8
	ds_write_b32 v135, v129
.LBB0_3488:
	s_or_b64 exec, exec, s[2:3]
	v_max_f32_e32 v129, v26, v26
	s_waitcnt lgkmcnt(0)
	v_max_f32_e32 v135, v30, v30
	s_mov_b32 s2, -1
	v_max_f32_e32 v129, v135, v129
	v_max3_f32 v129, v129, v22, v18
	v_mbcnt_lo_u32_b32 v135, s2, 0
	v_mbcnt_hi_u32_b32 v135, s2, v135
	v_max3_f32 v129, v129, v14, v10
	v_lshlrev_b32_e32 v135, 2, v135
	v_max3_f32 v129, v129, v6, v2
	v_xor_b32_e32 v136, 4, v135
	s_nop 1
	v_mov_b32_dpp v136, v129 quad_perm:[1,0,3,2] row_mask:0xf bank_mask:0xf
	s_waitcnt lgkmcnt(0)
	v_max_f32_e32 v136, v136, v136
	v_max_f32_e32 v129, v129, v136
	v_xor_b32_e32 v136, 8, v135
	s_nop 1
	v_mov_b32_dpp v136, v129 quad_perm:[2,3,0,1] row_mask:0xf bank_mask:0xf
	s_waitcnt lgkmcnt(0)
	v_max_f32_e32 v136, v136, v136
	v_max_f32_e32 v129, v129, v136
	v_xor_b32_e32 v136, 16, v135
	s_nop 1
	v_mov_b32_dpp v136, v129 row_half_mirror row_mask:0xf bank_mask:0xf
	s_nop 1
	v_mov_b32_dpp v136, v136 quad_perm:[3,2,1,0] row_mask:0xf bank_mask:0xf
	v_xor_b32_e32 v135, 32, v135
	s_waitcnt lgkmcnt(0)
	v_max_f32_e32 v136, v136, v136
	v_max_f32_e32 v129, v129, v136
	s_nop 1
	v_mov_b32_dpp v135, v129 row_ror:8 row_mask:0xf bank_mask:0xf
	s_and_saveexec_b64 s[2:3], vcc
	s_cbranch_execz .LBB0_3490
	s_waitcnt lgkmcnt(0)
	v_max_f32_e32 v135, v135, v135
	v_max_f32_e32 v129, v129, v129
	s_mov_b32 s8, 0x100c8
	v_max_f32_e32 v129, v129, v135
	v_add3_u32 v135, v133, v134, s8
	ds_write_b32 v135, v129
.LBB0_3490:
	s_or_b64 exec, exec, s[2:3]
	v_max_f32_e32 v129, v27, v27
	s_waitcnt lgkmcnt(0)
	v_max_f32_e32 v135, v31, v31
	s_mov_b32 s2, -1
	v_max_f32_e32 v129, v135, v129
	v_max3_f32 v129, v129, v23, v19
	v_mbcnt_lo_u32_b32 v135, s2, 0
	v_mbcnt_hi_u32_b32 v135, s2, v135
	v_max3_f32 v129, v129, v15, v11
	v_lshlrev_b32_e32 v135, 2, v135
	v_max3_f32 v129, v129, v7, v3
	v_xor_b32_e32 v136, 4, v135
	s_nop 1
	v_mov_b32_dpp v136, v129 quad_perm:[1,0,3,2] row_mask:0xf bank_mask:0xf
	s_waitcnt lgkmcnt(0)
	v_max_f32_e32 v136, v136, v136
	v_max_f32_e32 v129, v129, v136
	v_xor_b32_e32 v136, 8, v135
	s_nop 1
	v_mov_b32_dpp v136, v129 quad_perm:[2,3,0,1] row_mask:0xf bank_mask:0xf
	s_waitcnt lgkmcnt(0)
	v_max_f32_e32 v136, v136, v136
	v_max_f32_e32 v129, v129, v136
	v_xor_b32_e32 v136, 16, v135
	s_nop 1
	v_mov_b32_dpp v136, v129 row_half_mirror row_mask:0xf bank_mask:0xf
	s_nop 1
	v_mov_b32_dpp v136, v136 quad_perm:[3,2,1,0] row_mask:0xf bank_mask:0xf
	v_xor_b32_e32 v135, 32, v135
	s_waitcnt lgkmcnt(0)
	v_max_f32_e32 v136, v136, v136
	v_max_f32_e32 v129, v129, v136
	s_nop 1
	v_mov_b32_dpp v135, v129 row_ror:8 row_mask:0xf bank_mask:0xf
	s_and_saveexec_b64 s[2:3], vcc
	s_cbranch_execz .LBB0_3492
	s_waitcnt lgkmcnt(0)
	v_max_f32_e32 v135, v135, v135
	v_max_f32_e32 v129, v129, v129
	s_mov_b32 s8, 0x100cc
	v_max_f32_e32 v129, v129, v135
	v_add3_u32 v135, v133, v134, s8
	ds_write_b32 v135, v129
; DEVFI int lane_opaque() { unsigned m = ~0u; asm volatile("" : "+s"(m)); return (int)__builtin_amdgcn_mbcnt_hi(m, __builtin_amdgcn_mbcnt_lo(m, 0u)); }
; DEVFI float shx(float v, int mask, int lane) { return __int_as_float(__builtin_amdgcn_ds_bpermute((lane ^ mask) << 2, __float_as_int(v))); }
; #define SBAR() __builtin_amdgcn_sched_barrier(0)
; DEVFI float red16(float v) {
;   const int ln = lane_opaque();
;   v += shx(v, 1, ln); v += shx(v, 2, ln); v += shx(v, 4, ln); v += shx(v, 8, ln); return v;
; }
; __global__ void __launch_bounds__(512) mega(Params p) {
;     ...
;             __syncthreads();
;             auto sexp = [&](f32x4 (&a)[8], const int m) {
; #pragma unroll
;               for (int j = 0; j < 4; ++j) { const int rr = rb + m * 16 + j; const float gm = fmaxf(red[rr], red[256 + rr]); float sm = 0;
; #pragma unroll
;                 for (int n = 0; n < 8; ++n) { const float e = __expf((a[n][j] - gm) * 0.0625f); a[n][j] = e; sm += e; }
;                 sm = red16(sm);
;                 if (fr == 0) red[512 + wcI * 256 + rr] = sm; }
;               SBAR(); };
;             sexp(acc[0], 0); sexp(acc[1], 1); sexp(acc[2], 2); sexp(acc[3], 3);
.LBB0_3492:
	s_or_b64 exec, exec, s[2:3]
	v_lshl_add_u32 v129, v128, 2, v182
	s_waitcnt vmcnt(0) lgkmcnt(0)
	s_barrier
	ds_read2st64_b32 v[136:137], v129 offset1:4
	s_mov_b32 s2, -1
	s_waitcnt lgkmcnt(0)
	v_max_f32_e32 v135, v137, v137
	v_max_f32_e32 v136, v136, v136
	v_max_f32_e32 v135, v136, v135
	v_sub_f32_e32 v124, v124, v135
	v_mul_f32_e32 v124, 0x3d800000, v124
	v_sub_f32_e32 v120, v120, v135
	v_mul_f32_e32 v124, 0x3fb8aa3b, v124
	v_mul_f32_e32 v120, 0x3d800000, v120
	v_sub_f32_e32 v116, v116, v135
	v_exp_f32_e32 v155, v124
	v_mul_f32_e32 v120, 0x3fb8aa3b, v120
	v_mul_f32_e32 v116, 0x3d800000, v116
	v_sub_f32_e32 v112, v112, v135
	v_exp_f32_e32 v156, v120
	v_mul_f32_e32 v116, 0x3fb8aa3b, v116
	v_mul_f32_e32 v112, 0x3d800000, v112
	v_sub_f32_e32 v108, v108, v135
	v_exp_f32_e32 v153, v116
	v_mul_f32_e32 v112, 0x3fb8aa3b, v112
	v_mul_f32_e32 v108, 0x3d800000, v108
	v_sub_f32_e32 v104, v104, v135
	v_exp_f32_e32 v154, v112
	v_mul_f32_e32 v108, 0x3fb8aa3b, v108
	v_mul_f32_e32 v104, 0x3d800000, v104
	v_sub_f32_e32 v100, v100, v135
	v_add_f32_e32 v112, 0, v155
	v_exp_f32_e32 v151, v108
	v_mul_f32_e32 v104, 0x3fb8aa3b, v104
	v_mul_f32_e32 v100, 0x3d800000, v100
	v_sub_f32_e32 v96, v96, v135
	v_add_f32_e32 v112, v156, v112
	v_exp_f32_e32 v152, v104
	v_mul_f32_e32 v100, 0x3fb8aa3b, v100
	v_mul_f32_e32 v96, 0x3d800000, v96
	v_add_f32_e32 v112, v153, v112
	v_exp_f32_e32 v149, v100
	v_mul_f32_e32 v96, 0x3fb8aa3b, v96
	v_add_f32_e32 v112, v154, v112
	v_exp_f32_e32 v150, v96
	v_add_f32_e32 v96, v151, v112
	v_mbcnt_lo_u32_b32 v100, s2, 0
	v_add_f32_e32 v96, v152, v96
	v_mbcnt_hi_u32_b32 v100, s2, v100
	v_add_f32_e32 v96, v149, v96
	v_lshlrev_b32_e32 v100, 2, v100
	v_add_f32_e32 v96, v150, v96
	v_xor_b32_e32 v104, 4, v100
	s_nop 1
	v_mov_b32_dpp v104, v96 quad_perm:[1,0,3,2] row_mask:0xf bank_mask:0xf
	s_waitcnt lgkmcnt(0)
	v_add_f32_e32 v96, v96, v104
	v_xor_b32_e32 v104, 8, v100
	s_nop 1
	v_mov_b32_dpp v104, v96 quad_perm:[2,3,0,1] row_mask:0xf bank_mask:0xf
	s_waitcnt lgkmcnt(0)
	v_add_f32_e32 v96, v96, v104
	v_xor_b32_e32 v104, 16, v100
	s_nop 1
	v_mov_b32_dpp v104, v96 row_half_mirror row_mask:0xf bank_mask:0xf
	s_nop 1
	v_mov_b32_dpp v104, v104 quad_perm:[3,2,1,0] row_mask:0xf bank_mask:0xf
	v_xor_b32_e32 v100, 32, v100
	s_waitcnt lgkmcnt(0)
	v_add_f32_e32 v96, v96, v104
	s_nop 1
	v_mov_b32_dpp v100, v96 row_ror:8 row_mask:0xf bank_mask:0xf
	s_and_saveexec_b64 s[2:3], vcc
	s_cbranch_execz .LBB0_3494
	s_mov_b32 s8, 0x10800
	v_add3_u32 v104, v133, v134, s8
	s_waitcnt lgkmcnt(0)
	v_add_f32_e32 v96, v96, v100
	ds_write_b32 v104, v96
.LBB0_3494:
	s_or_b64 exec, exec, s[2:3]
	v_add_u32_e32 v96, 4, v129
	ds_read2st64_b32 v[136:137], v96 offset1:4
	s_mov_b32 s2, -1
	s_waitcnt lgkmcnt(0)
	v_max_f32_e32 v96, v137, v137
	v_max_f32_e32 v100, v136, v136
	v_max_f32_e32 v96, v100, v96
	v_sub_f32_e32 v100, v125, v96
	v_mul_f32_e32 v100, 0x3d800000, v100
	v_sub_f32_e32 v104, v121, v96
	v_mul_f32_e32 v100, 0x3fb8aa3b, v100
	v_mul_f32_e32 v104, 0x3d800000, v104
	v_exp_f32_e32 v147, v100
	v_sub_f32_e32 v100, v117, v96
	v_mul_f32_e32 v104, 0x3fb8aa3b, v104
	v_mul_f32_e32 v100, 0x3d800000, v100
	v_exp_f32_e32 v148, v104
	v_mul_f32_e32 v100, 0x3fb8aa3b, v100
	v_sub_f32_e32 v104, v109, v96
	v_exp_f32_e32 v145, v100
	v_sub_f32_e32 v100, v113, v96
	v_mul_f32_e32 v104, 0x3d800000, v104
	v_mul_f32_e32 v100, 0x3d800000, v100
	v_mul_f32_e32 v104, 0x3fb8aa3b, v104
	v_mul_f32_e32 v100, 0x3fb8aa3b, v100
	v_exp_f32_e32 v143, v104
	v_sub_f32_e32 v104, v105, v96
	v_exp_f32_e32 v146, v100
	v_mul_f32_e32 v104, 0x3d800000, v104
	v_sub_f32_e32 v101, v101, v96
	v_add_f32_e32 v100, 0, v147
	v_mul_f32_e32 v104, 0x3fb8aa3b, v104
	v_mul_f32_e32 v101, 0x3d800000, v101
	v_sub_f32_e32 v96, v97, v96
	v_add_f32_e32 v100, v148, v100
	v_exp_f32_e32 v144, v104
	v_mul_f32_e32 v101, 0x3fb8aa3b, v101
	v_mul_f32_e32 v96, 0x3d800000, v96
	v_add_f32_e32 v100, v145, v100
	v_exp_f32_e32 v141, v101
	v_mul_f32_e32 v96, 0x3fb8aa3b, v96
	v_add_f32_e32 v100, v146, v100
	v_exp_f32_e32 v142, v96
	v_add_f32_e32 v96, v143, v100
	v_mbcnt_lo_u32_b32 v97, s2, 0
	v_add_f32_e32 v96, v144, v96
	v_mbcnt_hi_u32_b32 v97, s2, v97
	v_add_f32_e32 v96, v141, v96
	v_lshlrev_b32_e32 v97, 2, v97
	v_add_f32_e32 v96, v142, v96
	v_xor_b32_e32 v100, 4, v97
	s_nop 1
	v_mov_b32_dpp v100, v96 quad_perm:[1,0,3,2] row_mask:0xf bank_mask:0xf
	s_waitcnt lgkmcnt(0)
	v_add_f32_e32 v96, v96, v100
	v_xor_b32_e32 v100, 8, v97
	s_nop 1
	v_mov_b32_dpp v100, v96 quad_perm:[2,3,0,1] row_mask:0xf bank_mask:0xf
	s_waitcnt lgkmcnt(0)
	v_add_f32_e32 v96, v96, v100
	v_xor_b32_e32 v100, 16, v97
	s_nop 1
	v_mov_b32_dpp v100, v96 row_half_mirror row_mask:0xf bank_mask:0xf
	s_nop 1
	v_mov_b32_dpp v100, v100 quad_perm:[3,2,1,0] row_mask:0xf bank_mask:0xf
	v_xor_b32_e32 v97, 32, v97
	s_waitcnt lgkmcnt(0)
	v_add_f32_e32 v96, v96, v100
	s_nop 1
	v_mov_b32_dpp v97, v96 row_ror:8 row_mask:0xf bank_mask:0xf
	s_and_saveexec_b64 s[2:3], vcc
	s_cbranch_execz .LBB0_3496
	s_mov_b32 s8, 0x10804
	v_add3_u32 v100, v133, v134, s8
	s_waitcnt lgkmcnt(0)
	v_add_f32_e32 v96, v96, v97
	ds_write_b32 v100, v96
; DEVFI int lane_opaque() { unsigned m = ~0u; asm volatile("" : "+s"(m)); return (int)__builtin_amdgcn_mbcnt_hi(m, __builtin_amdgcn_mbcnt_lo(m, 0u)); }
; DEVFI float shx(float v, int mask, int lane) { return __int_as_float(__builtin_amdgcn_ds_bpermute((lane ^ mask) << 2, __float_as_int(v))); }
; #define SBAR() __builtin_amdgcn_sched_barrier(0)
; DEVFI float red16(float v) {
;   const int ln = lane_opaque();
;   v += shx(v, 1, ln); v += shx(v, 2, ln); v += shx(v, 4, ln); v += shx(v, 8, ln); return v;
; }
; __global__ void __launch_bounds__(512) mega(Params p) {
;     ...
;             auto sexp = [&](f32x4 (&a)[8], const int m) {
; #pragma unroll
;               for (int j = 0; j < 4; ++j) { const int rr = rb + m * 16 + j; const float gm = fmaxf(red[rr], red[256 + rr]); float sm = 0;
; #pragma unroll
;                 for (int n = 0; n < 8; ++n) { const float e = __expf((a[n][j] - gm) * 0.0625f); a[n][j] = e; sm += e; }
;                 sm = red16(sm);
;                 if (fr == 0) red[512 + wcI * 256 + rr] = sm; }
;               SBAR(); };
;             sexp(acc[0], 0); sexp(acc[1], 1); sexp(acc[2], 2); sexp(acc[3], 3);
.LBB0_3496:
	s_or_b64 exec, exec, s[2:3]
	v_add_u32_e32 v96, 8, v129
	s_waitcnt lgkmcnt(0)
	ds_read2st64_b32 v[96:97], v96 offset1:4
	s_mov_b32 s2, -1
	s_waitcnt lgkmcnt(0)
	v_max_f32_e32 v97, v97, v97
	v_max_f32_e32 v96, v96, v96
	v_max_f32_e32 v96, v96, v97
	v_sub_f32_e32 v97, v126, v96
	v_sub_f32_e32 v100, v122, v96
	v_mul_f32_e32 v97, 0x3d800000, v97
	v_mul_f32_e32 v100, 0x3d800000, v100
	v_mul_f32_e32 v97, 0x3fb8aa3b, v97
	v_mul_f32_e32 v100, 0x3fb8aa3b, v100
	v_exp_f32_e32 v139, v97
	v_exp_f32_e32 v140, v100
	v_sub_f32_e32 v97, v118, v96
	v_sub_f32_e32 v100, v110, v96
	v_mul_f32_e32 v97, 0x3d800000, v97
	v_mul_f32_e32 v100, 0x3d800000, v100
	v_mul_f32_e32 v97, 0x3fb8aa3b, v97
	v_mul_f32_e32 v100, 0x3fb8aa3b, v100
	v_exp_f32_e32 v137, v97
	v_sub_f32_e32 v97, v114, v96
	v_exp_f32_e32 v135, v100
	v_sub_f32_e32 v100, v106, v96
	v_mul_f32_e32 v97, 0x3d800000, v97
	v_mul_f32_e32 v100, 0x3d800000, v100
	v_mul_f32_e32 v97, 0x3fb8aa3b, v97
	v_mul_f32_e32 v100, 0x3fb8aa3b, v100
	v_exp_f32_e32 v138, v97
	v_exp_f32_e32 v136, v100
	v_sub_f32_e32 v100, v102, v96
	v_add_f32_e32 v97, 0, v139
	v_mul_f32_e32 v100, 0x3d800000, v100
	v_sub_f32_e32 v96, v98, v96
	v_add_f32_e32 v97, v140, v97
	v_mul_f32_e32 v100, 0x3fb8aa3b, v100
	v_mul_f32_e32 v96, 0x3d800000, v96
	v_add_f32_e32 v97, v137, v97
	v_exp_f32_e32 v125, v100
	v_mul_f32_e32 v96, 0x3fb8aa3b, v96
	v_add_f32_e32 v97, v138, v97
	v_exp_f32_e32 v126, v96
	v_add_f32_e32 v96, v135, v97
	v_mbcnt_lo_u32_b32 v97, s2, 0
	v_add_f32_e32 v96, v136, v96
	v_mbcnt_hi_u32_b32 v97, s2, v97
	v_add_f32_e32 v96, v125, v96
	v_lshlrev_b32_e32 v97, 2, v97
	v_add_f32_e32 v96, v126, v96
	v_xor_b32_e32 v98, 4, v97
	s_nop 1
	v_mov_b32_dpp v98, v96 quad_perm:[1,0,3,2] row_mask:0xf bank_mask:0xf
	s_waitcnt lgkmcnt(0)
	v_add_f32_e32 v96, v96, v98
	v_xor_b32_e32 v98, 8, v97
	s_nop 1
	v_mov_b32_dpp v98, v96 quad_perm:[2,3,0,1] row_mask:0xf bank_mask:0xf
	s_waitcnt lgkmcnt(0)
	v_add_f32_e32 v96, v96, v98
	v_xor_b32_e32 v98, 16, v97
	s_nop 1
	v_mov_b32_dpp v98, v96 row_half_mirror row_mask:0xf bank_mask:0xf
	s_nop 1
	v_mov_b32_dpp v98, v98 quad_perm:[3,2,1,0] row_mask:0xf bank_mask:0xf
	v_xor_b32_e32 v97, 32, v97
	s_waitcnt lgkmcnt(0)
	v_add_f32_e32 v96, v96, v98
	s_nop 1
	v_mov_b32_dpp v97, v96 row_ror:8 row_mask:0xf bank_mask:0xf
	s_and_saveexec_b64 s[2:3], vcc
	s_cbranch_execz .LBB0_3498
	s_mov_b32 s8, 0x10808
	v_add3_u32 v98, v133, v134, s8
	s_waitcnt lgkmcnt(0)
	v_add_f32_e32 v96, v96, v97
	ds_write_b32 v98, v96
.LBB0_3498:
	s_or_b64 exec, exec, s[2:3]
	v_add_u32_e32 v96, 12, v129
	s_waitcnt lgkmcnt(0)
	ds_read2st64_b32 v[96:97], v96 offset1:4
	s_mov_b32 s2, -1
	s_waitcnt lgkmcnt(0)
	v_max_f32_e32 v97, v97, v97
	v_max_f32_e32 v96, v96, v96
	v_max_f32_e32 v96, v96, v97
	v_sub_f32_e32 v97, v127, v96
	v_sub_f32_e32 v98, v123, v96
	v_mul_f32_e32 v97, 0x3d800000, v97
	v_mul_f32_e32 v98, 0x3d800000, v98
	v_mul_f32_e32 v97, 0x3fb8aa3b, v97
	v_mul_f32_e32 v98, 0x3fb8aa3b, v98
	v_exp_f32_e32 v123, v97
	v_exp_f32_e32 v124, v98
	v_sub_f32_e32 v97, v119, v96
	v_sub_f32_e32 v98, v111, v96
	v_mul_f32_e32 v97, 0x3d800000, v97
	v_mul_f32_e32 v98, 0x3d800000, v98
	v_mul_f32_e32 v97, 0x3fb8aa3b, v97
	v_mul_f32_e32 v98, 0x3fb8aa3b, v98
	v_exp_f32_e32 v121, v97
	v_sub_f32_e32 v97, v115, v96
	v_exp_f32_e32 v119, v98
	v_sub_f32_e32 v98, v107, v96
	v_mul_f32_e32 v97, 0x3d800000, v97
	v_mul_f32_e32 v98, 0x3d800000, v98
	v_mul_f32_e32 v97, 0x3fb8aa3b, v97
	v_mul_f32_e32 v98, 0x3fb8aa3b, v98
	v_exp_f32_e32 v122, v97
	v_exp_f32_e32 v120, v98
	v_sub_f32_e32 v98, v103, v96
	v_add_f32_e32 v97, 0, v123
	v_mul_f32_e32 v98, 0x3d800000, v98
	v_sub_f32_e32 v96, v99, v96
	v_add_f32_e32 v97, v124, v97
	v_mul_f32_e32 v98, 0x3fb8aa3b, v98
	v_mul_f32_e32 v96, 0x3d800000, v96
	v_add_f32_e32 v97, v121, v97
	v_exp_f32_e32 v117, v98
	v_mul_f32_e32 v96, 0x3fb8aa3b, v96
	v_add_f32_e32 v97, v122, v97
	v_exp_f32_e32 v118, v96
	v_add_f32_e32 v96, v119, v97
	v_mbcnt_lo_u32_b32 v97, s2, 0
	v_add_f32_e32 v96, v120, v96
	v_mbcnt_hi_u32_b32 v97, s2, v97
	v_add_f32_e32 v96, v117, v96
	v_lshlrev_b32_e32 v97, 2, v97
	v_add_f32_e32 v96, v118, v96
	v_xor_b32_e32 v98, 4, v97
	s_nop 1
	v_mov_b32_dpp v98, v96 quad_perm:[1,0,3,2] row_mask:0xf bank_mask:0xf
	s_waitcnt lgkmcnt(0)
	v_add_f32_e32 v96, v96, v98
	v_xor_b32_e32 v98, 8, v97
	s_nop 1
	v_mov_b32_dpp v98, v96 quad_perm:[2,3,0,1] row_mask:0xf bank_mask:0xf
	s_waitcnt lgkmcnt(0)
	v_add_f32_e32 v96, v96, v98
	v_xor_b32_e32 v98, 16, v97
	s_nop 1
	v_mov_b32_dpp v98, v96 row_half_mirror row_mask:0xf bank_mask:0xf
	s_nop 1
	v_mov_b32_dpp v98, v98 quad_perm:[3,2,1,0] row_mask:0xf bank_mask:0xf
	v_xor_b32_e32 v97, 32, v97
	s_waitcnt lgkmcnt(0)
	v_add_f32_e32 v96, v96, v98
	s_nop 1
	v_mov_b32_dpp v97, v96 row_ror:8 row_mask:0xf bank_mask:0xf
	s_and_saveexec_b64 s[2:3], vcc
	s_cbranch_execz .LBB0_3500
	s_mov_b32 s8, 0x1080c
	v_add3_u32 v98, v133, v134, s8
	s_waitcnt lgkmcnt(0)
	v_add_f32_e32 v96, v96, v97
	ds_write_b32 v98, v96
; DEVFI int lane_opaque() { unsigned m = ~0u; asm volatile("" : "+s"(m)); return (int)__builtin_amdgcn_mbcnt_hi(m, __builtin_amdgcn_mbcnt_lo(m, 0u)); }
; DEVFI float shx(float v, int mask, int lane) { return __int_as_float(__builtin_amdgcn_ds_bpermute((lane ^ mask) << 2, __float_as_int(v))); }
; #define SBAR() __builtin_amdgcn_sched_barrier(0)
; DEVFI float red16(float v) {
;   const int ln = lane_opaque();
;   v += shx(v, 1, ln); v += shx(v, 2, ln); v += shx(v, 4, ln); v += shx(v, 8, ln); return v;
; }
; __global__ void __launch_bounds__(512) mega(Params p) {
;     ...
;             auto sexp = [&](f32x4 (&a)[8], const int m) {
; #pragma unroll
;               for (int j = 0; j < 4; ++j) { const int rr = rb + m * 16 + j; const float gm = fmaxf(red[rr], red[256 + rr]); float sm = 0;
; #pragma unroll
;                 for (int n = 0; n < 8; ++n) { const float e = __expf((a[n][j] - gm) * 0.0625f); a[n][j] = e; sm += e; }
;                 sm = red16(sm);
;                 if (fr == 0) red[512 + wcI * 256 + rr] = sm; }
;               SBAR(); };
;             sexp(acc[0], 0); sexp(acc[1], 1); sexp(acc[2], 2); sexp(acc[3], 3);
.LBB0_3500:
	s_or_b64 exec, exec, s[2:3]
	v_add_u32_e32 v96, 64, v129
	s_waitcnt lgkmcnt(0)
	ds_read2st64_b32 v[96:97], v96 offset1:4
	s_mov_b32 s2, -1
	s_waitcnt lgkmcnt(0)
	v_max_f32_e32 v97, v97, v97
	v_max_f32_e32 v96, v96, v96
	v_max_f32_e32 v96, v96, v97
	v_sub_f32_e32 v92, v92, v96
	v_sub_f32_e32 v88, v88, v96
	v_mul_f32_e32 v92, 0x3d800000, v92
	v_mul_f32_e32 v88, 0x3d800000, v88
	v_mul_f32_e32 v92, 0x3fb8aa3b, v92
	v_sub_f32_e32 v84, v84, v96
	v_mul_f32_e32 v88, 0x3fb8aa3b, v88
	v_exp_f32_e32 v115, v92
	v_mul_f32_e32 v84, 0x3d800000, v84
	v_sub_f32_e32 v80, v80, v96
	v_exp_f32_e32 v116, v88
	v_mul_f32_e32 v84, 0x3fb8aa3b, v84
	v_mul_f32_e32 v80, 0x3d800000, v80
	v_sub_f32_e32 v76, v76, v96
	v_exp_f32_e32 v113, v84
	v_mul_f32_e32 v80, 0x3fb8aa3b, v80
	v_mul_f32_e32 v76, 0x3d800000, v76
	v_sub_f32_e32 v72, v72, v96
	v_exp_f32_e32 v114, v80
	v_mul_f32_e32 v76, 0x3fb8aa3b, v76
	v_mul_f32_e32 v72, 0x3d800000, v72
	v_sub_f32_e32 v68, v68, v96
	v_add_f32_e32 v80, 0, v115
	v_exp_f32_e32 v111, v76
	v_mul_f32_e32 v72, 0x3fb8aa3b, v72
	v_mul_f32_e32 v68, 0x3d800000, v68
	v_sub_f32_e32 v64, v64, v96
	v_add_f32_e32 v80, v116, v80
	v_exp_f32_e32 v112, v72
	v_mul_f32_e32 v68, 0x3fb8aa3b, v68
	v_mul_f32_e32 v64, 0x3d800000, v64
	v_add_f32_e32 v80, v113, v80
	v_exp_f32_e32 v109, v68
	v_mul_f32_e32 v64, 0x3fb8aa3b, v64
	v_add_f32_e32 v80, v114, v80
	v_exp_f32_e32 v110, v64
	v_add_f32_e32 v64, v111, v80
	v_mbcnt_lo_u32_b32 v68, s2, 0
	v_add_f32_e32 v64, v112, v64
	v_mbcnt_hi_u32_b32 v68, s2, v68
	v_add_f32_e32 v64, v109, v64
	v_lshlrev_b32_e32 v68, 2, v68
	v_add_f32_e32 v64, v110, v64
	v_xor_b32_e32 v72, 4, v68
	s_nop 1
	v_mov_b32_dpp v72, v64 quad_perm:[1,0,3,2] row_mask:0xf bank_mask:0xf
	s_waitcnt lgkmcnt(0)
	v_add_f32_e32 v64, v64, v72
	v_xor_b32_e32 v72, 8, v68
	s_nop 1
	v_mov_b32_dpp v72, v64 quad_perm:[2,3,0,1] row_mask:0xf bank_mask:0xf
	s_waitcnt lgkmcnt(0)
	v_add_f32_e32 v64, v64, v72
	v_xor_b32_e32 v72, 16, v68
	s_nop 1
	v_mov_b32_dpp v72, v64 row_half_mirror row_mask:0xf bank_mask:0xf
	s_nop 1
	v_mov_b32_dpp v72, v72 quad_perm:[3,2,1,0] row_mask:0xf bank_mask:0xf
	v_xor_b32_e32 v68, 32, v68
	s_waitcnt lgkmcnt(0)
	v_add_f32_e32 v64, v64, v72
	s_nop 1
	v_mov_b32_dpp v68, v64 row_ror:8 row_mask:0xf bank_mask:0xf
	s_and_saveexec_b64 s[2:3], vcc
	s_cbranch_execz .LBB0_3502
	s_mov_b32 s8, 0x10840
	v_add3_u32 v72, v133, v134, s8
	s_waitcnt lgkmcnt(0)
	v_add_f32_e32 v64, v64, v68
	ds_write_b32 v72, v64
.LBB0_3502:
	s_or_b64 exec, exec, s[2:3]
	v_add_u32_e32 v64, 0x44, v129
	ds_read2st64_b32 v[96:97], v64 offset1:4
	s_mov_b32 s2, -1
	s_waitcnt lgkmcnt(0)
	v_max_f32_e32 v64, v97, v97
	v_max_f32_e32 v68, v96, v96
	v_max_f32_e32 v64, v68, v64
	v_sub_f32_e32 v68, v93, v64
	v_mul_f32_e32 v68, 0x3d800000, v68
	v_sub_f32_e32 v72, v89, v64
	v_mul_f32_e32 v68, 0x3fb8aa3b, v68
	v_mul_f32_e32 v72, 0x3d800000, v72
	v_exp_f32_e32 v107, v68
	v_sub_f32_e32 v68, v85, v64
	v_mul_f32_e32 v72, 0x3fb8aa3b, v72
	v_mul_f32_e32 v68, 0x3d800000, v68
	v_exp_f32_e32 v108, v72
	v_mul_f32_e32 v68, 0x3fb8aa3b, v68
	v_sub_f32_e32 v72, v77, v64
	v_exp_f32_e32 v105, v68
	v_sub_f32_e32 v68, v81, v64
	v_mul_f32_e32 v72, 0x3d800000, v72
	v_mul_f32_e32 v68, 0x3d800000, v68
	v_mul_f32_e32 v72, 0x3fb8aa3b, v72
	v_mul_f32_e32 v68, 0x3fb8aa3b, v68
	v_exp_f32_e32 v103, v72
	v_sub_f32_e32 v72, v73, v64
	v_exp_f32_e32 v106, v68
	v_mul_f32_e32 v72, 0x3d800000, v72
	v_sub_f32_e32 v69, v69, v64
	v_add_f32_e32 v68, 0, v107
	v_mul_f32_e32 v72, 0x3fb8aa3b, v72
	v_mul_f32_e32 v69, 0x3d800000, v69
	v_sub_f32_e32 v64, v65, v64
	v_add_f32_e32 v68, v108, v68
	v_exp_f32_e32 v104, v72
	v_mul_f32_e32 v69, 0x3fb8aa3b, v69
	v_mul_f32_e32 v64, 0x3d800000, v64
	v_add_f32_e32 v68, v105, v68
	v_exp_f32_e32 v101, v69
	v_mul_f32_e32 v64, 0x3fb8aa3b, v64
	v_add_f32_e32 v68, v106, v68
	v_exp_f32_e32 v102, v64
	v_add_f32_e32 v64, v103, v68
	v_mbcnt_lo_u32_b32 v65, s2, 0
	v_add_f32_e32 v64, v104, v64
	v_mbcnt_hi_u32_b32 v65, s2, v65
	v_add_f32_e32 v64, v101, v64
	v_lshlrev_b32_e32 v65, 2, v65
	v_add_f32_e32 v64, v102, v64
	v_xor_b32_e32 v68, 4, v65
	s_nop 1
	v_mov_b32_dpp v68, v64 quad_perm:[1,0,3,2] row_mask:0xf bank_mask:0xf
	s_waitcnt lgkmcnt(0)
	v_add_f32_e32 v64, v64, v68
	v_xor_b32_e32 v68, 8, v65
	s_nop 1
	v_mov_b32_dpp v68, v64 quad_perm:[2,3,0,1] row_mask:0xf bank_mask:0xf
	s_waitcnt lgkmcnt(0)
	v_add_f32_e32 v64, v64, v68
	v_xor_b32_e32 v68, 16, v65
	s_nop 1
	v_mov_b32_dpp v68, v64 row_half_mirror row_mask:0xf bank_mask:0xf
	s_nop 1
	v_mov_b32_dpp v68, v68 quad_perm:[3,2,1,0] row_mask:0xf bank_mask:0xf
	v_xor_b32_e32 v65, 32, v65
	s_waitcnt lgkmcnt(0)
	v_add_f32_e32 v64, v64, v68
	s_nop 1
	v_mov_b32_dpp v65, v64 row_ror:8 row_mask:0xf bank_mask:0xf
	s_and_saveexec_b64 s[2:3], vcc
	s_cbranch_execz .LBB0_3504
	s_mov_b32 s8, 0x10844
	v_add3_u32 v68, v133, v134, s8
	s_waitcnt lgkmcnt(0)
	v_add_f32_e32 v64, v64, v65
	ds_write_b32 v68, v64
; DEVFI int lane_opaque() { unsigned m = ~0u; asm volatile("" : "+s"(m)); return (int)__builtin_amdgcn_mbcnt_hi(m, __builtin_amdgcn_mbcnt_lo(m, 0u)); }
; DEVFI float shx(float v, int mask, int lane) { return __int_as_float(__builtin_amdgcn_ds_bpermute((lane ^ mask) << 2, __float_as_int(v))); }
; #define SBAR() __builtin_amdgcn_sched_barrier(0)
; DEVFI float red16(float v) {
;   const int ln = lane_opaque();
;   v += shx(v, 1, ln); v += shx(v, 2, ln); v += shx(v, 4, ln); v += shx(v, 8, ln); return v;
; }
; __global__ void __launch_bounds__(512) mega(Params p) {
;     ...
;             auto sexp = [&](f32x4 (&a)[8], const int m) {
; #pragma unroll
;               for (int j = 0; j < 4; ++j) { const int rr = rb + m * 16 + j; const float gm = fmaxf(red[rr], red[256 + rr]); float sm = 0;
; #pragma unroll
;                 for (int n = 0; n < 8; ++n) { const float e = __expf((a[n][j] - gm) * 0.0625f); a[n][j] = e; sm += e; }
;                 sm = red16(sm);
;                 if (fr == 0) red[512 + wcI * 256 + rr] = sm; }
;               SBAR(); };
;             sexp(acc[0], 0); sexp(acc[1], 1); sexp(acc[2], 2); sexp(acc[3], 3);
.LBB0_3504:
	s_or_b64 exec, exec, s[2:3]
	v_add_u32_e32 v64, 0x48, v129
	s_waitcnt lgkmcnt(0)
	ds_read2st64_b32 v[64:65], v64 offset1:4
	s_mov_b32 s2, -1
	s_waitcnt lgkmcnt(0)
	v_max_f32_e32 v65, v65, v65
	v_max_f32_e32 v64, v64, v64
	v_max_f32_e32 v64, v64, v65
	v_sub_f32_e32 v65, v94, v64
	v_sub_f32_e32 v68, v90, v64
	v_mul_f32_e32 v65, 0x3d800000, v65
	v_mul_f32_e32 v68, 0x3d800000, v68
	v_mul_f32_e32 v65, 0x3fb8aa3b, v65
	v_mul_f32_e32 v68, 0x3fb8aa3b, v68
	v_exp_f32_e32 v99, v65
	v_exp_f32_e32 v100, v68
	v_sub_f32_e32 v65, v86, v64
	v_sub_f32_e32 v68, v78, v64
	v_mul_f32_e32 v65, 0x3d800000, v65
	v_mul_f32_e32 v68, 0x3d800000, v68
	v_mul_f32_e32 v65, 0x3fb8aa3b, v65
	v_mul_f32_e32 v68, 0x3fb8aa3b, v68
	v_exp_f32_e32 v97, v65
	v_sub_f32_e32 v65, v82, v64
	v_exp_f32_e32 v94, v68
	v_sub_f32_e32 v68, v74, v64
	v_mul_f32_e32 v65, 0x3d800000, v65
	v_mul_f32_e32 v68, 0x3d800000, v68
	v_mul_f32_e32 v65, 0x3fb8aa3b, v65
	v_mul_f32_e32 v68, 0x3fb8aa3b, v68
	v_exp_f32_e32 v98, v65
	v_exp_f32_e32 v96, v68
	v_sub_f32_e32 v68, v70, v64
	v_add_f32_e32 v65, 0, v99
	v_mul_f32_e32 v68, 0x3d800000, v68
	v_sub_f32_e32 v64, v66, v64
	v_add_f32_e32 v65, v100, v65
	v_mul_f32_e32 v68, 0x3fb8aa3b, v68
	v_mul_f32_e32 v64, 0x3d800000, v64
	v_add_f32_e32 v65, v97, v65
	v_exp_f32_e32 v92, v68
	v_mul_f32_e32 v64, 0x3fb8aa3b, v64
	v_add_f32_e32 v65, v98, v65
	v_exp_f32_e32 v93, v64
	v_add_f32_e32 v64, v94, v65
	v_mbcnt_lo_u32_b32 v65, s2, 0
	v_add_f32_e32 v64, v96, v64
	v_mbcnt_hi_u32_b32 v65, s2, v65
	v_add_f32_e32 v64, v92, v64
	v_lshlrev_b32_e32 v65, 2, v65
	v_add_f32_e32 v64, v93, v64
	v_xor_b32_e32 v66, 4, v65
	s_nop 1
	v_mov_b32_dpp v66, v64 quad_perm:[1,0,3,2] row_mask:0xf bank_mask:0xf
	s_waitcnt lgkmcnt(0)
	v_add_f32_e32 v64, v64, v66
	v_xor_b32_e32 v66, 8, v65
	s_nop 1
	v_mov_b32_dpp v66, v64 quad_perm:[2,3,0,1] row_mask:0xf bank_mask:0xf
	s_waitcnt lgkmcnt(0)
	v_add_f32_e32 v64, v64, v66
	v_xor_b32_e32 v66, 16, v65
	s_nop 1
	v_mov_b32_dpp v66, v64 row_half_mirror row_mask:0xf bank_mask:0xf
	s_nop 1
	v_mov_b32_dpp v66, v66 quad_perm:[3,2,1,0] row_mask:0xf bank_mask:0xf
	v_xor_b32_e32 v65, 32, v65
	s_waitcnt lgkmcnt(0)
	v_add_f32_e32 v64, v64, v66
	s_nop 1
	v_mov_b32_dpp v65, v64 row_ror:8 row_mask:0xf bank_mask:0xf
	s_and_saveexec_b64 s[2:3], vcc
	s_cbranch_execz .LBB0_3506
	s_mov_b32 s8, 0x10848
	v_add3_u32 v66, v133, v134, s8
	s_waitcnt lgkmcnt(0)
	v_add_f32_e32 v64, v64, v65
	ds_write_b32 v66, v64
.LBB0_3506:
	s_or_b64 exec, exec, s[2:3]
	v_add_u32_e32 v64, 0x4c, v129
	s_waitcnt lgkmcnt(0)
	ds_read2st64_b32 v[64:65], v64 offset1:4
	s_mov_b32 s2, -1
	s_waitcnt lgkmcnt(0)
	v_max_f32_e32 v65, v65, v65
	v_max_f32_e32 v64, v64, v64
	v_max_f32_e32 v64, v64, v65
	v_sub_f32_e32 v65, v95, v64
	v_sub_f32_e32 v66, v91, v64
	v_mul_f32_e32 v65, 0x3d800000, v65
	v_mul_f32_e32 v66, 0x3d800000, v66
	v_mul_f32_e32 v65, 0x3fb8aa3b, v65
	v_mul_f32_e32 v66, 0x3fb8aa3b, v66
	v_exp_f32_e32 v89, v65
	v_exp_f32_e32 v90, v66
	v_sub_f32_e32 v65, v87, v64
	v_sub_f32_e32 v66, v79, v64
	v_mul_f32_e32 v65, 0x3d800000, v65
	v_mul_f32_e32 v66, 0x3d800000, v66
	v_mul_f32_e32 v65, 0x3fb8aa3b, v65
	v_mul_f32_e32 v66, 0x3fb8aa3b, v66
	v_exp_f32_e32 v87, v65
	v_sub_f32_e32 v65, v83, v64
	v_exp_f32_e32 v85, v66
	v_sub_f32_e32 v66, v75, v64
	v_mul_f32_e32 v65, 0x3d800000, v65
	v_mul_f32_e32 v66, 0x3d800000, v66
	v_mul_f32_e32 v65, 0x3fb8aa3b, v65
	v_mul_f32_e32 v66, 0x3fb8aa3b, v66
	v_exp_f32_e32 v88, v65
	v_exp_f32_e32 v86, v66
	v_sub_f32_e32 v66, v71, v64
	v_add_f32_e32 v65, 0, v89
	v_mul_f32_e32 v66, 0x3d800000, v66
	v_sub_f32_e32 v64, v67, v64
	v_add_f32_e32 v65, v90, v65
	v_mul_f32_e32 v66, 0x3fb8aa3b, v66
	v_mul_f32_e32 v64, 0x3d800000, v64
	v_add_f32_e32 v65, v87, v65
	v_exp_f32_e32 v83, v66
	v_mul_f32_e32 v64, 0x3fb8aa3b, v64
	v_add_f32_e32 v65, v88, v65
	v_exp_f32_e32 v84, v64
	v_add_f32_e32 v64, v85, v65
	v_mbcnt_lo_u32_b32 v65, s2, 0
	v_add_f32_e32 v64, v86, v64
	v_mbcnt_hi_u32_b32 v65, s2, v65
	v_add_f32_e32 v64, v83, v64
	v_lshlrev_b32_e32 v65, 2, v65
	v_add_f32_e32 v64, v84, v64
	v_xor_b32_e32 v66, 4, v65
	s_nop 1
	v_mov_b32_dpp v66, v64 quad_perm:[1,0,3,2] row_mask:0xf bank_mask:0xf
	s_waitcnt lgkmcnt(0)
	v_add_f32_e32 v64, v64, v66
	v_xor_b32_e32 v66, 8, v65
	s_nop 1
	v_mov_b32_dpp v66, v64 quad_perm:[2,3,0,1] row_mask:0xf bank_mask:0xf
	s_waitcnt lgkmcnt(0)
	v_add_f32_e32 v64, v64, v66
	v_xor_b32_e32 v66, 16, v65
	s_nop 1
	v_mov_b32_dpp v66, v64 row_half_mirror row_mask:0xf bank_mask:0xf
	s_nop 1
	v_mov_b32_dpp v66, v66 quad_perm:[3,2,1,0] row_mask:0xf bank_mask:0xf
	v_xor_b32_e32 v65, 32, v65
	s_waitcnt lgkmcnt(0)
	v_add_f32_e32 v64, v64, v66
	s_nop 1
	v_mov_b32_dpp v65, v64 row_ror:8 row_mask:0xf bank_mask:0xf
	s_and_saveexec_b64 s[2:3], vcc
	s_cbranch_execz .LBB0_3508
	s_mov_b32 s8, 0x1084c
	v_add3_u32 v66, v133, v134, s8
	s_waitcnt lgkmcnt(0)
	v_add_f32_e32 v64, v64, v65
	ds_write_b32 v66, v64
; DEVFI int lane_opaque() { unsigned m = ~0u; asm volatile("" : "+s"(m)); return (int)__builtin_amdgcn_mbcnt_hi(m, __builtin_amdgcn_mbcnt_lo(m, 0u)); }
; DEVFI float shx(float v, int mask, int lane) { return __int_as_float(__builtin_amdgcn_ds_bpermute((lane ^ mask) << 2, __float_as_int(v))); }
; #define SBAR() __builtin_amdgcn_sched_barrier(0)
; DEVFI float red16(float v) {
;   const int ln = lane_opaque();
;   v += shx(v, 1, ln); v += shx(v, 2, ln); v += shx(v, 4, ln); v += shx(v, 8, ln); return v;
; }
; __global__ void __launch_bounds__(512) mega(Params p) {
;     ...
;             auto sexp = [&](f32x4 (&a)[8], const int m) {
; #pragma unroll
;               for (int j = 0; j < 4; ++j) { const int rr = rb + m * 16 + j; const float gm = fmaxf(red[rr], red[256 + rr]); float sm = 0;
; #pragma unroll
;                 for (int n = 0; n < 8; ++n) { const float e = __expf((a[n][j] - gm) * 0.0625f); a[n][j] = e; sm += e; }
;                 sm = red16(sm);
;                 if (fr == 0) red[512 + wcI * 256 + rr] = sm; }
;               SBAR(); };
;             sexp(acc[0], 0); sexp(acc[1], 1); sexp(acc[2], 2); sexp(acc[3], 3);
.LBB0_3508:
	s_or_b64 exec, exec, s[2:3]
	v_add_u32_e32 v64, 0x80, v129
	s_waitcnt lgkmcnt(0)
	ds_read2st64_b32 v[64:65], v64 offset1:4
	s_mov_b32 s2, -1
	s_waitcnt lgkmcnt(0)
	v_max_f32_e32 v65, v65, v65
	v_max_f32_e32 v64, v64, v64
	v_max_f32_e32 v64, v64, v65
	v_sub_f32_e32 v60, v60, v64
	v_sub_f32_e32 v56, v56, v64
	v_mul_f32_e32 v60, 0x3d800000, v60
	v_mul_f32_e32 v56, 0x3d800000, v56
	v_mul_f32_e32 v60, 0x3fb8aa3b, v60
	v_sub_f32_e32 v52, v52, v64
	v_mul_f32_e32 v56, 0x3fb8aa3b, v56
	v_exp_f32_e32 v81, v60
	v_mul_f32_e32 v52, 0x3d800000, v52
	v_sub_f32_e32 v48, v48, v64
	v_exp_f32_e32 v82, v56
	v_mul_f32_e32 v52, 0x3fb8aa3b, v52
	v_mul_f32_e32 v48, 0x3d800000, v48
	v_sub_f32_e32 v44, v44, v64
	v_exp_f32_e32 v79, v52
	v_mul_f32_e32 v48, 0x3fb8aa3b, v48
	v_mul_f32_e32 v44, 0x3d800000, v44
	v_sub_f32_e32 v40, v40, v64
	v_exp_f32_e32 v80, v48
	v_mul_f32_e32 v44, 0x3fb8aa3b, v44
	v_mul_f32_e32 v40, 0x3d800000, v40
	v_sub_f32_e32 v36, v36, v64
	v_add_f32_e32 v48, 0, v81
	v_exp_f32_e32 v77, v44
	v_mul_f32_e32 v40, 0x3fb8aa3b, v40
	v_mul_f32_e32 v36, 0x3d800000, v36
	v_sub_f32_e32 v32, v32, v64
	v_add_f32_e32 v48, v82, v48
	v_exp_f32_e32 v78, v40
	v_mul_f32_e32 v36, 0x3fb8aa3b, v36
	v_mul_f32_e32 v32, 0x3d800000, v32
	v_add_f32_e32 v48, v79, v48
	v_exp_f32_e32 v75, v36
	v_mul_f32_e32 v32, 0x3fb8aa3b, v32
	v_add_f32_e32 v48, v80, v48
	v_exp_f32_e32 v76, v32
	v_add_f32_e32 v32, v77, v48
	v_mbcnt_lo_u32_b32 v36, s2, 0
	v_add_f32_e32 v32, v78, v32
	v_mbcnt_hi_u32_b32 v36, s2, v36
	v_add_f32_e32 v32, v75, v32
	v_lshlrev_b32_e32 v36, 2, v36
	v_add_f32_e32 v32, v76, v32
	v_xor_b32_e32 v40, 4, v36
	s_nop 1
	v_mov_b32_dpp v40, v32 quad_perm:[1,0,3,2] row_mask:0xf bank_mask:0xf
	s_waitcnt lgkmcnt(0)
	v_add_f32_e32 v32, v32, v40
	v_xor_b32_e32 v40, 8, v36
	s_nop 1
	v_mov_b32_dpp v40, v32 quad_perm:[2,3,0,1] row_mask:0xf bank_mask:0xf
	s_waitcnt lgkmcnt(0)
	v_add_f32_e32 v32, v32, v40
	v_xor_b32_e32 v40, 16, v36
	s_nop 1
	v_mov_b32_dpp v40, v32 row_half_mirror row_mask:0xf bank_mask:0xf
	s_nop 1
	v_mov_b32_dpp v40, v40 quad_perm:[3,2,1,0] row_mask:0xf bank_mask:0xf
	v_xor_b32_e32 v36, 32, v36
	s_waitcnt lgkmcnt(0)
	v_add_f32_e32 v32, v32, v40
	s_nop 1
	v_mov_b32_dpp v36, v32 row_ror:8 row_mask:0xf bank_mask:0xf
	s_and_saveexec_b64 s[2:3], vcc
	s_cbranch_execz .LBB0_3510
	s_mov_b32 s8, 0x10880
	v_add3_u32 v40, v133, v134, s8
	s_waitcnt lgkmcnt(0)
	v_add_f32_e32 v32, v32, v36
	ds_write_b32 v40, v32
.LBB0_3510:
	s_or_b64 exec, exec, s[2:3]
	v_add_u32_e32 v32, 0x84, v129
	ds_read2st64_b32 v[64:65], v32 offset1:4
	s_mov_b32 s2, -1
	s_waitcnt lgkmcnt(0)
	v_max_f32_e32 v32, v65, v65
	v_max_f32_e32 v36, v64, v64
	v_max_f32_e32 v32, v36, v32
	v_sub_f32_e32 v36, v61, v32
	v_mul_f32_e32 v36, 0x3d800000, v36
	v_sub_f32_e32 v40, v57, v32
	v_mul_f32_e32 v36, 0x3fb8aa3b, v36
	v_mul_f32_e32 v40, 0x3d800000, v40
	v_exp_f32_e32 v73, v36
	v_sub_f32_e32 v36, v53, v32
	v_mul_f32_e32 v40, 0x3fb8aa3b, v40
	v_mul_f32_e32 v36, 0x3d800000, v36
	v_exp_f32_e32 v74, v40
	v_mul_f32_e32 v36, 0x3fb8aa3b, v36
	v_sub_f32_e32 v40, v45, v32
	v_exp_f32_e32 v71, v36
	v_sub_f32_e32 v36, v49, v32
	v_mul_f32_e32 v40, 0x3d800000, v40
	v_mul_f32_e32 v36, 0x3d800000, v36
	v_mul_f32_e32 v40, 0x3fb8aa3b, v40
	v_mul_f32_e32 v36, 0x3fb8aa3b, v36
	v_exp_f32_e32 v69, v40
	v_sub_f32_e32 v40, v41, v32
	v_exp_f32_e32 v72, v36
	v_mul_f32_e32 v40, 0x3d800000, v40
	v_sub_f32_e32 v37, v37, v32
	v_add_f32_e32 v36, 0, v73
	v_mul_f32_e32 v40, 0x3fb8aa3b, v40
	v_mul_f32_e32 v37, 0x3d800000, v37
	v_sub_f32_e32 v32, v33, v32
	v_add_f32_e32 v36, v74, v36
	v_exp_f32_e32 v70, v40
	v_mul_f32_e32 v37, 0x3fb8aa3b, v37
	v_mul_f32_e32 v32, 0x3d800000, v32
	v_add_f32_e32 v36, v71, v36
	v_exp_f32_e32 v67, v37
	v_mul_f32_e32 v32, 0x3fb8aa3b, v32
	v_add_f32_e32 v36, v72, v36
	v_exp_f32_e32 v68, v32
	v_add_f32_e32 v32, v69, v36
	v_mbcnt_lo_u32_b32 v33, s2, 0
	v_add_f32_e32 v32, v70, v32
	v_mbcnt_hi_u32_b32 v33, s2, v33
	v_add_f32_e32 v32, v67, v32
	v_lshlrev_b32_e32 v33, 2, v33
	v_add_f32_e32 v32, v68, v32
	v_xor_b32_e32 v36, 4, v33
	s_nop 1
	v_mov_b32_dpp v36, v32 quad_perm:[1,0,3,2] row_mask:0xf bank_mask:0xf
	s_waitcnt lgkmcnt(0)
	v_add_f32_e32 v32, v32, v36
	v_xor_b32_e32 v36, 8, v33
	s_nop 1
	v_mov_b32_dpp v36, v32 quad_perm:[2,3,0,1] row_mask:0xf bank_mask:0xf
	s_waitcnt lgkmcnt(0)
	v_add_f32_e32 v32, v32, v36
	v_xor_b32_e32 v36, 16, v33
	s_nop 1
	v_mov_b32_dpp v36, v32 row_half_mirror row_mask:0xf bank_mask:0xf
	s_nop 1
	v_mov_b32_dpp v36, v36 quad_perm:[3,2,1,0] row_mask:0xf bank_mask:0xf
	v_xor_b32_e32 v33, 32, v33
	s_waitcnt lgkmcnt(0)
	v_add_f32_e32 v32, v32, v36
	s_nop 1
	v_mov_b32_dpp v33, v32 row_ror:8 row_mask:0xf bank_mask:0xf
	s_and_saveexec_b64 s[2:3], vcc
	s_cbranch_execz .LBB0_3512
	s_mov_b32 s8, 0x10884
	v_add3_u32 v36, v133, v134, s8
	s_waitcnt lgkmcnt(0)
	v_add_f32_e32 v32, v32, v33
	ds_write_b32 v36, v32
; DEVFI int lane_opaque() { unsigned m = ~0u; asm volatile("" : "+s"(m)); return (int)__builtin_amdgcn_mbcnt_hi(m, __builtin_amdgcn_mbcnt_lo(m, 0u)); }
; DEVFI float shx(float v, int mask, int lane) { return __int_as_float(__builtin_amdgcn_ds_bpermute((lane ^ mask) << 2, __float_as_int(v))); }
; #define SBAR() __builtin_amdgcn_sched_barrier(0)
; DEVFI float red16(float v) {
;   const int ln = lane_opaque();
;   v += shx(v, 1, ln); v += shx(v, 2, ln); v += shx(v, 4, ln); v += shx(v, 8, ln); return v;
; }
; __global__ void __launch_bounds__(512) mega(Params p) {
;     ...
;             auto sexp = [&](f32x4 (&a)[8], const int m) {
; #pragma unroll
;               for (int j = 0; j < 4; ++j) { const int rr = rb + m * 16 + j; const float gm = fmaxf(red[rr], red[256 + rr]); float sm = 0;
; #pragma unroll
;                 for (int n = 0; n < 8; ++n) { const float e = __expf((a[n][j] - gm) * 0.0625f); a[n][j] = e; sm += e; }
;                 sm = red16(sm);
;                 if (fr == 0) red[512 + wcI * 256 + rr] = sm; }
;               SBAR(); };
;             sexp(acc[0], 0); sexp(acc[1], 1); sexp(acc[2], 2); sexp(acc[3], 3);
.LBB0_3512:
	s_or_b64 exec, exec, s[2:3]
	v_add_u32_e32 v32, 0x88, v129
	s_waitcnt lgkmcnt(0)
	ds_read2st64_b32 v[32:33], v32 offset1:4
	s_mov_b32 s2, -1
	s_waitcnt lgkmcnt(0)
	v_max_f32_e32 v33, v33, v33
	v_max_f32_e32 v32, v32, v32
	v_max_f32_e32 v32, v32, v33
	v_sub_f32_e32 v33, v62, v32
	v_sub_f32_e32 v36, v58, v32
	v_mul_f32_e32 v33, 0x3d800000, v33
	v_mul_f32_e32 v36, 0x3d800000, v36
	v_mul_f32_e32 v33, 0x3fb8aa3b, v33
	v_mul_f32_e32 v36, 0x3fb8aa3b, v36
	v_exp_f32_e32 v65, v33
	v_exp_f32_e32 v66, v36
	v_sub_f32_e32 v33, v54, v32
	v_sub_f32_e32 v36, v46, v32
	v_mul_f32_e32 v33, 0x3d800000, v33
	v_mul_f32_e32 v36, 0x3d800000, v36
	v_mul_f32_e32 v33, 0x3fb8aa3b, v33
	v_mul_f32_e32 v36, 0x3fb8aa3b, v36
	v_exp_f32_e32 v62, v33
	v_sub_f32_e32 v33, v50, v32
	v_exp_f32_e32 v60, v36
	v_sub_f32_e32 v36, v42, v32
	v_mul_f32_e32 v33, 0x3d800000, v33
	v_mul_f32_e32 v36, 0x3d800000, v36
	v_mul_f32_e32 v33, 0x3fb8aa3b, v33
	v_mul_f32_e32 v36, 0x3fb8aa3b, v36
	v_exp_f32_e32 v64, v33
	v_exp_f32_e32 v61, v36
	v_sub_f32_e32 v36, v38, v32
	v_add_f32_e32 v33, 0, v65
	v_mul_f32_e32 v36, 0x3d800000, v36
	v_sub_f32_e32 v32, v34, v32
	v_add_f32_e32 v33, v66, v33
	v_mul_f32_e32 v36, 0x3fb8aa3b, v36
	v_mul_f32_e32 v32, 0x3d800000, v32
	v_add_f32_e32 v33, v62, v33
	v_exp_f32_e32 v57, v36
	v_mul_f32_e32 v32, 0x3fb8aa3b, v32
	v_add_f32_e32 v33, v64, v33
	v_exp_f32_e32 v58, v32
	v_add_f32_e32 v32, v60, v33
	v_mbcnt_lo_u32_b32 v33, s2, 0
	v_add_f32_e32 v32, v61, v32
	v_mbcnt_hi_u32_b32 v33, s2, v33
	v_add_f32_e32 v32, v57, v32
	v_lshlrev_b32_e32 v33, 2, v33
	v_add_f32_e32 v32, v58, v32
	v_xor_b32_e32 v34, 4, v33
	s_nop 1
	v_mov_b32_dpp v34, v32 quad_perm:[1,0,3,2] row_mask:0xf bank_mask:0xf
	s_waitcnt lgkmcnt(0)
	v_add_f32_e32 v32, v32, v34
	v_xor_b32_e32 v34, 8, v33
	s_nop 1
	v_mov_b32_dpp v34, v32 quad_perm:[2,3,0,1] row_mask:0xf bank_mask:0xf
	s_waitcnt lgkmcnt(0)
	v_add_f32_e32 v32, v32, v34
	v_xor_b32_e32 v34, 16, v33
	s_nop 1
	v_mov_b32_dpp v34, v32 row_half_mirror row_mask:0xf bank_mask:0xf
	s_nop 1
	v_mov_b32_dpp v34, v34 quad_perm:[3,2,1,0] row_mask:0xf bank_mask:0xf
	v_xor_b32_e32 v33, 32, v33
	s_waitcnt lgkmcnt(0)
	v_add_f32_e32 v32, v32, v34
	s_nop 1
	v_mov_b32_dpp v33, v32 row_ror:8 row_mask:0xf bank_mask:0xf
	s_and_saveexec_b64 s[2:3], vcc
	s_cbranch_execz .LBB0_3514
	s_mov_b32 s8, 0x10888
	v_add3_u32 v34, v133, v134, s8
	s_waitcnt lgkmcnt(0)
	v_add_f32_e32 v32, v32, v33
	ds_write_b32 v34, v32
.LBB0_3514:
	s_or_b64 exec, exec, s[2:3]
	v_add_u32_e32 v32, 0x8c, v129
	s_waitcnt lgkmcnt(0)
	ds_read2st64_b32 v[32:33], v32 offset1:4
	s_mov_b32 s2, -1
	s_waitcnt lgkmcnt(0)
	v_max_f32_e32 v33, v33, v33
	v_max_f32_e32 v32, v32, v32
	v_max_f32_e32 v32, v32, v33
	v_sub_f32_e32 v33, v63, v32
	v_sub_f32_e32 v34, v59, v32
	v_mul_f32_e32 v33, 0x3d800000, v33
	v_mul_f32_e32 v34, 0x3d800000, v34
	v_mul_f32_e32 v33, 0x3fb8aa3b, v33
	v_mul_f32_e32 v34, 0x3fb8aa3b, v34
	v_exp_f32_e32 v54, v33
	v_exp_f32_e32 v56, v34
	v_sub_f32_e32 v33, v55, v32
	v_sub_f32_e32 v34, v47, v32
	v_mul_f32_e32 v33, 0x3d800000, v33
	v_mul_f32_e32 v34, 0x3d800000, v34
	v_mul_f32_e32 v33, 0x3fb8aa3b, v33
	v_mul_f32_e32 v34, 0x3fb8aa3b, v34
	v_exp_f32_e32 v52, v33
	v_sub_f32_e32 v33, v51, v32
	v_exp_f32_e32 v50, v34
	v_sub_f32_e32 v34, v43, v32
	v_mul_f32_e32 v33, 0x3d800000, v33
	v_mul_f32_e32 v34, 0x3d800000, v34
	v_mul_f32_e32 v33, 0x3fb8aa3b, v33
	v_mul_f32_e32 v34, 0x3fb8aa3b, v34
	v_exp_f32_e32 v53, v33
	v_exp_f32_e32 v51, v34
	v_sub_f32_e32 v34, v39, v32
	v_add_f32_e32 v33, 0, v54
	v_mul_f32_e32 v34, 0x3d800000, v34
	v_sub_f32_e32 v32, v35, v32
	v_add_f32_e32 v33, v56, v33
	v_mul_f32_e32 v34, 0x3fb8aa3b, v34
	v_mul_f32_e32 v32, 0x3d800000, v32
	v_add_f32_e32 v33, v52, v33
	v_exp_f32_e32 v48, v34
	v_mul_f32_e32 v32, 0x3fb8aa3b, v32
	v_add_f32_e32 v33, v53, v33
	v_exp_f32_e32 v49, v32
	v_add_f32_e32 v32, v50, v33
	v_mbcnt_lo_u32_b32 v33, s2, 0
	v_add_f32_e32 v32, v51, v32
	v_mbcnt_hi_u32_b32 v33, s2, v33
	v_add_f32_e32 v32, v48, v32
	v_lshlrev_b32_e32 v33, 2, v33
	v_add_f32_e32 v32, v49, v32
	v_xor_b32_e32 v34, 4, v33
	s_nop 1
	v_mov_b32_dpp v34, v32 quad_perm:[1,0,3,2] row_mask:0xf bank_mask:0xf
	s_waitcnt lgkmcnt(0)
	v_add_f32_e32 v32, v32, v34
	v_xor_b32_e32 v34, 8, v33
	s_nop 1
	v_mov_b32_dpp v34, v32 quad_perm:[2,3,0,1] row_mask:0xf bank_mask:0xf
	s_waitcnt lgkmcnt(0)
	v_add_f32_e32 v32, v32, v34
	v_xor_b32_e32 v34, 16, v33
	s_nop 1
	v_mov_b32_dpp v34, v32 row_half_mirror row_mask:0xf bank_mask:0xf
	s_nop 1
	v_mov_b32_dpp v34, v34 quad_perm:[3,2,1,0] row_mask:0xf bank_mask:0xf
	v_xor_b32_e32 v33, 32, v33
	s_waitcnt lgkmcnt(0)
	v_add_f32_e32 v32, v32, v34
	s_nop 1
	v_mov_b32_dpp v33, v32 row_ror:8 row_mask:0xf bank_mask:0xf
	s_and_saveexec_b64 s[2:3], vcc
	s_cbranch_execz .LBB0_3516
	s_mov_b32 s8, 0x1088c
	v_add3_u32 v34, v133, v134, s8
	s_waitcnt lgkmcnt(0)
	v_add_f32_e32 v32, v32, v33
	ds_write_b32 v34, v32
; DEVFI int lane_opaque() { unsigned m = ~0u; asm volatile("" : "+s"(m)); return (int)__builtin_amdgcn_mbcnt_hi(m, __builtin_amdgcn_mbcnt_lo(m, 0u)); }
; DEVFI float shx(float v, int mask, int lane) { return __int_as_float(__builtin_amdgcn_ds_bpermute((lane ^ mask) << 2, __float_as_int(v))); }
; #define SBAR() __builtin_amdgcn_sched_barrier(0)
; DEVFI float red16(float v) {
;   const int ln = lane_opaque();
;   v += shx(v, 1, ln); v += shx(v, 2, ln); v += shx(v, 4, ln); v += shx(v, 8, ln); return v;
; }
; __global__ void __launch_bounds__(512) mega(Params p) {
;     ...
;             auto sexp = [&](f32x4 (&a)[8], const int m) {
; #pragma unroll
;               for (int j = 0; j < 4; ++j) { const int rr = rb + m * 16 + j; const float gm = fmaxf(red[rr], red[256 + rr]); float sm = 0;
; #pragma unroll
;                 for (int n = 0; n < 8; ++n) { const float e = __expf((a[n][j] - gm) * 0.0625f); a[n][j] = e; sm += e; }
;                 sm = red16(sm);
;                 if (fr == 0) red[512 + wcI * 256 + rr] = sm; }
;               SBAR(); };
;             sexp(acc[0], 0); sexp(acc[1], 1); sexp(acc[2], 2); sexp(acc[3], 3);
.LBB0_3516:
	s_or_b64 exec, exec, s[2:3]
	v_add_u32_e32 v32, 0xc0, v129
	s_waitcnt lgkmcnt(0)
	ds_read2st64_b32 v[32:33], v32 offset1:4
	s_mov_b32 s2, -1
	s_waitcnt lgkmcnt(0)
	v_max_f32_e32 v33, v33, v33
	v_max_f32_e32 v32, v32, v32
	v_max_f32_e32 v32, v32, v33
	v_sub_f32_e32 v28, v28, v32
	v_sub_f32_e32 v24, v24, v32
	v_mul_f32_e32 v28, 0x3d800000, v28
	v_mul_f32_e32 v24, 0x3d800000, v24
	v_mul_f32_e32 v28, 0x3fb8aa3b, v28
	v_sub_f32_e32 v20, v20, v32
	v_mul_f32_e32 v24, 0x3fb8aa3b, v24
	v_exp_f32_e32 v46, v28
	v_mul_f32_e32 v20, 0x3d800000, v20
	v_sub_f32_e32 v16, v16, v32
	v_exp_f32_e32 v47, v24
	v_mul_f32_e32 v20, 0x3fb8aa3b, v20
	v_mul_f32_e32 v16, 0x3d800000, v16
	v_sub_f32_e32 v12, v12, v32
	v_exp_f32_e32 v44, v20
	v_mul_f32_e32 v16, 0x3fb8aa3b, v16
	v_mul_f32_e32 v12, 0x3d800000, v12
	v_sub_f32_e32 v8, v8, v32
	v_exp_f32_e32 v45, v16
	v_mul_f32_e32 v12, 0x3fb8aa3b, v12
	v_mul_f32_e32 v8, 0x3d800000, v8
	v_sub_f32_e32 v4, v4, v32
	v_add_f32_e32 v16, 0, v46
	v_exp_f32_e32 v42, v12
	v_mul_f32_e32 v8, 0x3fb8aa3b, v8
	v_mul_f32_e32 v4, 0x3d800000, v4
	v_sub_f32_e32 v0, v0, v32
	v_add_f32_e32 v16, v47, v16
	v_exp_f32_e32 v43, v8
	v_mul_f32_e32 v4, 0x3fb8aa3b, v4
	v_mul_f32_e32 v0, 0x3d800000, v0
	v_add_f32_e32 v16, v44, v16
	v_exp_f32_e32 v40, v4
	v_mul_f32_e32 v0, 0x3fb8aa3b, v0
	v_add_f32_e32 v16, v45, v16
	v_exp_f32_e32 v41, v0
	v_add_f32_e32 v0, v42, v16
	v_mbcnt_lo_u32_b32 v4, s2, 0
	v_add_f32_e32 v0, v43, v0
	v_mbcnt_hi_u32_b32 v4, s2, v4
	v_add_f32_e32 v0, v40, v0
	v_lshlrev_b32_e32 v4, 2, v4
	v_add_f32_e32 v0, v41, v0
	v_xor_b32_e32 v8, 4, v4
	s_nop 1
	v_mov_b32_dpp v8, v0 quad_perm:[1,0,3,2] row_mask:0xf bank_mask:0xf
	s_waitcnt lgkmcnt(0)
	v_add_f32_e32 v0, v0, v8
	v_xor_b32_e32 v8, 8, v4
	s_nop 1
	v_mov_b32_dpp v8, v0 quad_perm:[2,3,0,1] row_mask:0xf bank_mask:0xf
	s_waitcnt lgkmcnt(0)
	v_add_f32_e32 v0, v0, v8
	v_xor_b32_e32 v8, 16, v4
	s_nop 1
	v_mov_b32_dpp v8, v0 row_half_mirror row_mask:0xf bank_mask:0xf
	s_nop 1
	v_mov_b32_dpp v8, v8 quad_perm:[3,2,1,0] row_mask:0xf bank_mask:0xf
	v_xor_b32_e32 v4, 32, v4
	s_waitcnt lgkmcnt(0)
	v_add_f32_e32 v0, v0, v8
	s_nop 1
	v_mov_b32_dpp v4, v0 row_ror:8 row_mask:0xf bank_mask:0xf
	s_and_saveexec_b64 s[2:3], vcc
	s_cbranch_execz .LBB0_3518
	s_mov_b32 s8, 0x108c0
	v_add3_u32 v8, v133, v134, s8
	s_waitcnt lgkmcnt(0)
	v_add_f32_e32 v0, v0, v4
	ds_write_b32 v8, v0
.LBB0_3518:
	s_or_b64 exec, exec, s[2:3]
	v_add_u32_e32 v0, 0xc4, v129
	ds_read2st64_b32 v[32:33], v0 offset1:4
	s_mov_b32 s2, -1
	s_waitcnt lgkmcnt(0)
	v_max_f32_e32 v0, v33, v33
	v_max_f32_e32 v4, v32, v32
	v_max_f32_e32 v0, v4, v0
	v_sub_f32_e32 v4, v29, v0
	v_mul_f32_e32 v4, 0x3d800000, v4
	v_sub_f32_e32 v8, v25, v0
	v_mul_f32_e32 v4, 0x3fb8aa3b, v4
	v_mul_f32_e32 v8, 0x3d800000, v8
	v_exp_f32_e32 v38, v4
	v_sub_f32_e32 v4, v21, v0
	v_mul_f32_e32 v8, 0x3fb8aa3b, v8
	v_mul_f32_e32 v4, 0x3d800000, v4
	v_exp_f32_e32 v39, v8
	v_mul_f32_e32 v4, 0x3fb8aa3b, v4
	v_sub_f32_e32 v8, v13, v0
	v_exp_f32_e32 v36, v4
	v_sub_f32_e32 v4, v17, v0
	v_mul_f32_e32 v8, 0x3d800000, v8
	v_mul_f32_e32 v4, 0x3d800000, v4
	v_mul_f32_e32 v8, 0x3fb8aa3b, v8
	v_mul_f32_e32 v4, 0x3fb8aa3b, v4
	v_exp_f32_e32 v34, v8
	v_sub_f32_e32 v8, v9, v0
	v_exp_f32_e32 v37, v4
	v_mul_f32_e32 v8, 0x3d800000, v8
	v_sub_f32_e32 v5, v5, v0
	v_add_f32_e32 v4, 0, v38
	v_mul_f32_e32 v8, 0x3fb8aa3b, v8
	v_mul_f32_e32 v5, 0x3d800000, v5
	v_sub_f32_e32 v0, v1, v0
	v_add_f32_e32 v4, v39, v4
	v_exp_f32_e32 v35, v8
	v_mul_f32_e32 v5, 0x3fb8aa3b, v5
	v_mul_f32_e32 v0, 0x3d800000, v0
	v_add_f32_e32 v4, v36, v4
	v_exp_f32_e32 v32, v5
	v_mul_f32_e32 v0, 0x3fb8aa3b, v0
	v_add_f32_e32 v4, v37, v4
	v_exp_f32_e32 v33, v0
	v_add_f32_e32 v0, v34, v4
	v_mbcnt_lo_u32_b32 v1, s2, 0
	v_add_f32_e32 v0, v35, v0
	v_mbcnt_hi_u32_b32 v1, s2, v1
	v_add_f32_e32 v0, v32, v0
	v_lshlrev_b32_e32 v1, 2, v1
	v_add_f32_e32 v0, v33, v0
	v_xor_b32_e32 v4, 4, v1
	s_nop 1
	v_mov_b32_dpp v4, v0 quad_perm:[1,0,3,2] row_mask:0xf bank_mask:0xf
	s_waitcnt lgkmcnt(0)
	v_add_f32_e32 v0, v0, v4
	v_xor_b32_e32 v4, 8, v1
	s_nop 1
	v_mov_b32_dpp v4, v0 quad_perm:[2,3,0,1] row_mask:0xf bank_mask:0xf
	s_waitcnt lgkmcnt(0)
	v_add_f32_e32 v0, v0, v4
	v_xor_b32_e32 v4, 16, v1
	s_nop 1
	v_mov_b32_dpp v4, v0 row_half_mirror row_mask:0xf bank_mask:0xf
	s_nop 1
	v_mov_b32_dpp v4, v4 quad_perm:[3,2,1,0] row_mask:0xf bank_mask:0xf
	v_xor_b32_e32 v1, 32, v1
	s_waitcnt lgkmcnt(0)
	v_add_f32_e32 v0, v0, v4
	s_nop 1
	v_mov_b32_dpp v1, v0 row_ror:8 row_mask:0xf bank_mask:0xf
	s_and_saveexec_b64 s[2:3], vcc
	s_cbranch_execz .LBB0_3520
	s_mov_b32 s8, 0x108c4
	v_add3_u32 v4, v133, v134, s8
	s_waitcnt lgkmcnt(0)
	v_add_f32_e32 v0, v0, v1
	ds_write_b32 v4, v0
; DEVFI int lane_opaque() { unsigned m = ~0u; asm volatile("" : "+s"(m)); return (int)__builtin_amdgcn_mbcnt_hi(m, __builtin_amdgcn_mbcnt_lo(m, 0u)); }
; DEVFI float shx(float v, int mask, int lane) { return __int_as_float(__builtin_amdgcn_ds_bpermute((lane ^ mask) << 2, __float_as_int(v))); }
; #define SBAR() __builtin_amdgcn_sched_barrier(0)
; DEVFI float red16(float v) {
;   const int ln = lane_opaque();
;   v += shx(v, 1, ln); v += shx(v, 2, ln); v += shx(v, 4, ln); v += shx(v, 8, ln); return v;
; }
; __global__ void __launch_bounds__(512) mega(Params p) {
;     ...
;             auto sexp = [&](f32x4 (&a)[8], const int m) {
; #pragma unroll
;               for (int j = 0; j < 4; ++j) { const int rr = rb + m * 16 + j; const float gm = fmaxf(red[rr], red[256 + rr]); float sm = 0;
; #pragma unroll
;                 for (int n = 0; n < 8; ++n) { const float e = __expf((a[n][j] - gm) * 0.0625f); a[n][j] = e; sm += e; }
;                 sm = red16(sm);
;                 if (fr == 0) red[512 + wcI * 256 + rr] = sm; }
;               SBAR(); };
;             sexp(acc[0], 0); sexp(acc[1], 1); sexp(acc[2], 2); sexp(acc[3], 3);
.LBB0_3520:
	s_or_b64 exec, exec, s[2:3]
	v_add_u32_e32 v0, 0xc8, v129
	s_waitcnt lgkmcnt(0)
	ds_read2st64_b32 v[0:1], v0 offset1:4
	s_mov_b32 s2, -1
	s_waitcnt lgkmcnt(0)
	v_max_f32_e32 v1, v1, v1
	v_max_f32_e32 v0, v0, v0
	v_max_f32_e32 v0, v0, v1
	v_sub_f32_e32 v1, v30, v0
	v_sub_f32_e32 v4, v26, v0
	v_mul_f32_e32 v1, 0x3d800000, v1
	v_mul_f32_e32 v4, 0x3d800000, v4
	v_mul_f32_e32 v1, 0x3fb8aa3b, v1
	v_mul_f32_e32 v4, 0x3fb8aa3b, v4
	v_exp_f32_e32 v29, v1
	v_exp_f32_e32 v30, v4
	v_sub_f32_e32 v1, v22, v0
	v_sub_f32_e32 v4, v14, v0
	v_mul_f32_e32 v1, 0x3d800000, v1
	v_mul_f32_e32 v4, 0x3d800000, v4
	v_mul_f32_e32 v1, 0x3fb8aa3b, v1
	v_mul_f32_e32 v4, 0x3fb8aa3b, v4
	v_exp_f32_e32 v26, v1
	v_sub_f32_e32 v1, v18, v0
	v_exp_f32_e32 v24, v4
	v_sub_f32_e32 v4, v10, v0
	v_mul_f32_e32 v1, 0x3d800000, v1
	v_mul_f32_e32 v4, 0x3d800000, v4
	v_mul_f32_e32 v1, 0x3fb8aa3b, v1
	v_mul_f32_e32 v4, 0x3fb8aa3b, v4
	v_exp_f32_e32 v28, v1
	v_exp_f32_e32 v25, v4
	v_sub_f32_e32 v4, v6, v0
	v_add_f32_e32 v1, 0, v29
	v_mul_f32_e32 v4, 0x3d800000, v4
	v_sub_f32_e32 v0, v2, v0
	v_add_f32_e32 v1, v30, v1
	v_mul_f32_e32 v4, 0x3fb8aa3b, v4
	v_mul_f32_e32 v0, 0x3d800000, v0
	v_add_f32_e32 v1, v26, v1
	v_exp_f32_e32 v21, v4
	v_mul_f32_e32 v0, 0x3fb8aa3b, v0
	v_add_f32_e32 v1, v28, v1
	v_exp_f32_e32 v22, v0
	v_add_f32_e32 v0, v24, v1
	v_mbcnt_lo_u32_b32 v1, s2, 0
	v_add_f32_e32 v0, v25, v0
	v_mbcnt_hi_u32_b32 v1, s2, v1
	v_add_f32_e32 v0, v21, v0
	v_lshlrev_b32_e32 v1, 2, v1
	v_add_f32_e32 v0, v22, v0
	v_xor_b32_e32 v2, 4, v1
	s_nop 1
	v_mov_b32_dpp v2, v0 quad_perm:[1,0,3,2] row_mask:0xf bank_mask:0xf
	s_waitcnt lgkmcnt(0)
	v_add_f32_e32 v0, v0, v2
	v_xor_b32_e32 v2, 8, v1
	s_nop 1
	v_mov_b32_dpp v2, v0 quad_perm:[2,3,0,1] row_mask:0xf bank_mask:0xf
	s_waitcnt lgkmcnt(0)
	v_add_f32_e32 v0, v0, v2
	v_xor_b32_e32 v2, 16, v1
	s_nop 1
	v_mov_b32_dpp v2, v0 row_half_mirror row_mask:0xf bank_mask:0xf
	s_nop 1
	v_mov_b32_dpp v2, v2 quad_perm:[3,2,1,0] row_mask:0xf bank_mask:0xf
	v_xor_b32_e32 v1, 32, v1
	s_waitcnt lgkmcnt(0)
	v_add_f32_e32 v0, v0, v2
	s_nop 1
	v_mov_b32_dpp v1, v0 row_ror:8 row_mask:0xf bank_mask:0xf
	s_and_saveexec_b64 s[2:3], vcc
	s_cbranch_execz .LBB0_3522
	s_mov_b32 s8, 0x108c8
	v_add3_u32 v2, v133, v134, s8
	s_waitcnt lgkmcnt(0)
	v_add_f32_e32 v0, v0, v1
	ds_write_b32 v2, v0
.LBB0_3522:
	s_or_b64 exec, exec, s[2:3]
	v_add_u32_e32 v0, 0xcc, v129
	s_waitcnt lgkmcnt(0)
	ds_read2st64_b32 v[0:1], v0 offset1:4
	s_mov_b32 s2, -1
	s_waitcnt lgkmcnt(0)
	v_max_f32_e32 v1, v1, v1
	v_max_f32_e32 v0, v0, v0
	v_max_f32_e32 v0, v0, v1
	v_sub_f32_e32 v1, v31, v0
	v_sub_f32_e32 v2, v27, v0
	v_mul_f32_e32 v1, 0x3d800000, v1
	v_mul_f32_e32 v2, 0x3d800000, v2
	v_mul_f32_e32 v1, 0x3fb8aa3b, v1
	v_mul_f32_e32 v2, 0x3fb8aa3b, v2
	v_exp_f32_e32 v18, v1
	v_exp_f32_e32 v20, v2
	v_sub_f32_e32 v1, v23, v0
	v_sub_f32_e32 v2, v15, v0
	v_mul_f32_e32 v1, 0x3d800000, v1
	v_mul_f32_e32 v2, 0x3d800000, v2
	v_mul_f32_e32 v1, 0x3fb8aa3b, v1
	v_mul_f32_e32 v2, 0x3fb8aa3b, v2
	v_exp_f32_e32 v16, v1
	v_sub_f32_e32 v1, v19, v0
	v_exp_f32_e32 v14, v2
	v_sub_f32_e32 v2, v11, v0
	v_mul_f32_e32 v1, 0x3d800000, v1
	v_mul_f32_e32 v2, 0x3d800000, v2
	v_mul_f32_e32 v1, 0x3fb8aa3b, v1
	v_mul_f32_e32 v2, 0x3fb8aa3b, v2
	v_exp_f32_e32 v17, v1
	v_exp_f32_e32 v15, v2
	v_sub_f32_e32 v2, v7, v0
	v_add_f32_e32 v1, 0, v18
	v_mul_f32_e32 v2, 0x3d800000, v2
	v_sub_f32_e32 v0, v3, v0
	v_add_f32_e32 v1, v20, v1
	v_mul_f32_e32 v2, 0x3fb8aa3b, v2
	v_mul_f32_e32 v0, 0x3d800000, v0
	v_add_f32_e32 v1, v16, v1
	v_exp_f32_e32 v12, v2
	v_mul_f32_e32 v0, 0x3fb8aa3b, v0
	v_add_f32_e32 v1, v17, v1
	v_exp_f32_e32 v13, v0
	v_add_f32_e32 v0, v14, v1
	v_mbcnt_lo_u32_b32 v1, s2, 0
	v_add_f32_e32 v0, v15, v0
	v_mbcnt_hi_u32_b32 v1, s2, v1
	v_add_f32_e32 v0, v12, v0
	v_lshlrev_b32_e32 v1, 2, v1
	v_add_f32_e32 v0, v13, v0
	v_xor_b32_e32 v2, 4, v1
	s_nop 1
	v_mov_b32_dpp v2, v0 quad_perm:[1,0,3,2] row_mask:0xf bank_mask:0xf
	s_waitcnt lgkmcnt(0)
	v_add_f32_e32 v0, v0, v2
	v_xor_b32_e32 v2, 8, v1
	s_nop 1
	v_mov_b32_dpp v2, v0 quad_perm:[2,3,0,1] row_mask:0xf bank_mask:0xf
	s_waitcnt lgkmcnt(0)
	v_add_f32_e32 v0, v0, v2
	v_xor_b32_e32 v2, 16, v1
	s_nop 1
	v_mov_b32_dpp v2, v0 row_half_mirror row_mask:0xf bank_mask:0xf
	s_nop 1
	v_mov_b32_dpp v2, v2 quad_perm:[3,2,1,0] row_mask:0xf bank_mask:0xf
	v_xor_b32_e32 v1, 32, v1
	s_waitcnt lgkmcnt(0)
	v_add_f32_e32 v0, v0, v2
	s_nop 1
	v_mov_b32_dpp v1, v0 row_ror:8 row_mask:0xf bank_mask:0xf
	s_and_saveexec_b64 s[2:3], vcc
	s_cbranch_execz .LBB0_3524
	s_mov_b32 s8, 0x108cc
	v_add3_u32 v2, v133, v134, s8
	s_waitcnt lgkmcnt(0)
	v_add_f32_e32 v0, v0, v1
	ds_write_b32 v2, v0

; DEVFI void ln_resid4(const float* ysrc, float* ydst, bfraw* fb, float* stats, const float* pw, const float* pb,
;                      const float* w, const float* b, int lane, bool fin) {
;   f32x4 v[4][4];
; #pragma unroll
;   for (int r = 0; r < 4; ++r)
; #pragma unroll
;     for (int i = 0; i < 4; ++i) v[r][i] = __builtin_nontemporal_load((const f32x4*)(ysrc + r * 1024) + i * 64 + lane);
;   u32x2 fv[4][4];
; #pragma unroll
;   for (int r = 0; r < 4; ++r)
; #pragma unroll
;     for (int i = 0; i < 4; ++i) fv[r][i] = __builtin_nontemporal_load((const u32x2*)(fb + r * 1024) + i * 64 + lane);
;   f32x4 pwv[4], pbv[4], ww[4], bb[4];
; #pragma unroll
;   for (int i = 0; i < 4; ++i) { pwv[i] = ((const f32x4*)pw)[i * 64 + lane]; pbv[i] = ((const f32x4*)pb)[i * 64 + lane];
;     ww[i] = ((const f32x4*)w)[i * 64 + lane]; bb[i] = ((const f32x4*)b)[i * 64 + lane]; }
; #pragma unroll
;   for (int r = 0; r < 4; ++r) {
;     const float pmu = stats[r * 2], prs = stats[r * 2 + 1];
;     f32x4 y[4];
; #pragma unroll
;     for (int i = 0; i < 4; ++i) { const unsigned f0 = fv[r][i][0], f1 = fv[r][i][1];
;       const f32x4 f4 = {__uint_as_float(f0 << 16), __uint_as_float(f0 & 0xffff0000u), __uint_as_float(f1 << 16), __uint_as_float(f1 & 0xffff0000u)};
;       y[i] = ALPHA * ((v[r][i] - pmu) * prs * pwv[i] + pbv[i]) + f4; }
;     float s = 0;
; #pragma unroll
;     for (int i = 0; i < 4; ++i) s += y[i][0] + y[i][1] + y[i][2] + y[i][3];
;     const float mean = red64(s) * (1.f / 1024.f);
.LBB0_4340:
	v_add_co_u32_e32 v0, vcc, 0x1000, v142
	global_load_dwordx4 v[124:127], v[142:143], off nt
	global_load_dwordx4 v[120:123], v[142:143], off offset:1024 nt
	global_load_dwordx4 v[116:119], v[142:143], off offset:2048 nt
	global_load_dwordx4 v[112:115], v[142:143], off offset:3072 nt
	v_addc_co_u32_e32 v1, vcc, 0, v143, vcc
	global_load_dwordx4 v[108:111], v[0:1], off nt
	global_load_dwordx4 v[104:107], v[0:1], off offset:1024 nt
	global_load_dwordx4 v[100:103], v[0:1], off offset:2048 nt
	global_load_dwordx4 v[96:99], v[0:1], off offset:3072 nt
	v_add_co_u32_e32 v0, vcc, s53, v142
	s_movk_i32 s2, 0x3000
	s_nop 0
	v_addc_co_u32_e32 v1, vcc, 0, v143, vcc
	v_add_co_u32_e32 v2, vcc, s2, v142
	s_mov_b32 s2, -1
	s_nop 0
	v_addc_co_u32_e32 v3, vcc, 0, v143, vcc
	global_load_dwordx4 v[92:95], v[2:3], off offset:-4096 nt
	global_load_dwordx4 v[88:91], v[0:1], off offset:1024 nt
	global_load_dwordx4 v[84:87], v[0:1], off offset:2048 nt
	global_load_dwordx4 v[80:83], v[0:1], off offset:3072 nt
	global_load_dwordx4 v[44:47], v[2:3], off nt
	global_load_dwordx4 v[40:43], v[2:3], off offset:1024 nt
	global_load_dwordx4 v[36:39], v[2:3], off offset:2048 nt
	global_load_dwordx4 v[32:35], v[2:3], off offset:3072 nt
	global_load_dwordx2 v[174:175], v[138:139], off nt
	global_load_dwordx2 v[172:173], v[138:139], off offset:512 nt
	global_load_dwordx2 v[170:171], v[138:139], off offset:1024 nt
	global_load_dwordx2 v[168:169], v[138:139], off offset:1536 nt
	global_load_dwordx2 v[166:167], v[138:139], off offset:2048 nt
	global_load_dwordx2 v[164:165], v[138:139], off offset:2560 nt
	global_load_dwordx2 v[162:163], v[138:139], off offset:3072 nt
	global_load_dwordx2 v[160:161], v[138:139], off offset:3584 nt
	v_add_co_u32_e32 v0, vcc, s56, v138
	v_mov_b32_e32 v192, 0x10000
	s_nop 0
	v_addc_co_u32_e32 v1, vcc, 0, v139, vcc
	global_load_dwordx2 v[158:159], v[0:1], off nt
	global_load_dwordx2 v[156:157], v[0:1], off offset:512 nt
	global_load_dwordx2 v[154:155], v[0:1], off offset:1024 nt
	global_load_dwordx2 v[152:153], v[0:1], off offset:1536 nt
	global_load_dwordx2 v[150:151], v[0:1], off offset:2048 nt
	global_load_dwordx2 v[148:149], v[0:1], off offset:2560 nt
	global_load_dwordx2 v[146:147], v[0:1], off offset:3072 nt
	global_load_dwordx2 v[144:145], v[0:1], off offset:3584 nt
	global_load_dwordx4 v[56:59], v[130:131], off
	global_load_dwordx4 v[60:63], v[132:133], off
	global_load_dwordx4 v[24:27], v[134:135], off
	global_load_dwordx4 v[28:31], v[136:137], off
	global_load_dwordx4 v[64:67], v[130:131], off offset:1024
	global_load_dwordx4 v[68:71], v[132:133], off offset:1024
	global_load_dwordx4 v[16:19], v[134:135], off offset:1024
	global_load_dwordx4 v[20:23], v[136:137], off offset:1024
	global_load_dwordx4 v[72:75], v[130:131], off offset:2048
	global_load_dwordx4 v[76:79], v[132:133], off offset:2048
	global_load_dwordx4 v[8:11], v[134:135], off offset:2048
	global_load_dwordx4 v[12:15], v[136:137], off offset:2048
	global_load_dwordx4 v[48:51], v[130:131], off offset:3072
	global_load_dwordx4 v[52:55], v[132:133], off offset:3072
	global_load_dwordx4 v[0:3], v[134:135], off offset:3072
	global_load_dwordx4 v[4:7], v[136:137], off offset:3072
	global_load_dwordx2 v[184:185], v[140:141], off
	s_waitcnt vmcnt(32)
	v_lshlrev_b32_e32 v178, 16, v174
	v_and_b32_e32 v179, 0xffff0000, v174
	v_lshlrev_b32_e32 v174, 16, v175
	v_and_b32_e32 v175, 0xffff0000, v175
	s_waitcnt vmcnt(0)
	v_sub_f32_e32 v127, v127, v184
	v_sub_f32_e32 v126, v126, v184
	v_pk_mul_f32 v[126:127], v[184:185], v[126:127] op_sel:[1,0]
	v_sub_f32_e32 v123, v123, v184
	v_sub_f32_e32 v122, v122, v184
	v_sub_f32_e32 v125, v125, v184
	v_sub_f32_e32 v124, v124, v184
	v_pk_fma_f32 v[126:127], v[58:59], v[126:127], v[62:63]
	v_sub_f32_e32 v121, v121, v184
	v_sub_f32_e32 v120, v120, v184
	v_pk_mul_f32 v[122:123], v[184:185], v[122:123] op_sel:[1,0]
	v_sub_f32_e32 v119, v119, v184
	v_sub_f32_e32 v118, v118, v184
	v_pk_mul_f32 v[124:125], v[184:185], v[124:125] op_sel:[1,0]
	v_pk_fma_f32 v[126:127], v[126:127], s[52:53], v[174:175] op_sel_hi:[1,0,1]
	v_lshlrev_b32_e32 v174, 16, v172
	v_and_b32_e32 v175, 0xffff0000, v172
	v_lshlrev_b32_e32 v172, 16, v173
	v_and_b32_e32 v173, 0xffff0000, v173
	v_pk_mul_f32 v[120:121], v[184:185], v[120:121] op_sel:[1,0]
	v_pk_fma_f32 v[122:123], v[66:67], v[122:123], v[70:71]
	v_pk_mul_f32 v[118:119], v[184:185], v[118:119] op_sel:[1,0]
	v_sub_f32_e32 v113, v113, v184
	v_sub_f32_e32 v112, v112, v184
	v_sub_f32_e32 v115, v115, v184
	v_sub_f32_e32 v114, v114, v184
	v_pk_fma_f32 v[124:125], v[56:57], v[124:125], v[60:61]
	v_pk_fma_f32 v[120:121], v[64:65], v[120:121], v[68:69]
	v_pk_fma_f32 v[122:123], v[122:123], s[52:53], v[172:173] op_sel_hi:[1,0,1]
	v_lshlrev_b32_e32 v172, 16, v170
	v_and_b32_e32 v173, 0xffff0000, v170
	v_lshlrev_b32_e32 v170, 16, v171
	v_and_b32_e32 v171, 0xffff0000, v171
	v_pk_fma_f32 v[118:119], v[74:75], v[118:119], v[78:79]
	v_pk_mul_f32 v[114:115], v[184:185], v[114:115] op_sel:[1,0]
	v_pk_mul_f32 v[112:113], v[184:185], v[112:113] op_sel:[1,0]
	v_pk_fma_f32 v[124:125], v[124:125], s[52:53], v[178:179] op_sel_hi:[1,0,1]
	v_pk_fma_f32 v[120:121], v[120:121], s[52:53], v[174:175] op_sel_hi:[1,0,1]
	v_pk_fma_f32 v[118:119], v[118:119], s[52:53], v[170:171] op_sel_hi:[1,0,1]
	v_lshlrev_b32_e32 v170, 16, v168
	v_and_b32_e32 v171, 0xffff0000, v168
	v_lshlrev_b32_e32 v168, 16, v169
	v_and_b32_e32 v169, 0xffff0000, v169
	v_pk_fma_f32 v[112:113], v[48:49], v[112:113], v[52:53]
	v_pk_fma_f32 v[114:115], v[50:51], v[114:115], v[54:55]
	v_pk_fma_f32 v[112:113], v[112:113], s[52:53], v[170:171] op_sel_hi:[1,0,1]
	v_pk_fma_f32 v[114:115], v[114:115], s[52:53], v[168:169] op_sel_hi:[1,0,1]
	v_mov_b32_e32 v168, v120
	v_mov_b32_e32 v169, v124
	v_mov_b32_e32 v170, v121
	v_mov_b32_e32 v171, v125
	v_sub_f32_e32 v117, v117, v184
	v_sub_f32_e32 v116, v116, v184
	v_pk_add_f32 v[168:169], v[168:169], v[170:171]
	v_mov_b32_e32 v170, v122
	v_mov_b32_e32 v171, v126
	v_pk_mul_f32 v[116:117], v[184:185], v[116:117] op_sel:[1,0]
	v_pk_add_f32 v[168:169], v[170:171], v[168:169]
	v_mov_b32_e32 v170, v123
	v_mov_b32_e32 v171, v127
	v_pk_fma_f32 v[116:117], v[72:73], v[116:117], v[76:77]
	v_pk_add_f32 v[168:169], v[170:171], v[168:169]
	v_pk_fma_f32 v[116:117], v[116:117], s[52:53], v[172:173] op_sel_hi:[1,0,1]
	v_add_f32_e32 v129, 0, v169
	v_add_f32_e32 v129, v168, v129
	v_mov_b32_e32 v168, v112
	v_mov_b32_e32 v169, v116
	v_mov_b32_e32 v170, v113
	v_mov_b32_e32 v171, v117
	v_pk_add_f32 v[168:169], v[168:169], v[170:171]
	v_mov_b32_e32 v170, v114
	v_mov_b32_e32 v171, v118
	v_pk_add_f32 v[168:169], v[170:171], v[168:169]
	v_mov_b32_e32 v170, v115
	v_mov_b32_e32 v171, v119
	v_pk_add_f32 v[168:169], v[170:171], v[168:169]
	s_nop 0
	v_add_f32_e32 v129, v169, v129
	v_add_f32_e32 v129, v168, v129
	v_mbcnt_lo_u32_b32 v168, s2, 0
	v_mbcnt_hi_u32_b32 v168, s2, v168
	v_lshlrev_b32_e32 v168, 2, v168
	v_xor_b32_e32 v169, 0x80, v168
	ds_bpermute_b32 v169, v169, v129
	s_mov_b32 s2, -1
	s_waitcnt lgkmcnt(0)
; DEVFI int lane_opaque() { unsigned m = ~0u; asm volatile("" : "+s"(m)); return (int)__builtin_amdgcn_mbcnt_hi(m, __builtin_amdgcn_mbcnt_lo(m, 0u)); }
; DEVFI float shx(float v, int mask, int lane) { return __int_as_float(__builtin_amdgcn_ds_bpermute((lane ^ mask) << 2, __float_as_int(v))); }
; DEVFI float red64(float v) {
;   const int ln = lane_opaque();
;   v += shx(v, 32, ln); v += shx(v, 16, ln); v += shx(v, 8, ln); v += shx(v, 4, ln); v += shx(v, 2, ln); v += shx(v, 1, ln); return v;
; }
; DEVFI void ln_resid4(const float* ysrc, float* ydst, bfraw* fb, float* stats, const float* pw, const float* pb,
;                      const float* w, const float* b, int lane, bool fin) {
;     ...
;     const float mean = red64(s) * (1.f / 1024.f);
;     float q = 0;
; #pragma unroll
;     for (int i = 0; i < 4; ++i) { const f32x4 d = y[i] - mean; q += d[0] * d[0] + d[1] * d[1] + d[2] * d[2] + d[3] * d[3]; }
;     const float rstd = 1.f / sqrtf(red64(q) * (1.f / 1024.f) + LN_EPS);
;     if (lane == 0) { stats[r * 2] = mean; stats[r * 2 + 1] = rstd; }
	v_add_f32_e32 v129, v129, v169
	v_xor_b32_e32 v169, 64, v168
	ds_bpermute_b32 v169, v169, v129
	s_waitcnt lgkmcnt(0)
	v_add_f32_e32 v129, v129, v169
	v_xor_b32_e32 v169, 32, v168
	s_nop 1
	v_mov_b32_dpp v169, v129 row_ror:8 row_mask:0xf bank_mask:0xf
	s_waitcnt lgkmcnt(0)
	v_add_f32_e32 v129, v129, v169
	v_xor_b32_e32 v169, 16, v168
	s_nop 1
	v_mov_b32_dpp v169, v129 row_half_mirror row_mask:0xf bank_mask:0xf
	s_nop 1
	v_mov_b32_dpp v169, v169 quad_perm:[3,2,1,0] row_mask:0xf bank_mask:0xf
	s_waitcnt lgkmcnt(0)
	v_add_f32_e32 v129, v129, v169
	v_xor_b32_e32 v169, 8, v168
	s_nop 1
	v_mov_b32_dpp v169, v129 quad_perm:[2,3,0,1] row_mask:0xf bank_mask:0xf
	v_xor_b32_e32 v168, 4, v168
	s_waitcnt lgkmcnt(0)
	v_add_f32_e32 v129, v129, v169
	s_nop 1
	v_mov_b32_dpp v168, v129 quad_perm:[1,0,3,2] row_mask:0xf bank_mask:0xf
	s_waitcnt lgkmcnt(0)
	v_add_f32_e32 v129, v129, v168
	v_fmamk_f32 v191, v129, 0xba800000, v125
	v_fmamk_f32 v187, v129, 0xba800000, v121
	v_fmamk_f32 v190, v129, 0xba800000, v124
	v_mul_f32_e32 v168, v191, v191
	v_fmamk_f32 v186, v129, 0xba800000, v120
	v_mul_f32_e32 v169, v187, v187
	v_fmamk_f32 v188, v129, 0xba800000, v126
	v_fmac_f32_e32 v168, v190, v190
	v_fmamk_f32 v184, v129, 0xba800000, v122
	v_fmac_f32_e32 v169, v186, v186
	v_fmamk_f32 v189, v129, 0xba800000, v127
	v_fmac_f32_e32 v168, v188, v188
	v_fmamk_f32 v185, v129, 0xba800000, v123
	v_fmac_f32_e32 v169, v184, v184
	v_fmac_f32_e32 v168, v189, v189
	v_fmac_f32_e32 v169, v185, v185
	v_fmamk_f32 v175, v129, 0xba800000, v117
	v_add_f32_e32 v168, v168, v169
	v_fmamk_f32 v174, v129, 0xba800000, v116
	v_mul_f32_e32 v169, v175, v175
	v_fmamk_f32 v172, v129, 0xba800000, v118
	v_fmac_f32_e32 v169, v174, v174
	v_fmamk_f32 v173, v129, 0xba800000, v119
	v_fmac_f32_e32 v169, v172, v172
	v_fmamk_f32 v171, v129, 0xba800000, v113
	v_fmac_f32_e32 v169, v173, v173
	v_fmamk_f32 v170, v129, 0xba800000, v112
	v_mul_f32_e32 v178, v171, v171
	v_add_f32_e32 v176, v169, v168
	v_fmamk_f32 v168, v129, 0xba800000, v114
	v_fmac_f32_e32 v178, v170, v170
	v_fmamk_f32 v169, v129, 0xba800000, v115
	v_fmac_f32_e32 v178, v168, v168
	v_fmac_f32_e32 v178, v169, v169
	v_add_f32_e32 v176, v178, v176
	v_mbcnt_lo_u32_b32 v178, s2, 0
	v_mbcnt_hi_u32_b32 v178, s2, v178
	v_lshlrev_b32_e32 v178, 2, v178
	v_xor_b32_e32 v179, 0x80, v178
	ds_bpermute_b32 v179, v179, v176
	s_waitcnt lgkmcnt(0)
	v_add_f32_e32 v176, v176, v179
	v_xor_b32_e32 v179, 64, v178
	ds_bpermute_b32 v179, v179, v176
	s_waitcnt lgkmcnt(0)
	v_add_f32_e32 v176, v176, v179
	v_xor_b32_e32 v179, 32, v178
	s_nop 1
	v_mov_b32_dpp v179, v176 row_ror:8 row_mask:0xf bank_mask:0xf
	s_waitcnt lgkmcnt(0)
	v_add_f32_e32 v176, v176, v179
	v_xor_b32_e32 v179, 16, v178
	s_nop 1
	v_mov_b32_dpp v179, v176 row_half_mirror row_mask:0xf bank_mask:0xf
	s_nop 1
	v_mov_b32_dpp v179, v179 quad_perm:[3,2,1,0] row_mask:0xf bank_mask:0xf
	s_waitcnt lgkmcnt(0)
	v_add_f32_e32 v176, v176, v179
	v_xor_b32_e32 v179, 8, v178
	s_nop 1
	v_mov_b32_dpp v179, v176 quad_perm:[2,3,0,1] row_mask:0xf bank_mask:0xf
	v_xor_b32_e32 v178, 4, v178
	s_waitcnt lgkmcnt(0)
	v_add_f32_e32 v176, v176, v179
	s_nop 1
	v_mov_b32_dpp v178, v176 quad_perm:[1,0,3,2] row_mask:0xf bank_mask:0xf
	s_waitcnt lgkmcnt(0)
	v_add_f32_e32 v176, v176, v178
	v_fmamk_f32 v176, v176, 0x3a800000, v183
	v_cmp_gt_f32_e32 vcc, s30, v176
	v_mul_f32_e32 v178, 0x4f800000, v176
	s_nop 0
	v_cndmask_b32_e32 v176, v176, v178, vcc
	v_sqrt_f32_e32 v178, v176
	s_nop 0
	v_add_u32_e32 v179, -1, v178
	v_fma_f32 v180, -v179, v178, v176
	v_cmp_ge_f32_e64 s[8:9], 0, v180
	v_add_u32_e32 v180, 1, v178
	s_nop 0
	v_cndmask_b32_e64 v179, v178, v179, s[8:9]
	v_fma_f32 v178, -v180, v178, v176
	v_cmp_lt_f32_e64 s[8:9], 0, v178
	s_nop 1
	v_cndmask_b32_e64 v178, v179, v180, s[8:9]
	v_mul_f32_e32 v179, 0x37800000, v178
	v_cndmask_b32_e32 v178, v178, v179, vcc
	v_cmp_class_f32_e32 vcc, v176, v222
	s_nop 1
	v_cndmask_b32_e32 v176, v178, v176, vcc
	s_nop 0
	v_rcp_f32_e32 v179, v176
	s_nop 0
	v_fma_f32 v178, -v176, v179, 1.0
	v_fma_f32 v178, v178, v179, v179
	v_div_fixup_f32 v176, v178, v176, 1.0
	s_and_saveexec_b64 s[2:3], s[6:7]
	s_cbranch_execz .LBB0_4342
	v_mul_f32_e32 v178, 0x3a800000, v129
	v_mov_b32_e32 v179, v176
	global_store_dwordx2 v[140:141], v[178:179], off
; DEVFI void ln_resid4(const float* ysrc, float* ydst, bfraw* fb, float* stats, const float* pw, const float* pb,
;                      const float* w, const float* b, int lane, bool fin) {
;     ...
;   for (int r = 0; r < 4; ++r) {
;     const float pmu = stats[r * 2], prs = stats[r * 2 + 1];
;     f32x4 y[4];
; #pragma unroll
;     for (int i = 0; i < 4; ++i) { const unsigned f0 = fv[r][i][0], f1 = fv[r][i][1];
;       const f32x4 f4 = {__uint_as_float(f0 << 16), __uint_as_float(f0 & 0xffff0000u), __uint_as_float(f1 << 16), __uint_as_float(f1 & 0xffff0000u)};
;       y[i] = ALPHA * ((v[r][i] - pmu) * prs * pwv[i] + pbv[i]) + f4; }
;     float s = 0;
; #pragma unroll
;     for (int i = 0; i < 4; ++i) s += y[i][0] + y[i][1] + y[i][2] + y[i][3];
;     const float mean = red64(s) * (1.f / 1024.f);
;     float q = 0;
; #pragma unroll
;     for (int i = 0; i < 4; ++i) { const f32x4 d = y[i] - mean; q += d[0] * d[0] + d[1] * d[1] + d[2] * d[2] + d[3] * d[3]; }
;     const float rstd = 1.f / sqrtf(red64(q) * (1.f / 1024.f) + LN_EPS);
;     if (lane == 0) { stats[r * 2] = mean; stats[r * 2 + 1] = rstd; }
; #pragma unroll
;     for (int i = 0; i < 4; ++i) { const int c4 = i * 64 + lane;
;       const f32x4 z = (y[i] - mean) * rstd * ww[i] + bb[i];
;       __builtin_nontemporal_store(fin ? z : y[i], (f32x4*)(ydst + r * 1024) + c4);
;       u32x2 pk = {cvtpk(z[0], z[1]), cvtpk(z[2], z[3])}; ((u32x2*)(fb + r * 1024))[c4] = pk; }
.LBB0_4342:
	s_or_b64 exec, exec, s[2:3]
	v_pk_mul_f32 v[178:179], v[188:189], v[176:177] op_sel_hi:[1,0]
	v_pk_mul_f32 v[180:181], v[190:191], v[176:177] op_sel_hi:[1,0]
	v_pk_fma_f32 v[178:179], v[26:27], v[178:179], v[30:31]
	v_pk_fma_f32 v[180:181], v[24:25], v[180:181], v[28:29]
	global_store_dwordx4 v[142:143], v[124:127], off nt
	s_mov_b32 s2, -1
	s_nop 0
	v_cvt_pk_bf16_f32 v124, v180, v181
	v_cvt_pk_bf16_f32 v125, v178, v179
	global_store_dwordx2 v[138:139], v[124:125], off
	v_pk_mul_f32 v[124:125], v[184:185], v[176:177] op_sel_hi:[1,0]
	v_pk_mul_f32 v[126:127], v[186:187], v[176:177] op_sel_hi:[1,0]
	v_pk_fma_f32 v[124:125], v[18:19], v[124:125], v[22:23]
	v_pk_fma_f32 v[126:127], v[16:17], v[126:127], v[20:21]
	global_store_dwordx4 v[142:143], v[120:123], off offset:1024 nt
	s_nop 1
	v_cvt_pk_bf16_f32 v120, v126, v127
	v_cvt_pk_bf16_f32 v121, v124, v125
	global_store_dwordx2 v[138:139], v[120:121], off offset:512
	v_pk_mul_f32 v[120:121], v[172:173], v[176:177] op_sel_hi:[1,0]
	v_pk_mul_f32 v[122:123], v[174:175], v[176:177] op_sel_hi:[1,0]
	v_pk_fma_f32 v[120:121], v[10:11], v[120:121], v[14:15]
	v_pk_fma_f32 v[122:123], v[8:9], v[122:123], v[12:13]
	global_store_dwordx4 v[142:143], v[116:119], off offset:2048 nt
	v_lshlrev_b32_e32 v126, 16, v160
	v_and_b32_e32 v127, 0xffff0000, v160
	v_cvt_pk_bf16_f32 v116, v122, v123
	v_cvt_pk_bf16_f32 v117, v120, v121
	global_store_dwordx2 v[138:139], v[116:117], off offset:1024
	v_pk_mul_f32 v[116:117], v[168:169], v[176:177] op_sel_hi:[1,0]
	v_pk_mul_f32 v[118:119], v[170:171], v[176:177] op_sel_hi:[1,0]
	v_pk_fma_f32 v[116:117], v[2:3], v[116:117], v[6:7]
	v_pk_fma_f32 v[118:119], v[0:1], v[118:119], v[4:5]
	global_store_dwordx4 v[142:143], v[112:115], off offset:3072 nt
	v_lshlrev_b32_e32 v120, 16, v165
	v_and_b32_e32 v121, 0xffff0000, v165
	v_cvt_pk_bf16_f32 v112, v118, v119
	v_cvt_pk_bf16_f32 v113, v116, v117
	global_store_dwordx2 v[138:139], v[112:113], off offset:1536
	global_load_dwordx2 v[112:113], v[140:141], off offset:8
	v_lshlrev_b32_e32 v114, 16, v166
	v_and_b32_e32 v115, 0xffff0000, v166
	v_lshlrev_b32_e32 v118, 16, v164
	v_and_b32_e32 v119, 0xffff0000, v164
	v_lshlrev_b32_e32 v116, 16, v167
	v_and_b32_e32 v117, 0xffff0000, v167
	v_lshlrev_b32_e32 v122, 16, v162
	v_and_b32_e32 v123, 0xffff0000, v162
	v_lshlrev_b32_e32 v124, 16, v163
	v_and_b32_e32 v125, 0xffff0000, v163
	v_lshlrev_b32_e32 v160, 16, v161
	v_and_b32_e32 v161, 0xffff0000, v161
	s_waitcnt vmcnt(0)
	v_sub_f32_e32 v109, v109, v112
	v_sub_f32_e32 v108, v108, v112
	v_sub_f32_e32 v105, v105, v112
	v_sub_f32_e32 v104, v104, v112
	v_sub_f32_e32 v111, v111, v112
	v_sub_f32_e32 v110, v110, v112
	v_sub_f32_e32 v107, v107, v112
	v_sub_f32_e32 v106, v106, v112
	v_pk_mul_f32 v[108:109], v[112:113], v[108:109] op_sel:[1,0]
	v_pk_mul_f32 v[104:105], v[112:113], v[104:105] op_sel:[1,0]
	v_pk_mul_f32 v[110:111], v[112:113], v[110:111] op_sel:[1,0]
	v_pk_mul_f32 v[106:107], v[112:113], v[106:107] op_sel:[1,0]
	v_pk_fma_f32 v[108:109], v[56:57], v[108:109], v[60:61]
	v_pk_fma_f32 v[104:105], v[64:65], v[104:105], v[68:69]
	v_sub_f32_e32 v101, v101, v112
	v_sub_f32_e32 v100, v100, v112
	v_sub_f32_e32 v103, v103, v112
	v_sub_f32_e32 v102, v102, v112
	v_sub_f32_e32 v97, v97, v112
	v_sub_f32_e32 v96, v96, v112
	v_sub_f32_e32 v99, v99, v112
	v_sub_f32_e32 v98, v98, v112
	v_pk_fma_f32 v[110:111], v[58:59], v[110:111], v[62:63]
	v_pk_fma_f32 v[106:107], v[66:67], v[106:107], v[70:71]
	v_pk_fma_f32 v[108:109], v[108:109], s[52:53], v[114:115] op_sel_hi:[1,0,1]
	v_pk_fma_f32 v[104:105], v[104:105], s[52:53], v[118:119] op_sel_hi:[1,0,1]
	v_pk_mul_f32 v[102:103], v[112:113], v[102:103] op_sel:[1,0]
	v_pk_mul_f32 v[100:101], v[112:113], v[100:101] op_sel:[1,0]
	v_pk_mul_f32 v[98:99], v[112:113], v[98:99] op_sel:[1,0]
	v_pk_mul_f32 v[96:97], v[112:113], v[96:97] op_sel:[1,0]
	v_pk_fma_f32 v[110:111], v[110:111], s[52:53], v[116:117] op_sel_hi:[1,0,1]
	v_pk_fma_f32 v[106:107], v[106:107], s[52:53], v[120:121] op_sel_hi:[1,0,1]
	v_mov_b32_e32 v112, v104
	v_mov_b32_e32 v113, v108
	v_mov_b32_e32 v114, v105
	v_mov_b32_e32 v115, v109
	v_pk_add_f32 v[112:113], v[112:113], v[114:115]
	v_mov_b32_e32 v114, v106
	v_mov_b32_e32 v115, v110
	v_pk_add_f32 v[112:113], v[114:115], v[112:113]
	v_mov_b32_e32 v114, v107
	v_mov_b32_e32 v115, v111
	v_pk_fma_f32 v[100:101], v[72:73], v[100:101], v[76:77]
	v_pk_fma_f32 v[96:97], v[48:49], v[96:97], v[52:53]
	v_pk_add_f32 v[112:113], v[114:115], v[112:113]
	v_pk_fma_f32 v[102:103], v[74:75], v[102:103], v[78:79]
	v_pk_fma_f32 v[98:99], v[50:51], v[98:99], v[54:55]
	v_pk_fma_f32 v[100:101], v[100:101], s[52:53], v[122:123] op_sel_hi:[1,0,1]
	v_pk_fma_f32 v[96:97], v[96:97], s[52:53], v[126:127] op_sel_hi:[1,0,1]
	v_add_f32_e32 v113, 0, v113
	v_pk_fma_f32 v[102:103], v[102:103], s[52:53], v[124:125] op_sel_hi:[1,0,1]
	v_pk_fma_f32 v[98:99], v[98:99], s[52:53], v[160:161] op_sel_hi:[1,0,1]
	v_add_f32_e32 v116, v112, v113
	v_mov_b32_e32 v112, v96
	v_mov_b32_e32 v113, v100
	v_mov_b32_e32 v114, v97
	v_mov_b32_e32 v115, v101
	v_pk_add_f32 v[112:113], v[112:113], v[114:115]
	v_mov_b32_e32 v114, v98
	v_mov_b32_e32 v115, v102
	v_pk_add_f32 v[112:113], v[114:115], v[112:113]
	v_mov_b32_e32 v114, v99
	v_mov_b32_e32 v115, v103
	v_pk_add_f32 v[112:113], v[114:115], v[112:113]
	s_nop 0
	v_add_f32_e32 v113, v113, v116
	v_add_f32_e32 v112, v112, v113
	v_mbcnt_lo_u32_b32 v113, s2, 0
	v_mbcnt_hi_u32_b32 v113, s2, v113
	v_lshlrev_b32_e32 v113, 2, v113
	v_xor_b32_e32 v114, 0x80, v113
	ds_bpermute_b32 v114, v114, v112
	s_mov_b32 s2, -1
	s_waitcnt lgkmcnt(0)
	v_add_f32_e32 v112, v112, v114
	v_xor_b32_e32 v114, 64, v113
	ds_bpermute_b32 v114, v114, v112
	s_waitcnt lgkmcnt(0)
; DEVFI int lane_opaque() { unsigned m = ~0u; asm volatile("" : "+s"(m)); return (int)__builtin_amdgcn_mbcnt_hi(m, __builtin_amdgcn_mbcnt_lo(m, 0u)); }
; DEVFI float shx(float v, int mask, int lane) { return __int_as_float(__builtin_amdgcn_ds_bpermute((lane ^ mask) << 2, __float_as_int(v))); }
; DEVFI float red64(float v) {
;   const int ln = lane_opaque();
;   v += shx(v, 32, ln); v += shx(v, 16, ln); v += shx(v, 8, ln); v += shx(v, 4, ln); v += shx(v, 2, ln); v += shx(v, 1, ln); return v;
; }
; DEVFI void ln_resid4(const float* ysrc, float* ydst, bfraw* fb, float* stats, const float* pw, const float* pb,
;                      const float* w, const float* b, int lane, bool fin) {
;     ...
;   for (int r = 0; r < 4; ++r) {
;     const float pmu = stats[r * 2], prs = stats[r * 2 + 1];
;     f32x4 y[4];
; #pragma unroll
;     for (int i = 0; i < 4; ++i) { const unsigned f0 = fv[r][i][0], f1 = fv[r][i][1];
;       const f32x4 f4 = {__uint_as_float(f0 << 16), __uint_as_float(f0 & 0xffff0000u), __uint_as_float(f1 << 16), __uint_as_float(f1 & 0xffff0000u)};
;       y[i] = ALPHA * ((v[r][i] - pmu) * prs * pwv[i] + pbv[i]) + f4; }
;     float s = 0;
; #pragma unroll
;     for (int i = 0; i < 4; ++i) s += y[i][0] + y[i][1] + y[i][2] + y[i][3];
;     const float mean = red64(s) * (1.f / 1024.f);
;     float q = 0;
; #pragma unroll
;     for (int i = 0; i < 4; ++i) { const f32x4 d = y[i] - mean; q += d[0] * d[0] + d[1] * d[1] + d[2] * d[2] + d[3] * d[3]; }
;     const float rstd = 1.f / sqrtf(red64(q) * (1.f / 1024.f) + LN_EPS);
;     if (lane == 0) { stats[r * 2] = mean; stats[r * 2 + 1] = rstd; }
; #pragma unroll
;     for (int i = 0; i < 4; ++i) { const int c4 = i * 64 + lane;
;       const f32x4 z = (y[i] - mean) * rstd * ww[i] + bb[i];
;       __builtin_nontemporal_store(fin ? z : y[i], (f32x4*)(ydst + r * 1024) + c4);
;       u32x2 pk = {cvtpk(z[0], z[1]), cvtpk(z[2], z[3])}; ((u32x2*)(fb + r * 1024))[c4] = pk; }
	v_add_f32_e32 v112, v112, v114
	v_xor_b32_e32 v114, 32, v113
	s_nop 1
	v_mov_b32_dpp v114, v112 row_ror:8 row_mask:0xf bank_mask:0xf
	s_waitcnt lgkmcnt(0)
	v_add_f32_e32 v112, v112, v114
	v_xor_b32_e32 v114, 16, v113
	s_nop 1
	v_mov_b32_dpp v114, v112 row_half_mirror row_mask:0xf bank_mask:0xf
	s_nop 1
	v_mov_b32_dpp v114, v114 quad_perm:[3,2,1,0] row_mask:0xf bank_mask:0xf
	s_waitcnt lgkmcnt(0)
	v_add_f32_e32 v112, v112, v114
	v_xor_b32_e32 v114, 8, v113
	s_nop 1
	v_mov_b32_dpp v114, v112 quad_perm:[2,3,0,1] row_mask:0xf bank_mask:0xf
	v_xor_b32_e32 v113, 4, v113
	s_waitcnt lgkmcnt(0)
	v_add_f32_e32 v112, v112, v114
	s_nop 1
	v_mov_b32_dpp v113, v112 quad_perm:[1,0,3,2] row_mask:0xf bank_mask:0xf
	s_waitcnt lgkmcnt(0)
	v_add_f32_e32 v129, v112, v113
	v_fmamk_f32 v127, v129, 0xba800000, v109
	v_fmamk_f32 v123, v129, 0xba800000, v105
	v_fmamk_f32 v126, v129, 0xba800000, v108
	v_mul_f32_e32 v112, v127, v127
	v_fmamk_f32 v122, v129, 0xba800000, v104
	v_mul_f32_e32 v113, v123, v123
	v_fmamk_f32 v124, v129, 0xba800000, v110
	v_fmac_f32_e32 v112, v126, v126
	v_fmamk_f32 v120, v129, 0xba800000, v106
	v_fmac_f32_e32 v113, v122, v122
	v_fmamk_f32 v125, v129, 0xba800000, v111
	v_fmac_f32_e32 v112, v124, v124
	v_fmamk_f32 v121, v129, 0xba800000, v107
	v_fmac_f32_e32 v113, v120, v120
	v_fmac_f32_e32 v112, v125, v125
	v_fmac_f32_e32 v113, v121, v121
	v_fmamk_f32 v119, v129, 0xba800000, v101
	v_add_f32_e32 v112, v112, v113
	v_fmamk_f32 v118, v129, 0xba800000, v100
	v_mul_f32_e32 v113, v119, v119
	v_fmamk_f32 v116, v129, 0xba800000, v102
	v_fmac_f32_e32 v113, v118, v118
	v_fmamk_f32 v117, v129, 0xba800000, v103
	v_fmac_f32_e32 v113, v116, v116
	v_fmamk_f32 v115, v129, 0xba800000, v97
	v_fmac_f32_e32 v113, v117, v117
	v_fmamk_f32 v114, v129, 0xba800000, v96
	v_mul_f32_e32 v161, v115, v115
	v_add_f32_e32 v160, v113, v112
	v_fmamk_f32 v112, v129, 0xba800000, v98
	v_fmac_f32_e32 v161, v114, v114
	v_fmamk_f32 v113, v129, 0xba800000, v99
	v_fmac_f32_e32 v161, v112, v112
	v_fmac_f32_e32 v161, v113, v113
	v_add_f32_e32 v160, v161, v160
	v_mbcnt_lo_u32_b32 v161, s2, 0
	v_mbcnt_hi_u32_b32 v161, s2, v161
	v_lshlrev_b32_e32 v161, 2, v161
	v_xor_b32_e32 v162, 0x80, v161
	ds_bpermute_b32 v162, v162, v160
	s_waitcnt lgkmcnt(0)
	v_add_f32_e32 v160, v160, v162
	v_xor_b32_e32 v162, 64, v161
	ds_bpermute_b32 v162, v162, v160
	s_waitcnt lgkmcnt(0)
	v_add_f32_e32 v160, v160, v162
	v_xor_b32_e32 v162, 32, v161
	s_nop 1
	v_mov_b32_dpp v162, v160 row_ror:8 row_mask:0xf bank_mask:0xf
	s_waitcnt lgkmcnt(0)
	v_add_f32_e32 v160, v160, v162
	v_xor_b32_e32 v162, 16, v161
	s_nop 1
	v_mov_b32_dpp v162, v160 row_half_mirror row_mask:0xf bank_mask:0xf
	s_nop 1
	v_mov_b32_dpp v162, v162 quad_perm:[3,2,1,0] row_mask:0xf bank_mask:0xf
	s_waitcnt lgkmcnt(0)
	v_add_f32_e32 v160, v160, v162
	v_xor_b32_e32 v162, 8, v161
	s_nop 1
	v_mov_b32_dpp v162, v160 quad_perm:[2,3,0,1] row_mask:0xf bank_mask:0xf
	v_xor_b32_e32 v161, 4, v161
	s_waitcnt lgkmcnt(0)
	v_add_f32_e32 v160, v160, v162
	s_nop 1
	v_mov_b32_dpp v161, v160 quad_perm:[1,0,3,2] row_mask:0xf bank_mask:0xf
	s_waitcnt lgkmcnt(0)
	v_add_f32_e32 v160, v160, v161
	v_fmamk_f32 v160, v160, 0x3a800000, v183
	v_mul_f32_e32 v161, 0x4f800000, v160
	v_cmp_gt_f32_e32 vcc, s30, v160
	s_nop 1
	v_cndmask_b32_e32 v160, v160, v161, vcc
	v_sqrt_f32_e32 v161, v160
	s_nop 0
	v_add_u32_e32 v162, -1, v161
	v_fma_f32 v163, -v162, v161, v160
	v_cmp_ge_f32_e64 s[8:9], 0, v163
	v_add_u32_e32 v163, 1, v161
	s_nop 0
	v_cndmask_b32_e64 v162, v161, v162, s[8:9]
	v_fma_f32 v161, -v163, v161, v160
	v_cmp_lt_f32_e64 s[8:9], 0, v161
	s_nop 1
	v_cndmask_b32_e64 v161, v162, v163, s[8:9]
	v_mul_f32_e32 v162, 0x37800000, v161
	v_cndmask_b32_e32 v161, v161, v162, vcc
	v_cmp_class_f32_e32 vcc, v160, v222
	s_nop 1
	v_cndmask_b32_e32 v160, v161, v160, vcc
	s_nop 0
	v_rcp_f32_e32 v162, v160
	s_nop 0
	v_fma_f32 v161, -v160, v162, 1.0
	v_fma_f32 v161, v161, v162, v162
	v_div_fixup_f32 v160, v161, v160, 1.0
	s_and_saveexec_b64 s[2:3], s[6:7]
	s_cbranch_execz .LBB0_4344
	v_mul_f32_e32 v162, 0x3a800000, v129
	v_mov_b32_e32 v163, v160
	global_store_dwordx2 v[140:141], v[162:163], off offset:8
.LBB0_4344:
	s_or_b64 exec, exec, s[2:3]
	s_mov_b64 s[2:3], 0x1000
	v_lshl_add_u64 v[162:163], v[142:143], 0, s[2:3]
	v_pk_mul_f32 v[124:125], v[124:125], v[160:161] op_sel_hi:[1,0]
	v_pk_mul_f32 v[126:127], v[126:127], v[160:161] op_sel_hi:[1,0]
	s_mov_b64 s[2:3], 0x1400
	v_pk_fma_f32 v[124:125], v[26:27], v[124:125], v[30:31]
	v_pk_fma_f32 v[126:127], v[24:25], v[126:127], v[28:29]
	global_store_dwordx4 v[162:163], v[108:111], off nt
	v_lshl_add_u64 v[164:165], v[142:143], 0, s[2:3]
	s_mov_b64 s[2:3], 0x1800
	v_cvt_pk_bf16_f32 v108, v126, v127
	v_cvt_pk_bf16_f32 v109, v124, v125
	global_store_dwordx2 v[138:139], v[108:109], off offset:2048
	v_pk_mul_f32 v[108:109], v[120:121], v[160:161] op_sel_hi:[1,0]
	v_pk_mul_f32 v[110:111], v[122:123], v[160:161] op_sel_hi:[1,0]
	v_pk_fma_f32 v[108:109], v[18:19], v[108:109], v[22:23]
	v_pk_fma_f32 v[110:111], v[16:17], v[110:111], v[20:21]
	global_store_dwordx4 v[164:165], v[104:107], off nt
	v_lshl_add_u64 v[166:167], v[142:143], 0, s[2:3]
	s_mov_b64 s[2:3], 0x1c00
	v_cvt_pk_bf16_f32 v104, v110, v111
	v_cvt_pk_bf16_f32 v105, v108, v109
	global_store_dwordx2 v[138:139], v[104:105], off offset:2560
	v_pk_mul_f32 v[104:105], v[116:117], v[160:161] op_sel_hi:[1,0]
	v_pk_mul_f32 v[106:107], v[118:119], v[160:161] op_sel_hi:[1,0]
	v_pk_fma_f32 v[104:105], v[10:11], v[104:105], v[14:15]
	v_pk_fma_f32 v[106:107], v[8:9], v[106:107], v[12:13]
	global_store_dwordx4 v[166:167], v[100:103], off nt
	v_lshl_add_u64 v[168:169], v[142:143], 0, s[2:3]
	v_lshlrev_b32_e32 v110, 16, v152
	v_cvt_pk_bf16_f32 v100, v106, v107
	v_cvt_pk_bf16_f32 v101, v104, v105
	global_store_dwordx2 v[138:139], v[100:101], off offset:3072
	v_pk_mul_f32 v[100:101], v[112:113], v[160:161] op_sel_hi:[1,0]
	v_pk_mul_f32 v[102:103], v[114:115], v[160:161] op_sel_hi:[1,0]
	v_pk_fma_f32 v[100:101], v[2:3], v[100:101], v[6:7]
	v_pk_fma_f32 v[102:103], v[0:1], v[102:103], v[4:5]
	global_store_dwordx4 v[168:169], v[96:99], off nt
	v_lshlrev_b32_e32 v104, 16, v157
	v_and_b32_e32 v105, 0xffff0000, v157
	v_cvt_pk_bf16_f32 v96, v102, v103
	v_cvt_pk_bf16_f32 v97, v100, v101
	global_store_dwordx2 v[138:139], v[96:97], off offset:3584
	global_load_dwordx2 v[96:97], v[140:141], off offset:16
	v_lshlrev_b32_e32 v98, 16, v158
	v_and_b32_e32 v99, 0xffff0000, v158
	v_lshlrev_b32_e32 v102, 16, v156
	v_and_b32_e32 v103, 0xffff0000, v156
	v_lshlrev_b32_e32 v100, 16, v159
	v_and_b32_e32 v101, 0xffff0000, v159
	v_lshlrev_b32_e32 v106, 16, v154
	v_and_b32_e32 v107, 0xffff0000, v154
	v_and_b32_e32 v111, 0xffff0000, v152
	v_lshlrev_b32_e32 v108, 16, v155
	v_and_b32_e32 v109, 0xffff0000, v155
	v_lshlrev_b32_e32 v112, 16, v153
	v_and_b32_e32 v113, 0xffff0000, v153
	s_mov_b32 s2, -1
	s_waitcnt vmcnt(0)
; DEVFI int lane_opaque() { unsigned m = ~0u; asm volatile("" : "+s"(m)); return (int)__builtin_amdgcn_mbcnt_hi(m, __builtin_amdgcn_mbcnt_lo(m, 0u)); }
; DEVFI float shx(float v, int mask, int lane) { return __int_as_float(__builtin_amdgcn_ds_bpermute((lane ^ mask) << 2, __float_as_int(v))); }
; DEVFI float red64(float v) {
;   const int ln = lane_opaque();
;   v += shx(v, 32, ln); v += shx(v, 16, ln); v += shx(v, 8, ln); v += shx(v, 4, ln); v += shx(v, 2, ln); v += shx(v, 1, ln); return v;
; }
; DEVFI void ln_resid4(const float* ysrc, float* ydst, bfraw* fb, float* stats, const float* pw, const float* pb,
;                      const float* w, const float* b, int lane, bool fin) {
;     ...
;     for (int i = 0; i < 4; ++i) { const unsigned f0 = fv[r][i][0], f1 = fv[r][i][1];
;       const f32x4 f4 = {__uint_as_float(f0 << 16), __uint_as_float(f0 & 0xffff0000u), __uint_as_float(f1 << 16), __uint_as_float(f1 & 0xffff0000u)};
;       y[i] = ALPHA * ((v[r][i] - pmu) * prs * pwv[i] + pbv[i]) + f4; }
;     float s = 0;
; #pragma unroll
;     for (int i = 0; i < 4; ++i) s += y[i][0] + y[i][1] + y[i][2] + y[i][3];
;     const float mean = red64(s) * (1.f / 1024.f);
;     float q = 0;
; #pragma unroll
;     for (int i = 0; i < 4; ++i) { const f32x4 d = y[i] - mean; q += d[0] * d[0] + d[1] * d[1] + d[2] * d[2] + d[3] * d[3]; }
;     const float rstd = 1.f / sqrtf(red64(q) * (1.f / 1024.f) + LN_EPS);
;     if (lane == 0) { stats[r * 2] = mean; stats[r * 2 + 1] = rstd; }
	v_sub_f32_e32 v93, v93, v96
	v_sub_f32_e32 v92, v92, v96
	v_sub_f32_e32 v89, v89, v96
	v_sub_f32_e32 v88, v88, v96
	v_sub_f32_e32 v95, v95, v96
	v_sub_f32_e32 v94, v94, v96
	v_sub_f32_e32 v91, v91, v96
	v_sub_f32_e32 v90, v90, v96
	v_pk_mul_f32 v[92:93], v[96:97], v[92:93] op_sel:[1,0]
	v_pk_mul_f32 v[88:89], v[96:97], v[88:89] op_sel:[1,0]
	v_pk_mul_f32 v[94:95], v[96:97], v[94:95] op_sel:[1,0]
	v_pk_mul_f32 v[90:91], v[96:97], v[90:91] op_sel:[1,0]
	v_pk_fma_f32 v[92:93], v[56:57], v[92:93], v[60:61]
	v_pk_fma_f32 v[88:89], v[64:65], v[88:89], v[68:69]
	v_sub_f32_e32 v85, v85, v96
	v_sub_f32_e32 v84, v84, v96
	v_sub_f32_e32 v87, v87, v96
	v_sub_f32_e32 v86, v86, v96
	v_sub_f32_e32 v81, v81, v96
	v_sub_f32_e32 v80, v80, v96
	v_sub_f32_e32 v83, v83, v96
	v_sub_f32_e32 v82, v82, v96
	v_pk_fma_f32 v[94:95], v[58:59], v[94:95], v[62:63]
	v_pk_fma_f32 v[90:91], v[66:67], v[90:91], v[70:71]
	v_pk_fma_f32 v[92:93], v[92:93], s[52:53], v[98:99] op_sel_hi:[1,0,1]
	v_pk_fma_f32 v[88:89], v[88:89], s[52:53], v[102:103] op_sel_hi:[1,0,1]
	v_pk_mul_f32 v[86:87], v[96:97], v[86:87] op_sel:[1,0]
	v_pk_mul_f32 v[84:85], v[96:97], v[84:85] op_sel:[1,0]
	v_pk_mul_f32 v[82:83], v[96:97], v[82:83] op_sel:[1,0]
	v_pk_mul_f32 v[80:81], v[96:97], v[80:81] op_sel:[1,0]
	v_pk_fma_f32 v[94:95], v[94:95], s[52:53], v[100:101] op_sel_hi:[1,0,1]
	v_pk_fma_f32 v[90:91], v[90:91], s[52:53], v[104:105] op_sel_hi:[1,0,1]
	v_mov_b32_e32 v96, v88
	v_mov_b32_e32 v97, v92
	v_mov_b32_e32 v98, v89
	v_mov_b32_e32 v99, v93
	v_pk_add_f32 v[96:97], v[96:97], v[98:99]
	v_mov_b32_e32 v98, v90
	v_mov_b32_e32 v99, v94
	v_pk_add_f32 v[96:97], v[98:99], v[96:97]
	v_mov_b32_e32 v98, v91
	v_mov_b32_e32 v99, v95
	v_pk_fma_f32 v[84:85], v[72:73], v[84:85], v[76:77]
	v_pk_fma_f32 v[80:81], v[48:49], v[80:81], v[52:53]
	v_pk_add_f32 v[96:97], v[98:99], v[96:97]
	v_pk_fma_f32 v[86:87], v[74:75], v[86:87], v[78:79]
	v_pk_fma_f32 v[82:83], v[50:51], v[82:83], v[54:55]
	v_pk_fma_f32 v[84:85], v[84:85], s[52:53], v[106:107] op_sel_hi:[1,0,1]
	v_pk_fma_f32 v[80:81], v[80:81], s[52:53], v[110:111] op_sel_hi:[1,0,1]
	v_add_f32_e32 v97, 0, v97
	v_pk_fma_f32 v[86:87], v[86:87], s[52:53], v[108:109] op_sel_hi:[1,0,1]
	v_pk_fma_f32 v[82:83], v[82:83], s[52:53], v[112:113] op_sel_hi:[1,0,1]
	v_add_f32_e32 v100, v96, v97
	v_mov_b32_e32 v96, v80
	v_mov_b32_e32 v97, v84
	v_mov_b32_e32 v98, v81
	v_mov_b32_e32 v99, v85
	v_pk_add_f32 v[96:97], v[96:97], v[98:99]
	v_mov_b32_e32 v98, v82
	v_mov_b32_e32 v99, v86
	v_pk_add_f32 v[96:97], v[98:99], v[96:97]
	v_mov_b32_e32 v98, v83
	v_mov_b32_e32 v99, v87
	v_pk_add_f32 v[96:97], v[98:99], v[96:97]
	s_nop 0
	v_add_f32_e32 v97, v97, v100
	v_add_f32_e32 v96, v96, v97
	v_mbcnt_lo_u32_b32 v97, s2, 0
	v_mbcnt_hi_u32_b32 v97, s2, v97
	v_lshlrev_b32_e32 v97, 2, v97
	v_xor_b32_e32 v98, 0x80, v97
	ds_bpermute_b32 v98, v98, v96
	s_mov_b32 s2, -1
	s_waitcnt lgkmcnt(0)
	v_add_f32_e32 v96, v96, v98
	v_xor_b32_e32 v98, 64, v97
	ds_bpermute_b32 v98, v98, v96
	s_waitcnt lgkmcnt(0)
	v_add_f32_e32 v96, v96, v98
	v_xor_b32_e32 v98, 32, v97
	s_nop 1
	v_mov_b32_dpp v98, v96 row_ror:8 row_mask:0xf bank_mask:0xf
	s_waitcnt lgkmcnt(0)
	v_add_f32_e32 v96, v96, v98
	v_xor_b32_e32 v98, 16, v97
	s_nop 1
	v_mov_b32_dpp v98, v96 row_half_mirror row_mask:0xf bank_mask:0xf
	s_nop 1
	v_mov_b32_dpp v98, v98 quad_perm:[3,2,1,0] row_mask:0xf bank_mask:0xf
	s_waitcnt lgkmcnt(0)
	v_add_f32_e32 v96, v96, v98
	v_xor_b32_e32 v98, 8, v97
	s_nop 1
	v_mov_b32_dpp v98, v96 quad_perm:[2,3,0,1] row_mask:0xf bank_mask:0xf
	v_xor_b32_e32 v97, 4, v97
	s_waitcnt lgkmcnt(0)
	v_add_f32_e32 v96, v96, v98
	s_nop 1
	v_mov_b32_dpp v97, v96 quad_perm:[1,0,3,2] row_mask:0xf bank_mask:0xf
	s_waitcnt lgkmcnt(0)
	v_add_f32_e32 v113, v96, v97
	v_fmamk_f32 v111, v113, 0xba800000, v93
	v_fmamk_f32 v107, v113, 0xba800000, v89
	v_fmamk_f32 v110, v113, 0xba800000, v92
	v_mul_f32_e32 v96, v111, v111
	v_fmamk_f32 v106, v113, 0xba800000, v88
	v_mul_f32_e32 v97, v107, v107
	v_fmamk_f32 v108, v113, 0xba800000, v94
	v_fmac_f32_e32 v96, v110, v110
	v_fmamk_f32 v104, v113, 0xba800000, v90
	v_fmac_f32_e32 v97, v106, v106
	v_fmamk_f32 v109, v113, 0xba800000, v95
	v_fmac_f32_e32 v96, v108, v108
	v_fmamk_f32 v105, v113, 0xba800000, v91
	v_fmac_f32_e32 v97, v104, v104
	v_fmac_f32_e32 v96, v109, v109
	v_fmac_f32_e32 v97, v105, v105
	v_fmamk_f32 v103, v113, 0xba800000, v85
	v_add_f32_e32 v96, v96, v97
	v_fmamk_f32 v102, v113, 0xba800000, v84
	v_mul_f32_e32 v97, v103, v103
	v_fmamk_f32 v100, v113, 0xba800000, v86
	v_fmac_f32_e32 v97, v102, v102
	v_fmamk_f32 v101, v113, 0xba800000, v87
	v_fmac_f32_e32 v97, v100, v100
	v_fmamk_f32 v99, v113, 0xba800000, v81
	v_fmac_f32_e32 v97, v101, v101
	v_fmamk_f32 v98, v113, 0xba800000, v80
	v_mul_f32_e32 v114, v99, v99
	v_add_f32_e32 v112, v97, v96
	v_fmamk_f32 v96, v113, 0xba800000, v82
	v_fmac_f32_e32 v114, v98, v98
	v_fmamk_f32 v97, v113, 0xba800000, v83
	v_fmac_f32_e32 v114, v96, v96
	v_fmac_f32_e32 v114, v97, v97
	v_add_f32_e32 v112, v114, v112
	v_mbcnt_lo_u32_b32 v114, s2, 0
	v_mbcnt_hi_u32_b32 v114, s2, v114
	v_lshlrev_b32_e32 v114, 2, v114
	v_xor_b32_e32 v115, 0x80, v114
	ds_bpermute_b32 v115, v115, v112
	s_waitcnt lgkmcnt(0)
	v_add_f32_e32 v112, v112, v115
	v_xor_b32_e32 v115, 64, v114
	ds_bpermute_b32 v115, v115, v112
	s_waitcnt lgkmcnt(0)
	v_add_f32_e32 v112, v112, v115
	v_xor_b32_e32 v115, 32, v114
	s_nop 1
	v_mov_b32_dpp v115, v112 row_ror:8 row_mask:0xf bank_mask:0xf
	s_waitcnt lgkmcnt(0)
	v_add_f32_e32 v112, v112, v115
	v_xor_b32_e32 v115, 16, v114
	s_nop 1
	v_mov_b32_dpp v115, v112 row_half_mirror row_mask:0xf bank_mask:0xf
	s_nop 1
	v_mov_b32_dpp v115, v115 quad_perm:[3,2,1,0] row_mask:0xf bank_mask:0xf
	s_waitcnt lgkmcnt(0)
	v_add_f32_e32 v112, v112, v115
	v_xor_b32_e32 v115, 8, v114
	s_nop 1
	v_mov_b32_dpp v115, v112 quad_perm:[2,3,0,1] row_mask:0xf bank_mask:0xf
	v_xor_b32_e32 v114, 4, v114
	s_waitcnt lgkmcnt(0)
	v_add_f32_e32 v112, v112, v115
	s_nop 1
	v_mov_b32_dpp v114, v112 quad_perm:[1,0,3,2] row_mask:0xf bank_mask:0xf
	s_waitcnt lgkmcnt(0)
	v_add_f32_e32 v112, v112, v114
	v_fmamk_f32 v112, v112, 0x3a800000, v183
	v_mul_f32_e32 v114, 0x4f800000, v112
	v_cmp_gt_f32_e32 vcc, s30, v112
	s_nop 1
	v_cndmask_b32_e32 v112, v112, v114, vcc
	v_sqrt_f32_e32 v114, v112
	s_nop 0
	v_add_u32_e32 v115, -1, v114
	v_fma_f32 v116, -v115, v114, v112
	v_cmp_ge_f32_e64 s[8:9], 0, v116
	v_add_u32_e32 v116, 1, v114
	s_nop 0
	v_cndmask_b32_e64 v115, v114, v115, s[8:9]
	v_fma_f32 v114, -v116, v114, v112
	v_cmp_lt_f32_e64 s[8:9], 0, v114
	s_nop 1
	v_cndmask_b32_e64 v114, v115, v116, s[8:9]
	v_mul_f32_e32 v115, 0x37800000, v114
	v_cndmask_b32_e32 v114, v114, v115, vcc
	v_cmp_class_f32_e32 vcc, v112, v222
	s_nop 1
	v_cndmask_b32_e32 v112, v114, v112, vcc
	s_nop 0
	v_rcp_f32_e32 v115, v112
	s_nop 0
	v_fma_f32 v114, -v112, v115, 1.0
	v_fma_f32 v114, v114, v115, v115
	v_div_fixup_f32 v112, v114, v112, 1.0
	s_mov_b64 s[2:3], exec
	s_and_b64 s[8:9], s[2:3], s[6:7]
	v_mov_b32_e32 v182, v192
	s_mov_b64 exec, s[8:9]
	s_cbranch_execz .LBB0_4346
; DEVFI void ln_resid4(const float* ysrc, float* ydst, bfraw* fb, float* stats, const float* pw, const float* pb,
;                      const float* w, const float* b, int lane, bool fin) {
;     ...
;   for (int r = 0; r < 4; ++r) {
;     const float pmu = stats[r * 2], prs = stats[r * 2 + 1];
;     f32x4 y[4];
; #pragma unroll
;     for (int i = 0; i < 4; ++i) { const unsigned f0 = fv[r][i][0], f1 = fv[r][i][1];
;       const f32x4 f4 = {__uint_as_float(f0 << 16), __uint_as_float(f0 & 0xffff0000u), __uint_as_float(f1 << 16), __uint_as_float(f1 & 0xffff0000u)};
;       y[i] = ALPHA * ((v[r][i] - pmu) * prs * pwv[i] + pbv[i]) + f4; }
;     float s = 0;
; #pragma unroll
;     for (int i = 0; i < 4; ++i) s += y[i][0] + y[i][1] + y[i][2] + y[i][3];
;     const float mean = red64(s) * (1.f / 1024.f);
;     float q = 0;
; #pragma unroll
;     for (int i = 0; i < 4; ++i) { const f32x4 d = y[i] - mean; q += d[0] * d[0] + d[1] * d[1] + d[2] * d[2] + d[3] * d[3]; }
;     const float rstd = 1.f / sqrtf(red64(q) * (1.f / 1024.f) + LN_EPS);
;     if (lane == 0) { stats[r * 2] = mean; stats[r * 2 + 1] = rstd; }
; #pragma unroll
;     for (int i = 0; i < 4; ++i) { const int c4 = i * 64 + lane;
;       const f32x4 z = (y[i] - mean) * rstd * ww[i] + bb[i];
;       __builtin_nontemporal_store(fin ? z : y[i], (f32x4*)(ydst + r * 1024) + c4);
;       u32x2 pk = {cvtpk(z[0], z[1]), cvtpk(z[2], z[3])}; ((u32x2*)(fb + r * 1024))[c4] = pk; }
	v_mul_f32_e32 v114, 0x3a800000, v113
	v_mov_b32_e32 v115, v112
	global_store_dwordx2 v[140:141], v[114:115], off offset:16
.LBB0_4346:
	s_or_b64 exec, exec, s[2:3]
	s_mov_b64 s[2:3], 0x2000
	v_lshl_add_u64 v[114:115], v[142:143], 0, s[2:3]
	s_mov_b64 s[2:3], 0x2400
	v_lshl_add_u64 v[116:117], v[142:143], 0, s[2:3]
	s_mov_b64 s[2:3], 0x2800
	v_lshl_add_u64 v[118:119], v[142:143], 0, s[2:3]
	s_mov_b64 s[2:3], 0x2c00
	v_lshl_add_u64 v[120:121], v[142:143], 0, s[2:3]
	s_mov_b64 s[2:3], 0x1000
	v_pk_mul_f32 v[108:109], v[108:109], v[112:113] op_sel_hi:[1,0]
	v_pk_mul_f32 v[110:111], v[110:111], v[112:113] op_sel_hi:[1,0]
	v_lshl_add_u64 v[122:123], v[138:139], 0, s[2:3]
	v_pk_fma_f32 v[108:109], v[26:27], v[108:109], v[30:31]
	v_pk_fma_f32 v[110:111], v[24:25], v[110:111], v[28:29]
	global_store_dwordx4 v[114:115], v[92:95], off nt
	s_mov_b64 s[2:3], 0x1200
	v_lshl_add_u64 v[124:125], v[138:139], 0, s[2:3]
	v_cvt_pk_bf16_f32 v92, v110, v111
	v_cvt_pk_bf16_f32 v93, v108, v109
	global_store_dwordx2 v[122:123], v[92:93], off
	v_pk_mul_f32 v[92:93], v[104:105], v[112:113] op_sel_hi:[1,0]
	v_pk_mul_f32 v[94:95], v[106:107], v[112:113] op_sel_hi:[1,0]
	v_pk_fma_f32 v[92:93], v[18:19], v[92:93], v[22:23]
	v_pk_fma_f32 v[94:95], v[16:17], v[94:95], v[20:21]
	global_store_dwordx4 v[116:117], v[88:91], off nt
	s_mov_b64 s[2:3], 0x1400
	v_lshl_add_u64 v[126:127], v[138:139], 0, s[2:3]
	v_cvt_pk_bf16_f32 v88, v94, v95
	v_cvt_pk_bf16_f32 v89, v92, v93
	global_store_dwordx2 v[124:125], v[88:89], off
	v_pk_mul_f32 v[88:89], v[100:101], v[112:113] op_sel_hi:[1,0]
	v_pk_mul_f32 v[90:91], v[102:103], v[112:113] op_sel_hi:[1,0]
	s_mov_b64 s[2:3], 0x1600
	v_pk_fma_f32 v[88:89], v[10:11], v[88:89], v[14:15]
	v_pk_fma_f32 v[90:91], v[8:9], v[90:91], v[12:13]
	global_store_dwordx4 v[118:119], v[84:87], off nt
	v_lshl_add_u64 v[152:153], v[138:139], 0, s[2:3]
	v_lshlrev_b32_e32 v94, 16, v144
	v_cvt_pk_bf16_f32 v84, v90, v91
	v_cvt_pk_bf16_f32 v85, v88, v89
	global_store_dwordx2 v[126:127], v[84:85], off
	v_pk_mul_f32 v[84:85], v[96:97], v[112:113] op_sel_hi:[1,0]
	v_pk_mul_f32 v[86:87], v[98:99], v[112:113] op_sel_hi:[1,0]
	v_pk_fma_f32 v[84:85], v[2:3], v[84:85], v[6:7]
	v_pk_fma_f32 v[86:87], v[0:1], v[86:87], v[4:5]
	global_store_dwordx4 v[120:121], v[80:83], off nt
	v_lshlrev_b32_e32 v88, 16, v149
	v_and_b32_e32 v89, 0xffff0000, v149
	v_cvt_pk_bf16_f32 v80, v86, v87
	v_cvt_pk_bf16_f32 v81, v84, v85
	global_store_dwordx2 v[152:153], v[80:81], off
	global_load_dwordx2 v[80:81], v[140:141], off offset:24
	v_lshlrev_b32_e32 v82, 16, v150
	v_and_b32_e32 v83, 0xffff0000, v150
	v_lshlrev_b32_e32 v86, 16, v148
	v_and_b32_e32 v87, 0xffff0000, v148
	v_lshlrev_b32_e32 v84, 16, v151
	v_and_b32_e32 v85, 0xffff0000, v151
	v_lshlrev_b32_e32 v90, 16, v146
	v_and_b32_e32 v91, 0xffff0000, v146
	v_and_b32_e32 v95, 0xffff0000, v144
	v_lshlrev_b32_e32 v92, 16, v147
	v_and_b32_e32 v93, 0xffff0000, v147
	v_lshlrev_b32_e32 v96, 16, v145
	v_and_b32_e32 v97, 0xffff0000, v145
	s_mov_b32 s2, -1
	s_waitcnt vmcnt(0)
	v_sub_f32_e32 v45, v45, v80
	v_sub_f32_e32 v44, v44, v80
	v_sub_f32_e32 v41, v41, v80
	v_sub_f32_e32 v40, v40, v80
	v_sub_f32_e32 v47, v47, v80
	v_sub_f32_e32 v46, v46, v80
	v_sub_f32_e32 v43, v43, v80
	v_sub_f32_e32 v42, v42, v80
	v_pk_mul_f32 v[44:45], v[80:81], v[44:45] op_sel:[1,0]
	v_pk_mul_f32 v[40:41], v[80:81], v[40:41] op_sel:[1,0]
	v_sub_f32_e32 v33, v33, v80
	v_sub_f32_e32 v32, v32, v80
	v_sub_f32_e32 v35, v35, v80
	v_sub_f32_e32 v34, v34, v80
	v_pk_mul_f32 v[46:47], v[80:81], v[46:47] op_sel:[1,0]
	v_pk_mul_f32 v[42:43], v[80:81], v[42:43] op_sel:[1,0]
	v_pk_fma_f32 v[44:45], v[56:57], v[44:45], v[60:61]
	v_pk_fma_f32 v[40:41], v[64:65], v[40:41], v[68:69]
	v_pk_fma_f32 v[46:47], v[58:59], v[46:47], v[62:63]
	v_pk_fma_f32 v[42:43], v[66:67], v[42:43], v[70:71]
	v_pk_fma_f32 v[44:45], v[44:45], s[52:53], v[82:83] op_sel_hi:[1,0,1]
	v_pk_fma_f32 v[40:41], v[40:41], s[52:53], v[86:87] op_sel_hi:[1,0,1]
	v_pk_mul_f32 v[34:35], v[80:81], v[34:35] op_sel:[1,0]
	v_pk_mul_f32 v[32:33], v[80:81], v[32:33] op_sel:[1,0]
	v_pk_fma_f32 v[46:47], v[46:47], s[52:53], v[84:85] op_sel_hi:[1,0,1]
	v_pk_fma_f32 v[42:43], v[42:43], s[52:53], v[88:89] op_sel_hi:[1,0,1]
	v_pk_fma_f32 v[32:33], v[48:49], v[32:33], v[52:53]
	v_pk_fma_f32 v[34:35], v[50:51], v[34:35], v[54:55]
	v_mov_b32_e32 v48, v40
	v_mov_b32_e32 v49, v44
	v_mov_b32_e32 v50, v41
	v_mov_b32_e32 v51, v45
	v_sub_f32_e32 v37, v37, v80
	v_sub_f32_e32 v36, v36, v80
	v_pk_add_f32 v[48:49], v[48:49], v[50:51]
	v_mov_b32_e32 v50, v42
	v_mov_b32_e32 v51, v46
	v_sub_f32_e32 v39, v39, v80
	v_sub_f32_e32 v38, v38, v80
	v_pk_mul_f32 v[36:37], v[80:81], v[36:37] op_sel:[1,0]
	v_pk_add_f32 v[48:49], v[50:51], v[48:49]
	v_mov_b32_e32 v50, v43
	v_mov_b32_e32 v51, v47
	v_pk_mul_f32 v[38:39], v[80:81], v[38:39] op_sel:[1,0]
	v_pk_fma_f32 v[36:37], v[72:73], v[36:37], v[76:77]
	v_pk_add_f32 v[48:49], v[50:51], v[48:49]
	v_pk_fma_f32 v[38:39], v[74:75], v[38:39], v[78:79]
	v_pk_fma_f32 v[36:37], v[36:37], s[52:53], v[90:91] op_sel_hi:[1,0,1]
	v_pk_fma_f32 v[32:33], v[32:33], s[52:53], v[94:95] op_sel_hi:[1,0,1]
	v_add_f32_e32 v49, 0, v49
	v_pk_fma_f32 v[38:39], v[38:39], s[52:53], v[92:93] op_sel_hi:[1,0,1]
	v_pk_fma_f32 v[34:35], v[34:35], s[52:53], v[96:97] op_sel_hi:[1,0,1]
	v_add_f32_e32 v52, v48, v49
	v_mov_b32_e32 v48, v32
	v_mov_b32_e32 v49, v36
	v_mov_b32_e32 v50, v33
	v_mov_b32_e32 v51, v37
	v_pk_add_f32 v[48:49], v[48:49], v[50:51]
	v_mov_b32_e32 v50, v34
	v_mov_b32_e32 v51, v38
	v_pk_add_f32 v[48:49], v[50:51], v[48:49]
	v_mov_b32_e32 v50, v35
	v_mov_b32_e32 v51, v39
	v_pk_add_f32 v[48:49], v[50:51], v[48:49]
	s_nop 0
	v_add_f32_e32 v49, v49, v52
	v_add_f32_e32 v48, v48, v49
	v_mbcnt_lo_u32_b32 v49, s2, 0
	v_mbcnt_hi_u32_b32 v49, s2, v49
	v_lshlrev_b32_e32 v49, 2, v49
	v_xor_b32_e32 v50, 0x80, v49
	ds_bpermute_b32 v50, v50, v48
	s_mov_b32 s2, -1
	s_waitcnt lgkmcnt(0)
; DEVFI int lane_opaque() { unsigned m = ~0u; asm volatile("" : "+s"(m)); return (int)__builtin_amdgcn_mbcnt_hi(m, __builtin_amdgcn_mbcnt_lo(m, 0u)); }
; DEVFI float shx(float v, int mask, int lane) { return __int_as_float(__builtin_amdgcn_ds_bpermute((lane ^ mask) << 2, __float_as_int(v))); }
; DEVFI float red64(float v) {
;   const int ln = lane_opaque();
;   v += shx(v, 32, ln); v += shx(v, 16, ln); v += shx(v, 8, ln); v += shx(v, 4, ln); v += shx(v, 2, ln); v += shx(v, 1, ln); return v;
; }
; DEVFI void ln_resid4(const float* ysrc, float* ydst, bfraw* fb, float* stats, const float* pw, const float* pb,
;                      const float* w, const float* b, int lane, bool fin) {
;     ...
;     const float mean = red64(s) * (1.f / 1024.f);
;     float q = 0;
; #pragma unroll
;     for (int i = 0; i < 4; ++i) { const f32x4 d = y[i] - mean; q += d[0] * d[0] + d[1] * d[1] + d[2] * d[2] + d[3] * d[3]; }
;     const float rstd = 1.f / sqrtf(red64(q) * (1.f / 1024.f) + LN_EPS);
;     if (lane == 0) { stats[r * 2] = mean; stats[r * 2 + 1] = rstd; }
	v_add_f32_e32 v48, v48, v50
	v_xor_b32_e32 v50, 64, v49
	ds_bpermute_b32 v50, v50, v48
	s_waitcnt lgkmcnt(0)
	v_add_f32_e32 v48, v48, v50
	v_xor_b32_e32 v50, 32, v49
	s_nop 1
	v_mov_b32_dpp v50, v48 row_ror:8 row_mask:0xf bank_mask:0xf
	s_waitcnt lgkmcnt(0)
	v_add_f32_e32 v48, v48, v50
	v_xor_b32_e32 v50, 16, v49
	s_nop 1
	v_mov_b32_dpp v50, v48 row_half_mirror row_mask:0xf bank_mask:0xf
	s_nop 1
	v_mov_b32_dpp v50, v50 quad_perm:[3,2,1,0] row_mask:0xf bank_mask:0xf
	s_waitcnt lgkmcnt(0)
	v_add_f32_e32 v48, v48, v50
	v_xor_b32_e32 v50, 8, v49
	s_nop 1
	v_mov_b32_dpp v50, v48 quad_perm:[2,3,0,1] row_mask:0xf bank_mask:0xf
	v_xor_b32_e32 v49, 4, v49
	s_waitcnt lgkmcnt(0)
	v_add_f32_e32 v48, v48, v50
	s_nop 1
	v_mov_b32_dpp v49, v48 quad_perm:[1,0,3,2] row_mask:0xf bank_mask:0xf
	s_waitcnt lgkmcnt(0)
	v_add_f32_e32 v65, v48, v49
	v_fmamk_f32 v63, v65, 0xba800000, v45
	v_fmamk_f32 v59, v65, 0xba800000, v41
	v_fmamk_f32 v62, v65, 0xba800000, v44
	v_mul_f32_e32 v48, v63, v63
	v_fmamk_f32 v58, v65, 0xba800000, v40
	v_mul_f32_e32 v49, v59, v59
	v_fmamk_f32 v60, v65, 0xba800000, v46
	v_fmac_f32_e32 v48, v62, v62
	v_fmamk_f32 v56, v65, 0xba800000, v42
	v_fmac_f32_e32 v49, v58, v58
	v_fmamk_f32 v61, v65, 0xba800000, v47
	v_fmac_f32_e32 v48, v60, v60
	v_fmamk_f32 v57, v65, 0xba800000, v43
	v_fmac_f32_e32 v49, v56, v56
	v_fmac_f32_e32 v48, v61, v61
	v_fmac_f32_e32 v49, v57, v57
	v_fmamk_f32 v55, v65, 0xba800000, v37
	v_add_f32_e32 v48, v48, v49
	v_fmamk_f32 v54, v65, 0xba800000, v36
	v_mul_f32_e32 v49, v55, v55
	v_fmamk_f32 v52, v65, 0xba800000, v38
	v_fmac_f32_e32 v49, v54, v54
	v_fmamk_f32 v53, v65, 0xba800000, v39
	v_fmac_f32_e32 v49, v52, v52
	v_fmamk_f32 v51, v65, 0xba800000, v33
	v_fmac_f32_e32 v49, v53, v53
	v_fmamk_f32 v50, v65, 0xba800000, v32
	v_mul_f32_e32 v66, v51, v51
	v_add_f32_e32 v64, v49, v48
	v_fmamk_f32 v48, v65, 0xba800000, v34
	v_fmac_f32_e32 v66, v50, v50
	v_fmamk_f32 v49, v65, 0xba800000, v35
	v_fmac_f32_e32 v66, v48, v48
	v_fmac_f32_e32 v66, v49, v49
	v_add_f32_e32 v64, v66, v64
	v_mbcnt_lo_u32_b32 v66, s2, 0
	v_mbcnt_hi_u32_b32 v66, s2, v66
	v_lshlrev_b32_e32 v66, 2, v66
	v_xor_b32_e32 v67, 0x80, v66
	ds_bpermute_b32 v67, v67, v64
	s_waitcnt lgkmcnt(0)
	v_add_f32_e32 v64, v64, v67
	v_xor_b32_e32 v67, 64, v66
	ds_bpermute_b32 v67, v67, v64
	s_waitcnt lgkmcnt(0)
	v_add_f32_e32 v64, v64, v67
	v_xor_b32_e32 v67, 32, v66
	s_nop 1
	v_mov_b32_dpp v67, v64 row_ror:8 row_mask:0xf bank_mask:0xf
	s_waitcnt lgkmcnt(0)
	v_add_f32_e32 v64, v64, v67
	v_xor_b32_e32 v67, 16, v66
	s_nop 1
	v_mov_b32_dpp v67, v64 row_half_mirror row_mask:0xf bank_mask:0xf
	s_nop 1
	v_mov_b32_dpp v67, v67 quad_perm:[3,2,1,0] row_mask:0xf bank_mask:0xf
	s_waitcnt lgkmcnt(0)
	v_add_f32_e32 v64, v64, v67
	v_xor_b32_e32 v67, 8, v66
	s_nop 1
	v_mov_b32_dpp v67, v64 quad_perm:[2,3,0,1] row_mask:0xf bank_mask:0xf
	v_xor_b32_e32 v66, 4, v66
	s_waitcnt lgkmcnt(0)
	v_add_f32_e32 v64, v64, v67
	s_nop 1
	v_mov_b32_dpp v66, v64 quad_perm:[1,0,3,2] row_mask:0xf bank_mask:0xf
	s_waitcnt lgkmcnt(0)
	v_add_f32_e32 v64, v64, v66
	v_fmamk_f32 v64, v64, 0x3a800000, v183
	v_mul_f32_e32 v66, 0x4f800000, v64
	v_cmp_gt_f32_e32 vcc, s30, v64
	s_nop 1
	v_cndmask_b32_e32 v64, v64, v66, vcc
	v_sqrt_f32_e32 v66, v64
	s_nop 0
	v_add_u32_e32 v67, -1, v66
	v_fma_f32 v68, -v67, v66, v64
	v_cmp_ge_f32_e64 s[8:9], 0, v68
	v_add_u32_e32 v68, 1, v66
	s_nop 0
	v_cndmask_b32_e64 v67, v66, v67, s[8:9]
	v_fma_f32 v66, -v68, v66, v64
	v_cmp_lt_f32_e64 s[8:9], 0, v66
	s_nop 1
	v_cndmask_b32_e64 v66, v67, v68, s[8:9]
	v_mul_f32_e32 v67, 0x37800000, v66
	v_cndmask_b32_e32 v66, v66, v67, vcc
	v_cmp_class_f32_e32 vcc, v64, v222
	s_nop 1
	v_cndmask_b32_e32 v64, v66, v64, vcc
	s_nop 0
	v_rcp_f32_e32 v67, v64
	s_nop 0
	v_fma_f32 v66, -v64, v67, 1.0
	v_fma_f32 v66, v66, v67, v67
	v_div_fixup_f32 v64, v66, v64, 1.0
	s_and_saveexec_b64 s[2:3], s[6:7]
	s_cbranch_execz .LBB0_4339
	v_mul_f32_e32 v66, 0x3a800000, v65
	v_mov_b32_e32 v67, v64
	global_store_dwordx2 v[140:141], v[66:67], off offset:24
	s_branch .LBB0_4339

; DEVFI void ln_resid4(const float* ysrc, float* ydst, bfraw* fb, float* stats, const float* pw, const float* pb,
;                      const float* w, const float* b, int lane, bool fin) {
;   f32x4 v[4][4];
; #pragma unroll
;   for (int r = 0; r < 4; ++r)
; #pragma unroll
;     for (int i = 0; i < 4; ++i) v[r][i] = __builtin_nontemporal_load((const f32x4*)(ysrc + r * 1024) + i * 64 + lane);
;   u32x2 fv[4][4];
; #pragma unroll
;   for (int r = 0; r < 4; ++r)
; #pragma unroll
;     for (int i = 0; i < 4; ++i) fv[r][i] = __builtin_nontemporal_load((const u32x2*)(fb + r * 1024) + i * 64 + lane);
;   f32x4 pwv[4], pbv[4], ww[4], bb[4];
; #pragma unroll
;   for (int i = 0; i < 4; ++i) { pwv[i] = ((const f32x4*)pw)[i * 64 + lane]; pbv[i] = ((const f32x4*)pb)[i * 64 + lane];
;     ww[i] = ((const f32x4*)w)[i * 64 + lane]; bb[i] = ((const f32x4*)b)[i * 64 + lane]; }
; #pragma unroll
;   for (int r = 0; r < 4; ++r) {
;     const float pmu = stats[r * 2], prs = stats[r * 2 + 1];
;     f32x4 y[4];
; #pragma unroll
;     for (int i = 0; i < 4; ++i) { const unsigned f0 = fv[r][i][0], f1 = fv[r][i][1];
;       const f32x4 f4 = {__uint_as_float(f0 << 16), __uint_as_float(f0 & 0xffff0000u), __uint_as_float(f1 << 16), __uint_as_float(f1 & 0xffff0000u)};
;       y[i] = ALPHA * ((v[r][i] - pmu) * prs * pwv[i] + pbv[i]) + f4; }
;     float s = 0;
; #pragma unroll
;     for (int i = 0; i < 4; ++i) s += y[i][0] + y[i][1] + y[i][2] + y[i][3];
;     const float mean = red64(s) * (1.f / 1024.f);
.LBB0_4780:
	v_add_co_u32_e32 v0, vcc, 0x1000, v142
	global_load_dwordx4 v[124:127], v[142:143], off nt
	global_load_dwordx4 v[120:123], v[142:143], off offset:1024 nt
	global_load_dwordx4 v[116:119], v[142:143], off offset:2048 nt
	global_load_dwordx4 v[112:115], v[142:143], off offset:3072 nt
	v_addc_co_u32_e32 v1, vcc, 0, v143, vcc
	global_load_dwordx4 v[108:111], v[0:1], off nt
	global_load_dwordx4 v[104:107], v[0:1], off offset:1024 nt
	global_load_dwordx4 v[100:103], v[0:1], off offset:2048 nt
	global_load_dwordx4 v[96:99], v[0:1], off offset:3072 nt
	v_add_co_u32_e32 v0, vcc, s53, v142
	s_movk_i32 s2, 0x3000
	s_nop 0
	v_addc_co_u32_e32 v1, vcc, 0, v143, vcc
	v_add_co_u32_e32 v2, vcc, s2, v142
	s_mov_b32 s2, -1
	s_nop 0
	v_addc_co_u32_e32 v3, vcc, 0, v143, vcc
	global_load_dwordx4 v[92:95], v[2:3], off offset:-4096 nt
	global_load_dwordx4 v[88:91], v[0:1], off offset:1024 nt
	global_load_dwordx4 v[84:87], v[0:1], off offset:2048 nt
	global_load_dwordx4 v[80:83], v[0:1], off offset:3072 nt
	global_load_dwordx4 v[44:47], v[2:3], off nt
	global_load_dwordx4 v[40:43], v[2:3], off offset:1024 nt
	global_load_dwordx4 v[36:39], v[2:3], off offset:2048 nt
	global_load_dwordx4 v[32:35], v[2:3], off offset:3072 nt
	global_load_dwordx2 v[174:175], v[138:139], off nt
	global_load_dwordx2 v[172:173], v[138:139], off offset:512 nt
	global_load_dwordx2 v[170:171], v[138:139], off offset:1024 nt
	global_load_dwordx2 v[168:169], v[138:139], off offset:1536 nt
	global_load_dwordx2 v[166:167], v[138:139], off offset:2048 nt
	global_load_dwordx2 v[164:165], v[138:139], off offset:2560 nt
	global_load_dwordx2 v[162:163], v[138:139], off offset:3072 nt
	global_load_dwordx2 v[160:161], v[138:139], off offset:3584 nt
	v_add_co_u32_e32 v0, vcc, s56, v138
	v_mov_b32_e32 v192, 0x10000
	s_nop 0
	v_addc_co_u32_e32 v1, vcc, 0, v139, vcc
	global_load_dwordx2 v[158:159], v[0:1], off nt
	global_load_dwordx2 v[156:157], v[0:1], off offset:512 nt
	global_load_dwordx2 v[154:155], v[0:1], off offset:1024 nt
	global_load_dwordx2 v[152:153], v[0:1], off offset:1536 nt
	global_load_dwordx2 v[150:151], v[0:1], off offset:2048 nt
	global_load_dwordx2 v[148:149], v[0:1], off offset:2560 nt
	global_load_dwordx2 v[146:147], v[0:1], off offset:3072 nt
	global_load_dwordx2 v[144:145], v[0:1], off offset:3584 nt
	global_load_dwordx4 v[64:67], v[130:131], off
	global_load_dwordx4 v[68:71], v[132:133], off
	global_load_dwordx4 v[24:27], v[134:135], off
	global_load_dwordx4 v[28:31], v[136:137], off
	global_load_dwordx4 v[72:75], v[130:131], off offset:1024
	global_load_dwordx4 v[76:79], v[132:133], off offset:1024
	global_load_dwordx4 v[16:19], v[134:135], off offset:1024
	global_load_dwordx4 v[20:23], v[136:137], off offset:1024
	global_load_dwordx4 v[56:59], v[130:131], off offset:2048
	global_load_dwordx4 v[60:63], v[132:133], off offset:2048
	global_load_dwordx4 v[8:11], v[134:135], off offset:2048
	global_load_dwordx4 v[12:15], v[136:137], off offset:2048
	global_load_dwordx4 v[48:51], v[130:131], off offset:3072
	global_load_dwordx4 v[52:55], v[132:133], off offset:3072
	global_load_dwordx4 v[0:3], v[134:135], off offset:3072
	global_load_dwordx4 v[4:7], v[136:137], off offset:3072
	global_load_dwordx2 v[184:185], v[140:141], off
	s_waitcnt vmcnt(32)
	v_lshlrev_b32_e32 v178, 16, v174
	v_and_b32_e32 v179, 0xffff0000, v174
	v_lshlrev_b32_e32 v174, 16, v175
	v_and_b32_e32 v175, 0xffff0000, v175
	s_waitcnt vmcnt(0)
	v_sub_f32_e32 v127, v127, v184
	v_sub_f32_e32 v126, v126, v184
	v_pk_mul_f32 v[126:127], v[184:185], v[126:127] op_sel:[1,0]
	v_sub_f32_e32 v123, v123, v184
	v_sub_f32_e32 v122, v122, v184
	v_sub_f32_e32 v125, v125, v184
	v_sub_f32_e32 v124, v124, v184
	v_pk_fma_f32 v[126:127], v[66:67], v[126:127], v[70:71]
	v_sub_f32_e32 v121, v121, v184
	v_sub_f32_e32 v120, v120, v184
	v_pk_mul_f32 v[122:123], v[184:185], v[122:123] op_sel:[1,0]
	v_sub_f32_e32 v119, v119, v184
	v_sub_f32_e32 v118, v118, v184
	v_pk_mul_f32 v[124:125], v[184:185], v[124:125] op_sel:[1,0]
	v_pk_fma_f32 v[126:127], v[126:127], s[52:53], v[174:175] op_sel_hi:[1,0,1]
	v_lshlrev_b32_e32 v174, 16, v172
	v_and_b32_e32 v175, 0xffff0000, v172
	v_lshlrev_b32_e32 v172, 16, v173
	v_and_b32_e32 v173, 0xffff0000, v173
	v_pk_mul_f32 v[120:121], v[184:185], v[120:121] op_sel:[1,0]
	v_pk_fma_f32 v[122:123], v[74:75], v[122:123], v[78:79]
	v_pk_mul_f32 v[118:119], v[184:185], v[118:119] op_sel:[1,0]
	v_sub_f32_e32 v113, v113, v184
	v_sub_f32_e32 v112, v112, v184
	v_sub_f32_e32 v115, v115, v184
	v_sub_f32_e32 v114, v114, v184
	v_pk_fma_f32 v[124:125], v[64:65], v[124:125], v[68:69]
	v_pk_fma_f32 v[120:121], v[72:73], v[120:121], v[76:77]
	v_pk_fma_f32 v[122:123], v[122:123], s[52:53], v[172:173] op_sel_hi:[1,0,1]
	v_lshlrev_b32_e32 v172, 16, v170
	v_and_b32_e32 v173, 0xffff0000, v170
	v_lshlrev_b32_e32 v170, 16, v171
	v_and_b32_e32 v171, 0xffff0000, v171
	v_pk_fma_f32 v[118:119], v[58:59], v[118:119], v[62:63]
	v_pk_mul_f32 v[114:115], v[184:185], v[114:115] op_sel:[1,0]
	v_pk_mul_f32 v[112:113], v[184:185], v[112:113] op_sel:[1,0]
	v_pk_fma_f32 v[124:125], v[124:125], s[52:53], v[178:179] op_sel_hi:[1,0,1]
	v_pk_fma_f32 v[120:121], v[120:121], s[52:53], v[174:175] op_sel_hi:[1,0,1]
	v_pk_fma_f32 v[118:119], v[118:119], s[52:53], v[170:171] op_sel_hi:[1,0,1]
	v_lshlrev_b32_e32 v170, 16, v168
	v_and_b32_e32 v171, 0xffff0000, v168
	v_lshlrev_b32_e32 v168, 16, v169
	v_and_b32_e32 v169, 0xffff0000, v169
	v_pk_fma_f32 v[112:113], v[48:49], v[112:113], v[52:53]
	v_pk_fma_f32 v[114:115], v[50:51], v[114:115], v[54:55]
	v_pk_fma_f32 v[112:113], v[112:113], s[52:53], v[170:171] op_sel_hi:[1,0,1]
	v_pk_fma_f32 v[114:115], v[114:115], s[52:53], v[168:169] op_sel_hi:[1,0,1]
	v_mov_b32_e32 v168, v120
	v_mov_b32_e32 v169, v124
	v_mov_b32_e32 v170, v121
	v_mov_b32_e32 v171, v125
	v_sub_f32_e32 v117, v117, v184
	v_sub_f32_e32 v116, v116, v184
	v_pk_add_f32 v[168:169], v[168:169], v[170:171]
	v_mov_b32_e32 v170, v122
	v_mov_b32_e32 v171, v126
	v_pk_mul_f32 v[116:117], v[184:185], v[116:117] op_sel:[1,0]
	v_pk_add_f32 v[168:169], v[170:171], v[168:169]
	v_mov_b32_e32 v170, v123
	v_mov_b32_e32 v171, v127
	v_pk_fma_f32 v[116:117], v[56:57], v[116:117], v[60:61]
	v_pk_add_f32 v[168:169], v[170:171], v[168:169]
	v_pk_fma_f32 v[116:117], v[116:117], s[52:53], v[172:173] op_sel_hi:[1,0,1]
	v_add_f32_e32 v129, 0, v169
	v_add_f32_e32 v129, v168, v129
	v_mov_b32_e32 v168, v112
	v_mov_b32_e32 v169, v116
	v_mov_b32_e32 v170, v113
	v_mov_b32_e32 v171, v117
	v_pk_add_f32 v[168:169], v[168:169], v[170:171]
	v_mov_b32_e32 v170, v114
	v_mov_b32_e32 v171, v118
	v_pk_add_f32 v[168:169], v[170:171], v[168:169]
	v_mov_b32_e32 v170, v115
	v_mov_b32_e32 v171, v119
	v_pk_add_f32 v[168:169], v[170:171], v[168:169]
	s_nop 0
	v_add_f32_e32 v129, v169, v129
	v_add_f32_e32 v129, v168, v129
	v_mbcnt_lo_u32_b32 v168, s2, 0
	v_mbcnt_hi_u32_b32 v168, s2, v168
	v_lshlrev_b32_e32 v168, 2, v168
	v_xor_b32_e32 v169, 0x80, v168
	ds_bpermute_b32 v169, v169, v129
	s_mov_b32 s2, -1
	s_waitcnt lgkmcnt(0)
; DEVFI int lane_opaque() { unsigned m = ~0u; asm volatile("" : "+s"(m)); return (int)__builtin_amdgcn_mbcnt_hi(m, __builtin_amdgcn_mbcnt_lo(m, 0u)); }
; DEVFI float shx(float v, int mask, int lane) { return __int_as_float(__builtin_amdgcn_ds_bpermute((lane ^ mask) << 2, __float_as_int(v))); }
; DEVFI float red64(float v) {
;   const int ln = lane_opaque();
;   v += shx(v, 32, ln); v += shx(v, 16, ln); v += shx(v, 8, ln); v += shx(v, 4, ln); v += shx(v, 2, ln); v += shx(v, 1, ln); return v;
; }
; DEVFI void ln_resid4(const float* ysrc, float* ydst, bfraw* fb, float* stats, const float* pw, const float* pb,
;                      const float* w, const float* b, int lane, bool fin) {
;     ...
;     const float mean = red64(s) * (1.f / 1024.f);
;     float q = 0;
; #pragma unroll
;     for (int i = 0; i < 4; ++i) { const f32x4 d = y[i] - mean; q += d[0] * d[0] + d[1] * d[1] + d[2] * d[2] + d[3] * d[3]; }
;     const float rstd = 1.f / sqrtf(red64(q) * (1.f / 1024.f) + LN_EPS);
;     if (lane == 0) { stats[r * 2] = mean; stats[r * 2 + 1] = rstd; }
	v_add_f32_e32 v129, v129, v169
	v_xor_b32_e32 v169, 64, v168
	ds_bpermute_b32 v169, v169, v129
	s_waitcnt lgkmcnt(0)
	v_add_f32_e32 v129, v129, v169
	v_xor_b32_e32 v169, 32, v168
	s_nop 1
	v_mov_b32_dpp v169, v129 row_ror:8 row_mask:0xf bank_mask:0xf
	s_waitcnt lgkmcnt(0)
	v_add_f32_e32 v129, v129, v169
	v_xor_b32_e32 v169, 16, v168
	s_nop 1
	v_mov_b32_dpp v169, v129 row_half_mirror row_mask:0xf bank_mask:0xf
	s_nop 1
	v_mov_b32_dpp v169, v169 quad_perm:[3,2,1,0] row_mask:0xf bank_mask:0xf
	s_waitcnt lgkmcnt(0)
	v_add_f32_e32 v129, v129, v169
	v_xor_b32_e32 v169, 8, v168
	s_nop 1
	v_mov_b32_dpp v169, v129 quad_perm:[2,3,0,1] row_mask:0xf bank_mask:0xf
	v_xor_b32_e32 v168, 4, v168
	s_waitcnt lgkmcnt(0)
	v_add_f32_e32 v129, v129, v169
	s_nop 1
	v_mov_b32_dpp v168, v129 quad_perm:[1,0,3,2] row_mask:0xf bank_mask:0xf
	s_waitcnt lgkmcnt(0)
	v_add_f32_e32 v129, v129, v168
	v_fmamk_f32 v191, v129, 0xba800000, v125
	v_fmamk_f32 v187, v129, 0xba800000, v121
	v_fmamk_f32 v190, v129, 0xba800000, v124
	v_mul_f32_e32 v168, v191, v191
	v_fmamk_f32 v186, v129, 0xba800000, v120
	v_mul_f32_e32 v169, v187, v187
	v_fmamk_f32 v188, v129, 0xba800000, v126
	v_fmac_f32_e32 v168, v190, v190
	v_fmamk_f32 v184, v129, 0xba800000, v122
	v_fmac_f32_e32 v169, v186, v186
	v_fmamk_f32 v189, v129, 0xba800000, v127
	v_fmac_f32_e32 v168, v188, v188
	v_fmamk_f32 v185, v129, 0xba800000, v123
	v_fmac_f32_e32 v169, v184, v184
	v_fmac_f32_e32 v168, v189, v189
	v_fmac_f32_e32 v169, v185, v185
	v_fmamk_f32 v175, v129, 0xba800000, v117
	v_add_f32_e32 v168, v168, v169
	v_fmamk_f32 v174, v129, 0xba800000, v116
	v_mul_f32_e32 v169, v175, v175
	v_fmamk_f32 v172, v129, 0xba800000, v118
	v_fmac_f32_e32 v169, v174, v174
	v_fmamk_f32 v173, v129, 0xba800000, v119
	v_fmac_f32_e32 v169, v172, v172
	v_fmamk_f32 v171, v129, 0xba800000, v113
	v_fmac_f32_e32 v169, v173, v173
	v_fmamk_f32 v170, v129, 0xba800000, v112
	v_mul_f32_e32 v178, v171, v171
	v_add_f32_e32 v176, v169, v168
	v_fmamk_f32 v168, v129, 0xba800000, v114
	v_fmac_f32_e32 v178, v170, v170
	v_fmamk_f32 v169, v129, 0xba800000, v115
	v_fmac_f32_e32 v178, v168, v168
	v_fmac_f32_e32 v178, v169, v169
	v_add_f32_e32 v176, v178, v176
	v_mbcnt_lo_u32_b32 v178, s2, 0
	v_mbcnt_hi_u32_b32 v178, s2, v178
	v_lshlrev_b32_e32 v178, 2, v178
	v_xor_b32_e32 v179, 0x80, v178
	ds_bpermute_b32 v179, v179, v176
	s_waitcnt lgkmcnt(0)
	v_add_f32_e32 v176, v176, v179
	v_xor_b32_e32 v179, 64, v178
	ds_bpermute_b32 v179, v179, v176
	s_waitcnt lgkmcnt(0)
	v_add_f32_e32 v176, v176, v179
	v_xor_b32_e32 v179, 32, v178
	s_nop 1
	v_mov_b32_dpp v179, v176 row_ror:8 row_mask:0xf bank_mask:0xf
	s_waitcnt lgkmcnt(0)
	v_add_f32_e32 v176, v176, v179
	v_xor_b32_e32 v179, 16, v178
	s_nop 1
	v_mov_b32_dpp v179, v176 row_half_mirror row_mask:0xf bank_mask:0xf
	s_nop 1
	v_mov_b32_dpp v179, v179 quad_perm:[3,2,1,0] row_mask:0xf bank_mask:0xf
	s_waitcnt lgkmcnt(0)
	v_add_f32_e32 v176, v176, v179
	v_xor_b32_e32 v179, 8, v178
	s_nop 1
	v_mov_b32_dpp v179, v176 quad_perm:[2,3,0,1] row_mask:0xf bank_mask:0xf
	v_xor_b32_e32 v178, 4, v178
	s_waitcnt lgkmcnt(0)
	v_add_f32_e32 v176, v176, v179
	s_nop 1
	v_mov_b32_dpp v178, v176 quad_perm:[1,0,3,2] row_mask:0xf bank_mask:0xf
	s_waitcnt lgkmcnt(0)
	v_add_f32_e32 v176, v176, v178
	v_fmamk_f32 v176, v176, 0x3a800000, v183
	v_cmp_gt_f32_e32 vcc, s30, v176
	v_mul_f32_e32 v178, 0x4f800000, v176
	s_nop 0
	v_cndmask_b32_e32 v176, v176, v178, vcc
	v_sqrt_f32_e32 v178, v176
	s_nop 0
	v_add_u32_e32 v179, -1, v178
	v_fma_f32 v180, -v179, v178, v176
	v_cmp_ge_f32_e64 s[8:9], 0, v180
	v_add_u32_e32 v180, 1, v178
	s_nop 0
	v_cndmask_b32_e64 v179, v178, v179, s[8:9]
	v_fma_f32 v178, -v180, v178, v176
	v_cmp_lt_f32_e64 s[8:9], 0, v178
	s_nop 1
	v_cndmask_b32_e64 v178, v179, v180, s[8:9]
	v_mul_f32_e32 v179, 0x37800000, v178
	v_cndmask_b32_e32 v178, v178, v179, vcc
	v_cmp_class_f32_e32 vcc, v176, v222
	s_nop 1
	v_cndmask_b32_e32 v176, v178, v176, vcc
	s_nop 0
	v_rcp_f32_e32 v179, v176
	s_nop 0
	v_fma_f32 v178, -v176, v179, 1.0
	v_fma_f32 v178, v178, v179, v179
	v_div_fixup_f32 v176, v178, v176, 1.0
	s_and_saveexec_b64 s[2:3], s[6:7]
	s_cbranch_execz .LBB0_4782
	v_mul_f32_e32 v178, 0x3a800000, v129
	v_mov_b32_e32 v179, v176
	global_store_dwordx2 v[140:141], v[178:179], off
; DEVFI void ln_resid4(const float* ysrc, float* ydst, bfraw* fb, float* stats, const float* pw, const float* pb,
;                      const float* w, const float* b, int lane, bool fin) {
;     ...
;   for (int r = 0; r < 4; ++r) {
;     const float pmu = stats[r * 2], prs = stats[r * 2 + 1];
;     f32x4 y[4];
; #pragma unroll
;     for (int i = 0; i < 4; ++i) { const unsigned f0 = fv[r][i][0], f1 = fv[r][i][1];
;       const f32x4 f4 = {__uint_as_float(f0 << 16), __uint_as_float(f0 & 0xffff0000u), __uint_as_float(f1 << 16), __uint_as_float(f1 & 0xffff0000u)};
;       y[i] = ALPHA * ((v[r][i] - pmu) * prs * pwv[i] + pbv[i]) + f4; }
;     float s = 0;
; #pragma unroll
;     for (int i = 0; i < 4; ++i) s += y[i][0] + y[i][1] + y[i][2] + y[i][3];
;     const float mean = red64(s) * (1.f / 1024.f);
;     float q = 0;
; #pragma unroll
;     for (int i = 0; i < 4; ++i) { const f32x4 d = y[i] - mean; q += d[0] * d[0] + d[1] * d[1] + d[2] * d[2] + d[3] * d[3]; }
;     const float rstd = 1.f / sqrtf(red64(q) * (1.f / 1024.f) + LN_EPS);
;     if (lane == 0) { stats[r * 2] = mean; stats[r * 2 + 1] = rstd; }
; #pragma unroll
;     for (int i = 0; i < 4; ++i) { const int c4 = i * 64 + lane;
;       const f32x4 z = (y[i] - mean) * rstd * ww[i] + bb[i];
;       __builtin_nontemporal_store(fin ? z : y[i], (f32x4*)(ydst + r * 1024) + c4);
;       u32x2 pk = {cvtpk(z[0], z[1]), cvtpk(z[2], z[3])}; ((u32x2*)(fb + r * 1024))[c4] = pk; }
.LBB0_4782:
	s_or_b64 exec, exec, s[2:3]
	v_pk_mul_f32 v[178:179], v[188:189], v[176:177] op_sel_hi:[1,0]
	v_pk_mul_f32 v[180:181], v[190:191], v[176:177] op_sel_hi:[1,0]
	v_pk_fma_f32 v[178:179], v[26:27], v[178:179], v[30:31]
	v_pk_fma_f32 v[180:181], v[24:25], v[180:181], v[28:29]
	v_cndmask_b32_e64 v127, v127, v179, s[4:5]
	v_cndmask_b32_e64 v126, v126, v178, s[4:5]
	v_cndmask_b32_e64 v125, v125, v181, s[4:5]
	v_cndmask_b32_e64 v124, v124, v180, s[4:5]
	global_store_dwordx4 v[142:143], v[124:127], off nt
	s_mov_b32 s2, -1
	s_nop 0
	v_cvt_pk_bf16_f32 v124, v180, v181
	v_cvt_pk_bf16_f32 v125, v178, v179
	global_store_dwordx2 v[138:139], v[124:125], off
	v_pk_mul_f32 v[124:125], v[184:185], v[176:177] op_sel_hi:[1,0]
	v_pk_mul_f32 v[126:127], v[186:187], v[176:177] op_sel_hi:[1,0]
	v_pk_fma_f32 v[124:125], v[18:19], v[124:125], v[22:23]
	v_pk_fma_f32 v[126:127], v[16:17], v[126:127], v[20:21]
	v_cndmask_b32_e64 v123, v123, v125, s[4:5]
	v_cndmask_b32_e64 v122, v122, v124, s[4:5]
	v_cndmask_b32_e64 v121, v121, v127, s[4:5]
	v_cndmask_b32_e64 v120, v120, v126, s[4:5]
	global_store_dwordx4 v[142:143], v[120:123], off offset:1024 nt
	s_nop 1
	v_cvt_pk_bf16_f32 v120, v126, v127
	v_cvt_pk_bf16_f32 v121, v124, v125
	global_store_dwordx2 v[138:139], v[120:121], off offset:512
	v_pk_mul_f32 v[120:121], v[172:173], v[176:177] op_sel_hi:[1,0]
	v_pk_mul_f32 v[122:123], v[174:175], v[176:177] op_sel_hi:[1,0]
	v_pk_fma_f32 v[120:121], v[10:11], v[120:121], v[14:15]
	v_pk_fma_f32 v[122:123], v[8:9], v[122:123], v[12:13]
	v_cndmask_b32_e64 v119, v119, v121, s[4:5]
	v_cndmask_b32_e64 v118, v118, v120, s[4:5]
	v_cndmask_b32_e64 v117, v117, v123, s[4:5]
	v_cndmask_b32_e64 v116, v116, v122, s[4:5]
	global_store_dwordx4 v[142:143], v[116:119], off offset:2048 nt
	v_lshlrev_b32_e32 v126, 16, v160
	v_and_b32_e32 v127, 0xffff0000, v160
	v_cvt_pk_bf16_f32 v116, v122, v123
	v_cvt_pk_bf16_f32 v117, v120, v121
	global_store_dwordx2 v[138:139], v[116:117], off offset:1024
	v_pk_mul_f32 v[116:117], v[168:169], v[176:177] op_sel_hi:[1,0]
	v_pk_mul_f32 v[118:119], v[170:171], v[176:177] op_sel_hi:[1,0]
	v_pk_fma_f32 v[116:117], v[2:3], v[116:117], v[6:7]
	v_pk_fma_f32 v[118:119], v[0:1], v[118:119], v[4:5]
	v_cndmask_b32_e64 v115, v115, v117, s[4:5]
	v_cndmask_b32_e64 v114, v114, v116, s[4:5]
	v_cndmask_b32_e64 v113, v113, v119, s[4:5]
	v_cndmask_b32_e64 v112, v112, v118, s[4:5]
	global_store_dwordx4 v[142:143], v[112:115], off offset:3072 nt
	v_lshlrev_b32_e32 v120, 16, v165
	v_and_b32_e32 v121, 0xffff0000, v165
	v_cvt_pk_bf16_f32 v112, v118, v119
	v_cvt_pk_bf16_f32 v113, v116, v117
	global_store_dwordx2 v[138:139], v[112:113], off offset:1536
	global_load_dwordx2 v[112:113], v[140:141], off offset:8
	v_lshlrev_b32_e32 v114, 16, v166
	v_and_b32_e32 v115, 0xffff0000, v166
	v_lshlrev_b32_e32 v118, 16, v164
	v_and_b32_e32 v119, 0xffff0000, v164
	v_lshlrev_b32_e32 v116, 16, v167
	v_and_b32_e32 v117, 0xffff0000, v167
	v_lshlrev_b32_e32 v122, 16, v162
	v_and_b32_e32 v123, 0xffff0000, v162
	v_lshlrev_b32_e32 v124, 16, v163
	v_and_b32_e32 v125, 0xffff0000, v163
	s_waitcnt vmcnt(0)
	v_sub_f32_e32 v109, v109, v112
	v_sub_f32_e32 v108, v108, v112
	v_sub_f32_e32 v105, v105, v112
	v_sub_f32_e32 v104, v104, v112
	v_sub_f32_e32 v111, v111, v112
	v_sub_f32_e32 v110, v110, v112
	v_sub_f32_e32 v107, v107, v112
	v_sub_f32_e32 v106, v106, v112
	v_pk_mul_f32 v[108:109], v[112:113], v[108:109] op_sel:[1,0]
	v_pk_mul_f32 v[104:105], v[112:113], v[104:105] op_sel:[1,0]
	v_sub_f32_e32 v99, v99, v112
	v_sub_f32_e32 v98, v98, v112
	v_pk_mul_f32 v[110:111], v[112:113], v[110:111] op_sel:[1,0]
	v_pk_mul_f32 v[106:107], v[112:113], v[106:107] op_sel:[1,0]
	v_pk_fma_f32 v[108:109], v[64:65], v[108:109], v[68:69]
	v_pk_fma_f32 v[104:105], v[72:73], v[104:105], v[76:77]
	v_pk_mul_f32 v[98:99], v[112:113], v[98:99] op_sel:[1,0]
	v_sub_f32_e32 v101, v101, v112
	v_sub_f32_e32 v100, v100, v112
	v_sub_f32_e32 v103, v103, v112
	v_sub_f32_e32 v102, v102, v112
	v_pk_fma_f32 v[110:111], v[66:67], v[110:111], v[70:71]
	v_pk_fma_f32 v[106:107], v[74:75], v[106:107], v[78:79]
	v_pk_fma_f32 v[108:109], v[108:109], s[52:53], v[114:115] op_sel_hi:[1,0,1]
	v_pk_fma_f32 v[104:105], v[104:105], s[52:53], v[118:119] op_sel_hi:[1,0,1]
	v_lshlrev_b32_e32 v114, 16, v161
	v_and_b32_e32 v115, 0xffff0000, v161
	v_sub_f32_e32 v97, v97, v112
	v_sub_f32_e32 v96, v96, v112
	v_pk_fma_f32 v[98:99], v[50:51], v[98:99], v[54:55]
	v_pk_mul_f32 v[102:103], v[112:113], v[102:103] op_sel:[1,0]
	v_pk_mul_f32 v[100:101], v[112:113], v[100:101] op_sel:[1,0]
	v_pk_fma_f32 v[110:111], v[110:111], s[52:53], v[116:117] op_sel_hi:[1,0,1]
	v_pk_fma_f32 v[106:107], v[106:107], s[52:53], v[120:121] op_sel_hi:[1,0,1]
	v_pk_mul_f32 v[96:97], v[112:113], v[96:97] op_sel:[1,0]
	v_pk_fma_f32 v[98:99], v[98:99], s[52:53], v[114:115] op_sel_hi:[1,0,1]
	v_mov_b32_e32 v112, v104
	v_mov_b32_e32 v113, v108
	v_mov_b32_e32 v114, v105
	v_mov_b32_e32 v115, v109
	v_pk_add_f32 v[112:113], v[112:113], v[114:115]
	v_mov_b32_e32 v114, v106
	v_mov_b32_e32 v115, v110
	v_pk_add_f32 v[112:113], v[114:115], v[112:113]
	v_mov_b32_e32 v114, v107
	v_mov_b32_e32 v115, v111
	v_pk_fma_f32 v[100:101], v[56:57], v[100:101], v[60:61]
	v_pk_fma_f32 v[96:97], v[48:49], v[96:97], v[52:53]
	v_pk_add_f32 v[112:113], v[114:115], v[112:113]
	v_pk_fma_f32 v[102:103], v[58:59], v[102:103], v[62:63]
	v_pk_fma_f32 v[100:101], v[100:101], s[52:53], v[122:123] op_sel_hi:[1,0,1]
	v_pk_fma_f32 v[96:97], v[96:97], s[52:53], v[126:127] op_sel_hi:[1,0,1]
	v_add_f32_e32 v113, 0, v113
	v_pk_fma_f32 v[102:103], v[102:103], s[52:53], v[124:125] op_sel_hi:[1,0,1]
	v_add_f32_e32 v116, v112, v113
	v_mov_b32_e32 v112, v96
	v_mov_b32_e32 v113, v100
	v_mov_b32_e32 v114, v97
	v_mov_b32_e32 v115, v101
	v_pk_add_f32 v[112:113], v[112:113], v[114:115]
	v_mov_b32_e32 v114, v98
	v_mov_b32_e32 v115, v102
	v_pk_add_f32 v[112:113], v[114:115], v[112:113]
	v_mov_b32_e32 v114, v99
	v_mov_b32_e32 v115, v103
	v_pk_add_f32 v[112:113], v[114:115], v[112:113]
	s_nop 0
	v_add_f32_e32 v113, v113, v116
	v_add_f32_e32 v112, v112, v113
	v_mbcnt_lo_u32_b32 v113, s2, 0
	v_mbcnt_hi_u32_b32 v113, s2, v113
	v_lshlrev_b32_e32 v113, 2, v113
	v_xor_b32_e32 v114, 0x80, v113
	ds_bpermute_b32 v114, v114, v112
	s_mov_b32 s2, -1
	s_waitcnt lgkmcnt(0)
; DEVFI int lane_opaque() { unsigned m = ~0u; asm volatile("" : "+s"(m)); return (int)__builtin_amdgcn_mbcnt_hi(m, __builtin_amdgcn_mbcnt_lo(m, 0u)); }
; DEVFI float shx(float v, int mask, int lane) { return __int_as_float(__builtin_amdgcn_ds_bpermute((lane ^ mask) << 2, __float_as_int(v))); }
; DEVFI float red64(float v) {
;   const int ln = lane_opaque();
;   v += shx(v, 32, ln); v += shx(v, 16, ln); v += shx(v, 8, ln); v += shx(v, 4, ln); v += shx(v, 2, ln); v += shx(v, 1, ln); return v;
; }
; DEVFI void ln_resid4(const float* ysrc, float* ydst, bfraw* fb, float* stats, const float* pw, const float* pb,
;                      const float* w, const float* b, int lane, bool fin) {
;     ...
;     const float mean = red64(s) * (1.f / 1024.f);
;     float q = 0;
; #pragma unroll
;     for (int i = 0; i < 4; ++i) { const f32x4 d = y[i] - mean; q += d[0] * d[0] + d[1] * d[1] + d[2] * d[2] + d[3] * d[3]; }
;     const float rstd = 1.f / sqrtf(red64(q) * (1.f / 1024.f) + LN_EPS);
;     if (lane == 0) { stats[r * 2] = mean; stats[r * 2 + 1] = rstd; }
	v_add_f32_e32 v112, v112, v114
	v_xor_b32_e32 v114, 64, v113
	ds_bpermute_b32 v114, v114, v112
	s_waitcnt lgkmcnt(0)
	v_add_f32_e32 v112, v112, v114
	v_xor_b32_e32 v114, 32, v113
	s_nop 1
	v_mov_b32_dpp v114, v112 row_ror:8 row_mask:0xf bank_mask:0xf
	s_waitcnt lgkmcnt(0)
	v_add_f32_e32 v112, v112, v114
	v_xor_b32_e32 v114, 16, v113
	s_nop 1
	v_mov_b32_dpp v114, v112 row_half_mirror row_mask:0xf bank_mask:0xf
	s_nop 1
	v_mov_b32_dpp v114, v114 quad_perm:[3,2,1,0] row_mask:0xf bank_mask:0xf
	s_waitcnt lgkmcnt(0)
	v_add_f32_e32 v112, v112, v114
	v_xor_b32_e32 v114, 8, v113
	s_nop 1
	v_mov_b32_dpp v114, v112 quad_perm:[2,3,0,1] row_mask:0xf bank_mask:0xf
	v_xor_b32_e32 v113, 4, v113
	s_waitcnt lgkmcnt(0)
	v_add_f32_e32 v112, v112, v114
	s_nop 1
	v_mov_b32_dpp v113, v112 quad_perm:[1,0,3,2] row_mask:0xf bank_mask:0xf
	s_waitcnt lgkmcnt(0)
	v_add_f32_e32 v129, v112, v113
	v_fmamk_f32 v127, v129, 0xba800000, v109
	v_fmamk_f32 v123, v129, 0xba800000, v105
	v_fmamk_f32 v126, v129, 0xba800000, v108
	v_mul_f32_e32 v112, v127, v127
	v_fmamk_f32 v122, v129, 0xba800000, v104
	v_mul_f32_e32 v113, v123, v123
	v_fmamk_f32 v124, v129, 0xba800000, v110
	v_fmac_f32_e32 v112, v126, v126
	v_fmamk_f32 v120, v129, 0xba800000, v106
	v_fmac_f32_e32 v113, v122, v122
	v_fmamk_f32 v125, v129, 0xba800000, v111
	v_fmac_f32_e32 v112, v124, v124
	v_fmamk_f32 v121, v129, 0xba800000, v107
	v_fmac_f32_e32 v113, v120, v120
	v_fmac_f32_e32 v112, v125, v125
	v_fmac_f32_e32 v113, v121, v121
	v_fmamk_f32 v119, v129, 0xba800000, v101
	v_add_f32_e32 v112, v112, v113
	v_fmamk_f32 v118, v129, 0xba800000, v100
	v_mul_f32_e32 v113, v119, v119
	v_fmamk_f32 v116, v129, 0xba800000, v102
	v_fmac_f32_e32 v113, v118, v118
	v_fmamk_f32 v117, v129, 0xba800000, v103
	v_fmac_f32_e32 v113, v116, v116
	v_fmamk_f32 v115, v129, 0xba800000, v97
	v_fmac_f32_e32 v113, v117, v117
	v_fmamk_f32 v114, v129, 0xba800000, v96
	v_mul_f32_e32 v161, v115, v115
	v_add_f32_e32 v160, v113, v112
	v_fmamk_f32 v112, v129, 0xba800000, v98
	v_fmac_f32_e32 v161, v114, v114
	v_fmamk_f32 v113, v129, 0xba800000, v99
	v_fmac_f32_e32 v161, v112, v112
	v_fmac_f32_e32 v161, v113, v113
	v_add_f32_e32 v160, v161, v160
	v_mbcnt_lo_u32_b32 v161, s2, 0
	v_mbcnt_hi_u32_b32 v161, s2, v161
	v_lshlrev_b32_e32 v161, 2, v161
	v_xor_b32_e32 v162, 0x80, v161
	ds_bpermute_b32 v162, v162, v160
	s_waitcnt lgkmcnt(0)
	v_add_f32_e32 v160, v160, v162
	v_xor_b32_e32 v162, 64, v161
	ds_bpermute_b32 v162, v162, v160
	s_waitcnt lgkmcnt(0)
	v_add_f32_e32 v160, v160, v162
	v_xor_b32_e32 v162, 32, v161
	s_nop 1
	v_mov_b32_dpp v162, v160 row_ror:8 row_mask:0xf bank_mask:0xf
	s_waitcnt lgkmcnt(0)
	v_add_f32_e32 v160, v160, v162
	v_xor_b32_e32 v162, 16, v161
	s_nop 1
	v_mov_b32_dpp v162, v160 row_half_mirror row_mask:0xf bank_mask:0xf
	s_nop 1
	v_mov_b32_dpp v162, v162 quad_perm:[3,2,1,0] row_mask:0xf bank_mask:0xf
	s_waitcnt lgkmcnt(0)
	v_add_f32_e32 v160, v160, v162
	v_xor_b32_e32 v162, 8, v161
	s_nop 1
	v_mov_b32_dpp v162, v160 quad_perm:[2,3,0,1] row_mask:0xf bank_mask:0xf
	v_xor_b32_e32 v161, 4, v161
	s_waitcnt lgkmcnt(0)
	v_add_f32_e32 v160, v160, v162
	s_nop 1
	v_mov_b32_dpp v161, v160 quad_perm:[1,0,3,2] row_mask:0xf bank_mask:0xf
	s_waitcnt lgkmcnt(0)
	v_add_f32_e32 v160, v160, v161
	v_fmamk_f32 v160, v160, 0x3a800000, v183
	v_mul_f32_e32 v161, 0x4f800000, v160
	v_cmp_gt_f32_e32 vcc, s30, v160
	s_nop 1
	v_cndmask_b32_e32 v160, v160, v161, vcc
	v_sqrt_f32_e32 v161, v160
	s_nop 0
	v_add_u32_e32 v162, -1, v161
	v_fma_f32 v163, -v162, v161, v160
	v_cmp_ge_f32_e64 s[8:9], 0, v163
	v_add_u32_e32 v163, 1, v161
	s_nop 0
	v_cndmask_b32_e64 v162, v161, v162, s[8:9]
	v_fma_f32 v161, -v163, v161, v160
	v_cmp_lt_f32_e64 s[8:9], 0, v161
	s_nop 1
	v_cndmask_b32_e64 v161, v162, v163, s[8:9]
	v_mul_f32_e32 v162, 0x37800000, v161
	v_cndmask_b32_e32 v161, v161, v162, vcc
	v_cmp_class_f32_e32 vcc, v160, v222
	s_nop 1
	v_cndmask_b32_e32 v160, v161, v160, vcc
	s_nop 0
	v_rcp_f32_e32 v162, v160
	s_nop 0
	v_fma_f32 v161, -v160, v162, 1.0
	v_fma_f32 v161, v161, v162, v162
	v_div_fixup_f32 v160, v161, v160, 1.0
	s_and_saveexec_b64 s[2:3], s[6:7]
	s_cbranch_execz .LBB0_4784
	v_mul_f32_e32 v162, 0x3a800000, v129
	v_mov_b32_e32 v163, v160
	global_store_dwordx2 v[140:141], v[162:163], off offset:8
; DEVFI void ln_resid4(const float* ysrc, float* ydst, bfraw* fb, float* stats, const float* pw, const float* pb,
;                      const float* w, const float* b, int lane, bool fin) {
;     ...
;   for (int r = 0; r < 4; ++r) {
;     const float pmu = stats[r * 2], prs = stats[r * 2 + 1];
;     f32x4 y[4];
; #pragma unroll
;     for (int i = 0; i < 4; ++i) { const unsigned f0 = fv[r][i][0], f1 = fv[r][i][1];
;       const f32x4 f4 = {__uint_as_float(f0 << 16), __uint_as_float(f0 & 0xffff0000u), __uint_as_float(f1 << 16), __uint_as_float(f1 & 0xffff0000u)};
;       y[i] = ALPHA * ((v[r][i] - pmu) * prs * pwv[i] + pbv[i]) + f4; }
;     float s = 0;
; #pragma unroll
;     for (int i = 0; i < 4; ++i) s += y[i][0] + y[i][1] + y[i][2] + y[i][3];
;     const float mean = red64(s) * (1.f / 1024.f);
;     float q = 0;
; #pragma unroll
;     for (int i = 0; i < 4; ++i) { const f32x4 d = y[i] - mean; q += d[0] * d[0] + d[1] * d[1] + d[2] * d[2] + d[3] * d[3]; }
;     const float rstd = 1.f / sqrtf(red64(q) * (1.f / 1024.f) + LN_EPS);
;     if (lane == 0) { stats[r * 2] = mean; stats[r * 2 + 1] = rstd; }
; #pragma unroll
;     for (int i = 0; i < 4; ++i) { const int c4 = i * 64 + lane;
;       const f32x4 z = (y[i] - mean) * rstd * ww[i] + bb[i];
;       __builtin_nontemporal_store(fin ? z : y[i], (f32x4*)(ydst + r * 1024) + c4);
;       u32x2 pk = {cvtpk(z[0], z[1]), cvtpk(z[2], z[3])}; ((u32x2*)(fb + r * 1024))[c4] = pk; }
.LBB0_4784:
	s_or_b64 exec, exec, s[2:3]
	v_pk_mul_f32 v[124:125], v[124:125], v[160:161] op_sel_hi:[1,0]
	v_pk_mul_f32 v[126:127], v[126:127], v[160:161] op_sel_hi:[1,0]
	s_mov_b64 s[2:3], 0x1000
	v_pk_fma_f32 v[124:125], v[26:27], v[124:125], v[30:31]
	v_pk_fma_f32 v[126:127], v[24:25], v[126:127], v[28:29]
	v_lshl_add_u64 v[162:163], v[142:143], 0, s[2:3]
	v_cndmask_b32_e64 v111, v111, v125, s[4:5]
	v_cndmask_b32_e64 v110, v110, v124, s[4:5]
	v_cndmask_b32_e64 v109, v109, v127, s[4:5]
	v_cndmask_b32_e64 v108, v108, v126, s[4:5]
	global_store_dwordx4 v[162:163], v[108:111], off nt
	s_mov_b64 s[2:3], 0x1400
	v_lshl_add_u64 v[164:165], v[142:143], 0, s[2:3]
	v_cvt_pk_bf16_f32 v108, v126, v127
	v_cvt_pk_bf16_f32 v109, v124, v125
	global_store_dwordx2 v[138:139], v[108:109], off offset:2048
	v_pk_mul_f32 v[108:109], v[120:121], v[160:161] op_sel_hi:[1,0]
	v_pk_mul_f32 v[110:111], v[122:123], v[160:161] op_sel_hi:[1,0]
	v_pk_fma_f32 v[108:109], v[18:19], v[108:109], v[22:23]
	v_pk_fma_f32 v[110:111], v[16:17], v[110:111], v[20:21]
	v_cndmask_b32_e64 v107, v107, v109, s[4:5]
	v_cndmask_b32_e64 v106, v106, v108, s[4:5]
	v_cndmask_b32_e64 v105, v105, v111, s[4:5]
	v_cndmask_b32_e64 v104, v104, v110, s[4:5]
	global_store_dwordx4 v[164:165], v[104:107], off nt
	s_mov_b64 s[2:3], 0x1800
	v_lshl_add_u64 v[166:167], v[142:143], 0, s[2:3]
	v_cvt_pk_bf16_f32 v104, v110, v111
	v_cvt_pk_bf16_f32 v105, v108, v109
	global_store_dwordx2 v[138:139], v[104:105], off offset:2560
	v_pk_mul_f32 v[104:105], v[116:117], v[160:161] op_sel_hi:[1,0]
	v_pk_mul_f32 v[106:107], v[118:119], v[160:161] op_sel_hi:[1,0]
	v_pk_fma_f32 v[104:105], v[10:11], v[104:105], v[14:15]
	v_pk_fma_f32 v[106:107], v[8:9], v[106:107], v[12:13]
	v_cndmask_b32_e64 v103, v103, v105, s[4:5]
	v_cndmask_b32_e64 v102, v102, v104, s[4:5]
	v_cndmask_b32_e64 v101, v101, v107, s[4:5]
	v_cndmask_b32_e64 v100, v100, v106, s[4:5]
	global_store_dwordx4 v[166:167], v[100:103], off nt
	s_mov_b64 s[2:3], 0x1c00
	v_lshl_add_u64 v[168:169], v[142:143], 0, s[2:3]
	v_cvt_pk_bf16_f32 v100, v106, v107
	v_cvt_pk_bf16_f32 v101, v104, v105
	global_store_dwordx2 v[138:139], v[100:101], off offset:3072
	v_pk_mul_f32 v[100:101], v[112:113], v[160:161] op_sel_hi:[1,0]
	v_pk_mul_f32 v[102:103], v[114:115], v[160:161] op_sel_hi:[1,0]
	v_pk_fma_f32 v[100:101], v[2:3], v[100:101], v[6:7]
	v_pk_fma_f32 v[102:103], v[0:1], v[102:103], v[4:5]
	v_cndmask_b32_e64 v99, v99, v101, s[4:5]
	v_cndmask_b32_e64 v98, v98, v100, s[4:5]
	v_cndmask_b32_e64 v97, v97, v103, s[4:5]
	v_cndmask_b32_e64 v96, v96, v102, s[4:5]
	global_store_dwordx4 v[168:169], v[96:99], off nt
	v_lshlrev_b32_e32 v104, 16, v157
	v_and_b32_e32 v105, 0xffff0000, v157
	v_cvt_pk_bf16_f32 v96, v102, v103
	v_cvt_pk_bf16_f32 v97, v100, v101
	global_store_dwordx2 v[138:139], v[96:97], off offset:3584
	global_load_dwordx2 v[96:97], v[140:141], off offset:16
	v_lshlrev_b32_e32 v98, 16, v158
	v_and_b32_e32 v99, 0xffff0000, v158
	v_lshlrev_b32_e32 v102, 16, v156
	v_and_b32_e32 v103, 0xffff0000, v156
	v_lshlrev_b32_e32 v100, 16, v159
	v_and_b32_e32 v101, 0xffff0000, v159
	v_lshlrev_b32_e32 v106, 16, v154
	v_and_b32_e32 v107, 0xffff0000, v154
	v_lshlrev_b32_e32 v108, 16, v155
	v_and_b32_e32 v109, 0xffff0000, v155
	s_mov_b32 s2, -1
	s_waitcnt vmcnt(0)
	v_sub_f32_e32 v93, v93, v96
	v_sub_f32_e32 v92, v92, v96
	v_sub_f32_e32 v89, v89, v96
	v_sub_f32_e32 v88, v88, v96
	v_sub_f32_e32 v95, v95, v96
	v_sub_f32_e32 v94, v94, v96
	v_sub_f32_e32 v91, v91, v96
	v_sub_f32_e32 v90, v90, v96
	v_pk_mul_f32 v[92:93], v[96:97], v[92:93] op_sel:[1,0]
	v_pk_mul_f32 v[88:89], v[96:97], v[88:89] op_sel:[1,0]
	v_sub_f32_e32 v81, v81, v96
	v_sub_f32_e32 v80, v80, v96
	v_pk_mul_f32 v[94:95], v[96:97], v[94:95] op_sel:[1,0]
	v_pk_mul_f32 v[90:91], v[96:97], v[90:91] op_sel:[1,0]
	v_pk_fma_f32 v[92:93], v[64:65], v[92:93], v[68:69]
	v_pk_fma_f32 v[88:89], v[72:73], v[88:89], v[76:77]
	v_pk_mul_f32 v[80:81], v[96:97], v[80:81] op_sel:[1,0]
	v_sub_f32_e32 v85, v85, v96
	v_sub_f32_e32 v84, v84, v96
	v_sub_f32_e32 v87, v87, v96
	v_sub_f32_e32 v86, v86, v96
	v_pk_fma_f32 v[94:95], v[66:67], v[94:95], v[70:71]
	v_pk_fma_f32 v[90:91], v[74:75], v[90:91], v[78:79]
	v_pk_fma_f32 v[92:93], v[92:93], s[52:53], v[98:99] op_sel_hi:[1,0,1]
	v_pk_fma_f32 v[88:89], v[88:89], s[52:53], v[102:103] op_sel_hi:[1,0,1]
	v_lshlrev_b32_e32 v98, 16, v152
	v_and_b32_e32 v99, 0xffff0000, v152
	v_sub_f32_e32 v83, v83, v96
	v_sub_f32_e32 v82, v82, v96
	v_pk_fma_f32 v[80:81], v[48:49], v[80:81], v[52:53]
	v_pk_mul_f32 v[86:87], v[96:97], v[86:87] op_sel:[1,0]
	v_pk_mul_f32 v[84:85], v[96:97], v[84:85] op_sel:[1,0]
	v_pk_fma_f32 v[94:95], v[94:95], s[52:53], v[100:101] op_sel_hi:[1,0,1]
	v_pk_fma_f32 v[90:91], v[90:91], s[52:53], v[104:105] op_sel_hi:[1,0,1]
	v_pk_mul_f32 v[82:83], v[96:97], v[82:83] op_sel:[1,0]
	v_pk_fma_f32 v[80:81], v[80:81], s[52:53], v[98:99] op_sel_hi:[1,0,1]
	v_mov_b32_e32 v96, v88
	v_mov_b32_e32 v97, v92
	v_mov_b32_e32 v98, v89
	v_mov_b32_e32 v99, v93
	v_pk_add_f32 v[96:97], v[96:97], v[98:99]
	v_mov_b32_e32 v98, v90
	v_mov_b32_e32 v99, v94
	v_pk_add_f32 v[96:97], v[98:99], v[96:97]
	v_mov_b32_e32 v98, v91
	v_mov_b32_e32 v99, v95
	v_pk_fma_f32 v[84:85], v[56:57], v[84:85], v[60:61]
	v_pk_add_f32 v[96:97], v[98:99], v[96:97]
	v_pk_fma_f32 v[86:87], v[58:59], v[86:87], v[62:63]
	v_pk_fma_f32 v[84:85], v[84:85], s[52:53], v[106:107] op_sel_hi:[1,0,1]
	v_lshlrev_b32_e32 v100, 16, v153
	v_and_b32_e32 v101, 0xffff0000, v153
	v_pk_fma_f32 v[82:83], v[50:51], v[82:83], v[54:55]
	v_add_f32_e32 v97, 0, v97
	v_pk_fma_f32 v[86:87], v[86:87], s[52:53], v[108:109] op_sel_hi:[1,0,1]
	v_pk_fma_f32 v[82:83], v[82:83], s[52:53], v[100:101] op_sel_hi:[1,0,1]
	v_add_f32_e32 v100, v96, v97
	v_mov_b32_e32 v96, v80
	v_mov_b32_e32 v97, v84
	v_mov_b32_e32 v98, v81
	v_mov_b32_e32 v99, v85
	v_pk_add_f32 v[96:97], v[96:97], v[98:99]
	v_mov_b32_e32 v98, v82
	v_mov_b32_e32 v99, v86
	v_pk_add_f32 v[96:97], v[98:99], v[96:97]
	v_mov_b32_e32 v98, v83
	v_mov_b32_e32 v99, v87
	v_pk_add_f32 v[96:97], v[98:99], v[96:97]
	s_nop 0
	v_add_f32_e32 v97, v97, v100
	v_add_f32_e32 v96, v96, v97
	v_mbcnt_lo_u32_b32 v97, s2, 0
	v_mbcnt_hi_u32_b32 v97, s2, v97
	v_lshlrev_b32_e32 v97, 2, v97
	v_xor_b32_e32 v98, 0x80, v97
	ds_bpermute_b32 v98, v98, v96
	s_mov_b32 s2, -1
	s_waitcnt lgkmcnt(0)
; DEVFI int lane_opaque() { unsigned m = ~0u; asm volatile("" : "+s"(m)); return (int)__builtin_amdgcn_mbcnt_hi(m, __builtin_amdgcn_mbcnt_lo(m, 0u)); }
; DEVFI float shx(float v, int mask, int lane) { return __int_as_float(__builtin_amdgcn_ds_bpermute((lane ^ mask) << 2, __float_as_int(v))); }
; DEVFI float red64(float v) {
;   const int ln = lane_opaque();
;   v += shx(v, 32, ln); v += shx(v, 16, ln); v += shx(v, 8, ln); v += shx(v, 4, ln); v += shx(v, 2, ln); v += shx(v, 1, ln); return v;
; }
; DEVFI void ln_resid4(const float* ysrc, float* ydst, bfraw* fb, float* stats, const float* pw, const float* pb,
;                      const float* w, const float* b, int lane, bool fin) {
;     ...
;     const float mean = red64(s) * (1.f / 1024.f);
;     float q = 0;
; #pragma unroll
;     for (int i = 0; i < 4; ++i) { const f32x4 d = y[i] - mean; q += d[0] * d[0] + d[1] * d[1] + d[2] * d[2] + d[3] * d[3]; }
;     const float rstd = 1.f / sqrtf(red64(q) * (1.f / 1024.f) + LN_EPS);
;     if (lane == 0) { stats[r * 2] = mean; stats[r * 2 + 1] = rstd; }
	v_add_f32_e32 v96, v96, v98
	v_xor_b32_e32 v98, 64, v97
	ds_bpermute_b32 v98, v98, v96
	s_waitcnt lgkmcnt(0)
	v_add_f32_e32 v96, v96, v98
	v_xor_b32_e32 v98, 32, v97
	s_nop 1
	v_mov_b32_dpp v98, v96 row_ror:8 row_mask:0xf bank_mask:0xf
	s_waitcnt lgkmcnt(0)
	v_add_f32_e32 v96, v96, v98
	v_xor_b32_e32 v98, 16, v97
	s_nop 1
	v_mov_b32_dpp v98, v96 row_half_mirror row_mask:0xf bank_mask:0xf
	s_nop 1
	v_mov_b32_dpp v98, v98 quad_perm:[3,2,1,0] row_mask:0xf bank_mask:0xf
	s_waitcnt lgkmcnt(0)
	v_add_f32_e32 v96, v96, v98
	v_xor_b32_e32 v98, 8, v97
	s_nop 1
	v_mov_b32_dpp v98, v96 quad_perm:[2,3,0,1] row_mask:0xf bank_mask:0xf
	v_xor_b32_e32 v97, 4, v97
	s_waitcnt lgkmcnt(0)
	v_add_f32_e32 v96, v96, v98
	s_nop 1
	v_mov_b32_dpp v97, v96 quad_perm:[1,0,3,2] row_mask:0xf bank_mask:0xf
	s_waitcnt lgkmcnt(0)
	v_add_f32_e32 v113, v96, v97
	v_fmamk_f32 v111, v113, 0xba800000, v93
	v_fmamk_f32 v107, v113, 0xba800000, v89
	v_fmamk_f32 v110, v113, 0xba800000, v92
	v_mul_f32_e32 v96, v111, v111
	v_fmamk_f32 v106, v113, 0xba800000, v88
	v_mul_f32_e32 v97, v107, v107
	v_fmamk_f32 v108, v113, 0xba800000, v94
	v_fmac_f32_e32 v96, v110, v110
	v_fmamk_f32 v104, v113, 0xba800000, v90
	v_fmac_f32_e32 v97, v106, v106
	v_fmamk_f32 v109, v113, 0xba800000, v95
	v_fmac_f32_e32 v96, v108, v108
	v_fmamk_f32 v105, v113, 0xba800000, v91
	v_fmac_f32_e32 v97, v104, v104
	v_fmac_f32_e32 v96, v109, v109
	v_fmac_f32_e32 v97, v105, v105
	v_fmamk_f32 v103, v113, 0xba800000, v85
	v_add_f32_e32 v96, v96, v97
	v_fmamk_f32 v102, v113, 0xba800000, v84
	v_mul_f32_e32 v97, v103, v103
	v_fmamk_f32 v100, v113, 0xba800000, v86
	v_fmac_f32_e32 v97, v102, v102
	v_fmamk_f32 v101, v113, 0xba800000, v87
	v_fmac_f32_e32 v97, v100, v100
	v_fmamk_f32 v99, v113, 0xba800000, v81
	v_fmac_f32_e32 v97, v101, v101
	v_fmamk_f32 v98, v113, 0xba800000, v80
	v_mul_f32_e32 v114, v99, v99
	v_add_f32_e32 v112, v97, v96
	v_fmamk_f32 v96, v113, 0xba800000, v82
	v_fmac_f32_e32 v114, v98, v98
	v_fmamk_f32 v97, v113, 0xba800000, v83
	v_fmac_f32_e32 v114, v96, v96
	v_fmac_f32_e32 v114, v97, v97
	v_add_f32_e32 v112, v114, v112
	v_mbcnt_lo_u32_b32 v114, s2, 0
	v_mbcnt_hi_u32_b32 v114, s2, v114
	v_lshlrev_b32_e32 v114, 2, v114
	v_xor_b32_e32 v115, 0x80, v114
	ds_bpermute_b32 v115, v115, v112
	s_waitcnt lgkmcnt(0)
	v_add_f32_e32 v112, v112, v115
	v_xor_b32_e32 v115, 64, v114
	ds_bpermute_b32 v115, v115, v112
	s_waitcnt lgkmcnt(0)
	v_add_f32_e32 v112, v112, v115
	v_xor_b32_e32 v115, 32, v114
	s_nop 1
	v_mov_b32_dpp v115, v112 row_ror:8 row_mask:0xf bank_mask:0xf
	s_waitcnt lgkmcnt(0)
	v_add_f32_e32 v112, v112, v115
	v_xor_b32_e32 v115, 16, v114
	s_nop 1
	v_mov_b32_dpp v115, v112 row_half_mirror row_mask:0xf bank_mask:0xf
	s_nop 1
	v_mov_b32_dpp v115, v115 quad_perm:[3,2,1,0] row_mask:0xf bank_mask:0xf
	s_waitcnt lgkmcnt(0)
	v_add_f32_e32 v112, v112, v115
	v_xor_b32_e32 v115, 8, v114
	s_nop 1
	v_mov_b32_dpp v115, v112 quad_perm:[2,3,0,1] row_mask:0xf bank_mask:0xf
	v_xor_b32_e32 v114, 4, v114
	s_waitcnt lgkmcnt(0)
	v_add_f32_e32 v112, v112, v115
	s_nop 1
	v_mov_b32_dpp v114, v112 quad_perm:[1,0,3,2] row_mask:0xf bank_mask:0xf
	s_waitcnt lgkmcnt(0)
	v_add_f32_e32 v112, v112, v114
	v_fmamk_f32 v112, v112, 0x3a800000, v183
	v_mul_f32_e32 v114, 0x4f800000, v112
	v_cmp_gt_f32_e32 vcc, s30, v112
	s_nop 1
	v_cndmask_b32_e32 v112, v112, v114, vcc
	v_sqrt_f32_e32 v114, v112
	s_nop 0
	v_add_u32_e32 v115, -1, v114
	v_fma_f32 v116, -v115, v114, v112
	v_cmp_ge_f32_e64 s[8:9], 0, v116
	v_add_u32_e32 v116, 1, v114
	s_nop 0
	v_cndmask_b32_e64 v115, v114, v115, s[8:9]
	v_fma_f32 v114, -v116, v114, v112
	v_cmp_lt_f32_e64 s[8:9], 0, v114
	s_nop 1
	v_cndmask_b32_e64 v114, v115, v116, s[8:9]
	v_mul_f32_e32 v115, 0x37800000, v114
	v_cndmask_b32_e32 v114, v114, v115, vcc
	v_cmp_class_f32_e32 vcc, v112, v222
	s_nop 1
	v_cndmask_b32_e32 v112, v114, v112, vcc
	s_nop 0
	v_rcp_f32_e32 v115, v112
	s_nop 0
	v_fma_f32 v114, -v112, v115, 1.0
	v_fma_f32 v114, v114, v115, v115
	v_div_fixup_f32 v112, v114, v112, 1.0
	s_mov_b64 s[2:3], exec
	s_and_b64 s[8:9], s[2:3], s[6:7]
	v_mov_b32_e32 v182, v192
	s_mov_b64 exec, s[8:9]
	s_cbranch_execz .LBB0_4786
	v_mul_f32_e32 v114, 0x3a800000, v113
	v_mov_b32_e32 v115, v112
	global_store_dwordx2 v[140:141], v[114:115], off offset:16
; DEVFI void ln_resid4(const float* ysrc, float* ydst, bfraw* fb, float* stats, const float* pw, const float* pb,
;                      const float* w, const float* b, int lane, bool fin) {
;     ...
;   for (int r = 0; r < 4; ++r) {
;     const float pmu = stats[r * 2], prs = stats[r * 2 + 1];
;     f32x4 y[4];
; #pragma unroll
;     for (int i = 0; i < 4; ++i) { const unsigned f0 = fv[r][i][0], f1 = fv[r][i][1];
;       const f32x4 f4 = {__uint_as_float(f0 << 16), __uint_as_float(f0 & 0xffff0000u), __uint_as_float(f1 << 16), __uint_as_float(f1 & 0xffff0000u)};
;       y[i] = ALPHA * ((v[r][i] - pmu) * prs * pwv[i] + pbv[i]) + f4; }
;     float s = 0;
; #pragma unroll
;     for (int i = 0; i < 4; ++i) s += y[i][0] + y[i][1] + y[i][2] + y[i][3];
;     const float mean = red64(s) * (1.f / 1024.f);
;     float q = 0;
; #pragma unroll
;     for (int i = 0; i < 4; ++i) { const f32x4 d = y[i] - mean; q += d[0] * d[0] + d[1] * d[1] + d[2] * d[2] + d[3] * d[3]; }
;     const float rstd = 1.f / sqrtf(red64(q) * (1.f / 1024.f) + LN_EPS);
;     if (lane == 0) { stats[r * 2] = mean; stats[r * 2 + 1] = rstd; }
; #pragma unroll
;     for (int i = 0; i < 4; ++i) { const int c4 = i * 64 + lane;
;       const f32x4 z = (y[i] - mean) * rstd * ww[i] + bb[i];
;       __builtin_nontemporal_store(fin ? z : y[i], (f32x4*)(ydst + r * 1024) + c4);
;       u32x2 pk = {cvtpk(z[0], z[1]), cvtpk(z[2], z[3])}; ((u32x2*)(fb + r * 1024))[c4] = pk; }
.LBB0_4786:
	s_or_b64 exec, exec, s[2:3]
	s_mov_b64 s[2:3], 0x2000
	v_lshl_add_u64 v[114:115], v[142:143], 0, s[2:3]
	s_mov_b64 s[2:3], 0x2400
	v_lshl_add_u64 v[116:117], v[142:143], 0, s[2:3]
	s_mov_b64 s[2:3], 0x2800
	v_pk_mul_f32 v[108:109], v[108:109], v[112:113] op_sel_hi:[1,0]
	v_pk_mul_f32 v[110:111], v[110:111], v[112:113] op_sel_hi:[1,0]
	v_lshl_add_u64 v[118:119], v[142:143], 0, s[2:3]
	s_mov_b64 s[2:3], 0x2c00
	v_pk_fma_f32 v[108:109], v[26:27], v[108:109], v[30:31]
	v_pk_fma_f32 v[110:111], v[24:25], v[110:111], v[28:29]
	v_lshl_add_u64 v[120:121], v[142:143], 0, s[2:3]
	s_mov_b64 s[2:3], 0x1000
	v_cndmask_b32_e64 v95, v95, v109, s[4:5]
	v_cndmask_b32_e64 v94, v94, v108, s[4:5]
	v_cndmask_b32_e64 v93, v93, v111, s[4:5]
	v_cndmask_b32_e64 v92, v92, v110, s[4:5]
	v_lshl_add_u64 v[122:123], v[138:139], 0, s[2:3]
	global_store_dwordx4 v[114:115], v[92:95], off nt
	s_mov_b64 s[2:3], 0x1200
	v_lshl_add_u64 v[124:125], v[138:139], 0, s[2:3]
	v_cvt_pk_bf16_f32 v92, v110, v111
	v_cvt_pk_bf16_f32 v93, v108, v109
	global_store_dwordx2 v[122:123], v[92:93], off
	v_pk_mul_f32 v[92:93], v[104:105], v[112:113] op_sel_hi:[1,0]
	v_pk_mul_f32 v[94:95], v[106:107], v[112:113] op_sel_hi:[1,0]
	v_pk_fma_f32 v[92:93], v[18:19], v[92:93], v[22:23]
	v_pk_fma_f32 v[94:95], v[16:17], v[94:95], v[20:21]
	v_cndmask_b32_e64 v91, v91, v93, s[4:5]
	v_cndmask_b32_e64 v90, v90, v92, s[4:5]
	v_cndmask_b32_e64 v89, v89, v95, s[4:5]
	v_cndmask_b32_e64 v88, v88, v94, s[4:5]
	global_store_dwordx4 v[116:117], v[88:91], off nt
	s_mov_b64 s[2:3], 0x1400
	v_lshl_add_u64 v[126:127], v[138:139], 0, s[2:3]
	v_cvt_pk_bf16_f32 v88, v94, v95
	v_cvt_pk_bf16_f32 v89, v92, v93
	global_store_dwordx2 v[124:125], v[88:89], off
	v_pk_mul_f32 v[88:89], v[100:101], v[112:113] op_sel_hi:[1,0]
	v_pk_mul_f32 v[90:91], v[102:103], v[112:113] op_sel_hi:[1,0]
	v_pk_fma_f32 v[88:89], v[10:11], v[88:89], v[14:15]
	v_pk_fma_f32 v[90:91], v[8:9], v[90:91], v[12:13]
	v_cndmask_b32_e64 v87, v87, v89, s[4:5]
	v_cndmask_b32_e64 v86, v86, v88, s[4:5]
	v_cndmask_b32_e64 v85, v85, v91, s[4:5]
	v_cndmask_b32_e64 v84, v84, v90, s[4:5]
	global_store_dwordx4 v[118:119], v[84:87], off nt
	s_mov_b64 s[2:3], 0x1600
	v_lshl_add_u64 v[152:153], v[138:139], 0, s[2:3]
	v_cvt_pk_bf16_f32 v84, v90, v91
	v_cvt_pk_bf16_f32 v85, v88, v89
	global_store_dwordx2 v[126:127], v[84:85], off
	v_pk_mul_f32 v[84:85], v[96:97], v[112:113] op_sel_hi:[1,0]
	v_pk_mul_f32 v[86:87], v[98:99], v[112:113] op_sel_hi:[1,0]
	v_pk_fma_f32 v[84:85], v[2:3], v[84:85], v[6:7]
	v_pk_fma_f32 v[86:87], v[0:1], v[86:87], v[4:5]
	v_cndmask_b32_e64 v83, v83, v85, s[4:5]
	v_cndmask_b32_e64 v82, v82, v84, s[4:5]
	v_cndmask_b32_e64 v81, v81, v87, s[4:5]
	v_cndmask_b32_e64 v80, v80, v86, s[4:5]
	global_store_dwordx4 v[120:121], v[80:83], off nt
	v_lshlrev_b32_e32 v88, 16, v149
	v_and_b32_e32 v89, 0xffff0000, v149
	v_cvt_pk_bf16_f32 v80, v86, v87
	v_cvt_pk_bf16_f32 v81, v84, v85
	global_store_dwordx2 v[152:153], v[80:81], off
	global_load_dwordx2 v[80:81], v[140:141], off offset:24
	v_lshlrev_b32_e32 v82, 16, v150
	v_and_b32_e32 v83, 0xffff0000, v150
	v_lshlrev_b32_e32 v86, 16, v148
	v_and_b32_e32 v87, 0xffff0000, v148
	v_lshlrev_b32_e32 v84, 16, v151
	v_and_b32_e32 v85, 0xffff0000, v151
	v_lshlrev_b32_e32 v90, 16, v146
	v_and_b32_e32 v91, 0xffff0000, v146
	v_lshlrev_b32_e32 v92, 16, v147
	v_and_b32_e32 v93, 0xffff0000, v147
	s_mov_b32 s2, -1
	s_waitcnt vmcnt(0)
	v_sub_f32_e32 v45, v45, v80
	v_sub_f32_e32 v44, v44, v80
	v_sub_f32_e32 v41, v41, v80
	v_sub_f32_e32 v40, v40, v80
	v_sub_f32_e32 v47, v47, v80
	v_sub_f32_e32 v46, v46, v80
	v_sub_f32_e32 v43, v43, v80
	v_sub_f32_e32 v42, v42, v80
	v_pk_mul_f32 v[44:45], v[80:81], v[44:45] op_sel:[1,0]
	v_pk_mul_f32 v[40:41], v[80:81], v[40:41] op_sel:[1,0]
	v_pk_mul_f32 v[46:47], v[80:81], v[46:47] op_sel:[1,0]
	v_pk_mul_f32 v[42:43], v[80:81], v[42:43] op_sel:[1,0]
	v_pk_fma_f32 v[44:45], v[64:65], v[44:45], v[68:69]
	v_pk_fma_f32 v[40:41], v[72:73], v[40:41], v[76:77]
	v_sub_f32_e32 v33, v33, v80
	v_sub_f32_e32 v32, v32, v80
	v_sub_f32_e32 v35, v35, v80
	v_sub_f32_e32 v34, v34, v80
	v_pk_fma_f32 v[46:47], v[66:67], v[46:47], v[70:71]
	v_pk_fma_f32 v[42:43], v[74:75], v[42:43], v[78:79]
	v_pk_fma_f32 v[44:45], v[44:45], s[52:53], v[82:83] op_sel_hi:[1,0,1]
	v_pk_fma_f32 v[40:41], v[40:41], s[52:53], v[86:87] op_sel_hi:[1,0,1]
	v_pk_mul_f32 v[34:35], v[80:81], v[34:35] op_sel:[1,0]
	v_pk_mul_f32 v[32:33], v[80:81], v[32:33] op_sel:[1,0]
	v_pk_fma_f32 v[46:47], v[46:47], s[52:53], v[84:85] op_sel_hi:[1,0,1]
	v_pk_fma_f32 v[42:43], v[42:43], s[52:53], v[88:89] op_sel_hi:[1,0,1]
	v_pk_fma_f32 v[32:33], v[48:49], v[32:33], v[52:53]
	v_pk_fma_f32 v[34:35], v[50:51], v[34:35], v[54:55]
	v_mov_b32_e32 v48, v40
	v_mov_b32_e32 v49, v44
	v_mov_b32_e32 v50, v41
	v_mov_b32_e32 v51, v45
	v_sub_f32_e32 v37, v37, v80
	v_sub_f32_e32 v36, v36, v80
	v_pk_add_f32 v[48:49], v[48:49], v[50:51]
	v_mov_b32_e32 v50, v42
	v_mov_b32_e32 v51, v46
	v_sub_f32_e32 v39, v39, v80
	v_sub_f32_e32 v38, v38, v80
	v_pk_mul_f32 v[36:37], v[80:81], v[36:37] op_sel:[1,0]
	v_pk_add_f32 v[48:49], v[50:51], v[48:49]
	v_mov_b32_e32 v50, v43
	v_mov_b32_e32 v51, v47
	v_pk_mul_f32 v[38:39], v[80:81], v[38:39] op_sel:[1,0]
	v_pk_fma_f32 v[36:37], v[56:57], v[36:37], v[60:61]
	v_lshlrev_b32_e32 v56, 16, v144
	v_and_b32_e32 v57, 0xffff0000, v144
	v_pk_add_f32 v[48:49], v[50:51], v[48:49]
	v_pk_fma_f32 v[38:39], v[58:59], v[38:39], v[62:63]
	v_pk_fma_f32 v[36:37], v[36:37], s[52:53], v[90:91] op_sel_hi:[1,0,1]
	v_lshlrev_b32_e32 v58, 16, v145
	v_and_b32_e32 v59, 0xffff0000, v145
	v_pk_fma_f32 v[32:33], v[32:33], s[52:53], v[56:57] op_sel_hi:[1,0,1]
	v_add_f32_e32 v49, 0, v49
	v_pk_fma_f32 v[38:39], v[38:39], s[52:53], v[92:93] op_sel_hi:[1,0,1]
	v_pk_fma_f32 v[34:35], v[34:35], s[52:53], v[58:59] op_sel_hi:[1,0,1]
	v_add_f32_e32 v52, v48, v49
	v_mov_b32_e32 v48, v32
	v_mov_b32_e32 v49, v36
	v_mov_b32_e32 v50, v33
	v_mov_b32_e32 v51, v37
	v_pk_add_f32 v[48:49], v[48:49], v[50:51]
	v_mov_b32_e32 v50, v34
	v_mov_b32_e32 v51, v38
	v_pk_add_f32 v[48:49], v[50:51], v[48:49]
	v_mov_b32_e32 v50, v35
	v_mov_b32_e32 v51, v39
	v_pk_add_f32 v[48:49], v[50:51], v[48:49]
	s_nop 0
	v_add_f32_e32 v49, v49, v52
	v_add_f32_e32 v48, v48, v49
	v_mbcnt_lo_u32_b32 v49, s2, 0
	v_mbcnt_hi_u32_b32 v49, s2, v49
	v_lshlrev_b32_e32 v49, 2, v49
	v_xor_b32_e32 v50, 0x80, v49
	ds_bpermute_b32 v50, v50, v48
	s_mov_b32 s2, -1
	s_waitcnt lgkmcnt(0)
; DEVFI int lane_opaque() { unsigned m = ~0u; asm volatile("" : "+s"(m)); return (int)__builtin_amdgcn_mbcnt_hi(m, __builtin_amdgcn_mbcnt_lo(m, 0u)); }
; DEVFI float shx(float v, int mask, int lane) { return __int_as_float(__builtin_amdgcn_ds_bpermute((lane ^ mask) << 2, __float_as_int(v))); }
; DEVFI float red64(float v) {
;   const int ln = lane_opaque();
;   v += shx(v, 32, ln); v += shx(v, 16, ln); v += shx(v, 8, ln); v += shx(v, 4, ln); v += shx(v, 2, ln); v += shx(v, 1, ln); return v;
; }
; DEVFI void ln_resid4(const float* ysrc, float* ydst, bfraw* fb, float* stats, const float* pw, const float* pb,
;                      const float* w, const float* b, int lane, bool fin) {
;     ...
;     const float mean = red64(s) * (1.f / 1024.f);
;     float q = 0;
; #pragma unroll
;     for (int i = 0; i < 4; ++i) { const f32x4 d = y[i] - mean; q += d[0] * d[0] + d[1] * d[1] + d[2] * d[2] + d[3] * d[3]; }
;     const float rstd = 1.f / sqrtf(red64(q) * (1.f / 1024.f) + LN_EPS);
;     if (lane == 0) { stats[r * 2] = mean; stats[r * 2 + 1] = rstd; }
	v_add_f32_e32 v48, v48, v50
	v_xor_b32_e32 v50, 64, v49
	ds_bpermute_b32 v50, v50, v48
	s_waitcnt lgkmcnt(0)
	v_add_f32_e32 v48, v48, v50
	v_xor_b32_e32 v50, 32, v49
	s_nop 1
	v_mov_b32_dpp v50, v48 row_ror:8 row_mask:0xf bank_mask:0xf
	s_waitcnt lgkmcnt(0)
	v_add_f32_e32 v48, v48, v50
	v_xor_b32_e32 v50, 16, v49
	s_nop 1
	v_mov_b32_dpp v50, v48 row_half_mirror row_mask:0xf bank_mask:0xf
	s_nop 1
	v_mov_b32_dpp v50, v50 quad_perm:[3,2,1,0] row_mask:0xf bank_mask:0xf
	s_waitcnt lgkmcnt(0)
	v_add_f32_e32 v48, v48, v50
	v_xor_b32_e32 v50, 8, v49
	s_nop 1
	v_mov_b32_dpp v50, v48 quad_perm:[2,3,0,1] row_mask:0xf bank_mask:0xf
	v_xor_b32_e32 v49, 4, v49
	s_waitcnt lgkmcnt(0)
	v_add_f32_e32 v48, v48, v50
	s_nop 1
	v_mov_b32_dpp v49, v48 quad_perm:[1,0,3,2] row_mask:0xf bank_mask:0xf
	s_waitcnt lgkmcnt(0)
	v_add_f32_e32 v65, v48, v49
	v_fmamk_f32 v63, v65, 0xba800000, v45
	v_fmamk_f32 v59, v65, 0xba800000, v41
	v_fmamk_f32 v62, v65, 0xba800000, v44
	v_mul_f32_e32 v48, v63, v63
	v_fmamk_f32 v58, v65, 0xba800000, v40
	v_mul_f32_e32 v49, v59, v59
	v_fmamk_f32 v60, v65, 0xba800000, v46
	v_fmac_f32_e32 v48, v62, v62
	v_fmamk_f32 v56, v65, 0xba800000, v42
	v_fmac_f32_e32 v49, v58, v58
	v_fmamk_f32 v61, v65, 0xba800000, v47
	v_fmac_f32_e32 v48, v60, v60
	v_fmamk_f32 v57, v65, 0xba800000, v43
	v_fmac_f32_e32 v49, v56, v56
	v_fmac_f32_e32 v48, v61, v61
	v_fmac_f32_e32 v49, v57, v57
	v_fmamk_f32 v55, v65, 0xba800000, v37
	v_add_f32_e32 v48, v48, v49
	v_fmamk_f32 v54, v65, 0xba800000, v36
	v_mul_f32_e32 v49, v55, v55
	v_fmamk_f32 v52, v65, 0xba800000, v38
	v_fmac_f32_e32 v49, v54, v54
	v_fmamk_f32 v53, v65, 0xba800000, v39
	v_fmac_f32_e32 v49, v52, v52
	v_fmamk_f32 v51, v65, 0xba800000, v33
	v_fmac_f32_e32 v49, v53, v53
	v_fmamk_f32 v50, v65, 0xba800000, v32
	v_mul_f32_e32 v66, v51, v51
	v_add_f32_e32 v64, v49, v48
	v_fmamk_f32 v48, v65, 0xba800000, v34
	v_fmac_f32_e32 v66, v50, v50
	v_fmamk_f32 v49, v65, 0xba800000, v35
	v_fmac_f32_e32 v66, v48, v48
	v_fmac_f32_e32 v66, v49, v49
	v_add_f32_e32 v64, v66, v64
	v_mbcnt_lo_u32_b32 v66, s2, 0
	v_mbcnt_hi_u32_b32 v66, s2, v66
	v_lshlrev_b32_e32 v66, 2, v66
	v_xor_b32_e32 v67, 0x80, v66
	ds_bpermute_b32 v67, v67, v64
	s_waitcnt lgkmcnt(0)
	v_add_f32_e32 v64, v64, v67
	v_xor_b32_e32 v67, 64, v66
	ds_bpermute_b32 v67, v67, v64
	s_waitcnt lgkmcnt(0)
	v_add_f32_e32 v64, v64, v67
	v_xor_b32_e32 v67, 32, v66
	s_nop 1
	v_mov_b32_dpp v67, v64 row_ror:8 row_mask:0xf bank_mask:0xf
	s_waitcnt lgkmcnt(0)
	v_add_f32_e32 v64, v64, v67
	v_xor_b32_e32 v67, 16, v66
	s_nop 1
	v_mov_b32_dpp v67, v64 row_half_mirror row_mask:0xf bank_mask:0xf
	s_nop 1
	v_mov_b32_dpp v67, v67 quad_perm:[3,2,1,0] row_mask:0xf bank_mask:0xf
	s_waitcnt lgkmcnt(0)
	v_add_f32_e32 v64, v64, v67
	v_xor_b32_e32 v67, 8, v66
	s_nop 1
	v_mov_b32_dpp v67, v64 quad_perm:[2,3,0,1] row_mask:0xf bank_mask:0xf
	v_xor_b32_e32 v66, 4, v66
	s_waitcnt lgkmcnt(0)
	v_add_f32_e32 v64, v64, v67
	s_nop 1
	v_mov_b32_dpp v66, v64 quad_perm:[1,0,3,2] row_mask:0xf bank_mask:0xf
	s_waitcnt lgkmcnt(0)
	v_add_f32_e32 v64, v64, v66
	v_fmamk_f32 v64, v64, 0x3a800000, v183
	v_mul_f32_e32 v66, 0x4f800000, v64
	v_cmp_gt_f32_e32 vcc, s30, v64
	s_nop 1
	v_cndmask_b32_e32 v64, v64, v66, vcc
	v_sqrt_f32_e32 v66, v64
	s_nop 0
	v_add_u32_e32 v67, -1, v66
	v_fma_f32 v68, -v67, v66, v64
	v_cmp_ge_f32_e64 s[8:9], 0, v68
	v_add_u32_e32 v68, 1, v66
	s_nop 0
	v_cndmask_b32_e64 v67, v66, v67, s[8:9]
	v_fma_f32 v66, -v68, v66, v64
	v_cmp_lt_f32_e64 s[8:9], 0, v66
	s_nop 1
	v_cndmask_b32_e64 v66, v67, v68, s[8:9]
	v_mul_f32_e32 v67, 0x37800000, v66
	v_cndmask_b32_e32 v66, v66, v67, vcc
	v_cmp_class_f32_e32 vcc, v64, v222
	s_nop 1
	v_cndmask_b32_e32 v64, v66, v64, vcc
	s_nop 0
	v_rcp_f32_e32 v67, v64
	s_nop 0
	v_fma_f32 v66, -v64, v67, 1.0
	v_fma_f32 v66, v66, v67, v67
	v_div_fixup_f32 v64, v66, v64, 1.0
	s_and_saveexec_b64 s[2:3], s[6:7]
	s_cbranch_execz .LBB0_4779
	v_mul_f32_e32 v66, 0x3a800000, v65
	v_mov_b32_e32 v67, v64
	global_store_dwordx2 v[140:141], v[66:67], off offset:24
	s_branch .LBB0_4779
